# v31_noflat
# baseline (speedup 1.0000x reference)
; DEVI void spcopy_phase(int wv, const Params& p) {
;     ...
;   for (int i = gt; i < 4096; i += gs) SP[SP_FFN_NORM + i] = p.ffn_norm[i];
.LBB0_83:
	v_lshl_add_u64 v[8:9], s[16:17], 0, v[4:5]
	global_load_dword v7, v[8:9], off
	v_add_u32_e32 v6, s18, v6
	v_cmp_lt_i32_e32 vcc, s19, v6
	v_lshl_add_u64 v[8:9], s[4:5], 0, v[4:5]
	v_lshl_add_u64 v[4:5], v[4:5], 0, s[6:7]
	s_or_b64 s[20:21], vcc, s[20:21]
	s_waitcnt vmcnt(0)
	global_store_dword v[8:9], v7, off
	s_andn2_b64 exec, exec, s[20:21]
	s_cbranch_execnz .LBB0_83

; DEVI void spcopy_phase(int wv, const Params& p) {
;     ...
;   for (int i = gt; i < 2048; i += gs) { SP[SP_MIX_NORM + i] = p.mix_norm[i]; SP[SP_PLE_NORM + i] = p.ple_norm[i]; }
.LBB0_86:
	v_lshl_add_u64 v[8:9], s[22:23], 0, v[4:5]
	global_load_dword v7, v[8:9], off
	v_lshl_add_u64 v[8:9], s[8:9], 0, v[4:5]
	v_add_co_u32_e32 v12, vcc, 0x14624000, v8
	v_lshl_add_u64 v[10:11], s[34:35], 0, v[4:5]
	s_nop 0
	v_addc_co_u32_e32 v13, vcc, 0, v9, vcc
	v_add_u32_e32 v6, s18, v6
	v_cmp_lt_i32_e64 s[0:1], s19, v6
	v_add_co_u32_e32 v8, vcc, 0x14626000, v8
	v_lshl_add_u64 v[4:5], v[4:5], 0, s[20:21]
	s_or_b64 s[30:31], s[0:1], s[30:31]
	v_addc_co_u32_e32 v9, vcc, 0, v9, vcc
	s_waitcnt vmcnt(0)
	global_store_dword v[12:13], v7, off
	global_load_dword v7, v[10:11], off
	s_waitcnt vmcnt(0)
	global_store_dword v[8:9], v7, off
	s_andn2_b64 exec, exec, s[30:31]
	s_cbranch_execnz .LBB0_86

; DEVI void spcopy_phase(int wv, const Params& p) {
;     ...
;   for (int i = gt; i < 1024; i += gs) SP[SP_FINAL + i] = p.final_norm[i];
.LBB0_89:
	v_lshl_add_u64 v[8:9], s[36:37], 0, v[4:5]
	global_load_dword v7, v[8:9], off
	v_add_u32_e32 v6, s18, v6
	v_cmp_lt_i32_e32 vcc, s19, v6
	v_lshl_add_u64 v[8:9], s[20:21], 0, v[4:5]
	v_lshl_add_u64 v[4:5], v[4:5], 0, s[16:17]
	s_or_b64 s[22:23], vcc, s[22:23]
	s_waitcnt vmcnt(0)
	global_store_dword v[8:9], v7, off
	s_andn2_b64 exec, exec, s[22:23]
	s_cbranch_execnz .LBB0_89

; DEVI void spcopy_phase(int wv, const Params& p) {
;     ...
;   for (int i = gt; i < 256; i += gs) { SP[SP_GLA_ON + i] = p.gla_out_norm[i]; SP[SP_KVN + i] = p.mla_kv_norm[i]; }
.LBB0_92:
	v_lshl_add_u64 v[8:9], s[26:27], 0, v[4:5]
	global_load_dword v7, v[8:9], off
	v_lshl_add_u64 v[8:9], s[8:9], 0, v[4:5]
	v_add_co_u32_e32 v8, vcc, 0x14629000, v8
	s_waitcnt lgkmcnt(0)
	v_lshl_add_u64 v[10:11], s[6:7], 0, v[4:5]
	v_addc_co_u32_e32 v9, vcc, 0, v9, vcc
	v_add_u32_e32 v6, s18, v6
	v_cmp_lt_i32_e32 vcc, s19, v6
	v_lshl_add_u64 v[4:5], v[4:5], 0, s[16:17]
	s_or_b64 s[20:21], vcc, s[20:21]
	s_waitcnt vmcnt(0)
	global_store_dword v[8:9], v7, off
	global_load_dword v7, v[10:11], off
	s_waitcnt vmcnt(0)
	global_store_dword v[8:9], v7, off offset:2560
	s_andn2_b64 exec, exec, s[20:21]
	s_cbranch_execnz .LBB0_92

; DEVI void spcopy_phase(int wv, const Params& p) {
;     ...
;   for (int i = gt; i < 384; i += gs) SP[SP_QN + i] = p.mla_q_norm[i];
.LBB0_95:
	v_lshl_add_u64 v[8:9], s[4:5], 0, v[4:5]
	global_load_dword v7, v[8:9], off
	v_add_u32_e32 v6, s18, v6
	v_cmp_lt_i32_e32 vcc, s19, v6
	v_lshl_add_u64 v[8:9], s[16:17], 0, v[4:5]
	v_lshl_add_u64 v[4:5], v[4:5], 0, s[6:7]
	s_or_b64 s[20:21], vcc, s[20:21]
	s_waitcnt vmcnt(0)
	global_store_dword v[8:9], v7, off
	s_andn2_b64 exec, exec, s[20:21]
	s_cbranch_execnz .LBB0_95

; DEVI void spcopy_phase(int wv, const Params& p) {
;     ...
;   for (int i = gt; i < 8192; i += gs) { SP[SP_WGF + i] = p.gla_w_gf_up[i]; SP[SP_WGB + i] = p.gla_w_gb_up[i]; }
.LBB0_98:
	v_lshl_add_u64 v[8:9], s[10:11], 0, v[4:5]
	global_load_dword v7, v[8:9], off
	v_lshl_add_u64 v[8:9], s[8:9], 0, v[4:5]
	v_add_co_u32_e32 v12, vcc, 0x14629000, v8
	v_lshl_add_u64 v[10:11], s[14:15], 0, v[4:5]
	s_nop 0
	v_addc_co_u32_e32 v13, vcc, 0, v9, vcc
	v_add_u32_e32 v6, s18, v6
	v_cmp_lt_i32_e64 s[0:1], s19, v6
	v_add_co_u32_e32 v8, vcc, 0x14632000, v8
	v_lshl_add_u64 v[4:5], v[4:5], 0, s[6:7]
	s_or_b64 s[16:17], s[0:1], s[16:17]
	v_addc_co_u32_e32 v9, vcc, 0, v9, vcc
	s_waitcnt vmcnt(0)
	global_store_dword v[12:13], v7, off offset:3584
	global_load_dword v7, v[10:11], off
	s_waitcnt vmcnt(0)
	global_store_dword v[8:9], v7, off offset:1536
	s_andn2_b64 exec, exec, s[16:17]
	s_cbranch_execnz .LBB0_98

; DEVI void spcopy_phase(int wv, const Params& p) {
;     ...
;   for (int i = gt; i < 512; i += gs) { SP[SP_BGF + i] = p.gla_b_gf[i]; SP[SP_BGB + i] = p.gla_b_gb[i]; }
.LBB0_101:
	v_lshl_add_u64 v[6:7], s[12:13], 0, v[4:5]
	global_load_dword v3, v[6:7], off
	v_lshl_add_u64 v[6:7], s[8:9], 0, v[4:5]
	v_add_co_u32_e32 v10, vcc, 0x14631000, v6
	v_lshl_add_u64 v[8:9], s[24:25], 0, v[4:5]
	s_nop 0
	v_addc_co_u32_e32 v11, vcc, 0, v7, vcc
	v_add_u32_e32 v2, s18, v2
	v_cmp_lt_i32_e64 s[0:1], s14, v2
	v_add_co_u32_e32 v6, vcc, 0x1463a000, v6
	v_lshl_add_u64 v[4:5], v[4:5], 0, s[6:7]
	s_or_b64 s[10:11], s[0:1], s[10:11]
	v_addc_co_u32_e32 v7, vcc, 0, v7, vcc
	s_waitcnt vmcnt(0)
	global_store_dword v[10:11], v3, off offset:3584
	global_load_dword v3, v[8:9], off
	s_waitcnt vmcnt(0)
	global_store_dword v[6:7], v3, off offset:1536
	s_andn2_b64 exec, exec, s[10:11]
	s_cbranch_execnz .LBB0_101

; DEVI int onb() { int t = gridDim.x; asm volatile("" : "+s"(t)); return t; }
; DEVI int obid() { int t = blockIdx.x; asm volatile("" : "+s"(t)); return t; }
; DEVI void norm_phase(int wv, const Params& p, int mode) {
;     ...
;   for (int row = obid() * 8 + wave; row < MTOK; row += onb() * 8) {
;     const float* src;
;     if (mode == 1) src = row < MP ? p.x_prompt + (size_t)row * 1024 : p.x_sample + (size_t)(row - MP) * 1024;
;     else src = p.x + (size_t)row * 1024;
;     float4 v[4];
;     float ss = 0.f;
; #pragma unroll
;     for (int i = 0; i < 4; ++i) {
;       v[i] = ((const float4*)src)[lane + 64 * i];
;       ss += v[i].x * v[i].x + v[i].y * v[i].y + v[i].z * v[i].z + v[i].w * v[i].w;
;     }
;     ss = wsum(ss, lane);
;     if (mode == 1) {
;       if (lane == 0) SS0[row] = ss;
; #pragma unroll
;       for (int i = 0; i < 4; ++i) {
;         uint2 o;
;         o.x = pack2(v[i].x, v[i].y);
;         o.y = pack2(v[i].z, v[i].w);
;         *(uint2*)(XB + (size_t)row * 1024 + (lane + 64 * i) * 4) = o;
;       }
.LBB0_107:
	s_or_b64 exec, exec, s[0:1]
	v_lshlrev_b64 v[28:29], 11, v[18:19]
	v_cvt_pk_bf16_f32 v14, v14, v15
	v_cvt_pk_bf16_f32 v15, v16, v17
	v_lshl_add_u64 v[16:17], v[22:23], 0, v[28:29]
	v_cvt_pk_bf16_f32 v2, v2, v3
	v_cvt_pk_bf16_f32 v3, v4, v5
	global_store_dwordx2 v[16:17], v[2:3], off offset:512
	v_cvt_pk_bf16_f32 v2, v6, v7
	v_cvt_pk_bf16_f32 v3, v8, v9
	global_store_dwordx2 v[16:17], v[2:3], off offset:1024
	v_cvt_pk_bf16_f32 v2, v10, v11
	v_cvt_pk_bf16_f32 v3, v12, v13
	s_mov_b32 s0, s44
	global_store_dwordx2 v[16:17], v[14:15], off
	global_store_dwordx2 v[16:17], v[2:3], off offset:1536
	s_nop 0
	v_lshl_add_u32 v18, s0, 3, v18
	v_cmp_lt_i32_e64 s[0:1], s11, v18
	s_or_b64 s[8:9], s[0:1], s[8:9]
	s_andn2_b64 exec, exec, s[8:9]
	s_cbranch_execz .LBB0_110
.LBB0_108:
	v_ashrrev_i32_e32 v19, 31, v18
	v_add_u32_e32 v2, 0xffff0000, v18
	v_cmp_gt_i32_e64 s[0:1], s10, v18
	s_nop 1
	v_cndmask_b32_e64 v3, 0, v19, s[0:1]
	v_cndmask_b32_e64 v2, v2, v18, s[0:1]
	v_cndmask_b32_e64 v5, v24, v25, s[0:1]
	v_cndmask_b32_e64 v4, v26, v27, s[0:1]
	v_lshlrev_b64 v[2:3], 12, v[2:3]
	v_lshl_add_u64 v[2:3], v[4:5], 0, v[2:3]
	v_lshl_add_u64 v[28:29], v[2:3], 0, v[20:21]
	global_load_dwordx4 v[14:17], v[28:29], off
	global_load_dwordx4 v[2:5], v[28:29], off offset:1024
	global_load_dwordx4 v[6:9], v[28:29], off offset:2048
	global_load_dwordx4 v[10:13], v[28:29], off offset:3072
	s_waitcnt vmcnt(0)
	v_pk_mul_f32 v[28:29], v[14:15], v[14:15]
	v_pk_mul_f32 v[32:33], v[2:3], v[2:3]
	v_pk_mul_f32 v[30:31], v[16:17], v[16:17]
	v_pk_mul_f32 v[34:35], v[4:5], v[4:5]
	v_pk_mul_f32 v[36:37], v[6:7], v[6:7]
	v_add_f32_e32 v32, v32, v33
	v_add_f32_e32 v28, v28, v29
	v_pk_mul_f32 v[38:39], v[8:9], v[8:9]
	v_pk_mul_f32 v[40:41], v[10:11], v[10:11]
	v_add_f32_e32 v29, v36, v37
	v_add_f32_e32 v32, v32, v34
	v_add_f32_e32 v28, v28, v30
	v_pk_mul_f32 v[42:43], v[12:13], v[12:13]
	v_add_f32_e32 v33, v40, v41
	v_add_f32_e32 v29, v29, v38
	v_add_f32_e32 v32, v32, v35
	v_add_f32_e32 v28, v28, v31
	v_add_f32_e32 v30, v33, v42
	v_add_f32_e32 v29, v29, v39
	v_add_f32_e32 v28, v28, v32
	v_add_f32_e32 v30, v30, v43
	v_add_f32_e32 v28, v28, v29
	v_add_f32_e32 v28, v28, v30
	s_nop 1
	v_add_f32_dpp v28, v28, v28 row_ror:8 row_mask:0xf bank_mask:0xf bound_ctrl:1
	s_nop 1
	v_add_f32_dpp v28, v28, v28 row_ror:4 row_mask:0xf bank_mask:0xf bound_ctrl:1
	s_nop 1
	v_add_f32_dpp v28, v28, v28 row_ror:2 row_mask:0xf bank_mask:0xf bound_ctrl:1
	s_nop 1
	v_add_f32_dpp v28, v28, v28 row_ror:1 row_mask:0xf bank_mask:0xf bound_ctrl:1
	s_nop 0
	v_readlane_b32 s12, v28, 0
	v_readlane_b32 s15, v28, 16
	v_readlane_b32 s13, v28, 32
	v_readlane_b32 s14, v28, 48
	s_and_saveexec_b64 s[0:1], vcc
	s_cbranch_execz .LBB0_107
	v_mov_b32_e32 v30, s15
	v_add_f32_e32 v30, s12, v30
	v_add_f32_e32 v30, s13, v30
	v_lshl_add_u64 v[28:29], v[18:19], 2, s[6:7]
	v_add_f32_e32 v30, s14, v30
	global_store_dword v[28:29], v30, off
	s_branch .LBB0_107

; DEVI float fsig(float x) { return __builtin_amdgcn_rcpf(1.f + __expf(-x)); }
; DEVI float bflo(unsigned u) { return __uint_as_float(u << 16); }
; DEVI float bfhi(unsigned u) { return __uint_as_float(u & 0xffff0000u); }
; template <int EPI, int TS, bool VT>
; DEVI void gemm_epilogue(const Params& p, char* smem, f32x4 (&acc)[2][2][4][2], int m0, int n0, float scale, const float* ssin,
;                         float* ssout, u16* xbout, int wid, int lane, int wr, int wc, int fr, int fq) {
;     ...
;         for (int u = 0; u < 8; ++u) {
;           const int i = i0 + u;
;           const int grow = g0 + i;
;           const float* Tr = T + (r0 + i) * TS;
;           const float rs = __int_as_float(__builtin_amdgcn_readlane(__float_as_int(rsv), i));
;           if constexpr (EPI == E_RESID || EPI == E_PLEGATE) {
;             const float4 a = *(const float4*)(Tr + 4 * lane);
;             const size_t ro = (size_t)grow * 1024 + n0 + 4 * lane;
;             float4 x4 = xo[u];
;             if constexpr (EPI == E_PLEGATE) {
;               x4.x += bflo(pv[u].x) * fsig(a.x * rs);
;               x4.y += bfhi(pv[u].x) * fsig(a.y * rs);
;               x4.z += bflo(pv[u].y) * fsig(a.z * rs);
;               x4.w += bfhi(pv[u].y) * fsig(a.w * rs);
;             } else {
;               const float sc = fabsf(scale);
;               x4.x += sc * a.x; x4.y += sc * a.y; x4.z += sc * a.z; x4.w += sc * a.w;
;             }
;             st_nt16(p.x + ro, x4);
;             if (xbout) {
;               uint2 o;
;               o.x = pack2(x4.x, x4.y);
;               o.y = pack2(x4.z, x4.w);
;               st_nt8(xbout + ro, o);
;             }
;             if (ssout) {
;               const float ssq = wsum(x4.x * x4.x + x4.y * x4.y + x4.z * x4.z + x4.w * x4.w, lane);
;               if (lane == 0) atomicAdd(ssout + grow, ssq);
;             }
.LBB0_209:
	global_load_dwordx4 v[64:67], v[64:65], off
	v_lshlrev_b32_e32 v130, 2, v130
	s_mulk_i32 s68, 0x4100
	v_add_u32_e32 v130, s68, v130
	ds_read_b128 v[154:157], v130
	v_cmp_eq_u32_e64 s[0:1], 0, v152
	v_lshl_add_u64 v[114:115], v[114:115], 1, s[8:9]
	s_waitcnt vmcnt(7) lgkmcnt(0)
	v_pk_fma_f32 v[92:93], s[12:13], v[154:155], v[92:93]
	v_pk_fma_f32 v[94:95], s[12:13], v[156:157], v[94:95]
	global_store_dwordx4 v[122:123], v[92:95], off
	v_cvt_pk_bf16_f32 v122, v92, v93
	v_cvt_pk_bf16_f32 v123, v94, v95
	v_pk_mul_f32 v[92:93], v[92:93], v[92:93]
	v_pk_mul_f32 v[94:95], v[94:95], v[94:95]
	v_add_f32_e32 v92, v92, v93
	v_add_f32_e32 v92, v92, v94
	v_add_f32_e32 v92, v92, v95
	global_store_dwordx2 v[114:115], v[122:123], off
	s_nop 0
	v_add_f32_dpp v92, v92, v92 row_ror:8 row_mask:0xf bank_mask:0xf bound_ctrl:1
	s_nop 1
	v_add_f32_dpp v92, v92, v92 row_ror:4 row_mask:0xf bank_mask:0xf bound_ctrl:1
	s_nop 1
	v_add_f32_dpp v92, v92, v92 row_ror:2 row_mask:0xf bank_mask:0xf bound_ctrl:1
	s_nop 1
	v_add_f32_dpp v92, v92, v92 row_ror:1 row_mask:0xf bank_mask:0xf bound_ctrl:1
	s_nop 0
	v_readlane_b32 s70, v92, 0
	v_readlane_b32 s76, v92, 16
	v_readlane_b32 s71, v92, 32
	v_readlane_b32 s75, v92, 48
	s_and_saveexec_b64 s[68:69], s[0:1]
	s_cbranch_execz .LBB0_211
	s_lshl_b64 s[78:79], s[18:19], 2
	v_mov_b32_e32 v92, s76
	s_add_u32 s78, s16, s78
	v_add_f32_e32 v92, s70, v92
	s_addc_u32 s79, s17, s79
	v_add_f32_e32 v92, s71, v92
	v_add_f32_e32 v94, s75, v92
	v_mov_b64_e32 v[92:93], s[78:79]
	global_atomic_add_f32 v[92:93], v94, off
.LBB0_211:
	s_or_b64 exec, exec, s[68:69]
	ds_read_b128 v[92:95], v130 offset:1040
	v_lshl_add_u64 v[114:115], v[126:127], 1, s[8:9]
	s_waitcnt vmcnt(0) lgkmcnt(0)
	v_pk_fma_f32 v[88:89], s[12:13], v[92:93], v[88:89]
	v_pk_fma_f32 v[90:91], s[12:13], v[94:95], v[90:91]
	global_store_dwordx4 v[124:125], v[88:91], off
	v_cvt_pk_bf16_f32 v92, v88, v89
	v_cvt_pk_bf16_f32 v93, v90, v91
	v_pk_mul_f32 v[88:89], v[88:89], v[88:89]
	v_pk_mul_f32 v[90:91], v[90:91], v[90:91]
	v_add_f32_e32 v88, v88, v89
	v_add_f32_e32 v88, v88, v90
	v_add_f32_e32 v88, v88, v91
	global_store_dwordx2 v[114:115], v[92:93], off
	s_nop 0
	v_add_f32_dpp v88, v88, v88 row_ror:8 row_mask:0xf bank_mask:0xf bound_ctrl:1
	s_nop 1
	v_add_f32_dpp v88, v88, v88 row_ror:4 row_mask:0xf bank_mask:0xf bound_ctrl:1
	s_nop 1
	v_add_f32_dpp v88, v88, v88 row_ror:2 row_mask:0xf bank_mask:0xf bound_ctrl:1
	s_nop 1
	v_add_f32_dpp v88, v88, v88 row_ror:1 row_mask:0xf bank_mask:0xf bound_ctrl:1
	s_nop 0
	v_readlane_b32 s19, v88, 0
	v_readlane_b32 s75, v88, 16
	v_readlane_b32 s70, v88, 32
	v_readlane_b32 s71, v88, 48
	s_and_saveexec_b64 s[68:69], s[0:1]
	s_cbranch_execz .LBB0_213
	s_lshl_b64 s[66:67], s[66:67], 2
	v_mov_b32_e32 v88, s75
	s_add_u32 s66, s16, s66
	v_add_f32_e32 v88, s19, v88
	s_addc_u32 s67, s17, s67
	v_add_f32_e32 v88, s70, v88
	v_add_f32_e32 v90, s71, v88
	v_mov_b64_e32 v[88:89], s[66:67]
	global_atomic_add_f32 v[88:89], v90, off
.LBB0_213:
	s_or_b64 exec, exec, s[68:69]
	ds_read_b128 v[88:91], v130 offset:2080
	v_lshl_add_u64 v[92:93], v[120:121], 1, s[8:9]
	s_waitcnt lgkmcnt(0)
	v_pk_fma_f32 v[84:85], s[12:13], v[88:89], v[84:85]
	v_pk_fma_f32 v[86:87], s[12:13], v[90:91], v[86:87]
	global_store_dwordx4 v[118:119], v[84:87], off
	v_cvt_pk_bf16_f32 v88, v84, v85
	v_cvt_pk_bf16_f32 v89, v86, v87
	v_pk_mul_f32 v[84:85], v[84:85], v[84:85]
	v_pk_mul_f32 v[86:87], v[86:87], v[86:87]
	v_add_f32_e32 v84, v84, v85
	v_add_f32_e32 v84, v84, v86
	v_add_f32_e32 v84, v84, v87
	global_store_dwordx2 v[92:93], v[88:89], off
	s_nop 0
	v_add_f32_dpp v84, v84, v84 row_ror:8 row_mask:0xf bank_mask:0xf bound_ctrl:1
	s_nop 1
	v_add_f32_dpp v84, v84, v84 row_ror:4 row_mask:0xf bank_mask:0xf bound_ctrl:1
	s_nop 1
	v_add_f32_dpp v84, v84, v84 row_ror:2 row_mask:0xf bank_mask:0xf bound_ctrl:1
	s_nop 1
	v_add_f32_dpp v84, v84, v84 row_ror:1 row_mask:0xf bank_mask:0xf bound_ctrl:1
	s_nop 0
	v_readlane_b32 s19, v84, 0
	v_readlane_b32 s70, v84, 16
	v_readlane_b32 s68, v84, 32
	v_readlane_b32 s69, v84, 48
	s_and_saveexec_b64 s[66:67], s[0:1]
	s_cbranch_execz .LBB0_215
	s_lshl_b64 s[64:65], s[64:65], 2
	v_mov_b32_e32 v84, s70
	s_add_u32 s64, s16, s64
	v_add_f32_e32 v84, s19, v84
	s_addc_u32 s65, s17, s65
	v_add_f32_e32 v84, s68, v84
	v_add_f32_e32 v86, s69, v84
	v_mov_b64_e32 v[84:85], s[64:65]
	global_atomic_add_f32 v[84:85], v86, off
.LBB0_215:
	s_or_b64 exec, exec, s[66:67]
	ds_read_b128 v[84:87], v130 offset:3120
	v_lshl_add_u64 v[88:89], v[116:117], 1, s[8:9]
	s_waitcnt lgkmcnt(0)
	v_pk_fma_f32 v[80:81], s[12:13], v[84:85], v[80:81]
	v_pk_fma_f32 v[82:83], s[12:13], v[86:87], v[82:83]
	global_store_dwordx4 v[112:113], v[80:83], off
	v_cvt_pk_bf16_f32 v84, v80, v81
	v_cvt_pk_bf16_f32 v85, v82, v83
	v_pk_mul_f32 v[80:81], v[80:81], v[80:81]
	v_pk_mul_f32 v[82:83], v[82:83], v[82:83]
	v_add_f32_e32 v80, v80, v81
	v_add_f32_e32 v80, v80, v82
	v_add_f32_e32 v80, v80, v83
	global_store_dwordx2 v[88:89], v[84:85], off
	s_nop 0
	v_add_f32_dpp v80, v80, v80 row_ror:8 row_mask:0xf bank_mask:0xf bound_ctrl:1
	s_nop 1
	v_add_f32_dpp v80, v80, v80 row_ror:4 row_mask:0xf bank_mask:0xf bound_ctrl:1
	s_nop 1
	v_add_f32_dpp v80, v80, v80 row_ror:2 row_mask:0xf bank_mask:0xf bound_ctrl:1
	s_nop 1
	v_add_f32_dpp v80, v80, v80 row_ror:1 row_mask:0xf bank_mask:0xf bound_ctrl:1
	s_nop 0
	v_readlane_b32 s19, v80, 0
	v_readlane_b32 s68, v80, 16
	v_readlane_b32 s66, v80, 32
	v_readlane_b32 s67, v80, 48
	s_and_saveexec_b64 s[64:65], s[0:1]
	s_cbranch_execz .LBB0_217
	s_lshl_b64 s[62:63], s[62:63], 2
	v_mov_b32_e32 v80, s68
	s_add_u32 s62, s16, s62
	v_add_f32_e32 v80, s19, v80
	s_addc_u32 s63, s17, s63
	v_add_f32_e32 v80, s66, v80
	v_add_f32_e32 v82, s67, v80
	v_mov_b64_e32 v[80:81], s[62:63]
	global_atomic_add_f32 v[80:81], v82, off
; DEVI float fsig(float x) { return __builtin_amdgcn_rcpf(1.f + __expf(-x)); }
; DEVI float bflo(unsigned u) { return __uint_as_float(u << 16); }
; DEVI float bfhi(unsigned u) { return __uint_as_float(u & 0xffff0000u); }
; template <int EPI, int TS, bool VT>
; DEVI void gemm_epilogue(const Params& p, char* smem, f32x4 (&acc)[2][2][4][2], int m0, int n0, float scale, const float* ssin,
;                         float* ssout, u16* xbout, int wid, int lane, int wr, int wc, int fr, int fq) {
;     ...
;         for (int u = 0; u < 8; ++u) {
;           const int i = i0 + u;
;           const int grow = g0 + i;
;           const float* Tr = T + (r0 + i) * TS;
;           const float rs = __int_as_float(__builtin_amdgcn_readlane(__float_as_int(rsv), i));
;           if constexpr (EPI == E_RESID || EPI == E_PLEGATE) {
;             const float4 a = *(const float4*)(Tr + 4 * lane);
;             const size_t ro = (size_t)grow * 1024 + n0 + 4 * lane;
;             float4 x4 = xo[u];
;             if constexpr (EPI == E_PLEGATE) {
;               x4.x += bflo(pv[u].x) * fsig(a.x * rs);
;               x4.y += bfhi(pv[u].x) * fsig(a.y * rs);
;               x4.z += bflo(pv[u].y) * fsig(a.z * rs);
;               x4.w += bfhi(pv[u].y) * fsig(a.w * rs);
;             } else {
;               const float sc = fabsf(scale);
;               x4.x += sc * a.x; x4.y += sc * a.y; x4.z += sc * a.z; x4.w += sc * a.w;
;             }
;             st_nt16(p.x + ro, x4);
;             if (xbout) {
;               uint2 o;
;               o.x = pack2(x4.x, x4.y);
;               o.y = pack2(x4.z, x4.w);
;               st_nt8(xbout + ro, o);
;             }
;             if (ssout) {
;               const float ssq = wsum(x4.x * x4.x + x4.y * x4.y + x4.z * x4.z + x4.w * x4.w, lane);
;               if (lane == 0) atomicAdd(ssout + grow, ssq);
;             }
.LBB0_217:
	s_or_b64 exec, exec, s[64:65]
	ds_read_b128 v[80:83], v130 offset:4160
	v_lshl_add_u64 v[84:85], v[110:111], 1, s[8:9]
	s_waitcnt lgkmcnt(0)
	v_pk_fma_f32 v[76:77], s[12:13], v[80:81], v[76:77]
	v_pk_fma_f32 v[78:79], s[12:13], v[82:83], v[78:79]
	global_store_dwordx4 v[108:109], v[76:79], off
	v_cvt_pk_bf16_f32 v80, v76, v77
	v_cvt_pk_bf16_f32 v81, v78, v79
	v_pk_mul_f32 v[76:77], v[76:77], v[76:77]
	v_pk_mul_f32 v[78:79], v[78:79], v[78:79]
	v_add_f32_e32 v76, v76, v77
	v_add_f32_e32 v76, v76, v78
	v_add_f32_e32 v76, v76, v79
	global_store_dwordx2 v[84:85], v[80:81], off
	s_nop 0
	v_add_f32_dpp v76, v76, v76 row_ror:8 row_mask:0xf bank_mask:0xf bound_ctrl:1
	s_nop 1
	v_add_f32_dpp v76, v76, v76 row_ror:4 row_mask:0xf bank_mask:0xf bound_ctrl:1
	s_nop 1
	v_add_f32_dpp v76, v76, v76 row_ror:2 row_mask:0xf bank_mask:0xf bound_ctrl:1
	s_nop 1
	v_add_f32_dpp v76, v76, v76 row_ror:1 row_mask:0xf bank_mask:0xf bound_ctrl:1
	s_nop 0
	v_readlane_b32 s19, v76, 0
	v_readlane_b32 s66, v76, 16
	v_readlane_b32 s64, v76, 32
	v_readlane_b32 s65, v76, 48
	s_and_saveexec_b64 s[62:63], s[0:1]
	s_cbranch_execz .LBB0_219
	s_lshl_b64 s[34:35], s[34:35], 2
	v_mov_b32_e32 v76, s66
	s_add_u32 s34, s16, s34
	v_add_f32_e32 v76, s19, v76
	s_addc_u32 s35, s17, s35
	v_add_f32_e32 v76, s64, v76
	v_add_f32_e32 v78, s65, v76
	v_mov_b64_e32 v[76:77], s[34:35]
	global_atomic_add_f32 v[76:77], v78, off
.LBB0_219:
	s_or_b64 exec, exec, s[62:63]
	ds_read_b128 v[76:79], v130 offset:5200
	v_lshl_add_u64 v[80:81], v[106:107], 1, s[8:9]
	s_waitcnt lgkmcnt(0)
	v_pk_fma_f32 v[72:73], s[12:13], v[76:77], v[72:73]
	v_pk_fma_f32 v[74:75], s[12:13], v[78:79], v[74:75]
	global_store_dwordx4 v[104:105], v[72:75], off
	v_cvt_pk_bf16_f32 v76, v72, v73
	v_cvt_pk_bf16_f32 v77, v74, v75
	v_pk_mul_f32 v[72:73], v[72:73], v[72:73]
	v_pk_mul_f32 v[74:75], v[74:75], v[74:75]
	v_add_f32_e32 v72, v72, v73
	v_add_f32_e32 v72, v72, v74
	v_add_f32_e32 v72, v72, v75
	global_store_dwordx2 v[80:81], v[76:77], off
	s_nop 0
	v_add_f32_dpp v72, v72, v72 row_ror:8 row_mask:0xf bank_mask:0xf bound_ctrl:1
	s_nop 1
	v_add_f32_dpp v72, v72, v72 row_ror:4 row_mask:0xf bank_mask:0xf bound_ctrl:1
	s_nop 1
	v_add_f32_dpp v72, v72, v72 row_ror:2 row_mask:0xf bank_mask:0xf bound_ctrl:1
	s_nop 1
	v_add_f32_dpp v72, v72, v72 row_ror:1 row_mask:0xf bank_mask:0xf bound_ctrl:1
	s_nop 0
	v_readlane_b32 s19, v72, 0
	v_readlane_b32 s64, v72, 16
	v_readlane_b32 s62, v72, 32
	v_readlane_b32 s63, v72, 48
	s_and_saveexec_b64 s[34:35], s[0:1]
	s_cbranch_execz .LBB0_221
	s_lshl_b64 s[30:31], s[30:31], 2
	v_mov_b32_e32 v72, s64
	s_add_u32 s30, s16, s30
	v_add_f32_e32 v72, s19, v72
	s_addc_u32 s31, s17, s31
	v_add_f32_e32 v72, s62, v72
	v_add_f32_e32 v74, s63, v72
	v_mov_b64_e32 v[72:73], s[30:31]
	global_atomic_add_f32 v[72:73], v74, off
.LBB0_221:
	s_or_b64 exec, exec, s[34:35]
	ds_read_b128 v[72:75], v130 offset:6240
	v_lshl_add_u64 v[76:77], v[102:103], 1, s[8:9]
	s_waitcnt lgkmcnt(0)
	v_pk_fma_f32 v[68:69], s[12:13], v[72:73], v[68:69]
	v_pk_fma_f32 v[70:71], s[12:13], v[74:75], v[70:71]
	global_store_dwordx4 v[100:101], v[68:71], off
	v_cvt_pk_bf16_f32 v72, v68, v69
	v_cvt_pk_bf16_f32 v73, v70, v71
	v_pk_mul_f32 v[68:69], v[68:69], v[68:69]
	v_pk_mul_f32 v[70:71], v[70:71], v[70:71]
	v_add_f32_e32 v68, v68, v69
	v_add_f32_e32 v68, v68, v70
	v_add_f32_e32 v68, v68, v71
	global_store_dwordx2 v[76:77], v[72:73], off
	s_nop 0
	v_add_f32_dpp v68, v68, v68 row_ror:8 row_mask:0xf bank_mask:0xf bound_ctrl:1
	s_nop 1
	v_add_f32_dpp v68, v68, v68 row_ror:4 row_mask:0xf bank_mask:0xf bound_ctrl:1
	s_nop 1
	v_add_f32_dpp v68, v68, v68 row_ror:2 row_mask:0xf bank_mask:0xf bound_ctrl:1
	s_nop 1
	v_add_f32_dpp v68, v68, v68 row_ror:1 row_mask:0xf bank_mask:0xf bound_ctrl:1
	s_nop 0
	v_readlane_b32 s19, v68, 0
	v_readlane_b32 s62, v68, 16
	v_readlane_b32 s34, v68, 32
	v_readlane_b32 s35, v68, 48
	s_and_saveexec_b64 s[30:31], s[0:1]
	s_cbranch_execz .LBB0_223
	s_lshl_b64 s[22:23], s[22:23], 2
	v_mov_b32_e32 v68, s62
	s_add_u32 s22, s16, s22
	v_add_f32_e32 v68, s19, v68
	s_addc_u32 s23, s17, s23
	v_add_f32_e32 v68, s34, v68
	v_add_f32_e32 v70, s35, v68
	v_mov_b64_e32 v[68:69], s[22:23]
	global_atomic_add_f32 v[68:69], v70, off
.LBB0_223:
	s_or_b64 exec, exec, s[30:31]
	ds_read_b128 v[68:71], v130 offset:7280
	v_lshl_add_u64 v[72:73], v[98:99], 1, s[8:9]
	s_waitcnt lgkmcnt(0)
	v_pk_fma_f32 v[64:65], s[12:13], v[68:69], v[64:65]
	v_pk_fma_f32 v[66:67], s[12:13], v[70:71], v[66:67]
	global_store_dwordx4 v[96:97], v[64:67], off
	v_cvt_pk_bf16_f32 v68, v64, v65
	v_cvt_pk_bf16_f32 v69, v66, v67
	v_pk_mul_f32 v[64:65], v[64:65], v[64:65]
	v_pk_mul_f32 v[66:67], v[66:67], v[66:67]
	v_add_f32_e32 v64, v64, v65
	v_add_f32_e32 v64, v64, v66
	v_add_f32_e32 v64, v64, v67
	global_store_dwordx2 v[72:73], v[68:69], off
	s_nop 0
	v_add_f32_dpp v64, v64, v64 row_ror:8 row_mask:0xf bank_mask:0xf bound_ctrl:1
	s_nop 1
	v_add_f32_dpp v64, v64, v64 row_ror:4 row_mask:0xf bank_mask:0xf bound_ctrl:1
	s_nop 1
	v_add_f32_dpp v64, v64, v64 row_ror:2 row_mask:0xf bank_mask:0xf bound_ctrl:1
	s_nop 1
	v_add_f32_dpp v64, v64, v64 row_ror:1 row_mask:0xf bank_mask:0xf bound_ctrl:1
	s_nop 0
	v_readlane_b32 s19, v64, 0
	v_readlane_b32 s34, v64, 16
	v_readlane_b32 s30, v64, 32
	v_readlane_b32 s31, v64, 48
	s_and_saveexec_b64 s[22:23], s[0:1]
	s_cbranch_execz .LBB0_225
	s_lshl_b64 s[20:21], s[20:21], 2
	v_mov_b32_e32 v64, s34
	s_add_u32 s20, s16, s20
	v_add_f32_e32 v64, s19, v64
	s_addc_u32 s21, s17, s21
	v_add_f32_e32 v64, s30, v64
	v_add_f32_e32 v66, s31, v64
	v_mov_b64_e32 v[64:65], s[20:21]
	global_atomic_add_f32 v[64:65], v66, off

; DEVI float fsig(float x) { return __builtin_amdgcn_rcpf(1.f + __expf(-x)); }
; DEVI float bflo(unsigned u) { return __uint_as_float(u << 16); }
; DEVI float bfhi(unsigned u) { return __uint_as_float(u & 0xffff0000u); }
; template <int EPI, int TS, bool VT>
; DEVI void gemm_epilogue(const Params& p, char* smem, f32x4 (&acc)[2][2][4][2], int m0, int n0, float scale, const float* ssin,
;                         float* ssout, u16* xbout, int wid, int lane, int wr, int wc, int fr, int fq) {
;     ...
;         for (int u = 0; u < 8; ++u) {
;           const int i = i0 + u;
;           const int grow = g0 + i;
;           const float* Tr = T + (r0 + i) * TS;
;           const float rs = __int_as_float(__builtin_amdgcn_readlane(__float_as_int(rsv), i));
;           if constexpr (EPI == E_RESID || EPI == E_PLEGATE) {
;             const float4 a = *(const float4*)(Tr + 4 * lane);
;             const size_t ro = (size_t)grow * 1024 + n0 + 4 * lane;
;             float4 x4 = xo[u];
;             if constexpr (EPI == E_PLEGATE) {
;               x4.x += bflo(pv[u].x) * fsig(a.x * rs);
;               x4.y += bfhi(pv[u].x) * fsig(a.y * rs);
;               x4.z += bflo(pv[u].y) * fsig(a.z * rs);
;               x4.w += bfhi(pv[u].y) * fsig(a.w * rs);
;             } else {
;               const float sc = fabsf(scale);
;               x4.x += sc * a.x; x4.y += sc * a.y; x4.z += sc * a.z; x4.w += sc * a.w;
;             }
;             st_nt16(p.x + ro, x4);
;             if (xbout) {
;               uint2 o;
;               o.x = pack2(x4.x, x4.y);
;               o.y = pack2(x4.z, x4.w);
;               st_nt8(xbout + ro, o);
;             }
;             if (ssout) {
;               const float ssq = wsum(x4.x * x4.x + x4.y * x4.y + x4.z * x4.z + x4.w * x4.w, lane);
;               if (lane == 0) atomicAdd(ssout + grow, ssq);
;             }
.LBB0_265:
	global_load_dwordx4 v[64:67], v[64:65], off
	ds_read_b128 v[152:155], v130 offset:8320
	v_lshl_add_u64 v[120:121], v[120:121], 1, s[8:9]
	s_waitcnt vmcnt(0) lgkmcnt(0)
	v_pk_fma_f32 v[92:93], s[12:13], v[152:153], v[92:93]
	v_pk_fma_f32 v[94:95], s[12:13], v[154:155], v[94:95]
	global_store_dwordx4 v[126:127], v[92:95], off
	v_cvt_pk_bf16_f32 v126, v92, v93
	v_cvt_pk_bf16_f32 v127, v94, v95
	v_pk_mul_f32 v[92:93], v[92:93], v[92:93]
	v_pk_mul_f32 v[94:95], v[94:95], v[94:95]
	v_add_f32_e32 v92, v92, v93
	v_add_f32_e32 v92, v92, v94
	v_add_f32_e32 v92, v92, v95
	global_store_dwordx2 v[120:121], v[126:127], off
	s_nop 0
	v_add_f32_dpp v92, v92, v92 row_ror:8 row_mask:0xf bank_mask:0xf bound_ctrl:1
	s_nop 1
	v_add_f32_dpp v92, v92, v92 row_ror:4 row_mask:0xf bank_mask:0xf bound_ctrl:1
	s_nop 1
	v_add_f32_dpp v92, v92, v92 row_ror:2 row_mask:0xf bank_mask:0xf bound_ctrl:1
	s_nop 1
	v_add_f32_dpp v92, v92, v92 row_ror:1 row_mask:0xf bank_mask:0xf bound_ctrl:1
	s_nop 0
	v_readlane_b32 s19, v92, 0
	v_readlane_b32 s77, v92, 16
	v_readlane_b32 s75, v92, 32
	v_readlane_b32 s76, v92, 48
	s_and_saveexec_b64 s[70:71], s[0:1]
	s_cbranch_execz .LBB0_267
	s_lshl_b64 s[68:69], s[68:69], 2
	v_mov_b32_e32 v92, s77
	s_add_u32 s68, s16, s68
	v_add_f32_e32 v92, s19, v92
	s_addc_u32 s69, s17, s69
	v_add_f32_e32 v92, s75, v92
	v_add_f32_e32 v94, s76, v92
	v_mov_b64_e32 v[92:93], s[68:69]
	global_atomic_add_f32 v[92:93], v94, off
.LBB0_267:
	s_or_b64 exec, exec, s[70:71]
	ds_read_b128 v[92:95], v130 offset:9360
	v_lshl_add_u64 v[120:121], v[124:125], 1, s[8:9]
	s_waitcnt lgkmcnt(0)
	v_pk_fma_f32 v[88:89], s[12:13], v[92:93], v[88:89]
	v_pk_fma_f32 v[90:91], s[12:13], v[94:95], v[90:91]
	global_store_dwordx4 v[122:123], v[88:91], off
	v_cvt_pk_bf16_f32 v92, v88, v89
	v_cvt_pk_bf16_f32 v93, v90, v91
	v_pk_mul_f32 v[88:89], v[88:89], v[88:89]
	v_pk_mul_f32 v[90:91], v[90:91], v[90:91]
	v_add_f32_e32 v88, v88, v89
	v_add_f32_e32 v88, v88, v90
	v_add_f32_e32 v88, v88, v91
	global_store_dwordx2 v[120:121], v[92:93], off
	s_nop 0
	v_add_f32_dpp v88, v88, v88 row_ror:8 row_mask:0xf bank_mask:0xf bound_ctrl:1
	s_nop 1
	v_add_f32_dpp v88, v88, v88 row_ror:4 row_mask:0xf bank_mask:0xf bound_ctrl:1
	s_nop 1
	v_add_f32_dpp v88, v88, v88 row_ror:2 row_mask:0xf bank_mask:0xf bound_ctrl:1
	s_nop 1
	v_add_f32_dpp v88, v88, v88 row_ror:1 row_mask:0xf bank_mask:0xf bound_ctrl:1
	s_nop 0
	v_readlane_b32 s19, v88, 0
	v_readlane_b32 s75, v88, 16
	v_readlane_b32 s70, v88, 32
	v_readlane_b32 s71, v88, 48
	s_and_saveexec_b64 s[68:69], s[0:1]
	s_cbranch_execz .LBB0_269
	s_lshl_b64 s[66:67], s[66:67], 2
	v_mov_b32_e32 v88, s75
	s_add_u32 s66, s16, s66
	v_add_f32_e32 v88, s19, v88
	s_addc_u32 s67, s17, s67
	v_add_f32_e32 v88, s70, v88
	v_add_f32_e32 v90, s71, v88
	v_mov_b64_e32 v[88:89], s[66:67]
	global_atomic_add_f32 v[88:89], v90, off
.LBB0_269:
	s_or_b64 exec, exec, s[68:69]
	ds_read_b128 v[88:91], v130 offset:10400
	v_lshl_add_u64 v[92:93], v[118:119], 1, s[8:9]
	s_waitcnt lgkmcnt(0)
	v_pk_fma_f32 v[84:85], s[12:13], v[88:89], v[84:85]
	v_pk_fma_f32 v[86:87], s[12:13], v[90:91], v[86:87]
	global_store_dwordx4 v[116:117], v[84:87], off
	v_cvt_pk_bf16_f32 v88, v84, v85
	v_cvt_pk_bf16_f32 v89, v86, v87
	v_pk_mul_f32 v[84:85], v[84:85], v[84:85]
	v_pk_mul_f32 v[86:87], v[86:87], v[86:87]
	v_add_f32_e32 v84, v84, v85
	v_add_f32_e32 v84, v84, v86
	v_add_f32_e32 v84, v84, v87
	global_store_dwordx2 v[92:93], v[88:89], off
	s_nop 0
	v_add_f32_dpp v84, v84, v84 row_ror:8 row_mask:0xf bank_mask:0xf bound_ctrl:1
	s_nop 1
	v_add_f32_dpp v84, v84, v84 row_ror:4 row_mask:0xf bank_mask:0xf bound_ctrl:1
	s_nop 1
	v_add_f32_dpp v84, v84, v84 row_ror:2 row_mask:0xf bank_mask:0xf bound_ctrl:1
	s_nop 1
	v_add_f32_dpp v84, v84, v84 row_ror:1 row_mask:0xf bank_mask:0xf bound_ctrl:1
	s_nop 0
	v_readlane_b32 s19, v84, 0
	v_readlane_b32 s70, v84, 16
	v_readlane_b32 s68, v84, 32
	v_readlane_b32 s69, v84, 48
	s_and_saveexec_b64 s[66:67], s[0:1]
	s_cbranch_execz .LBB0_271
	s_lshl_b64 s[64:65], s[64:65], 2
	v_mov_b32_e32 v84, s70
	s_add_u32 s64, s16, s64
	v_add_f32_e32 v84, s19, v84
	s_addc_u32 s65, s17, s65
	v_add_f32_e32 v84, s68, v84
	v_add_f32_e32 v86, s69, v84
	v_mov_b64_e32 v[84:85], s[64:65]
	global_atomic_add_f32 v[84:85], v86, off
.LBB0_271:
	s_or_b64 exec, exec, s[66:67]
	ds_read_b128 v[84:87], v130 offset:11440
	v_lshl_add_u64 v[88:89], v[114:115], 1, s[8:9]
	s_waitcnt lgkmcnt(0)
	v_pk_fma_f32 v[80:81], s[12:13], v[84:85], v[80:81]
	v_pk_fma_f32 v[82:83], s[12:13], v[86:87], v[82:83]
	global_store_dwordx4 v[112:113], v[80:83], off
	v_cvt_pk_bf16_f32 v84, v80, v81
	v_cvt_pk_bf16_f32 v85, v82, v83
	v_pk_mul_f32 v[80:81], v[80:81], v[80:81]
	v_pk_mul_f32 v[82:83], v[82:83], v[82:83]
	v_add_f32_e32 v80, v80, v81
	v_add_f32_e32 v80, v80, v82
	v_add_f32_e32 v80, v80, v83
	global_store_dwordx2 v[88:89], v[84:85], off
	s_nop 0
	v_add_f32_dpp v80, v80, v80 row_ror:8 row_mask:0xf bank_mask:0xf bound_ctrl:1
	s_nop 1
	v_add_f32_dpp v80, v80, v80 row_ror:4 row_mask:0xf bank_mask:0xf bound_ctrl:1
	s_nop 1
	v_add_f32_dpp v80, v80, v80 row_ror:2 row_mask:0xf bank_mask:0xf bound_ctrl:1
	s_nop 1
	v_add_f32_dpp v80, v80, v80 row_ror:1 row_mask:0xf bank_mask:0xf bound_ctrl:1
	s_nop 0
	v_readlane_b32 s19, v80, 0
	v_readlane_b32 s68, v80, 16
	v_readlane_b32 s66, v80, 32
	v_readlane_b32 s67, v80, 48
	s_and_saveexec_b64 s[64:65], s[0:1]
	s_cbranch_execz .LBB0_273
	s_lshl_b64 s[62:63], s[62:63], 2
	v_mov_b32_e32 v80, s68
	s_add_u32 s62, s16, s62
	v_add_f32_e32 v80, s19, v80
	s_addc_u32 s63, s17, s63
	v_add_f32_e32 v80, s66, v80
	v_add_f32_e32 v82, s67, v80
	v_mov_b64_e32 v[80:81], s[62:63]
	global_atomic_add_f32 v[80:81], v82, off
; DEVI float fsig(float x) { return __builtin_amdgcn_rcpf(1.f + __expf(-x)); }
; DEVI float bflo(unsigned u) { return __uint_as_float(u << 16); }
; DEVI float bfhi(unsigned u) { return __uint_as_float(u & 0xffff0000u); }
; template <int EPI, int TS, bool VT>
; DEVI void gemm_epilogue(const Params& p, char* smem, f32x4 (&acc)[2][2][4][2], int m0, int n0, float scale, const float* ssin,
;                         float* ssout, u16* xbout, int wid, int lane, int wr, int wc, int fr, int fq) {
;     ...
;         for (int u = 0; u < 8; ++u) {
;           const int i = i0 + u;
;           const int grow = g0 + i;
;           const float* Tr = T + (r0 + i) * TS;
;           const float rs = __int_as_float(__builtin_amdgcn_readlane(__float_as_int(rsv), i));
;           if constexpr (EPI == E_RESID || EPI == E_PLEGATE) {
;             const float4 a = *(const float4*)(Tr + 4 * lane);
;             const size_t ro = (size_t)grow * 1024 + n0 + 4 * lane;
;             float4 x4 = xo[u];
;             if constexpr (EPI == E_PLEGATE) {
;               x4.x += bflo(pv[u].x) * fsig(a.x * rs);
;               x4.y += bfhi(pv[u].x) * fsig(a.y * rs);
;               x4.z += bflo(pv[u].y) * fsig(a.z * rs);
;               x4.w += bfhi(pv[u].y) * fsig(a.w * rs);
;             } else {
;               const float sc = fabsf(scale);
;               x4.x += sc * a.x; x4.y += sc * a.y; x4.z += sc * a.z; x4.w += sc * a.w;
;             }
;             st_nt16(p.x + ro, x4);
;             if (xbout) {
;               uint2 o;
;               o.x = pack2(x4.x, x4.y);
;               o.y = pack2(x4.z, x4.w);
;               st_nt8(xbout + ro, o);
;             }
;             if (ssout) {
;               const float ssq = wsum(x4.x * x4.x + x4.y * x4.y + x4.z * x4.z + x4.w * x4.w, lane);
;               if (lane == 0) atomicAdd(ssout + grow, ssq);
;             }
.LBB0_273:
	s_or_b64 exec, exec, s[64:65]
	ds_read_b128 v[80:83], v130 offset:12480
	v_lshl_add_u64 v[84:85], v[110:111], 1, s[8:9]
	s_waitcnt lgkmcnt(0)
	v_pk_fma_f32 v[76:77], s[12:13], v[80:81], v[76:77]
	v_pk_fma_f32 v[78:79], s[12:13], v[82:83], v[78:79]
	global_store_dwordx4 v[108:109], v[76:79], off
	v_cvt_pk_bf16_f32 v80, v76, v77
	v_cvt_pk_bf16_f32 v81, v78, v79
	v_pk_mul_f32 v[76:77], v[76:77], v[76:77]
	v_pk_mul_f32 v[78:79], v[78:79], v[78:79]
	v_add_f32_e32 v76, v76, v77
	v_add_f32_e32 v76, v76, v78
	v_add_f32_e32 v76, v76, v79
	global_store_dwordx2 v[84:85], v[80:81], off
	s_nop 0
	v_add_f32_dpp v76, v76, v76 row_ror:8 row_mask:0xf bank_mask:0xf bound_ctrl:1
	s_nop 1
	v_add_f32_dpp v76, v76, v76 row_ror:4 row_mask:0xf bank_mask:0xf bound_ctrl:1
	s_nop 1
	v_add_f32_dpp v76, v76, v76 row_ror:2 row_mask:0xf bank_mask:0xf bound_ctrl:1
	s_nop 1
	v_add_f32_dpp v76, v76, v76 row_ror:1 row_mask:0xf bank_mask:0xf bound_ctrl:1
	s_nop 0
	v_readlane_b32 s19, v76, 0
	v_readlane_b32 s66, v76, 16
	v_readlane_b32 s64, v76, 32
	v_readlane_b32 s65, v76, 48
	s_and_saveexec_b64 s[62:63], s[0:1]
	s_cbranch_execz .LBB0_275
	s_lshl_b64 s[34:35], s[34:35], 2
	v_mov_b32_e32 v76, s66
	s_add_u32 s34, s16, s34
	v_add_f32_e32 v76, s19, v76
	s_addc_u32 s35, s17, s35
	v_add_f32_e32 v76, s64, v76
	v_add_f32_e32 v78, s65, v76
	v_mov_b64_e32 v[76:77], s[34:35]
	global_atomic_add_f32 v[76:77], v78, off
.LBB0_275:
	s_or_b64 exec, exec, s[62:63]
	ds_read_b128 v[76:79], v130 offset:13520
	v_lshl_add_u64 v[80:81], v[106:107], 1, s[8:9]
	s_waitcnt lgkmcnt(0)
	v_pk_fma_f32 v[72:73], s[12:13], v[76:77], v[72:73]
	v_pk_fma_f32 v[74:75], s[12:13], v[78:79], v[74:75]
	global_store_dwordx4 v[104:105], v[72:75], off
	v_cvt_pk_bf16_f32 v76, v72, v73
	v_cvt_pk_bf16_f32 v77, v74, v75
	v_pk_mul_f32 v[72:73], v[72:73], v[72:73]
	v_pk_mul_f32 v[74:75], v[74:75], v[74:75]
	v_add_f32_e32 v72, v72, v73
	v_add_f32_e32 v72, v72, v74
	v_add_f32_e32 v72, v72, v75
	global_store_dwordx2 v[80:81], v[76:77], off
	s_nop 0
	v_add_f32_dpp v72, v72, v72 row_ror:8 row_mask:0xf bank_mask:0xf bound_ctrl:1
	s_nop 1
	v_add_f32_dpp v72, v72, v72 row_ror:4 row_mask:0xf bank_mask:0xf bound_ctrl:1
	s_nop 1
	v_add_f32_dpp v72, v72, v72 row_ror:2 row_mask:0xf bank_mask:0xf bound_ctrl:1
	s_nop 1
	v_add_f32_dpp v72, v72, v72 row_ror:1 row_mask:0xf bank_mask:0xf bound_ctrl:1
	s_nop 0
	v_readlane_b32 s19, v72, 0
	v_readlane_b32 s64, v72, 16
	v_readlane_b32 s62, v72, 32
	v_readlane_b32 s63, v72, 48
	s_and_saveexec_b64 s[34:35], s[0:1]
	s_cbranch_execz .LBB0_277
	s_lshl_b64 s[30:31], s[30:31], 2
	v_mov_b32_e32 v72, s64
	s_add_u32 s30, s16, s30
	v_add_f32_e32 v72, s19, v72
	s_addc_u32 s31, s17, s31
	v_add_f32_e32 v72, s62, v72
	v_add_f32_e32 v74, s63, v72
	v_mov_b64_e32 v[72:73], s[30:31]
	global_atomic_add_f32 v[72:73], v74, off
.LBB0_277:
	s_or_b64 exec, exec, s[34:35]
	ds_read_b128 v[72:75], v130 offset:14560
	v_lshl_add_u64 v[76:77], v[102:103], 1, s[8:9]
	s_waitcnt lgkmcnt(0)
	v_pk_fma_f32 v[68:69], s[12:13], v[72:73], v[68:69]
	v_pk_fma_f32 v[70:71], s[12:13], v[74:75], v[70:71]
	global_store_dwordx4 v[100:101], v[68:71], off
	v_cvt_pk_bf16_f32 v72, v68, v69
	v_cvt_pk_bf16_f32 v73, v70, v71
	v_pk_mul_f32 v[68:69], v[68:69], v[68:69]
	v_pk_mul_f32 v[70:71], v[70:71], v[70:71]
	v_add_f32_e32 v68, v68, v69
	v_add_f32_e32 v68, v68, v70
	v_add_f32_e32 v68, v68, v71
	global_store_dwordx2 v[76:77], v[72:73], off
	s_nop 0
	v_add_f32_dpp v68, v68, v68 row_ror:8 row_mask:0xf bank_mask:0xf bound_ctrl:1
	s_nop 1
	v_add_f32_dpp v68, v68, v68 row_ror:4 row_mask:0xf bank_mask:0xf bound_ctrl:1
	s_nop 1
	v_add_f32_dpp v68, v68, v68 row_ror:2 row_mask:0xf bank_mask:0xf bound_ctrl:1
	s_nop 1
	v_add_f32_dpp v68, v68, v68 row_ror:1 row_mask:0xf bank_mask:0xf bound_ctrl:1
	s_nop 0
	v_readlane_b32 s19, v68, 0
	v_readlane_b32 s62, v68, 16
	v_readlane_b32 s34, v68, 32
	v_readlane_b32 s35, v68, 48
	s_and_saveexec_b64 s[30:31], s[0:1]
	s_cbranch_execz .LBB0_279
	s_lshl_b64 s[22:23], s[22:23], 2
	v_mov_b32_e32 v68, s62
	s_add_u32 s22, s16, s22
	v_add_f32_e32 v68, s19, v68
	s_addc_u32 s23, s17, s23
	v_add_f32_e32 v68, s34, v68
	v_add_f32_e32 v70, s35, v68
	v_mov_b64_e32 v[68:69], s[22:23]
	global_atomic_add_f32 v[68:69], v70, off
.LBB0_279:
	s_or_b64 exec, exec, s[30:31]
	ds_read_b128 v[68:71], v130 offset:15600
	v_lshl_add_u64 v[72:73], v[98:99], 1, s[8:9]
	s_waitcnt lgkmcnt(0)
	v_pk_fma_f32 v[64:65], s[12:13], v[68:69], v[64:65]
	v_pk_fma_f32 v[66:67], s[12:13], v[70:71], v[66:67]
	global_store_dwordx4 v[96:97], v[64:67], off
	v_cvt_pk_bf16_f32 v68, v64, v65
	v_cvt_pk_bf16_f32 v69, v66, v67
	v_pk_mul_f32 v[64:65], v[64:65], v[64:65]
	v_pk_mul_f32 v[66:67], v[66:67], v[66:67]
	v_add_f32_e32 v64, v64, v65
	v_add_f32_e32 v64, v64, v66
	v_add_f32_e32 v64, v64, v67
	global_store_dwordx2 v[72:73], v[68:69], off
	s_nop 0
	v_add_f32_dpp v64, v64, v64 row_ror:8 row_mask:0xf bank_mask:0xf bound_ctrl:1
	s_nop 1
	v_add_f32_dpp v64, v64, v64 row_ror:4 row_mask:0xf bank_mask:0xf bound_ctrl:1
	s_nop 1
	v_add_f32_dpp v64, v64, v64 row_ror:2 row_mask:0xf bank_mask:0xf bound_ctrl:1
	s_nop 1
	v_add_f32_dpp v64, v64, v64 row_ror:1 row_mask:0xf bank_mask:0xf bound_ctrl:1
	s_nop 0
	v_readlane_b32 s19, v64, 0
	v_readlane_b32 s34, v64, 16
	v_readlane_b32 s30, v64, 32
	v_readlane_b32 s31, v64, 48
	s_and_saveexec_b64 s[22:23], s[0:1]
	s_cbranch_execz .LBB0_281
	s_lshl_b64 s[20:21], s[20:21], 2
	v_mov_b32_e32 v64, s34
	s_add_u32 s20, s16, s20
	v_add_f32_e32 v64, s19, v64
	s_addc_u32 s21, s17, s21
	v_add_f32_e32 v64, s30, v64
	v_add_f32_e32 v66, s31, v64
	v_mov_b64_e32 v[64:65], s[20:21]
	global_atomic_add_f32 v[64:65], v66, off

; DEVI float fsig(float x) { return __builtin_amdgcn_rcpf(1.f + __expf(-x)); }
; DEVI float bflo(unsigned u) { return __uint_as_float(u << 16); }
; DEVI float bfhi(unsigned u) { return __uint_as_float(u & 0xffff0000u); }
; template <int EPI, int TS, bool VT>
; DEVI void gemm_epilogue(const Params& p, char* smem, f32x4 (&acc)[2][2][4][2], int m0, int n0, float scale, const float* ssin,
;                         float* ssout, u16* xbout, int wid, int lane, int wr, int wc, int fr, int fq) {
;     ...
;         for (int u = 0; u < 8; ++u) {
;           const int i = i0 + u;
;           const int grow = g0 + i;
;           const float* Tr = T + (r0 + i) * TS;
;           const float rs = __int_as_float(__builtin_amdgcn_readlane(__float_as_int(rsv), i));
;           if constexpr (EPI == E_RESID || EPI == E_PLEGATE) {
;             const float4 a = *(const float4*)(Tr + 4 * lane);
;             const size_t ro = (size_t)grow * 1024 + n0 + 4 * lane;
;             float4 x4 = xo[u];
;             if constexpr (EPI == E_PLEGATE) {
;               x4.x += bflo(pv[u].x) * fsig(a.x * rs);
;               x4.y += bfhi(pv[u].x) * fsig(a.y * rs);
;               x4.z += bflo(pv[u].y) * fsig(a.z * rs);
;               x4.w += bfhi(pv[u].y) * fsig(a.w * rs);
;             } else {
;               const float sc = fabsf(scale);
;               x4.x += sc * a.x; x4.y += sc * a.y; x4.z += sc * a.z; x4.w += sc * a.w;
;             }
;             st_nt16(p.x + ro, x4);
;             if (xbout) {
;               uint2 o;
;               o.x = pack2(x4.x, x4.y);
;               o.y = pack2(x4.z, x4.w);
;               st_nt8(xbout + ro, o);
;             }
;             if (ssout) {
;               const float ssq = wsum(x4.x * x4.x + x4.y * x4.y + x4.z * x4.z + x4.w * x4.w, lane);
;               if (lane == 0) atomicAdd(ssout + grow, ssq);
;             }
.LBB0_321:
	global_load_dwordx4 v[0:3], v[0:1], off
	ds_read_b128 v[64:67], v130
	v_lshl_add_u64 v[56:57], v[56:57], 1, s[8:9]
	s_waitcnt vmcnt(0) lgkmcnt(0)
	v_pk_fma_f32 v[28:29], s[12:13], v[64:65], v[28:29]
	v_pk_fma_f32 v[30:31], s[12:13], v[66:67], v[30:31]
	global_store_dwordx4 v[62:63], v[28:31], off
	v_cvt_pk_bf16_f32 v62, v28, v29
	v_cvt_pk_bf16_f32 v63, v30, v31
	v_pk_mul_f32 v[28:29], v[28:29], v[28:29]
	v_pk_mul_f32 v[30:31], v[30:31], v[30:31]
	v_add_f32_e32 v28, v28, v29
	v_add_f32_e32 v28, v28, v30
	v_add_f32_e32 v28, v28, v31
	global_store_dwordx2 v[56:57], v[62:63], off
	s_nop 0
	v_add_f32_dpp v28, v28, v28 row_ror:8 row_mask:0xf bank_mask:0xf bound_ctrl:1
	s_nop 1
	v_add_f32_dpp v28, v28, v28 row_ror:4 row_mask:0xf bank_mask:0xf bound_ctrl:1
	s_nop 1
	v_add_f32_dpp v28, v28, v28 row_ror:2 row_mask:0xf bank_mask:0xf bound_ctrl:1
	s_nop 1
	v_add_f32_dpp v28, v28, v28 row_ror:1 row_mask:0xf bank_mask:0xf bound_ctrl:1
	s_nop 0
	v_readlane_b32 s19, v28, 0
	v_readlane_b32 s77, v28, 16
	v_readlane_b32 s75, v28, 32
	v_readlane_b32 s76, v28, 48
	s_and_saveexec_b64 s[70:71], s[0:1]
	s_cbranch_execz .LBB0_323
	s_lshl_b64 s[68:69], s[68:69], 2
	v_mov_b32_e32 v28, s77
	s_add_u32 s68, s16, s68
	v_add_f32_e32 v28, s19, v28
	s_addc_u32 s69, s17, s69
	v_add_f32_e32 v28, s75, v28
	v_add_f32_e32 v30, s76, v28
	v_mov_b64_e32 v[28:29], s[68:69]
	global_atomic_add_f32 v[28:29], v30, off
.LBB0_323:
	s_or_b64 exec, exec, s[70:71]
	ds_read_b128 v[28:31], v130 offset:1040
	v_lshl_add_u64 v[56:57], v[60:61], 1, s[8:9]
	s_waitcnt lgkmcnt(0)
	v_pk_fma_f32 v[24:25], s[12:13], v[28:29], v[24:25]
	v_pk_fma_f32 v[26:27], s[12:13], v[30:31], v[26:27]
	global_store_dwordx4 v[58:59], v[24:27], off
	v_cvt_pk_bf16_f32 v28, v24, v25
	v_cvt_pk_bf16_f32 v29, v26, v27
	v_pk_mul_f32 v[24:25], v[24:25], v[24:25]
	v_pk_mul_f32 v[26:27], v[26:27], v[26:27]
	v_add_f32_e32 v24, v24, v25
	v_add_f32_e32 v24, v24, v26
	v_add_f32_e32 v24, v24, v27
	global_store_dwordx2 v[56:57], v[28:29], off
	s_nop 0
	v_add_f32_dpp v24, v24, v24 row_ror:8 row_mask:0xf bank_mask:0xf bound_ctrl:1
	s_nop 1
	v_add_f32_dpp v24, v24, v24 row_ror:4 row_mask:0xf bank_mask:0xf bound_ctrl:1
	s_nop 1
	v_add_f32_dpp v24, v24, v24 row_ror:2 row_mask:0xf bank_mask:0xf bound_ctrl:1
	s_nop 1
	v_add_f32_dpp v24, v24, v24 row_ror:1 row_mask:0xf bank_mask:0xf bound_ctrl:1
	s_nop 0
	v_readlane_b32 s19, v24, 0
	v_readlane_b32 s75, v24, 16
	v_readlane_b32 s70, v24, 32
	v_readlane_b32 s71, v24, 48
	s_and_saveexec_b64 s[68:69], s[0:1]
	s_cbranch_execz .LBB0_325
	s_lshl_b64 s[66:67], s[66:67], 2
	v_mov_b32_e32 v24, s75
	s_add_u32 s66, s16, s66
	v_add_f32_e32 v24, s19, v24
	s_addc_u32 s67, s17, s67
	v_add_f32_e32 v24, s70, v24
	v_add_f32_e32 v26, s71, v24
	v_mov_b64_e32 v[24:25], s[66:67]
	global_atomic_add_f32 v[24:25], v26, off
.LBB0_325:
	s_or_b64 exec, exec, s[68:69]
	ds_read_b128 v[24:27], v130 offset:2080
	v_lshl_add_u64 v[28:29], v[54:55], 1, s[8:9]
	s_waitcnt lgkmcnt(0)
	v_pk_fma_f32 v[20:21], s[12:13], v[24:25], v[20:21]
	v_pk_fma_f32 v[22:23], s[12:13], v[26:27], v[22:23]
	global_store_dwordx4 v[52:53], v[20:23], off
	v_cvt_pk_bf16_f32 v24, v20, v21
	v_cvt_pk_bf16_f32 v25, v22, v23
	v_pk_mul_f32 v[20:21], v[20:21], v[20:21]
	v_pk_mul_f32 v[22:23], v[22:23], v[22:23]
	v_add_f32_e32 v20, v20, v21
	v_add_f32_e32 v20, v20, v22
	v_add_f32_e32 v20, v20, v23
	global_store_dwordx2 v[28:29], v[24:25], off
	s_nop 0
	v_add_f32_dpp v20, v20, v20 row_ror:8 row_mask:0xf bank_mask:0xf bound_ctrl:1
	s_nop 1
	v_add_f32_dpp v20, v20, v20 row_ror:4 row_mask:0xf bank_mask:0xf bound_ctrl:1
	s_nop 1
	v_add_f32_dpp v20, v20, v20 row_ror:2 row_mask:0xf bank_mask:0xf bound_ctrl:1
	s_nop 1
	v_add_f32_dpp v20, v20, v20 row_ror:1 row_mask:0xf bank_mask:0xf bound_ctrl:1
	s_nop 0
	v_readlane_b32 s19, v20, 0
	v_readlane_b32 s70, v20, 16
	v_readlane_b32 s68, v20, 32
	v_readlane_b32 s69, v20, 48
	s_and_saveexec_b64 s[66:67], s[0:1]
	s_cbranch_execz .LBB0_327
	s_lshl_b64 s[64:65], s[64:65], 2
	v_mov_b32_e32 v20, s70
	s_add_u32 s64, s16, s64
	v_add_f32_e32 v20, s19, v20
	s_addc_u32 s65, s17, s65
	v_add_f32_e32 v20, s68, v20
	v_add_f32_e32 v22, s69, v20
	v_mov_b64_e32 v[20:21], s[64:65]
	global_atomic_add_f32 v[20:21], v22, off
.LBB0_327:
	s_or_b64 exec, exec, s[66:67]
	ds_read_b128 v[20:23], v130 offset:3120
	v_lshl_add_u64 v[24:25], v[50:51], 1, s[8:9]
	s_waitcnt lgkmcnt(0)
	v_pk_fma_f32 v[16:17], s[12:13], v[20:21], v[16:17]
	v_pk_fma_f32 v[18:19], s[12:13], v[22:23], v[18:19]
	global_store_dwordx4 v[48:49], v[16:19], off
	v_cvt_pk_bf16_f32 v20, v16, v17
	v_cvt_pk_bf16_f32 v21, v18, v19
	v_pk_mul_f32 v[16:17], v[16:17], v[16:17]
	v_pk_mul_f32 v[18:19], v[18:19], v[18:19]
	v_add_f32_e32 v16, v16, v17
	v_add_f32_e32 v16, v16, v18
	v_add_f32_e32 v16, v16, v19
	global_store_dwordx2 v[24:25], v[20:21], off
	s_nop 0
	v_add_f32_dpp v16, v16, v16 row_ror:8 row_mask:0xf bank_mask:0xf bound_ctrl:1
	s_nop 1
	v_add_f32_dpp v16, v16, v16 row_ror:4 row_mask:0xf bank_mask:0xf bound_ctrl:1
	s_nop 1
	v_add_f32_dpp v16, v16, v16 row_ror:2 row_mask:0xf bank_mask:0xf bound_ctrl:1
	s_nop 1
	v_add_f32_dpp v16, v16, v16 row_ror:1 row_mask:0xf bank_mask:0xf bound_ctrl:1
	s_nop 0
	v_readlane_b32 s19, v16, 0
	v_readlane_b32 s68, v16, 16
	v_readlane_b32 s66, v16, 32
	v_readlane_b32 s67, v16, 48
	s_and_saveexec_b64 s[64:65], s[0:1]
	s_cbranch_execz .LBB0_329
	s_lshl_b64 s[62:63], s[62:63], 2
	v_mov_b32_e32 v16, s68
	s_add_u32 s62, s16, s62
	v_add_f32_e32 v16, s19, v16
	s_addc_u32 s63, s17, s63
	v_add_f32_e32 v16, s66, v16
	v_add_f32_e32 v18, s67, v16
	v_mov_b64_e32 v[16:17], s[62:63]
	global_atomic_add_f32 v[16:17], v18, off
; DEVI float fsig(float x) { return __builtin_amdgcn_rcpf(1.f + __expf(-x)); }
; DEVI float bflo(unsigned u) { return __uint_as_float(u << 16); }
; DEVI float bfhi(unsigned u) { return __uint_as_float(u & 0xffff0000u); }
; template <int EPI, int TS, bool VT>
; DEVI void gemm_epilogue(const Params& p, char* smem, f32x4 (&acc)[2][2][4][2], int m0, int n0, float scale, const float* ssin,
;                         float* ssout, u16* xbout, int wid, int lane, int wr, int wc, int fr, int fq) {
;     ...
;         for (int u = 0; u < 8; ++u) {
;           const int i = i0 + u;
;           const int grow = g0 + i;
;           const float* Tr = T + (r0 + i) * TS;
;           const float rs = __int_as_float(__builtin_amdgcn_readlane(__float_as_int(rsv), i));
;           if constexpr (EPI == E_RESID || EPI == E_PLEGATE) {
;             const float4 a = *(const float4*)(Tr + 4 * lane);
;             const size_t ro = (size_t)grow * 1024 + n0 + 4 * lane;
;             float4 x4 = xo[u];
;             if constexpr (EPI == E_PLEGATE) {
;               x4.x += bflo(pv[u].x) * fsig(a.x * rs);
;               x4.y += bfhi(pv[u].x) * fsig(a.y * rs);
;               x4.z += bflo(pv[u].y) * fsig(a.z * rs);
;               x4.w += bfhi(pv[u].y) * fsig(a.w * rs);
;             } else {
;               const float sc = fabsf(scale);
;               x4.x += sc * a.x; x4.y += sc * a.y; x4.z += sc * a.z; x4.w += sc * a.w;
;             }
;             st_nt16(p.x + ro, x4);
;             if (xbout) {
;               uint2 o;
;               o.x = pack2(x4.x, x4.y);
;               o.y = pack2(x4.z, x4.w);
;               st_nt8(xbout + ro, o);
;             }
;             if (ssout) {
;               const float ssq = wsum(x4.x * x4.x + x4.y * x4.y + x4.z * x4.z + x4.w * x4.w, lane);
;               if (lane == 0) atomicAdd(ssout + grow, ssq);
;             }
.LBB0_329:
	s_or_b64 exec, exec, s[64:65]
	ds_read_b128 v[16:19], v130 offset:4160
	v_lshl_add_u64 v[20:21], v[46:47], 1, s[8:9]
	s_waitcnt lgkmcnt(0)
	v_pk_fma_f32 v[12:13], s[12:13], v[16:17], v[12:13]
	v_pk_fma_f32 v[14:15], s[12:13], v[18:19], v[14:15]
	global_store_dwordx4 v[44:45], v[12:15], off
	v_cvt_pk_bf16_f32 v16, v12, v13
	v_cvt_pk_bf16_f32 v17, v14, v15
	v_pk_mul_f32 v[12:13], v[12:13], v[12:13]
	v_pk_mul_f32 v[14:15], v[14:15], v[14:15]
	v_add_f32_e32 v12, v12, v13
	v_add_f32_e32 v12, v12, v14
	v_add_f32_e32 v12, v12, v15
	global_store_dwordx2 v[20:21], v[16:17], off
	s_nop 0
	v_add_f32_dpp v12, v12, v12 row_ror:8 row_mask:0xf bank_mask:0xf bound_ctrl:1
	s_nop 1
	v_add_f32_dpp v12, v12, v12 row_ror:4 row_mask:0xf bank_mask:0xf bound_ctrl:1
	s_nop 1
	v_add_f32_dpp v12, v12, v12 row_ror:2 row_mask:0xf bank_mask:0xf bound_ctrl:1
	s_nop 1
	v_add_f32_dpp v12, v12, v12 row_ror:1 row_mask:0xf bank_mask:0xf bound_ctrl:1
	s_nop 0
	v_readlane_b32 s19, v12, 0
	v_readlane_b32 s66, v12, 16
	v_readlane_b32 s64, v12, 32
	v_readlane_b32 s65, v12, 48
	s_and_saveexec_b64 s[62:63], s[0:1]
	s_cbranch_execz .LBB0_331
	s_lshl_b64 s[34:35], s[34:35], 2
	v_mov_b32_e32 v12, s66
	s_add_u32 s34, s16, s34
	v_add_f32_e32 v12, s19, v12
	s_addc_u32 s35, s17, s35
	v_add_f32_e32 v12, s64, v12
	v_add_f32_e32 v14, s65, v12
	v_mov_b64_e32 v[12:13], s[34:35]
	global_atomic_add_f32 v[12:13], v14, off
.LBB0_331:
	s_or_b64 exec, exec, s[62:63]
	ds_read_b128 v[12:15], v130 offset:5200
	v_lshl_add_u64 v[16:17], v[42:43], 1, s[8:9]
	s_waitcnt lgkmcnt(0)
	v_pk_fma_f32 v[8:9], s[12:13], v[12:13], v[8:9]
	v_pk_fma_f32 v[10:11], s[12:13], v[14:15], v[10:11]
	global_store_dwordx4 v[40:41], v[8:11], off
	v_cvt_pk_bf16_f32 v12, v8, v9
	v_cvt_pk_bf16_f32 v13, v10, v11
	v_pk_mul_f32 v[8:9], v[8:9], v[8:9]
	v_pk_mul_f32 v[10:11], v[10:11], v[10:11]
	v_add_f32_e32 v8, v8, v9
	v_add_f32_e32 v8, v8, v10
	v_add_f32_e32 v8, v8, v11
	global_store_dwordx2 v[16:17], v[12:13], off
	s_nop 0
	v_add_f32_dpp v8, v8, v8 row_ror:8 row_mask:0xf bank_mask:0xf bound_ctrl:1
	s_nop 1
	v_add_f32_dpp v8, v8, v8 row_ror:4 row_mask:0xf bank_mask:0xf bound_ctrl:1
	s_nop 1
	v_add_f32_dpp v8, v8, v8 row_ror:2 row_mask:0xf bank_mask:0xf bound_ctrl:1
	s_nop 1
	v_add_f32_dpp v8, v8, v8 row_ror:1 row_mask:0xf bank_mask:0xf bound_ctrl:1
	s_nop 0
	v_readlane_b32 s19, v8, 0
	v_readlane_b32 s64, v8, 16
	v_readlane_b32 s62, v8, 32
	v_readlane_b32 s63, v8, 48
	s_and_saveexec_b64 s[34:35], s[0:1]
	s_cbranch_execz .LBB0_333
	s_lshl_b64 s[30:31], s[30:31], 2
	v_mov_b32_e32 v8, s64
	s_add_u32 s30, s16, s30
	v_add_f32_e32 v8, s19, v8
	s_addc_u32 s31, s17, s31
	v_add_f32_e32 v8, s62, v8
	v_add_f32_e32 v10, s63, v8
	v_mov_b64_e32 v[8:9], s[30:31]
	global_atomic_add_f32 v[8:9], v10, off
.LBB0_333:
	s_or_b64 exec, exec, s[34:35]
	ds_read_b128 v[8:11], v130 offset:6240
	v_lshl_add_u64 v[12:13], v[38:39], 1, s[8:9]
	s_waitcnt lgkmcnt(0)
	v_pk_fma_f32 v[4:5], s[12:13], v[8:9], v[4:5]
	v_pk_fma_f32 v[6:7], s[12:13], v[10:11], v[6:7]
	global_store_dwordx4 v[36:37], v[4:7], off
	v_cvt_pk_bf16_f32 v8, v4, v5
	v_cvt_pk_bf16_f32 v9, v6, v7
	v_pk_mul_f32 v[4:5], v[4:5], v[4:5]
	v_pk_mul_f32 v[6:7], v[6:7], v[6:7]
	v_add_f32_e32 v4, v4, v5
	v_add_f32_e32 v4, v4, v6
	v_add_f32_e32 v4, v4, v7
	global_store_dwordx2 v[12:13], v[8:9], off
	s_nop 0
	v_add_f32_dpp v4, v4, v4 row_ror:8 row_mask:0xf bank_mask:0xf bound_ctrl:1
	s_nop 1
	v_add_f32_dpp v4, v4, v4 row_ror:4 row_mask:0xf bank_mask:0xf bound_ctrl:1
	s_nop 1
	v_add_f32_dpp v4, v4, v4 row_ror:2 row_mask:0xf bank_mask:0xf bound_ctrl:1
	s_nop 1
	v_add_f32_dpp v4, v4, v4 row_ror:1 row_mask:0xf bank_mask:0xf bound_ctrl:1
	s_nop 0
	v_readlane_b32 s19, v4, 0
	v_readlane_b32 s62, v4, 16
	v_readlane_b32 s34, v4, 32
	v_readlane_b32 s35, v4, 48
	s_and_saveexec_b64 s[30:31], s[0:1]
	s_cbranch_execz .LBB0_335
	s_lshl_b64 s[22:23], s[22:23], 2
	v_mov_b32_e32 v4, s62
	s_add_u32 s22, s16, s22
	v_add_f32_e32 v4, s19, v4
	s_addc_u32 s23, s17, s23
	v_add_f32_e32 v4, s34, v4
	v_add_f32_e32 v6, s35, v4
	v_mov_b64_e32 v[4:5], s[22:23]
	global_atomic_add_f32 v[4:5], v6, off
.LBB0_335:
	s_or_b64 exec, exec, s[30:31]
	ds_read_b128 v[4:7], v130 offset:7280
	v_lshl_add_u64 v[8:9], v[34:35], 1, s[8:9]
	s_waitcnt lgkmcnt(0)
	v_pk_fma_f32 v[0:1], s[12:13], v[4:5], v[0:1]
	v_pk_fma_f32 v[2:3], s[12:13], v[6:7], v[2:3]
	global_store_dwordx4 v[32:33], v[0:3], off
	v_cvt_pk_bf16_f32 v4, v0, v1
	v_cvt_pk_bf16_f32 v5, v2, v3
	v_pk_mul_f32 v[0:1], v[0:1], v[0:1]
	v_pk_mul_f32 v[2:3], v[2:3], v[2:3]
	v_add_f32_e32 v0, v0, v1
	v_add_f32_e32 v0, v0, v2
	v_add_f32_e32 v0, v0, v3
	global_store_dwordx2 v[8:9], v[4:5], off
	s_nop 0
	v_add_f32_dpp v0, v0, v0 row_ror:8 row_mask:0xf bank_mask:0xf bound_ctrl:1
	s_nop 1
	v_add_f32_dpp v0, v0, v0 row_ror:4 row_mask:0xf bank_mask:0xf bound_ctrl:1
	s_nop 1
	v_add_f32_dpp v0, v0, v0 row_ror:2 row_mask:0xf bank_mask:0xf bound_ctrl:1
	s_nop 1
	v_add_f32_dpp v0, v0, v0 row_ror:1 row_mask:0xf bank_mask:0xf bound_ctrl:1
	s_nop 0
	v_readlane_b32 s19, v0, 0
	v_readlane_b32 s34, v0, 16
	v_readlane_b32 s30, v0, 32
	v_readlane_b32 s31, v0, 48
	s_and_saveexec_b64 s[22:23], s[0:1]
	s_cbranch_execz .LBB0_337
	s_lshl_b64 s[20:21], s[20:21], 2
	v_mov_b32_e32 v0, s34
	s_add_u32 s20, s16, s20
	v_add_f32_e32 v0, s19, v0
	s_addc_u32 s21, s17, s21
	v_add_f32_e32 v0, s30, v0
	v_add_f32_e32 v2, s31, v0
	v_mov_b64_e32 v[0:1], s[20:21]
	global_atomic_add_f32 v[0:1], v2, off

; DEVI float fsig(float x) { return __builtin_amdgcn_rcpf(1.f + __expf(-x)); }
; DEVI float bflo(unsigned u) { return __uint_as_float(u << 16); }
; DEVI float bfhi(unsigned u) { return __uint_as_float(u & 0xffff0000u); }
; template <int EPI, int TS, bool VT>
; DEVI void gemm_epilogue(const Params& p, char* smem, f32x4 (&acc)[2][2][4][2], int m0, int n0, float scale, const float* ssin,
;                         float* ssout, u16* xbout, int wid, int lane, int wr, int wc, int fr, int fq) {
;     ...
;         for (int u = 0; u < 8; ++u) {
;           const int i = i0 + u;
;           const int grow = g0 + i;
;           const float* Tr = T + (r0 + i) * TS;
;           const float rs = __int_as_float(__builtin_amdgcn_readlane(__float_as_int(rsv), i));
;           if constexpr (EPI == E_RESID || EPI == E_PLEGATE) {
;             const float4 a = *(const float4*)(Tr + 4 * lane);
;             const size_t ro = (size_t)grow * 1024 + n0 + 4 * lane;
;             float4 x4 = xo[u];
;             if constexpr (EPI == E_PLEGATE) {
;               x4.x += bflo(pv[u].x) * fsig(a.x * rs);
;               x4.y += bfhi(pv[u].x) * fsig(a.y * rs);
;               x4.z += bflo(pv[u].y) * fsig(a.z * rs);
;               x4.w += bfhi(pv[u].y) * fsig(a.w * rs);
;             } else {
;               const float sc = fabsf(scale);
;               x4.x += sc * a.x; x4.y += sc * a.y; x4.z += sc * a.z; x4.w += sc * a.w;
;             }
;             st_nt16(p.x + ro, x4);
;             if (xbout) {
;               uint2 o;
;               o.x = pack2(x4.x, x4.y);
;               o.y = pack2(x4.z, x4.w);
;               st_nt8(xbout + ro, o);
;             }
;             if (ssout) {
;               const float ssq = wsum(x4.x * x4.x + x4.y * x4.y + x4.z * x4.z + x4.w * x4.w, lane);
;               if (lane == 0) atomicAdd(ssout + grow, ssq);
;             }
.LBB0_377:
	global_load_dwordx4 v[0:3], v[0:1], off
	ds_read_b128 v[64:67], v130 offset:8320
	v_lshl_add_u64 v[56:57], v[56:57], 1, s[8:9]
	s_waitcnt vmcnt(0) lgkmcnt(0)
	v_pk_fma_f32 v[28:29], s[12:13], v[64:65], v[28:29]
	v_pk_fma_f32 v[30:31], s[12:13], v[66:67], v[30:31]
	global_store_dwordx4 v[62:63], v[28:31], off
	v_cvt_pk_bf16_f32 v62, v28, v29
	v_cvt_pk_bf16_f32 v63, v30, v31
	v_pk_mul_f32 v[28:29], v[28:29], v[28:29]
	v_pk_mul_f32 v[30:31], v[30:31], v[30:31]
	v_add_f32_e32 v28, v28, v29
	v_add_f32_e32 v28, v28, v30
	v_add_f32_e32 v28, v28, v31
	global_store_dwordx2 v[56:57], v[62:63], off
	s_nop 0
	v_add_f32_dpp v28, v28, v28 row_ror:8 row_mask:0xf bank_mask:0xf bound_ctrl:1
	s_nop 1
	v_add_f32_dpp v28, v28, v28 row_ror:4 row_mask:0xf bank_mask:0xf bound_ctrl:1
	s_nop 1
	v_add_f32_dpp v28, v28, v28 row_ror:2 row_mask:0xf bank_mask:0xf bound_ctrl:1
	s_nop 1
	v_add_f32_dpp v28, v28, v28 row_ror:1 row_mask:0xf bank_mask:0xf bound_ctrl:1
	s_nop 0
	v_readlane_b32 s68, v28, 0
	v_readlane_b32 s71, v28, 16
	v_readlane_b32 s69, v28, 32
	v_readlane_b32 s70, v28, 48
	s_and_saveexec_b64 s[4:5], s[0:1]
	s_cbranch_execz .LBB0_379
	s_lshl_b64 s[66:67], s[66:67], 2
	v_mov_b32_e32 v28, s71
	s_add_u32 s66, s16, s66
	v_add_f32_e32 v28, s68, v28
	s_addc_u32 s67, s17, s67
	v_add_f32_e32 v28, s69, v28
	v_add_f32_e32 v30, s70, v28
	v_mov_b64_e32 v[28:29], s[66:67]
	global_atomic_add_f32 v[28:29], v30, off
.LBB0_379:
	s_or_b64 exec, exec, s[4:5]
	ds_read_b128 v[28:31], v130 offset:9360
	v_lshl_add_u64 v[56:57], v[60:61], 1, s[8:9]
	s_waitcnt lgkmcnt(0)
	v_pk_fma_f32 v[24:25], s[12:13], v[28:29], v[24:25]
	v_pk_fma_f32 v[26:27], s[12:13], v[30:31], v[26:27]
	global_store_dwordx4 v[58:59], v[24:27], off
	v_cvt_pk_bf16_f32 v28, v24, v25
	v_cvt_pk_bf16_f32 v29, v26, v27
	v_pk_mul_f32 v[24:25], v[24:25], v[24:25]
	v_pk_mul_f32 v[26:27], v[26:27], v[26:27]
	v_add_f32_e32 v24, v24, v25
	v_add_f32_e32 v24, v24, v26
	v_add_f32_e32 v24, v24, v27
	global_store_dwordx2 v[56:57], v[28:29], off
	s_nop 0
	v_add_f32_dpp v24, v24, v24 row_ror:8 row_mask:0xf bank_mask:0xf bound_ctrl:1
	s_nop 1
	v_add_f32_dpp v24, v24, v24 row_ror:4 row_mask:0xf bank_mask:0xf bound_ctrl:1
	s_nop 1
	v_add_f32_dpp v24, v24, v24 row_ror:2 row_mask:0xf bank_mask:0xf bound_ctrl:1
	s_nop 1
	v_add_f32_dpp v24, v24, v24 row_ror:1 row_mask:0xf bank_mask:0xf bound_ctrl:1
	s_nop 0
	v_readlane_b32 s66, v24, 0
	v_readlane_b32 s69, v24, 16
	v_readlane_b32 s67, v24, 32
	v_readlane_b32 s68, v24, 48
	s_and_saveexec_b64 s[4:5], s[0:1]
	s_cbranch_execz .LBB0_381
	s_lshl_b64 s[64:65], s[64:65], 2
	v_mov_b32_e32 v24, s69
	s_add_u32 s64, s16, s64
	v_add_f32_e32 v24, s66, v24
	s_addc_u32 s65, s17, s65
	v_add_f32_e32 v24, s67, v24
	v_add_f32_e32 v26, s68, v24
	v_mov_b64_e32 v[24:25], s[64:65]
	global_atomic_add_f32 v[24:25], v26, off
.LBB0_381:
	s_or_b64 exec, exec, s[4:5]
	ds_read_b128 v[24:27], v130 offset:10400
	v_lshl_add_u64 v[28:29], v[54:55], 1, s[8:9]
	s_waitcnt lgkmcnt(0)
	v_pk_fma_f32 v[20:21], s[12:13], v[24:25], v[20:21]
	v_pk_fma_f32 v[22:23], s[12:13], v[26:27], v[22:23]
	global_store_dwordx4 v[52:53], v[20:23], off
	v_cvt_pk_bf16_f32 v24, v20, v21
	v_cvt_pk_bf16_f32 v25, v22, v23
	v_pk_mul_f32 v[20:21], v[20:21], v[20:21]
	v_pk_mul_f32 v[22:23], v[22:23], v[22:23]
	v_add_f32_e32 v20, v20, v21
	v_add_f32_e32 v20, v20, v22
	v_add_f32_e32 v20, v20, v23
	global_store_dwordx2 v[28:29], v[24:25], off
	s_nop 0
	v_add_f32_dpp v20, v20, v20 row_ror:8 row_mask:0xf bank_mask:0xf bound_ctrl:1
	s_nop 1
	v_add_f32_dpp v20, v20, v20 row_ror:4 row_mask:0xf bank_mask:0xf bound_ctrl:1
	s_nop 1
	v_add_f32_dpp v20, v20, v20 row_ror:2 row_mask:0xf bank_mask:0xf bound_ctrl:1
	s_nop 1
	v_add_f32_dpp v20, v20, v20 row_ror:1 row_mask:0xf bank_mask:0xf bound_ctrl:1
	s_nop 0
	v_readlane_b32 s64, v20, 0
	v_readlane_b32 s67, v20, 16
	v_readlane_b32 s65, v20, 32
	v_readlane_b32 s66, v20, 48
	s_and_saveexec_b64 s[4:5], s[0:1]
	s_cbranch_execz .LBB0_383
	s_lshl_b64 s[62:63], s[62:63], 2
	v_mov_b32_e32 v20, s67
	s_add_u32 s62, s16, s62
	v_add_f32_e32 v20, s64, v20
	s_addc_u32 s63, s17, s63
	v_add_f32_e32 v20, s65, v20
	v_add_f32_e32 v22, s66, v20
	v_mov_b64_e32 v[20:21], s[62:63]
	global_atomic_add_f32 v[20:21], v22, off
.LBB0_383:
	s_or_b64 exec, exec, s[4:5]
	ds_read_b128 v[20:23], v130 offset:11440
	v_lshl_add_u64 v[24:25], v[50:51], 1, s[8:9]
	s_waitcnt lgkmcnt(0)
	v_pk_fma_f32 v[16:17], s[12:13], v[20:21], v[16:17]
	v_pk_fma_f32 v[18:19], s[12:13], v[22:23], v[18:19]
	global_store_dwordx4 v[48:49], v[16:19], off
	v_cvt_pk_bf16_f32 v20, v16, v17
	v_cvt_pk_bf16_f32 v21, v18, v19
	v_pk_mul_f32 v[16:17], v[16:17], v[16:17]
	v_pk_mul_f32 v[18:19], v[18:19], v[18:19]
	v_add_f32_e32 v16, v16, v17
	v_add_f32_e32 v16, v16, v18
	v_add_f32_e32 v16, v16, v19
	global_store_dwordx2 v[24:25], v[20:21], off
	s_nop 0
	v_add_f32_dpp v16, v16, v16 row_ror:8 row_mask:0xf bank_mask:0xf bound_ctrl:1
	s_nop 1
	v_add_f32_dpp v16, v16, v16 row_ror:4 row_mask:0xf bank_mask:0xf bound_ctrl:1
	s_nop 1
	v_add_f32_dpp v16, v16, v16 row_ror:2 row_mask:0xf bank_mask:0xf bound_ctrl:1
	s_nop 1
	v_add_f32_dpp v16, v16, v16 row_ror:1 row_mask:0xf bank_mask:0xf bound_ctrl:1
	s_nop 0
	v_readlane_b32 s62, v16, 0
	v_readlane_b32 s65, v16, 16
	v_readlane_b32 s63, v16, 32
	v_readlane_b32 s64, v16, 48
	s_and_saveexec_b64 s[4:5], s[0:1]
	s_cbranch_execz .LBB0_385
	s_lshl_b64 s[34:35], s[34:35], 2
	v_mov_b32_e32 v16, s65
	s_add_u32 s34, s16, s34
	v_add_f32_e32 v16, s62, v16
	s_addc_u32 s35, s17, s35
	v_add_f32_e32 v16, s63, v16
	v_add_f32_e32 v18, s64, v16
	v_mov_b64_e32 v[16:17], s[34:35]
	global_atomic_add_f32 v[16:17], v18, off
; DEVI float fsig(float x) { return __builtin_amdgcn_rcpf(1.f + __expf(-x)); }
; DEVI float bflo(unsigned u) { return __uint_as_float(u << 16); }
; DEVI float bfhi(unsigned u) { return __uint_as_float(u & 0xffff0000u); }
; template <int EPI, int TS, bool VT>
; DEVI void gemm_epilogue(const Params& p, char* smem, f32x4 (&acc)[2][2][4][2], int m0, int n0, float scale, const float* ssin,
;                         float* ssout, u16* xbout, int wid, int lane, int wr, int wc, int fr, int fq) {
;     ...
;         for (int u = 0; u < 8; ++u) {
;           const int i = i0 + u;
;           const int grow = g0 + i;
;           const float* Tr = T + (r0 + i) * TS;
;           const float rs = __int_as_float(__builtin_amdgcn_readlane(__float_as_int(rsv), i));
;           if constexpr (EPI == E_RESID || EPI == E_PLEGATE) {
;             const float4 a = *(const float4*)(Tr + 4 * lane);
;             const size_t ro = (size_t)grow * 1024 + n0 + 4 * lane;
;             float4 x4 = xo[u];
;             if constexpr (EPI == E_PLEGATE) {
;               x4.x += bflo(pv[u].x) * fsig(a.x * rs);
;               x4.y += bfhi(pv[u].x) * fsig(a.y * rs);
;               x4.z += bflo(pv[u].y) * fsig(a.z * rs);
;               x4.w += bfhi(pv[u].y) * fsig(a.w * rs);
;             } else {
;               const float sc = fabsf(scale);
;               x4.x += sc * a.x; x4.y += sc * a.y; x4.z += sc * a.z; x4.w += sc * a.w;
;             }
;             st_nt16(p.x + ro, x4);
;             if (xbout) {
;               uint2 o;
;               o.x = pack2(x4.x, x4.y);
;               o.y = pack2(x4.z, x4.w);
;               st_nt8(xbout + ro, o);
;             }
;             if (ssout) {
;               const float ssq = wsum(x4.x * x4.x + x4.y * x4.y + x4.z * x4.z + x4.w * x4.w, lane);
;               if (lane == 0) atomicAdd(ssout + grow, ssq);
;             }
.LBB0_385:
	s_or_b64 exec, exec, s[4:5]
	ds_read_b128 v[16:19], v130 offset:12480
	v_lshl_add_u64 v[20:21], v[46:47], 1, s[8:9]
	s_waitcnt lgkmcnt(0)
	v_pk_fma_f32 v[12:13], s[12:13], v[16:17], v[12:13]
	v_pk_fma_f32 v[14:15], s[12:13], v[18:19], v[14:15]
	global_store_dwordx4 v[44:45], v[12:15], off
	v_cvt_pk_bf16_f32 v16, v12, v13
	v_cvt_pk_bf16_f32 v17, v14, v15
	v_pk_mul_f32 v[12:13], v[12:13], v[12:13]
	v_pk_mul_f32 v[14:15], v[14:15], v[14:15]
	v_add_f32_e32 v12, v12, v13
	v_add_f32_e32 v12, v12, v14
	v_add_f32_e32 v12, v12, v15
	global_store_dwordx2 v[20:21], v[16:17], off
	s_nop 0
	v_add_f32_dpp v12, v12, v12 row_ror:8 row_mask:0xf bank_mask:0xf bound_ctrl:1
	s_nop 1
	v_add_f32_dpp v12, v12, v12 row_ror:4 row_mask:0xf bank_mask:0xf bound_ctrl:1
	s_nop 1
	v_add_f32_dpp v12, v12, v12 row_ror:2 row_mask:0xf bank_mask:0xf bound_ctrl:1
	s_nop 1
	v_add_f32_dpp v12, v12, v12 row_ror:1 row_mask:0xf bank_mask:0xf bound_ctrl:1
	s_nop 0
	v_readlane_b32 s34, v12, 0
	v_readlane_b32 s63, v12, 16
	v_readlane_b32 s35, v12, 32
	v_readlane_b32 s62, v12, 48
	s_and_saveexec_b64 s[4:5], s[0:1]
	s_cbranch_execz .LBB0_387
	s_lshl_b64 s[30:31], s[30:31], 2
	v_mov_b32_e32 v12, s63
	s_add_u32 s30, s16, s30
	v_add_f32_e32 v12, s34, v12
	s_addc_u32 s31, s17, s31
	v_add_f32_e32 v12, s35, v12
	v_add_f32_e32 v14, s62, v12
	v_mov_b64_e32 v[12:13], s[30:31]
	global_atomic_add_f32 v[12:13], v14, off
.LBB0_387:
	s_or_b64 exec, exec, s[4:5]
	ds_read_b128 v[12:15], v130 offset:13520
	v_lshl_add_u64 v[16:17], v[42:43], 1, s[8:9]
	s_waitcnt lgkmcnt(0)
	v_pk_fma_f32 v[8:9], s[12:13], v[12:13], v[8:9]
	v_pk_fma_f32 v[10:11], s[12:13], v[14:15], v[10:11]
	global_store_dwordx4 v[40:41], v[8:11], off
	v_cvt_pk_bf16_f32 v12, v8, v9
	v_cvt_pk_bf16_f32 v13, v10, v11
	v_pk_mul_f32 v[8:9], v[8:9], v[8:9]
	v_pk_mul_f32 v[10:11], v[10:11], v[10:11]
	v_add_f32_e32 v8, v8, v9
	v_add_f32_e32 v8, v8, v10
	v_add_f32_e32 v8, v8, v11
	global_store_dwordx2 v[16:17], v[12:13], off
	s_nop 0
	v_add_f32_dpp v8, v8, v8 row_ror:8 row_mask:0xf bank_mask:0xf bound_ctrl:1
	s_nop 1
	v_add_f32_dpp v8, v8, v8 row_ror:4 row_mask:0xf bank_mask:0xf bound_ctrl:1
	s_nop 1
	v_add_f32_dpp v8, v8, v8 row_ror:2 row_mask:0xf bank_mask:0xf bound_ctrl:1
	s_nop 1
	v_add_f32_dpp v8, v8, v8 row_ror:1 row_mask:0xf bank_mask:0xf bound_ctrl:1
	s_nop 0
	v_readlane_b32 s30, v8, 0
	v_readlane_b32 s35, v8, 16
	v_readlane_b32 s31, v8, 32
	v_readlane_b32 s34, v8, 48
	s_and_saveexec_b64 s[4:5], s[0:1]
	s_cbranch_execz .LBB0_389
	s_lshl_b64 s[22:23], s[22:23], 2
	v_mov_b32_e32 v8, s35
	s_add_u32 s22, s16, s22
	v_add_f32_e32 v8, s30, v8
	s_addc_u32 s23, s17, s23
	v_add_f32_e32 v8, s31, v8
	v_add_f32_e32 v10, s34, v8
	v_mov_b64_e32 v[8:9], s[22:23]
	global_atomic_add_f32 v[8:9], v10, off
.LBB0_389:
	s_or_b64 exec, exec, s[4:5]
	ds_read_b128 v[8:11], v130 offset:14560
	v_lshl_add_u64 v[12:13], v[38:39], 1, s[8:9]
	s_waitcnt lgkmcnt(0)
	v_pk_fma_f32 v[4:5], s[12:13], v[8:9], v[4:5]
	v_pk_fma_f32 v[6:7], s[12:13], v[10:11], v[6:7]
	global_store_dwordx4 v[36:37], v[4:7], off
	v_cvt_pk_bf16_f32 v8, v4, v5
	v_cvt_pk_bf16_f32 v9, v6, v7
	v_pk_mul_f32 v[4:5], v[4:5], v[4:5]
	v_pk_mul_f32 v[6:7], v[6:7], v[6:7]
	v_add_f32_e32 v4, v4, v5
	v_add_f32_e32 v4, v4, v6
	v_add_f32_e32 v4, v4, v7
	global_store_dwordx2 v[12:13], v[8:9], off
	s_nop 0
	v_add_f32_dpp v4, v4, v4 row_ror:8 row_mask:0xf bank_mask:0xf bound_ctrl:1
	s_nop 1
	v_add_f32_dpp v4, v4, v4 row_ror:4 row_mask:0xf bank_mask:0xf bound_ctrl:1
	s_nop 1
	v_add_f32_dpp v4, v4, v4 row_ror:2 row_mask:0xf bank_mask:0xf bound_ctrl:1
	s_nop 1
	v_add_f32_dpp v4, v4, v4 row_ror:1 row_mask:0xf bank_mask:0xf bound_ctrl:1
	s_nop 0
	v_readlane_b32 s22, v4, 0
	v_readlane_b32 s31, v4, 16
	v_readlane_b32 s23, v4, 32
	v_readlane_b32 s30, v4, 48
	s_and_saveexec_b64 s[4:5], s[0:1]
	s_cbranch_execz .LBB0_391
	s_lshl_b64 s[20:21], s[20:21], 2
	v_mov_b32_e32 v4, s31
	s_add_u32 s20, s16, s20
	v_add_f32_e32 v4, s22, v4
	s_addc_u32 s21, s17, s21
	v_add_f32_e32 v4, s23, v4
	v_add_f32_e32 v6, s30, v4
	v_mov_b64_e32 v[4:5], s[20:21]
	global_atomic_add_f32 v[4:5], v6, off
.LBB0_391:
	s_or_b64 exec, exec, s[4:5]
	ds_read_b128 v[4:7], v130 offset:15600
	v_lshl_add_u64 v[8:9], v[34:35], 1, s[8:9]
	s_waitcnt lgkmcnt(0)
	v_pk_fma_f32 v[0:1], s[12:13], v[4:5], v[0:1]
	v_pk_fma_f32 v[2:3], s[12:13], v[6:7], v[2:3]
	global_store_dwordx4 v[32:33], v[0:3], off
	v_cvt_pk_bf16_f32 v4, v0, v1
	v_cvt_pk_bf16_f32 v5, v2, v3
	v_pk_mul_f32 v[0:1], v[0:1], v[0:1]
	v_pk_mul_f32 v[2:3], v[2:3], v[2:3]
	v_add_f32_e32 v0, v0, v1
	v_add_f32_e32 v0, v0, v2
	v_add_f32_e32 v0, v0, v3
	global_store_dwordx2 v[8:9], v[4:5], off
	s_nop 0
	v_add_f32_dpp v0, v0, v0 row_ror:8 row_mask:0xf bank_mask:0xf bound_ctrl:1
	s_nop 1
	v_add_f32_dpp v0, v0, v0 row_ror:4 row_mask:0xf bank_mask:0xf bound_ctrl:1
	s_nop 1
	v_add_f32_dpp v0, v0, v0 row_ror:2 row_mask:0xf bank_mask:0xf bound_ctrl:1
	s_nop 1
	v_add_f32_dpp v0, v0, v0 row_ror:1 row_mask:0xf bank_mask:0xf bound_ctrl:1
	s_nop 0
	v_readlane_b32 s20, v0, 0
	v_readlane_b32 s23, v0, 16
	v_readlane_b32 s21, v0, 32
	v_readlane_b32 s22, v0, 48
	s_and_saveexec_b64 s[4:5], s[0:1]
	s_cbranch_execz .LBB0_160
	s_lshl_b64 s[0:1], s[18:19], 2
	v_mov_b32_e32 v0, s23
	s_add_u32 s0, s16, s0
	v_add_f32_e32 v0, s20, v0
	s_addc_u32 s1, s17, s1
	v_add_f32_e32 v0, s21, v0
	v_add_f32_e32 v2, s22, v0
	v_mov_b64_e32 v[0:1], s[0:1]
	global_atomic_add_f32 v[0:1], v2, off
	s_branch .LBB0_160

; template <int EPI, int TS, bool VT>
; DEVI void gemm_epilogue(const Params& p, char* smem, f32x4 (&acc)[2][2][4][2], int m0, int n0, float scale, const float* ssin,
;                         float* ssout, u16* xbout, int wid, int lane, int wr, int wc, int fr, int fq) {
;     ...
;       float* tw = T + (wr * 64 + fq * 4) * TS + wc * 32 + fr;
; #pragma unroll
;       for (int m = 0; m < 4; ++m)
; #pragma unroll
;         for (int j = 0; j < 4; ++j)
; #pragma unroll
;           for (int v = 0; v < 4; ++v) tw[(m * 16 + j) * TS + (v >> 1) * 128 + (v & 1) * 16] = acc[ai][v >> 1][m][v & 1][j];
;     }
;     __syncthreads();
;     const int r0 = wid * 16;
;     const int g0 = m0 + ai * 128 + r0;
;     if constexpr (!VT) {
;       float rsv = 1.f;
;       if constexpr (EPI == E_PLEGATE || EPI == E_F32 || EPI == E_SWIGLU || EPI == E_GLAIN)
;         rsv = rsqrtf(ssin[g0 + (lane & 15)] * (1.f / 1024.f) + EPS);
;       if constexpr (EPI == E_QROPE) rsv = rsqrtf(ssin[g0 + (lane & 15)] * (1.f / 384.f) + EPS);
;       if constexpr (EPI == E_KV) rsv = rsqrtf(ssin[g0 + (lane & 15)] * (1.f / 256.f) + EPS);
.LBB0_419:
	v_lshrrev_b32_e32 v128, 2, v133
	v_and_or_b32 v128, v128, 12, s63
	s_movk_i32 s6, 0x410
	v_readlane_b32 s12, v254, 13
	v_mul_lo_u32 v128, v128, s6
	s_lshl_b32 s5, s5, 7
	v_lshlrev_b32_e32 v129, 2, v132
	v_readlane_b32 s13, v254, 14
	v_add3_u32 v128, s5, v128, v129
	ds_write2_b32 v128, v92, v100 offset1:16
	ds_write2_b32 v128, v120, v124 offset0:128 offset1:144
	v_add_u32_e32 v92, 0x400, v128
	ds_write2_b32 v92, v93, v101 offset0:4 offset1:20
	ds_write2_b32 v92, v121, v125 offset0:132 offset1:148
	v_add_u32_e32 v93, 0x800, v128
	ds_write2_b32 v93, v94, v102 offset0:8 offset1:24
	ds_write2_b32 v93, v122, v126 offset0:136 offset1:152
	v_add_u32_e32 v94, 0xc00, v128
	ds_write2_b32 v94, v95, v103 offset0:12 offset1:28
	ds_write2_b32 v94, v123, v127 offset0:140 offset1:156
	v_add_u32_e32 v95, 0x4000, v128
	ds_write2_b32 v95, v80, v84 offset0:64 offset1:80
	ds_write2_b32 v95, v112, v116 offset0:192 offset1:208
	v_add_u32_e32 v84, 0x4400, v128
	ds_write2_b32 v84, v81, v85 offset0:68 offset1:84
	ds_write2_b32 v84, v113, v117 offset0:196 offset1:212
	v_add_u32_e32 v81, 0x4800, v128
	s_lshl_b32 s82, s1, 4
	ds_write2_b32 v81, v82, v86 offset0:72 offset1:88
	ds_write2_b32 v81, v114, v118 offset0:200 offset1:216
	v_add_u32_e32 v82, 0x4c00, v128
	s_add_i32 s83, s82, s4
	ds_write2_b32 v82, v83, v87 offset0:76 offset1:92
	ds_write2_b32 v82, v115, v119 offset0:204 offset1:220
	v_add_u32_e32 v83, 0x8000, v128
	v_add_u32_e32 v85, 0x8400, v128
	v_add_u32_e32 v86, 0x8800, v128
	v_add_u32_e32 v87, 0x8c00, v128
	v_add_u32_e32 v100, 0x9000, v128
	v_add_u32_e32 v101, 0xc000, v128
	v_add_u32_e32 v102, 0xc400, v128
	ds_write2_b32 v83, v72, v76 offset0:128 offset1:144
	ds_write2_b32 v85, v104, v108 offset1:16
	ds_write2_b32 v85, v73, v77 offset0:132 offset1:148
	ds_write2_b32 v86, v105, v109 offset0:4 offset1:20
	ds_write2_b32 v86, v74, v78 offset0:136 offset1:152
	ds_write2_b32 v87, v106, v110 offset0:8 offset1:24
	ds_write2_b32 v87, v75, v79 offset0:140 offset1:156
	ds_write2_b32 v100, v107, v111 offset0:12 offset1:28
	ds_write2_b32 v101, v64, v68 offset0:192 offset1:208
	ds_write2_b32 v102, v88, v96 offset0:64 offset1:80
	ds_write2_b32 v102, v65, v69 offset0:196 offset1:212
	v_add_u32_e32 v88, 0xc800, v128
	v_or_b32_e32 v64, s83, v132
	ds_write2_b32 v88, v89, v97 offset0:68 offset1:84
	ds_write2_b32 v88, v66, v70 offset0:200 offset1:216
	v_add_u32_e32 v89, 0xcc00, v128
	v_ashrrev_i32_e32 v65, 31, v64
	ds_write2_b32 v89, v90, v98 offset0:72 offset1:88
	ds_write2_b32 v89, v67, v71 offset0:204 offset1:220
	v_add_u32_e32 v90, 0xd000, v128
	v_lshl_add_u64 v[64:65], v[64:65], 2, s[16:17]
	ds_write2_b32 v90, v91, v99 offset0:76 offset1:92
	s_waitcnt vmcnt(0) lgkmcnt(0)
	s_barrier
	global_load_dword v68, v[64:65], off
	s_cmp_lt_i32 s44, 2
	s_cselect_b64 s[34:35], -1, 0
	s_cmp_gt_i32 s44, 0
	v_and_b32_e32 v72, 63, v133
	s_cselect_b64 s[64:65], -1, 0
	s_cmp_eq_u32 s44, 2
	v_and_b32_e32 v64, 56, v133
	v_lshlrev_b32_e32 v69, 2, v72
	s_cselect_b64 s[6:7], -1, 0
	v_cmp_eq_u32_e32 vcc, 32, v64
	v_or_b32_e32 v148, s0, v69
	s_movk_i32 s0, 0x180
	s_movk_i32 s4, 0x17f
	s_and_b64 s[62:63], s[6:7], vcc
	s_movk_i32 s6, 0x280
	v_cmp_gt_i32_e64 s[0:1], s0, v148
	v_cmp_lt_i32_e64 s[4:5], s4, v148
	v_cmp_gt_u32_e64 s[6:7], s6, v148
	v_lshl_add_u64 v[64:65], v[148:149], 1, s[12:13]
	v_ashrrev_i32_e32 v67, 31, v148
	v_mov_b32_e32 v66, v148
	v_add_u32_e32 v70, 0xfffffe80, v148
	v_add_u32_e32 v148, 0xffffff80, v69
	s_movk_i32 s10, 0x100
	v_lshl_add_u64 v[66:67], v[66:67], 1, s[12:13]
	s_mov_b64 s[8:9], 0x2395ee00
	v_cmp_gt_u32_e64 s[10:11], s10, v70
	v_lshl_add_u64 v[70:71], v[148:149], 2, s[12:13]
	s_mov_b64 s[14:15], 0x5520000
	v_lshl_add_u64 v[66:67], v[66:67], 0, s[8:9]
	v_cmp_eq_u32_e64 s[8:9], 0, v72
	v_lshlrev_b32_e32 v80, 4, v72
	s_mov_b32 s84, 0
	s_mov_b64 s[66:67], -1
	s_waitcnt vmcnt(0) lgkmcnt(0)
	v_fmamk_f32 v68, v68, 0x3a800000, v150
	v_mul_f32_e32 v69, 0x4b800000, v68
	v_cmp_gt_f32_e32 vcc, s29, v68
	s_nop 1
	v_cndmask_b32_e32 v68, v68, v69, vcc
	v_rsq_f32_e32 v73, v68
	v_lshl_add_u64 v[68:69], v[70:71], 0, s[14:15]
	s_mov_b64 s[14:15], 0x55a0000
	v_lshl_add_u64 v[70:71], v[70:71], 0, s[14:15]
	v_mul_f32_e32 v74, 0x45800000, v73
	v_cndmask_b32_e32 v91, v73, v74, vcc
	v_lshl_add_u64 v[72:73], v[148:149], 1, s[12:13]
	s_mov_b64 s[12:13], 0x33d5ee00
	v_lshl_add_u64 v[72:73], v[72:73], 0, s[12:13]
	s_branch .LBB0_421

; template <int EPI, int TS, bool VT>
; DEVI void gemm_epilogue(const Params& p, char* smem, f32x4 (&acc)[2][2][4][2], int m0, int n0, float scale, const float* ssin,
;                         float* ssout, u16* xbout, int wid, int lane, int wr, int wc, int fr, int fq) {
;     ...
;           } else if constexpr (EPI == E_F32) {
;             const float4 a = *(const float4*)(Tr + 4 * lane);
;             const int col = n0 + 4 * lane;
;             const float v0 = a.x * rs, v1 = a.y * rs, v2 = a.z * rs, v3 = a.w * rs;
;             const float sq = v0 * v0 + v1 * v1 + v2 * v2 + v3 * v3;
;             uint2 o;
;             o.x = pack2(v0, v1);
;             o.y = pack2(v2, v3);
;             if (col < 384) *(uint2*)((u16*)(wsb + OFF_CQN) + (size_t)grow * 384 + col) = o;
;             else if (col < 640) *(uint2*)((u16*)(wsb + OFF_CKVN) + (size_t)grow * 256 + (col - 384)) = o;
.LBB0_421:
	s_or_b32 s12, s84, s82
	s_mulk_i32 s12, 0x410
	v_add_u32_e32 v96, s12, v80
	ds_read_b128 v[76:79], v96
	v_readlane_b32 s70, v91, s84
	s_or_b32 s68, s84, s83
	s_waitcnt lgkmcnt(0)
	v_pk_mul_f32 v[76:77], s[70:71], v[76:77] op_sel_hi:[0,1]
	v_pk_mul_f32 v[74:75], s[70:71], v[78:79] op_sel_hi:[0,1]
	v_cvt_pk_bf16_f32 v78, v76, v77
	v_cvt_pk_bf16_f32 v79, v74, v75
	s_and_saveexec_b64 s[12:13], s[4:5]
	s_xor_b64 s[12:13], exec, s[12:13]
	s_cbranch_execz .LBB0_425
	s_and_saveexec_b64 s[14:15], s[6:7]
	s_cbranch_execz .LBB0_424
	s_ashr_i32 s69, s68, 31
	s_lshl_b64 s[72:73], s[68:69], 9
	v_lshl_add_u64 v[98:99], v[64:65], 0, s[72:73]
	v_add_co_u32_e32 v98, vcc, 0x2755e000, v98
	s_nop 1
	v_addc_co_u32_e32 v99, vcc, 0, v99, vcc
	global_store_dwordx2 v[98:99], v[78:79], off offset:2816

; template <int EPI, int TS, bool VT>
; DEVI void gemm_epilogue(const Params& p, char* smem, f32x4 (&acc)[2][2][4][2], int m0, int n0, float scale, const float* ssin,
;                         float* ssout, u16* xbout, int wid, int lane, int wr, int wc, int fr, int fq) {
;     ...
;             const float v0 = a.x * rs, v1 = a.y * rs, v2 = a.z * rs, v3 = a.w * rs;
;             const float sq = v0 * v0 + v1 * v1 + v2 * v2 + v3 * v3;
;             uint2 o;
;             o.x = pack2(v0, v1);
;             o.y = pack2(v2, v3);
;             if (col < 384) *(uint2*)((u16*)(wsb + OFF_CQN) + (size_t)grow * 384 + col) = o;
;             else if (col < 640) *(uint2*)((u16*)(wsb + OFF_CKVN) + (size_t)grow * 256 + (col - 384)) = o;
;             if (n0 < 512) {
;               const float sqq = wsum(col < 384 ? sq : 0.f, lane);
;               if (lane == 0) atomicAdd(ssout + grow, sqq);
;             }
.LBB0_425:
	s_andn2_saveexec_b64 s[12:13], s[12:13]
	s_cbranch_execz .LBB0_427
	v_mad_i64_i32 v[98:99], s[14:15], s68, v169, v[66:67]
	global_store_dwordx2 v[98:99], v[78:79], off
.LBB0_427:
	s_or_b64 exec, exec, s[12:13]
	v_pk_mul_f32 v[78:79], v[76:77], v[76:77]
	v_pk_mul_f32 v[98:99], v[74:75], v[74:75]
	v_add_f32_e32 v78, v78, v79
	v_add_f32_e32 v78, v78, v98
	v_cndmask_b32_e64 v79, 0, 1, s[34:35]
	v_cmp_ne_u32_e64 s[12:13], 1, v79
	s_andn2_b64 vcc, exec, s[34:35]
	v_add_f32_e32 v78, v78, v99
	s_cbranch_vccnz .LBB0_431
	v_cndmask_b32_e64 v79, 0, v78, s[0:1]
	s_nop 1
	v_add_f32_dpp v79, v79, v79 row_ror:8 row_mask:0xf bank_mask:0xf bound_ctrl:1
	s_nop 1
	v_add_f32_dpp v79, v79, v79 row_ror:4 row_mask:0xf bank_mask:0xf bound_ctrl:1
	s_nop 1
	v_add_f32_dpp v79, v79, v79 row_ror:2 row_mask:0xf bank_mask:0xf bound_ctrl:1
	s_nop 1
	v_add_f32_dpp v79, v79, v79 row_ror:1 row_mask:0xf bank_mask:0xf bound_ctrl:1
	s_nop 0
	v_readlane_b32 s44, v79, 0
	v_readlane_b32 s73, v79, 16
	v_readlane_b32 s71, v79, 32
	v_readlane_b32 s72, v79, 48
	s_and_saveexec_b64 s[14:15], s[8:9]
	s_cbranch_execz .LBB0_430
	s_ashr_i32 s69, s68, 31
	s_lshl_b64 s[74:75], s[68:69], 2
	v_mov_b32_e32 v79, s73
	s_add_u32 s74, s18, s74
	v_add_f32_e32 v79, s44, v79
	s_addc_u32 s75, s19, s75
	v_add_f32_e32 v79, s71, v79
	v_add_f32_e32 v79, s72, v79
	v_mov_b64_e32 v[98:99], s[74:75]
	global_atomic_add_f32 v[98:99], v79, off

; template <int EPI, int TS, bool VT>
; DEVI void gemm_epilogue(const Params& p, char* smem, f32x4 (&acc)[2][2][4][2], int m0, int n0, float scale, const float* ssin,
;                         float* ssout, u16* xbout, int wid, int lane, int wr, int wc, int fr, int fq) {
;     ...
;             if (n0 >= 256) {
;               const float sqk = wsum((col >= 384 && col < 640) ? sq : 0.f, lane);
;               if (lane == 0) atomicAdd(ssout + MTOK + grow, sqk);
;             }
.LBB0_431:
	v_cndmask_b32_e64 v79, 0, 1, s[64:65]
	v_cmp_ne_u32_e64 s[14:15], 1, v79
	s_andn2_b64 vcc, exec, s[64:65]
	s_cbranch_vccnz .LBB0_435
	v_cndmask_b32_e64 v78, 0, v78, s[10:11]
	s_nop 1
	v_add_f32_dpp v78, v78, v78 row_ror:8 row_mask:0xf bank_mask:0xf bound_ctrl:1
	s_nop 1
	v_add_f32_dpp v78, v78, v78 row_ror:4 row_mask:0xf bank_mask:0xf bound_ctrl:1
	s_nop 1
	v_add_f32_dpp v78, v78, v78 row_ror:2 row_mask:0xf bank_mask:0xf bound_ctrl:1
	s_nop 1
	v_add_f32_dpp v78, v78, v78 row_ror:1 row_mask:0xf bank_mask:0xf bound_ctrl:1
	s_nop 0
	v_readlane_b32 s44, v78, 0
	v_readlane_b32 s75, v78, 16
	v_readlane_b32 s71, v78, 32
	v_readlane_b32 s74, v78, 48
	s_and_saveexec_b64 s[72:73], s[8:9]
	s_cbranch_execz .LBB0_434
	s_ashr_i32 s69, s68, 31
	s_lshl_b64 s[86:87], s[68:69], 2
	v_mov_b32_e32 v78, s75
	s_add_u32 s86, s78, s86
	v_add_f32_e32 v78, s44, v78
	s_addc_u32 s87, s79, s87
	v_add_f32_e32 v78, s71, v78
	v_add_f32_e32 v97, s74, v78
	v_mov_b64_e32 v[78:79], s[86:87]
	global_atomic_add_f32 v[78:79], v97, off

; template <int EPI, int TS, bool VT>
; DEVI void gemm_epilogue(const Params& p, char* smem, f32x4 (&acc)[2][2][4][2], int m0, int n0, float scale, const float* ssin,
;                         float* ssout, u16* xbout, int wid, int lane, int wr, int wc, int fr, int fq) {
;     ...
;           } else if constexpr (EPI == E_F32) {
;             const float4 a = *(const float4*)(Tr + 4 * lane);
;             const int col = n0 + 4 * lane;
;             const float v0 = a.x * rs, v1 = a.y * rs, v2 = a.z * rs, v3 = a.w * rs;
;             const float sq = v0 * v0 + v1 * v1 + v2 * v2 + v3 * v3;
;             uint2 o;
;             o.x = pack2(v0, v1);
;             o.y = pack2(v2, v3);
;             if (col < 384) *(uint2*)((u16*)(wsb + OFF_CQN) + (size_t)grow * 384 + col) = o;
;             else if (col < 640) *(uint2*)((u16*)(wsb + OFF_CKVN) + (size_t)grow * 256 + (col - 384)) = o;
;     ...
;             if (n0 == 512 && lane >= 32 && lane < 40) {
;               const int i0r = 4 * (lane - 32);
;               const float4 b4 = *(const float4*)(Tr + 160 + i0r);
;               const int pos = tok_pos(grow);
;               const float4 c4 = *(const float4*)((const float*)(wsb + OFF_COS) + pos * 32 + i0r);
;               const float4 s4 = *(const float4*)((const float*)(wsb + OFF_SIN) + pos * 32 + i0r);
;               const float x1[4] = {v0, v1, v2, v3};
;               const float x2[4] = {b4.x * rs, b4.y * rs, b4.z * rs, b4.w * rs};
;               const float cc[4] = {c4.x, c4.y, c4.z, c4.w}, sn[4] = {s4.x, s4.y, s4.z, s4.w};
;               uint2 o1, o2;
;               o1.x = pack2(x1[0] * cc[0] - x2[0] * sn[0], x1[1] * cc[1] - x2[1] * sn[1]);
;               o1.y = pack2(x1[2] * cc[2] - x2[2] * sn[2], x1[3] * cc[3] - x2[3] * sn[3]);
;               o2.x = pack2(x2[0] * cc[0] + x1[0] * sn[0], x2[1] * cc[1] + x1[1] * sn[1]);
;               o2.y = pack2(x2[2] * cc[2] + x1[2] * sn[2], x2[3] * cc[3] + x1[3] * sn[3]);
;               u16* kr = (u16*)(wsb + OFF_KRM) + (size_t)grow * 64;
;               *(uint2*)(kr + i0r) = o1;
;               *(uint2*)(kr + 32 + i0r) = o2;
;             }
.LBB0_435:
	s_and_saveexec_b64 s[72:73], s[62:63]
	s_cbranch_execz .LBB0_437
	s_cmp_lt_i32 s68, 0x10000
	s_movk_i32 s44, 0xff8
	s_cselect_b32 s44, s44, 0x7f8
	s_and_b32 s44, s44, s68
	s_lshl_b32 s44, s44, 7
	v_lshl_add_u64 v[78:79], v[68:69], 0, s[44:45]
	v_lshl_add_u64 v[108:109], v[70:71], 0, s[44:45]
	ds_read_b128 v[96:99], v96 offset:128
	global_load_dwordx4 v[104:107], v[78:79], off
	s_nop 0
	global_load_dwordx4 v[108:111], v[108:109], off
	s_mov_b32 s71, s70
	s_ashr_i32 s69, s68, 31
	s_lshl_b64 s[68:69], s[68:69], 7
	s_waitcnt lgkmcnt(0)
	v_pk_mul_f32 v[78:79], s[70:71], v[96:97]
	s_waitcnt vmcnt(0)
	v_pk_mul_f32 v[96:97], v[78:79], v[108:109]
	s_nop 0
	v_pk_fma_f32 v[96:97], v[76:77], v[104:105], v[96:97] neg_lo:[0,0,1] neg_hi:[0,0,1]
	v_pk_mul_f32 v[76:77], v[76:77], v[108:109]
	v_cvt_pk_bf16_f32 v96, v96, v97
	v_pk_fma_f32 v[76:77], v[78:79], v[104:105], v[76:77]
	v_pk_mul_f32 v[78:79], s[70:71], v[98:99]
	v_cvt_pk_bf16_f32 v76, v76, v77
	v_pk_mul_f32 v[98:99], v[78:79], v[110:111]
	s_nop 0
	v_pk_fma_f32 v[98:99], v[74:75], v[106:107], v[98:99] neg_lo:[0,0,1] neg_hi:[0,0,1]
	v_pk_mul_f32 v[74:75], v[74:75], v[110:111]
	v_cvt_pk_bf16_f32 v97, v98, v99
	v_pk_fma_f32 v[74:75], v[78:79], v[106:107], v[74:75]
	s_nop 0
	v_cvt_pk_bf16_f32 v77, v74, v75
	v_lshl_add_u64 v[74:75], v[72:73], 0, s[68:69]
	global_store_dwordx2 v[74:75], v[96:97], off
	global_store_dwordx2 v[74:75], v[76:77], off offset:64
.LBB0_437:
	s_or_b64 exec, exec, s[72:73]
	s_or_b32 s44, s84, 1
	s_or_b32 s68, s44, s82
	s_mulk_i32 s68, 0x410
	v_add_u32_e32 v96, s68, v80
	ds_read_b128 v[76:79], v96
	v_readlane_b32 s70, v91, s44
	s_or_b32 s68, s44, s83
	s_waitcnt lgkmcnt(0)
	v_pk_mul_f32 v[76:77], s[70:71], v[76:77] op_sel_hi:[0,1]
	v_pk_mul_f32 v[74:75], s[70:71], v[78:79] op_sel_hi:[0,1]
	v_cvt_pk_bf16_f32 v78, v76, v77
	v_cvt_pk_bf16_f32 v79, v74, v75
	s_and_saveexec_b64 s[72:73], s[4:5]
	s_xor_b64 s[72:73], exec, s[72:73]
	s_cbranch_execz .LBB0_441
	s_and_saveexec_b64 s[74:75], s[6:7]
	s_cbranch_execz .LBB0_440
	s_ashr_i32 s69, s68, 31
	s_lshl_b64 s[86:87], s[68:69], 9
	v_lshl_add_u64 v[98:99], v[64:65], 0, s[86:87]
	v_add_co_u32_e32 v98, vcc, 0x2755e000, v98
	s_nop 1
	v_addc_co_u32_e32 v99, vcc, 0, v99, vcc
	global_store_dwordx2 v[98:99], v[78:79], off offset:2816

; template <int EPI, int TS, bool VT>
; DEVI void gemm_epilogue(const Params& p, char* smem, f32x4 (&acc)[2][2][4][2], int m0, int n0, float scale, const float* ssin,
;                         float* ssout, u16* xbout, int wid, int lane, int wr, int wc, int fr, int fq) {
;     ...
;             const float sq = v0 * v0 + v1 * v1 + v2 * v2 + v3 * v3;
;             uint2 o;
;             o.x = pack2(v0, v1);
;             o.y = pack2(v2, v3);
;             if (col < 384) *(uint2*)((u16*)(wsb + OFF_CQN) + (size_t)grow * 384 + col) = o;
;             else if (col < 640) *(uint2*)((u16*)(wsb + OFF_CKVN) + (size_t)grow * 256 + (col - 384)) = o;
;             if (n0 < 512) {
;               const float sqq = wsum(col < 384 ? sq : 0.f, lane);
;               if (lane == 0) atomicAdd(ssout + grow, sqq);
;             }
.LBB0_441:
	s_andn2_saveexec_b64 s[72:73], s[72:73]
	s_cbranch_execz .LBB0_443
	v_mad_i64_i32 v[98:99], s[74:75], s68, v169, v[66:67]
	global_store_dwordx2 v[98:99], v[78:79], off
.LBB0_443:
	s_or_b64 exec, exec, s[72:73]
	v_pk_mul_f32 v[78:79], v[76:77], v[76:77]
	v_pk_mul_f32 v[98:99], v[74:75], v[74:75]
	v_add_f32_e32 v78, v78, v79
	v_add_f32_e32 v78, v78, v98
	s_and_b64 vcc, exec, s[12:13]
	v_add_f32_e32 v78, v78, v99
	s_cbranch_vccnz .LBB0_447
	v_cndmask_b32_e64 v79, 0, v78, s[0:1]
	s_nop 1
	v_add_f32_dpp v79, v79, v79 row_ror:8 row_mask:0xf bank_mask:0xf bound_ctrl:1
	s_nop 1
	v_add_f32_dpp v79, v79, v79 row_ror:4 row_mask:0xf bank_mask:0xf bound_ctrl:1
	s_nop 1
	v_add_f32_dpp v79, v79, v79 row_ror:2 row_mask:0xf bank_mask:0xf bound_ctrl:1
	s_nop 1
	v_add_f32_dpp v79, v79, v79 row_ror:1 row_mask:0xf bank_mask:0xf bound_ctrl:1
	s_nop 0
	v_readlane_b32 s44, v79, 0
	v_readlane_b32 s75, v79, 16
	v_readlane_b32 s71, v79, 32
	v_readlane_b32 s74, v79, 48
	s_and_saveexec_b64 s[72:73], s[8:9]
	s_cbranch_execz .LBB0_446
	s_ashr_i32 s69, s68, 31
	s_lshl_b64 s[86:87], s[68:69], 2
	v_mov_b32_e32 v79, s75
	s_add_u32 s86, s18, s86
	v_add_f32_e32 v79, s44, v79
	s_addc_u32 s87, s19, s87
	v_add_f32_e32 v79, s71, v79
	v_add_f32_e32 v79, s74, v79
	v_mov_b64_e32 v[98:99], s[86:87]
	global_atomic_add_f32 v[98:99], v79, off

; template <int EPI, int TS, bool VT>
; DEVI void gemm_epilogue(const Params& p, char* smem, f32x4 (&acc)[2][2][4][2], int m0, int n0, float scale, const float* ssin,
;                         float* ssout, u16* xbout, int wid, int lane, int wr, int wc, int fr, int fq) {
;     ...
;             if (n0 >= 256) {
;               const float sqk = wsum((col >= 384 && col < 640) ? sq : 0.f, lane);
;               if (lane == 0) atomicAdd(ssout + MTOK + grow, sqk);
;             }
.LBB0_447:
	s_and_b64 vcc, exec, s[14:15]
	s_cbranch_vccnz .LBB0_451
	v_cndmask_b32_e64 v78, 0, v78, s[10:11]
	s_nop 1
	v_add_f32_dpp v78, v78, v78 row_ror:8 row_mask:0xf bank_mask:0xf bound_ctrl:1
	s_nop 1
	v_add_f32_dpp v78, v78, v78 row_ror:4 row_mask:0xf bank_mask:0xf bound_ctrl:1
	s_nop 1
	v_add_f32_dpp v78, v78, v78 row_ror:2 row_mask:0xf bank_mask:0xf bound_ctrl:1
	s_nop 1
	v_add_f32_dpp v78, v78, v78 row_ror:1 row_mask:0xf bank_mask:0xf bound_ctrl:1
	s_nop 0
	v_readlane_b32 s44, v78, 0
	v_readlane_b32 s75, v78, 16
	v_readlane_b32 s71, v78, 32
	v_readlane_b32 s74, v78, 48
	s_and_saveexec_b64 s[72:73], s[8:9]
	s_cbranch_execz .LBB0_450
	s_ashr_i32 s69, s68, 31
	s_lshl_b64 s[86:87], s[68:69], 2
	v_mov_b32_e32 v78, s75
	s_add_u32 s86, s78, s86
	v_add_f32_e32 v78, s44, v78
	s_addc_u32 s87, s79, s87
	v_add_f32_e32 v78, s71, v78
	v_add_f32_e32 v97, s74, v78
	v_mov_b64_e32 v[78:79], s[86:87]
	global_atomic_add_f32 v[78:79], v97, off

; template <int EPI, int TS, bool VT>
; DEVI void gemm_epilogue(const Params& p, char* smem, f32x4 (&acc)[2][2][4][2], int m0, int n0, float scale, const float* ssin,
;                         float* ssout, u16* xbout, int wid, int lane, int wr, int wc, int fr, int fq) {
;     ...
;           } else if constexpr (EPI == E_F32) {
;             const float4 a = *(const float4*)(Tr + 4 * lane);
;             const int col = n0 + 4 * lane;
;             const float v0 = a.x * rs, v1 = a.y * rs, v2 = a.z * rs, v3 = a.w * rs;
;             const float sq = v0 * v0 + v1 * v1 + v2 * v2 + v3 * v3;
;             uint2 o;
;             o.x = pack2(v0, v1);
;             o.y = pack2(v2, v3);
;             if (col < 384) *(uint2*)((u16*)(wsb + OFF_CQN) + (size_t)grow * 384 + col) = o;
;             else if (col < 640) *(uint2*)((u16*)(wsb + OFF_CKVN) + (size_t)grow * 256 + (col - 384)) = o;
;     ...
;             if (n0 == 512 && lane >= 32 && lane < 40) {
;               const int i0r = 4 * (lane - 32);
;               const float4 b4 = *(const float4*)(Tr + 160 + i0r);
;               const int pos = tok_pos(grow);
;               const float4 c4 = *(const float4*)((const float*)(wsb + OFF_COS) + pos * 32 + i0r);
;               const float4 s4 = *(const float4*)((const float*)(wsb + OFF_SIN) + pos * 32 + i0r);
;               const float x1[4] = {v0, v1, v2, v3};
;               const float x2[4] = {b4.x * rs, b4.y * rs, b4.z * rs, b4.w * rs};
;               const float cc[4] = {c4.x, c4.y, c4.z, c4.w}, sn[4] = {s4.x, s4.y, s4.z, s4.w};
;               uint2 o1, o2;
;               o1.x = pack2(x1[0] * cc[0] - x2[0] * sn[0], x1[1] * cc[1] - x2[1] * sn[1]);
;               o1.y = pack2(x1[2] * cc[2] - x2[2] * sn[2], x1[3] * cc[3] - x2[3] * sn[3]);
;               o2.x = pack2(x2[0] * cc[0] + x1[0] * sn[0], x2[1] * cc[1] + x1[1] * sn[1]);
;               o2.y = pack2(x2[2] * cc[2] + x1[2] * sn[2], x2[3] * cc[3] + x1[3] * sn[3]);
;               u16* kr = (u16*)(wsb + OFF_KRM) + (size_t)grow * 64;
;               *(uint2*)(kr + i0r) = o1;
;               *(uint2*)(kr + 32 + i0r) = o2;
;             }
.LBB0_451:
	s_and_saveexec_b64 s[72:73], s[62:63]
	s_cbranch_execz .LBB0_453
	s_cmp_lt_i32 s68, 0x10000
	s_movk_i32 s44, 0xff9
	s_cselect_b32 s44, s44, 0x7f9
	s_and_b32 s44, s44, s68
	s_lshl_b32 s44, s44, 7
	v_lshl_add_u64 v[78:79], v[68:69], 0, s[44:45]
	v_lshl_add_u64 v[108:109], v[70:71], 0, s[44:45]
	ds_read_b128 v[96:99], v96 offset:128
	global_load_dwordx4 v[104:107], v[78:79], off
	s_nop 0
	global_load_dwordx4 v[108:111], v[108:109], off
	s_mov_b32 s71, s70
	s_ashr_i32 s69, s68, 31
	s_lshl_b64 s[68:69], s[68:69], 7
	s_waitcnt lgkmcnt(0)
	v_pk_mul_f32 v[78:79], s[70:71], v[96:97]
	s_waitcnt vmcnt(0)
	v_pk_mul_f32 v[96:97], v[78:79], v[108:109]
	s_nop 0
	v_pk_fma_f32 v[96:97], v[76:77], v[104:105], v[96:97] neg_lo:[0,0,1] neg_hi:[0,0,1]
	v_pk_mul_f32 v[76:77], v[76:77], v[108:109]
	v_cvt_pk_bf16_f32 v96, v96, v97
	v_pk_fma_f32 v[76:77], v[78:79], v[104:105], v[76:77]
	v_pk_mul_f32 v[78:79], s[70:71], v[98:99]
	v_cvt_pk_bf16_f32 v76, v76, v77
	v_pk_mul_f32 v[98:99], v[78:79], v[110:111]
	s_nop 0
	v_pk_fma_f32 v[98:99], v[74:75], v[106:107], v[98:99] neg_lo:[0,0,1] neg_hi:[0,0,1]
	v_pk_mul_f32 v[74:75], v[74:75], v[110:111]
	v_cvt_pk_bf16_f32 v97, v98, v99
	v_pk_fma_f32 v[74:75], v[78:79], v[106:107], v[74:75]
	s_nop 0
	v_cvt_pk_bf16_f32 v77, v74, v75
	v_lshl_add_u64 v[74:75], v[72:73], 0, s[68:69]
	global_store_dwordx2 v[74:75], v[96:97], off
	global_store_dwordx2 v[74:75], v[76:77], off offset:64
.LBB0_453:
	s_or_b64 exec, exec, s[72:73]
	s_or_b32 s44, s84, 2
	s_or_b32 s68, s44, s82
	s_mulk_i32 s68, 0x410
	v_add_u32_e32 v96, s68, v80
	ds_read_b128 v[76:79], v96
	v_readlane_b32 s70, v91, s44
	s_or_b32 s68, s44, s83
	s_waitcnt lgkmcnt(0)
	v_pk_mul_f32 v[76:77], s[70:71], v[76:77] op_sel_hi:[0,1]
	v_pk_mul_f32 v[74:75], s[70:71], v[78:79] op_sel_hi:[0,1]
	v_cvt_pk_bf16_f32 v78, v76, v77
	v_cvt_pk_bf16_f32 v79, v74, v75
	s_and_saveexec_b64 s[72:73], s[4:5]
	s_xor_b64 s[72:73], exec, s[72:73]
	s_cbranch_execz .LBB0_457
	s_and_saveexec_b64 s[74:75], s[6:7]
	s_cbranch_execz .LBB0_456
	s_ashr_i32 s69, s68, 31
	s_lshl_b64 s[86:87], s[68:69], 9
	v_lshl_add_u64 v[98:99], v[64:65], 0, s[86:87]
	v_add_co_u32_e32 v98, vcc, 0x2755e000, v98
	s_nop 1
	v_addc_co_u32_e32 v99, vcc, 0, v99, vcc
	global_store_dwordx2 v[98:99], v[78:79], off offset:2816

; template <int EPI, int TS, bool VT>
; DEVI void gemm_epilogue(const Params& p, char* smem, f32x4 (&acc)[2][2][4][2], int m0, int n0, float scale, const float* ssin,
;                         float* ssout, u16* xbout, int wid, int lane, int wr, int wc, int fr, int fq) {
;     ...
;           } else if constexpr (EPI == E_F32) {
;             const float4 a = *(const float4*)(Tr + 4 * lane);
;             const int col = n0 + 4 * lane;
;             const float v0 = a.x * rs, v1 = a.y * rs, v2 = a.z * rs, v3 = a.w * rs;
;             const float sq = v0 * v0 + v1 * v1 + v2 * v2 + v3 * v3;
;             uint2 o;
;             o.x = pack2(v0, v1);
;             o.y = pack2(v2, v3);
;             if (col < 384) *(uint2*)((u16*)(wsb + OFF_CQN) + (size_t)grow * 384 + col) = o;
;             else if (col < 640) *(uint2*)((u16*)(wsb + OFF_CKVN) + (size_t)grow * 256 + (col - 384)) = o;
;     ...
;             if (n0 == 512 && lane >= 32 && lane < 40) {
;               const int i0r = 4 * (lane - 32);
;               const float4 b4 = *(const float4*)(Tr + 160 + i0r);
;               const int pos = tok_pos(grow);
;               const float4 c4 = *(const float4*)((const float*)(wsb + OFF_COS) + pos * 32 + i0r);
;               const float4 s4 = *(const float4*)((const float*)(wsb + OFF_SIN) + pos * 32 + i0r);
;               const float x1[4] = {v0, v1, v2, v3};
;               const float x2[4] = {b4.x * rs, b4.y * rs, b4.z * rs, b4.w * rs};
;               const float cc[4] = {c4.x, c4.y, c4.z, c4.w}, sn[4] = {s4.x, s4.y, s4.z, s4.w};
;               uint2 o1, o2;
;               o1.x = pack2(x1[0] * cc[0] - x2[0] * sn[0], x1[1] * cc[1] - x2[1] * sn[1]);
;               o1.y = pack2(x1[2] * cc[2] - x2[2] * sn[2], x1[3] * cc[3] - x2[3] * sn[3]);
;               o2.x = pack2(x2[0] * cc[0] + x1[0] * sn[0], x2[1] * cc[1] + x1[1] * sn[1]);
;               o2.y = pack2(x2[2] * cc[2] + x1[2] * sn[2], x2[3] * cc[3] + x1[3] * sn[3]);
;               u16* kr = (u16*)(wsb + OFF_KRM) + (size_t)grow * 64;
;               *(uint2*)(kr + i0r) = o1;
;               *(uint2*)(kr + 32 + i0r) = o2;
;             }
.LBB0_467:
	s_and_saveexec_b64 s[72:73], s[62:63]
	s_cbranch_execz .LBB0_469
	s_cmp_lt_i32 s68, 0x10000
	s_movk_i32 s44, 0xffa
	s_cselect_b32 s44, s44, 0x7fa
	s_and_b32 s44, s44, s68
	s_lshl_b32 s44, s44, 7
	v_lshl_add_u64 v[78:79], v[68:69], 0, s[44:45]
	v_lshl_add_u64 v[108:109], v[70:71], 0, s[44:45]
	ds_read_b128 v[96:99], v96 offset:128
	global_load_dwordx4 v[104:107], v[78:79], off
	s_nop 0
	global_load_dwordx4 v[108:111], v[108:109], off
	s_mov_b32 s71, s70
	s_ashr_i32 s69, s68, 31
	s_lshl_b64 s[68:69], s[68:69], 7
	s_waitcnt lgkmcnt(0)
	v_pk_mul_f32 v[78:79], s[70:71], v[96:97]
	s_waitcnt vmcnt(0)
	v_pk_mul_f32 v[96:97], v[78:79], v[108:109]
	s_nop 0
	v_pk_fma_f32 v[96:97], v[76:77], v[104:105], v[96:97] neg_lo:[0,0,1] neg_hi:[0,0,1]
	v_pk_mul_f32 v[76:77], v[76:77], v[108:109]
	v_cvt_pk_bf16_f32 v96, v96, v97
	v_pk_fma_f32 v[76:77], v[78:79], v[104:105], v[76:77]
	v_pk_mul_f32 v[78:79], s[70:71], v[98:99]
	v_cvt_pk_bf16_f32 v76, v76, v77
	v_pk_mul_f32 v[98:99], v[78:79], v[110:111]
	s_nop 0
	v_pk_fma_f32 v[98:99], v[74:75], v[106:107], v[98:99] neg_lo:[0,0,1] neg_hi:[0,0,1]
	v_pk_mul_f32 v[74:75], v[74:75], v[110:111]
	v_cvt_pk_bf16_f32 v97, v98, v99
	v_pk_fma_f32 v[74:75], v[78:79], v[106:107], v[74:75]
	s_nop 0
	v_cvt_pk_bf16_f32 v77, v74, v75
	v_lshl_add_u64 v[74:75], v[72:73], 0, s[68:69]
	global_store_dwordx2 v[74:75], v[96:97], off
	global_store_dwordx2 v[74:75], v[76:77], off offset:64
.LBB0_469:
	s_or_b64 exec, exec, s[72:73]
	s_or_b32 s44, s84, 3
	s_or_b32 s68, s44, s82
	s_mulk_i32 s68, 0x410
	v_add_u32_e32 v96, s68, v80
	ds_read_b128 v[76:79], v96
	v_readlane_b32 s70, v91, s44
	s_or_b32 s68, s44, s83
	s_waitcnt lgkmcnt(0)
	v_pk_mul_f32 v[76:77], s[70:71], v[76:77] op_sel_hi:[0,1]
	v_pk_mul_f32 v[74:75], s[70:71], v[78:79] op_sel_hi:[0,1]
	v_cvt_pk_bf16_f32 v78, v76, v77
	v_cvt_pk_bf16_f32 v79, v74, v75
	s_and_saveexec_b64 s[72:73], s[4:5]
	s_xor_b64 s[72:73], exec, s[72:73]
	s_cbranch_execz .LBB0_473
	s_and_saveexec_b64 s[74:75], s[6:7]
	s_cbranch_execz .LBB0_472
	s_ashr_i32 s69, s68, 31
	s_lshl_b64 s[86:87], s[68:69], 9
	v_lshl_add_u64 v[98:99], v[64:65], 0, s[86:87]
	v_add_co_u32_e32 v98, vcc, 0x2755e000, v98
	s_nop 1
	v_addc_co_u32_e32 v99, vcc, 0, v99, vcc
	global_store_dwordx2 v[98:99], v[78:79], off offset:2816

; template <int EPI, int TS, bool VT>
; DEVI void gemm_epilogue(const Params& p, char* smem, f32x4 (&acc)[2][2][4][2], int m0, int n0, float scale, const float* ssin,
;                         float* ssout, u16* xbout, int wid, int lane, int wr, int wc, int fr, int fq) {
;     ...
;           } else if constexpr (EPI == E_F32) {
;             const float4 a = *(const float4*)(Tr + 4 * lane);
;             const int col = n0 + 4 * lane;
;             const float v0 = a.x * rs, v1 = a.y * rs, v2 = a.z * rs, v3 = a.w * rs;
;             const float sq = v0 * v0 + v1 * v1 + v2 * v2 + v3 * v3;
;             uint2 o;
;             o.x = pack2(v0, v1);
;             o.y = pack2(v2, v3);
;             if (col < 384) *(uint2*)((u16*)(wsb + OFF_CQN) + (size_t)grow * 384 + col) = o;
;             else if (col < 640) *(uint2*)((u16*)(wsb + OFF_CKVN) + (size_t)grow * 256 + (col - 384)) = o;
;     ...
;             if (n0 == 512 && lane >= 32 && lane < 40) {
;               const int i0r = 4 * (lane - 32);
;               const float4 b4 = *(const float4*)(Tr + 160 + i0r);
;               const int pos = tok_pos(grow);
;               const float4 c4 = *(const float4*)((const float*)(wsb + OFF_COS) + pos * 32 + i0r);
;               const float4 s4 = *(const float4*)((const float*)(wsb + OFF_SIN) + pos * 32 + i0r);
;               const float x1[4] = {v0, v1, v2, v3};
;               const float x2[4] = {b4.x * rs, b4.y * rs, b4.z * rs, b4.w * rs};
;               const float cc[4] = {c4.x, c4.y, c4.z, c4.w}, sn[4] = {s4.x, s4.y, s4.z, s4.w};
;               uint2 o1, o2;
;               o1.x = pack2(x1[0] * cc[0] - x2[0] * sn[0], x1[1] * cc[1] - x2[1] * sn[1]);
;               o1.y = pack2(x1[2] * cc[2] - x2[2] * sn[2], x1[3] * cc[3] - x2[3] * sn[3]);
;               o2.x = pack2(x2[0] * cc[0] + x1[0] * sn[0], x2[1] * cc[1] + x1[1] * sn[1]);
;               o2.y = pack2(x2[2] * cc[2] + x1[2] * sn[2], x2[3] * cc[3] + x1[3] * sn[3]);
;               u16* kr = (u16*)(wsb + OFF_KRM) + (size_t)grow * 64;
;               *(uint2*)(kr + i0r) = o1;
;               *(uint2*)(kr + 32 + i0r) = o2;
;             }
.LBB0_483:
	s_and_saveexec_b64 s[72:73], s[62:63]
	s_cbranch_execz .LBB0_485
	s_cmp_lt_i32 s68, 0x10000
	s_movk_i32 s44, 0xffb
	s_cselect_b32 s44, s44, 0x7fb
	s_and_b32 s44, s44, s68
	s_lshl_b32 s44, s44, 7
	v_lshl_add_u64 v[78:79], v[68:69], 0, s[44:45]
	v_lshl_add_u64 v[108:109], v[70:71], 0, s[44:45]
	ds_read_b128 v[96:99], v96 offset:128
	global_load_dwordx4 v[104:107], v[78:79], off
	s_nop 0
	global_load_dwordx4 v[108:111], v[108:109], off
	s_mov_b32 s71, s70
	s_ashr_i32 s69, s68, 31
	s_lshl_b64 s[68:69], s[68:69], 7
	s_waitcnt lgkmcnt(0)
	v_pk_mul_f32 v[78:79], s[70:71], v[96:97]
	s_waitcnt vmcnt(0)
	v_pk_mul_f32 v[96:97], v[78:79], v[108:109]
	s_nop 0
	v_pk_fma_f32 v[96:97], v[76:77], v[104:105], v[96:97] neg_lo:[0,0,1] neg_hi:[0,0,1]
	v_pk_mul_f32 v[76:77], v[76:77], v[108:109]
	v_cvt_pk_bf16_f32 v96, v96, v97
	v_pk_fma_f32 v[76:77], v[78:79], v[104:105], v[76:77]
	v_pk_mul_f32 v[78:79], s[70:71], v[98:99]
	v_cvt_pk_bf16_f32 v76, v76, v77
	v_pk_mul_f32 v[98:99], v[78:79], v[110:111]
	s_nop 0
	v_pk_fma_f32 v[98:99], v[74:75], v[106:107], v[98:99] neg_lo:[0,0,1] neg_hi:[0,0,1]
	v_pk_mul_f32 v[74:75], v[74:75], v[110:111]
	v_cvt_pk_bf16_f32 v97, v98, v99
	v_pk_fma_f32 v[74:75], v[78:79], v[106:107], v[74:75]
	s_nop 0
	v_cvt_pk_bf16_f32 v77, v74, v75
	v_lshl_add_u64 v[74:75], v[72:73], 0, s[68:69]
	global_store_dwordx2 v[74:75], v[96:97], off
	global_store_dwordx2 v[74:75], v[76:77], off offset:64
.LBB0_485:
	s_or_b64 exec, exec, s[72:73]
	s_or_b32 s44, s84, 4
	s_or_b32 s68, s44, s82
	s_mulk_i32 s68, 0x410
	v_add_u32_e32 v96, s68, v80
	ds_read_b128 v[76:79], v96
	v_readlane_b32 s70, v91, s44
	s_or_b32 s68, s44, s83
	s_waitcnt lgkmcnt(0)
	v_pk_mul_f32 v[76:77], s[70:71], v[76:77] op_sel_hi:[0,1]
	v_pk_mul_f32 v[74:75], s[70:71], v[78:79] op_sel_hi:[0,1]
	v_cvt_pk_bf16_f32 v78, v76, v77
	v_cvt_pk_bf16_f32 v79, v74, v75
	s_and_saveexec_b64 s[72:73], s[4:5]
	s_xor_b64 s[72:73], exec, s[72:73]
	s_cbranch_execz .LBB0_489
	s_and_saveexec_b64 s[74:75], s[6:7]
	s_cbranch_execz .LBB0_488
	s_ashr_i32 s69, s68, 31
	s_lshl_b64 s[86:87], s[68:69], 9
	v_lshl_add_u64 v[98:99], v[64:65], 0, s[86:87]
	v_add_co_u32_e32 v98, vcc, 0x2755e000, v98
	s_nop 1
	v_addc_co_u32_e32 v99, vcc, 0, v99, vcc
	global_store_dwordx2 v[98:99], v[78:79], off offset:2816

; template <int EPI, int TS, bool VT>
; DEVI void gemm_epilogue(const Params& p, char* smem, f32x4 (&acc)[2][2][4][2], int m0, int n0, float scale, const float* ssin,
;                         float* ssout, u16* xbout, int wid, int lane, int wr, int wc, int fr, int fq) {
;     ...
;           } else if constexpr (EPI == E_F32) {
;             const float4 a = *(const float4*)(Tr + 4 * lane);
;             const int col = n0 + 4 * lane;
;             const float v0 = a.x * rs, v1 = a.y * rs, v2 = a.z * rs, v3 = a.w * rs;
;             const float sq = v0 * v0 + v1 * v1 + v2 * v2 + v3 * v3;
;             uint2 o;
;             o.x = pack2(v0, v1);
;             o.y = pack2(v2, v3);
;             if (col < 384) *(uint2*)((u16*)(wsb + OFF_CQN) + (size_t)grow * 384 + col) = o;
;             else if (col < 640) *(uint2*)((u16*)(wsb + OFF_CKVN) + (size_t)grow * 256 + (col - 384)) = o;
;     ...
;             if (n0 == 512 && lane >= 32 && lane < 40) {
;               const int i0r = 4 * (lane - 32);
;               const float4 b4 = *(const float4*)(Tr + 160 + i0r);
;               const int pos = tok_pos(grow);
;               const float4 c4 = *(const float4*)((const float*)(wsb + OFF_COS) + pos * 32 + i0r);
;               const float4 s4 = *(const float4*)((const float*)(wsb + OFF_SIN) + pos * 32 + i0r);
;               const float x1[4] = {v0, v1, v2, v3};
;               const float x2[4] = {b4.x * rs, b4.y * rs, b4.z * rs, b4.w * rs};
;               const float cc[4] = {c4.x, c4.y, c4.z, c4.w}, sn[4] = {s4.x, s4.y, s4.z, s4.w};
;               uint2 o1, o2;
;               o1.x = pack2(x1[0] * cc[0] - x2[0] * sn[0], x1[1] * cc[1] - x2[1] * sn[1]);
;               o1.y = pack2(x1[2] * cc[2] - x2[2] * sn[2], x1[3] * cc[3] - x2[3] * sn[3]);
;               o2.x = pack2(x2[0] * cc[0] + x1[0] * sn[0], x2[1] * cc[1] + x1[1] * sn[1]);
;               o2.y = pack2(x2[2] * cc[2] + x1[2] * sn[2], x2[3] * cc[3] + x1[3] * sn[3]);
;               u16* kr = (u16*)(wsb + OFF_KRM) + (size_t)grow * 64;
;               *(uint2*)(kr + i0r) = o1;
;               *(uint2*)(kr + 32 + i0r) = o2;
;             }
.LBB0_499:
	s_and_saveexec_b64 s[72:73], s[62:63]
	s_cbranch_execz .LBB0_501
	s_cmp_lt_i32 s68, 0x10000
	s_movk_i32 s44, 0xffc
	s_cselect_b32 s44, s44, 0x7fc
	s_and_b32 s44, s44, s68
	s_lshl_b32 s44, s44, 7
	v_lshl_add_u64 v[78:79], v[68:69], 0, s[44:45]
	v_lshl_add_u64 v[108:109], v[70:71], 0, s[44:45]
	ds_read_b128 v[96:99], v96 offset:128
	global_load_dwordx4 v[104:107], v[78:79], off
	s_nop 0
	global_load_dwordx4 v[108:111], v[108:109], off
	s_mov_b32 s71, s70
	s_ashr_i32 s69, s68, 31
	s_lshl_b64 s[68:69], s[68:69], 7
	s_waitcnt lgkmcnt(0)
	v_pk_mul_f32 v[78:79], s[70:71], v[96:97]
	s_waitcnt vmcnt(0)
	v_pk_mul_f32 v[96:97], v[78:79], v[108:109]
	s_nop 0
	v_pk_fma_f32 v[96:97], v[76:77], v[104:105], v[96:97] neg_lo:[0,0,1] neg_hi:[0,0,1]
	v_pk_mul_f32 v[76:77], v[76:77], v[108:109]
	v_cvt_pk_bf16_f32 v96, v96, v97
	v_pk_fma_f32 v[76:77], v[78:79], v[104:105], v[76:77]
	v_pk_mul_f32 v[78:79], s[70:71], v[98:99]
	v_cvt_pk_bf16_f32 v76, v76, v77
	v_pk_mul_f32 v[98:99], v[78:79], v[110:111]
	s_nop 0
	v_pk_fma_f32 v[98:99], v[74:75], v[106:107], v[98:99] neg_lo:[0,0,1] neg_hi:[0,0,1]
	v_pk_mul_f32 v[74:75], v[74:75], v[110:111]
	v_cvt_pk_bf16_f32 v97, v98, v99
	v_pk_fma_f32 v[74:75], v[78:79], v[106:107], v[74:75]
	s_nop 0
	v_cvt_pk_bf16_f32 v77, v74, v75
	v_lshl_add_u64 v[74:75], v[72:73], 0, s[68:69]
	global_store_dwordx2 v[74:75], v[96:97], off
	global_store_dwordx2 v[74:75], v[76:77], off offset:64
.LBB0_501:
	s_or_b64 exec, exec, s[72:73]
	s_or_b32 s44, s84, 5
	s_or_b32 s68, s44, s82
	s_mulk_i32 s68, 0x410
	v_add_u32_e32 v96, s68, v80
	ds_read_b128 v[76:79], v96
	v_readlane_b32 s70, v91, s44
	s_or_b32 s68, s44, s83
	s_waitcnt lgkmcnt(0)
	v_pk_mul_f32 v[76:77], s[70:71], v[76:77] op_sel_hi:[0,1]
	v_pk_mul_f32 v[74:75], s[70:71], v[78:79] op_sel_hi:[0,1]
	v_cvt_pk_bf16_f32 v78, v76, v77
	v_cvt_pk_bf16_f32 v79, v74, v75
	s_and_saveexec_b64 s[72:73], s[4:5]
	s_xor_b64 s[72:73], exec, s[72:73]
	s_cbranch_execz .LBB0_505
	s_and_saveexec_b64 s[74:75], s[6:7]
	s_cbranch_execz .LBB0_504
	s_ashr_i32 s69, s68, 31
	s_lshl_b64 s[86:87], s[68:69], 9
	v_lshl_add_u64 v[98:99], v[64:65], 0, s[86:87]
	v_add_co_u32_e32 v98, vcc, 0x2755e000, v98
	s_nop 1
	v_addc_co_u32_e32 v99, vcc, 0, v99, vcc
	global_store_dwordx2 v[98:99], v[78:79], off offset:2816

; template <int EPI, int TS, bool VT>
; DEVI void gemm_epilogue(const Params& p, char* smem, f32x4 (&acc)[2][2][4][2], int m0, int n0, float scale, const float* ssin,
;                         float* ssout, u16* xbout, int wid, int lane, int wr, int wc, int fr, int fq) {
;     ...
;           } else if constexpr (EPI == E_F32) {
;             const float4 a = *(const float4*)(Tr + 4 * lane);
;             const int col = n0 + 4 * lane;
;             const float v0 = a.x * rs, v1 = a.y * rs, v2 = a.z * rs, v3 = a.w * rs;
;             const float sq = v0 * v0 + v1 * v1 + v2 * v2 + v3 * v3;
;             uint2 o;
;             o.x = pack2(v0, v1);
;             o.y = pack2(v2, v3);
;             if (col < 384) *(uint2*)((u16*)(wsb + OFF_CQN) + (size_t)grow * 384 + col) = o;
;             else if (col < 640) *(uint2*)((u16*)(wsb + OFF_CKVN) + (size_t)grow * 256 + (col - 384)) = o;
;     ...
;             if (n0 == 512 && lane >= 32 && lane < 40) {
;               const int i0r = 4 * (lane - 32);
;               const float4 b4 = *(const float4*)(Tr + 160 + i0r);
;               const int pos = tok_pos(grow);
;               const float4 c4 = *(const float4*)((const float*)(wsb + OFF_COS) + pos * 32 + i0r);
;               const float4 s4 = *(const float4*)((const float*)(wsb + OFF_SIN) + pos * 32 + i0r);
;               const float x1[4] = {v0, v1, v2, v3};
;               const float x2[4] = {b4.x * rs, b4.y * rs, b4.z * rs, b4.w * rs};
;               const float cc[4] = {c4.x, c4.y, c4.z, c4.w}, sn[4] = {s4.x, s4.y, s4.z, s4.w};
;               uint2 o1, o2;
;               o1.x = pack2(x1[0] * cc[0] - x2[0] * sn[0], x1[1] * cc[1] - x2[1] * sn[1]);
;               o1.y = pack2(x1[2] * cc[2] - x2[2] * sn[2], x1[3] * cc[3] - x2[3] * sn[3]);
;               o2.x = pack2(x2[0] * cc[0] + x1[0] * sn[0], x2[1] * cc[1] + x1[1] * sn[1]);
;               o2.y = pack2(x2[2] * cc[2] + x1[2] * sn[2], x2[3] * cc[3] + x1[3] * sn[3]);
;               u16* kr = (u16*)(wsb + OFF_KRM) + (size_t)grow * 64;
;               *(uint2*)(kr + i0r) = o1;
;               *(uint2*)(kr + 32 + i0r) = o2;
;             }
.LBB0_515:
	s_and_saveexec_b64 s[72:73], s[62:63]
	s_cbranch_execz .LBB0_517
	s_cmp_lt_i32 s68, 0x10000
	s_movk_i32 s44, 0xffd
	s_cselect_b32 s44, s44, 0x7fd
	s_and_b32 s44, s44, s68
	s_lshl_b32 s44, s44, 7
	v_lshl_add_u64 v[78:79], v[68:69], 0, s[44:45]
	v_lshl_add_u64 v[108:109], v[70:71], 0, s[44:45]
	ds_read_b128 v[96:99], v96 offset:128
	global_load_dwordx4 v[104:107], v[78:79], off
	s_nop 0
	global_load_dwordx4 v[108:111], v[108:109], off
	s_mov_b32 s71, s70
	s_ashr_i32 s69, s68, 31
	s_lshl_b64 s[68:69], s[68:69], 7
	s_waitcnt lgkmcnt(0)
	v_pk_mul_f32 v[78:79], s[70:71], v[96:97]
	s_waitcnt vmcnt(0)
	v_pk_mul_f32 v[96:97], v[78:79], v[108:109]
	s_nop 0
	v_pk_fma_f32 v[96:97], v[76:77], v[104:105], v[96:97] neg_lo:[0,0,1] neg_hi:[0,0,1]
	v_pk_mul_f32 v[76:77], v[76:77], v[108:109]
	v_cvt_pk_bf16_f32 v96, v96, v97
	v_pk_fma_f32 v[76:77], v[78:79], v[104:105], v[76:77]
	v_pk_mul_f32 v[78:79], s[70:71], v[98:99]
	v_cvt_pk_bf16_f32 v76, v76, v77
	v_pk_mul_f32 v[98:99], v[78:79], v[110:111]
	s_nop 0
	v_pk_fma_f32 v[98:99], v[74:75], v[106:107], v[98:99] neg_lo:[0,0,1] neg_hi:[0,0,1]
	v_pk_mul_f32 v[74:75], v[74:75], v[110:111]
	v_cvt_pk_bf16_f32 v97, v98, v99
	v_pk_fma_f32 v[74:75], v[78:79], v[106:107], v[74:75]
	s_nop 0
	v_cvt_pk_bf16_f32 v77, v74, v75
	v_lshl_add_u64 v[74:75], v[72:73], 0, s[68:69]
	global_store_dwordx2 v[74:75], v[96:97], off
	global_store_dwordx2 v[74:75], v[76:77], off offset:64
.LBB0_517:
	s_or_b64 exec, exec, s[72:73]
	s_or_b32 s44, s84, 6
	s_or_b32 s68, s44, s82
	s_mulk_i32 s68, 0x410
	v_add_u32_e32 v96, s68, v80
	ds_read_b128 v[76:79], v96
	v_readlane_b32 s70, v91, s44
	s_or_b32 s68, s44, s83
	s_waitcnt lgkmcnt(0)
	v_pk_mul_f32 v[76:77], s[70:71], v[76:77] op_sel_hi:[0,1]
	v_pk_mul_f32 v[74:75], s[70:71], v[78:79] op_sel_hi:[0,1]
	v_cvt_pk_bf16_f32 v78, v76, v77
	v_cvt_pk_bf16_f32 v79, v74, v75
	s_and_saveexec_b64 s[72:73], s[4:5]
	s_xor_b64 s[72:73], exec, s[72:73]
	s_cbranch_execz .LBB0_521
	s_and_saveexec_b64 s[74:75], s[6:7]
	s_cbranch_execz .LBB0_520
	s_ashr_i32 s69, s68, 31
	s_lshl_b64 s[86:87], s[68:69], 9
	v_lshl_add_u64 v[98:99], v[64:65], 0, s[86:87]
	v_add_co_u32_e32 v98, vcc, 0x2755e000, v98
	s_nop 1
	v_addc_co_u32_e32 v99, vcc, 0, v99, vcc
	global_store_dwordx2 v[98:99], v[78:79], off offset:2816

; template <int EPI, int TS, bool VT>
; DEVI void gemm_epilogue(const Params& p, char* smem, f32x4 (&acc)[2][2][4][2], int m0, int n0, float scale, const float* ssin,
;                         float* ssout, u16* xbout, int wid, int lane, int wr, int wc, int fr, int fq) {
;     ...
;           } else if constexpr (EPI == E_F32) {
;             const float4 a = *(const float4*)(Tr + 4 * lane);
;             const int col = n0 + 4 * lane;
;             const float v0 = a.x * rs, v1 = a.y * rs, v2 = a.z * rs, v3 = a.w * rs;
;             const float sq = v0 * v0 + v1 * v1 + v2 * v2 + v3 * v3;
;             uint2 o;
;             o.x = pack2(v0, v1);
;             o.y = pack2(v2, v3);
;             if (col < 384) *(uint2*)((u16*)(wsb + OFF_CQN) + (size_t)grow * 384 + col) = o;
;             else if (col < 640) *(uint2*)((u16*)(wsb + OFF_CKVN) + (size_t)grow * 256 + (col - 384)) = o;
;     ...
;             if (n0 == 512 && lane >= 32 && lane < 40) {
;               const int i0r = 4 * (lane - 32);
;               const float4 b4 = *(const float4*)(Tr + 160 + i0r);
;               const int pos = tok_pos(grow);
;               const float4 c4 = *(const float4*)((const float*)(wsb + OFF_COS) + pos * 32 + i0r);
;               const float4 s4 = *(const float4*)((const float*)(wsb + OFF_SIN) + pos * 32 + i0r);
;               const float x1[4] = {v0, v1, v2, v3};
;               const float x2[4] = {b4.x * rs, b4.y * rs, b4.z * rs, b4.w * rs};
;               const float cc[4] = {c4.x, c4.y, c4.z, c4.w}, sn[4] = {s4.x, s4.y, s4.z, s4.w};
;               uint2 o1, o2;
;               o1.x = pack2(x1[0] * cc[0] - x2[0] * sn[0], x1[1] * cc[1] - x2[1] * sn[1]);
;               o1.y = pack2(x1[2] * cc[2] - x2[2] * sn[2], x1[3] * cc[3] - x2[3] * sn[3]);
;               o2.x = pack2(x2[0] * cc[0] + x1[0] * sn[0], x2[1] * cc[1] + x1[1] * sn[1]);
;               o2.y = pack2(x2[2] * cc[2] + x1[2] * sn[2], x2[3] * cc[3] + x1[3] * sn[3]);
;               u16* kr = (u16*)(wsb + OFF_KRM) + (size_t)grow * 64;
;               *(uint2*)(kr + i0r) = o1;
;               *(uint2*)(kr + 32 + i0r) = o2;
;             }
.LBB0_531:
	s_and_saveexec_b64 s[72:73], s[62:63]
	s_cbranch_execz .LBB0_533
	s_cmp_lt_i32 s68, 0x10000
	s_movk_i32 s44, 0xffe
	s_cselect_b32 s44, s44, 0x7fe
	s_and_b32 s44, s44, s68
	s_lshl_b32 s44, s44, 7
	v_lshl_add_u64 v[78:79], v[68:69], 0, s[44:45]
	v_lshl_add_u64 v[108:109], v[70:71], 0, s[44:45]
	ds_read_b128 v[96:99], v96 offset:128
	global_load_dwordx4 v[104:107], v[78:79], off
	s_nop 0
	global_load_dwordx4 v[108:111], v[108:109], off
	s_mov_b32 s71, s70
	s_ashr_i32 s69, s68, 31
	s_lshl_b64 s[68:69], s[68:69], 7
	s_waitcnt lgkmcnt(0)
	v_pk_mul_f32 v[78:79], s[70:71], v[96:97]
	s_waitcnt vmcnt(0)
	v_pk_mul_f32 v[96:97], v[78:79], v[108:109]
	s_nop 0
	v_pk_fma_f32 v[96:97], v[76:77], v[104:105], v[96:97] neg_lo:[0,0,1] neg_hi:[0,0,1]
	v_pk_mul_f32 v[76:77], v[76:77], v[108:109]
	v_cvt_pk_bf16_f32 v96, v96, v97
	v_pk_fma_f32 v[76:77], v[78:79], v[104:105], v[76:77]
	v_pk_mul_f32 v[78:79], s[70:71], v[98:99]
	v_cvt_pk_bf16_f32 v76, v76, v77
	v_pk_mul_f32 v[98:99], v[78:79], v[110:111]
	s_nop 0
	v_pk_fma_f32 v[98:99], v[74:75], v[106:107], v[98:99] neg_lo:[0,0,1] neg_hi:[0,0,1]
	v_pk_mul_f32 v[74:75], v[74:75], v[110:111]
	v_cvt_pk_bf16_f32 v97, v98, v99
	v_pk_fma_f32 v[74:75], v[78:79], v[106:107], v[74:75]
	s_nop 0
	v_cvt_pk_bf16_f32 v77, v74, v75
	v_lshl_add_u64 v[74:75], v[72:73], 0, s[68:69]
	global_store_dwordx2 v[74:75], v[96:97], off
	global_store_dwordx2 v[74:75], v[76:77], off offset:64
.LBB0_533:
	s_or_b64 exec, exec, s[72:73]
	s_or_b32 s44, s84, 7
	s_or_b32 s68, s44, s82
	s_mulk_i32 s68, 0x410
	v_add_u32_e32 v96, s68, v80
	ds_read_b128 v[76:79], v96
	v_readlane_b32 s70, v91, s44
	s_or_b32 s68, s44, s83
	s_waitcnt lgkmcnt(0)
	v_pk_mul_f32 v[76:77], s[70:71], v[76:77] op_sel_hi:[0,1]
	v_pk_mul_f32 v[74:75], s[70:71], v[78:79] op_sel_hi:[0,1]
	v_cvt_pk_bf16_f32 v78, v76, v77
	v_cvt_pk_bf16_f32 v79, v74, v75
	s_and_saveexec_b64 s[72:73], s[4:5]
	s_xor_b64 s[72:73], exec, s[72:73]
	s_cbranch_execz .LBB0_537
	s_and_saveexec_b64 s[74:75], s[6:7]
	s_cbranch_execz .LBB0_536
	s_ashr_i32 s69, s68, 31
	s_lshl_b64 s[84:85], s[68:69], 9
	v_lshl_add_u64 v[98:99], v[64:65], 0, s[84:85]
	v_add_co_u32_e32 v98, vcc, 0x2755e000, v98
	s_nop 1
	v_addc_co_u32_e32 v99, vcc, 0, v99, vcc
	global_store_dwordx2 v[98:99], v[78:79], off offset:2816

; template <int EPI, int TS, bool VT>
; DEVI void gemm_epilogue(const Params& p, char* smem, f32x4 (&acc)[2][2][4][2], int m0, int n0, float scale, const float* ssin,
;                         float* ssout, u16* xbout, int wid, int lane, int wr, int wc, int fr, int fq) {
;     ...
;             const float sq = v0 * v0 + v1 * v1 + v2 * v2 + v3 * v3;
;             uint2 o;
;             o.x = pack2(v0, v1);
;             o.y = pack2(v2, v3);
;             if (col < 384) *(uint2*)((u16*)(wsb + OFF_CQN) + (size_t)grow * 384 + col) = o;
;             else if (col < 640) *(uint2*)((u16*)(wsb + OFF_CKVN) + (size_t)grow * 256 + (col - 384)) = o;
;             if (n0 < 512) {
;               const float sqq = wsum(col < 384 ? sq : 0.f, lane);
;               if (lane == 0) atomicAdd(ssout + grow, sqq);
;             }
.LBB0_539:
	s_or_b64 exec, exec, s[72:73]
	v_pk_mul_f32 v[78:79], v[76:77], v[76:77]
	v_pk_mul_f32 v[98:99], v[74:75], v[74:75]
	v_add_f32_e32 v78, v78, v79
	v_add_f32_e32 v78, v78, v98
	s_and_b64 vcc, exec, s[12:13]
	v_add_f32_e32 v78, v78, v99
	s_cbranch_vccnz .LBB0_543
	v_cndmask_b32_e64 v79, 0, v78, s[0:1]
	s_nop 1
	v_add_f32_dpp v79, v79, v79 row_ror:8 row_mask:0xf bank_mask:0xf bound_ctrl:1
	s_nop 1
	v_add_f32_dpp v79, v79, v79 row_ror:4 row_mask:0xf bank_mask:0xf bound_ctrl:1
	s_nop 1
	v_add_f32_dpp v79, v79, v79 row_ror:2 row_mask:0xf bank_mask:0xf bound_ctrl:1
	s_nop 1
	v_add_f32_dpp v79, v79, v79 row_ror:1 row_mask:0xf bank_mask:0xf bound_ctrl:1
	s_nop 0
	v_readlane_b32 s44, v79, 0
	v_readlane_b32 s75, v79, 16
	v_readlane_b32 s71, v79, 32
	v_readlane_b32 s74, v79, 48
	s_and_saveexec_b64 s[72:73], s[8:9]
	s_cbranch_execz .LBB0_542
	s_ashr_i32 s69, s68, 31
	s_lshl_b64 s[84:85], s[68:69], 2
	v_mov_b32_e32 v79, s75
	s_add_u32 s84, s18, s84
	v_add_f32_e32 v79, s44, v79
	s_addc_u32 s85, s19, s85
	v_add_f32_e32 v79, s71, v79
	v_add_f32_e32 v79, s74, v79
	v_mov_b64_e32 v[98:99], s[84:85]
	global_atomic_add_f32 v[98:99], v79, off

; template <int EPI, int TS, bool VT>
; DEVI void gemm_epilogue(const Params& p, char* smem, f32x4 (&acc)[2][2][4][2], int m0, int n0, float scale, const float* ssin,
;                         float* ssout, u16* xbout, int wid, int lane, int wr, int wc, int fr, int fq) {
;     ...
;             if (n0 >= 256) {
;               const float sqk = wsum((col >= 384 && col < 640) ? sq : 0.f, lane);
;               if (lane == 0) atomicAdd(ssout + MTOK + grow, sqk);
;             }
.LBB0_543:
	s_and_b64 vcc, exec, s[14:15]
	s_cbranch_vccnz .LBB0_547
	v_cndmask_b32_e64 v78, 0, v78, s[10:11]
	s_nop 1
	v_add_f32_dpp v78, v78, v78 row_ror:8 row_mask:0xf bank_mask:0xf bound_ctrl:1
	s_nop 1
	v_add_f32_dpp v78, v78, v78 row_ror:4 row_mask:0xf bank_mask:0xf bound_ctrl:1
	s_nop 1
	v_add_f32_dpp v78, v78, v78 row_ror:2 row_mask:0xf bank_mask:0xf bound_ctrl:1
	s_nop 1
	v_add_f32_dpp v78, v78, v78 row_ror:1 row_mask:0xf bank_mask:0xf bound_ctrl:1
	s_nop 0
	v_readlane_b32 s44, v78, 0
	v_readlane_b32 s75, v78, 16
	v_readlane_b32 s71, v78, 32
	v_readlane_b32 s74, v78, 48
	s_and_saveexec_b64 s[72:73], s[8:9]
	s_cbranch_execz .LBB0_546
	s_ashr_i32 s69, s68, 31
	s_lshl_b64 s[84:85], s[68:69], 2
	v_mov_b32_e32 v78, s75
	s_add_u32 s84, s78, s84
	v_add_f32_e32 v78, s44, v78
	s_addc_u32 s85, s79, s85
	v_add_f32_e32 v78, s71, v78
	v_add_f32_e32 v97, s74, v78
	v_mov_b64_e32 v[78:79], s[84:85]
	global_atomic_add_f32 v[78:79], v97, off

; template <int EPI, int TS, bool VT>
; DEVI void gemm_epilogue(const Params& p, char* smem, f32x4 (&acc)[2][2][4][2], int m0, int n0, float scale, const float* ssin,
;                         float* ssout, u16* xbout, int wid, int lane, int wr, int wc, int fr, int fq) {
;     ...
;       float* tw = T + (wr * 64 + fq * 4) * TS + wc * 32 + fr;
; #pragma unroll
;       for (int m = 0; m < 4; ++m)
; #pragma unroll
;         for (int j = 0; j < 4; ++j)
; #pragma unroll
;           for (int v = 0; v < 4; ++v) tw[(m * 16 + j) * TS + (v >> 1) * 128 + (v & 1) * 16] = acc[ai][v >> 1][m][v & 1][j];
;     }
;     __syncthreads();
;     const int r0 = wid * 16;
;     const int g0 = m0 + ai * 128 + r0;
;     if constexpr (!VT) {
;       float rsv = 1.f;
;       if constexpr (EPI == E_PLEGATE || EPI == E_F32 || EPI == E_SWIGLU || EPI == E_GLAIN)
;         rsv = rsqrtf(ssin[g0 + (lane & 15)] * (1.f / 1024.f) + EPS);
;     ...
;             if (n0 == 512 && lane >= 32 && lane < 40) {
;               const int i0r = 4 * (lane - 32);
;               const float4 b4 = *(const float4*)(Tr + 160 + i0r);
;               const int pos = tok_pos(grow);
;               const float4 c4 = *(const float4*)((const float*)(wsb + OFF_COS) + pos * 32 + i0r);
;               const float4 s4 = *(const float4*)((const float*)(wsb + OFF_SIN) + pos * 32 + i0r);
;               const float x1[4] = {v0, v1, v2, v3};
;               const float x2[4] = {b4.x * rs, b4.y * rs, b4.z * rs, b4.w * rs};
;               const float cc[4] = {c4.x, c4.y, c4.z, c4.w}, sn[4] = {s4.x, s4.y, s4.z, s4.w};
;               uint2 o1, o2;
;               o1.x = pack2(x1[0] * cc[0] - x2[0] * sn[0], x1[1] * cc[1] - x2[1] * sn[1]);
;               o1.y = pack2(x1[2] * cc[2] - x2[2] * sn[2], x1[3] * cc[3] - x2[3] * sn[3]);
;               o2.x = pack2(x2[0] * cc[0] + x1[0] * sn[0], x2[1] * cc[1] + x1[1] * sn[1]);
;               o2.y = pack2(x2[2] * cc[2] + x1[2] * sn[2], x2[3] * cc[3] + x1[3] * sn[3]);
;               u16* kr = (u16*)(wsb + OFF_KRM) + (size_t)grow * 64;
;               *(uint2*)(kr + i0r) = o1;
;               *(uint2*)(kr + 32 + i0r) = o2;
;             }
.LBB0_547:
	s_and_saveexec_b64 s[72:73], s[62:63]
	s_cbranch_execz .LBB0_420
	s_cmp_lt_i32 s68, 0x10000
	s_movk_i32 s44, 0xfff
	s_cselect_b32 s44, s44, 0x7ff
	s_and_b32 s44, s44, s68
	s_lshl_b32 s44, s44, 7
	v_lshl_add_u64 v[78:79], v[68:69], 0, s[44:45]
	v_lshl_add_u64 v[108:109], v[70:71], 0, s[44:45]
	ds_read_b128 v[96:99], v96 offset:128
	global_load_dwordx4 v[104:107], v[78:79], off
	s_nop 0
	global_load_dwordx4 v[108:111], v[108:109], off
	s_mov_b32 s71, s70
	s_ashr_i32 s69, s68, 31
	s_lshl_b64 s[68:69], s[68:69], 7
	s_waitcnt lgkmcnt(0)
	v_pk_mul_f32 v[78:79], s[70:71], v[96:97]
	s_waitcnt vmcnt(0)
	v_pk_mul_f32 v[96:97], v[78:79], v[108:109]
	s_nop 0
	v_pk_fma_f32 v[96:97], v[76:77], v[104:105], v[96:97] neg_lo:[0,0,1] neg_hi:[0,0,1]
	v_pk_mul_f32 v[76:77], v[76:77], v[108:109]
	v_cvt_pk_bf16_f32 v96, v96, v97
	v_pk_fma_f32 v[76:77], v[78:79], v[104:105], v[76:77]
	v_pk_mul_f32 v[78:79], s[70:71], v[98:99]
	v_cvt_pk_bf16_f32 v76, v76, v77
	v_pk_mul_f32 v[98:99], v[78:79], v[110:111]
	s_nop 0
	v_pk_fma_f32 v[98:99], v[74:75], v[106:107], v[98:99] neg_lo:[0,0,1] neg_hi:[0,0,1]
	v_pk_mul_f32 v[74:75], v[74:75], v[110:111]
	v_cvt_pk_bf16_f32 v97, v98, v99
	v_pk_fma_f32 v[74:75], v[78:79], v[106:107], v[74:75]
	s_nop 0
	v_cvt_pk_bf16_f32 v77, v74, v75
	v_lshl_add_u64 v[74:75], v[72:73], 0, s[68:69]
	global_store_dwordx2 v[74:75], v[96:97], off
	global_store_dwordx2 v[74:75], v[76:77], off offset:64
	s_branch .LBB0_420
.LBB0_549:
	s_addk_i32 s83, 0x80
	s_waitcnt lgkmcnt(0)
	s_barrier
	ds_write2_b32 v128, v24, v28 offset1:16
	ds_write2_b32 v128, v56, v60 offset0:128 offset1:144
	ds_write2_b32 v92, v25, v29 offset0:4 offset1:20
	ds_write2_b32 v92, v57, v61 offset0:132 offset1:148
	ds_write2_b32 v93, v26, v30 offset0:8 offset1:24
	ds_write2_b32 v93, v58, v62 offset0:136 offset1:152
	ds_write2_b32 v94, v27, v31 offset0:12 offset1:28
	ds_write2_b32 v94, v59, v63 offset0:140 offset1:156
	ds_write2_b32 v95, v16, v20 offset0:64 offset1:80
	ds_write2_b32 v95, v48, v52 offset0:192 offset1:208
	ds_write2_b32 v84, v17, v21 offset0:68 offset1:84
	ds_write2_b32 v84, v49, v53 offset0:196 offset1:212
	ds_write2_b32 v81, v18, v22 offset0:72 offset1:88
	ds_write2_b32 v81, v50, v54 offset0:200 offset1:216
	ds_write2_b32 v82, v19, v23 offset0:76 offset1:92
	ds_write2_b32 v82, v51, v55 offset0:204 offset1:220
	ds_write2_b32 v83, v8, v12 offset0:128 offset1:144
	ds_write2_b32 v85, v40, v44 offset1:16
	ds_write2_b32 v85, v9, v13 offset0:132 offset1:148
	ds_write2_b32 v86, v41, v45 offset0:4 offset1:20
	ds_write2_b32 v86, v10, v14 offset0:136 offset1:152
	ds_write2_b32 v87, v42, v46 offset0:8 offset1:24
	ds_write2_b32 v87, v11, v15 offset0:140 offset1:156
	ds_write2_b32 v100, v43, v47 offset0:12 offset1:28
	ds_write2_b32 v101, v0, v4 offset0:192 offset1:208
	ds_write2_b32 v102, v32, v36 offset0:64 offset1:80
	ds_write2_b32 v102, v1, v5 offset0:196 offset1:212
	ds_write2_b32 v88, v33, v37 offset0:68 offset1:84
	ds_write2_b32 v88, v2, v6 offset0:200 offset1:216
	ds_write2_b32 v89, v34, v38 offset0:72 offset1:88
	ds_write2_b32 v89, v3, v7 offset0:204 offset1:220
	ds_write2_b32 v90, v35, v39 offset0:76 offset1:92
	v_or_b32_e32 v0, s83, v132
	v_ashrrev_i32_e32 v1, 31, v0
	v_lshl_add_u64 v[0:1], v[0:1], 2, s[16:17]
	s_waitcnt lgkmcnt(0)
	s_barrier
	global_load_dword v0, v[0:1], off
	s_mov_b32 s72, 0
	s_mov_b64 s[34:35], -1
	s_waitcnt vmcnt(0) lgkmcnt(0)
	v_fmamk_f32 v0, v0, 0x3a800000, v150
	v_mul_f32_e32 v1, 0x4b800000, v0
	v_cmp_gt_f32_e32 vcc, s29, v0
	s_nop 1
	v_cndmask_b32_e32 v0, v0, v1, vcc
	v_rsq_f32_e32 v0, v0
	s_nop 0
	v_mul_f32_e32 v1, 0x45800000, v0
	v_cndmask_b32_e32 v6, v0, v1, vcc
	s_branch .LBB0_551

; template <int EPI, int TS, bool VT>
; DEVI void gemm_epilogue(const Params& p, char* smem, f32x4 (&acc)[2][2][4][2], int m0, int n0, float scale, const float* ssin,
;                         float* ssout, u16* xbout, int wid, int lane, int wr, int wc, int fr, int fq) {
;     ...
;           } else if constexpr (EPI == E_F32) {
;             const float4 a = *(const float4*)(Tr + 4 * lane);
;             const int col = n0 + 4 * lane;
;             const float v0 = a.x * rs, v1 = a.y * rs, v2 = a.z * rs, v3 = a.w * rs;
;             const float sq = v0 * v0 + v1 * v1 + v2 * v2 + v3 * v3;
;             uint2 o;
;             o.x = pack2(v0, v1);
;             o.y = pack2(v2, v3);
;             if (col < 384) *(uint2*)((u16*)(wsb + OFF_CQN) + (size_t)grow * 384 + col) = o;
;             else if (col < 640) *(uint2*)((u16*)(wsb + OFF_CKVN) + (size_t)grow * 256 + (col - 384)) = o;
.LBB0_551:
	s_or_b32 s44, s72, s82
	s_mulk_i32 s44, 0x410
	v_add_u32_e32 v7, s44, v80
	ds_read_b128 v[2:5], v7
	v_readlane_b32 s66, v6, s72
	s_or_b32 s64, s72, s83
	s_waitcnt lgkmcnt(0)
	v_pk_mul_f32 v[2:3], s[66:67], v[2:3] op_sel_hi:[0,1]
	v_pk_mul_f32 v[0:1], s[66:67], v[4:5] op_sel_hi:[0,1]
	v_cvt_pk_bf16_f32 v4, v2, v3
	v_cvt_pk_bf16_f32 v5, v0, v1
	s_and_saveexec_b64 s[68:69], s[4:5]
	s_xor_b64 s[68:69], exec, s[68:69]
	s_cbranch_execz .LBB0_555
	s_and_saveexec_b64 s[70:71], s[6:7]
	s_cbranch_execz .LBB0_554
	s_ashr_i32 s65, s64, 31
	s_lshl_b64 s[74:75], s[64:65], 9
	v_lshl_add_u64 v[8:9], v[64:65], 0, s[74:75]
	v_add_co_u32_e32 v8, vcc, 0x2755e000, v8
	s_nop 1
	v_addc_co_u32_e32 v9, vcc, 0, v9, vcc
	global_store_dwordx2 v[8:9], v[4:5], off offset:2816

; template <int EPI, int TS, bool VT>
; DEVI void gemm_epilogue(const Params& p, char* smem, f32x4 (&acc)[2][2][4][2], int m0, int n0, float scale, const float* ssin,
;                         float* ssout, u16* xbout, int wid, int lane, int wr, int wc, int fr, int fq) {
;     ...
;             const float sq = v0 * v0 + v1 * v1 + v2 * v2 + v3 * v3;
;             uint2 o;
;             o.x = pack2(v0, v1);
;             o.y = pack2(v2, v3);
;             if (col < 384) *(uint2*)((u16*)(wsb + OFF_CQN) + (size_t)grow * 384 + col) = o;
;             else if (col < 640) *(uint2*)((u16*)(wsb + OFF_CKVN) + (size_t)grow * 256 + (col - 384)) = o;
;             if (n0 < 512) {
;               const float sqq = wsum(col < 384 ? sq : 0.f, lane);
;               if (lane == 0) atomicAdd(ssout + grow, sqq);
;             }
.LBB0_555:
	s_andn2_saveexec_b64 s[68:69], s[68:69]
	s_cbranch_execz .LBB0_557
	v_mad_i64_i32 v[8:9], s[70:71], s64, v169, v[66:67]
	global_store_dwordx2 v[8:9], v[4:5], off
.LBB0_557:
	s_or_b64 exec, exec, s[68:69]
	v_pk_mul_f32 v[4:5], v[2:3], v[2:3]
	v_pk_mul_f32 v[8:9], v[0:1], v[0:1]
	v_add_f32_e32 v4, v4, v5
	v_add_f32_e32 v4, v4, v8
	s_and_b64 vcc, exec, s[12:13]
	v_add_f32_e32 v4, v4, v9
	s_cbranch_vccnz .LBB0_561
	v_cndmask_b32_e64 v5, 0, v4, s[0:1]
	s_nop 1
	v_add_f32_dpp v5, v5, v5 row_ror:8 row_mask:0xf bank_mask:0xf bound_ctrl:1
	s_nop 1
	v_add_f32_dpp v5, v5, v5 row_ror:4 row_mask:0xf bank_mask:0xf bound_ctrl:1
	s_nop 1
	v_add_f32_dpp v5, v5, v5 row_ror:2 row_mask:0xf bank_mask:0xf bound_ctrl:1
	s_nop 1
	v_add_f32_dpp v5, v5, v5 row_ror:1 row_mask:0xf bank_mask:0xf bound_ctrl:1
	s_nop 0
	v_readlane_b32 s44, v5, 0
	v_readlane_b32 s71, v5, 16
	v_readlane_b32 s67, v5, 32
	v_readlane_b32 s70, v5, 48
	s_and_saveexec_b64 s[68:69], s[8:9]
	s_cbranch_execz .LBB0_560
	s_ashr_i32 s65, s64, 31
	s_lshl_b64 s[74:75], s[64:65], 2
	v_mov_b32_e32 v5, s71
	s_add_u32 s74, s18, s74
	v_add_f32_e32 v5, s44, v5
	s_addc_u32 s75, s19, s75
	v_add_f32_e32 v5, s67, v5
	v_add_f32_e32 v5, s70, v5
	v_mov_b64_e32 v[8:9], s[74:75]
	global_atomic_add_f32 v[8:9], v5, off

; template <int EPI, int TS, bool VT>
; DEVI void gemm_epilogue(const Params& p, char* smem, f32x4 (&acc)[2][2][4][2], int m0, int n0, float scale, const float* ssin,
;                         float* ssout, u16* xbout, int wid, int lane, int wr, int wc, int fr, int fq) {
;     ...
;             if (n0 >= 256) {
;               const float sqk = wsum((col >= 384 && col < 640) ? sq : 0.f, lane);
;               if (lane == 0) atomicAdd(ssout + MTOK + grow, sqk);
;             }
.LBB0_561:
	s_and_b64 vcc, exec, s[14:15]
	s_cbranch_vccnz .LBB0_565
	v_cndmask_b32_e64 v4, 0, v4, s[10:11]
	s_nop 1
	v_add_f32_dpp v4, v4, v4 row_ror:8 row_mask:0xf bank_mask:0xf bound_ctrl:1
	s_nop 1
	v_add_f32_dpp v4, v4, v4 row_ror:4 row_mask:0xf bank_mask:0xf bound_ctrl:1
	s_nop 1
	v_add_f32_dpp v4, v4, v4 row_ror:2 row_mask:0xf bank_mask:0xf bound_ctrl:1
	s_nop 1
	v_add_f32_dpp v4, v4, v4 row_ror:1 row_mask:0xf bank_mask:0xf bound_ctrl:1
	s_nop 0
	v_readlane_b32 s44, v4, 0
	v_readlane_b32 s71, v4, 16
	v_readlane_b32 s67, v4, 32
	v_readlane_b32 s70, v4, 48
	s_and_saveexec_b64 s[68:69], s[8:9]
	s_cbranch_execz .LBB0_564
	s_ashr_i32 s65, s64, 31
	s_lshl_b64 s[74:75], s[64:65], 2
	v_mov_b32_e32 v4, s71
	s_add_u32 s74, s78, s74
	v_add_f32_e32 v4, s44, v4
	s_addc_u32 s75, s79, s75
	v_add_f32_e32 v4, s67, v4
	v_add_f32_e32 v8, s70, v4
	v_mov_b64_e32 v[4:5], s[74:75]
	global_atomic_add_f32 v[4:5], v8, off

; template <int EPI, int TS, bool VT>
; DEVI void gemm_epilogue(const Params& p, char* smem, f32x4 (&acc)[2][2][4][2], int m0, int n0, float scale, const float* ssin,
;                         float* ssout, u16* xbout, int wid, int lane, int wr, int wc, int fr, int fq) {
;     ...
;           } else if constexpr (EPI == E_F32) {
;             const float4 a = *(const float4*)(Tr + 4 * lane);
;             const int col = n0 + 4 * lane;
;             const float v0 = a.x * rs, v1 = a.y * rs, v2 = a.z * rs, v3 = a.w * rs;
;             const float sq = v0 * v0 + v1 * v1 + v2 * v2 + v3 * v3;
;             uint2 o;
;             o.x = pack2(v0, v1);
;             o.y = pack2(v2, v3);
;             if (col < 384) *(uint2*)((u16*)(wsb + OFF_CQN) + (size_t)grow * 384 + col) = o;
;             else if (col < 640) *(uint2*)((u16*)(wsb + OFF_CKVN) + (size_t)grow * 256 + (col - 384)) = o;
;     ...
;             if (n0 == 512 && lane >= 32 && lane < 40) {
;               const int i0r = 4 * (lane - 32);
;               const float4 b4 = *(const float4*)(Tr + 160 + i0r);
;               const int pos = tok_pos(grow);
;               const float4 c4 = *(const float4*)((const float*)(wsb + OFF_COS) + pos * 32 + i0r);
;               const float4 s4 = *(const float4*)((const float*)(wsb + OFF_SIN) + pos * 32 + i0r);
;               const float x1[4] = {v0, v1, v2, v3};
;               const float x2[4] = {b4.x * rs, b4.y * rs, b4.z * rs, b4.w * rs};
;               const float cc[4] = {c4.x, c4.y, c4.z, c4.w}, sn[4] = {s4.x, s4.y, s4.z, s4.w};
;               uint2 o1, o2;
;               o1.x = pack2(x1[0] * cc[0] - x2[0] * sn[0], x1[1] * cc[1] - x2[1] * sn[1]);
;               o1.y = pack2(x1[2] * cc[2] - x2[2] * sn[2], x1[3] * cc[3] - x2[3] * sn[3]);
;               o2.x = pack2(x2[0] * cc[0] + x1[0] * sn[0], x2[1] * cc[1] + x1[1] * sn[1]);
;               o2.y = pack2(x2[2] * cc[2] + x1[2] * sn[2], x2[3] * cc[3] + x1[3] * sn[3]);
;               u16* kr = (u16*)(wsb + OFF_KRM) + (size_t)grow * 64;
;               *(uint2*)(kr + i0r) = o1;
;               *(uint2*)(kr + 32 + i0r) = o2;
;             }
.LBB0_565:
	s_and_saveexec_b64 s[68:69], s[62:63]
	s_cbranch_execz .LBB0_567
	s_cmp_lt_i32 s64, 0x10000
	s_movk_i32 s44, 0xff8
	s_cselect_b32 s44, s44, 0x7f8
	s_and_b32 s44, s44, s64
	s_lshl_b32 s44, s44, 7
	v_lshl_add_u64 v[4:5], v[68:69], 0, s[44:45]
	v_lshl_add_u64 v[16:17], v[70:71], 0, s[44:45]
	ds_read_b128 v[8:11], v7 offset:128
	global_load_dwordx4 v[12:15], v[4:5], off
	s_nop 0
	global_load_dwordx4 v[16:19], v[16:17], off
	s_mov_b32 s67, s66
	s_ashr_i32 s65, s64, 31
	s_lshl_b64 s[64:65], s[64:65], 7
	s_waitcnt lgkmcnt(0)
	v_pk_mul_f32 v[4:5], s[66:67], v[8:9]
	s_waitcnt vmcnt(0)
	v_pk_mul_f32 v[8:9], v[4:5], v[16:17]
	s_nop 0
	v_pk_fma_f32 v[8:9], v[2:3], v[12:13], v[8:9] neg_lo:[0,0,1] neg_hi:[0,0,1]
	v_pk_mul_f32 v[2:3], v[2:3], v[16:17]
	v_cvt_pk_bf16_f32 v8, v8, v9
	v_pk_fma_f32 v[2:3], v[4:5], v[12:13], v[2:3]
	v_pk_mul_f32 v[4:5], s[66:67], v[10:11]
	v_cvt_pk_bf16_f32 v2, v2, v3
	v_pk_mul_f32 v[10:11], v[4:5], v[18:19]
	s_nop 0
	v_pk_fma_f32 v[10:11], v[0:1], v[14:15], v[10:11] neg_lo:[0,0,1] neg_hi:[0,0,1]
	v_pk_mul_f32 v[0:1], v[0:1], v[18:19]
	v_cvt_pk_bf16_f32 v9, v10, v11
	v_pk_fma_f32 v[0:1], v[4:5], v[14:15], v[0:1]
	s_nop 0
	v_cvt_pk_bf16_f32 v3, v0, v1
	v_lshl_add_u64 v[0:1], v[72:73], 0, s[64:65]
	global_store_dwordx2 v[0:1], v[8:9], off
	global_store_dwordx2 v[0:1], v[2:3], off offset:64
.LBB0_567:
	s_or_b64 exec, exec, s[68:69]
	s_or_b32 s44, s72, 1
	s_or_b32 s64, s44, s82
	s_mulk_i32 s64, 0x410
	v_add_u32_e32 v7, s64, v80
	ds_read_b128 v[2:5], v7
	v_readlane_b32 s66, v6, s44
	s_or_b32 s64, s44, s83
	s_waitcnt lgkmcnt(0)
	v_pk_mul_f32 v[2:3], s[66:67], v[2:3] op_sel_hi:[0,1]
	v_pk_mul_f32 v[0:1], s[66:67], v[4:5] op_sel_hi:[0,1]
	v_cvt_pk_bf16_f32 v4, v2, v3
	v_cvt_pk_bf16_f32 v5, v0, v1
	s_and_saveexec_b64 s[68:69], s[4:5]
	s_xor_b64 s[68:69], exec, s[68:69]
	s_cbranch_execz .LBB0_571
	s_and_saveexec_b64 s[70:71], s[6:7]
	s_cbranch_execz .LBB0_570
	s_ashr_i32 s65, s64, 31
	s_lshl_b64 s[74:75], s[64:65], 9
	v_lshl_add_u64 v[8:9], v[64:65], 0, s[74:75]
	v_add_co_u32_e32 v8, vcc, 0x2755e000, v8
	s_nop 1
	v_addc_co_u32_e32 v9, vcc, 0, v9, vcc
	global_store_dwordx2 v[8:9], v[4:5], off offset:2816

; template <int EPI, int TS, bool VT>
; DEVI void gemm_epilogue(const Params& p, char* smem, f32x4 (&acc)[2][2][4][2], int m0, int n0, float scale, const float* ssin,
;                         float* ssout, u16* xbout, int wid, int lane, int wr, int wc, int fr, int fq) {
;     ...
;           } else if constexpr (EPI == E_F32) {
;             const float4 a = *(const float4*)(Tr + 4 * lane);
;             const int col = n0 + 4 * lane;
;             const float v0 = a.x * rs, v1 = a.y * rs, v2 = a.z * rs, v3 = a.w * rs;
;             const float sq = v0 * v0 + v1 * v1 + v2 * v2 + v3 * v3;
;             uint2 o;
;             o.x = pack2(v0, v1);
;             o.y = pack2(v2, v3);
;             if (col < 384) *(uint2*)((u16*)(wsb + OFF_CQN) + (size_t)grow * 384 + col) = o;
;             else if (col < 640) *(uint2*)((u16*)(wsb + OFF_CKVN) + (size_t)grow * 256 + (col - 384)) = o;
;     ...
;             if (n0 == 512 && lane >= 32 && lane < 40) {
;               const int i0r = 4 * (lane - 32);
;               const float4 b4 = *(const float4*)(Tr + 160 + i0r);
;               const int pos = tok_pos(grow);
;               const float4 c4 = *(const float4*)((const float*)(wsb + OFF_COS) + pos * 32 + i0r);
;               const float4 s4 = *(const float4*)((const float*)(wsb + OFF_SIN) + pos * 32 + i0r);
;               const float x1[4] = {v0, v1, v2, v3};
;               const float x2[4] = {b4.x * rs, b4.y * rs, b4.z * rs, b4.w * rs};
;               const float cc[4] = {c4.x, c4.y, c4.z, c4.w}, sn[4] = {s4.x, s4.y, s4.z, s4.w};
;               uint2 o1, o2;
;               o1.x = pack2(x1[0] * cc[0] - x2[0] * sn[0], x1[1] * cc[1] - x2[1] * sn[1]);
;               o1.y = pack2(x1[2] * cc[2] - x2[2] * sn[2], x1[3] * cc[3] - x2[3] * sn[3]);
;               o2.x = pack2(x2[0] * cc[0] + x1[0] * sn[0], x2[1] * cc[1] + x1[1] * sn[1]);
;               o2.y = pack2(x2[2] * cc[2] + x1[2] * sn[2], x2[3] * cc[3] + x1[3] * sn[3]);
;               u16* kr = (u16*)(wsb + OFF_KRM) + (size_t)grow * 64;
;               *(uint2*)(kr + i0r) = o1;
;               *(uint2*)(kr + 32 + i0r) = o2;
;             }
.LBB0_581:
	s_and_saveexec_b64 s[68:69], s[62:63]
	s_cbranch_execz .LBB0_583
	s_cmp_lt_i32 s64, 0x10000
	s_movk_i32 s44, 0xff9
	s_cselect_b32 s44, s44, 0x7f9
	s_and_b32 s44, s44, s64
	s_lshl_b32 s44, s44, 7
	v_lshl_add_u64 v[4:5], v[68:69], 0, s[44:45]
	v_lshl_add_u64 v[16:17], v[70:71], 0, s[44:45]
	ds_read_b128 v[8:11], v7 offset:128
	global_load_dwordx4 v[12:15], v[4:5], off
	s_nop 0
	global_load_dwordx4 v[16:19], v[16:17], off
	s_mov_b32 s67, s66
	s_ashr_i32 s65, s64, 31
	s_lshl_b64 s[64:65], s[64:65], 7
	s_waitcnt lgkmcnt(0)
	v_pk_mul_f32 v[4:5], s[66:67], v[8:9]
	s_waitcnt vmcnt(0)
	v_pk_mul_f32 v[8:9], v[4:5], v[16:17]
	s_nop 0
	v_pk_fma_f32 v[8:9], v[2:3], v[12:13], v[8:9] neg_lo:[0,0,1] neg_hi:[0,0,1]
	v_pk_mul_f32 v[2:3], v[2:3], v[16:17]
	v_cvt_pk_bf16_f32 v8, v8, v9
	v_pk_fma_f32 v[2:3], v[4:5], v[12:13], v[2:3]
	v_pk_mul_f32 v[4:5], s[66:67], v[10:11]
	v_cvt_pk_bf16_f32 v2, v2, v3
	v_pk_mul_f32 v[10:11], v[4:5], v[18:19]
	s_nop 0
	v_pk_fma_f32 v[10:11], v[0:1], v[14:15], v[10:11] neg_lo:[0,0,1] neg_hi:[0,0,1]
	v_pk_mul_f32 v[0:1], v[0:1], v[18:19]
	v_cvt_pk_bf16_f32 v9, v10, v11
	v_pk_fma_f32 v[0:1], v[4:5], v[14:15], v[0:1]
	s_nop 0
	v_cvt_pk_bf16_f32 v3, v0, v1
	v_lshl_add_u64 v[0:1], v[72:73], 0, s[64:65]
	global_store_dwordx2 v[0:1], v[8:9], off
	global_store_dwordx2 v[0:1], v[2:3], off offset:64
.LBB0_583:
	s_or_b64 exec, exec, s[68:69]
	s_or_b32 s44, s72, 2
	s_or_b32 s64, s44, s82
	s_mulk_i32 s64, 0x410
	v_add_u32_e32 v7, s64, v80
	ds_read_b128 v[2:5], v7
	v_readlane_b32 s66, v6, s44
	s_or_b32 s64, s44, s83
	s_waitcnt lgkmcnt(0)
	v_pk_mul_f32 v[2:3], s[66:67], v[2:3] op_sel_hi:[0,1]
	v_pk_mul_f32 v[0:1], s[66:67], v[4:5] op_sel_hi:[0,1]
	v_cvt_pk_bf16_f32 v4, v2, v3
	v_cvt_pk_bf16_f32 v5, v0, v1
	s_and_saveexec_b64 s[68:69], s[4:5]
	s_xor_b64 s[68:69], exec, s[68:69]
	s_cbranch_execz .LBB0_587
	s_and_saveexec_b64 s[70:71], s[6:7]
	s_cbranch_execz .LBB0_586
	s_ashr_i32 s65, s64, 31
	s_lshl_b64 s[74:75], s[64:65], 9
	v_lshl_add_u64 v[8:9], v[64:65], 0, s[74:75]
	v_add_co_u32_e32 v8, vcc, 0x2755e000, v8
	s_nop 1
	v_addc_co_u32_e32 v9, vcc, 0, v9, vcc
	global_store_dwordx2 v[8:9], v[4:5], off offset:2816

; template <int EPI, int TS, bool VT>
; DEVI void gemm_epilogue(const Params& p, char* smem, f32x4 (&acc)[2][2][4][2], int m0, int n0, float scale, const float* ssin,
;                         float* ssout, u16* xbout, int wid, int lane, int wr, int wc, int fr, int fq) {
;     ...
;             const float4 a = *(const float4*)(Tr + 4 * lane);
;             const int col = n0 + 4 * lane;
;             const float v0 = a.x * rs, v1 = a.y * rs, v2 = a.z * rs, v3 = a.w * rs;
;             const float sq = v0 * v0 + v1 * v1 + v2 * v2 + v3 * v3;
;             uint2 o;
;             o.x = pack2(v0, v1);
;             o.y = pack2(v2, v3);
;             if (col < 384) *(uint2*)((u16*)(wsb + OFF_CQN) + (size_t)grow * 384 + col) = o;
;             else if (col < 640) *(uint2*)((u16*)(wsb + OFF_CKVN) + (size_t)grow * 256 + (col - 384)) = o;
;             if (n0 < 512) {
;               const float sqq = wsum(col < 384 ? sq : 0.f, lane);
;               if (lane == 0) atomicAdd(ssout + grow, sqq);
;             }
;             if (n0 >= 256) {
;               const float sqk = wsum((col >= 384 && col < 640) ? sq : 0.f, lane);
;               if (lane == 0) atomicAdd(ssout + MTOK + grow, sqk);
;             }
;             if (n0 == 512 && lane >= 32 && lane < 40) {
;               const int i0r = 4 * (lane - 32);
;               const float4 b4 = *(const float4*)(Tr + 160 + i0r);
;               const int pos = tok_pos(grow);
;               const float4 c4 = *(const float4*)((const float*)(wsb + OFF_COS) + pos * 32 + i0r);
;               const float4 s4 = *(const float4*)((const float*)(wsb + OFF_SIN) + pos * 32 + i0r);
;               const float x1[4] = {v0, v1, v2, v3};
;               const float x2[4] = {b4.x * rs, b4.y * rs, b4.z * rs, b4.w * rs};
;               const float cc[4] = {c4.x, c4.y, c4.z, c4.w}, sn[4] = {s4.x, s4.y, s4.z, s4.w};
;               uint2 o1, o2;
;               o1.x = pack2(x1[0] * cc[0] - x2[0] * sn[0], x1[1] * cc[1] - x2[1] * sn[1]);
;               o1.y = pack2(x1[2] * cc[2] - x2[2] * sn[2], x1[3] * cc[3] - x2[3] * sn[3]);
;               o2.x = pack2(x2[0] * cc[0] + x1[0] * sn[0], x2[1] * cc[1] + x1[1] * sn[1]);
;               o2.y = pack2(x2[2] * cc[2] + x1[2] * sn[2], x2[3] * cc[3] + x1[3] * sn[3]);
;               u16* kr = (u16*)(wsb + OFF_KRM) + (size_t)grow * 64;
;               *(uint2*)(kr + i0r) = o1;
.LBB0_597:
	s_and_saveexec_b64 s[68:69], s[62:63]
	s_cbranch_execz .LBB0_599
	s_cmp_lt_i32 s64, 0x10000
	s_movk_i32 s44, 0xffa
	s_cselect_b32 s44, s44, 0x7fa
	s_and_b32 s44, s44, s64
	s_lshl_b32 s44, s44, 7
	v_lshl_add_u64 v[4:5], v[68:69], 0, s[44:45]
	v_lshl_add_u64 v[16:17], v[70:71], 0, s[44:45]
	ds_read_b128 v[8:11], v7 offset:128
	global_load_dwordx4 v[12:15], v[4:5], off
	s_nop 0
	global_load_dwordx4 v[16:19], v[16:17], off
	s_mov_b32 s67, s66
	s_ashr_i32 s65, s64, 31
	s_lshl_b64 s[64:65], s[64:65], 7
	s_waitcnt lgkmcnt(0)
	v_pk_mul_f32 v[4:5], s[66:67], v[8:9]
	s_waitcnt vmcnt(0)
	v_pk_mul_f32 v[8:9], v[4:5], v[16:17]
	s_nop 0
	v_pk_fma_f32 v[8:9], v[2:3], v[12:13], v[8:9] neg_lo:[0,0,1] neg_hi:[0,0,1]
	v_pk_mul_f32 v[2:3], v[2:3], v[16:17]
	v_cvt_pk_bf16_f32 v8, v8, v9
	v_pk_fma_f32 v[2:3], v[4:5], v[12:13], v[2:3]
	v_pk_mul_f32 v[4:5], s[66:67], v[10:11]
	v_cvt_pk_bf16_f32 v2, v2, v3
	v_pk_mul_f32 v[10:11], v[4:5], v[18:19]
	s_nop 0
	v_pk_fma_f32 v[10:11], v[0:1], v[14:15], v[10:11] neg_lo:[0,0,1] neg_hi:[0,0,1]
	v_pk_mul_f32 v[0:1], v[0:1], v[18:19]
	v_cvt_pk_bf16_f32 v9, v10, v11
	v_pk_fma_f32 v[0:1], v[4:5], v[14:15], v[0:1]
	s_nop 0
	v_cvt_pk_bf16_f32 v3, v0, v1
	v_lshl_add_u64 v[0:1], v[72:73], 0, s[64:65]
	global_store_dwordx2 v[0:1], v[8:9], off
	global_store_dwordx2 v[0:1], v[2:3], off offset:64
.LBB0_599:
	s_or_b64 exec, exec, s[68:69]
	s_or_b32 s44, s72, 3
	s_or_b32 s64, s44, s82
	s_mulk_i32 s64, 0x410
	v_add_u32_e32 v7, s64, v80
	ds_read_b128 v[2:5], v7
	v_readlane_b32 s66, v6, s44
	s_or_b32 s64, s44, s83
	s_waitcnt lgkmcnt(0)
	v_pk_mul_f32 v[2:3], s[66:67], v[2:3] op_sel_hi:[0,1]
	v_pk_mul_f32 v[0:1], s[66:67], v[4:5] op_sel_hi:[0,1]
	v_cvt_pk_bf16_f32 v4, v2, v3
	v_cvt_pk_bf16_f32 v5, v0, v1
	s_and_saveexec_b64 s[68:69], s[4:5]
	s_xor_b64 s[68:69], exec, s[68:69]
	s_cbranch_execz .LBB0_603
	s_and_saveexec_b64 s[70:71], s[6:7]
	s_cbranch_execz .LBB0_602
	s_ashr_i32 s65, s64, 31
	s_lshl_b64 s[74:75], s[64:65], 9
	v_lshl_add_u64 v[8:9], v[64:65], 0, s[74:75]
	v_add_co_u32_e32 v8, vcc, 0x2755e000, v8
	s_nop 1
	v_addc_co_u32_e32 v9, vcc, 0, v9, vcc
	global_store_dwordx2 v[8:9], v[4:5], off offset:2816

; template <int EPI, int TS, bool VT>
; DEVI void gemm_epilogue(const Params& p, char* smem, f32x4 (&acc)[2][2][4][2], int m0, int n0, float scale, const float* ssin,
;                         float* ssout, u16* xbout, int wid, int lane, int wr, int wc, int fr, int fq) {
;     ...
;             const float4 a = *(const float4*)(Tr + 4 * lane);
;             const int col = n0 + 4 * lane;
;             const float v0 = a.x * rs, v1 = a.y * rs, v2 = a.z * rs, v3 = a.w * rs;
;             const float sq = v0 * v0 + v1 * v1 + v2 * v2 + v3 * v3;
;             uint2 o;
;             o.x = pack2(v0, v1);
;             o.y = pack2(v2, v3);
;             if (col < 384) *(uint2*)((u16*)(wsb + OFF_CQN) + (size_t)grow * 384 + col) = o;
;             else if (col < 640) *(uint2*)((u16*)(wsb + OFF_CKVN) + (size_t)grow * 256 + (col - 384)) = o;
;             if (n0 < 512) {
;               const float sqq = wsum(col < 384 ? sq : 0.f, lane);
;               if (lane == 0) atomicAdd(ssout + grow, sqq);
;             }
;             if (n0 >= 256) {
;               const float sqk = wsum((col >= 384 && col < 640) ? sq : 0.f, lane);
;               if (lane == 0) atomicAdd(ssout + MTOK + grow, sqk);
;             }
;             if (n0 == 512 && lane >= 32 && lane < 40) {
;               const int i0r = 4 * (lane - 32);
;               const float4 b4 = *(const float4*)(Tr + 160 + i0r);
;               const int pos = tok_pos(grow);
;               const float4 c4 = *(const float4*)((const float*)(wsb + OFF_COS) + pos * 32 + i0r);
;               const float4 s4 = *(const float4*)((const float*)(wsb + OFF_SIN) + pos * 32 + i0r);
;               const float x1[4] = {v0, v1, v2, v3};
;               const float x2[4] = {b4.x * rs, b4.y * rs, b4.z * rs, b4.w * rs};
;               const float cc[4] = {c4.x, c4.y, c4.z, c4.w}, sn[4] = {s4.x, s4.y, s4.z, s4.w};
;               uint2 o1, o2;
;               o1.x = pack2(x1[0] * cc[0] - x2[0] * sn[0], x1[1] * cc[1] - x2[1] * sn[1]);
;               o1.y = pack2(x1[2] * cc[2] - x2[2] * sn[2], x1[3] * cc[3] - x2[3] * sn[3]);
;               o2.x = pack2(x2[0] * cc[0] + x1[0] * sn[0], x2[1] * cc[1] + x1[1] * sn[1]);
;               o2.y = pack2(x2[2] * cc[2] + x1[2] * sn[2], x2[3] * cc[3] + x1[3] * sn[3]);
;               u16* kr = (u16*)(wsb + OFF_KRM) + (size_t)grow * 64;
;               *(uint2*)(kr + i0r) = o1;
.LBB0_613:
	s_and_saveexec_b64 s[68:69], s[62:63]
	s_cbranch_execz .LBB0_615
	s_cmp_lt_i32 s64, 0x10000
	s_movk_i32 s44, 0xffb
	s_cselect_b32 s44, s44, 0x7fb
	s_and_b32 s44, s44, s64
	s_lshl_b32 s44, s44, 7
	v_lshl_add_u64 v[4:5], v[68:69], 0, s[44:45]
	v_lshl_add_u64 v[16:17], v[70:71], 0, s[44:45]
	ds_read_b128 v[8:11], v7 offset:128
	global_load_dwordx4 v[12:15], v[4:5], off
	s_nop 0
	global_load_dwordx4 v[16:19], v[16:17], off
	s_mov_b32 s67, s66
	s_ashr_i32 s65, s64, 31
	s_lshl_b64 s[64:65], s[64:65], 7
	s_waitcnt lgkmcnt(0)
	v_pk_mul_f32 v[4:5], s[66:67], v[8:9]
	s_waitcnt vmcnt(0)
	v_pk_mul_f32 v[8:9], v[4:5], v[16:17]
	s_nop 0
	v_pk_fma_f32 v[8:9], v[2:3], v[12:13], v[8:9] neg_lo:[0,0,1] neg_hi:[0,0,1]
	v_pk_mul_f32 v[2:3], v[2:3], v[16:17]
	v_cvt_pk_bf16_f32 v8, v8, v9
	v_pk_fma_f32 v[2:3], v[4:5], v[12:13], v[2:3]
	v_pk_mul_f32 v[4:5], s[66:67], v[10:11]
	v_cvt_pk_bf16_f32 v2, v2, v3
	v_pk_mul_f32 v[10:11], v[4:5], v[18:19]
	s_nop 0
	v_pk_fma_f32 v[10:11], v[0:1], v[14:15], v[10:11] neg_lo:[0,0,1] neg_hi:[0,0,1]
	v_pk_mul_f32 v[0:1], v[0:1], v[18:19]
	v_cvt_pk_bf16_f32 v9, v10, v11
	v_pk_fma_f32 v[0:1], v[4:5], v[14:15], v[0:1]
	s_nop 0
	v_cvt_pk_bf16_f32 v3, v0, v1
	v_lshl_add_u64 v[0:1], v[72:73], 0, s[64:65]
	global_store_dwordx2 v[0:1], v[8:9], off
	global_store_dwordx2 v[0:1], v[2:3], off offset:64
.LBB0_615:
	s_or_b64 exec, exec, s[68:69]
	s_or_b32 s44, s72, 4
	s_or_b32 s64, s44, s82
	s_mulk_i32 s64, 0x410
	v_add_u32_e32 v7, s64, v80
	ds_read_b128 v[2:5], v7
	v_readlane_b32 s66, v6, s44
	s_or_b32 s64, s44, s83
	s_waitcnt lgkmcnt(0)
	v_pk_mul_f32 v[2:3], s[66:67], v[2:3] op_sel_hi:[0,1]
	v_pk_mul_f32 v[0:1], s[66:67], v[4:5] op_sel_hi:[0,1]
	v_cvt_pk_bf16_f32 v4, v2, v3
	v_cvt_pk_bf16_f32 v5, v0, v1
	s_and_saveexec_b64 s[68:69], s[4:5]
	s_xor_b64 s[68:69], exec, s[68:69]
	s_cbranch_execz .LBB0_619
	s_and_saveexec_b64 s[70:71], s[6:7]
	s_cbranch_execz .LBB0_618
	s_ashr_i32 s65, s64, 31
	s_lshl_b64 s[74:75], s[64:65], 9
	v_lshl_add_u64 v[8:9], v[64:65], 0, s[74:75]
	v_add_co_u32_e32 v8, vcc, 0x2755e000, v8
	s_nop 1
	v_addc_co_u32_e32 v9, vcc, 0, v9, vcc
	global_store_dwordx2 v[8:9], v[4:5], off offset:2816

; template <int EPI, int TS, bool VT>
; DEVI void gemm_epilogue(const Params& p, char* smem, f32x4 (&acc)[2][2][4][2], int m0, int n0, float scale, const float* ssin,
;                         float* ssout, u16* xbout, int wid, int lane, int wr, int wc, int fr, int fq) {
;     ...
;             const float4 a = *(const float4*)(Tr + 4 * lane);
;             const int col = n0 + 4 * lane;
;             const float v0 = a.x * rs, v1 = a.y * rs, v2 = a.z * rs, v3 = a.w * rs;
;             const float sq = v0 * v0 + v1 * v1 + v2 * v2 + v3 * v3;
;             uint2 o;
;             o.x = pack2(v0, v1);
;             o.y = pack2(v2, v3);
;             if (col < 384) *(uint2*)((u16*)(wsb + OFF_CQN) + (size_t)grow * 384 + col) = o;
;             else if (col < 640) *(uint2*)((u16*)(wsb + OFF_CKVN) + (size_t)grow * 256 + (col - 384)) = o;
;             if (n0 < 512) {
;               const float sqq = wsum(col < 384 ? sq : 0.f, lane);
;               if (lane == 0) atomicAdd(ssout + grow, sqq);
;             }
;             if (n0 >= 256) {
;               const float sqk = wsum((col >= 384 && col < 640) ? sq : 0.f, lane);
;               if (lane == 0) atomicAdd(ssout + MTOK + grow, sqk);
;             }
;             if (n0 == 512 && lane >= 32 && lane < 40) {
;               const int i0r = 4 * (lane - 32);
;               const float4 b4 = *(const float4*)(Tr + 160 + i0r);
;               const int pos = tok_pos(grow);
;               const float4 c4 = *(const float4*)((const float*)(wsb + OFF_COS) + pos * 32 + i0r);
;               const float4 s4 = *(const float4*)((const float*)(wsb + OFF_SIN) + pos * 32 + i0r);
;               const float x1[4] = {v0, v1, v2, v3};
;               const float x2[4] = {b4.x * rs, b4.y * rs, b4.z * rs, b4.w * rs};
;               const float cc[4] = {c4.x, c4.y, c4.z, c4.w}, sn[4] = {s4.x, s4.y, s4.z, s4.w};
;               uint2 o1, o2;
;               o1.x = pack2(x1[0] * cc[0] - x2[0] * sn[0], x1[1] * cc[1] - x2[1] * sn[1]);
;               o1.y = pack2(x1[2] * cc[2] - x2[2] * sn[2], x1[3] * cc[3] - x2[3] * sn[3]);
;               o2.x = pack2(x2[0] * cc[0] + x1[0] * sn[0], x2[1] * cc[1] + x1[1] * sn[1]);
;               o2.y = pack2(x2[2] * cc[2] + x1[2] * sn[2], x2[3] * cc[3] + x1[3] * sn[3]);
;               u16* kr = (u16*)(wsb + OFF_KRM) + (size_t)grow * 64;
;               *(uint2*)(kr + i0r) = o1;
.LBB0_629:
	s_and_saveexec_b64 s[68:69], s[62:63]
	s_cbranch_execz .LBB0_631
	s_cmp_lt_i32 s64, 0x10000
	s_movk_i32 s44, 0xffc
	s_cselect_b32 s44, s44, 0x7fc
	s_and_b32 s44, s44, s64
	s_lshl_b32 s44, s44, 7
	v_lshl_add_u64 v[4:5], v[68:69], 0, s[44:45]
	v_lshl_add_u64 v[16:17], v[70:71], 0, s[44:45]
	ds_read_b128 v[8:11], v7 offset:128
	global_load_dwordx4 v[12:15], v[4:5], off
	s_nop 0
	global_load_dwordx4 v[16:19], v[16:17], off
	s_mov_b32 s67, s66
	s_ashr_i32 s65, s64, 31
	s_lshl_b64 s[64:65], s[64:65], 7
	s_waitcnt lgkmcnt(0)
	v_pk_mul_f32 v[4:5], s[66:67], v[8:9]
	s_waitcnt vmcnt(0)
	v_pk_mul_f32 v[8:9], v[4:5], v[16:17]
	s_nop 0
	v_pk_fma_f32 v[8:9], v[2:3], v[12:13], v[8:9] neg_lo:[0,0,1] neg_hi:[0,0,1]
	v_pk_mul_f32 v[2:3], v[2:3], v[16:17]
	v_cvt_pk_bf16_f32 v8, v8, v9
	v_pk_fma_f32 v[2:3], v[4:5], v[12:13], v[2:3]
	v_pk_mul_f32 v[4:5], s[66:67], v[10:11]
	v_cvt_pk_bf16_f32 v2, v2, v3
	v_pk_mul_f32 v[10:11], v[4:5], v[18:19]
	s_nop 0
	v_pk_fma_f32 v[10:11], v[0:1], v[14:15], v[10:11] neg_lo:[0,0,1] neg_hi:[0,0,1]
	v_pk_mul_f32 v[0:1], v[0:1], v[18:19]
	v_cvt_pk_bf16_f32 v9, v10, v11
	v_pk_fma_f32 v[0:1], v[4:5], v[14:15], v[0:1]
	s_nop 0
	v_cvt_pk_bf16_f32 v3, v0, v1
	v_lshl_add_u64 v[0:1], v[72:73], 0, s[64:65]
	global_store_dwordx2 v[0:1], v[8:9], off
	global_store_dwordx2 v[0:1], v[2:3], off offset:64
.LBB0_631:
	s_or_b64 exec, exec, s[68:69]
	s_or_b32 s44, s72, 5
	s_or_b32 s64, s44, s82
	s_mulk_i32 s64, 0x410
	v_add_u32_e32 v7, s64, v80
	ds_read_b128 v[2:5], v7
	v_readlane_b32 s66, v6, s44
	s_or_b32 s64, s44, s83
	s_waitcnt lgkmcnt(0)
	v_pk_mul_f32 v[2:3], s[66:67], v[2:3] op_sel_hi:[0,1]
	v_pk_mul_f32 v[0:1], s[66:67], v[4:5] op_sel_hi:[0,1]
	v_cvt_pk_bf16_f32 v4, v2, v3
	v_cvt_pk_bf16_f32 v5, v0, v1
	s_and_saveexec_b64 s[68:69], s[4:5]
	s_xor_b64 s[68:69], exec, s[68:69]
	s_cbranch_execz .LBB0_635
	s_and_saveexec_b64 s[70:71], s[6:7]
	s_cbranch_execz .LBB0_634
	s_ashr_i32 s65, s64, 31
	s_lshl_b64 s[74:75], s[64:65], 9
	v_lshl_add_u64 v[8:9], v[64:65], 0, s[74:75]
	v_add_co_u32_e32 v8, vcc, 0x2755e000, v8
	s_nop 1
	v_addc_co_u32_e32 v9, vcc, 0, v9, vcc
	global_store_dwordx2 v[8:9], v[4:5], off offset:2816

; template <int EPI, int TS, bool VT>
; DEVI void gemm_epilogue(const Params& p, char* smem, f32x4 (&acc)[2][2][4][2], int m0, int n0, float scale, const float* ssin,
;                         float* ssout, u16* xbout, int wid, int lane, int wr, int wc, int fr, int fq) {
;     ...
;             const float4 a = *(const float4*)(Tr + 4 * lane);
;             const int col = n0 + 4 * lane;
;             const float v0 = a.x * rs, v1 = a.y * rs, v2 = a.z * rs, v3 = a.w * rs;
;             const float sq = v0 * v0 + v1 * v1 + v2 * v2 + v3 * v3;
;             uint2 o;
;             o.x = pack2(v0, v1);
;             o.y = pack2(v2, v3);
;             if (col < 384) *(uint2*)((u16*)(wsb + OFF_CQN) + (size_t)grow * 384 + col) = o;
;             else if (col < 640) *(uint2*)((u16*)(wsb + OFF_CKVN) + (size_t)grow * 256 + (col - 384)) = o;
;             if (n0 < 512) {
;               const float sqq = wsum(col < 384 ? sq : 0.f, lane);
;               if (lane == 0) atomicAdd(ssout + grow, sqq);
;             }
;             if (n0 >= 256) {
;               const float sqk = wsum((col >= 384 && col < 640) ? sq : 0.f, lane);
;               if (lane == 0) atomicAdd(ssout + MTOK + grow, sqk);
;             }
;             if (n0 == 512 && lane >= 32 && lane < 40) {
;               const int i0r = 4 * (lane - 32);
;               const float4 b4 = *(const float4*)(Tr + 160 + i0r);
;               const int pos = tok_pos(grow);
;               const float4 c4 = *(const float4*)((const float*)(wsb + OFF_COS) + pos * 32 + i0r);
;               const float4 s4 = *(const float4*)((const float*)(wsb + OFF_SIN) + pos * 32 + i0r);
;               const float x1[4] = {v0, v1, v2, v3};
;               const float x2[4] = {b4.x * rs, b4.y * rs, b4.z * rs, b4.w * rs};
;               const float cc[4] = {c4.x, c4.y, c4.z, c4.w}, sn[4] = {s4.x, s4.y, s4.z, s4.w};
;               uint2 o1, o2;
;               o1.x = pack2(x1[0] * cc[0] - x2[0] * sn[0], x1[1] * cc[1] - x2[1] * sn[1]);
;               o1.y = pack2(x1[2] * cc[2] - x2[2] * sn[2], x1[3] * cc[3] - x2[3] * sn[3]);
;               o2.x = pack2(x2[0] * cc[0] + x1[0] * sn[0], x2[1] * cc[1] + x1[1] * sn[1]);
;               o2.y = pack2(x2[2] * cc[2] + x1[2] * sn[2], x2[3] * cc[3] + x1[3] * sn[3]);
;               u16* kr = (u16*)(wsb + OFF_KRM) + (size_t)grow * 64;
;               *(uint2*)(kr + i0r) = o1;
.LBB0_645:
	s_and_saveexec_b64 s[68:69], s[62:63]
	s_cbranch_execz .LBB0_647
	s_cmp_lt_i32 s64, 0x10000
	s_movk_i32 s44, 0xffd
	s_cselect_b32 s44, s44, 0x7fd
	s_and_b32 s44, s44, s64
	s_lshl_b32 s44, s44, 7
	v_lshl_add_u64 v[4:5], v[68:69], 0, s[44:45]
	v_lshl_add_u64 v[16:17], v[70:71], 0, s[44:45]
	ds_read_b128 v[8:11], v7 offset:128
	global_load_dwordx4 v[12:15], v[4:5], off
	s_nop 0
	global_load_dwordx4 v[16:19], v[16:17], off
	s_mov_b32 s67, s66
	s_ashr_i32 s65, s64, 31
	s_lshl_b64 s[64:65], s[64:65], 7
	s_waitcnt lgkmcnt(0)
	v_pk_mul_f32 v[4:5], s[66:67], v[8:9]
	s_waitcnt vmcnt(0)
	v_pk_mul_f32 v[8:9], v[4:5], v[16:17]
	s_nop 0
	v_pk_fma_f32 v[8:9], v[2:3], v[12:13], v[8:9] neg_lo:[0,0,1] neg_hi:[0,0,1]
	v_pk_mul_f32 v[2:3], v[2:3], v[16:17]
	v_cvt_pk_bf16_f32 v8, v8, v9
	v_pk_fma_f32 v[2:3], v[4:5], v[12:13], v[2:3]
	v_pk_mul_f32 v[4:5], s[66:67], v[10:11]
	v_cvt_pk_bf16_f32 v2, v2, v3
	v_pk_mul_f32 v[10:11], v[4:5], v[18:19]
	s_nop 0
	v_pk_fma_f32 v[10:11], v[0:1], v[14:15], v[10:11] neg_lo:[0,0,1] neg_hi:[0,0,1]
	v_pk_mul_f32 v[0:1], v[0:1], v[18:19]
	v_cvt_pk_bf16_f32 v9, v10, v11
	v_pk_fma_f32 v[0:1], v[4:5], v[14:15], v[0:1]
	s_nop 0
	v_cvt_pk_bf16_f32 v3, v0, v1
	v_lshl_add_u64 v[0:1], v[72:73], 0, s[64:65]
	global_store_dwordx2 v[0:1], v[8:9], off
	global_store_dwordx2 v[0:1], v[2:3], off offset:64
.LBB0_647:
	s_or_b64 exec, exec, s[68:69]
	s_or_b32 s44, s72, 6
	s_or_b32 s64, s44, s82
	s_mulk_i32 s64, 0x410
	v_add_u32_e32 v7, s64, v80
	ds_read_b128 v[2:5], v7
	v_readlane_b32 s66, v6, s44
	s_or_b32 s64, s44, s83
	s_waitcnt lgkmcnt(0)
	v_pk_mul_f32 v[2:3], s[66:67], v[2:3] op_sel_hi:[0,1]
	v_pk_mul_f32 v[0:1], s[66:67], v[4:5] op_sel_hi:[0,1]
	v_cvt_pk_bf16_f32 v4, v2, v3
	v_cvt_pk_bf16_f32 v5, v0, v1
	s_and_saveexec_b64 s[68:69], s[4:5]
	s_xor_b64 s[68:69], exec, s[68:69]
	s_cbranch_execz .LBB0_651
	s_and_saveexec_b64 s[70:71], s[6:7]
	s_cbranch_execz .LBB0_650
	s_ashr_i32 s65, s64, 31
	s_lshl_b64 s[74:75], s[64:65], 9
	v_lshl_add_u64 v[8:9], v[64:65], 0, s[74:75]
	v_add_co_u32_e32 v8, vcc, 0x2755e000, v8
	s_nop 1
	v_addc_co_u32_e32 v9, vcc, 0, v9, vcc
	global_store_dwordx2 v[8:9], v[4:5], off offset:2816

; template <int EPI, int TS, bool VT>
; DEVI void gemm_epilogue(const Params& p, char* smem, f32x4 (&acc)[2][2][4][2], int m0, int n0, float scale, const float* ssin,
;                         float* ssout, u16* xbout, int wid, int lane, int wr, int wc, int fr, int fq) {
;     ...
;             const float4 a = *(const float4*)(Tr + 4 * lane);
;             const int col = n0 + 4 * lane;
;             const float v0 = a.x * rs, v1 = a.y * rs, v2 = a.z * rs, v3 = a.w * rs;
;             const float sq = v0 * v0 + v1 * v1 + v2 * v2 + v3 * v3;
;             uint2 o;
;             o.x = pack2(v0, v1);
;             o.y = pack2(v2, v3);
;             if (col < 384) *(uint2*)((u16*)(wsb + OFF_CQN) + (size_t)grow * 384 + col) = o;
;             else if (col < 640) *(uint2*)((u16*)(wsb + OFF_CKVN) + (size_t)grow * 256 + (col - 384)) = o;
;             if (n0 < 512) {
;               const float sqq = wsum(col < 384 ? sq : 0.f, lane);
;               if (lane == 0) atomicAdd(ssout + grow, sqq);
;             }
;             if (n0 >= 256) {
;               const float sqk = wsum((col >= 384 && col < 640) ? sq : 0.f, lane);
;               if (lane == 0) atomicAdd(ssout + MTOK + grow, sqk);
;             }
;             if (n0 == 512 && lane >= 32 && lane < 40) {
;               const int i0r = 4 * (lane - 32);
;               const float4 b4 = *(const float4*)(Tr + 160 + i0r);
;               const int pos = tok_pos(grow);
;               const float4 c4 = *(const float4*)((const float*)(wsb + OFF_COS) + pos * 32 + i0r);
;               const float4 s4 = *(const float4*)((const float*)(wsb + OFF_SIN) + pos * 32 + i0r);
;               const float x1[4] = {v0, v1, v2, v3};
;               const float x2[4] = {b4.x * rs, b4.y * rs, b4.z * rs, b4.w * rs};
;               const float cc[4] = {c4.x, c4.y, c4.z, c4.w}, sn[4] = {s4.x, s4.y, s4.z, s4.w};
;               uint2 o1, o2;
;               o1.x = pack2(x1[0] * cc[0] - x2[0] * sn[0], x1[1] * cc[1] - x2[1] * sn[1]);
;               o1.y = pack2(x1[2] * cc[2] - x2[2] * sn[2], x1[3] * cc[3] - x2[3] * sn[3]);
;               o2.x = pack2(x2[0] * cc[0] + x1[0] * sn[0], x2[1] * cc[1] + x1[1] * sn[1]);
;               o2.y = pack2(x2[2] * cc[2] + x1[2] * sn[2], x2[3] * cc[3] + x1[3] * sn[3]);
;               u16* kr = (u16*)(wsb + OFF_KRM) + (size_t)grow * 64;
;               *(uint2*)(kr + i0r) = o1;
.LBB0_661:
	s_and_saveexec_b64 s[68:69], s[62:63]
	s_cbranch_execz .LBB0_663
	s_cmp_lt_i32 s64, 0x10000
	s_movk_i32 s44, 0xffe
	s_cselect_b32 s44, s44, 0x7fe
	s_and_b32 s44, s44, s64
	s_lshl_b32 s44, s44, 7
	v_lshl_add_u64 v[4:5], v[68:69], 0, s[44:45]
	v_lshl_add_u64 v[16:17], v[70:71], 0, s[44:45]
	ds_read_b128 v[8:11], v7 offset:128
	global_load_dwordx4 v[12:15], v[4:5], off
	s_nop 0
	global_load_dwordx4 v[16:19], v[16:17], off
	s_mov_b32 s67, s66
	s_ashr_i32 s65, s64, 31
	s_lshl_b64 s[64:65], s[64:65], 7
	s_waitcnt lgkmcnt(0)
	v_pk_mul_f32 v[4:5], s[66:67], v[8:9]
	s_waitcnt vmcnt(0)
	v_pk_mul_f32 v[8:9], v[4:5], v[16:17]
	s_nop 0
	v_pk_fma_f32 v[8:9], v[2:3], v[12:13], v[8:9] neg_lo:[0,0,1] neg_hi:[0,0,1]
	v_pk_mul_f32 v[2:3], v[2:3], v[16:17]
	v_cvt_pk_bf16_f32 v8, v8, v9
	v_pk_fma_f32 v[2:3], v[4:5], v[12:13], v[2:3]
	v_pk_mul_f32 v[4:5], s[66:67], v[10:11]
	v_cvt_pk_bf16_f32 v2, v2, v3
	v_pk_mul_f32 v[10:11], v[4:5], v[18:19]
	s_nop 0
	v_pk_fma_f32 v[10:11], v[0:1], v[14:15], v[10:11] neg_lo:[0,0,1] neg_hi:[0,0,1]
	v_pk_mul_f32 v[0:1], v[0:1], v[18:19]
	v_cvt_pk_bf16_f32 v9, v10, v11
	v_pk_fma_f32 v[0:1], v[4:5], v[14:15], v[0:1]
	s_nop 0
	v_cvt_pk_bf16_f32 v3, v0, v1
	v_lshl_add_u64 v[0:1], v[72:73], 0, s[64:65]
	global_store_dwordx2 v[0:1], v[8:9], off
	global_store_dwordx2 v[0:1], v[2:3], off offset:64
.LBB0_663:
	s_or_b64 exec, exec, s[68:69]
	s_or_b32 s44, s72, 7
	s_or_b32 s64, s44, s82
	s_mulk_i32 s64, 0x410
	v_add_u32_e32 v7, s64, v80
	ds_read_b128 v[2:5], v7
	v_readlane_b32 s66, v6, s44
	s_or_b32 s64, s44, s83
	s_waitcnt lgkmcnt(0)
	v_pk_mul_f32 v[2:3], s[66:67], v[2:3] op_sel_hi:[0,1]
	v_pk_mul_f32 v[0:1], s[66:67], v[4:5] op_sel_hi:[0,1]
	v_cvt_pk_bf16_f32 v4, v2, v3
	v_cvt_pk_bf16_f32 v5, v0, v1
	s_and_saveexec_b64 s[68:69], s[4:5]
	s_xor_b64 s[68:69], exec, s[68:69]
	s_cbranch_execz .LBB0_667
	s_and_saveexec_b64 s[70:71], s[6:7]
	s_cbranch_execz .LBB0_666
	s_ashr_i32 s65, s64, 31
	s_lshl_b64 s[72:73], s[64:65], 9
	v_lshl_add_u64 v[8:9], v[64:65], 0, s[72:73]
	v_add_co_u32_e32 v8, vcc, 0x2755e000, v8
	s_nop 1
	v_addc_co_u32_e32 v9, vcc, 0, v9, vcc
	global_store_dwordx2 v[8:9], v[4:5], off offset:2816

; DEVI float wsum(float v, int lane) {
;     ...
;   v += dppf<0x128>(v);
;   v += dppf<0x124>(v);
;   v += dppf<0x122>(v);
;   v += dppf<0x121>(v);
;   const int iv = __float_as_int(v);
;   return __int_as_float(__builtin_amdgcn_readlane(iv, 0)) + __int_as_float(__builtin_amdgcn_readlane(iv, 16)) +
;          __int_as_float(__builtin_amdgcn_readlane(iv, 32)) + __int_as_float(__builtin_amdgcn_readlane(iv, 48));
; template <int EPI, int TS, bool VT>
; DEVI void gemm_epilogue(const Params& p, char* smem, f32x4 (&acc)[2][2][4][2], int m0, int n0, float scale, const float* ssin,
;                         float* ssout, u16* xbout, int wid, int lane, int wr, int wc, int fr, int fq) {
;     ...
;             if (n0 < 512) {
;               const float sqq = wsum(col < 384 ? sq : 0.f, lane);
;               if (lane == 0) atomicAdd(ssout + grow, sqq);
;             }
.LBB0_669:
	s_or_b64 exec, exec, s[68:69]
	v_pk_mul_f32 v[4:5], v[2:3], v[2:3]
	v_pk_mul_f32 v[8:9], v[0:1], v[0:1]
	v_add_f32_e32 v4, v4, v5
	v_add_f32_e32 v4, v4, v8
	s_and_b64 vcc, exec, s[12:13]
	v_add_f32_e32 v4, v4, v9
	s_cbranch_vccnz .LBB0_673
	v_cndmask_b32_e64 v5, 0, v4, s[0:1]
	s_nop 1
	v_add_f32_dpp v5, v5, v5 row_ror:8 row_mask:0xf bank_mask:0xf bound_ctrl:1
	s_nop 1
	v_add_f32_dpp v5, v5, v5 row_ror:4 row_mask:0xf bank_mask:0xf bound_ctrl:1
	s_nop 1
	v_add_f32_dpp v5, v5, v5 row_ror:2 row_mask:0xf bank_mask:0xf bound_ctrl:1
	s_nop 1
	v_add_f32_dpp v5, v5, v5 row_ror:1 row_mask:0xf bank_mask:0xf bound_ctrl:1
	s_nop 0
	v_readlane_b32 s44, v5, 0
	v_readlane_b32 s71, v5, 16
	v_readlane_b32 s67, v5, 32
	v_readlane_b32 s70, v5, 48
	s_and_saveexec_b64 s[68:69], s[8:9]
	s_cbranch_execz .LBB0_672
	s_ashr_i32 s65, s64, 31
	s_lshl_b64 s[72:73], s[64:65], 2
	v_mov_b32_e32 v5, s71
	s_add_u32 s72, s18, s72
	v_add_f32_e32 v5, s44, v5
	s_addc_u32 s73, s19, s73
	v_add_f32_e32 v5, s67, v5
	v_add_f32_e32 v5, s70, v5
	v_mov_b64_e32 v[8:9], s[72:73]
	global_atomic_add_f32 v[8:9], v5, off

; DEVI float wsum(float v, int lane) {
;     ...
;   v += dppf<0x128>(v);
;   v += dppf<0x124>(v);
;   v += dppf<0x122>(v);
;   v += dppf<0x121>(v);
;   const int iv = __float_as_int(v);
;   return __int_as_float(__builtin_amdgcn_readlane(iv, 0)) + __int_as_float(__builtin_amdgcn_readlane(iv, 16)) +
;          __int_as_float(__builtin_amdgcn_readlane(iv, 32)) + __int_as_float(__builtin_amdgcn_readlane(iv, 48));
; template <int EPI, int TS, bool VT>
; DEVI void gemm_epilogue(const Params& p, char* smem, f32x4 (&acc)[2][2][4][2], int m0, int n0, float scale, const float* ssin,
;                         float* ssout, u16* xbout, int wid, int lane, int wr, int wc, int fr, int fq) {
;     ...
;             if (n0 >= 256) {
;               const float sqk = wsum((col >= 384 && col < 640) ? sq : 0.f, lane);
;               if (lane == 0) atomicAdd(ssout + MTOK + grow, sqk);
;             }
.LBB0_673:
	s_and_b64 vcc, exec, s[14:15]
	s_cbranch_vccnz .LBB0_677
	v_cndmask_b32_e64 v4, 0, v4, s[10:11]
	s_nop 1
	v_add_f32_dpp v4, v4, v4 row_ror:8 row_mask:0xf bank_mask:0xf bound_ctrl:1
	s_nop 1
	v_add_f32_dpp v4, v4, v4 row_ror:4 row_mask:0xf bank_mask:0xf bound_ctrl:1
	s_nop 1
	v_add_f32_dpp v4, v4, v4 row_ror:2 row_mask:0xf bank_mask:0xf bound_ctrl:1
	s_nop 1
	v_add_f32_dpp v4, v4, v4 row_ror:1 row_mask:0xf bank_mask:0xf bound_ctrl:1
	s_nop 0
	v_readlane_b32 s44, v4, 0
	v_readlane_b32 s71, v4, 16
	v_readlane_b32 s67, v4, 32
	v_readlane_b32 s70, v4, 48
	s_and_saveexec_b64 s[68:69], s[8:9]
	s_cbranch_execz .LBB0_676
	s_ashr_i32 s65, s64, 31
	s_lshl_b64 s[72:73], s[64:65], 2
	v_mov_b32_e32 v4, s71
	s_add_u32 s72, s78, s72
	v_add_f32_e32 v4, s44, v4
	s_addc_u32 s73, s79, s73
	v_add_f32_e32 v4, s67, v4
	v_add_f32_e32 v8, s70, v4
	v_mov_b64_e32 v[4:5], s[72:73]
	global_atomic_add_f32 v[4:5], v8, off

; template <int EPI, int TS, bool VT>
; DEVI void gemm_epilogue(const Params& p, char* smem, f32x4 (&acc)[2][2][4][2], int m0, int n0, float scale, const float* ssin,
;                         float* ssout, u16* xbout, int wid, int lane, int wr, int wc, int fr, int fq) {
;     ...
;             if (n0 == 512 && lane >= 32 && lane < 40) {
;               const int i0r = 4 * (lane - 32);
;               const float4 b4 = *(const float4*)(Tr + 160 + i0r);
;               const int pos = tok_pos(grow);
;               const float4 c4 = *(const float4*)((const float*)(wsb + OFF_COS) + pos * 32 + i0r);
;               const float4 s4 = *(const float4*)((const float*)(wsb + OFF_SIN) + pos * 32 + i0r);
;               const float x1[4] = {v0, v1, v2, v3};
;               const float x2[4] = {b4.x * rs, b4.y * rs, b4.z * rs, b4.w * rs};
;               const float cc[4] = {c4.x, c4.y, c4.z, c4.w}, sn[4] = {s4.x, s4.y, s4.z, s4.w};
;               uint2 o1, o2;
;               o1.x = pack2(x1[0] * cc[0] - x2[0] * sn[0], x1[1] * cc[1] - x2[1] * sn[1]);
;               o1.y = pack2(x1[2] * cc[2] - x2[2] * sn[2], x1[3] * cc[3] - x2[3] * sn[3]);
;               o2.x = pack2(x2[0] * cc[0] + x1[0] * sn[0], x2[1] * cc[1] + x1[1] * sn[1]);
;               o2.y = pack2(x2[2] * cc[2] + x1[2] * sn[2], x2[3] * cc[3] + x1[3] * sn[3]);
;               u16* kr = (u16*)(wsb + OFF_KRM) + (size_t)grow * 64;
;               *(uint2*)(kr + i0r) = o1;
;               *(uint2*)(kr + 32 + i0r) = o2;
;             }
.LBB0_677:
	s_and_saveexec_b64 s[68:69], s[62:63]
	s_cbranch_execz .LBB0_550
	s_cmp_lt_i32 s64, 0x10000
	s_movk_i32 s44, 0xfff
	s_cselect_b32 s44, s44, 0x7ff
	s_and_b32 s44, s44, s64
	s_lshl_b32 s44, s44, 7
	v_lshl_add_u64 v[4:5], v[68:69], 0, s[44:45]
	v_lshl_add_u64 v[16:17], v[70:71], 0, s[44:45]
	ds_read_b128 v[8:11], v7 offset:128
	global_load_dwordx4 v[12:15], v[4:5], off
	s_nop 0
	global_load_dwordx4 v[16:19], v[16:17], off
	s_mov_b32 s67, s66
	s_ashr_i32 s65, s64, 31
	s_lshl_b64 s[64:65], s[64:65], 7
	s_waitcnt lgkmcnt(0)
	v_pk_mul_f32 v[4:5], s[66:67], v[8:9]
	s_waitcnt vmcnt(0)
	v_pk_mul_f32 v[8:9], v[4:5], v[16:17]
	s_nop 0
	v_pk_fma_f32 v[8:9], v[2:3], v[12:13], v[8:9] neg_lo:[0,0,1] neg_hi:[0,0,1]
	v_pk_mul_f32 v[2:3], v[2:3], v[16:17]
	v_cvt_pk_bf16_f32 v8, v8, v9
	v_pk_fma_f32 v[2:3], v[4:5], v[12:13], v[2:3]
	v_pk_mul_f32 v[4:5], s[66:67], v[10:11]
	v_cvt_pk_bf16_f32 v2, v2, v3
	v_pk_mul_f32 v[10:11], v[4:5], v[18:19]
	s_nop 0
	v_pk_fma_f32 v[10:11], v[0:1], v[14:15], v[10:11] neg_lo:[0,0,1] neg_hi:[0,0,1]
	v_pk_mul_f32 v[0:1], v[0:1], v[18:19]
	v_cvt_pk_bf16_f32 v9, v10, v11
	v_pk_fma_f32 v[0:1], v[4:5], v[14:15], v[0:1]
	s_nop 0
	v_cvt_pk_bf16_f32 v3, v0, v1
	v_lshl_add_u64 v[0:1], v[72:73], 0, s[64:65]
	global_store_dwordx2 v[0:1], v[8:9], off
	global_store_dwordx2 v[0:1], v[2:3], off offset:64
	s_branch .LBB0_550

; template <int EPI, int TS, bool VT>
; DEVI void gemm_epilogue(const Params& p, char* smem, f32x4 (&acc)[2][2][4][2], int m0, int n0, float scale, const float* ssin,
;                         float* ssout, u16* xbout, int wid, int lane, int wr, int wc, int fr, int fq) {
;     ...
;   for (int ai = 0; ai < 2; ++ai) {
;     {
;       float* tw = T + (wr * 64 + fq * 4) * TS + wc * 32 + fr;
; #pragma unroll
;       for (int m = 0; m < 4; ++m)
; #pragma unroll
;         for (int j = 0; j < 4; ++j)
; #pragma unroll
;           for (int v = 0; v < 4; ++v) tw[(m * 16 + j) * TS + (v >> 1) * 128 + (v & 1) * 16] = acc[ai][v >> 1][m][v & 1][j];
;     }
;     __syncthreads();
;     const int r0 = wid * 16;
;     const int g0 = m0 + ai * 128 + r0;
;     if constexpr (!VT) {
;       float rsv = 1.f;
;       if constexpr (EPI == E_PLEGATE || EPI == E_F32 || EPI == E_SWIGLU || EPI == E_GLAIN)
;         rsv = rsqrtf(ssin[g0 + (lane & 15)] * (1.f / 1024.f) + EPS);
;       if constexpr (EPI == E_QROPE) rsv = rsqrtf(ssin[g0 + (lane & 15)] * (1.f / 384.f) + EPS);
;     ...
;           } else if constexpr (EPI == E_QROPE) {
;             const float qs = 0.07216878364870323f * 1.4426950408889634f * rs;
;             const int G = (n0 >> 4) + (lane >> 2), f0 = (lane & 3) * 4;
;             const int head = G / 12, gh = G - head * 12;
;             const float4 a = *(const float4*)(Tr + 4 * lane);
;             u16* o = (u16*)(wsb + OFF_QM) + (size_t)grow * 1536 + head * 192;
;             if (gh < 8) {
;               uint2 ov;
;               ov.x = pack2(a.x * qs, a.y * qs);
;               ov.y = pack2(a.z * qs, a.w * qs);
;               *(uint2*)(o + gh * 16 + f0) = ov;
;             } else if (gh == 8 || gh == 10) {
;               const float4 b4 = *(const float4*)(Tr + 4 * lane + 16);
;               const int i0r = (gh == 8 ? 0 : 16) + f0;
;               const int pos = tok_pos(grow);
;               const float4 c4 = *(const float4*)((const float*)(wsb + OFF_COS) + pos * 32 + i0r);
;               const float4 s4 = *(const float4*)((const float*)(wsb + OFF_SIN) + pos * 32 + i0r);
.LBB0_706:
	s_lshl_b32 s0, s22, 6
	v_lshrrev_b32_e32 v129, 2, v130
	v_and_or_b32 v129, v129, 12, s0
	s_movk_i32 s0, 0x410
	v_readlane_b32 s12, v254, 13
	v_mul_lo_u32 v129, v129, s0
	s_lshl_b32 s0, s31, 7
	v_lshlrev_b32_e32 v132, 2, v128
	v_readlane_b32 s13, v254, 14
	v_add3_u32 v129, s0, v129, v132
	ds_write2_b32 v129, v92, v100 offset1:16
	ds_write2_b32 v129, v120, v124 offset0:128 offset1:144
	v_add_u32_e32 v92, 0x400, v129
	ds_write2_b32 v92, v93, v101 offset0:4 offset1:20
	ds_write2_b32 v92, v121, v125 offset0:132 offset1:148
	v_add_u32_e32 v93, 0x800, v129
	ds_write2_b32 v93, v94, v102 offset0:8 offset1:24
	ds_write2_b32 v93, v122, v126 offset0:136 offset1:152
	v_add_u32_e32 v94, 0xc00, v129
	ds_write2_b32 v94, v95, v103 offset0:12 offset1:28
	ds_write2_b32 v94, v123, v127 offset0:140 offset1:156
	v_add_u32_e32 v95, 0x4000, v129
	v_add_u32_e32 v100, 0x4400, v129
	v_add_u32_e32 v101, 0x4800, v129
	v_add_u32_e32 v102, 0x4c00, v129
	ds_write2_b32 v95, v80, v84 offset0:64 offset1:80
	ds_write2_b32 v95, v112, v116 offset0:192 offset1:208
	ds_write2_b32 v100, v81, v85 offset0:68 offset1:84
	ds_write2_b32 v100, v113, v117 offset0:196 offset1:212
	ds_write2_b32 v101, v82, v86 offset0:72 offset1:88
	ds_write2_b32 v101, v114, v118 offset0:200 offset1:216
	ds_write2_b32 v102, v83, v87 offset0:76 offset1:92
	ds_write2_b32 v102, v115, v119 offset0:204 offset1:220
	v_add_u32_e32 v83, 0x8000, v129
	v_add_u32_e32 v103, 0x8400, v129
	s_lshl_b32 s64, s30, 4
	ds_write2_b32 v83, v72, v76 offset0:128 offset1:144
	ds_write2_b32 v103, v104, v108 offset1:16
	ds_write2_b32 v103, v73, v77 offset0:132 offset1:148
	v_add_u32_e32 v73, 0x8800, v129
	v_add_u32_e32 v104, 0x8c00, v129
	s_add_i32 s65, s64, s21
	ds_write2_b32 v73, v105, v109 offset0:4 offset1:20
	ds_write2_b32 v73, v74, v78 offset0:136 offset1:152
	ds_write2_b32 v104, v106, v110 offset0:8 offset1:24
	ds_write2_b32 v104, v75, v79 offset0:140 offset1:156
	v_add_u32_e32 v105, 0x9000, v129
	v_add_u32_e32 v106, 0xc000, v129
	ds_write2_b32 v105, v107, v111 offset0:12 offset1:28
	ds_write2_b32 v106, v64, v68 offset0:192 offset1:208
	v_add_u32_e32 v107, 0xc400, v129
	v_or_b32_e32 v64, s65, v128
	ds_write2_b32 v107, v88, v96 offset0:64 offset1:80
	ds_write2_b32 v107, v65, v69 offset0:196 offset1:212
	v_add_u32_e32 v96, 0xc800, v129
	v_ashrrev_i32_e32 v65, 31, v64
	ds_write2_b32 v96, v89, v97 offset0:68 offset1:84
	ds_write2_b32 v96, v66, v70 offset0:200 offset1:216
	v_add_u32_e32 v89, 0xcc00, v129
	v_add_u32_e32 v97, 0xd000, v129
	v_lshl_add_u64 v[64:65], v[64:65], 2, s[18:19]
	ds_write2_b32 v89, v90, v98 offset0:72 offset1:88
	ds_write2_b32 v89, v67, v71 offset0:204 offset1:220
	ds_write2_b32 v97, v91, v99 offset0:76 offset1:92
	s_waitcnt vmcnt(0) lgkmcnt(0)
	s_barrier
	global_load_dword v66, v[64:65], off
	v_bfe_u32 v64, v130, 2, 4
	v_lshl_or_b32 v64, s20, 4, v64
	v_mul_hi_i32 v67, v64, s26
	v_lshrrev_b32_e32 v68, 31, v67
	v_ashrrev_i32_e32 v67, 1, v67
	v_and_b32_e32 v65, 63, v130
	v_add_u32_e32 v67, v67, v68
	v_mad_u64_u32 v[68:69], s[0:1], v67, -12, v[64:65]
	s_movk_i32 s0, 0xc0
	s_nop 0
	v_mul_lo_u32 v64, v67, s0
	v_lshlrev_b32_e32 v69, 4, v65
	v_ashrrev_i32_e32 v65, 31, v64
	v_lshl_add_u64 v[64:65], v[64:65], 1, s[12:13]
	s_mov_b64 s[0:1], 0x1495ee00
	v_cmp_eq_u32_e64 s[4:5], 8, v68
	v_and_b32_e32 v82, 12, v131
	v_lshl_add_u64 v[70:71], v[64:65], 0, s[0:1]
	v_cndmask_b32_e64 v64, 16, 0, s[4:5]
	v_or_b32_e32 v72, v64, v82
	v_lshlrev_b32_e32 v148, 2, v72
	v_lshl_add_u64 v[64:65], s[12:13], 0, v[148:149]
	s_mov_b64 s[12:13], 0x5520000
	v_lshl_add_u64 v[74:75], v[64:65], 0, s[12:13]
	s_mov_b64 s[12:13], 0x55a0000
	v_lshl_add_u64 v[76:77], v[64:65], 0, s[12:13]
	v_lshlrev_b32_e32 v78, 4, v68
	v_cmp_lt_i32_e64 s[0:1], 7, v68
	s_mov_b32 s66, 0
	v_ashrrev_i32_e32 v79, 31, v78
	s_mov_b64 s[12:13], -1
	s_waitcnt vmcnt(0) lgkmcnt(0)
	v_fmamk_f32 v66, v66, 0x3b2aaaab, v150
	v_mul_f32_e32 v67, 0x4b800000, v66
	v_cmp_gt_f32_e32 vcc, s29, v66
	s_nop 1
	v_cndmask_b32_e32 v66, v66, v67, vcc
	v_rsq_f32_e32 v66, v66
	s_nop 0
	v_mul_f32_e32 v64, 0x45800000, v66
	v_cndmask_b32_e32 v98, v66, v64, vcc
	s_branch .LBB0_708

; template <int EPI, int TS, bool VT>
; DEVI void gemm_epilogue(const Params& p, char* smem, f32x4 (&acc)[2][2][4][2], int m0, int n0, float scale, const float* ssin,
;                         float* ssout, u16* xbout, int wid, int lane, int wr, int wc, int fr, int fq) {
;     ...
;           } else if constexpr (EPI == E_QROPE) {
;             const float qs = 0.07216878364870323f * 1.4426950408889634f * rs;
;             const int G = (n0 >> 4) + (lane >> 2), f0 = (lane & 3) * 4;
;             const int head = G / 12, gh = G - head * 12;
;             const float4 a = *(const float4*)(Tr + 4 * lane);
;             u16* o = (u16*)(wsb + OFF_QM) + (size_t)grow * 1536 + head * 192;
;             if (gh < 8) {
;               uint2 ov;
;               ov.x = pack2(a.x * qs, a.y * qs);
;               ov.y = pack2(a.z * qs, a.w * qs);
;               *(uint2*)(o + gh * 16 + f0) = ov;
;             } else if (gh == 8 || gh == 10) {
;               const float4 b4 = *(const float4*)(Tr + 4 * lane + 16);
;               const int i0r = (gh == 8 ? 0 : 16) + f0;
;               const int pos = tok_pos(grow);
;               const float4 c4 = *(const float4*)((const float*)(wsb + OFF_COS) + pos * 32 + i0r);
;               const float4 s4 = *(const float4*)((const float*)(wsb + OFF_SIN) + pos * 32 + i0r);
;               uint2 o1, o2;
;               o1.x = pack2((a.x * c4.x - b4.x * s4.x) * qs, (a.y * c4.y - b4.y * s4.y) * qs);
;               o1.y = pack2((a.z * c4.z - b4.z * s4.z) * qs, (a.w * c4.w - b4.w * s4.w) * qs);
;               o2.x = pack2((b4.x * c4.x + a.x * s4.x) * qs, (b4.y * c4.y + a.y * s4.y) * qs);
;               o2.y = pack2((b4.z * c4.z + a.z * s4.z) * qs, (b4.w * c4.w + a.w * s4.w) * qs);
;               *(uint2*)(o + 128 + i0r) = o1;
;               *(uint2*)(o + 160 + i0r) = o2;
.LBB0_708:
	s_or_b32 s14, s66, s64
	s_mulk_i32 s14, 0x410
	v_add_u32_e32 v80, s14, v69
	s_waitcnt lgkmcnt(0)
	ds_read_b128 v[64:67], v80
	s_or_b32 s30, s66, s65
	v_readlane_b32 s15, v98, s66
	s_mov_b64 s[20:21], 0
	s_nop 0
	v_mul_f32_e32 v88, s15, v170
	v_mad_i64_i32 v[90:91], s[14:15], s30, v171, v[70:71]
	s_and_saveexec_b64 s[14:15], s[0:1]
	s_xor_b64 s[14:15], exec, s[14:15]
	s_cbranch_execz .LBB0_721
	v_cmp_lt_i32_e32 vcc, 9, v68
	s_and_saveexec_b64 s[22:23], vcc
	s_xor_b64 s[22:23], exec, s[22:23]
	v_cmp_eq_u32_e32 vcc, 10, v68
	s_and_b64 s[20:21], vcc, exec
	s_andn2_saveexec_b64 s[22:23], s[22:23]
	s_andn2_b64 s[20:21], s[20:21], exec
	s_and_b64 s[68:69], s[4:5], exec
	s_or_b64 s[20:21], s[20:21], s[68:69]
	s_or_b64 exec, exec, s[22:23]
	s_mov_b64 s[22:23], 0
	s_and_saveexec_b64 s[68:69], s[20:21]
	s_xor_b64 s[20:21], exec, s[68:69]
	s_cbranch_execz .LBB0_715
	s_cmp_lt_i32 s30, 0x10000
	s_movk_i32 s22, 0xff8
	s_cselect_b32 s22, s22, 0x7f8
	s_and_b32 s22, s22, s30
	s_lshl_b32 s44, s22, 7
	v_lshl_add_u64 v[108:109], v[74:75], 0, s[44:45]
	v_lshl_add_u64 v[112:113], v[76:77], 0, s[44:45]
	ds_read_b128 v[84:87], v80 offset:64
	global_load_dwordx4 v[108:111], v[108:109], off
	s_nop 0
	global_load_dwordx4 v[112:115], v[112:113], off
	v_lshlrev_b32_e32 v148, 1, v72
	s_mov_b64 s[22:23], exec
	s_waitcnt vmcnt(0) lgkmcnt(0)
	v_pk_mul_f32 v[116:117], v[84:85], v[112:113]
	s_nop 0
	v_pk_fma_f32 v[116:117], v[64:65], v[108:109], v[116:117] neg_lo:[0,0,1] neg_hi:[0,0,1]
	v_pk_mul_f32 v[64:65], v[64:65], v[112:113]
	v_pk_mul_f32 v[80:81], v[86:87], v[114:115]
	v_pk_fma_f32 v[64:65], v[84:85], v[108:109], v[64:65]
	v_pk_fma_f32 v[80:81], v[66:67], v[110:111], v[80:81] neg_lo:[0,0,1] neg_hi:[0,0,1]
	v_pk_mul_f32 v[64:65], v[88:89], v[64:65] op_sel_hi:[0,1]
	v_pk_mul_f32 v[84:85], v[66:67], v[114:115]
	v_mov_b32_e32 v66, v87
	v_mov_b32_e32 v114, v111
	v_cvt_pk_bf16_f32 v99, v64, v65
	v_pk_mul_f32 v[64:65], v[86:87], v[110:111]
	v_pk_mul_f32 v[66:67], v[66:67], v[114:115]
	v_pk_mul_f32 v[80:81], v[88:89], v[80:81] op_sel_hi:[0,1]
	v_mov_b32_e32 v65, v66
	v_mov_b32_e32 v85, v67
	v_pk_add_f32 v[64:65], v[64:65], v[84:85]
	v_pk_mul_f32 v[116:117], v[88:89], v[116:117] op_sel_hi:[0,1]
	v_pk_mul_f32 v[84:85], v[88:89], v[64:65] op_sel_hi:[0,1]
	v_lshl_add_u64 v[64:65], v[90:91], 0, v[148:149]
	v_cvt_pk_bf16_f32 v81, v80, v81
	v_cvt_pk_bf16_f32 v80, v116, v117
	v_lshl_add_u64 v[86:87], v[64:65], 0, s[42:43]
	global_store_dwordx2 v[64:65], v[80:81], off offset:256
	global_store_dword v[64:65], v99, off offset:320

; template <int EPI, int TS, bool VT>
; DEVI void gemm_epilogue(const Params& p, char* smem, f32x4 (&acc)[2][2][4][2], int m0, int n0, float scale, const float* ssin,
;                         float* ssout, u16* xbout, int wid, int lane, int wr, int wc, int fr, int fq) {
;     ...
;             if (gh < 8) {
;               uint2 ov;
;               ov.x = pack2(a.x * qs, a.y * qs);
;               ov.y = pack2(a.z * qs, a.w * qs);
;               *(uint2*)(o + gh * 16 + f0) = ov;
;             } else if (gh == 8 || gh == 10) {
;               const float4 b4 = *(const float4*)(Tr + 4 * lane + 16);
;               const int i0r = (gh == 8 ? 0 : 16) + f0;
;               const int pos = tok_pos(grow);
;               const float4 c4 = *(const float4*)((const float*)(wsb + OFF_COS) + pos * 32 + i0r);
;               const float4 s4 = *(const float4*)((const float*)(wsb + OFF_SIN) + pos * 32 + i0r);
;               uint2 o1, o2;
;               o1.x = pack2((a.x * c4.x - b4.x * s4.x) * qs, (a.y * c4.y - b4.y * s4.y) * qs);
;               o1.y = pack2((a.z * c4.z - b4.z * s4.z) * qs, (a.w * c4.w - b4.w * s4.w) * qs);
;               o2.x = pack2((b4.x * c4.x + a.x * s4.x) * qs, (b4.y * c4.y + a.y * s4.y) * qs);
;               o2.y = pack2((b4.z * c4.z + a.z * s4.z) * qs, (b4.w * c4.w + a.w * s4.w) * qs);
;               *(uint2*)(o + 128 + i0r) = o1;
;               *(uint2*)(o + 160 + i0r) = o2;
.LBB0_717:
	s_waitcnt lgkmcnt(0)
	v_cvt_pk_bf16_f32 v64, v84, v85
	global_store_dword v[86:87], v64, off offset:4

; template <int EPI, int TS, bool VT>
; DEVI void gemm_epilogue(const Params& p, char* smem, f32x4 (&acc)[2][2][4][2], int m0, int n0, float scale, const float* ssin,
;                         float* ssout, u16* xbout, int wid, int lane, int wr, int wc, int fr, int fq) {
;     ...
;             if (gh < 8) {
;               uint2 ov;
;               ov.x = pack2(a.x * qs, a.y * qs);
;               ov.y = pack2(a.z * qs, a.w * qs);
;               *(uint2*)(o + gh * 16 + f0) = ov;
.LBB0_722:
	s_waitcnt lgkmcnt(0)
	v_pk_mul_f32 v[64:65], v[64:65], v[88:89] op_sel_hi:[1,0]
	v_mov_b32_e32 v81, v149
	v_cvt_pk_bf16_f32 v99, v64, v65
	v_lshl_add_u64 v[64:65], v[78:79], 1, v[90:91]
	v_pk_mul_f32 v[84:85], v[88:89], v[66:67] op_sel_hi:[0,1]
	v_lshl_add_u64 v[86:87], v[64:65], 0, v[80:81]
	s_or_b64 s[20:21], s[20:21], exec
	global_store_dword v[86:87], v99, off
	s_or_b64 exec, exec, s[14:15]
	s_and_saveexec_b64 s[14:15], s[20:21]
	s_cbranch_execnz .LBB0_717
	s_branch .LBB0_718

; template <int EPI, int TS, bool VT>
; DEVI void gemm_epilogue(const Params& p, char* smem, f32x4 (&acc)[2][2][4][2], int m0, int n0, float scale, const float* ssin,
;                         float* ssout, u16* xbout, int wid, int lane, int wr, int wc, int fr, int fq) {
;     ...
;             } else if (gh == 8 || gh == 10) {
;               const float4 b4 = *(const float4*)(Tr + 4 * lane + 16);
;               const int i0r = (gh == 8 ? 0 : 16) + f0;
;               const int pos = tok_pos(grow);
;               const float4 c4 = *(const float4*)((const float*)(wsb + OFF_COS) + pos * 32 + i0r);
;               const float4 s4 = *(const float4*)((const float*)(wsb + OFF_SIN) + pos * 32 + i0r);
;               uint2 o1, o2;
;               o1.x = pack2((a.x * c4.x - b4.x * s4.x) * qs, (a.y * c4.y - b4.y * s4.y) * qs);
;               o1.y = pack2((a.z * c4.z - b4.z * s4.z) * qs, (a.w * c4.w - b4.w * s4.w) * qs);
;               o2.x = pack2((b4.x * c4.x + a.x * s4.x) * qs, (b4.y * c4.y + a.y * s4.y) * qs);
;               o2.y = pack2((b4.z * c4.z + a.z * s4.z) * qs, (b4.w * c4.w + a.w * s4.w) * qs);
;               *(uint2*)(o + 128 + i0r) = o1;
;               *(uint2*)(o + 160 + i0r) = o2;
.LBB0_726:
	s_andn2_b64 s[22:23], s[30:31], exec
	s_and_b64 s[30:31], s[4:5], exec
	s_or_b64 s[30:31], s[22:23], s[30:31]
	s_or_b64 exec, exec, s[20:21]
	s_mov_b64 s[22:23], 0
	s_and_saveexec_b64 s[20:21], s[30:31]
	s_cbranch_execz .LBB0_729
	s_cmp_lt_i32 s44, 0x10000
	s_movk_i32 s22, 0xff9
	s_cselect_b32 s22, s22, 0x7f9
	s_and_b32 s22, s22, s44
	s_lshl_b32 s44, s22, 7
	v_lshl_add_u64 v[108:109], v[74:75], 0, s[44:45]
	v_lshl_add_u64 v[112:113], v[76:77], 0, s[44:45]
	ds_read_b128 v[84:87], v81 offset:64
	global_load_dwordx4 v[108:111], v[108:109], off
	s_nop 0
	global_load_dwordx4 v[112:115], v[112:113], off
	v_lshlrev_b32_e32 v148, 1, v72
	s_mov_b64 s[22:23], exec
	s_waitcnt vmcnt(0) lgkmcnt(0)
	v_pk_mul_f32 v[118:119], v[84:85], v[112:113]
	s_nop 0
	v_pk_fma_f32 v[118:119], v[64:65], v[108:109], v[118:119] neg_lo:[0,0,1] neg_hi:[0,0,1]
	v_pk_mul_f32 v[64:65], v[64:65], v[112:113]
	v_pk_mul_f32 v[116:117], v[86:87], v[114:115]
	v_pk_fma_f32 v[64:65], v[84:85], v[108:109], v[64:65]
	v_pk_fma_f32 v[116:117], v[66:67], v[110:111], v[116:117] neg_lo:[0,0,1] neg_hi:[0,0,1]
	v_pk_mul_f32 v[64:65], v[88:89], v[64:65] op_sel_hi:[0,1]
	v_pk_mul_f32 v[84:85], v[66:67], v[114:115]
	v_mov_b32_e32 v66, v87
	v_mov_b32_e32 v114, v111
	v_cvt_pk_bf16_f32 v81, v64, v65
	v_pk_mul_f32 v[64:65], v[86:87], v[110:111]
	v_pk_mul_f32 v[66:67], v[66:67], v[114:115]
	v_pk_mul_f32 v[116:117], v[88:89], v[116:117] op_sel_hi:[0,1]
	v_mov_b32_e32 v65, v66
	v_mov_b32_e32 v85, v67
	v_pk_add_f32 v[64:65], v[64:65], v[84:85]
	v_pk_mul_f32 v[118:119], v[88:89], v[118:119] op_sel_hi:[0,1]
	v_pk_mul_f32 v[84:85], v[88:89], v[64:65] op_sel_hi:[0,1]
	v_lshl_add_u64 v[64:65], v[90:91], 0, v[148:149]
	v_cvt_pk_bf16_f32 v117, v116, v117
	v_cvt_pk_bf16_f32 v116, v118, v119
	v_lshl_add_u64 v[86:87], v[64:65], 0, s[42:43]
	global_store_dwordx2 v[64:65], v[116:117], off offset:256
	global_store_dword v[64:65], v81, off offset:320

; template <int EPI, int TS, bool VT>
; DEVI void gemm_epilogue(const Params& p, char* smem, f32x4 (&acc)[2][2][4][2], int m0, int n0, float scale, const float* ssin,
;                         float* ssout, u16* xbout, int wid, int lane, int wr, int wc, int fr, int fq) {
;     ...
;             } else if (gh == 8 || gh == 10) {
;               const float4 b4 = *(const float4*)(Tr + 4 * lane + 16);
;               const int i0r = (gh == 8 ? 0 : 16) + f0;
;               const int pos = tok_pos(grow);
;               const float4 c4 = *(const float4*)((const float*)(wsb + OFF_COS) + pos * 32 + i0r);
;               const float4 s4 = *(const float4*)((const float*)(wsb + OFF_SIN) + pos * 32 + i0r);
;               uint2 o1, o2;
;               o1.x = pack2((a.x * c4.x - b4.x * s4.x) * qs, (a.y * c4.y - b4.y * s4.y) * qs);
;               o1.y = pack2((a.z * c4.z - b4.z * s4.z) * qs, (a.w * c4.w - b4.w * s4.w) * qs);
;               o2.x = pack2((b4.x * c4.x + a.x * s4.x) * qs, (b4.y * c4.y + a.y * s4.y) * qs);
;               o2.y = pack2((b4.z * c4.z + a.z * s4.z) * qs, (b4.w * c4.w + a.w * s4.w) * qs);
;               *(uint2*)(o + 128 + i0r) = o1;
;               *(uint2*)(o + 160 + i0r) = o2;
.LBB0_738:
	s_andn2_b64 s[22:23], s[30:31], exec
	s_and_b64 s[30:31], s[4:5], exec
	s_or_b64 s[30:31], s[22:23], s[30:31]
	s_or_b64 exec, exec, s[20:21]
	s_mov_b64 s[22:23], 0
	s_and_saveexec_b64 s[20:21], s[30:31]
	s_cbranch_execz .LBB0_741
	s_cmp_lt_i32 s44, 0x10000
	s_movk_i32 s22, 0xffa
	s_cselect_b32 s22, s22, 0x7fa
	s_and_b32 s22, s22, s44
	s_lshl_b32 s44, s22, 7
	v_lshl_add_u64 v[108:109], v[74:75], 0, s[44:45]
	v_lshl_add_u64 v[112:113], v[76:77], 0, s[44:45]
	ds_read_b128 v[84:87], v81 offset:64
	global_load_dwordx4 v[108:111], v[108:109], off
	s_nop 0
	global_load_dwordx4 v[112:115], v[112:113], off
	v_lshlrev_b32_e32 v148, 1, v72
	s_mov_b64 s[22:23], exec
	s_waitcnt vmcnt(0) lgkmcnt(0)
	v_pk_mul_f32 v[118:119], v[84:85], v[112:113]
	s_nop 0
	v_pk_fma_f32 v[118:119], v[64:65], v[108:109], v[118:119] neg_lo:[0,0,1] neg_hi:[0,0,1]
	v_pk_mul_f32 v[64:65], v[64:65], v[112:113]
	v_pk_mul_f32 v[116:117], v[86:87], v[114:115]
	v_pk_fma_f32 v[64:65], v[84:85], v[108:109], v[64:65]
	v_pk_fma_f32 v[116:117], v[66:67], v[110:111], v[116:117] neg_lo:[0,0,1] neg_hi:[0,0,1]
	v_pk_mul_f32 v[64:65], v[88:89], v[64:65] op_sel_hi:[0,1]
	v_pk_mul_f32 v[84:85], v[66:67], v[114:115]
	v_mov_b32_e32 v66, v87
	v_mov_b32_e32 v114, v111
	v_cvt_pk_bf16_f32 v81, v64, v65
	v_pk_mul_f32 v[64:65], v[86:87], v[110:111]
	v_pk_mul_f32 v[66:67], v[66:67], v[114:115]
	v_pk_mul_f32 v[116:117], v[88:89], v[116:117] op_sel_hi:[0,1]
	v_mov_b32_e32 v65, v66
	v_mov_b32_e32 v85, v67
	v_pk_add_f32 v[64:65], v[64:65], v[84:85]
	v_pk_mul_f32 v[118:119], v[88:89], v[118:119] op_sel_hi:[0,1]
	v_pk_mul_f32 v[84:85], v[88:89], v[64:65] op_sel_hi:[0,1]
	v_lshl_add_u64 v[64:65], v[90:91], 0, v[148:149]
	v_cvt_pk_bf16_f32 v117, v116, v117
	v_cvt_pk_bf16_f32 v116, v118, v119
	v_lshl_add_u64 v[86:87], v[64:65], 0, s[42:43]
	global_store_dwordx2 v[64:65], v[116:117], off offset:256
	global_store_dword v[64:65], v81, off offset:320

; template <int EPI, int TS, bool VT>
; DEVI void gemm_epilogue(const Params& p, char* smem, f32x4 (&acc)[2][2][4][2], int m0, int n0, float scale, const float* ssin,
;                         float* ssout, u16* xbout, int wid, int lane, int wr, int wc, int fr, int fq) {
;     ...
;             } else if (gh == 8 || gh == 10) {
;               const float4 b4 = *(const float4*)(Tr + 4 * lane + 16);
;               const int i0r = (gh == 8 ? 0 : 16) + f0;
;               const int pos = tok_pos(grow);
;               const float4 c4 = *(const float4*)((const float*)(wsb + OFF_COS) + pos * 32 + i0r);
;               const float4 s4 = *(const float4*)((const float*)(wsb + OFF_SIN) + pos * 32 + i0r);
;               uint2 o1, o2;
;               o1.x = pack2((a.x * c4.x - b4.x * s4.x) * qs, (a.y * c4.y - b4.y * s4.y) * qs);
;               o1.y = pack2((a.z * c4.z - b4.z * s4.z) * qs, (a.w * c4.w - b4.w * s4.w) * qs);
;               o2.x = pack2((b4.x * c4.x + a.x * s4.x) * qs, (b4.y * c4.y + a.y * s4.y) * qs);
;               o2.y = pack2((b4.z * c4.z + a.z * s4.z) * qs, (b4.w * c4.w + a.w * s4.w) * qs);
;               *(uint2*)(o + 128 + i0r) = o1;
;               *(uint2*)(o + 160 + i0r) = o2;
.LBB0_750:
	s_andn2_b64 s[22:23], s[30:31], exec
	s_and_b64 s[30:31], s[4:5], exec
	s_or_b64 s[30:31], s[22:23], s[30:31]
	s_or_b64 exec, exec, s[20:21]
	s_mov_b64 s[22:23], 0
	s_and_saveexec_b64 s[20:21], s[30:31]
	s_cbranch_execz .LBB0_753
	s_cmp_lt_i32 s44, 0x10000
	s_movk_i32 s22, 0xffb
	s_cselect_b32 s22, s22, 0x7fb
	s_and_b32 s22, s22, s44
	s_lshl_b32 s44, s22, 7
	v_lshl_add_u64 v[108:109], v[74:75], 0, s[44:45]
	v_lshl_add_u64 v[112:113], v[76:77], 0, s[44:45]
	ds_read_b128 v[84:87], v81 offset:64
	global_load_dwordx4 v[108:111], v[108:109], off
	s_nop 0
	global_load_dwordx4 v[112:115], v[112:113], off
	v_lshlrev_b32_e32 v148, 1, v72
	s_mov_b64 s[22:23], exec
	s_waitcnt vmcnt(0) lgkmcnt(0)
	v_pk_mul_f32 v[118:119], v[84:85], v[112:113]
	s_nop 0
	v_pk_fma_f32 v[118:119], v[64:65], v[108:109], v[118:119] neg_lo:[0,0,1] neg_hi:[0,0,1]
	v_pk_mul_f32 v[64:65], v[64:65], v[112:113]
	v_pk_mul_f32 v[116:117], v[86:87], v[114:115]
	v_pk_fma_f32 v[64:65], v[84:85], v[108:109], v[64:65]
	v_pk_fma_f32 v[116:117], v[66:67], v[110:111], v[116:117] neg_lo:[0,0,1] neg_hi:[0,0,1]
	v_pk_mul_f32 v[64:65], v[88:89], v[64:65] op_sel_hi:[0,1]
	v_pk_mul_f32 v[84:85], v[66:67], v[114:115]
	v_mov_b32_e32 v66, v87
	v_mov_b32_e32 v114, v111
	v_cvt_pk_bf16_f32 v81, v64, v65
	v_pk_mul_f32 v[64:65], v[86:87], v[110:111]
	v_pk_mul_f32 v[66:67], v[66:67], v[114:115]
	v_pk_mul_f32 v[116:117], v[88:89], v[116:117] op_sel_hi:[0,1]
	v_mov_b32_e32 v65, v66
	v_mov_b32_e32 v85, v67
	v_pk_add_f32 v[64:65], v[64:65], v[84:85]
	v_pk_mul_f32 v[118:119], v[88:89], v[118:119] op_sel_hi:[0,1]
	v_pk_mul_f32 v[84:85], v[88:89], v[64:65] op_sel_hi:[0,1]
	v_lshl_add_u64 v[64:65], v[90:91], 0, v[148:149]
	v_cvt_pk_bf16_f32 v117, v116, v117
	v_cvt_pk_bf16_f32 v116, v118, v119
	v_lshl_add_u64 v[86:87], v[64:65], 0, s[42:43]
	global_store_dwordx2 v[64:65], v[116:117], off offset:256
	global_store_dword v[64:65], v81, off offset:320

; template <int EPI, int TS, bool VT>
; DEVI void gemm_epilogue(const Params& p, char* smem, f32x4 (&acc)[2][2][4][2], int m0, int n0, float scale, const float* ssin,
;                         float* ssout, u16* xbout, int wid, int lane, int wr, int wc, int fr, int fq) {
;     ...
;             } else if (gh == 8 || gh == 10) {
;               const float4 b4 = *(const float4*)(Tr + 4 * lane + 16);
;               const int i0r = (gh == 8 ? 0 : 16) + f0;
;               const int pos = tok_pos(grow);
;               const float4 c4 = *(const float4*)((const float*)(wsb + OFF_COS) + pos * 32 + i0r);
;               const float4 s4 = *(const float4*)((const float*)(wsb + OFF_SIN) + pos * 32 + i0r);
;               uint2 o1, o2;
;               o1.x = pack2((a.x * c4.x - b4.x * s4.x) * qs, (a.y * c4.y - b4.y * s4.y) * qs);
;               o1.y = pack2((a.z * c4.z - b4.z * s4.z) * qs, (a.w * c4.w - b4.w * s4.w) * qs);
;               o2.x = pack2((b4.x * c4.x + a.x * s4.x) * qs, (b4.y * c4.y + a.y * s4.y) * qs);
;               o2.y = pack2((b4.z * c4.z + a.z * s4.z) * qs, (b4.w * c4.w + a.w * s4.w) * qs);
;               *(uint2*)(o + 128 + i0r) = o1;
;               *(uint2*)(o + 160 + i0r) = o2;
.LBB0_762:
	s_andn2_b64 s[22:23], s[30:31], exec
	s_and_b64 s[30:31], s[4:5], exec
	s_or_b64 s[30:31], s[22:23], s[30:31]
	s_or_b64 exec, exec, s[20:21]
	s_mov_b64 s[22:23], 0
	s_and_saveexec_b64 s[20:21], s[30:31]
	s_cbranch_execz .LBB0_765
	s_cmp_lt_i32 s44, 0x10000
	s_movk_i32 s22, 0xffc
	s_cselect_b32 s22, s22, 0x7fc
	s_and_b32 s22, s22, s44
	s_lshl_b32 s44, s22, 7
	v_lshl_add_u64 v[108:109], v[74:75], 0, s[44:45]
	v_lshl_add_u64 v[112:113], v[76:77], 0, s[44:45]
	ds_read_b128 v[84:87], v81 offset:64
	global_load_dwordx4 v[108:111], v[108:109], off
	s_nop 0
	global_load_dwordx4 v[112:115], v[112:113], off
	v_lshlrev_b32_e32 v148, 1, v72
	s_mov_b64 s[22:23], exec
	s_waitcnt vmcnt(0) lgkmcnt(0)
	v_pk_mul_f32 v[118:119], v[84:85], v[112:113]
	s_nop 0
	v_pk_fma_f32 v[118:119], v[64:65], v[108:109], v[118:119] neg_lo:[0,0,1] neg_hi:[0,0,1]
	v_pk_mul_f32 v[64:65], v[64:65], v[112:113]
	v_pk_mul_f32 v[116:117], v[86:87], v[114:115]
	v_pk_fma_f32 v[64:65], v[84:85], v[108:109], v[64:65]
	v_pk_fma_f32 v[116:117], v[66:67], v[110:111], v[116:117] neg_lo:[0,0,1] neg_hi:[0,0,1]
	v_pk_mul_f32 v[64:65], v[88:89], v[64:65] op_sel_hi:[0,1]
	v_pk_mul_f32 v[84:85], v[66:67], v[114:115]
	v_mov_b32_e32 v66, v87
	v_mov_b32_e32 v114, v111
	v_cvt_pk_bf16_f32 v81, v64, v65
	v_pk_mul_f32 v[64:65], v[86:87], v[110:111]
	v_pk_mul_f32 v[66:67], v[66:67], v[114:115]
	v_pk_mul_f32 v[116:117], v[88:89], v[116:117] op_sel_hi:[0,1]
	v_mov_b32_e32 v65, v66
	v_mov_b32_e32 v85, v67
	v_pk_add_f32 v[64:65], v[64:65], v[84:85]
	v_pk_mul_f32 v[118:119], v[88:89], v[118:119] op_sel_hi:[0,1]
	v_pk_mul_f32 v[84:85], v[88:89], v[64:65] op_sel_hi:[0,1]
	v_lshl_add_u64 v[64:65], v[90:91], 0, v[148:149]
	v_cvt_pk_bf16_f32 v117, v116, v117
	v_cvt_pk_bf16_f32 v116, v118, v119
	v_lshl_add_u64 v[86:87], v[64:65], 0, s[42:43]
	global_store_dwordx2 v[64:65], v[116:117], off offset:256
	global_store_dword v[64:65], v81, off offset:320

; template <int EPI, int TS, bool VT>
; DEVI void gemm_epilogue(const Params& p, char* smem, f32x4 (&acc)[2][2][4][2], int m0, int n0, float scale, const float* ssin,
;                         float* ssout, u16* xbout, int wid, int lane, int wr, int wc, int fr, int fq) {
;     ...
;             } else if (gh == 8 || gh == 10) {
;               const float4 b4 = *(const float4*)(Tr + 4 * lane + 16);
;               const int i0r = (gh == 8 ? 0 : 16) + f0;
;               const int pos = tok_pos(grow);
;               const float4 c4 = *(const float4*)((const float*)(wsb + OFF_COS) + pos * 32 + i0r);
;               const float4 s4 = *(const float4*)((const float*)(wsb + OFF_SIN) + pos * 32 + i0r);
;               uint2 o1, o2;
;               o1.x = pack2((a.x * c4.x - b4.x * s4.x) * qs, (a.y * c4.y - b4.y * s4.y) * qs);
;               o1.y = pack2((a.z * c4.z - b4.z * s4.z) * qs, (a.w * c4.w - b4.w * s4.w) * qs);
;               o2.x = pack2((b4.x * c4.x + a.x * s4.x) * qs, (b4.y * c4.y + a.y * s4.y) * qs);
;               o2.y = pack2((b4.z * c4.z + a.z * s4.z) * qs, (b4.w * c4.w + a.w * s4.w) * qs);
;               *(uint2*)(o + 128 + i0r) = o1;
;               *(uint2*)(o + 160 + i0r) = o2;
.LBB0_774:
	s_andn2_b64 s[22:23], s[30:31], exec
	s_and_b64 s[30:31], s[4:5], exec
	s_or_b64 s[30:31], s[22:23], s[30:31]
	s_or_b64 exec, exec, s[20:21]
	s_mov_b64 s[22:23], 0
	s_and_saveexec_b64 s[20:21], s[30:31]
	s_cbranch_execz .LBB0_777
	s_cmp_lt_i32 s44, 0x10000
	s_movk_i32 s22, 0xffd
	s_cselect_b32 s22, s22, 0x7fd
	s_and_b32 s22, s22, s44
	s_lshl_b32 s44, s22, 7
	v_lshl_add_u64 v[108:109], v[74:75], 0, s[44:45]
	v_lshl_add_u64 v[112:113], v[76:77], 0, s[44:45]
	ds_read_b128 v[84:87], v81 offset:64
	global_load_dwordx4 v[108:111], v[108:109], off
	s_nop 0
	global_load_dwordx4 v[112:115], v[112:113], off
	v_lshlrev_b32_e32 v148, 1, v72
	s_mov_b64 s[22:23], exec
	s_waitcnt vmcnt(0) lgkmcnt(0)
	v_pk_mul_f32 v[118:119], v[84:85], v[112:113]
	s_nop 0
	v_pk_fma_f32 v[118:119], v[64:65], v[108:109], v[118:119] neg_lo:[0,0,1] neg_hi:[0,0,1]
	v_pk_mul_f32 v[64:65], v[64:65], v[112:113]
	v_pk_mul_f32 v[116:117], v[86:87], v[114:115]
	v_pk_fma_f32 v[64:65], v[84:85], v[108:109], v[64:65]
	v_pk_fma_f32 v[116:117], v[66:67], v[110:111], v[116:117] neg_lo:[0,0,1] neg_hi:[0,0,1]
	v_pk_mul_f32 v[64:65], v[88:89], v[64:65] op_sel_hi:[0,1]
	v_pk_mul_f32 v[84:85], v[66:67], v[114:115]
	v_mov_b32_e32 v66, v87
	v_mov_b32_e32 v114, v111
	v_cvt_pk_bf16_f32 v81, v64, v65
	v_pk_mul_f32 v[64:65], v[86:87], v[110:111]
	v_pk_mul_f32 v[66:67], v[66:67], v[114:115]
	v_pk_mul_f32 v[116:117], v[88:89], v[116:117] op_sel_hi:[0,1]
	v_mov_b32_e32 v65, v66
	v_mov_b32_e32 v85, v67
	v_pk_add_f32 v[64:65], v[64:65], v[84:85]
	v_pk_mul_f32 v[118:119], v[88:89], v[118:119] op_sel_hi:[0,1]
	v_pk_mul_f32 v[84:85], v[88:89], v[64:65] op_sel_hi:[0,1]
	v_lshl_add_u64 v[64:65], v[90:91], 0, v[148:149]
	v_cvt_pk_bf16_f32 v117, v116, v117
	v_cvt_pk_bf16_f32 v116, v118, v119
	v_lshl_add_u64 v[86:87], v[64:65], 0, s[42:43]
	global_store_dwordx2 v[64:65], v[116:117], off offset:256
	global_store_dword v[64:65], v81, off offset:320

; template <int EPI, int TS, bool VT>
; DEVI void gemm_epilogue(const Params& p, char* smem, f32x4 (&acc)[2][2][4][2], int m0, int n0, float scale, const float* ssin,
;                         float* ssout, u16* xbout, int wid, int lane, int wr, int wc, int fr, int fq) {
;     ...
;             } else if (gh == 8 || gh == 10) {
;               const float4 b4 = *(const float4*)(Tr + 4 * lane + 16);
;               const int i0r = (gh == 8 ? 0 : 16) + f0;
;               const int pos = tok_pos(grow);
;               const float4 c4 = *(const float4*)((const float*)(wsb + OFF_COS) + pos * 32 + i0r);
;               const float4 s4 = *(const float4*)((const float*)(wsb + OFF_SIN) + pos * 32 + i0r);
;               uint2 o1, o2;
;               o1.x = pack2((a.x * c4.x - b4.x * s4.x) * qs, (a.y * c4.y - b4.y * s4.y) * qs);
;               o1.y = pack2((a.z * c4.z - b4.z * s4.z) * qs, (a.w * c4.w - b4.w * s4.w) * qs);
;               o2.x = pack2((b4.x * c4.x + a.x * s4.x) * qs, (b4.y * c4.y + a.y * s4.y) * qs);
;               o2.y = pack2((b4.z * c4.z + a.z * s4.z) * qs, (b4.w * c4.w + a.w * s4.w) * qs);
;               *(uint2*)(o + 128 + i0r) = o1;
;               *(uint2*)(o + 160 + i0r) = o2;
.LBB0_786:
	s_andn2_b64 s[22:23], s[30:31], exec
	s_and_b64 s[30:31], s[4:5], exec
	s_or_b64 s[30:31], s[22:23], s[30:31]
	s_or_b64 exec, exec, s[20:21]
	s_mov_b64 s[22:23], 0
	s_and_saveexec_b64 s[20:21], s[30:31]
	s_cbranch_execz .LBB0_789
	s_cmp_lt_i32 s44, 0x10000
	s_movk_i32 s22, 0xffe
	s_cselect_b32 s22, s22, 0x7fe
	s_and_b32 s22, s22, s44
	s_lshl_b32 s44, s22, 7
	v_lshl_add_u64 v[108:109], v[74:75], 0, s[44:45]
	v_lshl_add_u64 v[112:113], v[76:77], 0, s[44:45]
	ds_read_b128 v[84:87], v81 offset:64
	global_load_dwordx4 v[108:111], v[108:109], off
	s_nop 0
	global_load_dwordx4 v[112:115], v[112:113], off
	v_lshlrev_b32_e32 v148, 1, v72
	s_mov_b64 s[22:23], exec
	s_waitcnt vmcnt(0) lgkmcnt(0)
	v_pk_mul_f32 v[118:119], v[84:85], v[112:113]
	s_nop 0
	v_pk_fma_f32 v[118:119], v[64:65], v[108:109], v[118:119] neg_lo:[0,0,1] neg_hi:[0,0,1]
	v_pk_mul_f32 v[64:65], v[64:65], v[112:113]
	v_pk_mul_f32 v[116:117], v[86:87], v[114:115]
	v_pk_fma_f32 v[64:65], v[84:85], v[108:109], v[64:65]
	v_pk_fma_f32 v[116:117], v[66:67], v[110:111], v[116:117] neg_lo:[0,0,1] neg_hi:[0,0,1]
	v_pk_mul_f32 v[64:65], v[88:89], v[64:65] op_sel_hi:[0,1]
	v_pk_mul_f32 v[84:85], v[66:67], v[114:115]
	v_mov_b32_e32 v66, v87
	v_mov_b32_e32 v114, v111
	v_cvt_pk_bf16_f32 v81, v64, v65
	v_pk_mul_f32 v[64:65], v[86:87], v[110:111]
	v_pk_mul_f32 v[66:67], v[66:67], v[114:115]
	v_pk_mul_f32 v[116:117], v[88:89], v[116:117] op_sel_hi:[0,1]
	v_mov_b32_e32 v65, v66
	v_mov_b32_e32 v85, v67
	v_pk_add_f32 v[64:65], v[64:65], v[84:85]
	v_pk_mul_f32 v[118:119], v[88:89], v[118:119] op_sel_hi:[0,1]
	v_pk_mul_f32 v[84:85], v[88:89], v[64:65] op_sel_hi:[0,1]
	v_lshl_add_u64 v[64:65], v[90:91], 0, v[148:149]
	v_cvt_pk_bf16_f32 v117, v116, v117
	v_cvt_pk_bf16_f32 v116, v118, v119
	v_lshl_add_u64 v[86:87], v[64:65], 0, s[42:43]
	global_store_dwordx2 v[64:65], v[116:117], off offset:256
	global_store_dword v[64:65], v81, off offset:320

; template <int EPI, int TS, bool VT>
; DEVI void gemm_epilogue(const Params& p, char* smem, f32x4 (&acc)[2][2][4][2], int m0, int n0, float scale, const float* ssin,
;                         float* ssout, u16* xbout, int wid, int lane, int wr, int wc, int fr, int fq) {
;     ...
;             if (gh < 8) {
;               uint2 ov;
;               ov.x = pack2(a.x * qs, a.y * qs);
;               ov.y = pack2(a.z * qs, a.w * qs);
;               *(uint2*)(o + gh * 16 + f0) = ov;
.LBB0_796:
	s_waitcnt lgkmcnt(0)
	v_pk_mul_f32 v[64:65], v[64:65], v[88:89] op_sel_hi:[1,0]
	v_mov_b32_e32 v81, v149
	v_cvt_pk_bf16_f32 v99, v64, v65
	v_lshl_add_u64 v[64:65], v[78:79], 1, v[90:91]
	v_pk_mul_f32 v[84:85], v[88:89], v[66:67] op_sel_hi:[0,1]
	v_lshl_add_u64 v[86:87], v[64:65], 0, v[80:81]
	s_or_b64 s[20:21], s[20:21], exec
	global_store_dword v[86:87], v99, off
	s_or_b64 exec, exec, s[14:15]
	s_and_saveexec_b64 s[14:15], s[20:21]
	s_cbranch_execz .LBB0_707
	s_branch .LBB0_803

; template <int EPI, int TS, bool VT>
; DEVI void gemm_epilogue(const Params& p, char* smem, f32x4 (&acc)[2][2][4][2], int m0, int n0, float scale, const float* ssin,
;                         float* ssout, u16* xbout, int wid, int lane, int wr, int wc, int fr, int fq) {
;     ...
;             } else if (gh == 8 || gh == 10) {
;               const float4 b4 = *(const float4*)(Tr + 4 * lane + 16);
;               const int i0r = (gh == 8 ? 0 : 16) + f0;
;               const int pos = tok_pos(grow);
;               const float4 c4 = *(const float4*)((const float*)(wsb + OFF_COS) + pos * 32 + i0r);
;               const float4 s4 = *(const float4*)((const float*)(wsb + OFF_SIN) + pos * 32 + i0r);
;               uint2 o1, o2;
;               o1.x = pack2((a.x * c4.x - b4.x * s4.x) * qs, (a.y * c4.y - b4.y * s4.y) * qs);
;               o1.y = pack2((a.z * c4.z - b4.z * s4.z) * qs, (a.w * c4.w - b4.w * s4.w) * qs);
;               o2.x = pack2((b4.x * c4.x + a.x * s4.x) * qs, (b4.y * c4.y + a.y * s4.y) * qs);
;               o2.y = pack2((b4.z * c4.z + a.z * s4.z) * qs, (b4.w * c4.w + a.w * s4.w) * qs);
;               *(uint2*)(o + 128 + i0r) = o1;
;               *(uint2*)(o + 160 + i0r) = o2;
.LBB0_798:
	s_andn2_b64 s[22:23], s[30:31], exec
	s_and_b64 s[30:31], s[4:5], exec
	s_or_b64 s[30:31], s[22:23], s[30:31]
	s_or_b64 exec, exec, s[20:21]
	s_mov_b64 s[22:23], 0
	s_and_saveexec_b64 s[20:21], s[30:31]
	s_cbranch_execz .LBB0_801
	s_cmp_lt_i32 s44, 0x10000
	s_movk_i32 s22, 0xfff
	s_cselect_b32 s22, s22, 0x7ff
	s_and_b32 s22, s22, s44
	s_lshl_b32 s44, s22, 7
	v_lshl_add_u64 v[108:109], v[74:75], 0, s[44:45]
	v_lshl_add_u64 v[112:113], v[76:77], 0, s[44:45]
	ds_read_b128 v[84:87], v81 offset:64
	global_load_dwordx4 v[108:111], v[108:109], off
	s_nop 0
	global_load_dwordx4 v[112:115], v[112:113], off
	v_lshlrev_b32_e32 v148, 1, v72
	s_mov_b64 s[22:23], exec
	s_waitcnt vmcnt(0) lgkmcnt(0)
	v_pk_mul_f32 v[118:119], v[84:85], v[112:113]
	s_nop 0
	v_pk_fma_f32 v[118:119], v[64:65], v[108:109], v[118:119] neg_lo:[0,0,1] neg_hi:[0,0,1]
	v_pk_mul_f32 v[64:65], v[64:65], v[112:113]
	v_pk_mul_f32 v[116:117], v[86:87], v[114:115]
	v_pk_fma_f32 v[64:65], v[84:85], v[108:109], v[64:65]
	v_pk_fma_f32 v[116:117], v[66:67], v[110:111], v[116:117] neg_lo:[0,0,1] neg_hi:[0,0,1]
	v_pk_mul_f32 v[64:65], v[88:89], v[64:65] op_sel_hi:[0,1]
	v_pk_mul_f32 v[84:85], v[66:67], v[114:115]
	v_mov_b32_e32 v66, v87
	v_mov_b32_e32 v114, v111
	v_cvt_pk_bf16_f32 v81, v64, v65
	v_pk_mul_f32 v[64:65], v[86:87], v[110:111]
	v_pk_mul_f32 v[66:67], v[66:67], v[114:115]
	v_pk_mul_f32 v[116:117], v[88:89], v[116:117] op_sel_hi:[0,1]
	v_mov_b32_e32 v65, v66
	v_mov_b32_e32 v85, v67
	v_pk_add_f32 v[64:65], v[64:65], v[84:85]
	v_pk_mul_f32 v[118:119], v[88:89], v[118:119] op_sel_hi:[0,1]
	v_pk_mul_f32 v[84:85], v[88:89], v[64:65] op_sel_hi:[0,1]
	v_lshl_add_u64 v[64:65], v[90:91], 0, v[148:149]
	v_cvt_pk_bf16_f32 v117, v116, v117
	v_cvt_pk_bf16_f32 v116, v118, v119
	v_lshl_add_u64 v[86:87], v[64:65], 0, s[42:43]
	global_store_dwordx2 v[64:65], v[116:117], off offset:256
	global_store_dword v[64:65], v81, off offset:320

; template <int EPI, int TS, bool VT>
; DEVI void gemm_epilogue(const Params& p, char* smem, f32x4 (&acc)[2][2][4][2], int m0, int n0, float scale, const float* ssin,
;                         float* ssout, u16* xbout, int wid, int lane, int wr, int wc, int fr, int fq) {
;     ...
;   for (int ai = 0; ai < 2; ++ai) {
;     {
;       float* tw = T + (wr * 64 + fq * 4) * TS + wc * 32 + fr;
; #pragma unroll
;       for (int m = 0; m < 4; ++m)
; #pragma unroll
;         for (int j = 0; j < 4; ++j)
; #pragma unroll
;           for (int v = 0; v < 4; ++v) tw[(m * 16 + j) * TS + (v >> 1) * 128 + (v & 1) * 16] = acc[ai][v >> 1][m][v & 1][j];
;     }
;     __syncthreads();
;     const int r0 = wid * 16;
;     const int g0 = m0 + ai * 128 + r0;
;     if constexpr (!VT) {
;       float rsv = 1.f;
;       if constexpr (EPI == E_PLEGATE || EPI == E_F32 || EPI == E_SWIGLU || EPI == E_GLAIN)
;         rsv = rsqrtf(ssin[g0 + (lane & 15)] * (1.f / 1024.f) + EPS);
;       if constexpr (EPI == E_QROPE) rsv = rsqrtf(ssin[g0 + (lane & 15)] * (1.f / 384.f) + EPS);
.LBB0_803:
	s_waitcnt lgkmcnt(0)
	v_cvt_pk_bf16_f32 v64, v84, v85
	global_store_dword v[86:87], v64, off offset:4
	s_branch .LBB0_707
.LBB0_804:
	s_addk_i32 s65, 0x80
	s_waitcnt lgkmcnt(0)
	s_barrier
	ds_write2_b32 v129, v24, v28 offset1:16
	ds_write2_b32 v129, v56, v60 offset0:128 offset1:144
	ds_write2_b32 v92, v25, v29 offset0:4 offset1:20
	ds_write2_b32 v92, v57, v61 offset0:132 offset1:148
	ds_write2_b32 v93, v26, v30 offset0:8 offset1:24
	ds_write2_b32 v93, v58, v62 offset0:136 offset1:152
	ds_write2_b32 v94, v27, v31 offset0:12 offset1:28
	ds_write2_b32 v94, v59, v63 offset0:140 offset1:156
	ds_write2_b32 v95, v16, v20 offset0:64 offset1:80
	ds_write2_b32 v95, v48, v52 offset0:192 offset1:208
	ds_write2_b32 v100, v17, v21 offset0:68 offset1:84
	ds_write2_b32 v100, v49, v53 offset0:196 offset1:212
	ds_write2_b32 v101, v18, v22 offset0:72 offset1:88
	ds_write2_b32 v101, v50, v54 offset0:200 offset1:216
	ds_write2_b32 v102, v19, v23 offset0:76 offset1:92
	ds_write2_b32 v102, v51, v55 offset0:204 offset1:220
	ds_write2_b32 v83, v8, v12 offset0:128 offset1:144
	ds_write2_b32 v103, v40, v44 offset1:16
	ds_write2_b32 v103, v9, v13 offset0:132 offset1:148
	ds_write2_b32 v73, v41, v45 offset0:4 offset1:20
	ds_write2_b32 v73, v10, v14 offset0:136 offset1:152
	ds_write2_b32 v104, v42, v46 offset0:8 offset1:24
	ds_write2_b32 v104, v11, v15 offset0:140 offset1:156
	ds_write2_b32 v105, v43, v47 offset0:12 offset1:28
	ds_write2_b32 v106, v0, v4 offset0:192 offset1:208
	ds_write2_b32 v107, v32, v36 offset0:64 offset1:80
	ds_write2_b32 v107, v1, v5 offset0:196 offset1:212
	ds_write2_b32 v96, v33, v37 offset0:68 offset1:84
	ds_write2_b32 v96, v2, v6 offset0:200 offset1:216
	ds_write2_b32 v89, v34, v38 offset0:72 offset1:88
	ds_write2_b32 v89, v3, v7 offset0:204 offset1:220
	ds_write2_b32 v97, v35, v39 offset0:76 offset1:92
	v_or_b32_e32 v0, s65, v128
	v_ashrrev_i32_e32 v1, 31, v0
	v_lshl_add_u64 v[0:1], v[0:1], 2, s[18:19]
	s_waitcnt lgkmcnt(0)
	s_barrier
	global_load_dword v0, v[0:1], off
	s_mov_b32 s66, 0
	s_mov_b64 s[12:13], -1
	s_waitcnt vmcnt(0) lgkmcnt(0)
	v_fmamk_f32 v0, v0, 0x3b2aaaab, v150
	v_mul_f32_e32 v1, 0x4b800000, v0
	v_cmp_gt_f32_e32 vcc, s29, v0
	s_nop 1
	v_cndmask_b32_e32 v0, v0, v1, vcc
	v_rsq_f32_e32 v0, v0
	s_nop 0
	v_mul_f32_e32 v1, 0x45800000, v0
	v_cndmask_b32_e32 v9, v0, v1, vcc
	s_branch .LBB0_806

; template <int EPI, int TS, bool VT>
; DEVI void gemm_epilogue(const Params& p, char* smem, f32x4 (&acc)[2][2][4][2], int m0, int n0, float scale, const float* ssin,
;                         float* ssout, u16* xbout, int wid, int lane, int wr, int wc, int fr, int fq) {
;     ...
;             if (gh < 8) {
;               uint2 ov;
;               ov.x = pack2(a.x * qs, a.y * qs);
;               ov.y = pack2(a.z * qs, a.w * qs);
;               *(uint2*)(o + gh * 16 + f0) = ov;
.LBB0_810:
	s_waitcnt lgkmcnt(0)
	v_pk_mul_f32 v[0:1], v[0:1], v[8:9] op_sel_hi:[1,0]
	v_mov_b32_e32 v81, v149
	v_cvt_pk_bf16_f32 v12, v0, v1
	v_lshl_add_u64 v[0:1], v[78:79], 1, v[10:11]
	v_pk_mul_f32 v[4:5], v[8:9], v[2:3] op_sel_hi:[0,1]
	v_lshl_add_u64 v[6:7], v[0:1], 0, v[80:81]
	s_or_b64 s[20:21], s[20:21], exec
	global_store_dword v[6:7], v12, off
	s_or_b64 exec, exec, s[14:15]
	s_and_saveexec_b64 s[14:15], s[20:21]
	s_cbranch_execnz .LBB0_817
	s_branch .LBB0_818

; template <int EPI, int TS, bool VT>
; DEVI void gemm_epilogue(const Params& p, char* smem, f32x4 (&acc)[2][2][4][2], int m0, int n0, float scale, const float* ssin,
;                         float* ssout, u16* xbout, int wid, int lane, int wr, int wc, int fr, int fq) {
;     ...
;             } else if (gh == 8 || gh == 10) {
;               const float4 b4 = *(const float4*)(Tr + 4 * lane + 16);
;               const int i0r = (gh == 8 ? 0 : 16) + f0;
;               const int pos = tok_pos(grow);
;               const float4 c4 = *(const float4*)((const float*)(wsb + OFF_COS) + pos * 32 + i0r);
;               const float4 s4 = *(const float4*)((const float*)(wsb + OFF_SIN) + pos * 32 + i0r);
;               uint2 o1, o2;
;               o1.x = pack2((a.x * c4.x - b4.x * s4.x) * qs, (a.y * c4.y - b4.y * s4.y) * qs);
;               o1.y = pack2((a.z * c4.z - b4.z * s4.z) * qs, (a.w * c4.w - b4.w * s4.w) * qs);
;               o2.x = pack2((b4.x * c4.x + a.x * s4.x) * qs, (b4.y * c4.y + a.y * s4.y) * qs);
;               o2.y = pack2((b4.z * c4.z + a.z * s4.z) * qs, (b4.w * c4.w + a.w * s4.w) * qs);
;               *(uint2*)(o + 128 + i0r) = o1;
;               *(uint2*)(o + 160 + i0r) = o2;
.LBB0_812:
	s_andn2_b64 s[22:23], s[30:31], exec
	s_and_b64 s[30:31], s[4:5], exec
	s_or_b64 s[30:31], s[22:23], s[30:31]
	s_or_b64 exec, exec, s[20:21]
	s_mov_b64 s[22:23], 0
	s_and_saveexec_b64 s[20:21], s[30:31]
	s_cbranch_execz .LBB0_815
	s_cmp_lt_i32 s44, 0x10000
	s_movk_i32 s22, 0xff8
	s_cselect_b32 s22, s22, 0x7f8
	s_and_b32 s22, s22, s44
	s_lshl_b32 s44, s22, 7
	v_lshl_add_u64 v[14:15], v[74:75], 0, s[44:45]
	v_lshl_add_u64 v[16:17], v[76:77], 0, s[44:45]
	ds_read_b128 v[4:7], v12 offset:64
	global_load_dwordx4 v[12:15], v[14:15], off
	s_nop 0
	global_load_dwordx4 v[16:19], v[16:17], off
	v_lshlrev_b32_e32 v148, 1, v72
	s_mov_b64 s[22:23], exec
	s_waitcnt vmcnt(0) lgkmcnt(0)
	v_pk_mul_f32 v[22:23], v[4:5], v[16:17]
	s_nop 0
	v_pk_fma_f32 v[22:23], v[0:1], v[12:13], v[22:23] neg_lo:[0,0,1] neg_hi:[0,0,1]
	v_pk_mul_f32 v[0:1], v[0:1], v[16:17]
	v_pk_mul_f32 v[20:21], v[6:7], v[18:19]
	v_pk_fma_f32 v[0:1], v[4:5], v[12:13], v[0:1]
	v_pk_fma_f32 v[20:21], v[2:3], v[14:15], v[20:21] neg_lo:[0,0,1] neg_hi:[0,0,1]
	v_pk_mul_f32 v[0:1], v[8:9], v[0:1] op_sel_hi:[0,1]
	v_pk_mul_f32 v[4:5], v[2:3], v[18:19]
	v_mov_b32_e32 v2, v7
	v_mov_b32_e32 v18, v15
	v_cvt_pk_bf16_f32 v12, v0, v1
	v_pk_mul_f32 v[0:1], v[6:7], v[14:15]
	v_pk_mul_f32 v[2:3], v[2:3], v[18:19]
	v_pk_mul_f32 v[20:21], v[8:9], v[20:21] op_sel_hi:[0,1]
	v_mov_b32_e32 v1, v2
	v_mov_b32_e32 v5, v3
	v_pk_add_f32 v[0:1], v[0:1], v[4:5]
	v_pk_mul_f32 v[22:23], v[8:9], v[22:23] op_sel_hi:[0,1]
	v_pk_mul_f32 v[4:5], v[8:9], v[0:1] op_sel_hi:[0,1]
	v_lshl_add_u64 v[0:1], v[10:11], 0, v[148:149]
	v_cvt_pk_bf16_f32 v21, v20, v21
	v_cvt_pk_bf16_f32 v20, v22, v23
	v_lshl_add_u64 v[6:7], v[0:1], 0, s[42:43]
	global_store_dwordx2 v[0:1], v[20:21], off offset:256
	global_store_dword v[0:1], v12, off offset:320

; template <int EPI, int TS, bool VT>
; DEVI void gemm_epilogue(const Params& p, char* smem, f32x4 (&acc)[2][2][4][2], int m0, int n0, float scale, const float* ssin,
;                         float* ssout, u16* xbout, int wid, int lane, int wr, int wc, int fr, int fq) {
;     ...
;             if (gh < 8) {
;               uint2 ov;
;               ov.x = pack2(a.x * qs, a.y * qs);
;               ov.y = pack2(a.z * qs, a.w * qs);
;               *(uint2*)(o + gh * 16 + f0) = ov;
;             } else if (gh == 8 || gh == 10) {
;               const float4 b4 = *(const float4*)(Tr + 4 * lane + 16);
;               const int i0r = (gh == 8 ? 0 : 16) + f0;
;               const int pos = tok_pos(grow);
;               const float4 c4 = *(const float4*)((const float*)(wsb + OFF_COS) + pos * 32 + i0r);
;               const float4 s4 = *(const float4*)((const float*)(wsb + OFF_SIN) + pos * 32 + i0r);
;               uint2 o1, o2;
;               o1.x = pack2((a.x * c4.x - b4.x * s4.x) * qs, (a.y * c4.y - b4.y * s4.y) * qs);
;               o1.y = pack2((a.z * c4.z - b4.z * s4.z) * qs, (a.w * c4.w - b4.w * s4.w) * qs);
;               o2.x = pack2((b4.x * c4.x + a.x * s4.x) * qs, (b4.y * c4.y + a.y * s4.y) * qs);
;               o2.y = pack2((b4.z * c4.z + a.z * s4.z) * qs, (b4.w * c4.w + a.w * s4.w) * qs);
;               *(uint2*)(o + 128 + i0r) = o1;
;               *(uint2*)(o + 160 + i0r) = o2;
.LBB0_817:
	s_waitcnt lgkmcnt(0)
	v_cvt_pk_bf16_f32 v0, v4, v5
	global_store_dword v[6:7], v0, off offset:4

; template <int EPI, int TS, bool VT>
; DEVI void gemm_epilogue(const Params& p, char* smem, f32x4 (&acc)[2][2][4][2], int m0, int n0, float scale, const float* ssin,
;                         float* ssout, u16* xbout, int wid, int lane, int wr, int wc, int fr, int fq) {
;     ...
;             } else if (gh == 8 || gh == 10) {
;               const float4 b4 = *(const float4*)(Tr + 4 * lane + 16);
;               const int i0r = (gh == 8 ? 0 : 16) + f0;
;               const int pos = tok_pos(grow);
;               const float4 c4 = *(const float4*)((const float*)(wsb + OFF_COS) + pos * 32 + i0r);
;               const float4 s4 = *(const float4*)((const float*)(wsb + OFF_SIN) + pos * 32 + i0r);
;               uint2 o1, o2;
;               o1.x = pack2((a.x * c4.x - b4.x * s4.x) * qs, (a.y * c4.y - b4.y * s4.y) * qs);
;               o1.y = pack2((a.z * c4.z - b4.z * s4.z) * qs, (a.w * c4.w - b4.w * s4.w) * qs);
;               o2.x = pack2((b4.x * c4.x + a.x * s4.x) * qs, (b4.y * c4.y + a.y * s4.y) * qs);
;               o2.y = pack2((b4.z * c4.z + a.z * s4.z) * qs, (b4.w * c4.w + a.w * s4.w) * qs);
;               *(uint2*)(o + 128 + i0r) = o1;
;               *(uint2*)(o + 160 + i0r) = o2;
.LBB0_824:
	s_andn2_b64 s[22:23], s[30:31], exec
	s_and_b64 s[30:31], s[4:5], exec
	s_or_b64 s[30:31], s[22:23], s[30:31]
	s_or_b64 exec, exec, s[20:21]
	s_mov_b64 s[22:23], 0
	s_and_saveexec_b64 s[20:21], s[30:31]
	s_cbranch_execz .LBB0_827
	s_cmp_lt_i32 s44, 0x10000
	s_movk_i32 s22, 0xff9
	s_cselect_b32 s22, s22, 0x7f9
	s_and_b32 s22, s22, s44
	s_lshl_b32 s44, s22, 7
	v_lshl_add_u64 v[14:15], v[74:75], 0, s[44:45]
	v_lshl_add_u64 v[16:17], v[76:77], 0, s[44:45]
	ds_read_b128 v[4:7], v12 offset:64
	global_load_dwordx4 v[12:15], v[14:15], off
	s_nop 0
	global_load_dwordx4 v[16:19], v[16:17], off
	v_lshlrev_b32_e32 v148, 1, v72
	s_mov_b64 s[22:23], exec
	s_waitcnt vmcnt(0) lgkmcnt(0)
	v_pk_mul_f32 v[22:23], v[4:5], v[16:17]
	s_nop 0
	v_pk_fma_f32 v[22:23], v[0:1], v[12:13], v[22:23] neg_lo:[0,0,1] neg_hi:[0,0,1]
	v_pk_mul_f32 v[0:1], v[0:1], v[16:17]
	v_pk_mul_f32 v[20:21], v[6:7], v[18:19]
	v_pk_fma_f32 v[0:1], v[4:5], v[12:13], v[0:1]
	v_pk_fma_f32 v[20:21], v[2:3], v[14:15], v[20:21] neg_lo:[0,0,1] neg_hi:[0,0,1]
	v_pk_mul_f32 v[0:1], v[8:9], v[0:1] op_sel_hi:[0,1]
	v_pk_mul_f32 v[4:5], v[2:3], v[18:19]
	v_mov_b32_e32 v2, v7
	v_mov_b32_e32 v18, v15
	v_cvt_pk_bf16_f32 v12, v0, v1
	v_pk_mul_f32 v[0:1], v[6:7], v[14:15]
	v_pk_mul_f32 v[2:3], v[2:3], v[18:19]
	v_pk_mul_f32 v[20:21], v[8:9], v[20:21] op_sel_hi:[0,1]
	v_mov_b32_e32 v1, v2
	v_mov_b32_e32 v5, v3
	v_pk_add_f32 v[0:1], v[0:1], v[4:5]
	v_pk_mul_f32 v[22:23], v[8:9], v[22:23] op_sel_hi:[0,1]
	v_pk_mul_f32 v[4:5], v[8:9], v[0:1] op_sel_hi:[0,1]
	v_lshl_add_u64 v[0:1], v[10:11], 0, v[148:149]
	v_cvt_pk_bf16_f32 v21, v20, v21
	v_cvt_pk_bf16_f32 v20, v22, v23
	v_lshl_add_u64 v[6:7], v[0:1], 0, s[42:43]
	global_store_dwordx2 v[0:1], v[20:21], off offset:256
	global_store_dword v[0:1], v12, off offset:320

; template <int EPI, int TS, bool VT>
; DEVI void gemm_epilogue(const Params& p, char* smem, f32x4 (&acc)[2][2][4][2], int m0, int n0, float scale, const float* ssin,
;                         float* ssout, u16* xbout, int wid, int lane, int wr, int wc, int fr, int fq) {
;     ...
;             } else if (gh == 8 || gh == 10) {
;               const float4 b4 = *(const float4*)(Tr + 4 * lane + 16);
;               const int i0r = (gh == 8 ? 0 : 16) + f0;
;               const int pos = tok_pos(grow);
;               const float4 c4 = *(const float4*)((const float*)(wsb + OFF_COS) + pos * 32 + i0r);
;               const float4 s4 = *(const float4*)((const float*)(wsb + OFF_SIN) + pos * 32 + i0r);
;               uint2 o1, o2;
;               o1.x = pack2((a.x * c4.x - b4.x * s4.x) * qs, (a.y * c4.y - b4.y * s4.y) * qs);
;               o1.y = pack2((a.z * c4.z - b4.z * s4.z) * qs, (a.w * c4.w - b4.w * s4.w) * qs);
;               o2.x = pack2((b4.x * c4.x + a.x * s4.x) * qs, (b4.y * c4.y + a.y * s4.y) * qs);
;               o2.y = pack2((b4.z * c4.z + a.z * s4.z) * qs, (b4.w * c4.w + a.w * s4.w) * qs);
;               *(uint2*)(o + 128 + i0r) = o1;
;               *(uint2*)(o + 160 + i0r) = o2;
.LBB0_836:
	s_andn2_b64 s[22:23], s[30:31], exec
	s_and_b64 s[30:31], s[4:5], exec
	s_or_b64 s[30:31], s[22:23], s[30:31]
	s_or_b64 exec, exec, s[20:21]
	s_mov_b64 s[22:23], 0
	s_and_saveexec_b64 s[20:21], s[30:31]
	s_cbranch_execz .LBB0_839
	s_cmp_lt_i32 s44, 0x10000
	s_movk_i32 s22, 0xffa
	s_cselect_b32 s22, s22, 0x7fa
	s_and_b32 s22, s22, s44
	s_lshl_b32 s44, s22, 7
	v_lshl_add_u64 v[14:15], v[74:75], 0, s[44:45]
	v_lshl_add_u64 v[16:17], v[76:77], 0, s[44:45]
	ds_read_b128 v[4:7], v12 offset:64
	global_load_dwordx4 v[12:15], v[14:15], off
	s_nop 0
	global_load_dwordx4 v[16:19], v[16:17], off
	v_lshlrev_b32_e32 v148, 1, v72
	s_mov_b64 s[22:23], exec
	s_waitcnt vmcnt(0) lgkmcnt(0)
	v_pk_mul_f32 v[22:23], v[4:5], v[16:17]
	s_nop 0
	v_pk_fma_f32 v[22:23], v[0:1], v[12:13], v[22:23] neg_lo:[0,0,1] neg_hi:[0,0,1]
	v_pk_mul_f32 v[0:1], v[0:1], v[16:17]
	v_pk_mul_f32 v[20:21], v[6:7], v[18:19]
	v_pk_fma_f32 v[0:1], v[4:5], v[12:13], v[0:1]
	v_pk_fma_f32 v[20:21], v[2:3], v[14:15], v[20:21] neg_lo:[0,0,1] neg_hi:[0,0,1]
	v_pk_mul_f32 v[0:1], v[8:9], v[0:1] op_sel_hi:[0,1]
	v_pk_mul_f32 v[4:5], v[2:3], v[18:19]
	v_mov_b32_e32 v2, v7
	v_mov_b32_e32 v18, v15
	v_cvt_pk_bf16_f32 v12, v0, v1
	v_pk_mul_f32 v[0:1], v[6:7], v[14:15]
	v_pk_mul_f32 v[2:3], v[2:3], v[18:19]
	v_pk_mul_f32 v[20:21], v[8:9], v[20:21] op_sel_hi:[0,1]
	v_mov_b32_e32 v1, v2
	v_mov_b32_e32 v5, v3
	v_pk_add_f32 v[0:1], v[0:1], v[4:5]
	v_pk_mul_f32 v[22:23], v[8:9], v[22:23] op_sel_hi:[0,1]
	v_pk_mul_f32 v[4:5], v[8:9], v[0:1] op_sel_hi:[0,1]
	v_lshl_add_u64 v[0:1], v[10:11], 0, v[148:149]
	v_cvt_pk_bf16_f32 v21, v20, v21
	v_cvt_pk_bf16_f32 v20, v22, v23
	v_lshl_add_u64 v[6:7], v[0:1], 0, s[42:43]
	global_store_dwordx2 v[0:1], v[20:21], off offset:256
	global_store_dword v[0:1], v12, off offset:320

; template <int EPI, int TS, bool VT>
; DEVI void gemm_epilogue(const Params& p, char* smem, f32x4 (&acc)[2][2][4][2], int m0, int n0, float scale, const float* ssin,
;                         float* ssout, u16* xbout, int wid, int lane, int wr, int wc, int fr, int fq) {
;     ...
;             } else if (gh == 8 || gh == 10) {
;               const float4 b4 = *(const float4*)(Tr + 4 * lane + 16);
;               const int i0r = (gh == 8 ? 0 : 16) + f0;
;               const int pos = tok_pos(grow);
;               const float4 c4 = *(const float4*)((const float*)(wsb + OFF_COS) + pos * 32 + i0r);
;               const float4 s4 = *(const float4*)((const float*)(wsb + OFF_SIN) + pos * 32 + i0r);
;               uint2 o1, o2;
;               o1.x = pack2((a.x * c4.x - b4.x * s4.x) * qs, (a.y * c4.y - b4.y * s4.y) * qs);
;               o1.y = pack2((a.z * c4.z - b4.z * s4.z) * qs, (a.w * c4.w - b4.w * s4.w) * qs);
;               o2.x = pack2((b4.x * c4.x + a.x * s4.x) * qs, (b4.y * c4.y + a.y * s4.y) * qs);
;               o2.y = pack2((b4.z * c4.z + a.z * s4.z) * qs, (b4.w * c4.w + a.w * s4.w) * qs);
;               *(uint2*)(o + 128 + i0r) = o1;
;               *(uint2*)(o + 160 + i0r) = o2;
.LBB0_848:
	s_andn2_b64 s[22:23], s[30:31], exec
	s_and_b64 s[30:31], s[4:5], exec
	s_or_b64 s[30:31], s[22:23], s[30:31]
	s_or_b64 exec, exec, s[20:21]
	s_mov_b64 s[22:23], 0
	s_and_saveexec_b64 s[20:21], s[30:31]
	s_cbranch_execz .LBB0_851
	s_cmp_lt_i32 s44, 0x10000
	s_movk_i32 s22, 0xffb
	s_cselect_b32 s22, s22, 0x7fb
	s_and_b32 s22, s22, s44
	s_lshl_b32 s44, s22, 7
	v_lshl_add_u64 v[14:15], v[74:75], 0, s[44:45]
	v_lshl_add_u64 v[16:17], v[76:77], 0, s[44:45]
	ds_read_b128 v[4:7], v12 offset:64
	global_load_dwordx4 v[12:15], v[14:15], off
	s_nop 0
	global_load_dwordx4 v[16:19], v[16:17], off
	v_lshlrev_b32_e32 v148, 1, v72
	s_mov_b64 s[22:23], exec
	s_waitcnt vmcnt(0) lgkmcnt(0)
	v_pk_mul_f32 v[22:23], v[4:5], v[16:17]
	s_nop 0
	v_pk_fma_f32 v[22:23], v[0:1], v[12:13], v[22:23] neg_lo:[0,0,1] neg_hi:[0,0,1]
	v_pk_mul_f32 v[0:1], v[0:1], v[16:17]
	v_pk_mul_f32 v[20:21], v[6:7], v[18:19]
	v_pk_fma_f32 v[0:1], v[4:5], v[12:13], v[0:1]
	v_pk_fma_f32 v[20:21], v[2:3], v[14:15], v[20:21] neg_lo:[0,0,1] neg_hi:[0,0,1]
	v_pk_mul_f32 v[0:1], v[8:9], v[0:1] op_sel_hi:[0,1]
	v_pk_mul_f32 v[4:5], v[2:3], v[18:19]
	v_mov_b32_e32 v2, v7
	v_mov_b32_e32 v18, v15
	v_cvt_pk_bf16_f32 v12, v0, v1
	v_pk_mul_f32 v[0:1], v[6:7], v[14:15]
	v_pk_mul_f32 v[2:3], v[2:3], v[18:19]
	v_pk_mul_f32 v[20:21], v[8:9], v[20:21] op_sel_hi:[0,1]
	v_mov_b32_e32 v1, v2
	v_mov_b32_e32 v5, v3
	v_pk_add_f32 v[0:1], v[0:1], v[4:5]
	v_pk_mul_f32 v[22:23], v[8:9], v[22:23] op_sel_hi:[0,1]
	v_pk_mul_f32 v[4:5], v[8:9], v[0:1] op_sel_hi:[0,1]
	v_lshl_add_u64 v[0:1], v[10:11], 0, v[148:149]
	v_cvt_pk_bf16_f32 v21, v20, v21
	v_cvt_pk_bf16_f32 v20, v22, v23
	v_lshl_add_u64 v[6:7], v[0:1], 0, s[42:43]
	global_store_dwordx2 v[0:1], v[20:21], off offset:256
	global_store_dword v[0:1], v12, off offset:320

; template <int EPI, int TS, bool VT>
; DEVI void gemm_epilogue(const Params& p, char* smem, f32x4 (&acc)[2][2][4][2], int m0, int n0, float scale, const float* ssin,
;                         float* ssout, u16* xbout, int wid, int lane, int wr, int wc, int fr, int fq) {
;     ...
;             } else if (gh == 8 || gh == 10) {
;               const float4 b4 = *(const float4*)(Tr + 4 * lane + 16);
;               const int i0r = (gh == 8 ? 0 : 16) + f0;
;               const int pos = tok_pos(grow);
;               const float4 c4 = *(const float4*)((const float*)(wsb + OFF_COS) + pos * 32 + i0r);
;               const float4 s4 = *(const float4*)((const float*)(wsb + OFF_SIN) + pos * 32 + i0r);
;               uint2 o1, o2;
;               o1.x = pack2((a.x * c4.x - b4.x * s4.x) * qs, (a.y * c4.y - b4.y * s4.y) * qs);
;               o1.y = pack2((a.z * c4.z - b4.z * s4.z) * qs, (a.w * c4.w - b4.w * s4.w) * qs);
;               o2.x = pack2((b4.x * c4.x + a.x * s4.x) * qs, (b4.y * c4.y + a.y * s4.y) * qs);
;               o2.y = pack2((b4.z * c4.z + a.z * s4.z) * qs, (b4.w * c4.w + a.w * s4.w) * qs);
;               *(uint2*)(o + 128 + i0r) = o1;
;               *(uint2*)(o + 160 + i0r) = o2;
.LBB0_860:
	s_andn2_b64 s[22:23], s[30:31], exec
	s_and_b64 s[30:31], s[4:5], exec
	s_or_b64 s[30:31], s[22:23], s[30:31]
	s_or_b64 exec, exec, s[20:21]
	s_mov_b64 s[22:23], 0
	s_and_saveexec_b64 s[20:21], s[30:31]
	s_cbranch_execz .LBB0_863
	s_cmp_lt_i32 s44, 0x10000
	s_movk_i32 s22, 0xffc
	s_cselect_b32 s22, s22, 0x7fc
	s_and_b32 s22, s22, s44
	s_lshl_b32 s44, s22, 7
	v_lshl_add_u64 v[14:15], v[74:75], 0, s[44:45]
	v_lshl_add_u64 v[16:17], v[76:77], 0, s[44:45]
	ds_read_b128 v[4:7], v12 offset:64
	global_load_dwordx4 v[12:15], v[14:15], off
	s_nop 0
	global_load_dwordx4 v[16:19], v[16:17], off
	v_lshlrev_b32_e32 v148, 1, v72
	s_mov_b64 s[22:23], exec
	s_waitcnt vmcnt(0) lgkmcnt(0)
	v_pk_mul_f32 v[22:23], v[4:5], v[16:17]
	s_nop 0
	v_pk_fma_f32 v[22:23], v[0:1], v[12:13], v[22:23] neg_lo:[0,0,1] neg_hi:[0,0,1]
	v_pk_mul_f32 v[0:1], v[0:1], v[16:17]
	v_pk_mul_f32 v[20:21], v[6:7], v[18:19]
	v_pk_fma_f32 v[0:1], v[4:5], v[12:13], v[0:1]
	v_pk_fma_f32 v[20:21], v[2:3], v[14:15], v[20:21] neg_lo:[0,0,1] neg_hi:[0,0,1]
	v_pk_mul_f32 v[0:1], v[8:9], v[0:1] op_sel_hi:[0,1]
	v_pk_mul_f32 v[4:5], v[2:3], v[18:19]
	v_mov_b32_e32 v2, v7
	v_mov_b32_e32 v18, v15
	v_cvt_pk_bf16_f32 v12, v0, v1
	v_pk_mul_f32 v[0:1], v[6:7], v[14:15]
	v_pk_mul_f32 v[2:3], v[2:3], v[18:19]
	v_pk_mul_f32 v[20:21], v[8:9], v[20:21] op_sel_hi:[0,1]
	v_mov_b32_e32 v1, v2
	v_mov_b32_e32 v5, v3
	v_pk_add_f32 v[0:1], v[0:1], v[4:5]
	v_pk_mul_f32 v[22:23], v[8:9], v[22:23] op_sel_hi:[0,1]
	v_pk_mul_f32 v[4:5], v[8:9], v[0:1] op_sel_hi:[0,1]
	v_lshl_add_u64 v[0:1], v[10:11], 0, v[148:149]
	v_cvt_pk_bf16_f32 v21, v20, v21
	v_cvt_pk_bf16_f32 v20, v22, v23
	v_lshl_add_u64 v[6:7], v[0:1], 0, s[42:43]
	global_store_dwordx2 v[0:1], v[20:21], off offset:256
	global_store_dword v[0:1], v12, off offset:320

; template <int EPI, int TS, bool VT>
; DEVI void gemm_epilogue(const Params& p, char* smem, f32x4 (&acc)[2][2][4][2], int m0, int n0, float scale, const float* ssin,
;                         float* ssout, u16* xbout, int wid, int lane, int wr, int wc, int fr, int fq) {
;     ...
;             } else if (gh == 8 || gh == 10) {
;               const float4 b4 = *(const float4*)(Tr + 4 * lane + 16);
;               const int i0r = (gh == 8 ? 0 : 16) + f0;
;               const int pos = tok_pos(grow);
;               const float4 c4 = *(const float4*)((const float*)(wsb + OFF_COS) + pos * 32 + i0r);
;               const float4 s4 = *(const float4*)((const float*)(wsb + OFF_SIN) + pos * 32 + i0r);
;               uint2 o1, o2;
;               o1.x = pack2((a.x * c4.x - b4.x * s4.x) * qs, (a.y * c4.y - b4.y * s4.y) * qs);
;               o1.y = pack2((a.z * c4.z - b4.z * s4.z) * qs, (a.w * c4.w - b4.w * s4.w) * qs);
;               o2.x = pack2((b4.x * c4.x + a.x * s4.x) * qs, (b4.y * c4.y + a.y * s4.y) * qs);
;               o2.y = pack2((b4.z * c4.z + a.z * s4.z) * qs, (b4.w * c4.w + a.w * s4.w) * qs);
;               *(uint2*)(o + 128 + i0r) = o1;
;               *(uint2*)(o + 160 + i0r) = o2;
.LBB0_872:
	s_andn2_b64 s[22:23], s[30:31], exec
	s_and_b64 s[30:31], s[4:5], exec
	s_or_b64 s[30:31], s[22:23], s[30:31]
	s_or_b64 exec, exec, s[20:21]
	s_mov_b64 s[22:23], 0
	s_and_saveexec_b64 s[20:21], s[30:31]
	s_cbranch_execz .LBB0_875
	s_cmp_lt_i32 s44, 0x10000
	s_movk_i32 s22, 0xffd
	s_cselect_b32 s22, s22, 0x7fd
	s_and_b32 s22, s22, s44
	s_lshl_b32 s44, s22, 7
	v_lshl_add_u64 v[14:15], v[74:75], 0, s[44:45]
	v_lshl_add_u64 v[16:17], v[76:77], 0, s[44:45]
	ds_read_b128 v[4:7], v12 offset:64
	global_load_dwordx4 v[12:15], v[14:15], off
	s_nop 0
	global_load_dwordx4 v[16:19], v[16:17], off
	v_lshlrev_b32_e32 v148, 1, v72
	s_mov_b64 s[22:23], exec
	s_waitcnt vmcnt(0) lgkmcnt(0)
	v_pk_mul_f32 v[22:23], v[4:5], v[16:17]
	s_nop 0
	v_pk_fma_f32 v[22:23], v[0:1], v[12:13], v[22:23] neg_lo:[0,0,1] neg_hi:[0,0,1]
	v_pk_mul_f32 v[0:1], v[0:1], v[16:17]
	v_pk_mul_f32 v[20:21], v[6:7], v[18:19]
	v_pk_fma_f32 v[0:1], v[4:5], v[12:13], v[0:1]
	v_pk_fma_f32 v[20:21], v[2:3], v[14:15], v[20:21] neg_lo:[0,0,1] neg_hi:[0,0,1]
	v_pk_mul_f32 v[0:1], v[8:9], v[0:1] op_sel_hi:[0,1]
	v_pk_mul_f32 v[4:5], v[2:3], v[18:19]
	v_mov_b32_e32 v2, v7
	v_mov_b32_e32 v18, v15
	v_cvt_pk_bf16_f32 v12, v0, v1
	v_pk_mul_f32 v[0:1], v[6:7], v[14:15]
	v_pk_mul_f32 v[2:3], v[2:3], v[18:19]
	v_pk_mul_f32 v[20:21], v[8:9], v[20:21] op_sel_hi:[0,1]
	v_mov_b32_e32 v1, v2
	v_mov_b32_e32 v5, v3
	v_pk_add_f32 v[0:1], v[0:1], v[4:5]
	v_pk_mul_f32 v[22:23], v[8:9], v[22:23] op_sel_hi:[0,1]
	v_pk_mul_f32 v[4:5], v[8:9], v[0:1] op_sel_hi:[0,1]
	v_lshl_add_u64 v[0:1], v[10:11], 0, v[148:149]
	v_cvt_pk_bf16_f32 v21, v20, v21
	v_cvt_pk_bf16_f32 v20, v22, v23
	v_lshl_add_u64 v[6:7], v[0:1], 0, s[42:43]
	global_store_dwordx2 v[0:1], v[20:21], off offset:256
	global_store_dword v[0:1], v12, off offset:320

; template <int EPI, int TS, bool VT>
; DEVI void gemm_epilogue(const Params& p, char* smem, f32x4 (&acc)[2][2][4][2], int m0, int n0, float scale, const float* ssin,
;                         float* ssout, u16* xbout, int wid, int lane, int wr, int wc, int fr, int fq) {
;     ...
;             } else if (gh == 8 || gh == 10) {
;               const float4 b4 = *(const float4*)(Tr + 4 * lane + 16);
;               const int i0r = (gh == 8 ? 0 : 16) + f0;
;               const int pos = tok_pos(grow);
;               const float4 c4 = *(const float4*)((const float*)(wsb + OFF_COS) + pos * 32 + i0r);
;               const float4 s4 = *(const float4*)((const float*)(wsb + OFF_SIN) + pos * 32 + i0r);
;               uint2 o1, o2;
;               o1.x = pack2((a.x * c4.x - b4.x * s4.x) * qs, (a.y * c4.y - b4.y * s4.y) * qs);
;               o1.y = pack2((a.z * c4.z - b4.z * s4.z) * qs, (a.w * c4.w - b4.w * s4.w) * qs);
;               o2.x = pack2((b4.x * c4.x + a.x * s4.x) * qs, (b4.y * c4.y + a.y * s4.y) * qs);
;               o2.y = pack2((b4.z * c4.z + a.z * s4.z) * qs, (b4.w * c4.w + a.w * s4.w) * qs);
;               *(uint2*)(o + 128 + i0r) = o1;
;               *(uint2*)(o + 160 + i0r) = o2;
.LBB0_884:
	s_andn2_b64 s[22:23], s[30:31], exec
	s_and_b64 s[30:31], s[4:5], exec
	s_or_b64 s[30:31], s[22:23], s[30:31]
	s_or_b64 exec, exec, s[20:21]
	s_mov_b64 s[22:23], 0
	s_and_saveexec_b64 s[20:21], s[30:31]
	s_cbranch_execz .LBB0_887
	s_cmp_lt_i32 s44, 0x10000
	s_movk_i32 s22, 0xffe
	s_cselect_b32 s22, s22, 0x7fe
	s_and_b32 s22, s22, s44
	s_lshl_b32 s44, s22, 7
	v_lshl_add_u64 v[14:15], v[74:75], 0, s[44:45]
	v_lshl_add_u64 v[16:17], v[76:77], 0, s[44:45]
	ds_read_b128 v[4:7], v12 offset:64
	global_load_dwordx4 v[12:15], v[14:15], off
	s_nop 0
	global_load_dwordx4 v[16:19], v[16:17], off
	v_lshlrev_b32_e32 v148, 1, v72
	s_mov_b64 s[22:23], exec
	s_waitcnt vmcnt(0) lgkmcnt(0)
	v_pk_mul_f32 v[22:23], v[4:5], v[16:17]
	s_nop 0
	v_pk_fma_f32 v[22:23], v[0:1], v[12:13], v[22:23] neg_lo:[0,0,1] neg_hi:[0,0,1]
	v_pk_mul_f32 v[0:1], v[0:1], v[16:17]
	v_pk_mul_f32 v[20:21], v[6:7], v[18:19]
	v_pk_fma_f32 v[0:1], v[4:5], v[12:13], v[0:1]
	v_pk_fma_f32 v[20:21], v[2:3], v[14:15], v[20:21] neg_lo:[0,0,1] neg_hi:[0,0,1]
	v_pk_mul_f32 v[0:1], v[8:9], v[0:1] op_sel_hi:[0,1]
	v_pk_mul_f32 v[4:5], v[2:3], v[18:19]
	v_mov_b32_e32 v2, v7
	v_mov_b32_e32 v18, v15
	v_cvt_pk_bf16_f32 v12, v0, v1
	v_pk_mul_f32 v[0:1], v[6:7], v[14:15]
	v_pk_mul_f32 v[2:3], v[2:3], v[18:19]
	v_pk_mul_f32 v[20:21], v[8:9], v[20:21] op_sel_hi:[0,1]
	v_mov_b32_e32 v1, v2
	v_mov_b32_e32 v5, v3
	v_pk_add_f32 v[0:1], v[0:1], v[4:5]
	v_pk_mul_f32 v[22:23], v[8:9], v[22:23] op_sel_hi:[0,1]
	v_pk_mul_f32 v[4:5], v[8:9], v[0:1] op_sel_hi:[0,1]
	v_lshl_add_u64 v[0:1], v[10:11], 0, v[148:149]
	v_cvt_pk_bf16_f32 v21, v20, v21
	v_cvt_pk_bf16_f32 v20, v22, v23
	v_lshl_add_u64 v[6:7], v[0:1], 0, s[42:43]
	global_store_dwordx2 v[0:1], v[20:21], off offset:256
	global_store_dword v[0:1], v12, off offset:320

; template <int EPI, int TS, bool VT>
; DEVI void gemm_epilogue(const Params& p, char* smem, f32x4 (&acc)[2][2][4][2], int m0, int n0, float scale, const float* ssin,
;                         float* ssout, u16* xbout, int wid, int lane, int wr, int wc, int fr, int fq) {
;     ...
;             if (gh < 8) {
;               uint2 ov;
;               ov.x = pack2(a.x * qs, a.y * qs);
;               ov.y = pack2(a.z * qs, a.w * qs);
;               *(uint2*)(o + gh * 16 + f0) = ov;
.LBB0_894:
	s_waitcnt lgkmcnt(0)
	v_pk_mul_f32 v[0:1], v[0:1], v[8:9] op_sel_hi:[1,0]
	v_mov_b32_e32 v81, v149
	v_cvt_pk_bf16_f32 v12, v0, v1
	v_lshl_add_u64 v[0:1], v[78:79], 1, v[10:11]
	v_pk_mul_f32 v[4:5], v[8:9], v[2:3] op_sel_hi:[0,1]
	v_lshl_add_u64 v[6:7], v[0:1], 0, v[80:81]
	s_or_b64 s[20:21], s[20:21], exec
	global_store_dword v[6:7], v12, off
	s_or_b64 exec, exec, s[14:15]
	s_and_saveexec_b64 s[14:15], s[20:21]
	s_cbranch_execz .LBB0_805
	s_branch .LBB0_901

; template <int EPI, int TS, bool VT>
; DEVI void gemm_epilogue(const Params& p, char* smem, f32x4 (&acc)[2][2][4][2], int m0, int n0, float scale, const float* ssin,
;                         float* ssout, u16* xbout, int wid, int lane, int wr, int wc, int fr, int fq) {
;     ...
;             } else if (gh == 8 || gh == 10) {
;               const float4 b4 = *(const float4*)(Tr + 4 * lane + 16);
;               const int i0r = (gh == 8 ? 0 : 16) + f0;
;               const int pos = tok_pos(grow);
;               const float4 c4 = *(const float4*)((const float*)(wsb + OFF_COS) + pos * 32 + i0r);
;               const float4 s4 = *(const float4*)((const float*)(wsb + OFF_SIN) + pos * 32 + i0r);
;               uint2 o1, o2;
;               o1.x = pack2((a.x * c4.x - b4.x * s4.x) * qs, (a.y * c4.y - b4.y * s4.y) * qs);
;               o1.y = pack2((a.z * c4.z - b4.z * s4.z) * qs, (a.w * c4.w - b4.w * s4.w) * qs);
;               o2.x = pack2((b4.x * c4.x + a.x * s4.x) * qs, (b4.y * c4.y + a.y * s4.y) * qs);
;               o2.y = pack2((b4.z * c4.z + a.z * s4.z) * qs, (b4.w * c4.w + a.w * s4.w) * qs);
;               *(uint2*)(o + 128 + i0r) = o1;
;               *(uint2*)(o + 160 + i0r) = o2;
.LBB0_896:
	s_andn2_b64 s[22:23], s[30:31], exec
	s_and_b64 s[30:31], s[4:5], exec
	s_or_b64 s[30:31], s[22:23], s[30:31]
	s_or_b64 exec, exec, s[20:21]
	s_mov_b64 s[22:23], 0
	s_and_saveexec_b64 s[20:21], s[30:31]
	s_cbranch_execz .LBB0_899
	s_cmp_lt_i32 s44, 0x10000
	s_movk_i32 s22, 0xfff
	s_cselect_b32 s22, s22, 0x7ff
	s_and_b32 s22, s22, s44
	s_lshl_b32 s44, s22, 7
	v_lshl_add_u64 v[14:15], v[74:75], 0, s[44:45]
	v_lshl_add_u64 v[16:17], v[76:77], 0, s[44:45]
	ds_read_b128 v[4:7], v12 offset:64
	global_load_dwordx4 v[12:15], v[14:15], off
	s_nop 0
	global_load_dwordx4 v[16:19], v[16:17], off
	v_lshlrev_b32_e32 v148, 1, v72
	s_mov_b64 s[22:23], exec
	s_waitcnt vmcnt(0) lgkmcnt(0)
	v_pk_mul_f32 v[22:23], v[4:5], v[16:17]
	s_nop 0
	v_pk_fma_f32 v[22:23], v[0:1], v[12:13], v[22:23] neg_lo:[0,0,1] neg_hi:[0,0,1]
	v_pk_mul_f32 v[0:1], v[0:1], v[16:17]
	v_pk_mul_f32 v[20:21], v[6:7], v[18:19]
	v_pk_fma_f32 v[0:1], v[4:5], v[12:13], v[0:1]
	v_pk_fma_f32 v[20:21], v[2:3], v[14:15], v[20:21] neg_lo:[0,0,1] neg_hi:[0,0,1]
	v_pk_mul_f32 v[0:1], v[8:9], v[0:1] op_sel_hi:[0,1]
	v_pk_mul_f32 v[4:5], v[2:3], v[18:19]
	v_mov_b32_e32 v2, v7
	v_mov_b32_e32 v18, v15
	v_cvt_pk_bf16_f32 v12, v0, v1
	v_pk_mul_f32 v[0:1], v[6:7], v[14:15]
	v_pk_mul_f32 v[2:3], v[2:3], v[18:19]
	v_pk_mul_f32 v[20:21], v[8:9], v[20:21] op_sel_hi:[0,1]
	v_mov_b32_e32 v1, v2
	v_mov_b32_e32 v5, v3
	v_pk_add_f32 v[0:1], v[0:1], v[4:5]
	v_pk_mul_f32 v[22:23], v[8:9], v[22:23] op_sel_hi:[0,1]
	v_pk_mul_f32 v[4:5], v[8:9], v[0:1] op_sel_hi:[0,1]
	v_lshl_add_u64 v[0:1], v[10:11], 0, v[148:149]
	v_cvt_pk_bf16_f32 v21, v20, v21
	v_cvt_pk_bf16_f32 v20, v22, v23
	v_lshl_add_u64 v[6:7], v[0:1], 0, s[42:43]
	global_store_dwordx2 v[0:1], v[20:21], off offset:256
	global_store_dword v[0:1], v12, off offset:320

; template <int EPI, int TS, bool VT>
; DEVI void gemm_epilogue(const Params& p, char* smem, f32x4 (&acc)[2][2][4][2], int m0, int n0, float scale, const float* ssin,
;                         float* ssout, u16* xbout, int wid, int lane, int wr, int wc, int fr, int fq) {
;     ...
;             if (gh < 8) {
;               uint2 ov;
;               ov.x = pack2(a.x * qs, a.y * qs);
;               ov.y = pack2(a.z * qs, a.w * qs);
;               *(uint2*)(o + gh * 16 + f0) = ov;
;             } else if (gh == 8 || gh == 10) {
;               const float4 b4 = *(const float4*)(Tr + 4 * lane + 16);
;               const int i0r = (gh == 8 ? 0 : 16) + f0;
;               const int pos = tok_pos(grow);
;               const float4 c4 = *(const float4*)((const float*)(wsb + OFF_COS) + pos * 32 + i0r);
;               const float4 s4 = *(const float4*)((const float*)(wsb + OFF_SIN) + pos * 32 + i0r);
;               uint2 o1, o2;
;               o1.x = pack2((a.x * c4.x - b4.x * s4.x) * qs, (a.y * c4.y - b4.y * s4.y) * qs);
;               o1.y = pack2((a.z * c4.z - b4.z * s4.z) * qs, (a.w * c4.w - b4.w * s4.w) * qs);
;               o2.x = pack2((b4.x * c4.x + a.x * s4.x) * qs, (b4.y * c4.y + a.y * s4.y) * qs);
;               o2.y = pack2((b4.z * c4.z + a.z * s4.z) * qs, (b4.w * c4.w + a.w * s4.w) * qs);
;               *(uint2*)(o + 128 + i0r) = o1;
;               *(uint2*)(o + 160 + i0r) = o2;
.LBB0_901:
	s_waitcnt lgkmcnt(0)
	v_cvt_pk_bf16_f32 v0, v4, v5
	global_store_dword v[6:7], v0, off offset:4
	s_branch .LBB0_805

; template <int EPI, int TS, bool VT>
; DEVI void gemm_epilogue(const Params& p, char* smem, f32x4 (&acc)[2][2][4][2], int m0, int n0, float scale, const float* ssin,
;                         float* ssout, u16* xbout, int wid, int lane, int wr, int wc, int fr, int fq) {
;     ...
;           } else {
;             rsa = rsqrtf(ssin[t0 + 2 * tp] * (1.f / 256.f) + EPS);
;             rsb = rsqrtf(ssin[t0 + 2 * tp + 1] * (1.f / 256.f) + EPS);
;             const size_t S = t0 < MP ? 4096 : 2048;
;             const size_t sb = t0 < MP ? (size_t)(t0 >> 12) * 8 * 128 * 4096 + (t0 & 4095)
;                                       : (size_t)MP * 1024 + (size_t)((t0 - MP) >> 11) * 8 * 128 * 2048 + (t0 & 2047);
;             vbase = (u16*)(wsb + OFF_VTM) + sb + (size_t)(n0 - 1024) * S + 2 * tp;
;             dstr = S;
;           }
;           const float* Tc = T + (c * 64 + 2 * tp) * TS;
;           for (int d = 0; d < 16; ++d) {
;             const int dv = wid * 32 + d * 2 + dsub;
;             const float va = Tc[dv] * rsa, vb = Tc[TS + dv] * rsb;
;             *(unsigned*)(vbase + (size_t)dv * dstr) = pack2(va, vb);
;           }
.LBB0_903:
	s_and_b32 s3, s3, s13
	s_lshl_b64 s[0:1], s[0:1], 1
	s_add_u32 s0, s15, s0
	s_addc_u32 s1, s63, s1
	s_lshl_b32 s3, s3, 1
	s_add_u32 s3, s0, s3
	s_addc_u32 s12, s1, 0
	s_lshl_b64 s[0:1], s[44:45], s2
	s_lshl_b64 s[0:1], s[0:1], 1
	s_add_u32 s0, s3, s0
	s_addc_u32 s1, s12, s1
	v_lshl_add_u64 v[0:1], s[0:1], 0, v[148:149]
	s_mov_b32 s0, 0x3b800000
	s_waitcnt vmcnt(0)
	v_pk_fma_f32 v[2:3], v[2:3], s[0:1], v[150:151] op_sel_hi:[1,0,0]
	ds_read2_b32 v[4:5], v97 offset0:1 offset1:3
	v_mul_f32_e32 v6, 0x4b800000, v3
	v_cmp_gt_f32_e64 s[0:1], s29, v3
	v_cmp_gt_f32_e32 vcc, s29, v2
	s_mov_b32 s12, 0x45800000
	v_cndmask_b32_e64 v3, v3, v6, s[0:1]
	v_mul_f32_e32 v6, 0x4b800000, v2
	v_cndmask_b32_e32 v2, v2, v6, vcc
	v_rsq_f32_e32 v3, v3
	v_rsq_f32_e32 v2, v2
	s_waitcnt lgkmcnt(0)
	v_mov_b32_e32 v13, v4
	v_pk_mul_f32 v[6:7], v[2:3], s[12:13] op_sel_hi:[1,0]
	s_nop 0
	v_cndmask_b32_e64 v3, v3, v7, s[0:1]
	v_cndmask_b32_e32 v2, v2, v6, vcc
	ds_read2_b32 v[6:7], v96 offset1:2
	ds_read2_b32 v[8:9], v96 offset0:4 offset1:6
	ds_read2_b32 v[10:11], v96 offset0:8 offset1:10
	s_waitcnt lgkmcnt(2)
	v_mov_b32_e32 v12, v6
	v_pk_mul_f32 v[12:13], v[2:3], v[12:13]
	s_nop 0
	v_cvt_pk_bf16_f32 v4, v12, v13
	v_lshlrev_b64 v[12:13], s2, v[64:65]
	v_lshl_add_u64 v[12:13], v[12:13], 1, v[0:1]
	global_store_dword v[12:13], v4, off
	v_mov_b32_e32 v4, v7
	v_pk_mul_f32 v[4:5], v[2:3], v[4:5]
	s_nop 0
	v_cvt_pk_bf16_f32 v6, v4, v5
	v_lshlrev_b64 v[4:5], s2, v[82:83]
	v_lshl_add_u64 v[4:5], v[4:5], 1, v[0:1]
	global_store_dword v[4:5], v6, off
	ds_read2_b32 v[4:5], v97 offset0:5 offset1:7
	s_waitcnt lgkmcnt(0)
	v_mov_b32_e32 v6, v8
	v_mov_b32_e32 v7, v4
	v_pk_mul_f32 v[6:7], v[2:3], v[6:7]
	s_nop 0
	v_cvt_pk_bf16_f32 v4, v6, v7
	v_lshlrev_b64 v[6:7], s2, v[72:73]
	v_lshl_add_u64 v[6:7], v[6:7], 1, v[0:1]
	global_store_dword v[6:7], v4, off
	v_mov_b32_e32 v4, v9
	v_pk_mul_f32 v[4:5], v[2:3], v[4:5]
	s_nop 0
	v_cvt_pk_bf16_f32 v6, v4, v5
	v_lshlrev_b64 v[4:5], s2, v[88:89]
	v_lshl_add_u64 v[4:5], v[4:5], 1, v[0:1]
	global_store_dword v[4:5], v6, off
	ds_read2_b32 v[4:5], v97 offset0:9 offset1:11
	v_mov_b32_e32 v6, v10
	s_waitcnt lgkmcnt(0)
	v_mov_b32_e32 v7, v4
	v_pk_mul_f32 v[6:7], v[2:3], v[6:7]
	s_nop 0
	v_cvt_pk_bf16_f32 v4, v6, v7
	v_lshlrev_b64 v[6:7], s2, v[76:77]
	v_lshl_add_u64 v[6:7], v[6:7], 1, v[0:1]
	global_store_dword v[6:7], v4, off
	v_mov_b32_e32 v4, v11
	v_pk_mul_f32 v[4:5], v[2:3], v[4:5]
	s_nop 0
	v_cvt_pk_bf16_f32 v6, v4, v5
	v_lshlrev_b64 v[4:5], s2, v[90:91]
	v_lshl_add_u64 v[4:5], v[4:5], 1, v[0:1]
	global_store_dword v[4:5], v6, off
	ds_read2_b32 v[4:5], v96 offset0:12 offset1:14
	ds_read2_b32 v[6:7], v97 offset0:13 offset1:15
	s_waitcnt lgkmcnt(0)
	v_mov_b32_e32 v8, v4
	v_mov_b32_e32 v9, v6
	v_pk_mul_f32 v[8:9], v[2:3], v[8:9]
	v_mov_b32_e32 v6, v5
	v_cvt_pk_bf16_f32 v4, v8, v9
	v_lshlrev_b64 v[8:9], s2, v[78:79]
	v_lshl_add_u64 v[8:9], v[8:9], 1, v[0:1]
	global_store_dword v[8:9], v4, off
	v_pk_mul_f32 v[4:5], v[2:3], v[6:7]
	s_nop 0
	v_cvt_pk_bf16_f32 v6, v4, v5
	v_lshlrev_b64 v[4:5], s2, v[94:95]
	v_lshl_add_u64 v[4:5], v[4:5], 1, v[0:1]
	global_store_dword v[4:5], v6, off
	ds_read2_b32 v[4:5], v96 offset0:16 offset1:18
	ds_read2_b32 v[6:7], v97 offset0:17 offset1:19
	s_waitcnt lgkmcnt(0)
	v_mov_b32_e32 v8, v4
	v_mov_b32_e32 v9, v6
	v_pk_mul_f32 v[8:9], v[2:3], v[8:9]
	v_mov_b32_e32 v6, v5
	v_cvt_pk_bf16_f32 v4, v8, v9
	v_lshlrev_b64 v[8:9], s2, v[86:87]
	v_lshl_add_u64 v[8:9], v[8:9], 1, v[0:1]
	global_store_dword v[8:9], v4, off
	v_pk_mul_f32 v[4:5], v[2:3], v[6:7]
	s_nop 0
	v_cvt_pk_bf16_f32 v6, v4, v5
	v_lshlrev_b64 v[4:5], s2, v[92:93]
	v_lshl_add_u64 v[4:5], v[4:5], 1, v[0:1]
	global_store_dword v[4:5], v6, off
	ds_read2_b32 v[4:5], v96 offset0:20 offset1:22
	ds_read2_b32 v[6:7], v97 offset0:21 offset1:23
	s_waitcnt lgkmcnt(0)
	v_mov_b32_e32 v8, v4
	v_mov_b32_e32 v9, v6
	v_pk_mul_f32 v[8:9], v[2:3], v[8:9]
	v_mov_b32_e32 v6, v5
	v_cvt_pk_bf16_f32 v4, v8, v9
	v_lshlrev_b64 v[8:9], s2, v[80:81]
	v_lshl_add_u64 v[8:9], v[8:9], 1, v[0:1]
	global_store_dword v[8:9], v4, off
	v_pk_mul_f32 v[4:5], v[2:3], v[6:7]
	s_nop 0
	v_cvt_pk_bf16_f32 v6, v4, v5
	v_lshlrev_b64 v[4:5], s2, v[84:85]
	v_lshl_add_u64 v[4:5], v[4:5], 1, v[0:1]
	global_store_dword v[4:5], v6, off
	ds_read2_b32 v[4:5], v96 offset0:24 offset1:26
	ds_read2_b32 v[6:7], v97 offset0:25 offset1:27
	s_waitcnt lgkmcnt(0)
	v_mov_b32_e32 v8, v4
	v_mov_b32_e32 v9, v6
	v_pk_mul_f32 v[8:9], v[2:3], v[8:9]
	v_mov_b32_e32 v6, v5
	v_cvt_pk_bf16_f32 v4, v8, v9
	v_lshlrev_b64 v[8:9], s2, v[70:71]
	v_lshl_add_u64 v[8:9], v[8:9], 1, v[0:1]
	global_store_dword v[8:9], v4, off
	v_pk_mul_f32 v[4:5], v[2:3], v[6:7]
	s_nop 0
	v_cvt_pk_bf16_f32 v6, v4, v5
	v_lshlrev_b64 v[4:5], s2, v[74:75]
	v_lshl_add_u64 v[4:5], v[4:5], 1, v[0:1]
	global_store_dword v[4:5], v6, off
	ds_read2_b32 v[4:5], v96 offset0:28 offset1:30
	ds_read2_b32 v[6:7], v97 offset0:29 offset1:31
	s_waitcnt lgkmcnt(0)
	v_mov_b32_e32 v8, v4
	v_mov_b32_e32 v9, v6
	v_pk_mul_f32 v[8:9], v[2:3], v[8:9]
	v_mov_b32_e32 v6, v5
	v_cvt_pk_bf16_f32 v4, v8, v9
	v_lshlrev_b64 v[8:9], s2, v[66:67]
	v_lshl_add_u64 v[8:9], v[8:9], 1, v[0:1]
	v_pk_mul_f32 v[2:3], v[2:3], v[6:7]
	global_store_dword v[8:9], v4, off
	v_cvt_pk_bf16_f32 v4, v2, v3
	v_lshlrev_b64 v[2:3], s2, v[68:69]
	v_lshl_add_u64 v[0:1], v[2:3], 1, v[0:1]
	global_store_dword v[0:1], v4, off
	s_waitcnt lgkmcnt(0)
	s_barrier

; template <int EPI, int TS, bool VT>
; DEVI void gemm_epilogue(const Params& p, char* smem, f32x4 (&acc)[2][2][4][2], int m0, int n0, float scale, const float* ssin,
;                         float* ssout, u16* xbout, int wid, int lane, int wr, int wc, int fr, int fq) {
;     ...
;   for (int ai = 0; ai < 2; ++ai) {
;     {
;       float* tw = T + (wr * 64 + fq * 4) * TS + wc * 32 + fr;
; #pragma unroll
;       for (int m = 0; m < 4; ++m)
; #pragma unroll
;         for (int j = 0; j < 4; ++j)
; #pragma unroll
;           for (int v = 0; v < 4; ++v) tw[(m * 16 + j) * TS + (v >> 1) * 128 + (v & 1) * 16] = acc[ai][v >> 1][m][v & 1][j];
;     }
;     __syncthreads();
;     const int r0 = wid * 16;
;     const int g0 = m0 + ai * 128 + r0;
;     if constexpr (!VT) {
;       float rsv = 1.f;
;       if constexpr (EPI == E_PLEGATE || EPI == E_F32 || EPI == E_SWIGLU || EPI == E_GLAIN)
;         rsv = rsqrtf(ssin[g0 + (lane & 15)] * (1.f / 1024.f) + EPS);
;       if constexpr (EPI == E_QROPE) rsv = rsqrtf(ssin[g0 + (lane & 15)] * (1.f / 384.f) + EPS);
;       if constexpr (EPI == E_KV) rsv = rsqrtf(ssin[g0 + (lane & 15)] * (1.f / 256.f) + EPS);
;     ...
;           } else if constexpr (EPI == E_KV) {
;             const float4 a = *(const float4*)(Tr + 4 * lane);
;             uint2 o;
;             o.x = pack2(a.x * rs, a.y * rs);
;             o.y = pack2(a.z * rs, a.w * rs);
;             st_nt8((u16*)(wsb + OFF_KM) + (size_t)grow * 1024 + n0 + 4 * lane, o);
;           }
.LBB0_911:
	s_lshl_b32 s2, s63, 6
	v_and_b32_e32 v131, 63, v128
	s_lshl_b32 s15, s15, 7
	v_lshrrev_b32_e32 v128, 2, v128
	s_cmp_lt_i32 s44, 4
	v_and_or_b32 v132, v128, 12, s2
	s_mov_b64 s[2:3], -1
	v_lshlrev_b32_e32 v133, 2, v130
	s_cbranch_scc0 .LBB0_913
	v_readlane_b32 s18, v254, 13
	s_movk_i32 s2, 0x410
	v_readlane_b32 s19, v254, 14
	v_mul_lo_u32 v128, v132, s2
	s_lshl_b32 s2, s13, 4
	s_add_i32 s2, s2, s12
	s_lshl_b64 s[20:21], s[0:1], 1
	s_add_u32 s18, s18, s20
	v_or_b32_e32 v156, s2, v130
	v_add3_u32 v135, s15, v128, v133
	s_addc_u32 s19, s19, s21
	v_lshlrev_b32_e32 v148, 3, v131
	v_ashrrev_i32_e32 v157, 31, v156
	v_lshl_add_u64 v[128:129], s[18:19], 0, v[148:149]
	v_add_u32_e32 v136, 0x400, v135
	v_add_u32_e32 v137, 0x800, v135
	v_add_u32_e32 v138, 0xc00, v135
	v_add_u32_e32 v139, 0x4000, v135
	v_add_u32_e32 v140, 0x4400, v135
	v_add_u32_e32 v141, 0x4800, v135
	v_add_u32_e32 v142, 0x4c00, v135
	v_add_u32_e32 v143, 0x8000, v135
	v_add_u32_e32 v144, 0x8400, v135
	v_add_u32_e32 v145, 0x8800, v135
	v_add_u32_e32 v146, 0x8c00, v135
	v_add_u32_e32 v147, 0x9000, v135
	v_add_u32_e32 v148, 0xc000, v135
	v_add_u32_e32 v152, 0xc400, v135
	v_add_u32_e32 v153, 0xc800, v135
	v_add_u32_e32 v154, 0xcc00, v135
	v_add_u32_e32 v155, 0xd000, v135
	v_lshl_add_u64 v[156:157], v[156:157], 2, s[8:9]
	ds_write2_b32 v135, v88, v96 offset1:16
	ds_write2_b32 v135, v120, v124 offset0:128 offset1:144
	ds_write2_b32 v136, v89, v97 offset0:4 offset1:20
	ds_write2_b32 v136, v121, v125 offset0:132 offset1:148
	ds_write2_b32 v137, v90, v98 offset0:8 offset1:24
	ds_write2_b32 v137, v122, v126 offset0:136 offset1:152
	ds_write2_b32 v138, v91, v99 offset0:12 offset1:28
	ds_write2_b32 v138, v123, v127 offset0:140 offset1:156
	ds_write2_b32 v139, v80, v84 offset0:64 offset1:80
	ds_write2_b32 v139, v112, v116 offset0:192 offset1:208
	ds_write2_b32 v140, v81, v85 offset0:68 offset1:84
	ds_write2_b32 v140, v113, v117 offset0:196 offset1:212
	ds_write2_b32 v141, v82, v86 offset0:72 offset1:88
	ds_write2_b32 v141, v114, v118 offset0:200 offset1:216
	ds_write2_b32 v142, v83, v87 offset0:76 offset1:92
	ds_write2_b32 v142, v115, v119 offset0:204 offset1:220
	ds_write2_b32 v143, v72, v76 offset0:128 offset1:144
	ds_write2_b32 v144, v104, v108 offset1:16
	ds_write2_b32 v144, v73, v77 offset0:132 offset1:148
	ds_write2_b32 v145, v105, v109 offset0:4 offset1:20
	ds_write2_b32 v145, v74, v78 offset0:136 offset1:152
	ds_write2_b32 v146, v106, v110 offset0:8 offset1:24
	ds_write2_b32 v146, v75, v79 offset0:140 offset1:156
	ds_write2_b32 v147, v107, v111 offset0:12 offset1:28
	ds_write2_b32 v148, v64, v68 offset0:192 offset1:208
	ds_write2_b32 v152, v92, v100 offset0:64 offset1:80
	ds_write2_b32 v152, v65, v69 offset0:196 offset1:212
	ds_write2_b32 v153, v93, v101 offset0:68 offset1:84
	ds_write2_b32 v153, v66, v70 offset0:200 offset1:216
	ds_write2_b32 v154, v94, v102 offset0:72 offset1:88
	ds_write2_b32 v154, v67, v71 offset0:204 offset1:220
	ds_write2_b32 v155, v95, v103 offset0:76 offset1:92
	s_waitcnt vmcnt(0) lgkmcnt(0)
	s_barrier
	global_load_dword v134, v[156:157], off
	s_mul_i32 s1, s13, 0x4100
	s_mov_b64 s[18:19], 0x29d5ee00
	v_lshl_add_u64 v[128:129], v[128:129], 0, s[18:19]
	s_ashr_i32 s3, s2, 31
	s_waitcnt vmcnt(0) lgkmcnt(0)
	v_fmamk_f32 v134, v134, 0x3b800000, v150
	v_cmp_gt_f32_e32 vcc, s29, v134
	v_mul_f32_e32 v156, 0x4b800000, v134
	s_nop 0
	v_cndmask_b32_e32 v134, v134, v156, vcc
	v_rsq_f32_e32 v134, v134
	s_nop 0
	v_mul_f32_e32 v156, 0x45800000, v134
	v_cndmask_b32_e32 v156, v134, v156, vcc
	v_lshl_add_u32 v134, v131, 4, s1
	ds_read_b128 v[158:161], v134
	v_readlane_b32 s18, v156, 0
	v_readlane_b32 s20, v156, 1
	s_waitcnt lgkmcnt(0)
	v_pk_mul_f32 v[158:159], s[18:19], v[158:159] op_sel_hi:[0,1]
	v_pk_mul_f32 v[160:161], s[18:19], v[160:161] op_sel_hi:[0,1]
	s_lshl_b64 s[18:19], s[2:3], 11
	v_cvt_pk_bf16_f32 v158, v158, v159
	v_cvt_pk_bf16_f32 v159, v160, v161
	v_lshl_add_u64 v[160:161], v[128:129], 0, s[18:19]
	global_store_dwordx2 v[160:161], v[158:159], off
	ds_read_b128 v[158:161], v134 offset:1040
	s_or_b32 s18, s2, 1
	s_ashr_i32 s19, s18, 31
	s_lshl_b64 s[18:19], s[18:19], 11
	s_waitcnt lgkmcnt(0)
	v_pk_mul_f32 v[158:159], s[20:21], v[158:159] op_sel_hi:[0,1]
	v_pk_mul_f32 v[160:161], s[20:21], v[160:161] op_sel_hi:[0,1]
	v_cvt_pk_bf16_f32 v158, v158, v159
	v_cvt_pk_bf16_f32 v159, v160, v161
	v_lshl_add_u64 v[160:161], v[128:129], 0, s[18:19]
	global_store_dwordx2 v[160:161], v[158:159], off
	ds_read_b128 v[158:161], v134 offset:2080
	s_or_b32 s18, s2, 2
	v_readlane_b32 s20, v156, 2
	s_ashr_i32 s19, s18, 31
	s_lshl_b64 s[18:19], s[18:19], 11
	s_waitcnt lgkmcnt(0)
	v_pk_mul_f32 v[158:159], s[20:21], v[158:159] op_sel_hi:[0,1]
	v_pk_mul_f32 v[160:161], s[20:21], v[160:161] op_sel_hi:[0,1]
	v_cvt_pk_bf16_f32 v158, v158, v159
	v_cvt_pk_bf16_f32 v159, v160, v161
	v_lshl_add_u64 v[160:161], v[128:129], 0, s[18:19]
	global_store_dwordx2 v[160:161], v[158:159], off
	ds_read_b128 v[158:161], v134 offset:3120
	s_or_b32 s18, s2, 3
	v_readlane_b32 s20, v156, 3
	s_ashr_i32 s19, s18, 31
	s_lshl_b64 s[18:19], s[18:19], 11
	s_waitcnt lgkmcnt(0)
	v_pk_mul_f32 v[158:159], s[20:21], v[158:159] op_sel_hi:[0,1]
	v_pk_mul_f32 v[160:161], s[20:21], v[160:161] op_sel_hi:[0,1]
	v_cvt_pk_bf16_f32 v158, v158, v159
	v_cvt_pk_bf16_f32 v159, v160, v161
	v_lshl_add_u64 v[160:161], v[128:129], 0, s[18:19]
	global_store_dwordx2 v[160:161], v[158:159], off
	ds_read_b128 v[158:161], v134 offset:4160
	s_or_b32 s18, s2, 4
	v_readlane_b32 s20, v156, 4
	s_ashr_i32 s19, s18, 31
	s_lshl_b64 s[18:19], s[18:19], 11
	s_waitcnt lgkmcnt(0)
; template <int EPI, int TS, bool VT>
; DEVI void gemm_epilogue(const Params& p, char* smem, f32x4 (&acc)[2][2][4][2], int m0, int n0, float scale, const float* ssin,
;                         float* ssout, u16* xbout, int wid, int lane, int wr, int wc, int fr, int fq) {
;     ...
;           } else if constexpr (EPI == E_KV) {
;             const float4 a = *(const float4*)(Tr + 4 * lane);
;             uint2 o;
;             o.x = pack2(a.x * rs, a.y * rs);
;             o.y = pack2(a.z * rs, a.w * rs);
;             st_nt8((u16*)(wsb + OFF_KM) + (size_t)grow * 1024 + n0 + 4 * lane, o);
;           }
	v_pk_mul_f32 v[158:159], s[20:21], v[158:159] op_sel_hi:[0,1]
	v_pk_mul_f32 v[160:161], s[20:21], v[160:161] op_sel_hi:[0,1]
	v_cvt_pk_bf16_f32 v158, v158, v159
	v_cvt_pk_bf16_f32 v159, v160, v161
	v_lshl_add_u64 v[160:161], v[128:129], 0, s[18:19]
	global_store_dwordx2 v[160:161], v[158:159], off
	ds_read_b128 v[158:161], v134 offset:5200
	s_or_b32 s18, s2, 5
	v_readlane_b32 s20, v156, 5
	s_ashr_i32 s19, s18, 31
	s_lshl_b64 s[18:19], s[18:19], 11
	s_waitcnt lgkmcnt(0)
	v_pk_mul_f32 v[158:159], s[20:21], v[158:159] op_sel_hi:[0,1]
	v_pk_mul_f32 v[160:161], s[20:21], v[160:161] op_sel_hi:[0,1]
	v_cvt_pk_bf16_f32 v158, v158, v159
	v_cvt_pk_bf16_f32 v159, v160, v161
	v_lshl_add_u64 v[160:161], v[128:129], 0, s[18:19]
	global_store_dwordx2 v[160:161], v[158:159], off
	ds_read_b128 v[158:161], v134 offset:6240
	s_or_b32 s18, s2, 6
	v_readlane_b32 s20, v156, 6
	s_ashr_i32 s19, s18, 31
	s_lshl_b64 s[18:19], s[18:19], 11
	s_waitcnt lgkmcnt(0)
	v_pk_mul_f32 v[158:159], s[20:21], v[158:159] op_sel_hi:[0,1]
	v_pk_mul_f32 v[160:161], s[20:21], v[160:161] op_sel_hi:[0,1]
	v_cvt_pk_bf16_f32 v158, v158, v159
	v_cvt_pk_bf16_f32 v159, v160, v161
	v_lshl_add_u64 v[160:161], v[128:129], 0, s[18:19]
	global_store_dwordx2 v[160:161], v[158:159], off
	ds_read_b128 v[158:161], v134 offset:7280
	s_or_b32 s18, s2, 7
	v_readlane_b32 s20, v156, 7
	s_ashr_i32 s19, s18, 31
	s_lshl_b64 s[18:19], s[18:19], 11
	s_waitcnt lgkmcnt(0)
	v_pk_mul_f32 v[158:159], s[20:21], v[158:159] op_sel_hi:[0,1]
	v_pk_mul_f32 v[160:161], s[20:21], v[160:161] op_sel_hi:[0,1]
	v_cvt_pk_bf16_f32 v158, v158, v159
	v_cvt_pk_bf16_f32 v159, v160, v161
	v_lshl_add_u64 v[160:161], v[128:129], 0, s[18:19]
	global_store_dwordx2 v[160:161], v[158:159], off
	ds_read_b128 v[158:161], v134 offset:8320
	s_or_b32 s18, s2, 8
	v_readlane_b32 s20, v156, 8
	s_ashr_i32 s19, s18, 31
	s_lshl_b64 s[18:19], s[18:19], 11
	s_waitcnt lgkmcnt(0)
	v_pk_mul_f32 v[158:159], s[20:21], v[158:159] op_sel_hi:[0,1]
	v_pk_mul_f32 v[160:161], s[20:21], v[160:161] op_sel_hi:[0,1]
	v_cvt_pk_bf16_f32 v158, v158, v159
	v_cvt_pk_bf16_f32 v159, v160, v161
	v_lshl_add_u64 v[160:161], v[128:129], 0, s[18:19]
	global_store_dwordx2 v[160:161], v[158:159], off
	ds_read_b128 v[158:161], v134 offset:9360
	s_or_b32 s18, s2, 9
	v_readlane_b32 s20, v156, 9
	s_ashr_i32 s19, s18, 31
	s_lshl_b64 s[18:19], s[18:19], 11
	s_waitcnt lgkmcnt(0)
	v_pk_mul_f32 v[158:159], s[20:21], v[158:159] op_sel_hi:[0,1]
	v_pk_mul_f32 v[160:161], s[20:21], v[160:161] op_sel_hi:[0,1]
	v_cvt_pk_bf16_f32 v158, v158, v159
	v_cvt_pk_bf16_f32 v159, v160, v161
	v_lshl_add_u64 v[160:161], v[128:129], 0, s[18:19]
	global_store_dwordx2 v[160:161], v[158:159], off
	ds_read_b128 v[158:161], v134 offset:10400
	s_or_b32 s18, s2, 10
	v_readlane_b32 s20, v156, 10
	s_ashr_i32 s19, s18, 31
	s_lshl_b64 s[18:19], s[18:19], 11
	s_waitcnt lgkmcnt(0)
	v_pk_mul_f32 v[158:159], s[20:21], v[158:159] op_sel_hi:[0,1]
	v_pk_mul_f32 v[160:161], s[20:21], v[160:161] op_sel_hi:[0,1]
	v_cvt_pk_bf16_f32 v158, v158, v159
	v_cvt_pk_bf16_f32 v159, v160, v161
	v_lshl_add_u64 v[160:161], v[128:129], 0, s[18:19]
	global_store_dwordx2 v[160:161], v[158:159], off
	ds_read_b128 v[158:161], v134 offset:11440
	s_or_b32 s18, s2, 11
	v_readlane_b32 s20, v156, 11
	s_ashr_i32 s19, s18, 31
	s_lshl_b64 s[18:19], s[18:19], 11
	s_waitcnt lgkmcnt(0)
	v_pk_mul_f32 v[158:159], s[20:21], v[158:159] op_sel_hi:[0,1]
	v_pk_mul_f32 v[160:161], s[20:21], v[160:161] op_sel_hi:[0,1]
	v_cvt_pk_bf16_f32 v158, v158, v159
	v_cvt_pk_bf16_f32 v159, v160, v161
	v_lshl_add_u64 v[160:161], v[128:129], 0, s[18:19]
	global_store_dwordx2 v[160:161], v[158:159], off
	ds_read_b128 v[158:161], v134 offset:12480
	s_or_b32 s18, s2, 12
	v_readlane_b32 s20, v156, 12
	s_ashr_i32 s19, s18, 31
	s_lshl_b64 s[18:19], s[18:19], 11
	s_waitcnt lgkmcnt(0)
	v_pk_mul_f32 v[158:159], s[20:21], v[158:159] op_sel_hi:[0,1]
	v_pk_mul_f32 v[160:161], s[20:21], v[160:161] op_sel_hi:[0,1]
	v_cvt_pk_bf16_f32 v158, v158, v159
	v_cvt_pk_bf16_f32 v159, v160, v161
	v_lshl_add_u64 v[160:161], v[128:129], 0, s[18:19]
	global_store_dwordx2 v[160:161], v[158:159], off
	ds_read_b128 v[158:161], v134 offset:13520
	s_or_b32 s18, s2, 13
	v_readlane_b32 s20, v156, 13
	s_ashr_i32 s19, s18, 31
	s_lshl_b64 s[18:19], s[18:19], 11
	s_waitcnt lgkmcnt(0)
	v_pk_mul_f32 v[158:159], s[20:21], v[158:159] op_sel_hi:[0,1]
	v_pk_mul_f32 v[160:161], s[20:21], v[160:161] op_sel_hi:[0,1]
	v_cvt_pk_bf16_f32 v158, v158, v159
	v_cvt_pk_bf16_f32 v159, v160, v161
	v_lshl_add_u64 v[160:161], v[128:129], 0, s[18:19]
	global_store_dwordx2 v[160:161], v[158:159], off
	ds_read_b128 v[158:161], v134 offset:14560
	s_or_b32 s18, s2, 14
	v_readlane_b32 s20, v156, 14
	s_ashr_i32 s19, s18, 31
	s_lshl_b64 s[18:19], s[18:19], 11
	s_waitcnt lgkmcnt(0)
	v_pk_mul_f32 v[158:159], s[20:21], v[158:159] op_sel_hi:[0,1]
	v_pk_mul_f32 v[160:161], s[20:21], v[160:161] op_sel_hi:[0,1]
	v_cvt_pk_bf16_f32 v158, v158, v159
	v_cvt_pk_bf16_f32 v159, v160, v161
	v_lshl_add_u64 v[160:161], v[128:129], 0, s[18:19]
	global_store_dwordx2 v[160:161], v[158:159], off
	v_readlane_b32 s20, v156, 15
	ds_read_b128 v[156:159], v134 offset:15600
	s_or_b32 s18, s2, 15
	s_ashr_i32 s19, s18, 31
	s_lshl_b64 s[18:19], s[18:19], 11
	s_waitcnt lgkmcnt(0)
	v_pk_mul_f32 v[156:157], s[20:21], v[156:157] op_sel_hi:[0,1]
	v_pk_mul_f32 v[158:159], s[20:21], v[158:159] op_sel_hi:[0,1]
	v_cvt_pk_bf16_f32 v156, v156, v157
	v_cvt_pk_bf16_f32 v157, v158, v159
	v_lshl_add_u64 v[158:159], v[128:129], 0, s[18:19]
	s_add_i32 s18, s2, 0x80
	global_store_dwordx2 v[158:159], v[156:157], off
	s_waitcnt lgkmcnt(0)
	s_barrier
; template <int EPI, int TS, bool VT>
; DEVI void gemm_epilogue(const Params& p, char* smem, f32x4 (&acc)[2][2][4][2], int m0, int n0, float scale, const float* ssin,
;                         float* ssout, u16* xbout, int wid, int lane, int wr, int wc, int fr, int fq) {
;     ...
;   for (int ai = 0; ai < 2; ++ai) {
;     {
;       float* tw = T + (wr * 64 + fq * 4) * TS + wc * 32 + fr;
; #pragma unroll
;       for (int m = 0; m < 4; ++m)
; #pragma unroll
;         for (int j = 0; j < 4; ++j)
; #pragma unroll
;           for (int v = 0; v < 4; ++v) tw[(m * 16 + j) * TS + (v >> 1) * 128 + (v & 1) * 16] = acc[ai][v >> 1][m][v & 1][j];
;     }
;     __syncthreads();
;     ...
;           } else if constexpr (EPI == E_KV) {
;             const float4 a = *(const float4*)(Tr + 4 * lane);
;             uint2 o;
;             o.x = pack2(a.x * rs, a.y * rs);
;             o.y = pack2(a.z * rs, a.w * rs);
;             st_nt8((u16*)(wsb + OFF_KM) + (size_t)grow * 1024 + n0 + 4 * lane, o);
;           }
	ds_write2_b32 v135, v24, v28 offset1:16
	ds_write2_b32 v135, v56, v60 offset0:128 offset1:144
	ds_write2_b32 v136, v25, v29 offset0:4 offset1:20
	ds_write2_b32 v136, v57, v61 offset0:132 offset1:148
	ds_write2_b32 v137, v26, v30 offset0:8 offset1:24
	ds_write2_b32 v137, v58, v62 offset0:136 offset1:152
	ds_write2_b32 v138, v27, v31 offset0:12 offset1:28
	ds_write2_b32 v138, v59, v63 offset0:140 offset1:156
	ds_write2_b32 v139, v16, v20 offset0:64 offset1:80
	ds_write2_b32 v139, v48, v52 offset0:192 offset1:208
	ds_write2_b32 v140, v17, v21 offset0:68 offset1:84
	ds_write2_b32 v140, v49, v53 offset0:196 offset1:212
	ds_write2_b32 v141, v18, v22 offset0:72 offset1:88
	ds_write2_b32 v141, v50, v54 offset0:200 offset1:216
	ds_write2_b32 v142, v19, v23 offset0:76 offset1:92
	ds_write2_b32 v142, v51, v55 offset0:204 offset1:220
	ds_write2_b32 v143, v8, v12 offset0:128 offset1:144
	ds_write2_b32 v144, v40, v44 offset1:16
	ds_write2_b32 v144, v9, v13 offset0:132 offset1:148
	ds_write2_b32 v145, v41, v45 offset0:4 offset1:20
	ds_write2_b32 v145, v10, v14 offset0:136 offset1:152
	ds_write2_b32 v146, v42, v46 offset0:8 offset1:24
	ds_write2_b32 v146, v11, v15 offset0:140 offset1:156
	ds_write2_b32 v147, v43, v47 offset0:12 offset1:28
	ds_write2_b32 v148, v0, v4 offset0:192 offset1:208
	ds_write2_b32 v152, v32, v36 offset0:64 offset1:80
	ds_write2_b32 v152, v1, v5 offset0:196 offset1:212
	ds_write2_b32 v153, v33, v37 offset0:68 offset1:84
	ds_write2_b32 v153, v2, v6 offset0:200 offset1:216
	ds_write2_b32 v154, v34, v38 offset0:72 offset1:88
	ds_write2_b32 v154, v3, v7 offset0:204 offset1:220
	ds_write2_b32 v155, v35, v39 offset0:76 offset1:92
	v_or_b32_e32 v136, s18, v130
	v_ashrrev_i32_e32 v137, 31, v136
	v_lshl_add_u64 v[136:137], v[136:137], 2, s[8:9]
	s_waitcnt lgkmcnt(0)
	s_barrier
	global_load_dword v130, v[136:137], off
	ds_read_b128 v[136:139], v134
	s_ashr_i32 s19, s18, 31
	s_lshl_b64 s[18:19], s[18:19], 11
	s_waitcnt vmcnt(0) lgkmcnt(0)
	v_fmamk_f32 v130, v130, 0x3b800000, v150
	v_cmp_gt_f32_e32 vcc, s29, v130
	v_mul_f32_e32 v135, 0x4b800000, v130
	s_nop 0
	v_cndmask_b32_e32 v130, v130, v135, vcc
	v_rsq_f32_e32 v130, v130
	s_nop 0
	v_mul_f32_e32 v135, 0x45800000, v130
	v_cndmask_b32_e32 v130, v130, v135, vcc
	s_nop 0
	v_readlane_b32 s20, v130, 0
	s_nop 1
	v_pk_mul_f32 v[136:137], s[20:21], v[136:137] op_sel_hi:[0,1]
	v_pk_mul_f32 v[138:139], s[20:21], v[138:139] op_sel_hi:[0,1]
	v_cvt_pk_bf16_f32 v136, v136, v137
	v_cvt_pk_bf16_f32 v137, v138, v139
	v_lshl_add_u64 v[138:139], v[128:129], 0, s[18:19]
	global_store_dwordx2 v[138:139], v[136:137], off
	ds_read_b128 v[136:139], v134 offset:1040
	s_add_i32 s18, s2, 0x81
	v_readlane_b32 s20, v130, 1
	s_ashr_i32 s19, s18, 31
	s_lshl_b64 s[18:19], s[18:19], 11
	s_waitcnt lgkmcnt(0)
	v_pk_mul_f32 v[136:137], s[20:21], v[136:137] op_sel_hi:[0,1]
	v_pk_mul_f32 v[138:139], s[20:21], v[138:139] op_sel_hi:[0,1]
	v_cvt_pk_bf16_f32 v136, v136, v137
	v_cvt_pk_bf16_f32 v137, v138, v139
	v_lshl_add_u64 v[138:139], v[128:129], 0, s[18:19]
	global_store_dwordx2 v[138:139], v[136:137], off
	ds_read_b128 v[136:139], v134 offset:2080
	s_add_i32 s18, s2, 0x82
	v_readlane_b32 s20, v130, 2
	s_ashr_i32 s19, s18, 31
	s_lshl_b64 s[18:19], s[18:19], 11
	s_waitcnt lgkmcnt(0)
	v_pk_mul_f32 v[136:137], s[20:21], v[136:137] op_sel_hi:[0,1]
	v_pk_mul_f32 v[138:139], s[20:21], v[138:139] op_sel_hi:[0,1]
	v_cvt_pk_bf16_f32 v136, v136, v137
	v_cvt_pk_bf16_f32 v137, v138, v139
	v_lshl_add_u64 v[138:139], v[128:129], 0, s[18:19]
	global_store_dwordx2 v[138:139], v[136:137], off
	ds_read_b128 v[136:139], v134 offset:3120
	s_add_i32 s18, s2, 0x83
	v_readlane_b32 s20, v130, 3
	s_ashr_i32 s19, s18, 31
	s_lshl_b64 s[18:19], s[18:19], 11
	s_waitcnt lgkmcnt(0)
	v_pk_mul_f32 v[136:137], s[20:21], v[136:137] op_sel_hi:[0,1]
	v_pk_mul_f32 v[138:139], s[20:21], v[138:139] op_sel_hi:[0,1]
	v_cvt_pk_bf16_f32 v136, v136, v137
	v_cvt_pk_bf16_f32 v137, v138, v139
	v_lshl_add_u64 v[138:139], v[128:129], 0, s[18:19]
	global_store_dwordx2 v[138:139], v[136:137], off
	ds_read_b128 v[136:139], v134 offset:4160
	s_add_i32 s18, s2, 0x84
	v_readlane_b32 s20, v130, 4
	s_ashr_i32 s19, s18, 31
	s_lshl_b64 s[18:19], s[18:19], 11
	s_waitcnt lgkmcnt(0)
	v_pk_mul_f32 v[136:137], s[20:21], v[136:137] op_sel_hi:[0,1]
	v_pk_mul_f32 v[138:139], s[20:21], v[138:139] op_sel_hi:[0,1]
	v_cvt_pk_bf16_f32 v136, v136, v137
	v_cvt_pk_bf16_f32 v137, v138, v139
	v_lshl_add_u64 v[138:139], v[128:129], 0, s[18:19]
	global_store_dwordx2 v[138:139], v[136:137], off
	ds_read_b128 v[136:139], v134 offset:5200
	s_add_i32 s18, s2, 0x85
	v_readlane_b32 s20, v130, 5
	s_ashr_i32 s19, s18, 31
	s_lshl_b64 s[18:19], s[18:19], 11
	s_waitcnt lgkmcnt(0)
	v_pk_mul_f32 v[136:137], s[20:21], v[136:137] op_sel_hi:[0,1]
	v_pk_mul_f32 v[138:139], s[20:21], v[138:139] op_sel_hi:[0,1]
	v_cvt_pk_bf16_f32 v136, v136, v137
	v_cvt_pk_bf16_f32 v137, v138, v139
	v_lshl_add_u64 v[138:139], v[128:129], 0, s[18:19]
	global_store_dwordx2 v[138:139], v[136:137], off
	ds_read_b128 v[136:139], v134 offset:6240
	s_add_i32 s18, s2, 0x86
	v_readlane_b32 s20, v130, 6
	s_ashr_i32 s19, s18, 31
	s_lshl_b64 s[18:19], s[18:19], 11
	s_waitcnt lgkmcnt(0)
	v_pk_mul_f32 v[136:137], s[20:21], v[136:137] op_sel_hi:[0,1]
	v_pk_mul_f32 v[138:139], s[20:21], v[138:139] op_sel_hi:[0,1]
	v_cvt_pk_bf16_f32 v136, v136, v137
	v_cvt_pk_bf16_f32 v137, v138, v139
	v_lshl_add_u64 v[138:139], v[128:129], 0, s[18:19]
	global_store_dwordx2 v[138:139], v[136:137], off
	ds_read_b128 v[136:139], v134 offset:7280
	s_add_i32 s18, s2, 0x87
	v_readlane_b32 s20, v130, 7
	s_ashr_i32 s19, s18, 31
	s_lshl_b64 s[18:19], s[18:19], 11
	s_waitcnt lgkmcnt(0)
; template <int EPI, int TS, bool VT>
; DEVI void gemm_epilogue(const Params& p, char* smem, f32x4 (&acc)[2][2][4][2], int m0, int n0, float scale, const float* ssin,
;                         float* ssout, u16* xbout, int wid, int lane, int wr, int wc, int fr, int fq) {
;     ...
;           } else if constexpr (EPI == E_KV) {
;             const float4 a = *(const float4*)(Tr + 4 * lane);
;             uint2 o;
;             o.x = pack2(a.x * rs, a.y * rs);
;             o.y = pack2(a.z * rs, a.w * rs);
;             st_nt8((u16*)(wsb + OFF_KM) + (size_t)grow * 1024 + n0 + 4 * lane, o);
;           }
	v_pk_mul_f32 v[136:137], s[20:21], v[136:137] op_sel_hi:[0,1]
	v_pk_mul_f32 v[138:139], s[20:21], v[138:139] op_sel_hi:[0,1]
	v_cvt_pk_bf16_f32 v136, v136, v137
	v_cvt_pk_bf16_f32 v137, v138, v139
	v_lshl_add_u64 v[138:139], v[128:129], 0, s[18:19]
	global_store_dwordx2 v[138:139], v[136:137], off
	ds_read_b128 v[136:139], v134 offset:8320
	s_add_i32 s18, s2, 0x88
	v_readlane_b32 s20, v130, 8
	s_ashr_i32 s19, s18, 31
	s_lshl_b64 s[18:19], s[18:19], 11
	s_waitcnt lgkmcnt(0)
	v_pk_mul_f32 v[136:137], s[20:21], v[136:137] op_sel_hi:[0,1]
	v_pk_mul_f32 v[138:139], s[20:21], v[138:139] op_sel_hi:[0,1]
	v_cvt_pk_bf16_f32 v136, v136, v137
	v_cvt_pk_bf16_f32 v137, v138, v139
	v_lshl_add_u64 v[138:139], v[128:129], 0, s[18:19]
	global_store_dwordx2 v[138:139], v[136:137], off
	ds_read_b128 v[136:139], v134 offset:9360
	s_add_i32 s18, s2, 0x89
	v_readlane_b32 s20, v130, 9
	s_ashr_i32 s19, s18, 31
	s_lshl_b64 s[18:19], s[18:19], 11
	s_waitcnt lgkmcnt(0)
	v_pk_mul_f32 v[136:137], s[20:21], v[136:137] op_sel_hi:[0,1]
	v_pk_mul_f32 v[138:139], s[20:21], v[138:139] op_sel_hi:[0,1]
	v_cvt_pk_bf16_f32 v136, v136, v137
	v_cvt_pk_bf16_f32 v137, v138, v139
	v_lshl_add_u64 v[138:139], v[128:129], 0, s[18:19]
	global_store_dwordx2 v[138:139], v[136:137], off
	ds_read_b128 v[136:139], v134 offset:10400
	s_add_i32 s18, s2, 0x8a
	v_readlane_b32 s20, v130, 10
	s_ashr_i32 s19, s18, 31
	s_lshl_b64 s[18:19], s[18:19], 11
	s_waitcnt lgkmcnt(0)
	v_pk_mul_f32 v[136:137], s[20:21], v[136:137] op_sel_hi:[0,1]
	v_pk_mul_f32 v[138:139], s[20:21], v[138:139] op_sel_hi:[0,1]
	v_cvt_pk_bf16_f32 v136, v136, v137
	v_cvt_pk_bf16_f32 v137, v138, v139
	v_lshl_add_u64 v[138:139], v[128:129], 0, s[18:19]
	global_store_dwordx2 v[138:139], v[136:137], off
	ds_read_b128 v[136:139], v134 offset:11440
	s_add_i32 s18, s2, 0x8b
	v_readlane_b32 s20, v130, 11
	s_ashr_i32 s19, s18, 31
	s_lshl_b64 s[18:19], s[18:19], 11
	s_waitcnt lgkmcnt(0)
	v_pk_mul_f32 v[136:137], s[20:21], v[136:137] op_sel_hi:[0,1]
	v_pk_mul_f32 v[138:139], s[20:21], v[138:139] op_sel_hi:[0,1]
	v_cvt_pk_bf16_f32 v136, v136, v137
	v_cvt_pk_bf16_f32 v137, v138, v139
	v_lshl_add_u64 v[138:139], v[128:129], 0, s[18:19]
	global_store_dwordx2 v[138:139], v[136:137], off
	ds_read_b128 v[136:139], v134 offset:12480
	s_add_i32 s18, s2, 0x8c
	v_readlane_b32 s20, v130, 12
	s_ashr_i32 s19, s18, 31
	s_lshl_b64 s[18:19], s[18:19], 11
	s_waitcnt lgkmcnt(0)
	v_pk_mul_f32 v[136:137], s[20:21], v[136:137] op_sel_hi:[0,1]
	v_pk_mul_f32 v[138:139], s[20:21], v[138:139] op_sel_hi:[0,1]
	v_cvt_pk_bf16_f32 v136, v136, v137
	v_cvt_pk_bf16_f32 v137, v138, v139
	v_lshl_add_u64 v[138:139], v[128:129], 0, s[18:19]
	global_store_dwordx2 v[138:139], v[136:137], off
	ds_read_b128 v[136:139], v134 offset:13520
	s_add_i32 s18, s2, 0x8d
	v_readlane_b32 s20, v130, 13
	s_ashr_i32 s19, s18, 31
	s_lshl_b64 s[18:19], s[18:19], 11
	s_waitcnt lgkmcnt(0)
	v_pk_mul_f32 v[136:137], s[20:21], v[136:137] op_sel_hi:[0,1]
	v_pk_mul_f32 v[138:139], s[20:21], v[138:139] op_sel_hi:[0,1]
	v_cvt_pk_bf16_f32 v136, v136, v137
	v_cvt_pk_bf16_f32 v137, v138, v139
	v_lshl_add_u64 v[138:139], v[128:129], 0, s[18:19]
	global_store_dwordx2 v[138:139], v[136:137], off
	ds_read_b128 v[136:139], v134 offset:14560
	s_add_i32 s18, s2, 0x8e
	v_readlane_b32 s20, v130, 14
	s_ashr_i32 s19, s18, 31
	s_lshl_b64 s[18:19], s[18:19], 11
	s_waitcnt lgkmcnt(0)
	v_pk_mul_f32 v[136:137], s[20:21], v[136:137] op_sel_hi:[0,1]
	v_pk_mul_f32 v[138:139], s[20:21], v[138:139] op_sel_hi:[0,1]
	v_cvt_pk_bf16_f32 v136, v136, v137
	v_cvt_pk_bf16_f32 v137, v138, v139
	v_lshl_add_u64 v[138:139], v[128:129], 0, s[18:19]
	global_store_dwordx2 v[138:139], v[136:137], off
	ds_read_b128 v[134:137], v134 offset:15600
	s_addk_i32 s2, 0x8f
	v_readlane_b32 s18, v130, 15
	s_ashr_i32 s3, s2, 31
	s_lshl_b64 s[2:3], s[2:3], 11
	s_waitcnt lgkmcnt(0)
	v_pk_mul_f32 v[134:135], s[18:19], v[134:135] op_sel_hi:[0,1]
	v_pk_mul_f32 v[136:137], s[18:19], v[136:137] op_sel_hi:[0,1]
	v_cvt_pk_bf16_f32 v134, v134, v135
	v_cvt_pk_bf16_f32 v135, v136, v137
	v_lshl_add_u64 v[128:129], v[128:129], 0, s[2:3]
	global_store_dwordx2 v[128:129], v[134:135], off
	s_waitcnt lgkmcnt(0)
	s_barrier
	s_mov_b64 s[2:3], 0
; template <int EPI, int TS, bool VT>
; DEVI void gemm_epilogue(const Params& p, char* smem, f32x4 (&acc)[2][2][4][2], int m0, int n0, float scale, const float* ssin,
;                         float* ssout, u16* xbout, int wid, int lane, int wr, int wc, int fr, int fq) {
;     ...
;   for (int ai = 0; ai < 2; ++ai) {
;     {
;       float* tw = T + (wr * 64 + fq * 4) * TS + wc * 32 + fr;
; #pragma unroll
;       for (int m = 0; m < 4; ++m)
; #pragma unroll
;         for (int j = 0; j < 4; ++j)
; #pragma unroll
;           for (int v = 0; v < 4; ++v) tw[(m * 16 + j) * TS + (v >> 1) * 128 + (v & 1) * 16] = acc[ai][v >> 1][m][v & 1][j];
;     }
;     __syncthreads();
;     ...
;           } else {
;             rsa = rsqrtf(ssin[t0 + 2 * tp] * (1.f / 256.f) + EPS);
;             rsb = rsqrtf(ssin[t0 + 2 * tp + 1] * (1.f / 256.f) + EPS);
;             const size_t S = t0 < MP ? 4096 : 2048;
;             const size_t sb = t0 < MP ? (size_t)(t0 >> 12) * 8 * 128 * 4096 + (t0 & 4095)
;                                       : (size_t)MP * 1024 + (size_t)((t0 - MP) >> 11) * 8 * 128 * 2048 + (t0 & 2047);
;             vbase = (u16*)(wsb + OFF_VTM) + sb + (size_t)(n0 - 1024) * S + 2 * tp;
;             dstr = S;
;           }
.LBB0_913:
	s_andn2_b64 vcc, exec, s[2:3]
	s_cbranch_vccnz .LBB0_904
	s_movk_i32 s1, 0x404
	v_readlane_b32 s20, v254, 13
	v_mul_lo_u32 v128, v132, s1
	v_readlane_b32 s21, v254, 14
	v_add3_u32 v130, s15, v128, v133
	ds_write2_b32 v130, v88, v96 offset1:16
	ds_write2_b32 v130, v120, v124 offset0:128 offset1:144
	v_add_u32_e32 v120, 0x400, v130
	ds_write2_b32 v120, v89, v97 offset0:1 offset1:17
	ds_write2_b32 v120, v121, v125 offset0:129 offset1:145
	v_add_u32_e32 v121, 0x800, v130
	ds_write2_b32 v121, v90, v98 offset0:2 offset1:18
	ds_write2_b32 v121, v122, v126 offset0:130 offset1:146
	v_add_u32_e32 v122, 0xc00, v130
	ds_write2_b32 v122, v91, v99 offset0:3 offset1:19
	ds_write2_b32 v122, v123, v127 offset0:131 offset1:147
	v_add_u32_e32 v123, 0x4000, v130
	ds_write2_b32 v123, v80, v84 offset0:16 offset1:32
	ds_write2_b32 v123, v112, v116 offset0:144 offset1:160
	v_add_u32_e32 v112, 0x4400, v130
	ds_write2_b32 v112, v81, v85 offset0:17 offset1:33
	ds_write2_b32 v112, v113, v117 offset0:145 offset1:161
	v_add_u32_e32 v113, 0x4800, v130
	ds_write2_b32 v113, v82, v86 offset0:18 offset1:34
	ds_write2_b32 v113, v114, v118 offset0:146 offset1:162
	v_add_u32_e32 v114, 0x4c00, v130
	ds_write2_b32 v114, v83, v87 offset0:19 offset1:35
	ds_write2_b32 v114, v115, v119 offset0:147 offset1:163
	v_add_u32_e32 v115, 0x8000, v130
	ds_write2_b32 v115, v72, v76 offset0:32 offset1:48
	ds_write2_b32 v115, v104, v108 offset0:160 offset1:176
	v_add_u32_e32 v104, 0x8400, v130
	ds_write2_b32 v104, v73, v77 offset0:33 offset1:49
	ds_write2_b32 v104, v105, v109 offset0:161 offset1:177
	v_add_u32_e32 v105, 0x8800, v130
	v_lshlrev_b32_e32 v128, 1, v131
	ds_write2_b32 v105, v74, v78 offset0:34 offset1:50
	ds_write2_b32 v105, v106, v110 offset0:162 offset1:178
	v_add_u32_e32 v106, 0x8c00, v130
	v_and_b32_e32 v129, 62, v128
	ds_write2_b32 v106, v75, v79 offset0:35 offset1:51
	ds_write2_b32 v106, v107, v111 offset0:163 offset1:179
	v_add_u32_e32 v107, 0xc000, v130
	ds_write2_b32 v107, v64, v68 offset0:48 offset1:64
	ds_write2_b32 v107, v92, v100 offset0:176 offset1:192
	v_add_u32_e32 v108, 0xc400, v130
	v_or_b32_e32 v64, s12, v129
	ds_write2_b32 v108, v65, v69 offset0:49 offset1:65
	ds_write2_b32 v108, v93, v101 offset0:177 offset1:193
	v_add_u32_e32 v109, 0xc800, v130
	v_ashrrev_i32_e32 v65, 31, v64
	ds_write2_b32 v109, v66, v70 offset0:50 offset1:66
	ds_write2_b32 v109, v94, v102 offset0:178 offset1:194
	v_add_u32_e32 v102, 0xcc00, v130
	v_lshl_add_u64 v[64:65], v[64:65], 2, s[8:9]
	ds_write2_b32 v102, v67, v71 offset0:51 offset1:67
	ds_write2_b32 v102, v95, v103 offset0:179 offset1:195
	s_waitcnt vmcnt(0) lgkmcnt(0)
	s_barrier
	global_load_dwordx2 v[66:67], v[64:65], off
	s_cmpk_gt_i32 s62, 0xff
	s_cselect_b64 s[2:3], -1, 0
	s_mov_b64 s[18:19], -1
	s_and_b64 vcc, exec, s[2:3]
	s_cbranch_vccz .LBB0_916
	s_add_i32 s1, s12, 0xffff0000
	s_lshr_b32 s1, s1, 1
	s_and_b32 s44, s1, 0x7ffffc00
	s_lshl_b64 s[18:19], s[44:45], 11
	s_add_u32 s22, s18, 0x4000000
	s_addc_u32 s23, s19, 0
	s_mov_b64 s[18:19], 0

; template <int EPI, int TS, bool VT>
; DEVI void gemm_epilogue(const Params& p, char* smem, f32x4 (&acc)[2][2][4][2], int m0, int n0, float scale, const float* ssin,
;                         float* ssout, u16* xbout, int wid, int lane, int wr, int wc, int fr, int fq) {
;     ...
;           } else {
;             rsa = rsqrtf(ssin[t0 + 2 * tp] * (1.f / 256.f) + EPS);
;             rsb = rsqrtf(ssin[t0 + 2 * tp + 1] * (1.f / 256.f) + EPS);
;             const size_t S = t0 < MP ? 4096 : 2048;
;             const size_t sb = t0 < MP ? (size_t)(t0 >> 12) * 8 * 128 * 4096 + (t0 & 4095)
;                                       : (size_t)MP * 1024 + (size_t)((t0 - MP) >> 11) * 8 * 128 * 2048 + (t0 & 2047);
;             vbase = (u16*)(wsb + OFF_VTM) + sb + (size_t)(n0 - 1024) * S + 2 * tp;
;             dstr = S;
;           }
;           const float* Tc = T + (c * 64 + 2 * tp) * TS;
;           for (int d = 0; d < 16; ++d) {
;             const int dv = wid * 32 + d * 2 + dsub;
;             const float va = Tc[dv] * rsa, vb = Tc[TS + dv] * rsb;
;             *(unsigned*)(vbase + (size_t)dv * dstr) = pack2(va, vb);
;           }
.LBB0_919:
	s_add_u32 s15, s20, 0x3475ee00
	s_addc_u32 s63, s21, 0
	s_add_i32 s44, s0, 0xfffffc00
	s_mov_b32 s0, 0x3b800000
	s_waitcnt vmcnt(0) lgkmcnt(0)
	v_pk_fma_f32 v[66:67], v[66:67], s[0:1], v[150:151] op_sel_hi:[1,0,0]
	s_mov_b32 s20, 0x45800000
	v_mul_f32_e32 v68, 0x4b800000, v66
	v_cmp_gt_f32_e64 s[0:1], s29, v66
	v_cmp_gt_f32_e32 vcc, s29, v67
	v_lshrrev_b32_e32 v64, 5, v131
	v_cndmask_b32_e64 v66, v66, v68, s[0:1]
	v_mul_f32_e32 v68, 0x4b800000, v67
	v_cndmask_b32_e32 v67, v67, v68, vcc
	v_rsq_f32_e32 v66, v66
	v_rsq_f32_e32 v67, v67
	v_lshl_or_b32 v64, s13, 5, v64
	s_and_b32 s13, s19, s12
	v_lshlrev_b32_e32 v148, 1, v129
	v_pk_mul_f32 v[68:69], v[66:67], s[20:21] op_sel_hi:[1,0]
	v_ashrrev_i32_e32 v65, 31, v64
	v_cndmask_b32_e64 v96, v66, v68, s[0:1]
	s_lshl_b64 s[0:1], s[22:23], 1
	s_add_u32 s0, s15, s0
	s_addc_u32 s1, s63, s1
	s_lshl_b32 s13, s13, 1
	s_add_u32 s13, s0, s13
	s_addc_u32 s19, s1, 0
	s_lshl_b64 s[0:1], s[44:45], s18
	s_lshl_b64 s[0:1], s[0:1], 1
	s_add_u32 s0, s13, s0
	s_addc_u32 s1, s19, s1
	v_lshl_add_u64 v[98:99], s[0:1], 0, v[148:149]
	v_lshlrev_b32_e32 v66, 2, v64
	s_movk_i32 s0, 0x404
	v_mad_u32_u24 v100, v129, s0, v66
	v_add_u32_e32 v101, 0x400, v100
	v_cndmask_b32_e32 v97, v67, v69, vcc
	ds_read2_b32 v[66:67], v101 offset0:1 offset1:3
	ds_read2_b32 v[68:69], v100 offset1:2
	ds_read2_b32 v[70:71], v100 offset0:4 offset1:6
	ds_read2_b32 v[74:75], v100 offset0:8 offset1:10
	v_or_b32_e32 v82, 2, v64
	s_waitcnt lgkmcnt(3)
	v_mov_b32_e32 v73, v66
	s_waitcnt lgkmcnt(2)
	v_mov_b32_e32 v72, v68
	v_pk_mul_f32 v[72:73], v[96:97], v[72:73]
	v_ashrrev_i32_e32 v83, 31, v82
	v_cvt_pk_bf16_f32 v66, v72, v73
	v_lshlrev_b64 v[72:73], s18, v[64:65]
	v_lshl_add_u64 v[72:73], v[72:73], 1, v[98:99]
	global_store_dword v[72:73], v66, off
	v_mov_b32_e32 v66, v69
	v_pk_mul_f32 v[66:67], v[96:97], v[66:67]
	v_or_b32_e32 v72, 4, v64
	v_cvt_pk_bf16_f32 v68, v66, v67
	v_lshlrev_b64 v[66:67], s18, v[82:83]
	v_lshl_add_u64 v[66:67], v[66:67], 1, v[98:99]
	global_store_dword v[66:67], v68, off
	ds_read2_b32 v[66:67], v101 offset0:5 offset1:7
	s_waitcnt lgkmcnt(0)
	v_mov_b32_e32 v68, v70
	v_ashrrev_i32_e32 v73, 31, v72
	v_or_b32_e32 v88, 6, v64
	v_ashrrev_i32_e32 v89, 31, v88
	v_mov_b32_e32 v69, v66
	v_pk_mul_f32 v[68:69], v[96:97], v[68:69]
	v_or_b32_e32 v76, 8, v64
	v_cvt_pk_bf16_f32 v66, v68, v69
	v_lshlrev_b64 v[68:69], s18, v[72:73]
	v_lshl_add_u64 v[68:69], v[68:69], 1, v[98:99]
	global_store_dword v[68:69], v66, off
	v_mov_b32_e32 v66, v71
	v_pk_mul_f32 v[66:67], v[96:97], v[66:67]
	v_ashrrev_i32_e32 v77, 31, v76
	v_cvt_pk_bf16_f32 v68, v66, v67
	v_lshlrev_b64 v[66:67], s18, v[88:89]
	v_lshl_add_u64 v[66:67], v[66:67], 1, v[98:99]
	global_store_dword v[66:67], v68, off
	ds_read2_b32 v[66:67], v101 offset0:9 offset1:11
	v_mov_b32_e32 v68, v74
	v_or_b32_e32 v90, 10, v64
	v_ashrrev_i32_e32 v91, 31, v90
	v_or_b32_e32 v78, 12, v64
	s_waitcnt lgkmcnt(0)
	v_mov_b32_e32 v69, v66
	v_pk_mul_f32 v[68:69], v[96:97], v[68:69]
	v_ashrrev_i32_e32 v79, 31, v78
	v_cvt_pk_bf16_f32 v66, v68, v69
	v_lshlrev_b64 v[68:69], s18, v[76:77]
	v_lshl_add_u64 v[68:69], v[68:69], 1, v[98:99]
	global_store_dword v[68:69], v66, off
	v_mov_b32_e32 v66, v75
	v_pk_mul_f32 v[66:67], v[96:97], v[66:67]
	v_or_b32_e32 v94, 14, v64
	v_cvt_pk_bf16_f32 v68, v66, v67
	v_lshlrev_b64 v[66:67], s18, v[90:91]
	v_lshl_add_u64 v[66:67], v[66:67], 1, v[98:99]
	global_store_dword v[66:67], v68, off
	ds_read2_b32 v[66:67], v100 offset0:12 offset1:14
	ds_read2_b32 v[68:69], v101 offset0:13 offset1:15
	v_ashrrev_i32_e32 v95, 31, v94
	v_or_b32_e32 v86, 16, v64
	v_ashrrev_i32_e32 v87, 31, v86
	s_waitcnt lgkmcnt(0)
; template <int EPI, int TS, bool VT>
; DEVI void gemm_epilogue(const Params& p, char* smem, f32x4 (&acc)[2][2][4][2], int m0, int n0, float scale, const float* ssin,
;                         float* ssout, u16* xbout, int wid, int lane, int wr, int wc, int fr, int fq) {
;     ...
;             rsa = rsqrtf(ssin[t0 + 2 * tp] * (1.f / 256.f) + EPS);
;             rsb = rsqrtf(ssin[t0 + 2 * tp + 1] * (1.f / 256.f) + EPS);
;     ...
;           const float* Tc = T + (c * 64 + 2 * tp) * TS;
;           for (int d = 0; d < 16; ++d) {
;             const int dv = wid * 32 + d * 2 + dsub;
;             const float va = Tc[dv] * rsa, vb = Tc[TS + dv] * rsb;
;             *(unsigned*)(vbase + (size_t)dv * dstr) = pack2(va, vb);
;           }
	v_mov_b32_e32 v70, v66
	v_mov_b32_e32 v71, v68
	v_pk_mul_f32 v[70:71], v[96:97], v[70:71]
	v_mov_b32_e32 v68, v67
	v_cvt_pk_bf16_f32 v66, v70, v71
	v_lshlrev_b64 v[70:71], s18, v[78:79]
	v_lshl_add_u64 v[70:71], v[70:71], 1, v[98:99]
	global_store_dword v[70:71], v66, off
	v_pk_mul_f32 v[66:67], v[96:97], v[68:69]
	v_or_b32_e32 v92, 18, v64
	v_cvt_pk_bf16_f32 v68, v66, v67
	v_lshlrev_b64 v[66:67], s18, v[94:95]
	v_lshl_add_u64 v[66:67], v[66:67], 1, v[98:99]
	global_store_dword v[66:67], v68, off
	ds_read2_b32 v[66:67], v100 offset0:16 offset1:18
	ds_read2_b32 v[68:69], v101 offset0:17 offset1:19
	v_ashrrev_i32_e32 v93, 31, v92
	v_or_b32_e32 v80, 20, v64
	v_ashrrev_i32_e32 v81, 31, v80
	s_waitcnt lgkmcnt(0)
	v_mov_b32_e32 v70, v66
	v_mov_b32_e32 v71, v68
	v_pk_mul_f32 v[70:71], v[96:97], v[70:71]
	v_mov_b32_e32 v68, v67
	v_cvt_pk_bf16_f32 v66, v70, v71
	v_lshlrev_b64 v[70:71], s18, v[86:87]
	v_lshl_add_u64 v[70:71], v[70:71], 1, v[98:99]
	global_store_dword v[70:71], v66, off
	v_pk_mul_f32 v[66:67], v[96:97], v[68:69]
	v_or_b32_e32 v84, 22, v64
	v_cvt_pk_bf16_f32 v68, v66, v67
	v_lshlrev_b64 v[66:67], s18, v[92:93]
	v_lshl_add_u64 v[66:67], v[66:67], 1, v[98:99]
	global_store_dword v[66:67], v68, off
	ds_read2_b32 v[66:67], v100 offset0:20 offset1:22
	ds_read2_b32 v[68:69], v101 offset0:21 offset1:23
	v_ashrrev_i32_e32 v85, 31, v84
	s_or_b32 s13, s12, 64
	s_andn2_b64 vcc, exec, s[2:3]
	s_waitcnt lgkmcnt(0)
	v_mov_b32_e32 v70, v66
	v_mov_b32_e32 v71, v68
	v_pk_mul_f32 v[70:71], v[96:97], v[70:71]
	v_mov_b32_e32 v68, v67
	v_cvt_pk_bf16_f32 v66, v70, v71
	v_lshlrev_b64 v[70:71], s18, v[80:81]
	v_lshl_add_u64 v[70:71], v[70:71], 1, v[98:99]
	global_store_dword v[70:71], v66, off
	v_pk_mul_f32 v[66:67], v[96:97], v[68:69]
	v_or_b32_e32 v70, 24, v64
	v_cvt_pk_bf16_f32 v68, v66, v67
	v_lshlrev_b64 v[66:67], s18, v[84:85]
	v_lshl_add_u64 v[66:67], v[66:67], 1, v[98:99]
	global_store_dword v[66:67], v68, off
	ds_read2_b32 v[66:67], v100 offset0:24 offset1:26
	ds_read2_b32 v[68:69], v101 offset0:25 offset1:27
	v_ashrrev_i32_e32 v71, 31, v70
	s_waitcnt lgkmcnt(0)
	v_mov_b32_e32 v74, v66
	v_mov_b32_e32 v75, v68
	v_pk_mul_f32 v[74:75], v[96:97], v[74:75]
	v_mov_b32_e32 v68, v67
	v_cvt_pk_bf16_f32 v66, v74, v75
	v_lshlrev_b64 v[74:75], s18, v[70:71]
	v_lshl_add_u64 v[74:75], v[74:75], 1, v[98:99]
	global_store_dword v[74:75], v66, off
	v_or_b32_e32 v74, 26, v64
	v_ashrrev_i32_e32 v75, 31, v74
	v_pk_mul_f32 v[66:67], v[96:97], v[68:69]
	s_nop 0
	v_cvt_pk_bf16_f32 v68, v66, v67
	v_lshlrev_b64 v[66:67], s18, v[74:75]
	v_lshl_add_u64 v[66:67], v[66:67], 1, v[98:99]
	global_store_dword v[66:67], v68, off
	ds_read2_b32 v[110:111], v100 offset0:28 offset1:30
	ds_read2_b32 v[116:117], v101 offset0:29 offset1:31
	v_or_b32_e32 v66, 28, v64
	v_ashrrev_i32_e32 v67, 31, v66
	s_waitcnt lgkmcnt(0)
	v_mov_b32_e32 v68, v110
	v_mov_b32_e32 v69, v116
	v_pk_mul_f32 v[68:69], v[96:97], v[68:69]
	v_mov_b32_e32 v116, v111
	v_cvt_pk_bf16_f32 v103, v68, v69
	v_lshlrev_b64 v[68:69], s18, v[66:67]
	v_lshl_add_u64 v[68:69], v[68:69], 1, v[98:99]
	global_store_dword v[68:69], v103, off
	v_or_b32_e32 v68, 30, v64
	v_ashrrev_i32_e32 v69, 31, v68
	v_pk_mul_f32 v[96:97], v[96:97], v[116:117]
	s_nop 0
	v_cvt_pk_bf16_f32 v103, v96, v97
	v_lshlrev_b64 v[96:97], s18, v[68:69]
	v_lshl_add_u64 v[96:97], v[96:97], 1, v[98:99]
	global_store_dword v[96:97], v103, off
	v_or_b32_e32 v96, s13, v128
	v_ashrrev_i32_e32 v97, 31, v96
	v_lshl_add_u64 v[96:97], v[96:97], 2, s[8:9]
	global_load_dwordx2 v[96:97], v[96:97], off
	v_cndmask_b32_e64 v98, 0, 1, s[2:3]
	s_mov_b64 s[18:19], -1
	v_cmp_ne_u32_e64 s[0:1], 1, v98
	s_cbranch_vccnz .LBB0_921
	s_add_i32 s2, s12, 0xffff0040
	s_lshr_b32 s2, s2, 1
	s_and_b32 s2, s2, 0x7ffffc00
	s_mov_b32 s3, s45
	s_lshl_b64 s[2:3], s[2:3], 11
	s_add_u32 s20, s2, 0x4000000
	s_addc_u32 s21, s3, 0
	s_mov_b64 s[18:19], 0

; template <int EPI, int TS, bool VT>
; DEVI void gemm_epilogue(const Params& p, char* smem, f32x4 (&acc)[2][2][4][2], int m0, int n0, float scale, const float* ssin,
;                         float* ssout, u16* xbout, int wid, int lane, int wr, int wc, int fr, int fq) {
;     ...
;           } else {
;             rsa = rsqrtf(ssin[t0 + 2 * tp] * (1.f / 256.f) + EPS);
;             rsb = rsqrtf(ssin[t0 + 2 * tp + 1] * (1.f / 256.f) + EPS);
;             const size_t S = t0 < MP ? 4096 : 2048;
;             const size_t sb = t0 < MP ? (size_t)(t0 >> 12) * 8 * 128 * 4096 + (t0 & 4095)
;                                       : (size_t)MP * 1024 + (size_t)((t0 - MP) >> 11) * 8 * 128 * 2048 + (t0 & 2047);
;             vbase = (u16*)(wsb + OFF_VTM) + sb + (size_t)(n0 - 1024) * S + 2 * tp;
;             dstr = S;
;           }
;           const float* Tc = T + (c * 64 + 2 * tp) * TS;
;           for (int d = 0; d < 16; ++d) {
;             const int dv = wid * 32 + d * 2 + dsub;
;             const float va = Tc[dv] * rsa, vb = Tc[TS + dv] * rsb;
;             *(unsigned*)(vbase + (size_t)dv * dstr) = pack2(va, vb);
;           }
.LBB0_924:
	s_mov_b32 s2, 0x3b800000
	s_waitcnt vmcnt(0) lgkmcnt(0)
	v_pk_fma_f32 v[96:97], v[96:97], s[2:3], v[150:151] op_sel_hi:[1,0,0]
	s_mov_b32 s22, 0x45800000
	v_mul_f32_e32 v98, 0x4b800000, v96
	v_cmp_gt_f32_e32 vcc, s29, v96
	v_cmp_gt_f32_e64 s[2:3], s29, v97
	s_and_b32 s13, s19, s13
	v_cndmask_b32_e32 v96, v96, v98, vcc
	v_mul_f32_e32 v98, 0x4b800000, v97
	v_cndmask_b32_e64 v97, v97, v98, s[2:3]
	v_rsq_f32_e32 v96, v96
	v_rsq_f32_e32 v97, v97
	v_or_b32_e32 v98, 64, v128
	v_mul_u32_u24_e32 v103, 0x404, v98
	v_pk_mul_f32 v[98:99], v[96:97], s[22:23] op_sel_hi:[1,0]
	s_nop 0
	v_cndmask_b32_e64 v99, v97, v99, s[2:3]
	v_cndmask_b32_e32 v98, v96, v98, vcc
	v_lshl_add_u32 v96, v64, 2, v103
	s_lshl_b64 s[2:3], s[20:21], 1
	s_add_u32 s2, s15, s2
	v_add_u32_e32 v97, 0x400, v96
	ds_read2_b32 v[110:111], v96 offset1:2
	ds_read2_b32 v[116:117], v97 offset0:1 offset1:3
	s_addc_u32 s3, s63, s3
	s_lshl_b32 s13, s13, 1
	s_add_u32 s13, s2, s13
	s_addc_u32 s19, s3, 0
	s_lshl_b64 s[2:3], s[44:45], s18
	s_lshl_b64 s[2:3], s[2:3], 1
	s_add_u32 s2, s13, s2
	s_waitcnt lgkmcnt(1)
	v_mov_b32_e32 v132, v110
	s_waitcnt lgkmcnt(0)
	v_mov_b32_e32 v133, v116
	s_addc_u32 s3, s19, s3
	v_pk_mul_f32 v[132:133], v[98:99], v[132:133]
	v_lshl_add_u64 v[118:119], s[2:3], 0, v[148:149]
	v_cvt_pk_bf16_f32 v103, v132, v133
	v_lshlrev_b64 v[132:133], s18, v[64:65]
	v_mov_b32_e32 v116, v111
	v_lshl_add_u64 v[132:133], v[132:133], 1, v[118:119]
	v_pk_mul_f32 v[110:111], v[98:99], v[116:117]
	ds_read2_b32 v[124:125], v96 offset0:4 offset1:6
	ds_read2_b32 v[126:127], v96 offset0:8 offset1:10
	global_store_dword v[132:133], v103, off
	v_cvt_pk_bf16_f32 v103, v110, v111
	ds_read2_b32 v[110:111], v97 offset0:5 offset1:7
	v_lshlrev_b64 v[116:117], s18, v[82:83]
	v_lshl_add_u64 v[116:117], v[116:117], 1, v[118:119]
	global_store_dword v[116:117], v103, off
	s_waitcnt lgkmcnt(0)
	v_mov_b32_e32 v116, v124
	v_mov_b32_e32 v117, v110
	v_pk_mul_f32 v[116:117], v[98:99], v[116:117]
	v_mov_b32_e32 v110, v125
	v_cvt_pk_bf16_f32 v103, v116, v117
	v_lshlrev_b64 v[116:117], s18, v[72:73]
	v_lshl_add_u64 v[116:117], v[116:117], 1, v[118:119]
	v_pk_mul_f32 v[110:111], v[98:99], v[110:111]
	global_store_dword v[116:117], v103, off
	v_cvt_pk_bf16_f32 v103, v110, v111
	ds_read2_b32 v[110:111], v97 offset0:9 offset1:11
	v_lshlrev_b64 v[116:117], s18, v[88:89]
	v_lshl_add_u64 v[116:117], v[116:117], 1, v[118:119]
	global_store_dword v[116:117], v103, off
	v_mov_b32_e32 v116, v126
	s_waitcnt lgkmcnt(0)
	v_mov_b32_e32 v117, v110
	v_pk_mul_f32 v[116:117], v[98:99], v[116:117]
	v_mov_b32_e32 v110, v127
	v_cvt_pk_bf16_f32 v103, v116, v117
	v_lshlrev_b64 v[116:117], s18, v[76:77]
	v_lshl_add_u64 v[116:117], v[116:117], 1, v[118:119]
	global_store_dword v[116:117], v103, off
	v_pk_mul_f32 v[110:111], v[98:99], v[110:111]
	v_lshlrev_b64 v[124:125], s18, v[90:91]
	v_cvt_pk_bf16_f32 v103, v110, v111
	ds_read2_b32 v[110:111], v96 offset0:12 offset1:14
	ds_read2_b32 v[116:117], v97 offset0:13 offset1:15
	v_lshl_add_u64 v[124:125], v[124:125], 1, v[118:119]
	global_store_dword v[124:125], v103, off
	s_and_b64 vcc, exec, s[0:1]
	s_waitcnt lgkmcnt(0)
	v_mov_b32_e32 v124, v110
	v_mov_b32_e32 v125, v116
	v_pk_mul_f32 v[124:125], v[98:99], v[124:125]
	v_mov_b32_e32 v116, v111
	v_cvt_pk_bf16_f32 v103, v124, v125
	v_lshlrev_b64 v[124:125], s18, v[78:79]
	v_lshl_add_u64 v[124:125], v[124:125], 1, v[118:119]
	global_store_dword v[124:125], v103, off
	v_pk_mul_f32 v[110:111], v[98:99], v[116:117]
	v_lshlrev_b64 v[124:125], s18, v[94:95]
	v_cvt_pk_bf16_f32 v103, v110, v111
	ds_read2_b32 v[110:111], v96 offset0:16 offset1:18
	ds_read2_b32 v[116:117], v97 offset0:17 offset1:19
	v_lshl_add_u64 v[124:125], v[124:125], 1, v[118:119]
	global_store_dword v[124:125], v103, off
	s_mov_b64 s[2:3], -1
	s_waitcnt lgkmcnt(0)
	v_mov_b32_e32 v124, v110
	v_mov_b32_e32 v125, v116
	v_pk_mul_f32 v[124:125], v[98:99], v[124:125]
	v_mov_b32_e32 v116, v111
	v_cvt_pk_bf16_f32 v103, v124, v125
	v_lshlrev_b64 v[124:125], s18, v[86:87]
	v_lshl_add_u64 v[124:125], v[124:125], 1, v[118:119]
	global_store_dword v[124:125], v103, off
	v_pk_mul_f32 v[110:111], v[98:99], v[116:117]
	v_lshlrev_b64 v[124:125], s18, v[92:93]
	v_cvt_pk_bf16_f32 v103, v110, v111
	ds_read2_b32 v[110:111], v96 offset0:20 offset1:22
	ds_read2_b32 v[116:117], v97 offset0:21 offset1:23
	v_lshl_add_u64 v[124:125], v[124:125], 1, v[118:119]
	global_store_dword v[124:125], v103, off
	s_waitcnt lgkmcnt(0)
	v_mov_b32_e32 v124, v110
	v_mov_b32_e32 v125, v116
	v_pk_mul_f32 v[124:125], v[98:99], v[124:125]
	v_mov_b32_e32 v116, v111
	v_cvt_pk_bf16_f32 v103, v124, v125
	v_lshlrev_b64 v[124:125], s18, v[80:81]
	v_lshl_add_u64 v[124:125], v[124:125], 1, v[118:119]
	global_store_dword v[124:125], v103, off
	v_pk_mul_f32 v[110:111], v[98:99], v[116:117]
	v_lshlrev_b64 v[124:125], s18, v[84:85]
	v_cvt_pk_bf16_f32 v103, v110, v111
	ds_read2_b32 v[110:111], v96 offset0:24 offset1:26
	ds_read2_b32 v[116:117], v97 offset0:25 offset1:27
	v_lshl_add_u64 v[124:125], v[124:125], 1, v[118:119]
	global_store_dword v[124:125], v103, off
	s_waitcnt lgkmcnt(0)
	v_mov_b32_e32 v124, v110
	v_mov_b32_e32 v125, v116
	v_pk_mul_f32 v[124:125], v[98:99], v[124:125]
	v_mov_b32_e32 v116, v111
	v_cvt_pk_bf16_f32 v103, v124, v125
	v_lshlrev_b64 v[124:125], s18, v[70:71]
	v_lshl_add_u64 v[124:125], v[124:125], 1, v[118:119]
	global_store_dword v[124:125], v103, off
	v_pk_mul_f32 v[110:111], v[98:99], v[116:117]
	v_lshlrev_b64 v[124:125], s18, v[74:75]
	v_cvt_pk_bf16_f32 v103, v110, v111
	ds_read2_b32 v[110:111], v96 offset0:28 offset1:30
	ds_read2_b32 v[116:117], v97 offset0:29 offset1:31
	v_lshl_add_u64 v[124:125], v[124:125], 1, v[118:119]
	global_store_dword v[124:125], v103, off
	s_waitcnt lgkmcnt(0)
	v_mov_b32_e32 v124, v110
	v_mov_b32_e32 v125, v116
	v_pk_mul_f32 v[124:125], v[98:99], v[124:125]
	v_mov_b32_e32 v116, v111
	v_cvt_pk_bf16_f32 v103, v124, v125
	v_lshlrev_b64 v[124:125], s18, v[66:67]
	v_lshl_add_u64 v[124:125], v[124:125], 1, v[118:119]
	v_pk_mul_f32 v[98:99], v[98:99], v[116:117]
	global_store_dword v[124:125], v103, off
	v_cvt_pk_bf16_f32 v103, v98, v99
	v_lshlrev_b64 v[98:99], s18, v[68:69]
	v_lshl_add_u64 v[98:99], v[98:99], 1, v[118:119]
	global_store_dword v[98:99], v103, off
	s_waitcnt lgkmcnt(0)
	s_barrier
; template <int EPI, int TS, bool VT>
; DEVI void gemm_epilogue(const Params& p, char* smem, f32x4 (&acc)[2][2][4][2], int m0, int n0, float scale, const float* ssin,
;                         float* ssout, u16* xbout, int wid, int lane, int wr, int wc, int fr, int fq) {
;     ...
;   for (int ai = 0; ai < 2; ++ai) {
;     {
;       float* tw = T + (wr * 64 + fq * 4) * TS + wc * 32 + fr;
; #pragma unroll
;       for (int m = 0; m < 4; ++m)
; #pragma unroll
;         for (int j = 0; j < 4; ++j)
; #pragma unroll
;           for (int v = 0; v < 4; ++v) tw[(m * 16 + j) * TS + (v >> 1) * 128 + (v & 1) * 16] = acc[ai][v >> 1][m][v & 1][j];
;     }
;     __syncthreads();
;     ...
;             rsa = rsqrtf(ssin[t0 + 2 * tp] * (1.f / 256.f) + EPS);
;             rsb = rsqrtf(ssin[t0 + 2 * tp + 1] * (1.f / 256.f) + EPS);
	ds_write2_b32 v130, v24, v28 offset1:16
	ds_write2_b32 v130, v56, v60 offset0:128 offset1:144
	ds_write2_b32 v120, v25, v29 offset0:1 offset1:17
	ds_write2_b32 v120, v57, v61 offset0:129 offset1:145
	ds_write2_b32 v121, v26, v30 offset0:2 offset1:18
	ds_write2_b32 v121, v58, v62 offset0:130 offset1:146
	ds_write2_b32 v122, v27, v31 offset0:3 offset1:19
	ds_write2_b32 v122, v59, v63 offset0:131 offset1:147
	ds_write2_b32 v123, v16, v20 offset0:16 offset1:32
	ds_write2_b32 v123, v48, v52 offset0:144 offset1:160
	ds_write2_b32 v112, v17, v21 offset0:17 offset1:33
	ds_write2_b32 v112, v49, v53 offset0:145 offset1:161
	ds_write2_b32 v113, v18, v22 offset0:18 offset1:34
	ds_write2_b32 v113, v50, v54 offset0:146 offset1:162
	ds_write2_b32 v114, v19, v23 offset0:19 offset1:35
	ds_write2_b32 v114, v51, v55 offset0:147 offset1:163
	ds_write2_b32 v115, v8, v12 offset0:32 offset1:48
	ds_write2_b32 v115, v40, v44 offset0:160 offset1:176
	ds_write2_b32 v104, v9, v13 offset0:33 offset1:49
	ds_write2_b32 v104, v41, v45 offset0:161 offset1:177
	ds_write2_b32 v105, v10, v14 offset0:34 offset1:50
	ds_write2_b32 v105, v42, v46 offset0:162 offset1:178
	ds_write2_b32 v106, v11, v15 offset0:35 offset1:51
	ds_write2_b32 v106, v43, v47 offset0:163 offset1:179
	ds_write2_b32 v107, v0, v4 offset0:48 offset1:64
	ds_write2_b32 v107, v32, v36 offset0:176 offset1:192
	ds_write2_b32 v108, v1, v5 offset0:49 offset1:65
	ds_write2_b32 v108, v33, v37 offset0:177 offset1:193
	ds_write2_b32 v109, v2, v6 offset0:50 offset1:66
	ds_write2_b32 v109, v34, v38 offset0:178 offset1:194
	ds_write2_b32 v102, v3, v7 offset0:51 offset1:67
	ds_write2_b32 v102, v35, v39 offset0:179 offset1:195
	v_or_b32_e32 v0, s14, v129
	v_ashrrev_i32_e32 v1, 31, v0
	v_lshl_add_u64 v[0:1], v[0:1], 2, s[8:9]
	s_waitcnt lgkmcnt(0)
	s_barrier
	global_load_dwordx2 v[0:1], v[0:1], off
	s_cbranch_vccnz .LBB0_926
	s_add_i32 s2, s12, 0xffff0080
	s_lshr_b32 s2, s2, 1
	s_and_b32 s2, s2, 0x7ffffc00
	s_mov_b32 s3, s45
	s_lshl_b64 s[2:3], s[2:3], 11
	s_add_u32 s20, s2, 0x4000000
	s_addc_u32 s21, s3, 0
	s_mov_b64 s[2:3], 0

; template <int EPI, int TS, bool VT>
; DEVI void gemm_epilogue(const Params& p, char* smem, f32x4 (&acc)[2][2][4][2], int m0, int n0, float scale, const float* ssin,
;                         float* ssout, u16* xbout, int wid, int lane, int wr, int wc, int fr, int fq) {
;     ...
;           } else {
;             rsa = rsqrtf(ssin[t0 + 2 * tp] * (1.f / 256.f) + EPS);
;             rsb = rsqrtf(ssin[t0 + 2 * tp + 1] * (1.f / 256.f) + EPS);
;             const size_t S = t0 < MP ? 4096 : 2048;
;             const size_t sb = t0 < MP ? (size_t)(t0 >> 12) * 8 * 128 * 4096 + (t0 & 4095)
;                                       : (size_t)MP * 1024 + (size_t)((t0 - MP) >> 11) * 8 * 128 * 2048 + (t0 & 2047);
;             vbase = (u16*)(wsb + OFF_VTM) + sb + (size_t)(n0 - 1024) * S + 2 * tp;
;             dstr = S;
;           }
;           const float* Tc = T + (c * 64 + 2 * tp) * TS;
;           for (int d = 0; d < 16; ++d) {
;             const int dv = wid * 32 + d * 2 + dsub;
;             const float va = Tc[dv] * rsa, vb = Tc[TS + dv] * rsb;
;             *(unsigned*)(vbase + (size_t)dv * dstr) = pack2(va, vb);
;           }
.LBB0_929:
	s_mov_b32 s2, 0x3b800000
	s_waitcnt vmcnt(0) lgkmcnt(0)
	v_pk_fma_f32 v[0:1], v[0:1], s[2:3], v[150:151] op_sel_hi:[1,0,0]
	s_and_b32 s13, s13, s14
	v_mul_f32_e32 v2, 0x4b800000, v0
	v_cmp_gt_f32_e32 vcc, s29, v0
	v_cmp_gt_f32_e64 s[2:3], s29, v1
	s_nop 0
	v_cndmask_b32_e32 v0, v0, v2, vcc
	v_mul_f32_e32 v2, 0x4b800000, v1
	v_cndmask_b32_e64 v1, v1, v2, s[2:3]
	v_rsq_f32_e32 v0, v0
	v_rsq_f32_e32 v1, v1
	s_nop 0
	v_pk_mul_f32 v[2:3], v[0:1], s[22:23] op_sel_hi:[1,0]
	s_nop 0
	v_cndmask_b32_e64 v1, v1, v3, s[2:3]
	s_lshl_b64 s[2:3], s[20:21], 1
	v_cndmask_b32_e32 v0, v0, v2, vcc
	s_add_u32 s2, s15, s2
	ds_read2_b32 v[2:3], v100 offset1:2
	ds_read2_b32 v[4:5], v101 offset0:1 offset1:3
	s_addc_u32 s3, s63, s3
	s_lshl_b32 s13, s13, 1
	s_add_u32 s13, s2, s13
	s_addc_u32 s14, s3, 0
	s_lshl_b64 s[2:3], s[44:45], s18
	s_lshl_b64 s[2:3], s[2:3], 1
	s_add_u32 s2, s13, s2
	s_waitcnt lgkmcnt(1)
	v_mov_b32_e32 v12, v2
	s_waitcnt lgkmcnt(0)
	v_mov_b32_e32 v13, v4
	s_addc_u32 s3, s14, s3
	v_pk_mul_f32 v[12:13], v[0:1], v[12:13]
	v_lshl_add_u64 v[6:7], s[2:3], 0, v[148:149]
	v_cvt_pk_bf16_f32 v2, v12, v13
	v_lshlrev_b64 v[12:13], s18, v[64:65]
	v_lshl_add_u64 v[12:13], v[12:13], 1, v[6:7]
	v_mov_b32_e32 v4, v3
	ds_read2_b32 v[8:9], v100 offset0:4 offset1:6
	ds_read2_b32 v[10:11], v100 offset0:8 offset1:10
	global_store_dword v[12:13], v2, off
	v_pk_mul_f32 v[2:3], v[0:1], v[4:5]
	v_lshlrev_b64 v[4:5], s18, v[82:83]
	v_cvt_pk_bf16_f32 v12, v2, v3
	ds_read2_b32 v[2:3], v101 offset0:5 offset1:7
	v_lshl_add_u64 v[4:5], v[4:5], 1, v[6:7]
	global_store_dword v[4:5], v12, off
	s_waitcnt lgkmcnt(0)
	v_mov_b32_e32 v4, v8
	s_or_b32 s13, s12, 0xc0
	v_mov_b32_e32 v5, v2
	v_pk_mul_f32 v[4:5], v[0:1], v[4:5]
	s_and_b64 vcc, exec, s[0:1]
	v_cvt_pk_bf16_f32 v2, v4, v5
	v_lshlrev_b64 v[4:5], s18, v[72:73]
	v_lshl_add_u64 v[4:5], v[4:5], 1, v[6:7]
	global_store_dword v[4:5], v2, off
	v_mov_b32_e32 v2, v9
	v_pk_mul_f32 v[2:3], v[0:1], v[2:3]
	v_lshlrev_b64 v[4:5], s18, v[88:89]
	v_cvt_pk_bf16_f32 v8, v2, v3
	ds_read2_b32 v[2:3], v101 offset0:9 offset1:11
	v_lshl_add_u64 v[4:5], v[4:5], 1, v[6:7]
	global_store_dword v[4:5], v8, off
	v_mov_b32_e32 v4, v10
	ds_read2_b32 v[8:9], v101 offset0:13 offset1:15
	s_waitcnt lgkmcnt(0)
	v_mov_b32_e32 v5, v2
	v_pk_mul_f32 v[4:5], v[0:1], v[4:5]
	s_mov_b64 s[2:3], -1
	v_cvt_pk_bf16_f32 v2, v4, v5
	v_lshlrev_b64 v[4:5], s18, v[76:77]
	v_lshl_add_u64 v[4:5], v[4:5], 1, v[6:7]
	global_store_dword v[4:5], v2, off
	v_mov_b32_e32 v2, v11
	v_pk_mul_f32 v[2:3], v[0:1], v[2:3]
	ds_read2_b32 v[4:5], v100 offset0:12 offset1:14
	v_cvt_pk_bf16_f32 v12, v2, v3
	v_or_b32_e32 v2, s13, v128
	v_ashrrev_i32_e32 v3, 31, v2
	v_lshl_add_u64 v[2:3], v[2:3], 2, s[8:9]
	global_load_dwordx2 v[2:3], v[2:3], off
	v_lshlrev_b64 v[10:11], s18, v[90:91]
	v_lshl_add_u64 v[10:11], v[10:11], 1, v[6:7]
	global_store_dword v[10:11], v12, off
	s_waitcnt lgkmcnt(0)
	v_mov_b32_e32 v10, v4
	v_mov_b32_e32 v11, v8
	v_pk_mul_f32 v[10:11], v[0:1], v[10:11]
	v_mov_b32_e32 v8, v5
	v_cvt_pk_bf16_f32 v4, v10, v11
	v_lshlrev_b64 v[10:11], s18, v[78:79]
	v_lshl_add_u64 v[10:11], v[10:11], 1, v[6:7]
	global_store_dword v[10:11], v4, off
	v_pk_mul_f32 v[4:5], v[0:1], v[8:9]
	v_lshlrev_b64 v[10:11], s18, v[94:95]
	v_cvt_pk_bf16_f32 v12, v4, v5
	ds_read2_b32 v[4:5], v100 offset0:16 offset1:18
	ds_read2_b32 v[8:9], v101 offset0:17 offset1:19
	v_lshl_add_u64 v[10:11], v[10:11], 1, v[6:7]
	global_store_dword v[10:11], v12, off
	s_waitcnt lgkmcnt(0)
	v_mov_b32_e32 v10, v4
	v_mov_b32_e32 v11, v8
	v_pk_mul_f32 v[10:11], v[0:1], v[10:11]
	v_mov_b32_e32 v8, v5
	v_cvt_pk_bf16_f32 v4, v10, v11
	v_lshlrev_b64 v[10:11], s18, v[86:87]
	v_lshl_add_u64 v[10:11], v[10:11], 1, v[6:7]
	global_store_dword v[10:11], v4, off
	v_pk_mul_f32 v[4:5], v[0:1], v[8:9]
	v_lshlrev_b64 v[10:11], s18, v[92:93]
	v_cvt_pk_bf16_f32 v12, v4, v5
	ds_read2_b32 v[4:5], v100 offset0:20 offset1:22
	ds_read2_b32 v[8:9], v101 offset0:21 offset1:23
	v_lshl_add_u64 v[10:11], v[10:11], 1, v[6:7]
	global_store_dword v[10:11], v12, off
	s_waitcnt lgkmcnt(0)
	v_mov_b32_e32 v10, v4
	v_mov_b32_e32 v11, v8
	v_pk_mul_f32 v[10:11], v[0:1], v[10:11]
	v_mov_b32_e32 v8, v5
	v_cvt_pk_bf16_f32 v4, v10, v11
	v_lshlrev_b64 v[10:11], s18, v[80:81]
	v_lshl_add_u64 v[10:11], v[10:11], 1, v[6:7]
	global_store_dword v[10:11], v4, off
	v_pk_mul_f32 v[4:5], v[0:1], v[8:9]
	v_lshlrev_b64 v[10:11], s18, v[84:85]
	v_cvt_pk_bf16_f32 v12, v4, v5
	ds_read2_b32 v[4:5], v100 offset0:24 offset1:26
	ds_read2_b32 v[8:9], v101 offset0:25 offset1:27
	v_lshl_add_u64 v[10:11], v[10:11], 1, v[6:7]
	global_store_dword v[10:11], v12, off
	s_waitcnt lgkmcnt(0)
	v_mov_b32_e32 v10, v4
	v_mov_b32_e32 v11, v8
	v_pk_mul_f32 v[10:11], v[0:1], v[10:11]
	v_mov_b32_e32 v8, v5
	v_cvt_pk_bf16_f32 v4, v10, v11
	v_lshlrev_b64 v[10:11], s18, v[70:71]
	v_lshl_add_u64 v[10:11], v[10:11], 1, v[6:7]
	global_store_dword v[10:11], v4, off
	v_pk_mul_f32 v[4:5], v[0:1], v[8:9]
	v_lshlrev_b64 v[10:11], s18, v[74:75]
	v_cvt_pk_bf16_f32 v12, v4, v5
	ds_read2_b32 v[4:5], v100 offset0:28 offset1:30
	ds_read2_b32 v[8:9], v101 offset0:29 offset1:31
	v_lshl_add_u64 v[10:11], v[10:11], 1, v[6:7]
	global_store_dword v[10:11], v12, off
	s_waitcnt lgkmcnt(0)
	v_mov_b32_e32 v10, v4
	v_mov_b32_e32 v11, v8
	v_pk_mul_f32 v[10:11], v[0:1], v[10:11]
	v_mov_b32_e32 v8, v5
	v_cvt_pk_bf16_f32 v4, v10, v11
	v_lshlrev_b64 v[10:11], s18, v[66:67]
	v_lshl_add_u64 v[10:11], v[10:11], 1, v[6:7]
	v_pk_mul_f32 v[0:1], v[0:1], v[8:9]
	global_store_dword v[10:11], v4, off
	v_cvt_pk_bf16_f32 v4, v0, v1
	v_lshlrev_b64 v[0:1], s18, v[68:69]
	v_lshl_add_u64 v[0:1], v[0:1], 1, v[6:7]
	global_store_dword v[0:1], v4, off
	s_cbranch_vccnz .LBB0_931
	s_add_i32 s0, s12, 0xffff00c0
	s_lshr_b32 s0, s0, 1
	s_and_b32 s0, s0, 0x7ffffc00
	s_mov_b32 s1, s45
	s_lshl_b64 s[0:1], s[0:1], 11
	s_add_u32 s0, s0, 0x4000000
	s_addc_u32 s1, s1, 0
	s_mov_b64 s[2:3], 0

; DEVI f32x4 mfma16(bf16x8 a, bf16x8 b, f32x4 c) { return __builtin_amdgcn_mfma_f32_16x16x32_bf16(a, b, c, 0, 0, 0); }
; DEVI void attn_phase(int wv, const Params& p, char* smem) {
;     ...
; #pragma unroll
;           for (int mh = 0; mh < 2; ++mh)
; #pragma unroll
;             for (int j = 0; j < 4; ++j) {
;               const float pv = __builtin_amdgcn_exp2f(st[2 * kk + mh][nt][j] - mref);
;               ps += pv;
;               st[2 * kk + mh][nt][j] = pv;
;             }
;           lrun[nt] += ps;
;           u32x4 w;
;           w.x = pack2(st[2 * kk][nt][0], st[2 * kk][nt][1]);
;           w.y = pack2(st[2 * kk][nt][2], st[2 * kk][nt][3]);
;           w.z = pack2(st[2 * kk + 1][nt][0], st[2 * kk + 1][nt][1]);
;           w.w = pack2(st[2 * kk + 1][nt][2], st[2 * kk + 1][nt][3]);
;           pf[nt] = __builtin_bit_cast(bf16x8, w);
;         }
; #pragma unroll
;         for (int dt = 0; dt < 8; ++dt) {
;           const bf16x8 vf = *(const bf16x8*)(cV + (dt * 16 + fr) * 64 + (((kk * 4 + g) ^ (fr & 7)) << 3));
;           ot[dt][0] = mfma16(vf, pf[0], ot[dt][0]);
;           ot[dt][1] = mfma16(vf, pf[1], ot[dt][1]);
;         }
;       }
;       asm volatile("s_waitcnt vmcnt(0)" ::: "memory");
;       __syncthreads();
.LBB0_947:
	v_sub_f32_e32 v16, v16, v181
	v_exp_f32_e32 v16, v16
	v_sub_f32_e32 v17, v17, v181
	v_exp_f32_e32 v17, v17
	v_sub_f32_e32 v18, v18, v181
	v_exp_f32_e32 v18, v18
	v_sub_f32_e32 v19, v19, v181
	v_exp_f32_e32 v19, v19
	v_sub_f32_e32 v12, v12, v181
	v_sub_f32_e32 v13, v13, v181
	v_sub_f32_e32 v8, v8, v180
	v_add_f32_e32 v53, 0, v16
	v_exp_f32_e32 v12, v12
	v_exp_f32_e32 v13, v13
	v_exp_f32_e32 v8, v8
	v_sub_f32_e32 v9, v9, v180
	v_add_f32_e32 v53, v17, v53
	v_exp_f32_e32 v9, v9
	v_sub_f32_e32 v10, v10, v180
	v_add_f32_e32 v53, v18, v53
	v_exp_f32_e32 v10, v10
	v_sub_f32_e32 v11, v11, v180
	v_add_f32_e32 v53, v19, v53
	v_exp_f32_e32 v11, v11
	v_sub_f32_e32 v0, v0, v180
	v_add_f32_e32 v53, v12, v53
	v_cvt_pk_bf16_f32 v62, v12, v13
	v_add_f32_e32 v12, 0, v8
	v_exp_f32_e32 v0, v0
	v_sub_f32_e32 v1, v1, v180
	v_sub_f32_e32 v14, v14, v181
	v_add_f32_e32 v12, v9, v12
	v_exp_f32_e32 v1, v1
	v_sub_f32_e32 v2, v2, v180
	v_exp_f32_e32 v14, v14
	v_sub_f32_e32 v15, v15, v181
	v_add_f32_e32 v12, v10, v12
	v_exp_f32_e32 v2, v2
	v_sub_f32_e32 v3, v3, v180
	v_exp_f32_e32 v15, v15
	v_add_f32_e32 v12, v11, v12
	v_exp_f32_e32 v3, v3
	v_add_f32_e32 v12, v0, v12
	v_add_f32_e32 v53, v13, v53
	v_add_f32_e32 v12, v1, v12
	v_add_f32_e32 v53, v14, v53
	v_add_f32_e32 v12, v2, v12
	v_add_f32_e32 v53, v15, v53
	v_add_f32_e32 v12, v3, v12
	v_add_u32_e32 v82, v124, v166
	v_add_f32_e32 v80, v125, v53
	v_add_f32_e32 v81, v52, v12
	v_cvt_pk_bf16_f32 v52, v8, v9
	v_cvt_pk_bf16_f32 v53, v10, v11
	v_cvt_pk_bf16_f32 v54, v0, v1
	v_cvt_pk_bf16_f32 v55, v2, v3
	ds_read_b128 v[0:3], v82 offset:49152
	ds_read_b128 v[8:11], v82 offset:51200
	v_cvt_pk_bf16_f32 v60, v16, v17
	v_cvt_pk_bf16_f32 v61, v18, v19
	v_cvt_pk_bf16_f32 v63, v14, v15
	ds_read_b128 v[12:15], v82 offset:59392
	s_add_i32 s7, s7, s6
	s_waitcnt lgkmcnt(1)
	v_mfma_f32_16x16x32_bf16 v[72:75], v[8:11], v[60:63], v[48:51]
	s_cmpk_gt_i32 s7, 0x9ff
	v_mfma_f32_16x16x32_bf16 v[48:51], v[8:11], v[52:55], v[100:103]
	ds_read_b128 v[8:11], v82 offset:53248
	s_waitcnt lgkmcnt(0)
	v_mfma_f32_16x16x32_bf16 v[44:47], v[8:11], v[60:63], v[44:47]
	v_mfma_f32_16x16x32_bf16 v[16:19], v[8:11], v[52:55], v[92:95]
	ds_read_b128 v[8:11], v82 offset:55296
	v_mfma_f32_16x16x32_bf16 v[32:35], v[12:15], v[60:63], v[32:35]
	v_mfma_f32_16x16x32_bf16 v[12:15], v[12:15], v[52:55], v[56:59]
	s_nop 2
	ds_read_b128 v[56:59], v82 offset:61440
	s_waitcnt lgkmcnt(1)
	v_mfma_f32_16x16x32_bf16 v[76:79], v[8:11], v[60:63], v[40:43]
	v_mfma_f32_16x16x32_bf16 v[40:43], v[8:11], v[52:55], v[84:87]
	ds_read_b128 v[8:11], v82 offset:57344
	s_waitcnt lgkmcnt(0)
	v_mfma_f32_16x16x32_bf16 v[36:39], v[8:11], v[60:63], v[36:39]
	v_mfma_f32_16x16x32_bf16 v[8:11], v[8:11], v[52:55], v[68:71]
	v_mfma_f32_16x16x32_bf16 v[68:71], v[56:59], v[60:63], v[4:7]
	v_mfma_f32_16x16x32_bf16 v[4:7], v[56:59], v[52:55], v[20:23]
	s_nop 2
	ds_read_b128 v[20:23], v82 offset:63488
	s_waitcnt lgkmcnt(0)
	v_mfma_f32_16x16x32_bf16 v[24:27], v[20:23], v[60:63], v[24:27]
	s_waitcnt vmcnt(0)
	s_barrier
; DEVI float sxor(float v, int mask, int lane) { return __int_as_float(__builtin_amdgcn_ds_bpermute((lane ^ mask) << 2, __float_as_int(v))); }
; DEVI f32x4 mfma16(bf16x8 a, bf16x8 b, f32x4 c) { return __builtin_amdgcn_mfma_f32_16x16x32_bf16(a, b, c, 0, 0, 0); }
; DEVI void attn_phase(int wv, const Params& p, char* smem) {
;     ...
; #pragma unroll
;         for (int dt = 0; dt < 8; ++dt) {
;           const bf16x8 vf = *(const bf16x8*)(cV + (dt * 16 + fr) * 64 + (((kk * 4 + g) ^ (fr & 7)) << 3));
;           ot[dt][0] = mfma16(vf, pf[0], ot[dt][0]);
;           ot[dt][1] = mfma16(vf, pf[1], ot[dt][1]);
;         }
;       }
;       asm volatile("s_waitcnt vmcnt(0)" ::: "memory");
;       __syncthreads();
;     }
;     ...
; #pragma unroll
;     for (int nt = 0; nt < 2; ++nt) {
;       float l = lrun[nt];
;       l += sxor(l, 16, lane);
;       l += sxor(l, 32, lane);
;       const float inv = 1.f / l;
;       u16* o = Om + (size_t)(tq + nt * 16 + fr) * 1024 + head * 128 + g * 4;
; #pragma unroll
;       for (int dt = 0; dt < 8; ++dt) {
;         uint2 v;
;         v.x = pack2(ot[dt][nt][0] * inv, ot[dt][nt][1] * inv);
;         v.y = pack2(ot[dt][nt][2] * inv, ot[dt][nt][3] * inv);
;         *(uint2*)(o + dt * 16) = v;
;       }
;     }
	v_mfma_f32_16x16x32_bf16 v[20:23], v[20:23], v[52:55], v[28:31]
	s_nop 2
	ds_bpermute_b32 v30, v161, v80
	v_mfma_f32_16x16x32_bf16 v[64:67], v[0:3], v[60:63], v[112:115]
	v_lshl_add_u64 v[28:29], v[154:155], 0, s[44:45]
	s_waitcnt lgkmcnt(0)
	v_add_f32_e32 v30, v80, v30
	ds_bpermute_b32 v31, v162, v30
	v_mfma_f32_16x16x32_bf16 v[0:3], v[0:3], v[52:55], v[108:111]
	s_waitcnt lgkmcnt(0)
	v_add_f32_e32 v30, v30, v31
	v_div_scale_f32 v31, s[2:3], v30, v30, 1.0
	v_rcp_f32_e32 v52, v31
	s_nop 0
	v_fma_f32 v53, -v31, v52, 1.0
	v_fmac_f32_e32 v52, v53, v52
	v_div_scale_f32 v53, vcc, 1.0, v30, 1.0
	v_mul_f32_e32 v54, v53, v52
	v_fma_f32 v55, -v31, v54, v53
	v_fmac_f32_e32 v54, v55, v52
	v_fma_f32 v31, -v31, v54, v53
	v_div_fmas_f32 v31, v31, v52, v54
	v_div_fixup_f32 v30, v31, v30, 1.0
	v_lshlrev_b64 v[52:53], 11, v[158:159]
	v_pk_mul_f32 v[24:25], v[24:25], v[30:31] op_sel_hi:[1,0]
	v_pk_mul_f32 v[26:27], v[26:27], v[30:31] op_sel_hi:[1,0]
	v_lshl_add_u64 v[52:53], v[28:29], 0, v[52:53]
	v_cvt_pk_bf16_f32 v24, v24, v25
	v_cvt_pk_bf16_f32 v25, v26, v27
	global_store_dwordx2 v[52:53], v[24:25], off offset:224
	ds_bpermute_b32 v24, v161, v81
	v_pk_mul_f32 v[54:55], v[64:65], v[30:31] op_sel_hi:[1,0]
	v_pk_mul_f32 v[56:57], v[66:67], v[30:31] op_sel_hi:[1,0]
	v_pk_mul_f32 v[44:45], v[44:45], v[30:31] op_sel_hi:[1,0]
	v_pk_mul_f32 v[46:47], v[46:47], v[30:31] op_sel_hi:[1,0]
	s_waitcnt lgkmcnt(0)
	v_add_f32_e32 v24, v81, v24
	ds_bpermute_b32 v25, v162, v24
	v_pk_mul_f32 v[32:33], v[32:33], v[30:31] op_sel_hi:[1,0]
	v_pk_mul_f32 v[34:35], v[34:35], v[30:31] op_sel_hi:[1,0]
	v_cvt_pk_bf16_f32 v54, v54, v55
	v_cvt_pk_bf16_f32 v55, v56, v57
	s_waitcnt lgkmcnt(0)
	v_add_f32_e32 v24, v24, v25
	v_div_scale_f32 v25, s[2:3], v24, v24, 1.0
	v_rcp_f32_e32 v26, v25
	v_cvt_pk_bf16_f32 v44, v44, v45
	v_cvt_pk_bf16_f32 v45, v46, v47
	v_cvt_pk_bf16_f32 v32, v32, v33
	v_fma_f32 v27, -v25, v26, 1.0
	v_cvt_pk_bf16_f32 v33, v34, v35
	v_fmac_f32_e32 v26, v27, v26
	v_div_scale_f32 v27, vcc, 1.0, v24, 1.0
	global_store_dwordx2 v[52:53], v[54:55], off
	v_pk_mul_f32 v[54:55], v[72:73], v[30:31] op_sel_hi:[1,0]
	v_pk_mul_f32 v[56:57], v[74:75], v[30:31] op_sel_hi:[1,0]
	global_store_dwordx2 v[52:53], v[44:45], off offset:64
	v_pk_mul_f32 v[44:45], v[76:77], v[30:31] op_sel_hi:[1,0]
	v_pk_mul_f32 v[46:47], v[78:79], v[30:31] op_sel_hi:[1,0]
	v_pk_mul_f32 v[36:37], v[36:37], v[30:31] op_sel_hi:[1,0]
	v_pk_mul_f32 v[38:39], v[38:39], v[30:31] op_sel_hi:[1,0]
	global_store_dwordx2 v[52:53], v[32:33], off offset:160
	v_pk_mul_f32 v[32:33], v[68:69], v[30:31] op_sel_hi:[1,0]
	v_pk_mul_f32 v[34:35], v[70:71], v[30:31] op_sel_hi:[1,0]
	v_mul_f32_e32 v30, v27, v26
	v_fma_f32 v31, -v25, v30, v27
	v_fmac_f32_e32 v30, v31, v26
	v_fma_f32 v25, -v25, v30, v27
	v_div_fmas_f32 v25, v25, v26, v30
	v_div_fixup_f32 v24, v25, v24, 1.0
	v_lshlrev_b64 v[26:27], 11, v[156:157]
	v_pk_mul_f32 v[0:1], v[0:1], v[24:25] op_sel_hi:[1,0]
	v_pk_mul_f32 v[2:3], v[2:3], v[24:25] op_sel_hi:[1,0]
	v_lshl_add_u64 v[26:27], v[28:29], 0, v[26:27]
	v_cvt_pk_bf16_f32 v0, v0, v1
	v_cvt_pk_bf16_f32 v1, v2, v3
	global_store_dwordx2 v[26:27], v[0:1], off
	v_pk_mul_f32 v[0:1], v[48:49], v[24:25] op_sel_hi:[1,0]
	v_pk_mul_f32 v[2:3], v[50:51], v[24:25] op_sel_hi:[1,0]
	v_cvt_pk_bf16_f32 v0, v0, v1
	v_cvt_pk_bf16_f32 v1, v2, v3
	global_store_dwordx2 v[26:27], v[0:1], off offset:32
	v_pk_mul_f32 v[0:1], v[16:17], v[24:25] op_sel_hi:[1,0]
	v_pk_mul_f32 v[2:3], v[18:19], v[24:25] op_sel_hi:[1,0]
	v_cvt_pk_bf16_f32 v0, v0, v1
	v_cvt_pk_bf16_f32 v1, v2, v3
	global_store_dwordx2 v[26:27], v[0:1], off offset:64
	v_pk_mul_f32 v[0:1], v[40:41], v[24:25] op_sel_hi:[1,0]
	v_pk_mul_f32 v[2:3], v[42:43], v[24:25] op_sel_hi:[1,0]
	v_cvt_pk_bf16_f32 v0, v0, v1
	v_cvt_pk_bf16_f32 v1, v2, v3
	global_store_dwordx2 v[26:27], v[0:1], off offset:96
	v_pk_mul_f32 v[0:1], v[8:9], v[24:25] op_sel_hi:[1,0]
	v_pk_mul_f32 v[2:3], v[10:11], v[24:25] op_sel_hi:[1,0]
	v_cvt_pk_bf16_f32 v0, v0, v1
	v_cvt_pk_bf16_f32 v1, v2, v3
	global_store_dwordx2 v[26:27], v[0:1], off offset:128
	v_pk_mul_f32 v[0:1], v[12:13], v[24:25] op_sel_hi:[1,0]
	v_pk_mul_f32 v[2:3], v[14:15], v[24:25] op_sel_hi:[1,0]
	v_cvt_pk_bf16_f32 v0, v0, v1
	v_cvt_pk_bf16_f32 v1, v2, v3
	global_store_dwordx2 v[26:27], v[0:1], off offset:160
	v_pk_mul_f32 v[0:1], v[4:5], v[24:25] op_sel_hi:[1,0]
	v_pk_mul_f32 v[2:3], v[6:7], v[24:25] op_sel_hi:[1,0]
	v_cvt_pk_bf16_f32 v0, v0, v1
	v_cvt_pk_bf16_f32 v1, v2, v3
	global_store_dwordx2 v[26:27], v[0:1], off offset:192
	v_pk_mul_f32 v[0:1], v[20:21], v[24:25] op_sel_hi:[1,0]
	v_pk_mul_f32 v[2:3], v[22:23], v[24:25] op_sel_hi:[1,0]
	v_cvt_pk_bf16_f32 v54, v54, v55
	v_cvt_pk_bf16_f32 v55, v56, v57
	v_cvt_pk_bf16_f32 v44, v44, v45
	v_cvt_pk_bf16_f32 v45, v46, v47
	v_cvt_pk_bf16_f32 v36, v36, v37
	v_cvt_pk_bf16_f32 v37, v38, v39
	v_cvt_pk_bf16_f32 v32, v32, v33
	v_cvt_pk_bf16_f32 v33, v34, v35
	v_cvt_pk_bf16_f32 v0, v0, v1
	v_cvt_pk_bf16_f32 v1, v2, v3
	global_store_dwordx2 v[52:53], v[54:55], off offset:32
	global_store_dwordx2 v[52:53], v[44:45], off offset:96
	global_store_dwordx2 v[52:53], v[36:37], off offset:128
	global_store_dwordx2 v[52:53], v[32:33], off offset:192
	global_store_dwordx2 v[26:27], v[0:1], off offset:224
	s_cbranch_scc1 .LBB0_994

; DEVI f32x4 ozero() { float z = 0.f; asm volatile("" : "+v"(z)); return f32x4{z, z, z, z}; }
; DEVI void attn_phase(int wv, const Params& p, char* smem) {
;     ...
;     const int tq = T0 + qb * 256 + wave * 32;
;     bf16x8 qf[2][6];
; #pragma unroll
;     for (int nt = 0; nt < 2; ++nt)
; #pragma unroll
;       for (int ks = 0; ks < 6; ++ks)
;         qf[nt][ks] = *(const bf16x8*)(Qm + (size_t)(tq + nt * 16 + fr) * 1536 + head * 192 + ks * 32 + g * 8);
;     f32x4 ot[8][2];
;     const f32x4 zq = ozero();
; #pragma unroll
;     for (int i = 0; i < 8; ++i) { ot[i][0] = zq; ot[i][1] = zq; }
;     float mrun[2] = {-1e30f, -1e30f}, lrun[2] = {0.f, 0.f};
;     const int nkt = S >> 6;
;     const char* vtbb = (const char*)vtb;
;     ...
;     ATT_STAGE(0, sK, sV);
;     asm volatile("s_waitcnt vmcnt(0)" ::: "memory");
;     __syncthreads();
.LBB0_952:
	s_lshl_b32 s4, s15, 8
	s_add_i32 s4, s4, s12
	v_add_u32_e32 v158, s4, v179
	s_mul_i32 s44, s14, 0xc0
	v_lshl_add_u64 v[4:5], s[44:45], 1, v[152:153]
	s_movk_i32 s15, 0xc00
	v_add_u32_e32 v156, 16, v158
	v_mad_i64_i32 v[0:1], s[4:5], v158, s15, v[4:5]
	v_mad_i64_i32 v[4:5], s[4:5], v156, s15, v[4:5]
	global_load_dwordx4 v[40:43], v[0:1], off
	global_load_dwordx4 v[32:35], v[0:1], off offset:64
	global_load_dwordx4 v[24:27], v[0:1], off offset:128
	global_load_dwordx4 v[16:19], v[0:1], off offset:192
	global_load_dwordx4 v[8:11], v[0:1], off offset:256
	s_nop 0
	global_load_dwordx4 v[0:3], v[0:1], off offset:320
	s_nop 0
	global_load_dwordx4 v[44:47], v[4:5], off
	global_load_dwordx4 v[36:39], v[4:5], off offset:64
	global_load_dwordx4 v[28:31], v[4:5], off offset:128
	global_load_dwordx4 v[20:23], v[4:5], off offset:192
	global_load_dwordx4 v[12:15], v[4:5], off offset:256
	s_nop 0
	global_load_dwordx4 v[4:7], v[4:5], off offset:320
	v_mov_b32_e32 v48, v149
	v_mov_b32_e32 v50, v160
	s_nop 0
	v_mul_hi_i32 v49, v50, s26
	v_lshrrev_b32_e32 v51, 31, v49
	v_ashrrev_i32_e32 v49, 2, v49
	v_add_u32_e32 v49, v49, v51
	v_mad_u64_u32 v[52:53], s[4:5], v49, s27, v[50:51]
	v_bitop3_b32 v51, v52, v49, 7 bitop3:0x78
	v_and_b32_e32 v52, 0xffffffe0, v49
	v_lshlrev_b32_e32 v53, 1, v49
	v_lshrrev_b32_e32 v54, 2, v49
	v_and_b32_e32 v49, 3, v49
	v_and_b32_e32 v53, 24, v53
	v_and_b32_e32 v54, 4, v54
	v_add3_u32 v49, v52, s12, v49
	v_add3_u32 v49, v49, v53, v54
	v_cmp_lt_i32_e32 vcc, 15, v51
	v_lshlrev_b32_e32 v52, 4, v51
	s_and_saveexec_b64 s[4:5], vcc
	s_xor_b64 s[4:5], exec, s[4:5]
	v_lshlrev_b32_e32 v49, 7, v49
	s_mov_b32 s15, 0x33d5ed00
	v_add3_u32 v51, v52, v49, s15
	s_or_saveexec_b64 s[4:5], s[4:5]
	s_lshl_b32 s44, s14, 8
	s_add_i32 s14, s44, 0x29d5ee00
	s_xor_b64 exec, exec, s[4:5]
	v_lshlrev_b32_e32 v49, 11, v49
	v_add3_u32 v51, v52, s14, v49
	s_or_b64 exec, exec, s[4:5]
	v_lshlrev_b32_e32 v49, 4, v50
	v_add_u32_e32 v52, 0x200, v50
	v_readfirstlane_b32 s4, v49
	s_mov_b32 m0, s4
	s_nop 0
	global_load_lds_dwordx4 v51, s[0:1]
	v_mul_hi_i32 v51, v52, s26
	v_lshrrev_b32_e32 v53, 31, v51
	v_ashrrev_i32_e32 v51, 2, v51
	v_add_u32_e32 v51, v51, v53
	v_mad_u64_u32 v[54:55], s[4:5], v51, s27, v[52:53]
	v_bitop3_b32 v53, v54, v51, 7 bitop3:0x78
	v_and_b32_e32 v54, 0xffffffe0, v51
	v_lshlrev_b32_e32 v55, 1, v51
	v_lshrrev_b32_e32 v56, 2, v51
	v_and_b32_e32 v51, 3, v51
	v_and_b32_e32 v55, 24, v55
	v_and_b32_e32 v56, 4, v56
	v_add3_u32 v51, v54, s12, v51
	v_add3_u32 v51, v51, v55, v56
	v_cmp_lt_i32_e32 vcc, 15, v53
	v_lshlrev_b32_e32 v54, 4, v53
	s_and_saveexec_b64 s[4:5], vcc
	s_xor_b64 s[4:5], exec, s[4:5]
	v_lshlrev_b32_e32 v51, 7, v51
	s_mov_b32 s15, 0x33d5ed00
	v_add3_u32 v53, v54, v51, s15
	s_andn2_saveexec_b64 s[4:5], s[4:5]
	v_lshlrev_b32_e32 v51, 11, v51
	v_add3_u32 v53, v54, s14, v51
	s_or_b64 exec, exec, s[4:5]
	v_lshlrev_b32_e32 v51, 4, v52
	v_add_u32_e32 v54, 0x400, v50
	v_readfirstlane_b32 s4, v51
	s_mov_b32 m0, s4
	s_nop 0
	global_load_lds_dwordx4 v53, s[0:1]
	v_mul_hi_i32 v53, v54, s26
	v_lshrrev_b32_e32 v55, 31, v53
	v_ashrrev_i32_e32 v53, 2, v53
	v_add_u32_e32 v53, v53, v55
	v_mad_u64_u32 v[56:57], s[4:5], v53, s27, v[54:55]
	v_bitop3_b32 v56, v56, v53, 7 bitop3:0x78
	v_and_b32_e32 v55, 0xffffffe0, v53
	v_lshlrev_b32_e32 v57, 1, v53
	v_lshrrev_b32_e32 v58, 2, v53
	v_and_b32_e32 v53, 3, v53
	v_and_b32_e32 v57, 24, v57
	v_and_b32_e32 v58, 4, v58
	v_add3_u32 v53, v55, s12, v53
	v_add3_u32 v55, v53, v57, v58
	v_cmp_lt_i32_e32 vcc, 15, v56
	v_lshlrev_b32_e32 v56, 4, v56
	s_and_saveexec_b64 s[4:5], vcc
	s_xor_b64 s[4:5], exec, s[4:5]
	v_lshlrev_b32_e32 v53, 7, v55
	s_mov_b32 s15, 0x33d5ed00
	v_add3_u32 v53, v56, v53, s15
	s_andn2_saveexec_b64 s[4:5], s[4:5]
	v_lshlrev_b32_e32 v53, 11, v55
	v_add3_u32 v53, v56, s14, v53
	s_or_b64 exec, exec, s[4:5]
	v_lshlrev_b32_e32 v54, 4, v54
	v_add_u32_e32 v49, 0xc000, v49
	v_readfirstlane_b32 s4, v54
	s_mov_b32 m0, s4
	v_readfirstlane_b32 s4, v49
	global_load_lds_dwordx4 v53, s[0:1]
	v_ashrrev_i32_e32 v53, 3, v50
	v_ashrrev_i32_e32 v49, 3, v52
	v_xor_b32_e32 v54, v53, v50
	v_xor_b32_e32 v50, v49, v50
	v_mul_lo_u32 v53, v53, s13
	v_lshlrev_b32_e32 v54, 3, v54
	v_mul_lo_u32 v49, v49, s13
	v_lshlrev_b32_e32 v50, 3, v50
	v_and_or_b32 v53, v54, 56, v53
	v_and_or_b32 v49, v50, 56, v49
	v_add_u32_e32 v50, 0xc000, v51
	v_lshlrev_b32_e32 v53, 1, v53
	s_mov_b32 m0, s4
	v_readfirstlane_b32 s4, v50
	global_load_lds_dwordx4 v53, s[2:3]
	v_lshlrev_b32_e32 v49, 1, v49
	s_mov_b32 m0, s4
	v_mov_b32_e32 v50, v48
	global_load_lds_dwordx4 v49, s[2:3]
	v_mov_b32_e32 v51, v48
	s_waitcnt vmcnt(0)
	v_mov_b32_e32 v49, v48
	v_mov_b64_e32 v[54:55], v[50:51]
	v_mov_b64_e32 v[66:67], v[50:51]
	v_mov_b64_e32 v[74:75], v[50:51]
	v_mov_b64_e32 v[82:83], v[50:51]
	v_mov_b64_e32 v[58:59], v[50:51]
	v_mov_b64_e32 v[62:63], v[50:51]
	v_mov_b64_e32 v[70:71], v[50:51]
	v_mov_b64_e32 v[78:79], v[50:51]
	v_mov_b64_e32 v[86:87], v[50:51]
	v_mov_b64_e32 v[90:91], v[50:51]
	v_mov_b64_e32 v[94:95], v[50:51]
	v_mov_b64_e32 v[98:99], v[50:51]
	v_mov_b64_e32 v[102:103], v[50:51]
	v_mov_b64_e32 v[106:107], v[50:51]
	v_mov_b64_e32 v[110:111], v[50:51]
	v_mov_b64_e32 v[114:115], v[50:51]
	v_ashrrev_i32_e32 v159, 31, v158
	v_ashrrev_i32_e32 v157, 31, v156
	s_mov_b32 s15, 1
	s_lshr_b32 s18, s13, 6
	v_mov_b32_e32 v182, 0
	v_mov_b32_e32 v180, 0xf149f2ca
	s_mov_b32 s19, 64
	v_mov_b64_e32 v[52:53], v[48:49]
	v_mov_b64_e32 v[64:65], v[48:49]
	v_mov_b64_e32 v[72:73], v[48:49]
	v_mov_b64_e32 v[80:81], v[48:49]
	v_mov_b64_e32 v[56:57], v[48:49]
	v_mov_b64_e32 v[60:61], v[48:49]
	v_mov_b64_e32 v[68:69], v[48:49]
	v_mov_b64_e32 v[76:77], v[48:49]
	v_mov_b64_e32 v[84:85], v[48:49]
	v_mov_b64_e32 v[88:89], v[48:49]
	v_mov_b64_e32 v[92:93], v[48:49]
	v_mov_b64_e32 v[96:97], v[48:49]
	v_mov_b64_e32 v[100:101], v[48:49]
	v_mov_b64_e32 v[104:105], v[48:49]
	v_mov_b64_e32 v[108:109], v[48:49]
	v_mov_b64_e32 v[112:113], v[48:49]
	v_mov_b32_e32 v181, 0xf149f2ca
	v_mov_b32_e32 v183, 0
	s_waitcnt vmcnt(0) lgkmcnt(0)
	s_barrier
	s_branch .LBB0_966

; template <int EPI, int TS, bool VT>
; DEVI void gemm_epilogue(const Params& p, char* smem, f32x4 (&acc)[2][2][4][2], int m0, int n0, float scale, const float* ssin,
;                         float* ssout, u16* xbout, int wid, int lane, int wr, int wc, int fr, int fq) {
;     ...
;     {
;       float* tw = T + (wr * 64 + fq * 4) * TS + wc * 32 + fr;
; #pragma unroll
;       for (int m = 0; m < 4; ++m)
; #pragma unroll
;         for (int j = 0; j < 4; ++j)
; #pragma unroll
;           for (int v = 0; v < 4; ++v) tw[(m * 16 + j) * TS + (v >> 1) * 128 + (v & 1) * 16] = acc[ai][v >> 1][m][v & 1][j];
;     }
;     __syncthreads();
;     ...
;           for (int u = 0; u < 8; ++u) {
;             const size_t ro = (size_t)(g0 + i0 + u) * 1024 + n0 + 4 * lane;
;             const int gr = g0 + i0 + u;
;             const float* xs = p.x + ro;
;             if (scale < 0.f)
;               xs = (gr < MP ? p.x_prompt + ro : p.x_sample + (ro - (size_t)MP * 1024));
;             { const f32x4 t_ = __builtin_nontemporal_load((const f32x4*)xs); xo[u] = make_float4(t_[0], t_[1], t_[2], t_[3]); }
;             if constexpr (EPI == E_PLEGATE) {
;               const unsigned long long t2_ = __builtin_nontemporal_load((const unsigned long long*)((const u16*)(wsb + OFF_PP) + ro));
;               pv[u] = make_uint2((unsigned)t2_, (unsigned)(t2_ >> 32));
;             }
;           }
;         }
; #pragma unroll
;         for (int u = 0; u < 8; ++u) {
;           const int i = i0 + u;
;           const int grow = g0 + i;
;           const float* Tr = T + (r0 + i) * TS;
;           const float rs = __int_as_float(__builtin_amdgcn_readlane(__float_as_int(rsv), i));
;           if constexpr (EPI == E_RESID || EPI == E_PLEGATE) {
;             const float4 a = *(const float4*)(Tr + 4 * lane);
;             const size_t ro = (size_t)grow * 1024 + n0 + 4 * lane;
;             float4 x4 = xo[u];
;             if constexpr (EPI == E_PLEGATE) {
;               x4.x += bflo(pv[u].x) * fsig(a.x * rs);
;               x4.y += bfhi(pv[u].x) * fsig(a.y * rs);
;               x4.z += bflo(pv[u].y) * fsig(a.z * rs);
;               x4.w += bfhi(pv[u].y) * fsig(a.w * rs);
;             } else {
;               const float sc = fabsf(scale);
;               x4.x += sc * a.x; x4.y += sc * a.y; x4.z += sc * a.z; x4.w += sc * a.w;
;             }
;             st_nt16(p.x + ro, x4);
;             if (xbout) {
.LBB0_1019:
	v_readlane_b32 s12, v254, 13
	v_readlane_b32 s13, v254, 14
	v_lshrrev_b32_e32 v128, 2, v132
	v_and_or_b32 v128, v128, 12, s62
	s_movk_i32 s12, 0x410
	v_mul_lo_u32 v128, v128, s12
	s_lshl_b32 s9, s9, 7
	v_lshlrev_b32_e32 v129, 2, v133
	v_add3_u32 v130, s9, v128, v129
	s_lshl_b32 s9, s35, 4
	s_add_i32 s8, s9, s8
	v_and_b32_e32 v141, 63, v132
	ds_write2_b32 v130, v92, v100 offset1:16
	ds_write2_b32 v130, v120, v124 offset0:128 offset1:144
	v_add_u32_e32 v124, 0x400, v130
	s_ashr_i32 s9, s8, 31
	v_lshl_or_b32 v128, v141, 2, s10
	v_mov_b32_e32 v129, s11
	ds_write2_b32 v124, v93, v101 offset0:4 offset1:20
	ds_write2_b32 v124, v121, v125 offset0:132 offset1:148
	v_add_u32_e32 v121, 0x800, v130
	s_lshl_b64 s[10:11], s[8:9], 10
	s_or_b32 s30, s8, 1
	ds_write2_b32 v121, v94, v102 offset0:8 offset1:24
	ds_write2_b32 v121, v122, v126 offset0:136 offset1:152
	v_add_u32_e32 v122, 0xc00, v130
	v_lshl_add_u64 v[146:147], s[10:11], 0, v[128:129]
	s_ashr_i32 s31, s30, 31
	s_or_b32 s22, s8, 2
	ds_write2_b32 v122, v95, v103 offset0:12 offset1:28
	ds_write2_b32 v122, v123, v127 offset0:140 offset1:156
	v_add_u32_e32 v123, 0x4000, v130
	v_add_u32_e32 v125, 0x4400, v130
	v_add_u32_e32 v126, 0x4800, v130
	v_add_u32_e32 v127, 0x4c00, v130
	v_add_u32_e32 v131, 0x8000, v130
	v_add_u32_e32 v132, 0x8400, v130
	v_add_u32_e32 v133, 0x8800, v130
	v_add_u32_e32 v134, 0x8c00, v130
	v_add_u32_e32 v135, 0x9000, v130
	v_add_u32_e32 v136, 0xc000, v130
	v_add_u32_e32 v137, 0xc400, v130
	v_add_u32_e32 v138, 0xc800, v130
	v_add_u32_e32 v139, 0xcc00, v130
	v_add_u32_e32 v140, 0xd000, v130
	v_lshl_add_u64 v[156:157], v[146:147], 2, s[38:39]
	s_lshl_b64 s[10:11], s[30:31], 10
	s_ashr_i32 s23, s22, 31
	s_or_b32 s20, s8, 3
	ds_write2_b32 v123, v80, v84 offset0:64 offset1:80
	ds_write2_b32 v123, v112, v116 offset0:192 offset1:208
	ds_write2_b32 v125, v81, v85 offset0:68 offset1:84
	ds_write2_b32 v125, v113, v117 offset0:196 offset1:212
	ds_write2_b32 v126, v82, v86 offset0:72 offset1:88
	ds_write2_b32 v126, v114, v118 offset0:200 offset1:216
	ds_write2_b32 v127, v83, v87 offset0:76 offset1:92
	ds_write2_b32 v127, v115, v119 offset0:204 offset1:220
	ds_write2_b32 v131, v72, v76 offset0:128 offset1:144
	ds_write2_b32 v132, v104, v108 offset1:16
	ds_write2_b32 v132, v73, v77 offset0:132 offset1:148
	ds_write2_b32 v133, v105, v109 offset0:4 offset1:20
	ds_write2_b32 v133, v74, v78 offset0:136 offset1:152
	ds_write2_b32 v134, v106, v110 offset0:8 offset1:24
	ds_write2_b32 v134, v75, v79 offset0:140 offset1:156
	ds_write2_b32 v135, v107, v111 offset0:12 offset1:28
	ds_write2_b32 v136, v64, v68 offset0:192 offset1:208
	ds_write2_b32 v137, v88, v96 offset0:64 offset1:80
	ds_write2_b32 v137, v65, v69 offset0:196 offset1:212
	ds_write2_b32 v138, v89, v97 offset0:68 offset1:84
	ds_write2_b32 v138, v66, v70 offset0:200 offset1:216
	ds_write2_b32 v139, v90, v98 offset0:72 offset1:88
	ds_write2_b32 v139, v67, v71 offset0:204 offset1:220
	ds_write2_b32 v140, v91, v99 offset0:76 offset1:92
	s_waitcnt vmcnt(0) lgkmcnt(0)
	s_barrier
	global_load_dwordx4 v[142:145], v[156:157], off
	v_lshl_add_u64 v[118:119], s[10:11], 0, v[128:129]
	s_lshl_b64 s[10:11], s[22:23], 10
	s_ashr_i32 s21, s20, 31
	s_or_b32 s18, s8, 4
	v_lshl_add_u64 v[114:115], s[10:11], 0, v[128:129]
	s_lshl_b64 s[10:11], s[20:21], 10
	s_ashr_i32 s19, s18, 31
	s_or_b32 s14, s8, 5
	v_lshl_add_u64 v[110:111], s[10:11], 0, v[128:129]
	s_lshl_b64 s[10:11], s[18:19], 10
	s_ashr_i32 s15, s14, 31
	s_or_b32 s12, s8, 6
	v_lshl_add_u64 v[106:107], s[10:11], 0, v[128:129]
	s_lshl_b64 s[10:11], s[14:15], 10
	s_ashr_i32 s13, s12, 31
	v_lshl_add_u64 v[102:103], s[10:11], 0, v[128:129]
	s_lshl_b64 s[10:11], s[12:13], 10
	v_lshl_add_u64 v[98:99], s[10:11], 0, v[128:129]
	s_or_b32 s10, s8, 7
	s_ashr_i32 s11, s10, 31
	s_lshl_b64 s[62:63], s[10:11], 10
	v_lshl_add_u64 v[94:95], s[62:63], 0, v[128:129]
	v_lshl_add_u64 v[116:117], v[118:119], 2, s[38:39]
	v_lshl_add_u64 v[108:109], v[110:111], 2, s[38:39]
	v_lshl_add_u64 v[100:101], v[102:103], 2, s[38:39]
	v_lshl_add_u64 v[92:93], v[94:95], 2, s[38:39]
	v_lshl_add_u64 v[112:113], v[114:115], 2, s[38:39]
	global_load_dwordx4 v[88:91], v[116:117], off
	global_load_dwordx4 v[84:87], v[112:113], off
	v_lshl_add_u64 v[104:105], v[106:107], 2, s[38:39]
	global_load_dwordx4 v[80:83], v[108:109], off
	global_load_dwordx4 v[76:79], v[104:105], off
	v_lshl_add_u64 v[96:97], v[98:99], 2, s[38:39]
	global_load_dwordx4 v[72:75], v[100:101], off
	global_load_dwordx4 v[68:71], v[96:97], off
	global_load_dwordx4 v[64:67], v[92:93], off
	v_lshlrev_b32_e32 v120, 4, v141
	s_mulk_i32 s35, 0x4100
	v_add_u32_e32 v120, s35, v120
	ds_read_b128 v[152:155], v120
	v_cmp_eq_u32_e32 vcc, 0, v141
	v_lshl_add_u64 v[146:147], v[146:147], 1, s[4:5]
	s_waitcnt vmcnt(7) lgkmcnt(0)
	v_pk_add_f32 v[142:143], v[142:143], v[152:153]
	v_pk_add_f32 v[144:145], v[144:145], v[154:155]
	global_store_dwordx4 v[156:157], v[142:145], off
	v_cvt_pk_bf16_f32 v152, v142, v143
	v_cvt_pk_bf16_f32 v153, v144, v145
	v_pk_mul_f32 v[142:143], v[142:143], v[142:143]
	v_pk_mul_f32 v[144:145], v[144:145], v[144:145]
	v_add_f32_e32 v141, v142, v143
	v_add_f32_e32 v141, v141, v144
	v_add_f32_e32 v141, v141, v145
	global_store_dwordx2 v[146:147], v[152:153], off
	s_nop 0
	v_add_f32_dpp v141, v141, v141 row_ror:8 row_mask:0xf bank_mask:0xf bound_ctrl:1
	s_nop 1
	v_add_f32_dpp v141, v141, v141 row_ror:4 row_mask:0xf bank_mask:0xf bound_ctrl:1
	s_nop 1
	v_add_f32_dpp v141, v141, v141 row_ror:2 row_mask:0xf bank_mask:0xf bound_ctrl:1
	s_nop 1
	v_add_f32_dpp v141, v141, v141 row_ror:1 row_mask:0xf bank_mask:0xf bound_ctrl:1
	s_nop 0
	v_readlane_b32 s62, v141, 0
	v_readlane_b32 s70, v141, 16
	v_readlane_b32 s63, v141, 32
	v_readlane_b32 s69, v141, 48
	s_and_saveexec_b64 s[34:35], vcc
	s_cbranch_execz .LBB0_1021
	s_lshl_b64 s[72:73], s[8:9], 2
	v_mov_b32_e32 v141, s70
	s_add_u32 s72, s65, s72
	v_add_f32_e32 v141, s62, v141
	s_addc_u32 s73, s66, s73
	v_add_f32_e32 v141, s63, v141
	v_add_f32_e32 v141, s69, v141
	v_mov_b64_e32 v[142:143], s[72:73]
	global_atomic_add_f32 v[142:143], v141, off
; DEVI float fsig(float x) { return __builtin_amdgcn_rcpf(1.f + __expf(-x)); }
; DEVI float bflo(unsigned u) { return __uint_as_float(u << 16); }
; DEVI float bfhi(unsigned u) { return __uint_as_float(u & 0xffff0000u); }
; template <int EPI, int TS, bool VT>
; DEVI void gemm_epilogue(const Params& p, char* smem, f32x4 (&acc)[2][2][4][2], int m0, int n0, float scale, const float* ssin,
;                         float* ssout, u16* xbout, int wid, int lane, int wr, int wc, int fr, int fq) {
;     ...
; #pragma unroll
;         for (int u = 0; u < 8; ++u) {
;           const int i = i0 + u;
;           const int grow = g0 + i;
;           const float* Tr = T + (r0 + i) * TS;
;           const float rs = __int_as_float(__builtin_amdgcn_readlane(__float_as_int(rsv), i));
;           if constexpr (EPI == E_RESID || EPI == E_PLEGATE) {
;             const float4 a = *(const float4*)(Tr + 4 * lane);
;             const size_t ro = (size_t)grow * 1024 + n0 + 4 * lane;
;             float4 x4 = xo[u];
;             if constexpr (EPI == E_PLEGATE) {
;               x4.x += bflo(pv[u].x) * fsig(a.x * rs);
;               x4.y += bfhi(pv[u].x) * fsig(a.y * rs);
;               x4.z += bflo(pv[u].y) * fsig(a.z * rs);
;               x4.w += bfhi(pv[u].y) * fsig(a.w * rs);
;             } else {
;               const float sc = fabsf(scale);
;               x4.x += sc * a.x; x4.y += sc * a.y; x4.z += sc * a.z; x4.w += sc * a.w;
;             }
;             st_nt16(p.x + ro, x4);
;             if (xbout) {
;               uint2 o;
;               o.x = pack2(x4.x, x4.y);
;               o.y = pack2(x4.z, x4.w);
;               st_nt8(xbout + ro, o);
;             }
;             if (ssout) {
;               const float ssq = wsum(x4.x * x4.x + x4.y * x4.y + x4.z * x4.z + x4.w * x4.w, lane);
;               if (lane == 0) atomicAdd(ssout + grow, ssq);
.LBB0_1021:
	s_or_b64 exec, exec, s[34:35]
	ds_read_b128 v[142:145], v120 offset:1040
	v_lshl_add_u64 v[118:119], v[118:119], 1, s[4:5]
	s_waitcnt vmcnt(0) lgkmcnt(0)
	v_pk_add_f32 v[88:89], v[88:89], v[142:143]
	v_pk_add_f32 v[90:91], v[90:91], v[144:145]
	global_store_dwordx4 v[116:117], v[88:91], off
	v_cvt_pk_bf16_f32 v116, v88, v89
	v_cvt_pk_bf16_f32 v117, v90, v91
	v_pk_mul_f32 v[88:89], v[88:89], v[88:89]
	v_pk_mul_f32 v[90:91], v[90:91], v[90:91]
	v_add_f32_e32 v88, v88, v89
	v_add_f32_e32 v88, v88, v90
	v_add_f32_e32 v88, v88, v91
	global_store_dwordx2 v[118:119], v[116:117], off
	s_nop 0
	v_add_f32_dpp v88, v88, v88 row_ror:8 row_mask:0xf bank_mask:0xf bound_ctrl:1
	s_nop 1
	v_add_f32_dpp v88, v88, v88 row_ror:4 row_mask:0xf bank_mask:0xf bound_ctrl:1
	s_nop 1
	v_add_f32_dpp v88, v88, v88 row_ror:2 row_mask:0xf bank_mask:0xf bound_ctrl:1
	s_nop 1
	v_add_f32_dpp v88, v88, v88 row_ror:1 row_mask:0xf bank_mask:0xf bound_ctrl:1
	s_nop 0
	v_readlane_b32 s9, v88, 0
	v_readlane_b32 s69, v88, 16
	v_readlane_b32 s62, v88, 32
	v_readlane_b32 s63, v88, 48
	s_and_saveexec_b64 s[34:35], vcc
	s_cbranch_execz .LBB0_1023
	s_lshl_b64 s[30:31], s[30:31], 2
	v_mov_b32_e32 v88, s69
	s_add_u32 s30, s65, s30
	v_add_f32_e32 v88, s9, v88
	s_addc_u32 s31, s66, s31
	v_add_f32_e32 v88, s62, v88
	v_add_f32_e32 v90, s63, v88
	v_mov_b64_e32 v[88:89], s[30:31]
	global_atomic_add_f32 v[88:89], v90, off
.LBB0_1023:
	s_or_b64 exec, exec, s[34:35]
	ds_read_b128 v[88:91], v120 offset:2080
	v_lshl_add_u64 v[114:115], v[114:115], 1, s[4:5]
	s_waitcnt lgkmcnt(0)
	v_pk_add_f32 v[84:85], v[84:85], v[88:89]
	v_pk_add_f32 v[86:87], v[86:87], v[90:91]
	global_store_dwordx4 v[112:113], v[84:87], off
	v_cvt_pk_bf16_f32 v88, v84, v85
	v_cvt_pk_bf16_f32 v89, v86, v87
	v_pk_mul_f32 v[84:85], v[84:85], v[84:85]
	v_pk_mul_f32 v[86:87], v[86:87], v[86:87]
	v_add_f32_e32 v84, v84, v85
	v_add_f32_e32 v84, v84, v86
	v_add_f32_e32 v84, v84, v87
	global_store_dwordx2 v[114:115], v[88:89], off
	s_nop 0
	v_add_f32_dpp v84, v84, v84 row_ror:8 row_mask:0xf bank_mask:0xf bound_ctrl:1
	s_nop 1
	v_add_f32_dpp v84, v84, v84 row_ror:4 row_mask:0xf bank_mask:0xf bound_ctrl:1
	s_nop 1
	v_add_f32_dpp v84, v84, v84 row_ror:2 row_mask:0xf bank_mask:0xf bound_ctrl:1
	s_nop 1
	v_add_f32_dpp v84, v84, v84 row_ror:1 row_mask:0xf bank_mask:0xf bound_ctrl:1
	s_nop 0
	v_readlane_b32 s9, v84, 0
	v_readlane_b32 s62, v84, 16
	v_readlane_b32 s34, v84, 32
	v_readlane_b32 s35, v84, 48
	s_and_saveexec_b64 s[30:31], vcc
	s_cbranch_execz .LBB0_1025
	s_lshl_b64 s[22:23], s[22:23], 2
	v_mov_b32_e32 v84, s62
	s_add_u32 s22, s65, s22
	v_add_f32_e32 v84, s9, v84
	s_addc_u32 s23, s66, s23
	v_add_f32_e32 v84, s34, v84
	v_add_f32_e32 v86, s35, v84
	v_mov_b64_e32 v[84:85], s[22:23]
	global_atomic_add_f32 v[84:85], v86, off
.LBB0_1025:
	s_or_b64 exec, exec, s[30:31]
	ds_read_b128 v[84:87], v120 offset:3120
	v_lshl_add_u64 v[88:89], v[110:111], 1, s[4:5]
	s_waitcnt lgkmcnt(0)
	v_pk_add_f32 v[80:81], v[80:81], v[84:85]
	v_pk_add_f32 v[82:83], v[82:83], v[86:87]
	global_store_dwordx4 v[108:109], v[80:83], off
	v_cvt_pk_bf16_f32 v84, v80, v81
	v_cvt_pk_bf16_f32 v85, v82, v83
	v_pk_mul_f32 v[80:81], v[80:81], v[80:81]
	v_pk_mul_f32 v[82:83], v[82:83], v[82:83]
	v_add_f32_e32 v80, v80, v81
	v_add_f32_e32 v80, v80, v82
	v_add_f32_e32 v80, v80, v83
	global_store_dwordx2 v[88:89], v[84:85], off
	s_nop 0
	v_add_f32_dpp v80, v80, v80 row_ror:8 row_mask:0xf bank_mask:0xf bound_ctrl:1
	s_nop 1
	v_add_f32_dpp v80, v80, v80 row_ror:4 row_mask:0xf bank_mask:0xf bound_ctrl:1
	s_nop 1
	v_add_f32_dpp v80, v80, v80 row_ror:2 row_mask:0xf bank_mask:0xf bound_ctrl:1
	s_nop 1
	v_add_f32_dpp v80, v80, v80 row_ror:1 row_mask:0xf bank_mask:0xf bound_ctrl:1
	s_nop 0
	v_readlane_b32 s9, v80, 0
	v_readlane_b32 s34, v80, 16
	v_readlane_b32 s30, v80, 32
	v_readlane_b32 s31, v80, 48
	s_and_saveexec_b64 s[22:23], vcc
	s_cbranch_execz .LBB0_1027
	s_lshl_b64 s[20:21], s[20:21], 2
	v_mov_b32_e32 v80, s34
	s_add_u32 s20, s65, s20
	v_add_f32_e32 v80, s9, v80
	s_addc_u32 s21, s66, s21
	v_add_f32_e32 v80, s30, v80
	v_add_f32_e32 v82, s31, v80
	v_mov_b64_e32 v[80:81], s[20:21]
	global_atomic_add_f32 v[80:81], v82, off
.LBB0_1027:
	s_or_b64 exec, exec, s[22:23]
	ds_read_b128 v[80:83], v120 offset:4160
	v_lshl_add_u64 v[84:85], v[106:107], 1, s[4:5]
	s_waitcnt lgkmcnt(0)
	v_pk_add_f32 v[76:77], v[76:77], v[80:81]
	v_pk_add_f32 v[78:79], v[78:79], v[82:83]
	global_store_dwordx4 v[104:105], v[76:79], off
	v_cvt_pk_bf16_f32 v80, v76, v77
	v_cvt_pk_bf16_f32 v81, v78, v79
	v_pk_mul_f32 v[76:77], v[76:77], v[76:77]
	v_pk_mul_f32 v[78:79], v[78:79], v[78:79]
	v_add_f32_e32 v76, v76, v77
	v_add_f32_e32 v76, v76, v78
	v_add_f32_e32 v76, v76, v79
	global_store_dwordx2 v[84:85], v[80:81], off
	s_nop 0
	v_add_f32_dpp v76, v76, v76 row_ror:8 row_mask:0xf bank_mask:0xf bound_ctrl:1
	s_nop 1
	v_add_f32_dpp v76, v76, v76 row_ror:4 row_mask:0xf bank_mask:0xf bound_ctrl:1
	s_nop 1
	v_add_f32_dpp v76, v76, v76 row_ror:2 row_mask:0xf bank_mask:0xf bound_ctrl:1
	s_nop 1
	v_add_f32_dpp v76, v76, v76 row_ror:1 row_mask:0xf bank_mask:0xf bound_ctrl:1
	s_nop 0
	v_readlane_b32 s9, v76, 0
	v_readlane_b32 s30, v76, 16
	v_readlane_b32 s22, v76, 32
	v_readlane_b32 s23, v76, 48
	s_and_saveexec_b64 s[20:21], vcc
	s_cbranch_execz .LBB0_1029
	s_lshl_b64 s[18:19], s[18:19], 2
	v_mov_b32_e32 v76, s30
	s_add_u32 s18, s65, s18
	v_add_f32_e32 v76, s9, v76
	s_addc_u32 s19, s66, s19
	v_add_f32_e32 v76, s22, v76
	v_add_f32_e32 v78, s23, v76
	v_mov_b64_e32 v[76:77], s[18:19]
	global_atomic_add_f32 v[76:77], v78, off
; template <int EPI, int TS, bool VT>
; DEVI void gemm_epilogue(const Params& p, char* smem, f32x4 (&acc)[2][2][4][2], int m0, int n0, float scale, const float* ssin,
;                         float* ssout, u16* xbout, int wid, int lane, int wr, int wc, int fr, int fq) {
;     ...
;           for (int u = 0; u < 8; ++u) {
;             const size_t ro = (size_t)(g0 + i0 + u) * 1024 + n0 + 4 * lane;
;             const int gr = g0 + i0 + u;
;             const float* xs = p.x + ro;
;             if (scale < 0.f)
;               xs = (gr < MP ? p.x_prompt + ro : p.x_sample + (ro - (size_t)MP * 1024));
;             { const f32x4 t_ = __builtin_nontemporal_load((const f32x4*)xs); xo[u] = make_float4(t_[0], t_[1], t_[2], t_[3]); }
;             if constexpr (EPI == E_PLEGATE) {
;               const unsigned long long t2_ = __builtin_nontemporal_load((const unsigned long long*)((const u16*)(wsb + OFF_PP) + ro));
;               pv[u] = make_uint2((unsigned)t2_, (unsigned)(t2_ >> 32));
;             }
;           }
;         }
; #pragma unroll
;         for (int u = 0; u < 8; ++u) {
;           const int i = i0 + u;
;           const int grow = g0 + i;
;           const float* Tr = T + (r0 + i) * TS;
;           const float rs = __int_as_float(__builtin_amdgcn_readlane(__float_as_int(rsv), i));
;           if constexpr (EPI == E_RESID || EPI == E_PLEGATE) {
;             const float4 a = *(const float4*)(Tr + 4 * lane);
;             const size_t ro = (size_t)grow * 1024 + n0 + 4 * lane;
;             float4 x4 = xo[u];
;             if constexpr (EPI == E_PLEGATE) {
;               x4.x += bflo(pv[u].x) * fsig(a.x * rs);
;               x4.y += bfhi(pv[u].x) * fsig(a.y * rs);
;               x4.z += bflo(pv[u].y) * fsig(a.z * rs);
;               x4.w += bfhi(pv[u].y) * fsig(a.w * rs);
;             } else {
;               const float sc = fabsf(scale);
;               x4.x += sc * a.x; x4.y += sc * a.y; x4.z += sc * a.z; x4.w += sc * a.w;
;             }
;             st_nt16(p.x + ro, x4);
;             if (xbout) {
;               uint2 o;
;               o.x = pack2(x4.x, x4.y);
;               o.y = pack2(x4.z, x4.w);
;               st_nt8(xbout + ro, o);
;             }
;             if (ssout) {
;               const float ssq = wsum(x4.x * x4.x + x4.y * x4.y + x4.z * x4.z + x4.w * x4.w, lane);
;               if (lane == 0) atomicAdd(ssout + grow, ssq);
.LBB0_1029:
	s_or_b64 exec, exec, s[20:21]
	ds_read_b128 v[76:79], v120 offset:5200
	v_lshl_add_u64 v[80:81], v[102:103], 1, s[4:5]
	s_waitcnt lgkmcnt(0)
	v_pk_add_f32 v[72:73], v[72:73], v[76:77]
	v_pk_add_f32 v[74:75], v[74:75], v[78:79]
	global_store_dwordx4 v[100:101], v[72:75], off
	v_cvt_pk_bf16_f32 v76, v72, v73
	v_cvt_pk_bf16_f32 v77, v74, v75
	v_pk_mul_f32 v[72:73], v[72:73], v[72:73]
	v_pk_mul_f32 v[74:75], v[74:75], v[74:75]
	v_add_f32_e32 v72, v72, v73
	v_add_f32_e32 v72, v72, v74
	v_add_f32_e32 v72, v72, v75
	global_store_dwordx2 v[80:81], v[76:77], off
	s_nop 0
	v_add_f32_dpp v72, v72, v72 row_ror:8 row_mask:0xf bank_mask:0xf bound_ctrl:1
	s_nop 1
	v_add_f32_dpp v72, v72, v72 row_ror:4 row_mask:0xf bank_mask:0xf bound_ctrl:1
	s_nop 1
	v_add_f32_dpp v72, v72, v72 row_ror:2 row_mask:0xf bank_mask:0xf bound_ctrl:1
	s_nop 1
	v_add_f32_dpp v72, v72, v72 row_ror:1 row_mask:0xf bank_mask:0xf bound_ctrl:1
	s_nop 0
	v_readlane_b32 s9, v72, 0
	v_readlane_b32 s22, v72, 16
	v_readlane_b32 s20, v72, 32
	v_readlane_b32 s21, v72, 48
	s_and_saveexec_b64 s[18:19], vcc
	s_cbranch_execz .LBB0_1031
	s_lshl_b64 s[14:15], s[14:15], 2
	v_mov_b32_e32 v72, s22
	s_add_u32 s14, s65, s14
	v_add_f32_e32 v72, s9, v72
	s_addc_u32 s15, s66, s15
	v_add_f32_e32 v72, s20, v72
	v_add_f32_e32 v74, s21, v72
	v_mov_b64_e32 v[72:73], s[14:15]
	global_atomic_add_f32 v[72:73], v74, off
.LBB0_1031:
	s_or_b64 exec, exec, s[18:19]
	ds_read_b128 v[72:75], v120 offset:6240
	v_lshl_add_u64 v[76:77], v[98:99], 1, s[4:5]
	s_waitcnt lgkmcnt(0)
	v_pk_add_f32 v[68:69], v[68:69], v[72:73]
	v_pk_add_f32 v[70:71], v[70:71], v[74:75]
	global_store_dwordx4 v[96:97], v[68:71], off
	v_cvt_pk_bf16_f32 v72, v68, v69
	v_cvt_pk_bf16_f32 v73, v70, v71
	v_pk_mul_f32 v[68:69], v[68:69], v[68:69]
	v_pk_mul_f32 v[70:71], v[70:71], v[70:71]
	v_add_f32_e32 v68, v68, v69
	v_add_f32_e32 v68, v68, v70
	v_add_f32_e32 v68, v68, v71
	global_store_dwordx2 v[76:77], v[72:73], off
	s_nop 0
	v_add_f32_dpp v68, v68, v68 row_ror:8 row_mask:0xf bank_mask:0xf bound_ctrl:1
	s_nop 1
	v_add_f32_dpp v68, v68, v68 row_ror:4 row_mask:0xf bank_mask:0xf bound_ctrl:1
	s_nop 1
	v_add_f32_dpp v68, v68, v68 row_ror:2 row_mask:0xf bank_mask:0xf bound_ctrl:1
	s_nop 1
	v_add_f32_dpp v68, v68, v68 row_ror:1 row_mask:0xf bank_mask:0xf bound_ctrl:1
	s_nop 0
	v_readlane_b32 s9, v68, 0
	v_readlane_b32 s20, v68, 16
	v_readlane_b32 s18, v68, 32
	v_readlane_b32 s19, v68, 48
	s_and_saveexec_b64 s[14:15], vcc
	s_cbranch_execz .LBB0_1033
	s_lshl_b64 s[12:13], s[12:13], 2
	v_mov_b32_e32 v68, s20
	s_add_u32 s12, s65, s12
	v_add_f32_e32 v68, s9, v68
	s_addc_u32 s13, s66, s13
	v_add_f32_e32 v68, s18, v68
	v_add_f32_e32 v70, s19, v68
	v_mov_b64_e32 v[68:69], s[12:13]
	global_atomic_add_f32 v[68:69], v70, off
.LBB0_1033:
	s_or_b64 exec, exec, s[14:15]
	ds_read_b128 v[68:71], v120 offset:7280
	v_lshl_add_u64 v[72:73], v[94:95], 1, s[4:5]
	s_waitcnt lgkmcnt(0)
	v_pk_add_f32 v[64:65], v[64:65], v[68:69]
	v_pk_add_f32 v[66:67], v[66:67], v[70:71]
	global_store_dwordx4 v[92:93], v[64:67], off
	v_cvt_pk_bf16_f32 v68, v64, v65
	v_cvt_pk_bf16_f32 v69, v66, v67
	v_pk_mul_f32 v[64:65], v[64:65], v[64:65]
	v_pk_mul_f32 v[66:67], v[66:67], v[66:67]
	v_add_f32_e32 v64, v64, v65
	v_add_f32_e32 v64, v64, v66
	v_add_f32_e32 v64, v64, v67
	global_store_dwordx2 v[72:73], v[68:69], off
	s_nop 0
	v_add_f32_dpp v64, v64, v64 row_ror:8 row_mask:0xf bank_mask:0xf bound_ctrl:1
	s_nop 1
	v_add_f32_dpp v64, v64, v64 row_ror:4 row_mask:0xf bank_mask:0xf bound_ctrl:1
	s_nop 1
	v_add_f32_dpp v64, v64, v64 row_ror:2 row_mask:0xf bank_mask:0xf bound_ctrl:1
	s_nop 1
	v_add_f32_dpp v64, v64, v64 row_ror:1 row_mask:0xf bank_mask:0xf bound_ctrl:1
	s_nop 0
	v_readlane_b32 s9, v64, 0
	v_readlane_b32 s18, v64, 16
	v_readlane_b32 s14, v64, 32
	v_readlane_b32 s15, v64, 48
	s_and_saveexec_b64 s[12:13], vcc
	s_cbranch_execz .LBB0_1035
	s_lshl_b64 s[10:11], s[10:11], 2
	v_mov_b32_e32 v64, s18
	s_add_u32 s10, s65, s10
	v_add_f32_e32 v64, s9, v64
	s_addc_u32 s11, s66, s11
	v_add_f32_e32 v64, s14, v64
	v_add_f32_e32 v66, s15, v64
	v_mov_b64_e32 v[64:65], s[10:11]
	global_atomic_add_f32 v[64:65], v66, off
.LBB0_1035:
	s_or_b64 exec, exec, s[12:13]
	s_or_b32 s34, s8, 8
	s_ashr_i32 s35, s34, 31
	s_lshl_b64 s[10:11], s[34:35], 10
	s_or_b32 s30, s8, 9
	v_lshl_add_u64 v[146:147], s[10:11], 0, v[128:129]
	s_ashr_i32 s31, s30, 31
	s_or_b32 s22, s8, 10
	v_lshl_add_u64 v[156:157], v[146:147], 2, s[38:39]
	s_lshl_b64 s[10:11], s[30:31], 10
	s_ashr_i32 s23, s22, 31
	s_or_b32 s20, s8, 11
	global_load_dwordx4 v[142:145], v[156:157], off
	v_lshl_add_u64 v[118:119], s[10:11], 0, v[128:129]
	s_lshl_b64 s[10:11], s[22:23], 10
	s_ashr_i32 s21, s20, 31
	s_or_b32 s18, s8, 12
	v_lshl_add_u64 v[114:115], s[10:11], 0, v[128:129]
	s_lshl_b64 s[10:11], s[20:21], 10
	s_ashr_i32 s19, s18, 31
	s_or_b32 s14, s8, 13
	v_lshl_add_u64 v[110:111], s[10:11], 0, v[128:129]
	s_lshl_b64 s[10:11], s[18:19], 10
	s_ashr_i32 s15, s14, 31
	s_or_b32 s12, s8, 14
	v_lshl_add_u64 v[106:107], s[10:11], 0, v[128:129]
	s_lshl_b64 s[10:11], s[14:15], 10
	s_ashr_i32 s13, s12, 31
	v_lshl_add_u64 v[102:103], s[10:11], 0, v[128:129]
	s_lshl_b64 s[10:11], s[12:13], 10
	v_lshl_add_u64 v[98:99], s[10:11], 0, v[128:129]
	s_or_b32 s10, s8, 15
	s_ashr_i32 s11, s10, 31
	s_lshl_b64 s[62:63], s[10:11], 10
	v_lshl_add_u64 v[94:95], s[62:63], 0, v[128:129]
	v_lshl_add_u64 v[116:117], v[118:119], 2, s[38:39]
	v_lshl_add_u64 v[108:109], v[110:111], 2, s[38:39]
	v_lshl_add_u64 v[100:101], v[102:103], 2, s[38:39]
	v_lshl_add_u64 v[92:93], v[94:95], 2, s[38:39]
	v_lshl_add_u64 v[112:113], v[114:115], 2, s[38:39]
	global_load_dwordx4 v[88:91], v[116:117], off
	global_load_dwordx4 v[84:87], v[112:113], off
	v_lshl_add_u64 v[104:105], v[106:107], 2, s[38:39]
	global_load_dwordx4 v[80:83], v[108:109], off
	global_load_dwordx4 v[76:79], v[104:105], off
	v_lshl_add_u64 v[96:97], v[98:99], 2, s[38:39]
	global_load_dwordx4 v[72:75], v[100:101], off
	global_load_dwordx4 v[68:71], v[96:97], off
	global_load_dwordx4 v[64:67], v[92:93], off
	ds_read_b128 v[152:155], v120 offset:8320
	v_lshl_add_u64 v[146:147], v[146:147], 1, s[4:5]
	s_waitcnt vmcnt(0) lgkmcnt(0)
; DEVI float fsig(float x) { return __builtin_amdgcn_rcpf(1.f + __expf(-x)); }
; DEVI float bflo(unsigned u) { return __uint_as_float(u << 16); }
; DEVI float bfhi(unsigned u) { return __uint_as_float(u & 0xffff0000u); }
; template <int EPI, int TS, bool VT>
; DEVI void gemm_epilogue(const Params& p, char* smem, f32x4 (&acc)[2][2][4][2], int m0, int n0, float scale, const float* ssin,
;                         float* ssout, u16* xbout, int wid, int lane, int wr, int wc, int fr, int fq) {
;     ...
; #pragma unroll
;         for (int u = 0; u < 8; ++u) {
;           const int i = i0 + u;
;           const int grow = g0 + i;
;           const float* Tr = T + (r0 + i) * TS;
;           const float rs = __int_as_float(__builtin_amdgcn_readlane(__float_as_int(rsv), i));
;           if constexpr (EPI == E_RESID || EPI == E_PLEGATE) {
;             const float4 a = *(const float4*)(Tr + 4 * lane);
;             const size_t ro = (size_t)grow * 1024 + n0 + 4 * lane;
;             float4 x4 = xo[u];
;             if constexpr (EPI == E_PLEGATE) {
;               x4.x += bflo(pv[u].x) * fsig(a.x * rs);
;               x4.y += bfhi(pv[u].x) * fsig(a.y * rs);
;               x4.z += bflo(pv[u].y) * fsig(a.z * rs);
;               x4.w += bfhi(pv[u].y) * fsig(a.w * rs);
;             } else {
;               const float sc = fabsf(scale);
;               x4.x += sc * a.x; x4.y += sc * a.y; x4.z += sc * a.z; x4.w += sc * a.w;
;             }
;             st_nt16(p.x + ro, x4);
;             if (xbout) {
;               uint2 o;
;               o.x = pack2(x4.x, x4.y);
;               o.y = pack2(x4.z, x4.w);
;               st_nt8(xbout + ro, o);
;             }
;             if (ssout) {
;               const float ssq = wsum(x4.x * x4.x + x4.y * x4.y + x4.z * x4.z + x4.w * x4.w, lane);
;               if (lane == 0) atomicAdd(ssout + grow, ssq);
	v_pk_add_f32 v[142:143], v[142:143], v[152:153]
	v_pk_add_f32 v[144:145], v[144:145], v[154:155]
	global_store_dwordx4 v[156:157], v[142:145], off
	v_cvt_pk_bf16_f32 v152, v142, v143
	v_cvt_pk_bf16_f32 v153, v144, v145
	v_pk_mul_f32 v[142:143], v[142:143], v[142:143]
	v_pk_mul_f32 v[144:145], v[144:145], v[144:145]
	v_add_f32_e32 v141, v142, v143
	v_add_f32_e32 v141, v141, v144
	v_add_f32_e32 v141, v141, v145
	global_store_dwordx2 v[146:147], v[152:153], off
	s_nop 0
	v_add_f32_dpp v141, v141, v141 row_ror:8 row_mask:0xf bank_mask:0xf bound_ctrl:1
	s_nop 1
	v_add_f32_dpp v141, v141, v141 row_ror:4 row_mask:0xf bank_mask:0xf bound_ctrl:1
	s_nop 1
	v_add_f32_dpp v141, v141, v141 row_ror:2 row_mask:0xf bank_mask:0xf bound_ctrl:1
	s_nop 1
	v_add_f32_dpp v141, v141, v141 row_ror:1 row_mask:0xf bank_mask:0xf bound_ctrl:1
	s_nop 0
	v_readlane_b32 s9, v141, 0
	v_readlane_b32 s71, v141, 16
	v_readlane_b32 s69, v141, 32
	v_readlane_b32 s70, v141, 48
	s_and_saveexec_b64 s[62:63], vcc
	s_cbranch_execz .LBB0_1037
	s_lshl_b64 s[34:35], s[34:35], 2
	v_mov_b32_e32 v141, s71
	s_add_u32 s34, s65, s34
	v_add_f32_e32 v141, s9, v141
	s_addc_u32 s35, s66, s35
	v_add_f32_e32 v141, s69, v141
	v_add_f32_e32 v141, s70, v141
	v_mov_b64_e32 v[142:143], s[34:35]
	global_atomic_add_f32 v[142:143], v141, off
.LBB0_1037:
	s_or_b64 exec, exec, s[62:63]
	ds_read_b128 v[142:145], v120 offset:9360
	v_lshl_add_u64 v[118:119], v[118:119], 1, s[4:5]
	s_waitcnt lgkmcnt(0)
	v_pk_add_f32 v[88:89], v[88:89], v[142:143]
	v_pk_add_f32 v[90:91], v[90:91], v[144:145]
	global_store_dwordx4 v[116:117], v[88:91], off
	v_cvt_pk_bf16_f32 v116, v88, v89
	v_cvt_pk_bf16_f32 v117, v90, v91
	v_pk_mul_f32 v[88:89], v[88:89], v[88:89]
	v_pk_mul_f32 v[90:91], v[90:91], v[90:91]
	v_add_f32_e32 v88, v88, v89
	v_add_f32_e32 v88, v88, v90
	v_add_f32_e32 v88, v88, v91
	global_store_dwordx2 v[118:119], v[116:117], off
	s_nop 0
	v_add_f32_dpp v88, v88, v88 row_ror:8 row_mask:0xf bank_mask:0xf bound_ctrl:1
	s_nop 1
	v_add_f32_dpp v88, v88, v88 row_ror:4 row_mask:0xf bank_mask:0xf bound_ctrl:1
	s_nop 1
	v_add_f32_dpp v88, v88, v88 row_ror:2 row_mask:0xf bank_mask:0xf bound_ctrl:1
	s_nop 1
	v_add_f32_dpp v88, v88, v88 row_ror:1 row_mask:0xf bank_mask:0xf bound_ctrl:1
	s_nop 0
	v_readlane_b32 s9, v88, 0
	v_readlane_b32 s69, v88, 16
	v_readlane_b32 s62, v88, 32
	v_readlane_b32 s63, v88, 48
	s_and_saveexec_b64 s[34:35], vcc
	s_cbranch_execz .LBB0_1039
	s_lshl_b64 s[30:31], s[30:31], 2
	v_mov_b32_e32 v88, s69
	s_add_u32 s30, s65, s30
	v_add_f32_e32 v88, s9, v88
	s_addc_u32 s31, s66, s31
	v_add_f32_e32 v88, s62, v88
	v_add_f32_e32 v90, s63, v88
	v_mov_b64_e32 v[88:89], s[30:31]
	global_atomic_add_f32 v[88:89], v90, off
.LBB0_1039:
	s_or_b64 exec, exec, s[34:35]
	ds_read_b128 v[88:91], v120 offset:10400
	v_lshl_add_u64 v[114:115], v[114:115], 1, s[4:5]
	s_waitcnt lgkmcnt(0)
	v_pk_add_f32 v[84:85], v[84:85], v[88:89]
	v_pk_add_f32 v[86:87], v[86:87], v[90:91]
	global_store_dwordx4 v[112:113], v[84:87], off
	v_cvt_pk_bf16_f32 v88, v84, v85
	v_cvt_pk_bf16_f32 v89, v86, v87
	v_pk_mul_f32 v[84:85], v[84:85], v[84:85]
	v_pk_mul_f32 v[86:87], v[86:87], v[86:87]
	v_add_f32_e32 v84, v84, v85
	v_add_f32_e32 v84, v84, v86
	v_add_f32_e32 v84, v84, v87
	global_store_dwordx2 v[114:115], v[88:89], off
	s_nop 0
	v_add_f32_dpp v84, v84, v84 row_ror:8 row_mask:0xf bank_mask:0xf bound_ctrl:1
	s_nop 1
	v_add_f32_dpp v84, v84, v84 row_ror:4 row_mask:0xf bank_mask:0xf bound_ctrl:1
	s_nop 1
	v_add_f32_dpp v84, v84, v84 row_ror:2 row_mask:0xf bank_mask:0xf bound_ctrl:1
	s_nop 1
	v_add_f32_dpp v84, v84, v84 row_ror:1 row_mask:0xf bank_mask:0xf bound_ctrl:1
	s_nop 0
	v_readlane_b32 s9, v84, 0
	v_readlane_b32 s62, v84, 16
	v_readlane_b32 s34, v84, 32
	v_readlane_b32 s35, v84, 48
	s_and_saveexec_b64 s[30:31], vcc
	s_cbranch_execz .LBB0_1041
	s_lshl_b64 s[22:23], s[22:23], 2
	v_mov_b32_e32 v84, s62
	s_add_u32 s22, s65, s22
	v_add_f32_e32 v84, s9, v84
	s_addc_u32 s23, s66, s23
	v_add_f32_e32 v84, s34, v84
	v_add_f32_e32 v86, s35, v84
	v_mov_b64_e32 v[84:85], s[22:23]
	global_atomic_add_f32 v[84:85], v86, off
.LBB0_1041:
	s_or_b64 exec, exec, s[30:31]
	ds_read_b128 v[84:87], v120 offset:11440
	v_lshl_add_u64 v[88:89], v[110:111], 1, s[4:5]
	s_waitcnt lgkmcnt(0)
	v_pk_add_f32 v[80:81], v[80:81], v[84:85]
	v_pk_add_f32 v[82:83], v[82:83], v[86:87]
	global_store_dwordx4 v[108:109], v[80:83], off
	v_cvt_pk_bf16_f32 v84, v80, v81
	v_cvt_pk_bf16_f32 v85, v82, v83
	v_pk_mul_f32 v[80:81], v[80:81], v[80:81]
	v_pk_mul_f32 v[82:83], v[82:83], v[82:83]
	v_add_f32_e32 v80, v80, v81
	v_add_f32_e32 v80, v80, v82
	v_add_f32_e32 v80, v80, v83
	global_store_dwordx2 v[88:89], v[84:85], off
	s_nop 0
	v_add_f32_dpp v80, v80, v80 row_ror:8 row_mask:0xf bank_mask:0xf bound_ctrl:1
	s_nop 1
	v_add_f32_dpp v80, v80, v80 row_ror:4 row_mask:0xf bank_mask:0xf bound_ctrl:1
	s_nop 1
	v_add_f32_dpp v80, v80, v80 row_ror:2 row_mask:0xf bank_mask:0xf bound_ctrl:1
	s_nop 1
	v_add_f32_dpp v80, v80, v80 row_ror:1 row_mask:0xf bank_mask:0xf bound_ctrl:1
	s_nop 0
	v_readlane_b32 s9, v80, 0
	v_readlane_b32 s34, v80, 16
	v_readlane_b32 s30, v80, 32
	v_readlane_b32 s31, v80, 48
	s_and_saveexec_b64 s[22:23], vcc
	s_cbranch_execz .LBB0_1043
	s_lshl_b64 s[20:21], s[20:21], 2
	v_mov_b32_e32 v80, s34
	s_add_u32 s20, s65, s20
	v_add_f32_e32 v80, s9, v80
	s_addc_u32 s21, s66, s21
	v_add_f32_e32 v80, s30, v80
	v_add_f32_e32 v82, s31, v80
	v_mov_b64_e32 v[80:81], s[20:21]
	global_atomic_add_f32 v[80:81], v82, off
; DEVI float fsig(float x) { return __builtin_amdgcn_rcpf(1.f + __expf(-x)); }
; DEVI float bflo(unsigned u) { return __uint_as_float(u << 16); }
; DEVI float bfhi(unsigned u) { return __uint_as_float(u & 0xffff0000u); }
; template <int EPI, int TS, bool VT>
; DEVI void gemm_epilogue(const Params& p, char* smem, f32x4 (&acc)[2][2][4][2], int m0, int n0, float scale, const float* ssin,
;                         float* ssout, u16* xbout, int wid, int lane, int wr, int wc, int fr, int fq) {
;     ...
; #pragma unroll
;         for (int u = 0; u < 8; ++u) {
;           const int i = i0 + u;
;           const int grow = g0 + i;
;           const float* Tr = T + (r0 + i) * TS;
;           const float rs = __int_as_float(__builtin_amdgcn_readlane(__float_as_int(rsv), i));
;           if constexpr (EPI == E_RESID || EPI == E_PLEGATE) {
;             const float4 a = *(const float4*)(Tr + 4 * lane);
;             const size_t ro = (size_t)grow * 1024 + n0 + 4 * lane;
;             float4 x4 = xo[u];
;             if constexpr (EPI == E_PLEGATE) {
;               x4.x += bflo(pv[u].x) * fsig(a.x * rs);
;               x4.y += bfhi(pv[u].x) * fsig(a.y * rs);
;               x4.z += bflo(pv[u].y) * fsig(a.z * rs);
;               x4.w += bfhi(pv[u].y) * fsig(a.w * rs);
;             } else {
;               const float sc = fabsf(scale);
;               x4.x += sc * a.x; x4.y += sc * a.y; x4.z += sc * a.z; x4.w += sc * a.w;
;             }
;             st_nt16(p.x + ro, x4);
;             if (xbout) {
;               uint2 o;
;               o.x = pack2(x4.x, x4.y);
;               o.y = pack2(x4.z, x4.w);
;               st_nt8(xbout + ro, o);
;             }
;             if (ssout) {
;               const float ssq = wsum(x4.x * x4.x + x4.y * x4.y + x4.z * x4.z + x4.w * x4.w, lane);
;               if (lane == 0) atomicAdd(ssout + grow, ssq);
.LBB0_1043:
	s_or_b64 exec, exec, s[22:23]
	ds_read_b128 v[80:83], v120 offset:12480
	v_lshl_add_u64 v[84:85], v[106:107], 1, s[4:5]
	s_waitcnt lgkmcnt(0)
	v_pk_add_f32 v[76:77], v[76:77], v[80:81]
	v_pk_add_f32 v[78:79], v[78:79], v[82:83]
	global_store_dwordx4 v[104:105], v[76:79], off
	v_cvt_pk_bf16_f32 v80, v76, v77
	v_cvt_pk_bf16_f32 v81, v78, v79
	v_pk_mul_f32 v[76:77], v[76:77], v[76:77]
	v_pk_mul_f32 v[78:79], v[78:79], v[78:79]
	v_add_f32_e32 v76, v76, v77
	v_add_f32_e32 v76, v76, v78
	v_add_f32_e32 v76, v76, v79
	global_store_dwordx2 v[84:85], v[80:81], off
	s_nop 0
	v_add_f32_dpp v76, v76, v76 row_ror:8 row_mask:0xf bank_mask:0xf bound_ctrl:1
	s_nop 1
	v_add_f32_dpp v76, v76, v76 row_ror:4 row_mask:0xf bank_mask:0xf bound_ctrl:1
	s_nop 1
	v_add_f32_dpp v76, v76, v76 row_ror:2 row_mask:0xf bank_mask:0xf bound_ctrl:1
	s_nop 1
	v_add_f32_dpp v76, v76, v76 row_ror:1 row_mask:0xf bank_mask:0xf bound_ctrl:1
	s_nop 0
	v_readlane_b32 s9, v76, 0
	v_readlane_b32 s30, v76, 16
	v_readlane_b32 s22, v76, 32
	v_readlane_b32 s23, v76, 48
	s_and_saveexec_b64 s[20:21], vcc
	s_cbranch_execz .LBB0_1045
	s_lshl_b64 s[18:19], s[18:19], 2
	v_mov_b32_e32 v76, s30
	s_add_u32 s18, s65, s18
	v_add_f32_e32 v76, s9, v76
	s_addc_u32 s19, s66, s19
	v_add_f32_e32 v76, s22, v76
	v_add_f32_e32 v78, s23, v76
	v_mov_b64_e32 v[76:77], s[18:19]
	global_atomic_add_f32 v[76:77], v78, off
.LBB0_1045:
	s_or_b64 exec, exec, s[20:21]
	ds_read_b128 v[76:79], v120 offset:13520
	v_lshl_add_u64 v[80:81], v[102:103], 1, s[4:5]
	s_waitcnt lgkmcnt(0)
	v_pk_add_f32 v[72:73], v[72:73], v[76:77]
	v_pk_add_f32 v[74:75], v[74:75], v[78:79]
	global_store_dwordx4 v[100:101], v[72:75], off
	v_cvt_pk_bf16_f32 v76, v72, v73
	v_cvt_pk_bf16_f32 v77, v74, v75
	v_pk_mul_f32 v[72:73], v[72:73], v[72:73]
	v_pk_mul_f32 v[74:75], v[74:75], v[74:75]
	v_add_f32_e32 v72, v72, v73
	v_add_f32_e32 v72, v72, v74
	v_add_f32_e32 v72, v72, v75
	global_store_dwordx2 v[80:81], v[76:77], off
	s_nop 0
	v_add_f32_dpp v72, v72, v72 row_ror:8 row_mask:0xf bank_mask:0xf bound_ctrl:1
	s_nop 1
	v_add_f32_dpp v72, v72, v72 row_ror:4 row_mask:0xf bank_mask:0xf bound_ctrl:1
	s_nop 1
	v_add_f32_dpp v72, v72, v72 row_ror:2 row_mask:0xf bank_mask:0xf bound_ctrl:1
	s_nop 1
	v_add_f32_dpp v72, v72, v72 row_ror:1 row_mask:0xf bank_mask:0xf bound_ctrl:1
	s_nop 0
	v_readlane_b32 s9, v72, 0
	v_readlane_b32 s22, v72, 16
	v_readlane_b32 s20, v72, 32
	v_readlane_b32 s21, v72, 48
	s_and_saveexec_b64 s[18:19], vcc
	s_cbranch_execz .LBB0_1047
	s_lshl_b64 s[14:15], s[14:15], 2
	v_mov_b32_e32 v72, s22
	s_add_u32 s14, s65, s14
	v_add_f32_e32 v72, s9, v72
	s_addc_u32 s15, s66, s15
	v_add_f32_e32 v72, s20, v72
	v_add_f32_e32 v74, s21, v72
	v_mov_b64_e32 v[72:73], s[14:15]
	global_atomic_add_f32 v[72:73], v74, off
.LBB0_1047:
	s_or_b64 exec, exec, s[18:19]
	ds_read_b128 v[72:75], v120 offset:14560
	v_lshl_add_u64 v[76:77], v[98:99], 1, s[4:5]
	s_waitcnt lgkmcnt(0)
	v_pk_add_f32 v[68:69], v[68:69], v[72:73]
	v_pk_add_f32 v[70:71], v[70:71], v[74:75]
	global_store_dwordx4 v[96:97], v[68:71], off
	v_cvt_pk_bf16_f32 v72, v68, v69
	v_cvt_pk_bf16_f32 v73, v70, v71
	v_pk_mul_f32 v[68:69], v[68:69], v[68:69]
	v_pk_mul_f32 v[70:71], v[70:71], v[70:71]
	v_add_f32_e32 v68, v68, v69
	v_add_f32_e32 v68, v68, v70
	v_add_f32_e32 v68, v68, v71
	global_store_dwordx2 v[76:77], v[72:73], off
	s_nop 0
	v_add_f32_dpp v68, v68, v68 row_ror:8 row_mask:0xf bank_mask:0xf bound_ctrl:1
	s_nop 1
	v_add_f32_dpp v68, v68, v68 row_ror:4 row_mask:0xf bank_mask:0xf bound_ctrl:1
	s_nop 1
	v_add_f32_dpp v68, v68, v68 row_ror:2 row_mask:0xf bank_mask:0xf bound_ctrl:1
	s_nop 1
	v_add_f32_dpp v68, v68, v68 row_ror:1 row_mask:0xf bank_mask:0xf bound_ctrl:1
	s_nop 0
	v_readlane_b32 s9, v68, 0
	v_readlane_b32 s20, v68, 16
	v_readlane_b32 s18, v68, 32
	v_readlane_b32 s19, v68, 48
	s_and_saveexec_b64 s[14:15], vcc
	s_cbranch_execz .LBB0_1049
	s_lshl_b64 s[12:13], s[12:13], 2
	v_mov_b32_e32 v68, s20
	s_add_u32 s12, s65, s12
	v_add_f32_e32 v68, s9, v68
	s_addc_u32 s13, s66, s13
	v_add_f32_e32 v68, s18, v68
	v_add_f32_e32 v70, s19, v68
	v_mov_b64_e32 v[68:69], s[12:13]
	global_atomic_add_f32 v[68:69], v70, off
.LBB0_1049:
	s_or_b64 exec, exec, s[14:15]
	ds_read_b128 v[68:71], v120 offset:15600
	v_lshl_add_u64 v[72:73], v[94:95], 1, s[4:5]
	s_waitcnt lgkmcnt(0)
	v_pk_add_f32 v[64:65], v[64:65], v[68:69]
	v_pk_add_f32 v[66:67], v[66:67], v[70:71]
	global_store_dwordx4 v[92:93], v[64:67], off
	v_cvt_pk_bf16_f32 v68, v64, v65
	v_cvt_pk_bf16_f32 v69, v66, v67
	v_pk_mul_f32 v[64:65], v[64:65], v[64:65]
	v_pk_mul_f32 v[66:67], v[66:67], v[66:67]
	v_add_f32_e32 v64, v64, v65
	v_add_f32_e32 v64, v64, v66
	v_add_f32_e32 v64, v64, v67
	global_store_dwordx2 v[72:73], v[68:69], off
	s_nop 0
	v_add_f32_dpp v64, v64, v64 row_ror:8 row_mask:0xf bank_mask:0xf bound_ctrl:1
	s_nop 1
	v_add_f32_dpp v64, v64, v64 row_ror:4 row_mask:0xf bank_mask:0xf bound_ctrl:1
	s_nop 1
	v_add_f32_dpp v64, v64, v64 row_ror:2 row_mask:0xf bank_mask:0xf bound_ctrl:1
	s_nop 1
	v_add_f32_dpp v64, v64, v64 row_ror:1 row_mask:0xf bank_mask:0xf bound_ctrl:1
	s_nop 0
	v_readlane_b32 s9, v64, 0
	v_readlane_b32 s18, v64, 16
	v_readlane_b32 s14, v64, 32
	v_readlane_b32 s15, v64, 48
	s_and_saveexec_b64 s[12:13], vcc
	s_cbranch_execz .LBB0_1051
	s_lshl_b64 s[10:11], s[10:11], 2
	v_mov_b32_e32 v64, s18
	s_add_u32 s10, s65, s10
	v_add_f32_e32 v64, s9, v64
	s_addc_u32 s11, s66, s11
	v_add_f32_e32 v64, s14, v64
	v_add_f32_e32 v66, s15, v64
	v_mov_b64_e32 v[64:65], s[10:11]
	global_atomic_add_f32 v[64:65], v66, off
; template <int EPI, int TS, bool VT>
; DEVI void gemm_epilogue(const Params& p, char* smem, f32x4 (&acc)[2][2][4][2], int m0, int n0, float scale, const float* ssin,
;                         float* ssout, u16* xbout, int wid, int lane, int wr, int wc, int fr, int fq) {
;     ...
;     {
;       float* tw = T + (wr * 64 + fq * 4) * TS + wc * 32 + fr;
; #pragma unroll
;       for (int m = 0; m < 4; ++m)
; #pragma unroll
;         for (int j = 0; j < 4; ++j)
; #pragma unroll
;           for (int v = 0; v < 4; ++v) tw[(m * 16 + j) * TS + (v >> 1) * 128 + (v & 1) * 16] = acc[ai][v >> 1][m][v & 1][j];
;     }
;     __syncthreads();
;     ...
;           for (int u = 0; u < 8; ++u) {
;             const size_t ro = (size_t)(g0 + i0 + u) * 1024 + n0 + 4 * lane;
;             const int gr = g0 + i0 + u;
;             const float* xs = p.x + ro;
;             if (scale < 0.f)
;               xs = (gr < MP ? p.x_prompt + ro : p.x_sample + (ro - (size_t)MP * 1024));
;             { const f32x4 t_ = __builtin_nontemporal_load((const f32x4*)xs); xo[u] = make_float4(t_[0], t_[1], t_[2], t_[3]); }
;             if constexpr (EPI == E_PLEGATE) {
;               const unsigned long long t2_ = __builtin_nontemporal_load((const unsigned long long*)((const u16*)(wsb + OFF_PP) + ro));
;               pv[u] = make_uint2((unsigned)t2_, (unsigned)(t2_ >> 32));
;             }
;           }
;         }
; #pragma unroll
;         for (int u = 0; u < 8; ++u) {
;           const int i = i0 + u;
;           const int grow = g0 + i;
;           const float* Tr = T + (r0 + i) * TS;
;           const float rs = __int_as_float(__builtin_amdgcn_readlane(__float_as_int(rsv), i));
;           if constexpr (EPI == E_RESID || EPI == E_PLEGATE) {
;             const float4 a = *(const float4*)(Tr + 4 * lane);
;             const size_t ro = (size_t)grow * 1024 + n0 + 4 * lane;
;             float4 x4 = xo[u];
;             if constexpr (EPI == E_PLEGATE) {
;               x4.x += bflo(pv[u].x) * fsig(a.x * rs);
;               x4.y += bfhi(pv[u].x) * fsig(a.y * rs);
;               x4.z += bflo(pv[u].y) * fsig(a.z * rs);
;               x4.w += bfhi(pv[u].y) * fsig(a.w * rs);
;             } else {
;               const float sc = fabsf(scale);
;               x4.x += sc * a.x; x4.y += sc * a.y; x4.z += sc * a.z; x4.w += sc * a.w;
;             }
;             st_nt16(p.x + ro, x4);
;             if (xbout) {
.LBB0_1051:
	s_or_b64 exec, exec, s[12:13]
	s_add_i32 s34, s8, 0x80
	s_ashr_i32 s35, s34, 31
	s_lshl_b64 s[10:11], s[34:35], 10
	s_add_i32 s30, s8, 0x81
	v_lshl_add_u64 v[64:65], s[10:11], 0, v[128:129]
	s_ashr_i32 s31, s30, 31
	s_add_i32 s22, s8, 0x82
	v_lshl_add_u64 v[66:67], v[64:65], 2, s[38:39]
	s_lshl_b64 s[10:11], s[30:31], 10
	s_ashr_i32 s23, s22, 31
	s_add_i32 s20, s8, 0x83
	s_waitcnt lgkmcnt(0)
	s_barrier
	ds_write2_b32 v130, v24, v28 offset1:16
	ds_write2_b32 v130, v56, v60 offset0:128 offset1:144
	ds_write2_b32 v124, v25, v29 offset0:4 offset1:20
	ds_write2_b32 v124, v57, v61 offset0:132 offset1:148
	ds_write2_b32 v121, v26, v30 offset0:8 offset1:24
	ds_write2_b32 v121, v58, v62 offset0:136 offset1:152
	ds_write2_b32 v122, v27, v31 offset0:12 offset1:28
	ds_write2_b32 v122, v59, v63 offset0:140 offset1:156
	ds_write2_b32 v123, v16, v20 offset0:64 offset1:80
	ds_write2_b32 v123, v48, v52 offset0:192 offset1:208
	ds_write2_b32 v125, v17, v21 offset0:68 offset1:84
	ds_write2_b32 v125, v49, v53 offset0:196 offset1:212
	ds_write2_b32 v126, v18, v22 offset0:72 offset1:88
	ds_write2_b32 v126, v50, v54 offset0:200 offset1:216
	ds_write2_b32 v127, v19, v23 offset0:76 offset1:92
	ds_write2_b32 v127, v51, v55 offset0:204 offset1:220
	ds_write2_b32 v131, v8, v12 offset0:128 offset1:144
	ds_write2_b32 v132, v40, v44 offset1:16
	ds_write2_b32 v132, v9, v13 offset0:132 offset1:148
	ds_write2_b32 v133, v41, v45 offset0:4 offset1:20
	ds_write2_b32 v133, v10, v14 offset0:136 offset1:152
	ds_write2_b32 v134, v42, v46 offset0:8 offset1:24
	ds_write2_b32 v134, v11, v15 offset0:140 offset1:156
	ds_write2_b32 v135, v43, v47 offset0:12 offset1:28
	ds_write2_b32 v136, v0, v4 offset0:192 offset1:208
	ds_write2_b32 v137, v32, v36 offset0:64 offset1:80
	ds_write2_b32 v137, v1, v5 offset0:196 offset1:212
	ds_write2_b32 v138, v33, v37 offset0:68 offset1:84
	ds_write2_b32 v138, v2, v6 offset0:200 offset1:216
	ds_write2_b32 v139, v34, v38 offset0:72 offset1:88
	ds_write2_b32 v139, v3, v7 offset0:204 offset1:220
	ds_write2_b32 v140, v35, v39 offset0:76 offset1:92
	s_waitcnt lgkmcnt(0)
	s_barrier
	global_load_dwordx4 v[56:59], v[66:67], off
	v_lshl_add_u64 v[54:55], s[10:11], 0, v[128:129]
	s_lshl_b64 s[10:11], s[22:23], 10
	s_ashr_i32 s21, s20, 31
	s_add_i32 s18, s8, 0x84
	v_lshl_add_u64 v[50:51], s[10:11], 0, v[128:129]
	s_lshl_b64 s[10:11], s[20:21], 10
	s_ashr_i32 s19, s18, 31
	s_add_i32 s14, s8, 0x85
	v_lshl_add_u64 v[46:47], s[10:11], 0, v[128:129]
	s_lshl_b64 s[10:11], s[18:19], 10
	s_ashr_i32 s15, s14, 31
	s_add_i32 s12, s8, 0x86
	v_lshl_add_u64 v[42:43], s[10:11], 0, v[128:129]
	s_lshl_b64 s[10:11], s[14:15], 10
	s_ashr_i32 s13, s12, 31
	v_lshl_add_u64 v[38:39], s[10:11], 0, v[128:129]
	s_lshl_b64 s[10:11], s[12:13], 10
	v_lshl_add_u64 v[34:35], s[10:11], 0, v[128:129]
	s_add_i32 s10, s8, 0x87
	s_ashr_i32 s11, s10, 31
	s_lshl_b64 s[62:63], s[10:11], 10
	v_lshl_add_u64 v[30:31], s[62:63], 0, v[128:129]
	v_lshl_add_u64 v[52:53], v[54:55], 2, s[38:39]
	v_lshl_add_u64 v[44:45], v[46:47], 2, s[38:39]
	v_lshl_add_u64 v[36:37], v[38:39], 2, s[38:39]
	v_lshl_add_u64 v[28:29], v[30:31], 2, s[38:39]
	v_lshl_add_u64 v[48:49], v[50:51], 2, s[38:39]
	global_load_dwordx4 v[24:27], v[52:53], off
	global_load_dwordx4 v[20:23], v[48:49], off
	v_lshl_add_u64 v[40:41], v[42:43], 2, s[38:39]
	global_load_dwordx4 v[16:19], v[44:45], off
	global_load_dwordx4 v[12:15], v[40:41], off
	v_lshl_add_u64 v[32:33], v[34:35], 2, s[38:39]
	global_load_dwordx4 v[8:11], v[36:37], off
	global_load_dwordx4 v[4:7], v[32:33], off
	global_load_dwordx4 v[0:3], v[28:29], off
	ds_read_b128 v[60:63], v120
	s_waitcnt vmcnt(0) lgkmcnt(0)
	v_pk_add_f32 v[56:57], v[56:57], v[60:61]
	v_pk_add_f32 v[58:59], v[58:59], v[62:63]
	global_store_dwordx4 v[66:67], v[56:59], off
	v_cvt_pk_bf16_f32 v60, v56, v57
	v_cvt_pk_bf16_f32 v61, v58, v59
	v_pk_mul_f32 v[56:57], v[56:57], v[56:57]
	v_pk_mul_f32 v[58:59], v[58:59], v[58:59]
	v_add_f32_e32 v56, v56, v57
	v_add_f32_e32 v56, v56, v58
	v_add_f32_e32 v56, v56, v59
	v_lshl_add_u64 v[62:63], v[64:65], 1, s[4:5]
	global_store_dwordx2 v[62:63], v[60:61], off
	v_add_f32_dpp v56, v56, v56 row_ror:8 row_mask:0xf bank_mask:0xf bound_ctrl:1
	s_nop 1
	v_add_f32_dpp v56, v56, v56 row_ror:4 row_mask:0xf bank_mask:0xf bound_ctrl:1
	s_nop 1
	v_add_f32_dpp v56, v56, v56 row_ror:2 row_mask:0xf bank_mask:0xf bound_ctrl:1
	s_nop 1
	v_add_f32_dpp v56, v56, v56 row_ror:1 row_mask:0xf bank_mask:0xf bound_ctrl:1
	s_nop 0
	v_readlane_b32 s9, v56, 0
	v_readlane_b32 s71, v56, 16
	v_readlane_b32 s69, v56, 32
	v_readlane_b32 s70, v56, 48
	s_and_saveexec_b64 s[62:63], vcc
	s_cbranch_execz .LBB0_1053
	s_lshl_b64 s[34:35], s[34:35], 2
	v_mov_b32_e32 v56, s71
	s_add_u32 s34, s65, s34
	v_add_f32_e32 v56, s9, v56
	s_addc_u32 s35, s66, s35
	v_add_f32_e32 v56, s69, v56
	v_add_f32_e32 v58, s70, v56
	v_mov_b64_e32 v[56:57], s[34:35]
	global_atomic_add_f32 v[56:57], v58, off
.LBB0_1053:
	s_or_b64 exec, exec, s[62:63]
	ds_read_b128 v[56:59], v120 offset:1040
	v_lshl_add_u64 v[54:55], v[54:55], 1, s[4:5]
	s_waitcnt lgkmcnt(0)
	v_pk_add_f32 v[24:25], v[24:25], v[56:57]
	v_pk_add_f32 v[26:27], v[26:27], v[58:59]
	global_store_dwordx4 v[52:53], v[24:27], off
	v_cvt_pk_bf16_f32 v52, v24, v25
	v_cvt_pk_bf16_f32 v53, v26, v27
	v_pk_mul_f32 v[24:25], v[24:25], v[24:25]
	v_pk_mul_f32 v[26:27], v[26:27], v[26:27]
	v_add_f32_e32 v24, v24, v25
	v_add_f32_e32 v24, v24, v26
	v_add_f32_e32 v24, v24, v27
	global_store_dwordx2 v[54:55], v[52:53], off
	s_nop 0
	v_add_f32_dpp v24, v24, v24 row_ror:8 row_mask:0xf bank_mask:0xf bound_ctrl:1
	s_nop 1
	v_add_f32_dpp v24, v24, v24 row_ror:4 row_mask:0xf bank_mask:0xf bound_ctrl:1
	s_nop 1
	v_add_f32_dpp v24, v24, v24 row_ror:2 row_mask:0xf bank_mask:0xf bound_ctrl:1
	s_nop 1
	v_add_f32_dpp v24, v24, v24 row_ror:1 row_mask:0xf bank_mask:0xf bound_ctrl:1
	s_nop 0
	v_readlane_b32 s9, v24, 0
	v_readlane_b32 s69, v24, 16
	v_readlane_b32 s62, v24, 32
	v_readlane_b32 s63, v24, 48
	s_and_saveexec_b64 s[34:35], vcc
	s_cbranch_execz .LBB0_1055
	s_lshl_b64 s[30:31], s[30:31], 2
	v_mov_b32_e32 v24, s69
	s_add_u32 s30, s65, s30
	v_add_f32_e32 v24, s9, v24
	s_addc_u32 s31, s66, s31
	v_add_f32_e32 v24, s62, v24
	v_add_f32_e32 v26, s63, v24
	v_mov_b64_e32 v[24:25], s[30:31]
	global_atomic_add_f32 v[24:25], v26, off
; DEVI float fsig(float x) { return __builtin_amdgcn_rcpf(1.f + __expf(-x)); }
; DEVI float bflo(unsigned u) { return __uint_as_float(u << 16); }
; DEVI float bfhi(unsigned u) { return __uint_as_float(u & 0xffff0000u); }
; template <int EPI, int TS, bool VT>
; DEVI void gemm_epilogue(const Params& p, char* smem, f32x4 (&acc)[2][2][4][2], int m0, int n0, float scale, const float* ssin,
;                         float* ssout, u16* xbout, int wid, int lane, int wr, int wc, int fr, int fq) {
;     ...
; #pragma unroll
;         for (int u = 0; u < 8; ++u) {
;           const int i = i0 + u;
;           const int grow = g0 + i;
;           const float* Tr = T + (r0 + i) * TS;
;           const float rs = __int_as_float(__builtin_amdgcn_readlane(__float_as_int(rsv), i));
;           if constexpr (EPI == E_RESID || EPI == E_PLEGATE) {
;             const float4 a = *(const float4*)(Tr + 4 * lane);
;             const size_t ro = (size_t)grow * 1024 + n0 + 4 * lane;
;             float4 x4 = xo[u];
;             if constexpr (EPI == E_PLEGATE) {
;               x4.x += bflo(pv[u].x) * fsig(a.x * rs);
;               x4.y += bfhi(pv[u].x) * fsig(a.y * rs);
;               x4.z += bflo(pv[u].y) * fsig(a.z * rs);
;               x4.w += bfhi(pv[u].y) * fsig(a.w * rs);
;             } else {
;               const float sc = fabsf(scale);
;               x4.x += sc * a.x; x4.y += sc * a.y; x4.z += sc * a.z; x4.w += sc * a.w;
;             }
;             st_nt16(p.x + ro, x4);
;             if (xbout) {
;               uint2 o;
;               o.x = pack2(x4.x, x4.y);
;               o.y = pack2(x4.z, x4.w);
;               st_nt8(xbout + ro, o);
;             }
;             if (ssout) {
;               const float ssq = wsum(x4.x * x4.x + x4.y * x4.y + x4.z * x4.z + x4.w * x4.w, lane);
;               if (lane == 0) atomicAdd(ssout + grow, ssq);
.LBB0_1055:
	s_or_b64 exec, exec, s[34:35]
	ds_read_b128 v[24:27], v120 offset:2080
	v_lshl_add_u64 v[50:51], v[50:51], 1, s[4:5]
	s_waitcnt lgkmcnt(0)
	v_pk_add_f32 v[20:21], v[20:21], v[24:25]
	v_pk_add_f32 v[22:23], v[22:23], v[26:27]
	global_store_dwordx4 v[48:49], v[20:23], off
	v_cvt_pk_bf16_f32 v24, v20, v21
	v_cvt_pk_bf16_f32 v25, v22, v23
	v_pk_mul_f32 v[20:21], v[20:21], v[20:21]
	v_pk_mul_f32 v[22:23], v[22:23], v[22:23]
	v_add_f32_e32 v20, v20, v21
	v_add_f32_e32 v20, v20, v22
	v_add_f32_e32 v20, v20, v23
	global_store_dwordx2 v[50:51], v[24:25], off
	s_nop 0
	v_add_f32_dpp v20, v20, v20 row_ror:8 row_mask:0xf bank_mask:0xf bound_ctrl:1
	s_nop 1
	v_add_f32_dpp v20, v20, v20 row_ror:4 row_mask:0xf bank_mask:0xf bound_ctrl:1
	s_nop 1
	v_add_f32_dpp v20, v20, v20 row_ror:2 row_mask:0xf bank_mask:0xf bound_ctrl:1
	s_nop 1
	v_add_f32_dpp v20, v20, v20 row_ror:1 row_mask:0xf bank_mask:0xf bound_ctrl:1
	s_nop 0
	v_readlane_b32 s9, v20, 0
	v_readlane_b32 s62, v20, 16
	v_readlane_b32 s34, v20, 32
	v_readlane_b32 s35, v20, 48
	s_and_saveexec_b64 s[30:31], vcc
	s_cbranch_execz .LBB0_1057
	s_lshl_b64 s[22:23], s[22:23], 2
	v_mov_b32_e32 v20, s62
	s_add_u32 s22, s65, s22
	v_add_f32_e32 v20, s9, v20
	s_addc_u32 s23, s66, s23
	v_add_f32_e32 v20, s34, v20
	v_add_f32_e32 v22, s35, v20
	v_mov_b64_e32 v[20:21], s[22:23]
	global_atomic_add_f32 v[20:21], v22, off
.LBB0_1057:
	s_or_b64 exec, exec, s[30:31]
	ds_read_b128 v[20:23], v120 offset:3120
	v_lshl_add_u64 v[24:25], v[46:47], 1, s[4:5]
	s_waitcnt lgkmcnt(0)
	v_pk_add_f32 v[16:17], v[16:17], v[20:21]
	v_pk_add_f32 v[18:19], v[18:19], v[22:23]
	global_store_dwordx4 v[44:45], v[16:19], off
	v_cvt_pk_bf16_f32 v20, v16, v17
	v_cvt_pk_bf16_f32 v21, v18, v19
	v_pk_mul_f32 v[16:17], v[16:17], v[16:17]
	v_pk_mul_f32 v[18:19], v[18:19], v[18:19]
	v_add_f32_e32 v16, v16, v17
	v_add_f32_e32 v16, v16, v18
	v_add_f32_e32 v16, v16, v19
	global_store_dwordx2 v[24:25], v[20:21], off
	s_nop 0
	v_add_f32_dpp v16, v16, v16 row_ror:8 row_mask:0xf bank_mask:0xf bound_ctrl:1
	s_nop 1
	v_add_f32_dpp v16, v16, v16 row_ror:4 row_mask:0xf bank_mask:0xf bound_ctrl:1
	s_nop 1
	v_add_f32_dpp v16, v16, v16 row_ror:2 row_mask:0xf bank_mask:0xf bound_ctrl:1
	s_nop 1
	v_add_f32_dpp v16, v16, v16 row_ror:1 row_mask:0xf bank_mask:0xf bound_ctrl:1
	s_nop 0
	v_readlane_b32 s9, v16, 0
	v_readlane_b32 s34, v16, 16
	v_readlane_b32 s30, v16, 32
	v_readlane_b32 s31, v16, 48
	s_and_saveexec_b64 s[22:23], vcc
	s_cbranch_execz .LBB0_1059
	s_lshl_b64 s[20:21], s[20:21], 2
	v_mov_b32_e32 v16, s34
	s_add_u32 s20, s65, s20
	v_add_f32_e32 v16, s9, v16
	s_addc_u32 s21, s66, s21
	v_add_f32_e32 v16, s30, v16
	v_add_f32_e32 v18, s31, v16
	v_mov_b64_e32 v[16:17], s[20:21]
	global_atomic_add_f32 v[16:17], v18, off
.LBB0_1059:
	s_or_b64 exec, exec, s[22:23]
	ds_read_b128 v[16:19], v120 offset:4160
	v_lshl_add_u64 v[20:21], v[42:43], 1, s[4:5]
	s_waitcnt lgkmcnt(0)
	v_pk_add_f32 v[12:13], v[12:13], v[16:17]
	v_pk_add_f32 v[14:15], v[14:15], v[18:19]
	global_store_dwordx4 v[40:41], v[12:15], off
	v_cvt_pk_bf16_f32 v16, v12, v13
	v_cvt_pk_bf16_f32 v17, v14, v15
	v_pk_mul_f32 v[12:13], v[12:13], v[12:13]
	v_pk_mul_f32 v[14:15], v[14:15], v[14:15]
	v_add_f32_e32 v12, v12, v13
	v_add_f32_e32 v12, v12, v14
	v_add_f32_e32 v12, v12, v15
	global_store_dwordx2 v[20:21], v[16:17], off
	s_nop 0
	v_add_f32_dpp v12, v12, v12 row_ror:8 row_mask:0xf bank_mask:0xf bound_ctrl:1
	s_nop 1
	v_add_f32_dpp v12, v12, v12 row_ror:4 row_mask:0xf bank_mask:0xf bound_ctrl:1
	s_nop 1
	v_add_f32_dpp v12, v12, v12 row_ror:2 row_mask:0xf bank_mask:0xf bound_ctrl:1
	s_nop 1
	v_add_f32_dpp v12, v12, v12 row_ror:1 row_mask:0xf bank_mask:0xf bound_ctrl:1
	s_nop 0
	v_readlane_b32 s9, v12, 0
	v_readlane_b32 s30, v12, 16
	v_readlane_b32 s22, v12, 32
	v_readlane_b32 s23, v12, 48
	s_and_saveexec_b64 s[20:21], vcc
	s_cbranch_execz .LBB0_1061
	s_lshl_b64 s[18:19], s[18:19], 2
	v_mov_b32_e32 v12, s30
	s_add_u32 s18, s65, s18
	v_add_f32_e32 v12, s9, v12
	s_addc_u32 s19, s66, s19
	v_add_f32_e32 v12, s22, v12
	v_add_f32_e32 v14, s23, v12
	v_mov_b64_e32 v[12:13], s[18:19]
	global_atomic_add_f32 v[12:13], v14, off
.LBB0_1061:
	s_or_b64 exec, exec, s[20:21]
	ds_read_b128 v[12:15], v120 offset:5200
	v_lshl_add_u64 v[16:17], v[38:39], 1, s[4:5]
	s_waitcnt lgkmcnt(0)
	v_pk_add_f32 v[8:9], v[8:9], v[12:13]
	v_pk_add_f32 v[10:11], v[10:11], v[14:15]
	global_store_dwordx4 v[36:37], v[8:11], off
	v_cvt_pk_bf16_f32 v12, v8, v9
	v_cvt_pk_bf16_f32 v13, v10, v11
	v_pk_mul_f32 v[8:9], v[8:9], v[8:9]
	v_pk_mul_f32 v[10:11], v[10:11], v[10:11]
	v_add_f32_e32 v8, v8, v9
	v_add_f32_e32 v8, v8, v10
	v_add_f32_e32 v8, v8, v11
	global_store_dwordx2 v[16:17], v[12:13], off
	s_nop 0
	v_add_f32_dpp v8, v8, v8 row_ror:8 row_mask:0xf bank_mask:0xf bound_ctrl:1
	s_nop 1
	v_add_f32_dpp v8, v8, v8 row_ror:4 row_mask:0xf bank_mask:0xf bound_ctrl:1
	s_nop 1
	v_add_f32_dpp v8, v8, v8 row_ror:2 row_mask:0xf bank_mask:0xf bound_ctrl:1
	s_nop 1
	v_add_f32_dpp v8, v8, v8 row_ror:1 row_mask:0xf bank_mask:0xf bound_ctrl:1
	s_nop 0
	v_readlane_b32 s9, v8, 0
	v_readlane_b32 s22, v8, 16
	v_readlane_b32 s20, v8, 32
	v_readlane_b32 s21, v8, 48
	s_and_saveexec_b64 s[18:19], vcc
	s_cbranch_execz .LBB0_1063
	s_lshl_b64 s[14:15], s[14:15], 2
	v_mov_b32_e32 v8, s22
	s_add_u32 s14, s65, s14
	v_add_f32_e32 v8, s9, v8
	s_addc_u32 s15, s66, s15
	v_add_f32_e32 v8, s20, v8
	v_add_f32_e32 v10, s21, v8
	v_mov_b64_e32 v[8:9], s[14:15]
	global_atomic_add_f32 v[8:9], v10, off
; template <int EPI, int TS, bool VT>
; DEVI void gemm_epilogue(const Params& p, char* smem, f32x4 (&acc)[2][2][4][2], int m0, int n0, float scale, const float* ssin,
;                         float* ssout, u16* xbout, int wid, int lane, int wr, int wc, int fr, int fq) {
;     ...
;           for (int u = 0; u < 8; ++u) {
;             const size_t ro = (size_t)(g0 + i0 + u) * 1024 + n0 + 4 * lane;
;             const int gr = g0 + i0 + u;
;             const float* xs = p.x + ro;
;             if (scale < 0.f)
;               xs = (gr < MP ? p.x_prompt + ro : p.x_sample + (ro - (size_t)MP * 1024));
;             { const f32x4 t_ = __builtin_nontemporal_load((const f32x4*)xs); xo[u] = make_float4(t_[0], t_[1], t_[2], t_[3]); }
;             if constexpr (EPI == E_PLEGATE) {
;               const unsigned long long t2_ = __builtin_nontemporal_load((const unsigned long long*)((const u16*)(wsb + OFF_PP) + ro));
;               pv[u] = make_uint2((unsigned)t2_, (unsigned)(t2_ >> 32));
;             }
;           }
;         }
; #pragma unroll
;         for (int u = 0; u < 8; ++u) {
;           const int i = i0 + u;
;           const int grow = g0 + i;
;           const float* Tr = T + (r0 + i) * TS;
;           const float rs = __int_as_float(__builtin_amdgcn_readlane(__float_as_int(rsv), i));
;           if constexpr (EPI == E_RESID || EPI == E_PLEGATE) {
;             const float4 a = *(const float4*)(Tr + 4 * lane);
;             const size_t ro = (size_t)grow * 1024 + n0 + 4 * lane;
;             float4 x4 = xo[u];
;             if constexpr (EPI == E_PLEGATE) {
;               x4.x += bflo(pv[u].x) * fsig(a.x * rs);
;               x4.y += bfhi(pv[u].x) * fsig(a.y * rs);
;               x4.z += bflo(pv[u].y) * fsig(a.z * rs);
;               x4.w += bfhi(pv[u].y) * fsig(a.w * rs);
;             } else {
;               const float sc = fabsf(scale);
;               x4.x += sc * a.x; x4.y += sc * a.y; x4.z += sc * a.z; x4.w += sc * a.w;
;             }
;             st_nt16(p.x + ro, x4);
;             if (xbout) {
;               uint2 o;
;               o.x = pack2(x4.x, x4.y);
;               o.y = pack2(x4.z, x4.w);
;               st_nt8(xbout + ro, o);
;             }
;             if (ssout) {
;               const float ssq = wsum(x4.x * x4.x + x4.y * x4.y + x4.z * x4.z + x4.w * x4.w, lane);
;               if (lane == 0) atomicAdd(ssout + grow, ssq);
.LBB0_1063:
	s_or_b64 exec, exec, s[18:19]
	ds_read_b128 v[8:11], v120 offset:6240
	v_lshl_add_u64 v[12:13], v[34:35], 1, s[4:5]
	s_waitcnt lgkmcnt(0)
	v_pk_add_f32 v[4:5], v[4:5], v[8:9]
	v_pk_add_f32 v[6:7], v[6:7], v[10:11]
	global_store_dwordx4 v[32:33], v[4:7], off
	v_cvt_pk_bf16_f32 v8, v4, v5
	v_cvt_pk_bf16_f32 v9, v6, v7
	v_pk_mul_f32 v[4:5], v[4:5], v[4:5]
	v_pk_mul_f32 v[6:7], v[6:7], v[6:7]
	v_add_f32_e32 v4, v4, v5
	v_add_f32_e32 v4, v4, v6
	v_add_f32_e32 v4, v4, v7
	global_store_dwordx2 v[12:13], v[8:9], off
	s_nop 0
	v_add_f32_dpp v4, v4, v4 row_ror:8 row_mask:0xf bank_mask:0xf bound_ctrl:1
	s_nop 1
	v_add_f32_dpp v4, v4, v4 row_ror:4 row_mask:0xf bank_mask:0xf bound_ctrl:1
	s_nop 1
	v_add_f32_dpp v4, v4, v4 row_ror:2 row_mask:0xf bank_mask:0xf bound_ctrl:1
	s_nop 1
	v_add_f32_dpp v4, v4, v4 row_ror:1 row_mask:0xf bank_mask:0xf bound_ctrl:1
	s_nop 0
	v_readlane_b32 s9, v4, 0
	v_readlane_b32 s20, v4, 16
	v_readlane_b32 s18, v4, 32
	v_readlane_b32 s19, v4, 48
	s_and_saveexec_b64 s[14:15], vcc
	s_cbranch_execz .LBB0_1065
	s_lshl_b64 s[12:13], s[12:13], 2
	v_mov_b32_e32 v4, s20
	s_add_u32 s12, s65, s12
	v_add_f32_e32 v4, s9, v4
	s_addc_u32 s13, s66, s13
	v_add_f32_e32 v4, s18, v4
	v_add_f32_e32 v6, s19, v4
	v_mov_b64_e32 v[4:5], s[12:13]
	global_atomic_add_f32 v[4:5], v6, off
.LBB0_1065:
	s_or_b64 exec, exec, s[14:15]
	ds_read_b128 v[4:7], v120 offset:7280
	v_lshl_add_u64 v[8:9], v[30:31], 1, s[4:5]
	s_waitcnt lgkmcnt(0)
	v_pk_add_f32 v[0:1], v[0:1], v[4:5]
	v_pk_add_f32 v[2:3], v[2:3], v[6:7]
	global_store_dwordx4 v[28:29], v[0:3], off
	v_cvt_pk_bf16_f32 v4, v0, v1
	v_cvt_pk_bf16_f32 v5, v2, v3
	v_pk_mul_f32 v[0:1], v[0:1], v[0:1]
	v_pk_mul_f32 v[2:3], v[2:3], v[2:3]
	v_add_f32_e32 v0, v0, v1
	v_add_f32_e32 v0, v0, v2
	v_add_f32_e32 v0, v0, v3
	global_store_dwordx2 v[8:9], v[4:5], off
	s_nop 0
	v_add_f32_dpp v0, v0, v0 row_ror:8 row_mask:0xf bank_mask:0xf bound_ctrl:1
	s_nop 1
	v_add_f32_dpp v0, v0, v0 row_ror:4 row_mask:0xf bank_mask:0xf bound_ctrl:1
	s_nop 1
	v_add_f32_dpp v0, v0, v0 row_ror:2 row_mask:0xf bank_mask:0xf bound_ctrl:1
	s_nop 1
	v_add_f32_dpp v0, v0, v0 row_ror:1 row_mask:0xf bank_mask:0xf bound_ctrl:1
	s_nop 0
	v_readlane_b32 s9, v0, 0
	v_readlane_b32 s18, v0, 16
	v_readlane_b32 s14, v0, 32
	v_readlane_b32 s15, v0, 48
	s_and_saveexec_b64 s[12:13], vcc
	s_cbranch_execz .LBB0_1067
	s_lshl_b64 s[10:11], s[10:11], 2
	v_mov_b32_e32 v0, s18
	s_add_u32 s10, s65, s10
	v_add_f32_e32 v0, s9, v0
	s_addc_u32 s11, s66, s11
	v_add_f32_e32 v0, s14, v0
	v_add_f32_e32 v2, s15, v0
	v_mov_b64_e32 v[0:1], s[10:11]
	global_atomic_add_f32 v[0:1], v2, off
.LBB0_1067:
	s_or_b64 exec, exec, s[12:13]
	s_add_i32 s30, s8, 0x88
	s_ashr_i32 s31, s30, 31
	s_lshl_b64 s[10:11], s[30:31], 10
	s_add_i32 s22, s8, 0x89
	v_lshl_add_u64 v[64:65], s[10:11], 0, v[128:129]
	s_ashr_i32 s23, s22, 31
	s_add_i32 s20, s8, 0x8a
	v_lshl_add_u64 v[66:67], v[64:65], 2, s[38:39]
	s_lshl_b64 s[10:11], s[22:23], 10
	s_ashr_i32 s21, s20, 31
	s_add_i32 s18, s8, 0x8b
	global_load_dwordx4 v[56:59], v[66:67], off
	v_lshl_add_u64 v[54:55], s[10:11], 0, v[128:129]
	s_lshl_b64 s[10:11], s[20:21], 10
	s_ashr_i32 s19, s18, 31
	s_add_i32 s14, s8, 0x8c
	v_lshl_add_u64 v[50:51], s[10:11], 0, v[128:129]
	s_lshl_b64 s[10:11], s[18:19], 10
	s_ashr_i32 s15, s14, 31
	s_add_i32 s12, s8, 0x8d
	v_lshl_add_u64 v[46:47], s[10:11], 0, v[128:129]
	s_lshl_b64 s[10:11], s[14:15], 10
	s_ashr_i32 s13, s12, 31
	v_lshl_add_u64 v[42:43], s[10:11], 0, v[128:129]
	s_lshl_b64 s[10:11], s[12:13], 10
	v_lshl_add_u64 v[38:39], s[10:11], 0, v[128:129]
	s_add_i32 s10, s8, 0x8e
	s_ashr_i32 s11, s10, 31
	s_addk_i32 s8, 0x8f
	s_lshl_b64 s[34:35], s[10:11], 10
	s_ashr_i32 s9, s8, 31
	v_lshl_add_u64 v[34:35], s[34:35], 0, v[128:129]
	s_lshl_b64 s[34:35], s[8:9], 10
	v_lshl_add_u64 v[30:31], s[34:35], 0, v[128:129]
	v_lshl_add_u64 v[52:53], v[54:55], 2, s[38:39]
	v_lshl_add_u64 v[44:45], v[46:47], 2, s[38:39]
	v_lshl_add_u64 v[36:37], v[38:39], 2, s[38:39]
	v_lshl_add_u64 v[28:29], v[30:31], 2, s[38:39]
	v_lshl_add_u64 v[48:49], v[50:51], 2, s[38:39]
	global_load_dwordx4 v[24:27], v[52:53], off
	global_load_dwordx4 v[20:23], v[48:49], off
	v_lshl_add_u64 v[40:41], v[42:43], 2, s[38:39]
	global_load_dwordx4 v[16:19], v[44:45], off
	global_load_dwordx4 v[12:15], v[40:41], off
	v_lshl_add_u64 v[32:33], v[34:35], 2, s[38:39]
	global_load_dwordx4 v[8:11], v[36:37], off
	global_load_dwordx4 v[4:7], v[32:33], off
	global_load_dwordx4 v[0:3], v[28:29], off
	ds_read_b128 v[60:63], v120 offset:8320
	v_lshl_add_u64 v[64:65], v[64:65], 1, s[4:5]
	s_waitcnt vmcnt(0) lgkmcnt(0)
	v_pk_add_f32 v[56:57], v[56:57], v[60:61]
	v_pk_add_f32 v[58:59], v[58:59], v[62:63]
	global_store_dwordx4 v[66:67], v[56:59], off
	v_cvt_pk_bf16_f32 v60, v56, v57
	v_cvt_pk_bf16_f32 v61, v58, v59
	v_pk_mul_f32 v[56:57], v[56:57], v[56:57]
	v_pk_mul_f32 v[58:59], v[58:59], v[58:59]
	v_add_f32_e32 v56, v56, v57
	v_add_f32_e32 v56, v56, v58
	v_add_f32_e32 v56, v56, v59
	global_store_dwordx2 v[64:65], v[60:61], off
	s_nop 0
	v_add_f32_dpp v56, v56, v56 row_ror:8 row_mask:0xf bank_mask:0xf bound_ctrl:1
	s_nop 1
	v_add_f32_dpp v56, v56, v56 row_ror:4 row_mask:0xf bank_mask:0xf bound_ctrl:1
	s_nop 1
	v_add_f32_dpp v56, v56, v56 row_ror:2 row_mask:0xf bank_mask:0xf bound_ctrl:1
	s_nop 1
	v_add_f32_dpp v56, v56, v56 row_ror:1 row_mask:0xf bank_mask:0xf bound_ctrl:1
	s_nop 0
	v_readlane_b32 s62, v56, 0
	v_readlane_b32 s70, v56, 16
	v_readlane_b32 s63, v56, 32
	v_readlane_b32 s69, v56, 48
	s_and_saveexec_b64 s[34:35], vcc
	s_cbranch_execz .LBB0_1069
	s_lshl_b64 s[30:31], s[30:31], 2
	v_mov_b32_e32 v56, s70
	s_add_u32 s30, s65, s30
	v_add_f32_e32 v56, s62, v56
	s_addc_u32 s31, s66, s31
	v_add_f32_e32 v56, s63, v56
	v_add_f32_e32 v58, s69, v56
	v_mov_b64_e32 v[56:57], s[30:31]
	global_atomic_add_f32 v[56:57], v58, off
; DEVI float fsig(float x) { return __builtin_amdgcn_rcpf(1.f + __expf(-x)); }
; DEVI float bflo(unsigned u) { return __uint_as_float(u << 16); }
; DEVI float bfhi(unsigned u) { return __uint_as_float(u & 0xffff0000u); }
; template <int EPI, int TS, bool VT>
; DEVI void gemm_epilogue(const Params& p, char* smem, f32x4 (&acc)[2][2][4][2], int m0, int n0, float scale, const float* ssin,
;                         float* ssout, u16* xbout, int wid, int lane, int wr, int wc, int fr, int fq) {
;     ...
; #pragma unroll
;         for (int u = 0; u < 8; ++u) {
;           const int i = i0 + u;
;           const int grow = g0 + i;
;           const float* Tr = T + (r0 + i) * TS;
;           const float rs = __int_as_float(__builtin_amdgcn_readlane(__float_as_int(rsv), i));
;           if constexpr (EPI == E_RESID || EPI == E_PLEGATE) {
;             const float4 a = *(const float4*)(Tr + 4 * lane);
;             const size_t ro = (size_t)grow * 1024 + n0 + 4 * lane;
;             float4 x4 = xo[u];
;             if constexpr (EPI == E_PLEGATE) {
;               x4.x += bflo(pv[u].x) * fsig(a.x * rs);
;               x4.y += bfhi(pv[u].x) * fsig(a.y * rs);
;               x4.z += bflo(pv[u].y) * fsig(a.z * rs);
;               x4.w += bfhi(pv[u].y) * fsig(a.w * rs);
;             } else {
;               const float sc = fabsf(scale);
;               x4.x += sc * a.x; x4.y += sc * a.y; x4.z += sc * a.z; x4.w += sc * a.w;
;             }
;             st_nt16(p.x + ro, x4);
;             if (xbout) {
;               uint2 o;
;               o.x = pack2(x4.x, x4.y);
;               o.y = pack2(x4.z, x4.w);
;               st_nt8(xbout + ro, o);
;             }
;             if (ssout) {
;               const float ssq = wsum(x4.x * x4.x + x4.y * x4.y + x4.z * x4.z + x4.w * x4.w, lane);
;               if (lane == 0) atomicAdd(ssout + grow, ssq);
.LBB0_1069:
	s_or_b64 exec, exec, s[34:35]
	ds_read_b128 v[56:59], v120 offset:9360
	v_lshl_add_u64 v[54:55], v[54:55], 1, s[4:5]
	s_waitcnt lgkmcnt(0)
	v_pk_add_f32 v[24:25], v[24:25], v[56:57]
	v_pk_add_f32 v[26:27], v[26:27], v[58:59]
	global_store_dwordx4 v[52:53], v[24:27], off
	v_cvt_pk_bf16_f32 v52, v24, v25
	v_cvt_pk_bf16_f32 v53, v26, v27
	v_pk_mul_f32 v[24:25], v[24:25], v[24:25]
	v_pk_mul_f32 v[26:27], v[26:27], v[26:27]
	v_add_f32_e32 v24, v24, v25
	v_add_f32_e32 v24, v24, v26
	v_add_f32_e32 v24, v24, v27
	global_store_dwordx2 v[54:55], v[52:53], off
	s_nop 0
	v_add_f32_dpp v24, v24, v24 row_ror:8 row_mask:0xf bank_mask:0xf bound_ctrl:1
	s_nop 1
	v_add_f32_dpp v24, v24, v24 row_ror:4 row_mask:0xf bank_mask:0xf bound_ctrl:1
	s_nop 1
	v_add_f32_dpp v24, v24, v24 row_ror:2 row_mask:0xf bank_mask:0xf bound_ctrl:1
	s_nop 1
	v_add_f32_dpp v24, v24, v24 row_ror:1 row_mask:0xf bank_mask:0xf bound_ctrl:1
	s_nop 0
	v_readlane_b32 s34, v24, 0
	v_readlane_b32 s63, v24, 16
	v_readlane_b32 s35, v24, 32
	v_readlane_b32 s62, v24, 48
	s_and_saveexec_b64 s[30:31], vcc
	s_cbranch_execz .LBB0_1071
	s_lshl_b64 s[22:23], s[22:23], 2
	v_mov_b32_e32 v24, s63
	s_add_u32 s22, s65, s22
	v_add_f32_e32 v24, s34, v24
	s_addc_u32 s23, s66, s23
	v_add_f32_e32 v24, s35, v24
	v_add_f32_e32 v26, s62, v24
	v_mov_b64_e32 v[24:25], s[22:23]
	global_atomic_add_f32 v[24:25], v26, off
.LBB0_1071:
	s_or_b64 exec, exec, s[30:31]
	ds_read_b128 v[24:27], v120 offset:10400
	v_lshl_add_u64 v[50:51], v[50:51], 1, s[4:5]
	s_waitcnt lgkmcnt(0)
	v_pk_add_f32 v[20:21], v[20:21], v[24:25]
	v_pk_add_f32 v[22:23], v[22:23], v[26:27]
	global_store_dwordx4 v[48:49], v[20:23], off
	v_cvt_pk_bf16_f32 v24, v20, v21
	v_cvt_pk_bf16_f32 v25, v22, v23
	v_pk_mul_f32 v[20:21], v[20:21], v[20:21]
	v_pk_mul_f32 v[22:23], v[22:23], v[22:23]
	v_add_f32_e32 v20, v20, v21
	v_add_f32_e32 v20, v20, v22
	v_add_f32_e32 v20, v20, v23
	global_store_dwordx2 v[50:51], v[24:25], off
	s_nop 0
	v_add_f32_dpp v20, v20, v20 row_ror:8 row_mask:0xf bank_mask:0xf bound_ctrl:1
	s_nop 1
	v_add_f32_dpp v20, v20, v20 row_ror:4 row_mask:0xf bank_mask:0xf bound_ctrl:1
	s_nop 1
	v_add_f32_dpp v20, v20, v20 row_ror:2 row_mask:0xf bank_mask:0xf bound_ctrl:1
	s_nop 1
	v_add_f32_dpp v20, v20, v20 row_ror:1 row_mask:0xf bank_mask:0xf bound_ctrl:1
	s_nop 0
	v_readlane_b32 s30, v20, 0
	v_readlane_b32 s35, v20, 16
	v_readlane_b32 s31, v20, 32
	v_readlane_b32 s34, v20, 48
	s_and_saveexec_b64 s[22:23], vcc
	s_cbranch_execz .LBB0_1073
	s_lshl_b64 s[20:21], s[20:21], 2
	v_mov_b32_e32 v20, s35
	s_add_u32 s20, s65, s20
	v_add_f32_e32 v20, s30, v20
	s_addc_u32 s21, s66, s21
	v_add_f32_e32 v20, s31, v20
	v_add_f32_e32 v22, s34, v20
	v_mov_b64_e32 v[20:21], s[20:21]
	global_atomic_add_f32 v[20:21], v22, off
.LBB0_1073:
	s_or_b64 exec, exec, s[22:23]
	ds_read_b128 v[20:23], v120 offset:11440
	v_lshl_add_u64 v[24:25], v[46:47], 1, s[4:5]
	s_waitcnt lgkmcnt(0)
	v_pk_add_f32 v[16:17], v[16:17], v[20:21]
	v_pk_add_f32 v[18:19], v[18:19], v[22:23]
	global_store_dwordx4 v[44:45], v[16:19], off
	v_cvt_pk_bf16_f32 v20, v16, v17
	v_cvt_pk_bf16_f32 v21, v18, v19
	v_pk_mul_f32 v[16:17], v[16:17], v[16:17]
	v_pk_mul_f32 v[18:19], v[18:19], v[18:19]
	v_add_f32_e32 v16, v16, v17
	v_add_f32_e32 v16, v16, v18
	v_add_f32_e32 v16, v16, v19
	global_store_dwordx2 v[24:25], v[20:21], off
	s_nop 0
	v_add_f32_dpp v16, v16, v16 row_ror:8 row_mask:0xf bank_mask:0xf bound_ctrl:1
	s_nop 1
	v_add_f32_dpp v16, v16, v16 row_ror:4 row_mask:0xf bank_mask:0xf bound_ctrl:1
	s_nop 1
	v_add_f32_dpp v16, v16, v16 row_ror:2 row_mask:0xf bank_mask:0xf bound_ctrl:1
	s_nop 1
	v_add_f32_dpp v16, v16, v16 row_ror:1 row_mask:0xf bank_mask:0xf bound_ctrl:1
	s_nop 0
	v_readlane_b32 s22, v16, 0
	v_readlane_b32 s31, v16, 16
	v_readlane_b32 s23, v16, 32
	v_readlane_b32 s30, v16, 48
	s_and_saveexec_b64 s[20:21], vcc
	s_cbranch_execz .LBB0_1075
	s_lshl_b64 s[18:19], s[18:19], 2
	v_mov_b32_e32 v16, s31
	s_add_u32 s18, s65, s18
	v_add_f32_e32 v16, s22, v16
	s_addc_u32 s19, s66, s19
	v_add_f32_e32 v16, s23, v16
	v_add_f32_e32 v18, s30, v16
	v_mov_b64_e32 v[16:17], s[18:19]
	global_atomic_add_f32 v[16:17], v18, off
; DEVI float fsig(float x) { return __builtin_amdgcn_rcpf(1.f + __expf(-x)); }
; DEVI float bflo(unsigned u) { return __uint_as_float(u << 16); }
; DEVI float bfhi(unsigned u) { return __uint_as_float(u & 0xffff0000u); }
; template <int EPI, int TS, bool VT>
; DEVI void gemm_epilogue(const Params& p, char* smem, f32x4 (&acc)[2][2][4][2], int m0, int n0, float scale, const float* ssin,
;                         float* ssout, u16* xbout, int wid, int lane, int wr, int wc, int fr, int fq) {
;     ...
; #pragma unroll
;         for (int u = 0; u < 8; ++u) {
;           const int i = i0 + u;
;           const int grow = g0 + i;
;           const float* Tr = T + (r0 + i) * TS;
;           const float rs = __int_as_float(__builtin_amdgcn_readlane(__float_as_int(rsv), i));
;           if constexpr (EPI == E_RESID || EPI == E_PLEGATE) {
;             const float4 a = *(const float4*)(Tr + 4 * lane);
;             const size_t ro = (size_t)grow * 1024 + n0 + 4 * lane;
;             float4 x4 = xo[u];
;             if constexpr (EPI == E_PLEGATE) {
;               x4.x += bflo(pv[u].x) * fsig(a.x * rs);
;               x4.y += bfhi(pv[u].x) * fsig(a.y * rs);
;               x4.z += bflo(pv[u].y) * fsig(a.z * rs);
;               x4.w += bfhi(pv[u].y) * fsig(a.w * rs);
;             } else {
;               const float sc = fabsf(scale);
;               x4.x += sc * a.x; x4.y += sc * a.y; x4.z += sc * a.z; x4.w += sc * a.w;
;             }
;             st_nt16(p.x + ro, x4);
;             if (xbout) {
;               uint2 o;
;               o.x = pack2(x4.x, x4.y);
;               o.y = pack2(x4.z, x4.w);
;               st_nt8(xbout + ro, o);
;             }
;             if (ssout) {
;               const float ssq = wsum(x4.x * x4.x + x4.y * x4.y + x4.z * x4.z + x4.w * x4.w, lane);
;               if (lane == 0) atomicAdd(ssout + grow, ssq);
.LBB0_1075:
	s_or_b64 exec, exec, s[20:21]
	ds_read_b128 v[16:19], v120 offset:12480
	v_lshl_add_u64 v[20:21], v[42:43], 1, s[4:5]
	s_waitcnt lgkmcnt(0)
	v_pk_add_f32 v[12:13], v[12:13], v[16:17]
	v_pk_add_f32 v[14:15], v[14:15], v[18:19]
	global_store_dwordx4 v[40:41], v[12:15], off
	v_cvt_pk_bf16_f32 v16, v12, v13
	v_cvt_pk_bf16_f32 v17, v14, v15
	v_pk_mul_f32 v[12:13], v[12:13], v[12:13]
	v_pk_mul_f32 v[14:15], v[14:15], v[14:15]
	v_add_f32_e32 v12, v12, v13
	v_add_f32_e32 v12, v12, v14
	v_add_f32_e32 v12, v12, v15
	global_store_dwordx2 v[20:21], v[16:17], off
	s_nop 0
	v_add_f32_dpp v12, v12, v12 row_ror:8 row_mask:0xf bank_mask:0xf bound_ctrl:1
	s_nop 1
	v_add_f32_dpp v12, v12, v12 row_ror:4 row_mask:0xf bank_mask:0xf bound_ctrl:1
	s_nop 1
	v_add_f32_dpp v12, v12, v12 row_ror:2 row_mask:0xf bank_mask:0xf bound_ctrl:1
	s_nop 1
	v_add_f32_dpp v12, v12, v12 row_ror:1 row_mask:0xf bank_mask:0xf bound_ctrl:1
	s_nop 0
	v_readlane_b32 s20, v12, 0
	v_readlane_b32 s23, v12, 16
	v_readlane_b32 s21, v12, 32
	v_readlane_b32 s22, v12, 48
	s_and_saveexec_b64 s[18:19], vcc
	s_cbranch_execz .LBB0_1077
	s_lshl_b64 s[14:15], s[14:15], 2
	v_mov_b32_e32 v12, s23
	s_add_u32 s14, s65, s14
	v_add_f32_e32 v12, s20, v12
	s_addc_u32 s15, s66, s15
	v_add_f32_e32 v12, s21, v12
	v_add_f32_e32 v14, s22, v12
	v_mov_b64_e32 v[12:13], s[14:15]
	global_atomic_add_f32 v[12:13], v14, off
.LBB0_1077:
	s_or_b64 exec, exec, s[18:19]
	ds_read_b128 v[12:15], v120 offset:13520
	v_lshl_add_u64 v[16:17], v[38:39], 1, s[4:5]
	s_waitcnt lgkmcnt(0)
	v_pk_add_f32 v[8:9], v[8:9], v[12:13]
	v_pk_add_f32 v[10:11], v[10:11], v[14:15]
	global_store_dwordx4 v[36:37], v[8:11], off
	v_cvt_pk_bf16_f32 v12, v8, v9
	v_cvt_pk_bf16_f32 v13, v10, v11
	v_pk_mul_f32 v[8:9], v[8:9], v[8:9]
	v_pk_mul_f32 v[10:11], v[10:11], v[10:11]
	v_add_f32_e32 v8, v8, v9
	v_add_f32_e32 v8, v8, v10
	v_add_f32_e32 v8, v8, v11
	global_store_dwordx2 v[16:17], v[12:13], off
	s_nop 0
	v_add_f32_dpp v8, v8, v8 row_ror:8 row_mask:0xf bank_mask:0xf bound_ctrl:1
	s_nop 1
	v_add_f32_dpp v8, v8, v8 row_ror:4 row_mask:0xf bank_mask:0xf bound_ctrl:1
	s_nop 1
	v_add_f32_dpp v8, v8, v8 row_ror:2 row_mask:0xf bank_mask:0xf bound_ctrl:1
	s_nop 1
	v_add_f32_dpp v8, v8, v8 row_ror:1 row_mask:0xf bank_mask:0xf bound_ctrl:1
	s_nop 0
	v_readlane_b32 s18, v8, 0
	v_readlane_b32 s21, v8, 16
	v_readlane_b32 s19, v8, 32
	v_readlane_b32 s20, v8, 48
	s_and_saveexec_b64 s[14:15], vcc
	s_cbranch_execz .LBB0_1079
	s_lshl_b64 s[12:13], s[12:13], 2
	v_mov_b32_e32 v8, s21
	s_add_u32 s12, s65, s12
	v_add_f32_e32 v8, s18, v8
	s_addc_u32 s13, s66, s13
	v_add_f32_e32 v8, s19, v8
	v_add_f32_e32 v10, s20, v8
	v_mov_b64_e32 v[8:9], s[12:13]
	global_atomic_add_f32 v[8:9], v10, off
.LBB0_1079:
	s_or_b64 exec, exec, s[14:15]
	ds_read_b128 v[8:11], v120 offset:14560
	v_lshl_add_u64 v[12:13], v[34:35], 1, s[4:5]
	s_waitcnt lgkmcnt(0)
	v_pk_add_f32 v[4:5], v[4:5], v[8:9]
	v_pk_add_f32 v[6:7], v[6:7], v[10:11]
	global_store_dwordx4 v[32:33], v[4:7], off
	v_cvt_pk_bf16_f32 v8, v4, v5
	v_cvt_pk_bf16_f32 v9, v6, v7
	v_pk_mul_f32 v[4:5], v[4:5], v[4:5]
	v_pk_mul_f32 v[6:7], v[6:7], v[6:7]
	v_add_f32_e32 v4, v4, v5
	v_add_f32_e32 v4, v4, v6
	v_add_f32_e32 v4, v4, v7
	global_store_dwordx2 v[12:13], v[8:9], off
	s_nop 0
	v_add_f32_dpp v4, v4, v4 row_ror:8 row_mask:0xf bank_mask:0xf bound_ctrl:1
	s_nop 1
	v_add_f32_dpp v4, v4, v4 row_ror:4 row_mask:0xf bank_mask:0xf bound_ctrl:1
	s_nop 1
	v_add_f32_dpp v4, v4, v4 row_ror:2 row_mask:0xf bank_mask:0xf bound_ctrl:1
	s_nop 1
	v_add_f32_dpp v4, v4, v4 row_ror:1 row_mask:0xf bank_mask:0xf bound_ctrl:1
	s_nop 0
	v_readlane_b32 s14, v4, 0
	v_readlane_b32 s19, v4, 16
	v_readlane_b32 s15, v4, 32
	v_readlane_b32 s18, v4, 48
	s_and_saveexec_b64 s[12:13], vcc
	s_cbranch_execz .LBB0_1081
	s_lshl_b64 s[10:11], s[10:11], 2
	v_mov_b32_e32 v4, s19
	s_add_u32 s10, s65, s10
	v_add_f32_e32 v4, s14, v4
	s_addc_u32 s11, s66, s11
	v_add_f32_e32 v4, s15, v4
	v_add_f32_e32 v6, s18, v4
	v_mov_b64_e32 v[4:5], s[10:11]
	global_atomic_add_f32 v[4:5], v6, off
.LBB0_1081:
	s_or_b64 exec, exec, s[12:13]
	ds_read_b128 v[4:7], v120 offset:15600
	v_lshl_add_u64 v[8:9], v[30:31], 1, s[4:5]
	s_waitcnt lgkmcnt(0)
	v_pk_add_f32 v[0:1], v[0:1], v[4:5]
	v_pk_add_f32 v[2:3], v[2:3], v[6:7]
	global_store_dwordx4 v[28:29], v[0:3], off
	v_cvt_pk_bf16_f32 v4, v0, v1
	v_cvt_pk_bf16_f32 v5, v2, v3
	v_pk_mul_f32 v[0:1], v[0:1], v[0:1]
	v_pk_mul_f32 v[2:3], v[2:3], v[2:3]
	v_add_f32_e32 v0, v0, v1
	v_add_f32_e32 v0, v0, v2
	v_add_f32_e32 v0, v0, v3
	global_store_dwordx2 v[8:9], v[4:5], off
	s_nop 0
	v_add_f32_dpp v0, v0, v0 row_ror:8 row_mask:0xf bank_mask:0xf bound_ctrl:1
	s_nop 1
	v_add_f32_dpp v0, v0, v0 row_ror:4 row_mask:0xf bank_mask:0xf bound_ctrl:1
	s_nop 1
	v_add_f32_dpp v0, v0, v0 row_ror:2 row_mask:0xf bank_mask:0xf bound_ctrl:1
	s_nop 1
	v_add_f32_dpp v0, v0, v0 row_ror:1 row_mask:0xf bank_mask:0xf bound_ctrl:1
	s_nop 0
	v_readlane_b32 s12, v0, 0
	v_readlane_b32 s15, v0, 16
	v_readlane_b32 s13, v0, 32
	v_readlane_b32 s14, v0, 48
	s_and_saveexec_b64 s[10:11], vcc
	s_cbranch_execz .LBB0_1010
	s_lshl_b64 s[8:9], s[8:9], 2
	v_mov_b32_e32 v0, s15
	s_add_u32 s8, s65, s8
	v_add_f32_e32 v0, s12, v0
	s_addc_u32 s9, s66, s9
	v_add_f32_e32 v0, s13, v0
	v_add_f32_e32 v2, s14, v0
	v_mov_b64_e32 v[0:1], s[8:9]
	global_atomic_add_f32 v[0:1], v2, off
	s_branch .LBB0_1010

; template <int EPI, int TS, bool VT>
; DEVI void gemm_epilogue(const Params& p, char* smem, f32x4 (&acc)[2][2][4][2], int m0, int n0, float scale, const float* ssin,
;                         float* ssout, u16* xbout, int wid, int lane, int wr, int wc, int fr, int fq) {
;     ...
;     {
;       float* tw = T + (wr * 64 + fq * 4) * TS + wc * 32 + fr;
; #pragma unroll
;       for (int m = 0; m < 4; ++m)
; #pragma unroll
;         for (int j = 0; j < 4; ++j)
; #pragma unroll
;           for (int v = 0; v < 4; ++v) tw[(m * 16 + j) * TS + (v >> 1) * 128 + (v & 1) * 16] = acc[ai][v >> 1][m][v & 1][j];
;     }
;     __syncthreads();
;     const int r0 = wid * 16;
;     const int g0 = m0 + ai * 128 + r0;
;     if constexpr (!VT) {
;       float rsv = 1.f;
;       if constexpr (EPI == E_PLEGATE || EPI == E_F32 || EPI == E_SWIGLU || EPI == E_GLAIN)
;         rsv = rsqrtf(ssin[g0 + (lane & 15)] * (1.f / 1024.f) + EPS);
;       if constexpr (EPI == E_QROPE) rsv = rsqrtf(ssin[g0 + (lane & 15)] * (1.f / 384.f) + EPS);
;       if constexpr (EPI == E_KV) rsv = rsqrtf(ssin[g0 + (lane & 15)] * (1.f / 256.f) + EPS);
;       for (int i0 = 0; i0 < 16; i0 += 8) {
;     ...
;           } else if constexpr (EPI == E_GLAIN) {
;             const float4 a = *(const float4*)(Tr + 4 * lane);
;             if (n0 < 3072) {
;               u16* O = (u16*)(wsb + (n0 < 512 ? OFF_QG : n0 < 1024 ? OFF_KG : OFF_RG));
;               const float f = n0 < 512 ? rs * 0.08838834764831845f : rs;
;               const int ld = n0 < 1024 ? 512 : 1024;
;               const int cc = n0 - (n0 < 512 ? 0 : n0 < 1024 ? 512 : 2048) + 4 * lane;
;               uint2 o;
;               o.x = pack2(a.x * f, a.y * f);
;               o.y = pack2(a.z * f, a.w * f);
;               st_nt8(O + (size_t)grow * ld + cc, o);
;             } else if (lane < 8) {
;               *(float4*)((float*)(wsb + OFF_GLO) + (size_t)grow * 32 + 4 * lane) = make_float4(a.x * rs, a.y * rs, a.z * rs, a.w * rs);
;             }
.LBB0_1120:
	s_and_b32 s0, s34, 0xfffffc
	s_lshl_b32 s19, s19, 7
	v_lshrrev_b32_e32 v128, 2, v132
	v_and_b32_e32 v137, 63, v132
	s_cmp_lg_u32 s0, 4
	v_and_or_b32 v138, v128, 12, s21
	s_mov_b64 s[0:1], -1
	v_lshlrev_b32_e32 v139, 2, v136
	s_cbranch_scc0 .LBB0_1314
	v_readlane_b32 s4, v254, 13
	s_movk_i32 s0, 0x410
	v_readlane_b32 s5, v254, 14
	v_mul_lo_u32 v128, v138, s0
	s_lshl_b32 s0, s15, 4
	v_lshlrev_b32_e32 v148, 4, v137
	v_add3_u32 v141, s19, v128, v139
	s_add_i32 s22, s0, s14
	v_lshl_add_u64 v[128:129], s[4:5], 0, v[148:149]
	s_mov_b64 s[0:1], 0x3295ee00
	v_lshl_add_u64 v[132:133], v[128:129], 0, s[0:1]
	v_or_b32_e32 v128, s22, v136
	v_ashrrev_i32_e32 v129, 31, v128
	v_add_u32_e32 v142, 0x400, v141
	v_add_u32_e32 v143, 0x800, v141
	v_add_u32_e32 v144, 0xc00, v141
	v_add_u32_e32 v145, 0x4000, v141
	v_add_u32_e32 v146, 0x4400, v141
	v_add_u32_e32 v147, 0x4800, v141
	v_add_u32_e32 v152, 0x4c00, v141
	v_add_u32_e32 v153, 0x8000, v141
	v_add_u32_e32 v154, 0x8400, v141
	v_add_u32_e32 v155, 0x8800, v141
	v_add_u32_e32 v156, 0x8c00, v141
	v_add_u32_e32 v157, 0x9000, v141
	v_add_u32_e32 v158, 0xc000, v141
	v_add_u32_e32 v159, 0xc400, v141
	v_add_u32_e32 v160, 0xc800, v141
	v_add_u32_e32 v161, 0xcc00, v141
	v_add_u32_e32 v162, 0xd000, v141
	v_lshl_add_u64 v[128:129], v[128:129], 2, s[16:17]
	ds_write2_b32 v141, v88, v96 offset1:16
	ds_write2_b32 v141, v120, v124 offset0:128 offset1:144
	ds_write2_b32 v142, v89, v97 offset0:4 offset1:20
	ds_write2_b32 v142, v121, v125 offset0:132 offset1:148
	ds_write2_b32 v143, v90, v98 offset0:8 offset1:24
	ds_write2_b32 v143, v122, v126 offset0:136 offset1:152
	ds_write2_b32 v144, v91, v99 offset0:12 offset1:28
	ds_write2_b32 v144, v123, v127 offset0:140 offset1:156
	ds_write2_b32 v145, v80, v84 offset0:64 offset1:80
	ds_write2_b32 v145, v112, v116 offset0:192 offset1:208
	ds_write2_b32 v146, v81, v85 offset0:68 offset1:84
	ds_write2_b32 v146, v113, v117 offset0:196 offset1:212
	ds_write2_b32 v147, v82, v86 offset0:72 offset1:88
	ds_write2_b32 v147, v114, v118 offset0:200 offset1:216
	ds_write2_b32 v152, v83, v87 offset0:76 offset1:92
	ds_write2_b32 v152, v115, v119 offset0:204 offset1:220
	ds_write2_b32 v153, v72, v76 offset0:128 offset1:144
	ds_write2_b32 v154, v104, v108 offset1:16
	ds_write2_b32 v154, v73, v77 offset0:132 offset1:148
	ds_write2_b32 v155, v105, v109 offset0:4 offset1:20
	ds_write2_b32 v155, v74, v78 offset0:136 offset1:152
	ds_write2_b32 v156, v106, v110 offset0:8 offset1:24
	ds_write2_b32 v156, v75, v79 offset0:140 offset1:156
	ds_write2_b32 v157, v107, v111 offset0:12 offset1:28
	ds_write2_b32 v158, v64, v68 offset0:192 offset1:208
	ds_write2_b32 v159, v92, v100 offset0:64 offset1:80
	ds_write2_b32 v159, v65, v69 offset0:196 offset1:212
	ds_write2_b32 v160, v93, v101 offset0:68 offset1:84
	ds_write2_b32 v160, v66, v70 offset0:200 offset1:216
	ds_write2_b32 v161, v94, v102 offset0:72 offset1:88
	ds_write2_b32 v161, v67, v71 offset0:204 offset1:220
	ds_write2_b32 v162, v95, v103 offset0:76 offset1:92
	s_waitcnt vmcnt(0) lgkmcnt(0)
	s_barrier
	global_load_dword v128, v[128:129], off
	s_cmp_gt_i32 s34, 11
	s_cselect_b64 s[8:9], -1, 0
	s_cmp_lt_i32 s34, 4
	s_mov_b32 s0, 0x1995ee00
	s_cselect_b32 s23, s0, 0x2895ee00
	s_movk_i32 s0, 0xfe00
	s_cselect_b32 s35, s0, 0xfffff800
	s_cselect_b32 s21, 9, 10
	s_cmp_lt_i32 s34, 2
	s_cselect_b64 s[0:1], -1, 0
	s_and_b64 s[30:31], s[0:1], exec
	s_cselect_b32 s23, 0x1495ee00, s23
	s_cselect_b32 s31, 0, s35
	s_add_u32 s4, s4, s23
	s_mul_i32 s23, s15, 0x4100
	v_add_u32_e32 v140, s23, v148
	v_cmp_gt_u32_e64 s[6:7], 8, v137
	s_addc_u32 s5, s5, 0
	s_mov_b64 s[34:35], -1
	s_waitcnt vmcnt(0) lgkmcnt(0)
	v_fmamk_f32 v128, v128, 0x3a800000, v150
	v_cmp_gt_f32_e32 vcc, s29, v128
	v_mul_f32_e32 v129, 0x4b800000, v128
	s_nop 0
	v_cndmask_b32_e32 v128, v128, v129, vcc
	v_rsq_f32_e32 v128, v128
	s_nop 0
	v_mul_f32_e32 v129, 0x45800000, v128
	v_cndmask_b32_e32 v163, v128, v129, vcc
	ds_read_b128 v[128:131], v140
	v_readlane_b32 s30, v163, 0
	s_and_b64 vcc, exec, s[8:9]
	s_cbranch_vccz .LBB0_1125
	s_and_saveexec_b64 s[34:35], s[6:7]
	s_cbranch_execz .LBB0_1124
	s_ashr_i32 s23, s22, 31
	s_lshl_b64 s[66:67], s[22:23], 7
	v_lshl_add_u64 v[134:135], v[132:133], 0, s[66:67]
	s_waitcnt lgkmcnt(0)
	v_pk_mul_f32 v[164:165], s[30:31], v[128:129] op_sel_hi:[0,1]
	v_pk_mul_f32 v[166:167], s[30:31], v[130:131] op_sel_hi:[0,1]
	global_store_dwordx4 v[134:135], v[164:167], off

; template <int EPI, int TS, bool VT>
; DEVI void gemm_epilogue(const Params& p, char* smem, f32x4 (&acc)[2][2][4][2], int m0, int n0, float scale, const float* ssin,
;                         float* ssout, u16* xbout, int wid, int lane, int wr, int wc, int fr, int fq) {
;     ...
;           } else if constexpr (EPI == E_GLAIN) {
;             const float4 a = *(const float4*)(Tr + 4 * lane);
;             if (n0 < 3072) {
;               u16* O = (u16*)(wsb + (n0 < 512 ? OFF_QG : n0 < 1024 ? OFF_KG : OFF_RG));
;               const float f = n0 < 512 ? rs * 0.08838834764831845f : rs;
;               const int ld = n0 < 1024 ? 512 : 1024;
;               const int cc = n0 - (n0 < 512 ? 0 : n0 < 1024 ? 512 : 2048) + 4 * lane;
;               uint2 o;
;               o.x = pack2(a.x * f, a.y * f);
;               o.y = pack2(a.z * f, a.w * f);
;               st_nt8(O + (size_t)grow * ld + cc, o);
;             } else if (lane < 8) {
;               *(float4*)((float*)(wsb + OFF_GLO) + (size_t)grow * 32 + 4 * lane) = make_float4(a.x * rs, a.y * rs, a.z * rs, a.w * rs);
;             }
.LBB0_1125:
	s_add_i32 s31, s31, s20
	v_lshl_or_b32 v134, v137, 2, s31
	v_ashrrev_i32_e32 v135, 31, v134
	s_andn2_b64 vcc, exec, s[34:35]
	v_lshl_add_u64 v[134:135], v[134:135], 1, s[4:5]
	s_cbranch_vccnz .LBB0_1127
	v_mul_f32_e32 v148, s30, v172
	v_mov_b32_e32 v164, s30
	v_cndmask_b32_e64 v148, v164, v148, s[0:1]
	s_ashr_i32 s23, s22, 31
	s_waitcnt lgkmcnt(0)
	v_pk_mul_f32 v[128:129], v[128:129], v[148:149] op_sel_hi:[1,0]
	v_pk_mul_f32 v[130:131], v[148:149], v[130:131] op_sel_hi:[0,1]
	s_lshl_b64 s[4:5], s[22:23], s21
	v_cvt_pk_bf16_f32 v128, v128, v129
	v_cvt_pk_bf16_f32 v129, v130, v131
	v_lshl_add_u64 v[130:131], s[4:5], 1, v[134:135]
	global_store_dwordx2 v[130:131], v[128:129], off
.LBB0_1127:
	s_waitcnt lgkmcnt(0)
	ds_read_b128 v[128:131], v140 offset:1040
	v_cndmask_b32_e64 v148, 0, 1, s[8:9]
	s_or_b32 s30, s22, 1
	v_readlane_b32 s34, v163, 1
	v_cmp_ne_u32_e64 s[4:5], 1, v148
	s_andn2_b64 vcc, exec, s[8:9]
	s_mov_b64 s[8:9], -1
	s_cbranch_vccnz .LBB0_1131
	s_and_saveexec_b64 s[8:9], s[6:7]
	s_cbranch_execz .LBB0_1130
	s_ashr_i32 s31, s30, 31
	s_lshl_b64 s[66:67], s[30:31], 7
	v_lshl_add_u64 v[174:175], v[132:133], 0, s[66:67]
	s_waitcnt lgkmcnt(0)
	v_pk_mul_f32 v[164:165], s[34:35], v[128:129] op_sel_hi:[0,1]
	v_pk_mul_f32 v[166:167], s[34:35], v[130:131] op_sel_hi:[0,1]
	global_store_dwordx4 v[174:175], v[164:167], off

; template <int EPI, int TS, bool VT>
; DEVI void gemm_epilogue(const Params& p, char* smem, f32x4 (&acc)[2][2][4][2], int m0, int n0, float scale, const float* ssin,
;                         float* ssout, u16* xbout, int wid, int lane, int wr, int wc, int fr, int fq) {
;     ...
;           } else if constexpr (EPI == E_GLAIN) {
;             const float4 a = *(const float4*)(Tr + 4 * lane);
;             if (n0 < 3072) {
;               u16* O = (u16*)(wsb + (n0 < 512 ? OFF_QG : n0 < 1024 ? OFF_KG : OFF_RG));
;               const float f = n0 < 512 ? rs * 0.08838834764831845f : rs;
;               const int ld = n0 < 1024 ? 512 : 1024;
;               const int cc = n0 - (n0 < 512 ? 0 : n0 < 1024 ? 512 : 2048) + 4 * lane;
;               uint2 o;
;               o.x = pack2(a.x * f, a.y * f);
;               o.y = pack2(a.z * f, a.w * f);
;               st_nt8(O + (size_t)grow * ld + cc, o);
;             } else if (lane < 8) {
;               *(float4*)((float*)(wsb + OFF_GLO) + (size_t)grow * 32 + 4 * lane) = make_float4(a.x * rs, a.y * rs, a.z * rs, a.w * rs);
;             }
.LBB0_1131:
	s_andn2_b64 vcc, exec, s[8:9]
	s_cbranch_vccnz .LBB0_1133
	v_mul_f32_e32 v148, s34, v172
	v_mov_b32_e32 v164, s34
	v_cndmask_b32_e64 v148, v164, v148, s[0:1]
	s_ashr_i32 s31, s30, 31
	s_waitcnt lgkmcnt(0)
	v_pk_mul_f32 v[128:129], v[128:129], v[148:149] op_sel_hi:[1,0]
	v_pk_mul_f32 v[130:131], v[148:149], v[130:131] op_sel_hi:[0,1]
	s_lshl_b64 s[8:9], s[30:31], s21
	v_cvt_pk_bf16_f32 v128, v128, v129
	v_cvt_pk_bf16_f32 v129, v130, v131
	v_lshl_add_u64 v[130:131], s[8:9], 1, v[134:135]
	global_store_dwordx2 v[130:131], v[128:129], off
.LBB0_1133:
	s_waitcnt lgkmcnt(0)
	ds_read_b128 v[128:131], v140 offset:2080
	s_or_b32 s8, s22, 2
	v_readlane_b32 s30, v163, 2
	s_and_b64 vcc, exec, s[4:5]
	s_mov_b64 s[34:35], -1
	s_cbranch_vccnz .LBB0_1137
	s_and_saveexec_b64 s[34:35], s[6:7]
	s_cbranch_execz .LBB0_1136
	s_ashr_i32 s9, s8, 31
	s_lshl_b64 s[66:67], s[8:9], 7
	v_lshl_add_u64 v[174:175], v[132:133], 0, s[66:67]
	s_waitcnt lgkmcnt(0)
	v_pk_mul_f32 v[164:165], s[30:31], v[128:129] op_sel_hi:[0,1]
	v_pk_mul_f32 v[166:167], s[30:31], v[130:131] op_sel_hi:[0,1]
	global_store_dwordx4 v[174:175], v[164:167], off

; template <int EPI, int TS, bool VT>
; DEVI void gemm_epilogue(const Params& p, char* smem, f32x4 (&acc)[2][2][4][2], int m0, int n0, float scale, const float* ssin,
;                         float* ssout, u16* xbout, int wid, int lane, int wr, int wc, int fr, int fq) {
;     ...
;           } else if constexpr (EPI == E_GLAIN) {
;             const float4 a = *(const float4*)(Tr + 4 * lane);
;             if (n0 < 3072) {
;               u16* O = (u16*)(wsb + (n0 < 512 ? OFF_QG : n0 < 1024 ? OFF_KG : OFF_RG));
;               const float f = n0 < 512 ? rs * 0.08838834764831845f : rs;
;               const int ld = n0 < 1024 ? 512 : 1024;
;               const int cc = n0 - (n0 < 512 ? 0 : n0 < 1024 ? 512 : 2048) + 4 * lane;
;               uint2 o;
;               o.x = pack2(a.x * f, a.y * f);
;               o.y = pack2(a.z * f, a.w * f);
;               st_nt8(O + (size_t)grow * ld + cc, o);
;             } else if (lane < 8) {
;               *(float4*)((float*)(wsb + OFF_GLO) + (size_t)grow * 32 + 4 * lane) = make_float4(a.x * rs, a.y * rs, a.z * rs, a.w * rs);
;             }
.LBB0_1137:
	s_andn2_b64 vcc, exec, s[34:35]
	s_cbranch_vccnz .LBB0_1139
	v_mul_f32_e32 v148, s30, v172
	v_mov_b32_e32 v164, s30
	v_cndmask_b32_e64 v148, v164, v148, s[0:1]
	s_ashr_i32 s9, s8, 31
	s_waitcnt lgkmcnt(0)
	v_pk_mul_f32 v[128:129], v[128:129], v[148:149] op_sel_hi:[1,0]
	v_pk_mul_f32 v[130:131], v[148:149], v[130:131] op_sel_hi:[0,1]
	s_lshl_b64 s[8:9], s[8:9], s21
	v_cvt_pk_bf16_f32 v128, v128, v129
	v_cvt_pk_bf16_f32 v129, v130, v131
	v_lshl_add_u64 v[130:131], s[8:9], 1, v[134:135]
	global_store_dwordx2 v[130:131], v[128:129], off
.LBB0_1139:
	s_waitcnt lgkmcnt(0)
	ds_read_b128 v[128:131], v140 offset:3120
	s_or_b32 s8, s22, 3
	v_readlane_b32 s30, v163, 3
	s_and_b64 vcc, exec, s[4:5]
	s_mov_b64 s[34:35], -1
	s_cbranch_vccnz .LBB0_1143
	s_and_saveexec_b64 s[34:35], s[6:7]
	s_cbranch_execz .LBB0_1142
	s_ashr_i32 s9, s8, 31
	s_lshl_b64 s[66:67], s[8:9], 7
	v_lshl_add_u64 v[174:175], v[132:133], 0, s[66:67]
	s_waitcnt lgkmcnt(0)
	v_pk_mul_f32 v[164:165], s[30:31], v[128:129] op_sel_hi:[0,1]
	v_pk_mul_f32 v[166:167], s[30:31], v[130:131] op_sel_hi:[0,1]
	global_store_dwordx4 v[174:175], v[164:167], off

; template <int EPI, int TS, bool VT>
; DEVI void gemm_epilogue(const Params& p, char* smem, f32x4 (&acc)[2][2][4][2], int m0, int n0, float scale, const float* ssin,
;                         float* ssout, u16* xbout, int wid, int lane, int wr, int wc, int fr, int fq) {
;     ...
;           } else if constexpr (EPI == E_GLAIN) {
;             const float4 a = *(const float4*)(Tr + 4 * lane);
;             if (n0 < 3072) {
;               u16* O = (u16*)(wsb + (n0 < 512 ? OFF_QG : n0 < 1024 ? OFF_KG : OFF_RG));
;               const float f = n0 < 512 ? rs * 0.08838834764831845f : rs;
;               const int ld = n0 < 1024 ? 512 : 1024;
;               const int cc = n0 - (n0 < 512 ? 0 : n0 < 1024 ? 512 : 2048) + 4 * lane;
;               uint2 o;
;               o.x = pack2(a.x * f, a.y * f);
;               o.y = pack2(a.z * f, a.w * f);
;               st_nt8(O + (size_t)grow * ld + cc, o);
;             } else if (lane < 8) {
;               *(float4*)((float*)(wsb + OFF_GLO) + (size_t)grow * 32 + 4 * lane) = make_float4(a.x * rs, a.y * rs, a.z * rs, a.w * rs);
;             }
.LBB0_1145:
	s_waitcnt lgkmcnt(0)
	ds_read_b128 v[128:131], v140 offset:4160
	s_or_b32 s8, s22, 4
	v_readlane_b32 s30, v163, 4
	s_and_b64 vcc, exec, s[4:5]
	s_mov_b64 s[34:35], -1
	s_cbranch_vccnz .LBB0_1149
	s_and_saveexec_b64 s[34:35], s[6:7]
	s_cbranch_execz .LBB0_1148
	s_ashr_i32 s9, s8, 31
	s_lshl_b64 s[66:67], s[8:9], 7
	v_lshl_add_u64 v[174:175], v[132:133], 0, s[66:67]
	s_waitcnt lgkmcnt(0)
	v_pk_mul_f32 v[164:165], s[30:31], v[128:129] op_sel_hi:[0,1]
	v_pk_mul_f32 v[166:167], s[30:31], v[130:131] op_sel_hi:[0,1]
	global_store_dwordx4 v[174:175], v[164:167], off

; template <int EPI, int TS, bool VT>
; DEVI void gemm_epilogue(const Params& p, char* smem, f32x4 (&acc)[2][2][4][2], int m0, int n0, float scale, const float* ssin,
;                         float* ssout, u16* xbout, int wid, int lane, int wr, int wc, int fr, int fq) {
;     ...
;           } else if constexpr (EPI == E_GLAIN) {
;             const float4 a = *(const float4*)(Tr + 4 * lane);
;             if (n0 < 3072) {
;               u16* O = (u16*)(wsb + (n0 < 512 ? OFF_QG : n0 < 1024 ? OFF_KG : OFF_RG));
;               const float f = n0 < 512 ? rs * 0.08838834764831845f : rs;
;               const int ld = n0 < 1024 ? 512 : 1024;
;               const int cc = n0 - (n0 < 512 ? 0 : n0 < 1024 ? 512 : 2048) + 4 * lane;
;               uint2 o;
;               o.x = pack2(a.x * f, a.y * f);
;               o.y = pack2(a.z * f, a.w * f);
;               st_nt8(O + (size_t)grow * ld + cc, o);
;             } else if (lane < 8) {
;               *(float4*)((float*)(wsb + OFF_GLO) + (size_t)grow * 32 + 4 * lane) = make_float4(a.x * rs, a.y * rs, a.z * rs, a.w * rs);
;             }
.LBB0_1151:
	s_waitcnt lgkmcnt(0)
	ds_read_b128 v[128:131], v140 offset:5200
	s_or_b32 s8, s22, 5
	v_readlane_b32 s30, v163, 5
	s_and_b64 vcc, exec, s[4:5]
	s_mov_b64 s[34:35], -1
	s_cbranch_vccnz .LBB0_1155
	s_and_saveexec_b64 s[34:35], s[6:7]
	s_cbranch_execz .LBB0_1154
	s_ashr_i32 s9, s8, 31
	s_lshl_b64 s[66:67], s[8:9], 7
	v_lshl_add_u64 v[174:175], v[132:133], 0, s[66:67]
	s_waitcnt lgkmcnt(0)
	v_pk_mul_f32 v[164:165], s[30:31], v[128:129] op_sel_hi:[0,1]
	v_pk_mul_f32 v[166:167], s[30:31], v[130:131] op_sel_hi:[0,1]
	global_store_dwordx4 v[174:175], v[164:167], off

; template <int EPI, int TS, bool VT>
; DEVI void gemm_epilogue(const Params& p, char* smem, f32x4 (&acc)[2][2][4][2], int m0, int n0, float scale, const float* ssin,
;                         float* ssout, u16* xbout, int wid, int lane, int wr, int wc, int fr, int fq) {
;     ...
;           } else if constexpr (EPI == E_GLAIN) {
;             const float4 a = *(const float4*)(Tr + 4 * lane);
;             if (n0 < 3072) {
;               u16* O = (u16*)(wsb + (n0 < 512 ? OFF_QG : n0 < 1024 ? OFF_KG : OFF_RG));
;               const float f = n0 < 512 ? rs * 0.08838834764831845f : rs;
;               const int ld = n0 < 1024 ? 512 : 1024;
;               const int cc = n0 - (n0 < 512 ? 0 : n0 < 1024 ? 512 : 2048) + 4 * lane;
;               uint2 o;
;               o.x = pack2(a.x * f, a.y * f);
;               o.y = pack2(a.z * f, a.w * f);
;               st_nt8(O + (size_t)grow * ld + cc, o);
;             } else if (lane < 8) {
;               *(float4*)((float*)(wsb + OFF_GLO) + (size_t)grow * 32 + 4 * lane) = make_float4(a.x * rs, a.y * rs, a.z * rs, a.w * rs);
;             }
.LBB0_1157:
	s_waitcnt lgkmcnt(0)
	ds_read_b128 v[128:131], v140 offset:6240
	s_or_b32 s8, s22, 6
	v_readlane_b32 s30, v163, 6
	s_and_b64 vcc, exec, s[4:5]
	s_mov_b64 s[34:35], -1
	s_cbranch_vccnz .LBB0_1161
	s_and_saveexec_b64 s[34:35], s[6:7]
	s_cbranch_execz .LBB0_1160
	s_ashr_i32 s9, s8, 31
	s_lshl_b64 s[66:67], s[8:9], 7
	v_lshl_add_u64 v[174:175], v[132:133], 0, s[66:67]
	s_waitcnt lgkmcnt(0)
	v_pk_mul_f32 v[164:165], s[30:31], v[128:129] op_sel_hi:[0,1]
	v_pk_mul_f32 v[166:167], s[30:31], v[130:131] op_sel_hi:[0,1]
	global_store_dwordx4 v[174:175], v[164:167], off

; template <int EPI, int TS, bool VT>
; DEVI void gemm_epilogue(const Params& p, char* smem, f32x4 (&acc)[2][2][4][2], int m0, int n0, float scale, const float* ssin,
;                         float* ssout, u16* xbout, int wid, int lane, int wr, int wc, int fr, int fq) {
;     ...
;           } else if constexpr (EPI == E_GLAIN) {
;             const float4 a = *(const float4*)(Tr + 4 * lane);
;             if (n0 < 3072) {
;               u16* O = (u16*)(wsb + (n0 < 512 ? OFF_QG : n0 < 1024 ? OFF_KG : OFF_RG));
;               const float f = n0 < 512 ? rs * 0.08838834764831845f : rs;
;               const int ld = n0 < 1024 ? 512 : 1024;
;               const int cc = n0 - (n0 < 512 ? 0 : n0 < 1024 ? 512 : 2048) + 4 * lane;
;               uint2 o;
;               o.x = pack2(a.x * f, a.y * f);
;               o.y = pack2(a.z * f, a.w * f);
;               st_nt8(O + (size_t)grow * ld + cc, o);
;             } else if (lane < 8) {
;               *(float4*)((float*)(wsb + OFF_GLO) + (size_t)grow * 32 + 4 * lane) = make_float4(a.x * rs, a.y * rs, a.z * rs, a.w * rs);
;             }
.LBB0_1163:
	s_waitcnt lgkmcnt(0)
	ds_read_b128 v[128:131], v140 offset:7280
	s_or_b32 s8, s22, 7
	v_readlane_b32 s30, v163, 7
	s_and_b64 vcc, exec, s[4:5]
	s_mov_b64 s[34:35], -1
	s_cbranch_vccnz .LBB0_1167
	s_and_saveexec_b64 s[34:35], s[6:7]
	s_cbranch_execz .LBB0_1166
	s_ashr_i32 s9, s8, 31
	s_lshl_b64 s[66:67], s[8:9], 7
	v_lshl_add_u64 v[174:175], v[132:133], 0, s[66:67]
	s_waitcnt lgkmcnt(0)
	v_pk_mul_f32 v[164:165], s[30:31], v[128:129] op_sel_hi:[0,1]
	v_pk_mul_f32 v[166:167], s[30:31], v[130:131] op_sel_hi:[0,1]
	global_store_dwordx4 v[174:175], v[164:167], off

; template <int EPI, int TS, bool VT>
; DEVI void gemm_epilogue(const Params& p, char* smem, f32x4 (&acc)[2][2][4][2], int m0, int n0, float scale, const float* ssin,
;                         float* ssout, u16* xbout, int wid, int lane, int wr, int wc, int fr, int fq) {
;     ...
;           } else if constexpr (EPI == E_GLAIN) {
;             const float4 a = *(const float4*)(Tr + 4 * lane);
;             if (n0 < 3072) {
;               u16* O = (u16*)(wsb + (n0 < 512 ? OFF_QG : n0 < 1024 ? OFF_KG : OFF_RG));
;               const float f = n0 < 512 ? rs * 0.08838834764831845f : rs;
;               const int ld = n0 < 1024 ? 512 : 1024;
;               const int cc = n0 - (n0 < 512 ? 0 : n0 < 1024 ? 512 : 2048) + 4 * lane;
;               uint2 o;
;               o.x = pack2(a.x * f, a.y * f);
;               o.y = pack2(a.z * f, a.w * f);
;               st_nt8(O + (size_t)grow * ld + cc, o);
;             } else if (lane < 8) {
;               *(float4*)((float*)(wsb + OFF_GLO) + (size_t)grow * 32 + 4 * lane) = make_float4(a.x * rs, a.y * rs, a.z * rs, a.w * rs);
;             }
.LBB0_1169:
	s_waitcnt lgkmcnt(0)
	ds_read_b128 v[128:131], v140 offset:8320
	s_or_b32 s8, s22, 8
	v_readlane_b32 s30, v163, 8
	s_and_b64 vcc, exec, s[4:5]
	s_mov_b64 s[34:35], -1
	s_cbranch_vccnz .LBB0_1173
	s_and_saveexec_b64 s[34:35], s[6:7]
	s_cbranch_execz .LBB0_1172
	s_ashr_i32 s9, s8, 31
	s_lshl_b64 s[66:67], s[8:9], 7
	v_lshl_add_u64 v[174:175], v[132:133], 0, s[66:67]
	s_waitcnt lgkmcnt(0)
	v_pk_mul_f32 v[164:165], s[30:31], v[128:129] op_sel_hi:[0,1]
	v_pk_mul_f32 v[166:167], s[30:31], v[130:131] op_sel_hi:[0,1]
	global_store_dwordx4 v[174:175], v[164:167], off

; template <int EPI, int TS, bool VT>
; DEVI void gemm_epilogue(const Params& p, char* smem, f32x4 (&acc)[2][2][4][2], int m0, int n0, float scale, const float* ssin,
;                         float* ssout, u16* xbout, int wid, int lane, int wr, int wc, int fr, int fq) {
;     ...
;           } else if constexpr (EPI == E_GLAIN) {
;             const float4 a = *(const float4*)(Tr + 4 * lane);
;             if (n0 < 3072) {
;               u16* O = (u16*)(wsb + (n0 < 512 ? OFF_QG : n0 < 1024 ? OFF_KG : OFF_RG));
;               const float f = n0 < 512 ? rs * 0.08838834764831845f : rs;
;               const int ld = n0 < 1024 ? 512 : 1024;
;               const int cc = n0 - (n0 < 512 ? 0 : n0 < 1024 ? 512 : 2048) + 4 * lane;
;               uint2 o;
;               o.x = pack2(a.x * f, a.y * f);
;               o.y = pack2(a.z * f, a.w * f);
;               st_nt8(O + (size_t)grow * ld + cc, o);
;             } else if (lane < 8) {
;               *(float4*)((float*)(wsb + OFF_GLO) + (size_t)grow * 32 + 4 * lane) = make_float4(a.x * rs, a.y * rs, a.z * rs, a.w * rs);
;             }
.LBB0_1175:
	s_waitcnt lgkmcnt(0)
	ds_read_b128 v[128:131], v140 offset:9360
	s_or_b32 s8, s22, 9
	v_readlane_b32 s30, v163, 9
	s_and_b64 vcc, exec, s[4:5]
	s_mov_b64 s[34:35], -1
	s_cbranch_vccnz .LBB0_1179
	s_and_saveexec_b64 s[34:35], s[6:7]
	s_cbranch_execz .LBB0_1178
	s_ashr_i32 s9, s8, 31
	s_lshl_b64 s[66:67], s[8:9], 7
	v_lshl_add_u64 v[174:175], v[132:133], 0, s[66:67]
	s_waitcnt lgkmcnt(0)
	v_pk_mul_f32 v[164:165], s[30:31], v[128:129] op_sel_hi:[0,1]
	v_pk_mul_f32 v[166:167], s[30:31], v[130:131] op_sel_hi:[0,1]
	global_store_dwordx4 v[174:175], v[164:167], off

; template <int EPI, int TS, bool VT>
; DEVI void gemm_epilogue(const Params& p, char* smem, f32x4 (&acc)[2][2][4][2], int m0, int n0, float scale, const float* ssin,
;                         float* ssout, u16* xbout, int wid, int lane, int wr, int wc, int fr, int fq) {
;     ...
;           } else if constexpr (EPI == E_GLAIN) {
;             const float4 a = *(const float4*)(Tr + 4 * lane);
;             if (n0 < 3072) {
;               u16* O = (u16*)(wsb + (n0 < 512 ? OFF_QG : n0 < 1024 ? OFF_KG : OFF_RG));
;               const float f = n0 < 512 ? rs * 0.08838834764831845f : rs;
;               const int ld = n0 < 1024 ? 512 : 1024;
;               const int cc = n0 - (n0 < 512 ? 0 : n0 < 1024 ? 512 : 2048) + 4 * lane;
;               uint2 o;
;               o.x = pack2(a.x * f, a.y * f);
;               o.y = pack2(a.z * f, a.w * f);
;               st_nt8(O + (size_t)grow * ld + cc, o);
;             } else if (lane < 8) {
;               *(float4*)((float*)(wsb + OFF_GLO) + (size_t)grow * 32 + 4 * lane) = make_float4(a.x * rs, a.y * rs, a.z * rs, a.w * rs);
;             }
.LBB0_1181:
	s_waitcnt lgkmcnt(0)
	ds_read_b128 v[128:131], v140 offset:10400
	s_or_b32 s8, s22, 10
	v_readlane_b32 s30, v163, 10
	s_and_b64 vcc, exec, s[4:5]
	s_mov_b64 s[34:35], -1
	s_cbranch_vccnz .LBB0_1185
	s_and_saveexec_b64 s[34:35], s[6:7]
	s_cbranch_execz .LBB0_1184
	s_ashr_i32 s9, s8, 31
	s_lshl_b64 s[66:67], s[8:9], 7
	v_lshl_add_u64 v[174:175], v[132:133], 0, s[66:67]
	s_waitcnt lgkmcnt(0)
	v_pk_mul_f32 v[164:165], s[30:31], v[128:129] op_sel_hi:[0,1]
	v_pk_mul_f32 v[166:167], s[30:31], v[130:131] op_sel_hi:[0,1]
	global_store_dwordx4 v[174:175], v[164:167], off

; template <int EPI, int TS, bool VT>
; DEVI void gemm_epilogue(const Params& p, char* smem, f32x4 (&acc)[2][2][4][2], int m0, int n0, float scale, const float* ssin,
;                         float* ssout, u16* xbout, int wid, int lane, int wr, int wc, int fr, int fq) {
;     ...
;           } else if constexpr (EPI == E_GLAIN) {
;             const float4 a = *(const float4*)(Tr + 4 * lane);
;             if (n0 < 3072) {
;               u16* O = (u16*)(wsb + (n0 < 512 ? OFF_QG : n0 < 1024 ? OFF_KG : OFF_RG));
;               const float f = n0 < 512 ? rs * 0.08838834764831845f : rs;
;               const int ld = n0 < 1024 ? 512 : 1024;
;               const int cc = n0 - (n0 < 512 ? 0 : n0 < 1024 ? 512 : 2048) + 4 * lane;
;               uint2 o;
;               o.x = pack2(a.x * f, a.y * f);
;               o.y = pack2(a.z * f, a.w * f);
;               st_nt8(O + (size_t)grow * ld + cc, o);
;             } else if (lane < 8) {
;               *(float4*)((float*)(wsb + OFF_GLO) + (size_t)grow * 32 + 4 * lane) = make_float4(a.x * rs, a.y * rs, a.z * rs, a.w * rs);
;             }
.LBB0_1187:
	s_waitcnt lgkmcnt(0)
	ds_read_b128 v[128:131], v140 offset:11440
	s_or_b32 s8, s22, 11
	v_readlane_b32 s30, v163, 11
	s_and_b64 vcc, exec, s[4:5]
	s_mov_b64 s[34:35], -1
	s_cbranch_vccnz .LBB0_1191
	s_and_saveexec_b64 s[34:35], s[6:7]
	s_cbranch_execz .LBB0_1190
	s_ashr_i32 s9, s8, 31
	s_lshl_b64 s[66:67], s[8:9], 7
	v_lshl_add_u64 v[174:175], v[132:133], 0, s[66:67]
	s_waitcnt lgkmcnt(0)
	v_pk_mul_f32 v[164:165], s[30:31], v[128:129] op_sel_hi:[0,1]
	v_pk_mul_f32 v[166:167], s[30:31], v[130:131] op_sel_hi:[0,1]
	global_store_dwordx4 v[174:175], v[164:167], off

; template <int EPI, int TS, bool VT>
; DEVI void gemm_epilogue(const Params& p, char* smem, f32x4 (&acc)[2][2][4][2], int m0, int n0, float scale, const float* ssin,
;                         float* ssout, u16* xbout, int wid, int lane, int wr, int wc, int fr, int fq) {
;     ...
;           } else if constexpr (EPI == E_GLAIN) {
;             const float4 a = *(const float4*)(Tr + 4 * lane);
;             if (n0 < 3072) {
;               u16* O = (u16*)(wsb + (n0 < 512 ? OFF_QG : n0 < 1024 ? OFF_KG : OFF_RG));
;               const float f = n0 < 512 ? rs * 0.08838834764831845f : rs;
;               const int ld = n0 < 1024 ? 512 : 1024;
;               const int cc = n0 - (n0 < 512 ? 0 : n0 < 1024 ? 512 : 2048) + 4 * lane;
;               uint2 o;
;               o.x = pack2(a.x * f, a.y * f);
;               o.y = pack2(a.z * f, a.w * f);
;               st_nt8(O + (size_t)grow * ld + cc, o);
;             } else if (lane < 8) {
;               *(float4*)((float*)(wsb + OFF_GLO) + (size_t)grow * 32 + 4 * lane) = make_float4(a.x * rs, a.y * rs, a.z * rs, a.w * rs);
;             }
.LBB0_1193:
	s_waitcnt lgkmcnt(0)
	ds_read_b128 v[128:131], v140 offset:12480
	s_or_b32 s8, s22, 12
	v_readlane_b32 s30, v163, 12
	s_and_b64 vcc, exec, s[4:5]
	s_mov_b64 s[34:35], -1
	s_cbranch_vccnz .LBB0_1197
	s_and_saveexec_b64 s[34:35], s[6:7]
	s_cbranch_execz .LBB0_1196
	s_ashr_i32 s9, s8, 31
	s_lshl_b64 s[66:67], s[8:9], 7
	v_lshl_add_u64 v[174:175], v[132:133], 0, s[66:67]
	s_waitcnt lgkmcnt(0)
	v_pk_mul_f32 v[164:165], s[30:31], v[128:129] op_sel_hi:[0,1]
	v_pk_mul_f32 v[166:167], s[30:31], v[130:131] op_sel_hi:[0,1]
	global_store_dwordx4 v[174:175], v[164:167], off

; template <int EPI, int TS, bool VT>
; DEVI void gemm_epilogue(const Params& p, char* smem, f32x4 (&acc)[2][2][4][2], int m0, int n0, float scale, const float* ssin,
;                         float* ssout, u16* xbout, int wid, int lane, int wr, int wc, int fr, int fq) {
;     ...
;           } else if constexpr (EPI == E_GLAIN) {
;             const float4 a = *(const float4*)(Tr + 4 * lane);
;             if (n0 < 3072) {
;               u16* O = (u16*)(wsb + (n0 < 512 ? OFF_QG : n0 < 1024 ? OFF_KG : OFF_RG));
;               const float f = n0 < 512 ? rs * 0.08838834764831845f : rs;
;               const int ld = n0 < 1024 ? 512 : 1024;
;               const int cc = n0 - (n0 < 512 ? 0 : n0 < 1024 ? 512 : 2048) + 4 * lane;
;               uint2 o;
;               o.x = pack2(a.x * f, a.y * f);
;               o.y = pack2(a.z * f, a.w * f);
;               st_nt8(O + (size_t)grow * ld + cc, o);
;             } else if (lane < 8) {
;               *(float4*)((float*)(wsb + OFF_GLO) + (size_t)grow * 32 + 4 * lane) = make_float4(a.x * rs, a.y * rs, a.z * rs, a.w * rs);
;             }
.LBB0_1199:
	s_waitcnt lgkmcnt(0)
	ds_read_b128 v[128:131], v140 offset:13520
	s_or_b32 s8, s22, 13
	v_readlane_b32 s30, v163, 13
	s_and_b64 vcc, exec, s[4:5]
	s_mov_b64 s[34:35], -1
	s_cbranch_vccnz .LBB0_1203
	s_and_saveexec_b64 s[34:35], s[6:7]
	s_cbranch_execz .LBB0_1202
	s_ashr_i32 s9, s8, 31
	s_lshl_b64 s[66:67], s[8:9], 7
	v_lshl_add_u64 v[174:175], v[132:133], 0, s[66:67]
	s_waitcnt lgkmcnt(0)
	v_pk_mul_f32 v[164:165], s[30:31], v[128:129] op_sel_hi:[0,1]
	v_pk_mul_f32 v[166:167], s[30:31], v[130:131] op_sel_hi:[0,1]
	global_store_dwordx4 v[174:175], v[164:167], off

; template <int EPI, int TS, bool VT>
; DEVI void gemm_epilogue(const Params& p, char* smem, f32x4 (&acc)[2][2][4][2], int m0, int n0, float scale, const float* ssin,
;                         float* ssout, u16* xbout, int wid, int lane, int wr, int wc, int fr, int fq) {
;     ...
;           } else if constexpr (EPI == E_GLAIN) {
;             const float4 a = *(const float4*)(Tr + 4 * lane);
;             if (n0 < 3072) {
;               u16* O = (u16*)(wsb + (n0 < 512 ? OFF_QG : n0 < 1024 ? OFF_KG : OFF_RG));
;               const float f = n0 < 512 ? rs * 0.08838834764831845f : rs;
;               const int ld = n0 < 1024 ? 512 : 1024;
;               const int cc = n0 - (n0 < 512 ? 0 : n0 < 1024 ? 512 : 2048) + 4 * lane;
;               uint2 o;
;               o.x = pack2(a.x * f, a.y * f);
;               o.y = pack2(a.z * f, a.w * f);
;               st_nt8(O + (size_t)grow * ld + cc, o);
;             } else if (lane < 8) {
;               *(float4*)((float*)(wsb + OFF_GLO) + (size_t)grow * 32 + 4 * lane) = make_float4(a.x * rs, a.y * rs, a.z * rs, a.w * rs);
;             }
.LBB0_1205:
	s_waitcnt lgkmcnt(0)
	ds_read_b128 v[128:131], v140 offset:14560
	s_or_b32 s8, s22, 14
	v_readlane_b32 s30, v163, 14
	s_and_b64 vcc, exec, s[4:5]
	s_mov_b64 s[34:35], -1
	s_cbranch_vccnz .LBB0_1209
	s_and_saveexec_b64 s[34:35], s[6:7]
	s_cbranch_execz .LBB0_1208
	s_ashr_i32 s9, s8, 31
	s_lshl_b64 s[66:67], s[8:9], 7
	v_lshl_add_u64 v[174:175], v[132:133], 0, s[66:67]
	s_waitcnt lgkmcnt(0)
	v_pk_mul_f32 v[164:165], s[30:31], v[128:129] op_sel_hi:[0,1]
	v_pk_mul_f32 v[166:167], s[30:31], v[130:131] op_sel_hi:[0,1]
	global_store_dwordx4 v[174:175], v[164:167], off

; template <int EPI, int TS, bool VT>
; DEVI void gemm_epilogue(const Params& p, char* smem, f32x4 (&acc)[2][2][4][2], int m0, int n0, float scale, const float* ssin,
;                         float* ssout, u16* xbout, int wid, int lane, int wr, int wc, int fr, int fq) {
;     ...
;           } else if constexpr (EPI == E_GLAIN) {
;             const float4 a = *(const float4*)(Tr + 4 * lane);
;             if (n0 < 3072) {
;               u16* O = (u16*)(wsb + (n0 < 512 ? OFF_QG : n0 < 1024 ? OFF_KG : OFF_RG));
;               const float f = n0 < 512 ? rs * 0.08838834764831845f : rs;
;               const int ld = n0 < 1024 ? 512 : 1024;
;               const int cc = n0 - (n0 < 512 ? 0 : n0 < 1024 ? 512 : 2048) + 4 * lane;
;               uint2 o;
;               o.x = pack2(a.x * f, a.y * f);
;               o.y = pack2(a.z * f, a.w * f);
;               st_nt8(O + (size_t)grow * ld + cc, o);
;             } else if (lane < 8) {
;               *(float4*)((float*)(wsb + OFF_GLO) + (size_t)grow * 32 + 4 * lane) = make_float4(a.x * rs, a.y * rs, a.z * rs, a.w * rs);
;             }
.LBB0_1211:
	s_waitcnt lgkmcnt(0)
	ds_read_b128 v[128:131], v140 offset:15600
	s_or_b32 s8, s22, 15
	v_readlane_b32 s30, v163, 15
	s_mov_b64 s[34:35], -1
	s_and_b64 vcc, exec, s[4:5]
	s_cbranch_vccnz .LBB0_1215
	s_and_saveexec_b64 s[34:35], s[6:7]
	s_cbranch_execz .LBB0_1214
	s_ashr_i32 s9, s8, 31
	s_lshl_b64 s[66:67], s[8:9], 7
	v_lshl_add_u64 v[174:175], v[132:133], 0, s[66:67]
	s_waitcnt lgkmcnt(0)
	v_pk_mul_f32 v[164:165], s[30:31], v[128:129] op_sel_hi:[0,1]
	v_pk_mul_f32 v[166:167], s[30:31], v[130:131] op_sel_hi:[0,1]
	global_store_dwordx4 v[174:175], v[164:167], off

; template <int EPI, int TS, bool VT>
; DEVI void gemm_epilogue(const Params& p, char* smem, f32x4 (&acc)[2][2][4][2], int m0, int n0, float scale, const float* ssin,
;                         float* ssout, u16* xbout, int wid, int lane, int wr, int wc, int fr, int fq) {
;     ...
;     {
;       float* tw = T + (wr * 64 + fq * 4) * TS + wc * 32 + fr;
; #pragma unroll
;       for (int m = 0; m < 4; ++m)
; #pragma unroll
;         for (int j = 0; j < 4; ++j)
; #pragma unroll
;           for (int v = 0; v < 4; ++v) tw[(m * 16 + j) * TS + (v >> 1) * 128 + (v & 1) * 16] = acc[ai][v >> 1][m][v & 1][j];
;     }
;     __syncthreads();
;     const int r0 = wid * 16;
;     const int g0 = m0 + ai * 128 + r0;
;     if constexpr (!VT) {
;       float rsv = 1.f;
;       if constexpr (EPI == E_PLEGATE || EPI == E_F32 || EPI == E_SWIGLU || EPI == E_GLAIN)
;         rsv = rsqrtf(ssin[g0 + (lane & 15)] * (1.f / 1024.f) + EPS);
;     ...
;           } else if constexpr (EPI == E_GLAIN) {
;             const float4 a = *(const float4*)(Tr + 4 * lane);
;             if (n0 < 3072) {
;               u16* O = (u16*)(wsb + (n0 < 512 ? OFF_QG : n0 < 1024 ? OFF_KG : OFF_RG));
;               const float f = n0 < 512 ? rs * 0.08838834764831845f : rs;
;               const int ld = n0 < 1024 ? 512 : 1024;
;               const int cc = n0 - (n0 < 512 ? 0 : n0 < 1024 ? 512 : 2048) + 4 * lane;
;               uint2 o;
;               o.x = pack2(a.x * f, a.y * f);
;               o.y = pack2(a.z * f, a.w * f);
;               st_nt8(O + (size_t)grow * ld + cc, o);
;             } else if (lane < 8) {
;               *(float4*)((float*)(wsb + OFF_GLO) + (size_t)grow * 32 + 4 * lane) = make_float4(a.x * rs, a.y * rs, a.z * rs, a.w * rs);
;             }
.LBB0_1215:
	s_andn2_b64 vcc, exec, s[34:35]
	s_cbranch_vccnz .LBB0_1217
	v_mul_f32_e32 v148, s30, v172
	v_mov_b32_e32 v163, s30
	v_cndmask_b32_e64 v148, v163, v148, s[0:1]
	s_ashr_i32 s9, s8, 31
	s_waitcnt lgkmcnt(0)
	v_pk_mul_f32 v[128:129], v[128:129], v[148:149] op_sel_hi:[1,0]
	v_pk_mul_f32 v[130:131], v[148:149], v[130:131] op_sel_hi:[0,1]
	s_lshl_b64 s[8:9], s[8:9], s21
	v_cvt_pk_bf16_f32 v128, v128, v129
	v_cvt_pk_bf16_f32 v129, v130, v131
	v_lshl_add_u64 v[130:131], s[8:9], 1, v[134:135]
	global_store_dwordx2 v[130:131], v[128:129], off
.LBB0_1217:
	s_add_i32 s30, s22, 0x80
	s_waitcnt lgkmcnt(0)
	v_or_b32_e32 v128, s30, v136
	v_ashrrev_i32_e32 v129, 31, v128
	v_lshl_add_u64 v[128:129], v[128:129], 2, s[16:17]
	s_barrier
	ds_write2_b32 v141, v24, v28 offset1:16
	ds_write2_b32 v141, v56, v60 offset0:128 offset1:144
	ds_write2_b32 v142, v25, v29 offset0:4 offset1:20
	ds_write2_b32 v142, v57, v61 offset0:132 offset1:148
	ds_write2_b32 v143, v26, v30 offset0:8 offset1:24
	ds_write2_b32 v143, v58, v62 offset0:136 offset1:152
	ds_write2_b32 v144, v27, v31 offset0:12 offset1:28
	ds_write2_b32 v144, v59, v63 offset0:140 offset1:156
	ds_write2_b32 v145, v16, v20 offset0:64 offset1:80
	ds_write2_b32 v145, v48, v52 offset0:192 offset1:208
	ds_write2_b32 v146, v17, v21 offset0:68 offset1:84
	ds_write2_b32 v146, v49, v53 offset0:196 offset1:212
	ds_write2_b32 v147, v18, v22 offset0:72 offset1:88
	ds_write2_b32 v147, v50, v54 offset0:200 offset1:216
	ds_write2_b32 v152, v19, v23 offset0:76 offset1:92
	ds_write2_b32 v152, v51, v55 offset0:204 offset1:220
	ds_write2_b32 v153, v8, v12 offset0:128 offset1:144
	ds_write2_b32 v154, v40, v44 offset1:16
	ds_write2_b32 v154, v9, v13 offset0:132 offset1:148
	ds_write2_b32 v155, v41, v45 offset0:4 offset1:20
	ds_write2_b32 v155, v10, v14 offset0:136 offset1:152
	ds_write2_b32 v156, v42, v46 offset0:8 offset1:24
	ds_write2_b32 v156, v11, v15 offset0:140 offset1:156
	ds_write2_b32 v157, v43, v47 offset0:12 offset1:28
	ds_write2_b32 v158, v0, v4 offset0:192 offset1:208
	ds_write2_b32 v159, v32, v36 offset0:64 offset1:80
	ds_write2_b32 v159, v1, v5 offset0:196 offset1:212
	ds_write2_b32 v160, v33, v37 offset0:68 offset1:84
	ds_write2_b32 v160, v2, v6 offset0:200 offset1:216
	ds_write2_b32 v161, v34, v38 offset0:72 offset1:88
	ds_write2_b32 v161, v3, v7 offset0:204 offset1:220
	ds_write2_b32 v162, v35, v39 offset0:76 offset1:92
	s_waitcnt lgkmcnt(0)
	s_barrier
	global_load_dword v128, v[128:129], off
	s_and_b64 vcc, exec, s[4:5]
	s_mov_b64 s[34:35], -1
	s_waitcnt vmcnt(0) lgkmcnt(0)
	v_fmamk_f32 v128, v128, 0x3a800000, v150
	v_mul_f32_e32 v129, 0x4b800000, v128
	v_cmp_gt_f32_e64 s[8:9], s29, v128
	s_nop 1
	v_cndmask_b32_e64 v128, v128, v129, s[8:9]
	v_rsq_f32_e32 v136, v128
	ds_read_b128 v[128:131], v140
	v_mul_f32_e32 v141, 0x45800000, v136
	v_cndmask_b32_e64 v136, v136, v141, s[8:9]
	s_nop 0
	v_readlane_b32 s8, v136, 0
	s_cbranch_vccnz .LBB0_1221
	s_and_saveexec_b64 s[34:35], s[6:7]
	s_cbranch_execz .LBB0_1220
	s_ashr_i32 s31, s30, 31
	s_lshl_b64 s[66:67], s[30:31], 7
	v_lshl_add_u64 v[146:147], v[132:133], 0, s[66:67]
	s_waitcnt lgkmcnt(0)
	v_pk_mul_f32 v[142:143], s[8:9], v[128:129] op_sel_hi:[0,1]
	v_pk_mul_f32 v[144:145], s[8:9], v[130:131] op_sel_hi:[0,1]
	global_store_dwordx4 v[146:147], v[142:145], off

; template <int EPI, int TS, bool VT>
; DEVI void gemm_epilogue(const Params& p, char* smem, f32x4 (&acc)[2][2][4][2], int m0, int n0, float scale, const float* ssin,
;                         float* ssout, u16* xbout, int wid, int lane, int wr, int wc, int fr, int fq) {
;     ...
;           } else if constexpr (EPI == E_GLAIN) {
;             const float4 a = *(const float4*)(Tr + 4 * lane);
;             if (n0 < 3072) {
;               u16* O = (u16*)(wsb + (n0 < 512 ? OFF_QG : n0 < 1024 ? OFF_KG : OFF_RG));
;               const float f = n0 < 512 ? rs * 0.08838834764831845f : rs;
;               const int ld = n0 < 1024 ? 512 : 1024;
;               const int cc = n0 - (n0 < 512 ? 0 : n0 < 1024 ? 512 : 2048) + 4 * lane;
;               uint2 o;
;               o.x = pack2(a.x * f, a.y * f);
;               o.y = pack2(a.z * f, a.w * f);
;               st_nt8(O + (size_t)grow * ld + cc, o);
;             } else if (lane < 8) {
;               *(float4*)((float*)(wsb + OFF_GLO) + (size_t)grow * 32 + 4 * lane) = make_float4(a.x * rs, a.y * rs, a.z * rs, a.w * rs);
;             }
.LBB0_1221:
	s_andn2_b64 vcc, exec, s[34:35]
	s_cbranch_vccnz .LBB0_1223
	v_mul_f32_e32 v141, s8, v172
	v_mov_b32_e32 v142, s8
	v_cndmask_b32_e64 v142, v142, v141, s[0:1]
	s_ashr_i32 s31, s30, 31
	s_waitcnt lgkmcnt(0)
	v_pk_mul_f32 v[128:129], v[128:129], v[142:143] op_sel_hi:[1,0]
	v_pk_mul_f32 v[130:131], v[142:143], v[130:131] op_sel_hi:[0,1]
	s_lshl_b64 s[8:9], s[30:31], s21
	v_cvt_pk_bf16_f32 v128, v128, v129
	v_cvt_pk_bf16_f32 v129, v130, v131
	v_lshl_add_u64 v[130:131], s[8:9], 1, v[134:135]
	global_store_dwordx2 v[130:131], v[128:129], off
.LBB0_1223:
	s_waitcnt lgkmcnt(0)
	ds_read_b128 v[128:131], v140 offset:1040
	s_add_i32 s8, s22, 0x81
	v_readlane_b32 s30, v136, 1
	s_and_b64 vcc, exec, s[4:5]
	s_mov_b64 s[34:35], -1
	s_cbranch_vccnz .LBB0_1227
	s_and_saveexec_b64 s[34:35], s[6:7]
	s_cbranch_execz .LBB0_1226
	s_ashr_i32 s9, s8, 31
	s_lshl_b64 s[66:67], s[8:9], 7
	v_lshl_add_u64 v[146:147], v[132:133], 0, s[66:67]
	s_waitcnt lgkmcnt(0)
	v_pk_mul_f32 v[142:143], s[30:31], v[128:129] op_sel_hi:[0,1]
	v_pk_mul_f32 v[144:145], s[30:31], v[130:131] op_sel_hi:[0,1]
	global_store_dwordx4 v[146:147], v[142:145], off

; template <int EPI, int TS, bool VT>
; DEVI void gemm_epilogue(const Params& p, char* smem, f32x4 (&acc)[2][2][4][2], int m0, int n0, float scale, const float* ssin,
;                         float* ssout, u16* xbout, int wid, int lane, int wr, int wc, int fr, int fq) {
;     ...
;           } else if constexpr (EPI == E_GLAIN) {
;             const float4 a = *(const float4*)(Tr + 4 * lane);
;             if (n0 < 3072) {
;               u16* O = (u16*)(wsb + (n0 < 512 ? OFF_QG : n0 < 1024 ? OFF_KG : OFF_RG));
;               const float f = n0 < 512 ? rs * 0.08838834764831845f : rs;
;               const int ld = n0 < 1024 ? 512 : 1024;
;               const int cc = n0 - (n0 < 512 ? 0 : n0 < 1024 ? 512 : 2048) + 4 * lane;
;               uint2 o;
;               o.x = pack2(a.x * f, a.y * f);
;               o.y = pack2(a.z * f, a.w * f);
;               st_nt8(O + (size_t)grow * ld + cc, o);
;             } else if (lane < 8) {
;               *(float4*)((float*)(wsb + OFF_GLO) + (size_t)grow * 32 + 4 * lane) = make_float4(a.x * rs, a.y * rs, a.z * rs, a.w * rs);
;             }
.LBB0_1227:
	s_andn2_b64 vcc, exec, s[34:35]
	s_cbranch_vccnz .LBB0_1229
	v_mul_f32_e32 v141, s30, v172
	v_mov_b32_e32 v142, s30
	v_cndmask_b32_e64 v142, v142, v141, s[0:1]
	s_ashr_i32 s9, s8, 31
	s_waitcnt lgkmcnt(0)
	v_pk_mul_f32 v[128:129], v[128:129], v[142:143] op_sel_hi:[1,0]
	v_pk_mul_f32 v[130:131], v[142:143], v[130:131] op_sel_hi:[0,1]
	s_lshl_b64 s[8:9], s[8:9], s21
	v_cvt_pk_bf16_f32 v128, v128, v129
	v_cvt_pk_bf16_f32 v129, v130, v131
	v_lshl_add_u64 v[130:131], s[8:9], 1, v[134:135]
	global_store_dwordx2 v[130:131], v[128:129], off
.LBB0_1229:
	s_waitcnt lgkmcnt(0)
	ds_read_b128 v[128:131], v140 offset:2080
	s_add_i32 s8, s22, 0x82
	v_readlane_b32 s30, v136, 2
	s_and_b64 vcc, exec, s[4:5]
	s_mov_b64 s[34:35], -1
	s_cbranch_vccnz .LBB0_1233
	s_and_saveexec_b64 s[34:35], s[6:7]
	s_cbranch_execz .LBB0_1232
	s_ashr_i32 s9, s8, 31
	s_lshl_b64 s[66:67], s[8:9], 7
	v_lshl_add_u64 v[146:147], v[132:133], 0, s[66:67]
	s_waitcnt lgkmcnt(0)
	v_pk_mul_f32 v[142:143], s[30:31], v[128:129] op_sel_hi:[0,1]
	v_pk_mul_f32 v[144:145], s[30:31], v[130:131] op_sel_hi:[0,1]
	global_store_dwordx4 v[146:147], v[142:145], off

; template <int EPI, int TS, bool VT>
; DEVI void gemm_epilogue(const Params& p, char* smem, f32x4 (&acc)[2][2][4][2], int m0, int n0, float scale, const float* ssin,
;                         float* ssout, u16* xbout, int wid, int lane, int wr, int wc, int fr, int fq) {
;     ...
;           } else if constexpr (EPI == E_GLAIN) {
;             const float4 a = *(const float4*)(Tr + 4 * lane);
;             if (n0 < 3072) {
;               u16* O = (u16*)(wsb + (n0 < 512 ? OFF_QG : n0 < 1024 ? OFF_KG : OFF_RG));
;               const float f = n0 < 512 ? rs * 0.08838834764831845f : rs;
;               const int ld = n0 < 1024 ? 512 : 1024;
;               const int cc = n0 - (n0 < 512 ? 0 : n0 < 1024 ? 512 : 2048) + 4 * lane;
;               uint2 o;
;               o.x = pack2(a.x * f, a.y * f);
;               o.y = pack2(a.z * f, a.w * f);
;               st_nt8(O + (size_t)grow * ld + cc, o);
;             } else if (lane < 8) {
;               *(float4*)((float*)(wsb + OFF_GLO) + (size_t)grow * 32 + 4 * lane) = make_float4(a.x * rs, a.y * rs, a.z * rs, a.w * rs);
;             }
.LBB0_1235:
	s_waitcnt lgkmcnt(0)
	ds_read_b128 v[128:131], v140 offset:3120
	s_add_i32 s8, s22, 0x83
	v_readlane_b32 s30, v136, 3
	s_and_b64 vcc, exec, s[4:5]
	s_mov_b64 s[34:35], -1
	s_cbranch_vccnz .LBB0_1239
	s_and_saveexec_b64 s[34:35], s[6:7]
	s_cbranch_execz .LBB0_1238
	s_ashr_i32 s9, s8, 31
	s_lshl_b64 s[66:67], s[8:9], 7
	v_lshl_add_u64 v[146:147], v[132:133], 0, s[66:67]
	s_waitcnt lgkmcnt(0)
	v_pk_mul_f32 v[142:143], s[30:31], v[128:129] op_sel_hi:[0,1]
	v_pk_mul_f32 v[144:145], s[30:31], v[130:131] op_sel_hi:[0,1]
	global_store_dwordx4 v[146:147], v[142:145], off

; template <int EPI, int TS, bool VT>
; DEVI void gemm_epilogue(const Params& p, char* smem, f32x4 (&acc)[2][2][4][2], int m0, int n0, float scale, const float* ssin,
;                         float* ssout, u16* xbout, int wid, int lane, int wr, int wc, int fr, int fq) {
;     ...
;           } else if constexpr (EPI == E_GLAIN) {
;             const float4 a = *(const float4*)(Tr + 4 * lane);
;             if (n0 < 3072) {
;               u16* O = (u16*)(wsb + (n0 < 512 ? OFF_QG : n0 < 1024 ? OFF_KG : OFF_RG));
;               const float f = n0 < 512 ? rs * 0.08838834764831845f : rs;
;               const int ld = n0 < 1024 ? 512 : 1024;
;               const int cc = n0 - (n0 < 512 ? 0 : n0 < 1024 ? 512 : 2048) + 4 * lane;
;               uint2 o;
;               o.x = pack2(a.x * f, a.y * f);
;               o.y = pack2(a.z * f, a.w * f);
;               st_nt8(O + (size_t)grow * ld + cc, o);
;             } else if (lane < 8) {
;               *(float4*)((float*)(wsb + OFF_GLO) + (size_t)grow * 32 + 4 * lane) = make_float4(a.x * rs, a.y * rs, a.z * rs, a.w * rs);
;             }
.LBB0_1241:
	s_waitcnt lgkmcnt(0)
	ds_read_b128 v[128:131], v140 offset:4160
	s_add_i32 s8, s22, 0x84
	v_readlane_b32 s30, v136, 4
	s_and_b64 vcc, exec, s[4:5]
	s_mov_b64 s[34:35], -1
	s_cbranch_vccnz .LBB0_1245
	s_and_saveexec_b64 s[34:35], s[6:7]
	s_cbranch_execz .LBB0_1244
	s_ashr_i32 s9, s8, 31
	s_lshl_b64 s[66:67], s[8:9], 7
	v_lshl_add_u64 v[146:147], v[132:133], 0, s[66:67]
	s_waitcnt lgkmcnt(0)
	v_pk_mul_f32 v[142:143], s[30:31], v[128:129] op_sel_hi:[0,1]
	v_pk_mul_f32 v[144:145], s[30:31], v[130:131] op_sel_hi:[0,1]
	global_store_dwordx4 v[146:147], v[142:145], off

; template <int EPI, int TS, bool VT>
; DEVI void gemm_epilogue(const Params& p, char* smem, f32x4 (&acc)[2][2][4][2], int m0, int n0, float scale, const float* ssin,
;                         float* ssout, u16* xbout, int wid, int lane, int wr, int wc, int fr, int fq) {
;     ...
;           } else if constexpr (EPI == E_GLAIN) {
;             const float4 a = *(const float4*)(Tr + 4 * lane);
;             if (n0 < 3072) {
;               u16* O = (u16*)(wsb + (n0 < 512 ? OFF_QG : n0 < 1024 ? OFF_KG : OFF_RG));
;               const float f = n0 < 512 ? rs * 0.08838834764831845f : rs;
;               const int ld = n0 < 1024 ? 512 : 1024;
;               const int cc = n0 - (n0 < 512 ? 0 : n0 < 1024 ? 512 : 2048) + 4 * lane;
;               uint2 o;
;               o.x = pack2(a.x * f, a.y * f);
;               o.y = pack2(a.z * f, a.w * f);
;               st_nt8(O + (size_t)grow * ld + cc, o);
;             } else if (lane < 8) {
;               *(float4*)((float*)(wsb + OFF_GLO) + (size_t)grow * 32 + 4 * lane) = make_float4(a.x * rs, a.y * rs, a.z * rs, a.w * rs);
;             }
.LBB0_1247:
	s_waitcnt lgkmcnt(0)
	ds_read_b128 v[128:131], v140 offset:5200
	s_add_i32 s8, s22, 0x85
	v_readlane_b32 s30, v136, 5
	s_and_b64 vcc, exec, s[4:5]
	s_mov_b64 s[34:35], -1
	s_cbranch_vccnz .LBB0_1251
	s_and_saveexec_b64 s[34:35], s[6:7]
	s_cbranch_execz .LBB0_1250
	s_ashr_i32 s9, s8, 31
	s_lshl_b64 s[66:67], s[8:9], 7
	v_lshl_add_u64 v[146:147], v[132:133], 0, s[66:67]
	s_waitcnt lgkmcnt(0)
	v_pk_mul_f32 v[142:143], s[30:31], v[128:129] op_sel_hi:[0,1]
	v_pk_mul_f32 v[144:145], s[30:31], v[130:131] op_sel_hi:[0,1]
	global_store_dwordx4 v[146:147], v[142:145], off

; template <int EPI, int TS, bool VT>
; DEVI void gemm_epilogue(const Params& p, char* smem, f32x4 (&acc)[2][2][4][2], int m0, int n0, float scale, const float* ssin,
;                         float* ssout, u16* xbout, int wid, int lane, int wr, int wc, int fr, int fq) {
;     ...
;           } else if constexpr (EPI == E_GLAIN) {
;             const float4 a = *(const float4*)(Tr + 4 * lane);
;             if (n0 < 3072) {
;               u16* O = (u16*)(wsb + (n0 < 512 ? OFF_QG : n0 < 1024 ? OFF_KG : OFF_RG));
;               const float f = n0 < 512 ? rs * 0.08838834764831845f : rs;
;               const int ld = n0 < 1024 ? 512 : 1024;
;               const int cc = n0 - (n0 < 512 ? 0 : n0 < 1024 ? 512 : 2048) + 4 * lane;
;               uint2 o;
;               o.x = pack2(a.x * f, a.y * f);
;               o.y = pack2(a.z * f, a.w * f);
;               st_nt8(O + (size_t)grow * ld + cc, o);
;             } else if (lane < 8) {
;               *(float4*)((float*)(wsb + OFF_GLO) + (size_t)grow * 32 + 4 * lane) = make_float4(a.x * rs, a.y * rs, a.z * rs, a.w * rs);
;             }
.LBB0_1253:
	s_waitcnt lgkmcnt(0)
	ds_read_b128 v[128:131], v140 offset:6240
	s_add_i32 s8, s22, 0x86
	v_readlane_b32 s30, v136, 6
	s_and_b64 vcc, exec, s[4:5]
	s_mov_b64 s[34:35], -1
	s_cbranch_vccnz .LBB0_1257
	s_and_saveexec_b64 s[34:35], s[6:7]
	s_cbranch_execz .LBB0_1256
	s_ashr_i32 s9, s8, 31
	s_lshl_b64 s[66:67], s[8:9], 7
	v_lshl_add_u64 v[146:147], v[132:133], 0, s[66:67]
	s_waitcnt lgkmcnt(0)
	v_pk_mul_f32 v[142:143], s[30:31], v[128:129] op_sel_hi:[0,1]
	v_pk_mul_f32 v[144:145], s[30:31], v[130:131] op_sel_hi:[0,1]
	global_store_dwordx4 v[146:147], v[142:145], off

; template <int EPI, int TS, bool VT>
; DEVI void gemm_epilogue(const Params& p, char* smem, f32x4 (&acc)[2][2][4][2], int m0, int n0, float scale, const float* ssin,
;                         float* ssout, u16* xbout, int wid, int lane, int wr, int wc, int fr, int fq) {
;     ...
;           } else if constexpr (EPI == E_GLAIN) {
;             const float4 a = *(const float4*)(Tr + 4 * lane);
;             if (n0 < 3072) {
;               u16* O = (u16*)(wsb + (n0 < 512 ? OFF_QG : n0 < 1024 ? OFF_KG : OFF_RG));
;               const float f = n0 < 512 ? rs * 0.08838834764831845f : rs;
;               const int ld = n0 < 1024 ? 512 : 1024;
;               const int cc = n0 - (n0 < 512 ? 0 : n0 < 1024 ? 512 : 2048) + 4 * lane;
;               uint2 o;
;               o.x = pack2(a.x * f, a.y * f);
;               o.y = pack2(a.z * f, a.w * f);
;               st_nt8(O + (size_t)grow * ld + cc, o);
;             } else if (lane < 8) {
;               *(float4*)((float*)(wsb + OFF_GLO) + (size_t)grow * 32 + 4 * lane) = make_float4(a.x * rs, a.y * rs, a.z * rs, a.w * rs);
;             }
.LBB0_1259:
	s_waitcnt lgkmcnt(0)
	ds_read_b128 v[128:131], v140 offset:7280
	s_add_i32 s8, s22, 0x87
	v_readlane_b32 s30, v136, 7
	s_and_b64 vcc, exec, s[4:5]
	s_mov_b64 s[34:35], -1
	s_cbranch_vccnz .LBB0_1263
	s_and_saveexec_b64 s[34:35], s[6:7]
	s_cbranch_execz .LBB0_1262
	s_ashr_i32 s9, s8, 31
	s_lshl_b64 s[66:67], s[8:9], 7
	v_lshl_add_u64 v[146:147], v[132:133], 0, s[66:67]
	s_waitcnt lgkmcnt(0)
	v_pk_mul_f32 v[142:143], s[30:31], v[128:129] op_sel_hi:[0,1]
	v_pk_mul_f32 v[144:145], s[30:31], v[130:131] op_sel_hi:[0,1]
	global_store_dwordx4 v[146:147], v[142:145], off

; template <int EPI, int TS, bool VT>
; DEVI void gemm_epilogue(const Params& p, char* smem, f32x4 (&acc)[2][2][4][2], int m0, int n0, float scale, const float* ssin,
;                         float* ssout, u16* xbout, int wid, int lane, int wr, int wc, int fr, int fq) {
;     ...
;           } else if constexpr (EPI == E_GLAIN) {
;             const float4 a = *(const float4*)(Tr + 4 * lane);
;             if (n0 < 3072) {
;               u16* O = (u16*)(wsb + (n0 < 512 ? OFF_QG : n0 < 1024 ? OFF_KG : OFF_RG));
;               const float f = n0 < 512 ? rs * 0.08838834764831845f : rs;
;               const int ld = n0 < 1024 ? 512 : 1024;
;               const int cc = n0 - (n0 < 512 ? 0 : n0 < 1024 ? 512 : 2048) + 4 * lane;
;               uint2 o;
;               o.x = pack2(a.x * f, a.y * f);
;               o.y = pack2(a.z * f, a.w * f);
;               st_nt8(O + (size_t)grow * ld + cc, o);
;             } else if (lane < 8) {
;               *(float4*)((float*)(wsb + OFF_GLO) + (size_t)grow * 32 + 4 * lane) = make_float4(a.x * rs, a.y * rs, a.z * rs, a.w * rs);
;             }
.LBB0_1265:
	s_waitcnt lgkmcnt(0)
	ds_read_b128 v[128:131], v140 offset:8320
	s_add_i32 s8, s22, 0x88
	v_readlane_b32 s30, v136, 8
	s_and_b64 vcc, exec, s[4:5]
	s_mov_b64 s[34:35], -1
	s_cbranch_vccnz .LBB0_1269
	s_and_saveexec_b64 s[34:35], s[6:7]
	s_cbranch_execz .LBB0_1268
	s_ashr_i32 s9, s8, 31
	s_lshl_b64 s[66:67], s[8:9], 7
	v_lshl_add_u64 v[146:147], v[132:133], 0, s[66:67]
	s_waitcnt lgkmcnt(0)
	v_pk_mul_f32 v[142:143], s[30:31], v[128:129] op_sel_hi:[0,1]
	v_pk_mul_f32 v[144:145], s[30:31], v[130:131] op_sel_hi:[0,1]
	global_store_dwordx4 v[146:147], v[142:145], off

; template <int EPI, int TS, bool VT>
; DEVI void gemm_epilogue(const Params& p, char* smem, f32x4 (&acc)[2][2][4][2], int m0, int n0, float scale, const float* ssin,
;                         float* ssout, u16* xbout, int wid, int lane, int wr, int wc, int fr, int fq) {
;     ...
;           } else if constexpr (EPI == E_GLAIN) {
;             const float4 a = *(const float4*)(Tr + 4 * lane);
;             if (n0 < 3072) {
;               u16* O = (u16*)(wsb + (n0 < 512 ? OFF_QG : n0 < 1024 ? OFF_KG : OFF_RG));
;               const float f = n0 < 512 ? rs * 0.08838834764831845f : rs;
;               const int ld = n0 < 1024 ? 512 : 1024;
;               const int cc = n0 - (n0 < 512 ? 0 : n0 < 1024 ? 512 : 2048) + 4 * lane;
;               uint2 o;
;               o.x = pack2(a.x * f, a.y * f);
;               o.y = pack2(a.z * f, a.w * f);
;               st_nt8(O + (size_t)grow * ld + cc, o);
;             } else if (lane < 8) {
;               *(float4*)((float*)(wsb + OFF_GLO) + (size_t)grow * 32 + 4 * lane) = make_float4(a.x * rs, a.y * rs, a.z * rs, a.w * rs);
;             }
.LBB0_1271:
	s_waitcnt lgkmcnt(0)
	ds_read_b128 v[128:131], v140 offset:9360
	s_add_i32 s8, s22, 0x89
	v_readlane_b32 s30, v136, 9
	s_and_b64 vcc, exec, s[4:5]
	s_mov_b64 s[34:35], -1
	s_cbranch_vccnz .LBB0_1275
	s_and_saveexec_b64 s[34:35], s[6:7]
	s_cbranch_execz .LBB0_1274
	s_ashr_i32 s9, s8, 31
	s_lshl_b64 s[66:67], s[8:9], 7
	v_lshl_add_u64 v[146:147], v[132:133], 0, s[66:67]
	s_waitcnt lgkmcnt(0)
	v_pk_mul_f32 v[142:143], s[30:31], v[128:129] op_sel_hi:[0,1]
	v_pk_mul_f32 v[144:145], s[30:31], v[130:131] op_sel_hi:[0,1]
	global_store_dwordx4 v[146:147], v[142:145], off

; template <int EPI, int TS, bool VT>
; DEVI void gemm_epilogue(const Params& p, char* smem, f32x4 (&acc)[2][2][4][2], int m0, int n0, float scale, const float* ssin,
;                         float* ssout, u16* xbout, int wid, int lane, int wr, int wc, int fr, int fq) {
;     ...
;           } else if constexpr (EPI == E_GLAIN) {
;             const float4 a = *(const float4*)(Tr + 4 * lane);
;             if (n0 < 3072) {
;               u16* O = (u16*)(wsb + (n0 < 512 ? OFF_QG : n0 < 1024 ? OFF_KG : OFF_RG));
;               const float f = n0 < 512 ? rs * 0.08838834764831845f : rs;
;               const int ld = n0 < 1024 ? 512 : 1024;
;               const int cc = n0 - (n0 < 512 ? 0 : n0 < 1024 ? 512 : 2048) + 4 * lane;
;               uint2 o;
;               o.x = pack2(a.x * f, a.y * f);
;               o.y = pack2(a.z * f, a.w * f);
;               st_nt8(O + (size_t)grow * ld + cc, o);
;             } else if (lane < 8) {
;               *(float4*)((float*)(wsb + OFF_GLO) + (size_t)grow * 32 + 4 * lane) = make_float4(a.x * rs, a.y * rs, a.z * rs, a.w * rs);
;             }
.LBB0_1277:
	s_waitcnt lgkmcnt(0)
	ds_read_b128 v[128:131], v140 offset:10400
	s_add_i32 s8, s22, 0x8a
	v_readlane_b32 s30, v136, 10
	s_and_b64 vcc, exec, s[4:5]
	s_mov_b64 s[34:35], -1
	s_cbranch_vccnz .LBB0_1281
	s_and_saveexec_b64 s[34:35], s[6:7]
	s_cbranch_execz .LBB0_1280
	s_ashr_i32 s9, s8, 31
	s_lshl_b64 s[66:67], s[8:9], 7
	v_lshl_add_u64 v[146:147], v[132:133], 0, s[66:67]
	s_waitcnt lgkmcnt(0)
	v_pk_mul_f32 v[142:143], s[30:31], v[128:129] op_sel_hi:[0,1]
	v_pk_mul_f32 v[144:145], s[30:31], v[130:131] op_sel_hi:[0,1]
	global_store_dwordx4 v[146:147], v[142:145], off

; template <int EPI, int TS, bool VT>
; DEVI void gemm_epilogue(const Params& p, char* smem, f32x4 (&acc)[2][2][4][2], int m0, int n0, float scale, const float* ssin,
;                         float* ssout, u16* xbout, int wid, int lane, int wr, int wc, int fr, int fq) {
;     ...
;           } else if constexpr (EPI == E_GLAIN) {
;             const float4 a = *(const float4*)(Tr + 4 * lane);
;             if (n0 < 3072) {
;               u16* O = (u16*)(wsb + (n0 < 512 ? OFF_QG : n0 < 1024 ? OFF_KG : OFF_RG));
;               const float f = n0 < 512 ? rs * 0.08838834764831845f : rs;
;               const int ld = n0 < 1024 ? 512 : 1024;
;               const int cc = n0 - (n0 < 512 ? 0 : n0 < 1024 ? 512 : 2048) + 4 * lane;
;               uint2 o;
;               o.x = pack2(a.x * f, a.y * f);
;               o.y = pack2(a.z * f, a.w * f);
;               st_nt8(O + (size_t)grow * ld + cc, o);
;             } else if (lane < 8) {
;               *(float4*)((float*)(wsb + OFF_GLO) + (size_t)grow * 32 + 4 * lane) = make_float4(a.x * rs, a.y * rs, a.z * rs, a.w * rs);
;             }
.LBB0_1283:
	s_waitcnt lgkmcnt(0)
	ds_read_b128 v[128:131], v140 offset:11440
	s_add_i32 s8, s22, 0x8b
	v_readlane_b32 s30, v136, 11
	s_and_b64 vcc, exec, s[4:5]
	s_mov_b64 s[34:35], -1
	s_cbranch_vccnz .LBB0_1287
	s_and_saveexec_b64 s[34:35], s[6:7]
	s_cbranch_execz .LBB0_1286
	s_ashr_i32 s9, s8, 31
	s_lshl_b64 s[66:67], s[8:9], 7
	v_lshl_add_u64 v[146:147], v[132:133], 0, s[66:67]
	s_waitcnt lgkmcnt(0)
	v_pk_mul_f32 v[142:143], s[30:31], v[128:129] op_sel_hi:[0,1]
	v_pk_mul_f32 v[144:145], s[30:31], v[130:131] op_sel_hi:[0,1]
	global_store_dwordx4 v[146:147], v[142:145], off

; template <int EPI, int TS, bool VT>
; DEVI void gemm_epilogue(const Params& p, char* smem, f32x4 (&acc)[2][2][4][2], int m0, int n0, float scale, const float* ssin,
;                         float* ssout, u16* xbout, int wid, int lane, int wr, int wc, int fr, int fq) {
;     ...
;           } else if constexpr (EPI == E_GLAIN) {
;             const float4 a = *(const float4*)(Tr + 4 * lane);
;             if (n0 < 3072) {
;               u16* O = (u16*)(wsb + (n0 < 512 ? OFF_QG : n0 < 1024 ? OFF_KG : OFF_RG));
;               const float f = n0 < 512 ? rs * 0.08838834764831845f : rs;
;               const int ld = n0 < 1024 ? 512 : 1024;
;               const int cc = n0 - (n0 < 512 ? 0 : n0 < 1024 ? 512 : 2048) + 4 * lane;
;               uint2 o;
;               o.x = pack2(a.x * f, a.y * f);
;               o.y = pack2(a.z * f, a.w * f);
;               st_nt8(O + (size_t)grow * ld + cc, o);
;             } else if (lane < 8) {
;               *(float4*)((float*)(wsb + OFF_GLO) + (size_t)grow * 32 + 4 * lane) = make_float4(a.x * rs, a.y * rs, a.z * rs, a.w * rs);
;             }
.LBB0_1289:
	s_waitcnt lgkmcnt(0)
	ds_read_b128 v[128:131], v140 offset:12480
	s_add_i32 s8, s22, 0x8c
	v_readlane_b32 s30, v136, 12
	s_and_b64 vcc, exec, s[4:5]
	s_mov_b64 s[34:35], -1
	s_cbranch_vccnz .LBB0_1293
	s_and_saveexec_b64 s[34:35], s[6:7]
	s_cbranch_execz .LBB0_1292
	s_ashr_i32 s9, s8, 31
	s_lshl_b64 s[66:67], s[8:9], 7
	v_lshl_add_u64 v[146:147], v[132:133], 0, s[66:67]
	s_waitcnt lgkmcnt(0)
	v_pk_mul_f32 v[142:143], s[30:31], v[128:129] op_sel_hi:[0,1]
	v_pk_mul_f32 v[144:145], s[30:31], v[130:131] op_sel_hi:[0,1]
	global_store_dwordx4 v[146:147], v[142:145], off

; template <int EPI, int TS, bool VT>
; DEVI void gemm_epilogue(const Params& p, char* smem, f32x4 (&acc)[2][2][4][2], int m0, int n0, float scale, const float* ssin,
;                         float* ssout, u16* xbout, int wid, int lane, int wr, int wc, int fr, int fq) {
;     ...
;           } else if constexpr (EPI == E_GLAIN) {
;             const float4 a = *(const float4*)(Tr + 4 * lane);
;             if (n0 < 3072) {
;               u16* O = (u16*)(wsb + (n0 < 512 ? OFF_QG : n0 < 1024 ? OFF_KG : OFF_RG));
;               const float f = n0 < 512 ? rs * 0.08838834764831845f : rs;
;               const int ld = n0 < 1024 ? 512 : 1024;
;               const int cc = n0 - (n0 < 512 ? 0 : n0 < 1024 ? 512 : 2048) + 4 * lane;
;               uint2 o;
;               o.x = pack2(a.x * f, a.y * f);
;               o.y = pack2(a.z * f, a.w * f);
;               st_nt8(O + (size_t)grow * ld + cc, o);
;             } else if (lane < 8) {
;               *(float4*)((float*)(wsb + OFF_GLO) + (size_t)grow * 32 + 4 * lane) = make_float4(a.x * rs, a.y * rs, a.z * rs, a.w * rs);
;             }
.LBB0_1295:
	s_waitcnt lgkmcnt(0)
	ds_read_b128 v[128:131], v140 offset:13520
	s_add_i32 s8, s22, 0x8d
	v_readlane_b32 s30, v136, 13
	s_and_b64 vcc, exec, s[4:5]
	s_mov_b64 s[34:35], -1
	s_cbranch_vccnz .LBB0_1299
	s_and_saveexec_b64 s[34:35], s[6:7]
	s_cbranch_execz .LBB0_1298
	s_ashr_i32 s9, s8, 31
	s_lshl_b64 s[66:67], s[8:9], 7
	v_lshl_add_u64 v[146:147], v[132:133], 0, s[66:67]
	s_waitcnt lgkmcnt(0)
	v_pk_mul_f32 v[142:143], s[30:31], v[128:129] op_sel_hi:[0,1]
	v_pk_mul_f32 v[144:145], s[30:31], v[130:131] op_sel_hi:[0,1]
	global_store_dwordx4 v[146:147], v[142:145], off

; template <int EPI, int TS, bool VT>
; DEVI void gemm_epilogue(const Params& p, char* smem, f32x4 (&acc)[2][2][4][2], int m0, int n0, float scale, const float* ssin,
;                         float* ssout, u16* xbout, int wid, int lane, int wr, int wc, int fr, int fq) {
;     ...
;           } else if constexpr (EPI == E_GLAIN) {
;             const float4 a = *(const float4*)(Tr + 4 * lane);
;             if (n0 < 3072) {
;               u16* O = (u16*)(wsb + (n0 < 512 ? OFF_QG : n0 < 1024 ? OFF_KG : OFF_RG));
;               const float f = n0 < 512 ? rs * 0.08838834764831845f : rs;
;               const int ld = n0 < 1024 ? 512 : 1024;
;               const int cc = n0 - (n0 < 512 ? 0 : n0 < 1024 ? 512 : 2048) + 4 * lane;
;               uint2 o;
;               o.x = pack2(a.x * f, a.y * f);
;               o.y = pack2(a.z * f, a.w * f);
;               st_nt8(O + (size_t)grow * ld + cc, o);
;             } else if (lane < 8) {
;               *(float4*)((float*)(wsb + OFF_GLO) + (size_t)grow * 32 + 4 * lane) = make_float4(a.x * rs, a.y * rs, a.z * rs, a.w * rs);
;             }
.LBB0_1301:
	s_waitcnt lgkmcnt(0)
	ds_read_b128 v[128:131], v140 offset:14560
	s_add_i32 s8, s22, 0x8e
	v_readlane_b32 s30, v136, 14
	s_and_b64 vcc, exec, s[4:5]
	s_mov_b64 s[34:35], -1
	s_cbranch_vccnz .LBB0_1305
	s_and_saveexec_b64 s[34:35], s[6:7]
	s_cbranch_execz .LBB0_1304
	s_ashr_i32 s9, s8, 31
	s_lshl_b64 s[66:67], s[8:9], 7
	v_lshl_add_u64 v[146:147], v[132:133], 0, s[66:67]
	s_waitcnt lgkmcnt(0)
	v_pk_mul_f32 v[142:143], s[30:31], v[128:129] op_sel_hi:[0,1]
	v_pk_mul_f32 v[144:145], s[30:31], v[130:131] op_sel_hi:[0,1]
	global_store_dwordx4 v[146:147], v[142:145], off

; template <int EPI, int TS, bool VT>
; DEVI void gemm_epilogue(const Params& p, char* smem, f32x4 (&acc)[2][2][4][2], int m0, int n0, float scale, const float* ssin,
;                         float* ssout, u16* xbout, int wid, int lane, int wr, int wc, int fr, int fq) {
;     ...
;           } else if constexpr (EPI == E_GLAIN) {
;             const float4 a = *(const float4*)(Tr + 4 * lane);
;             if (n0 < 3072) {
;               u16* O = (u16*)(wsb + (n0 < 512 ? OFF_QG : n0 < 1024 ? OFF_KG : OFF_RG));
;               const float f = n0 < 512 ? rs * 0.08838834764831845f : rs;
;               const int ld = n0 < 1024 ? 512 : 1024;
;               const int cc = n0 - (n0 < 512 ? 0 : n0 < 1024 ? 512 : 2048) + 4 * lane;
;               uint2 o;
;               o.x = pack2(a.x * f, a.y * f);
;               o.y = pack2(a.z * f, a.w * f);
;               st_nt8(O + (size_t)grow * ld + cc, o);
;             } else if (lane < 8) {
;               *(float4*)((float*)(wsb + OFF_GLO) + (size_t)grow * 32 + 4 * lane) = make_float4(a.x * rs, a.y * rs, a.z * rs, a.w * rs);
;             }
.LBB0_1307:
	s_waitcnt lgkmcnt(0)
	ds_read_b128 v[128:131], v140 offset:15600
	s_add_i32 s8, s22, 0x8f
	v_readlane_b32 s22, v136, 15
	s_and_b64 vcc, exec, s[4:5]
	s_mov_b64 s[4:5], -1
	s_cbranch_vccnz .LBB0_1311
	s_and_saveexec_b64 s[4:5], s[6:7]
	s_cbranch_execz .LBB0_1310
	s_ashr_i32 s9, s8, 31
	s_lshl_b64 s[6:7], s[8:9], 7
	v_lshl_add_u64 v[132:133], v[132:133], 0, s[6:7]
	s_waitcnt lgkmcnt(0)
	v_pk_mul_f32 v[140:141], s[22:23], v[128:129] op_sel_hi:[0,1]
	v_pk_mul_f32 v[142:143], s[22:23], v[130:131] op_sel_hi:[0,1]
	global_store_dwordx4 v[132:133], v[140:143], off

; template <int EPI, int TS, bool VT>
; DEVI void gemm_epilogue(const Params& p, char* smem, f32x4 (&acc)[2][2][4][2], int m0, int n0, float scale, const float* ssin,
;                         float* ssout, u16* xbout, int wid, int lane, int wr, int wc, int fr, int fq) {
;     ...
;           } else if constexpr (EPI == E_GLAIN) {
;             const float4 a = *(const float4*)(Tr + 4 * lane);
;             if (n0 < 3072) {
;               u16* O = (u16*)(wsb + (n0 < 512 ? OFF_QG : n0 < 1024 ? OFF_KG : OFF_RG));
;               const float f = n0 < 512 ? rs * 0.08838834764831845f : rs;
;               const int ld = n0 < 1024 ? 512 : 1024;
;               const int cc = n0 - (n0 < 512 ? 0 : n0 < 1024 ? 512 : 2048) + 4 * lane;
;               uint2 o;
;               o.x = pack2(a.x * f, a.y * f);
;               o.y = pack2(a.z * f, a.w * f);
;               st_nt8(O + (size_t)grow * ld + cc, o);
;             } else if (lane < 8) {
;               *(float4*)((float*)(wsb + OFF_GLO) + (size_t)grow * 32 + 4 * lane) = make_float4(a.x * rs, a.y * rs, a.z * rs, a.w * rs);
;             }
.LBB0_1311:
	s_andn2_b64 vcc, exec, s[4:5]
	s_cbranch_vccnz .LBB0_1313
	v_mul_f32_e32 v132, s22, v172
	v_mov_b32_e32 v133, s22
	v_cndmask_b32_e64 v132, v133, v132, s[0:1]
	s_ashr_i32 s9, s8, 31
	s_waitcnt lgkmcnt(0)
	v_pk_mul_f32 v[128:129], v[128:129], v[132:133] op_sel_hi:[1,0]
	v_pk_mul_f32 v[130:131], v[132:133], v[130:131] op_sel_hi:[0,1]
	s_lshl_b64 s[0:1], s[8:9], s21
	v_cvt_pk_bf16_f32 v128, v128, v129
	v_cvt_pk_bf16_f32 v129, v130, v131
	v_lshl_add_u64 v[130:131], s[0:1], 1, v[134:135]
	global_store_dwordx2 v[130:131], v[128:129], off

; template <int EPI, int TS, bool VT>
; DEVI void gemm_epilogue(const Params& p, char* smem, f32x4 (&acc)[2][2][4][2], int m0, int n0, float scale, const float* ssin,
;                         float* ssout, u16* xbout, int wid, int lane, int wr, int wc, int fr, int fq) {
;     ...
;     {
;       float* tw = T + (wr * 64 + fq * 4) * TS + wc * 32 + fr;
; #pragma unroll
;       for (int m = 0; m < 4; ++m)
; #pragma unroll
;         for (int j = 0; j < 4; ++j)
; #pragma unroll
;           for (int v = 0; v < 4; ++v) tw[(m * 16 + j) * TS + (v >> 1) * 128 + (v & 1) * 16] = acc[ai][v >> 1][m][v & 1][j];
;     }
;     __syncthreads();
;     ...
;       if constexpr (EPI == E_GLAIN || EPI == E_KV) {
;         const int tp = lane & 31, dsub = lane >> 5;
; #pragma unroll
;         for (int c = 0; c < 2; ++c) {
;           const int t0 = m0 + ai * 128 + c * 64;
;           float rsa = 1.f, rsb = 1.f;
;           u16* vbase;
;           size_t dstr;
;           if constexpr (EPI == E_GLAIN) {
;             rsa = rsqrtf(ssin[t0 + 2 * tp] * (1.f / 1024.f) + EPS);
;             rsb = rsqrtf(ssin[t0 + 2 * tp + 1] * (1.f / 1024.f) + EPS);
;             const int h = (n0 - 1024) >> 8;
;             vbase = (u16*)(wsb + OFF_VTG) + ((size_t)((t0 >> 6) * 4 + h) * 256) * 64 + 2 * tp;
;             dstr = 64;
;           } else {
;             rsa = rsqrtf(ssin[t0 + 2 * tp] * (1.f / 256.f) + EPS);
;             rsb = rsqrtf(ssin[t0 + 2 * tp + 1] * (1.f / 256.f) + EPS);
;             const size_t S = t0 < MP ? 4096 : 2048;
;             const size_t sb = t0 < MP ? (size_t)(t0 >> 12) * 8 * 128 * 4096 + (t0 & 4095)
;                                       : (size_t)MP * 1024 + (size_t)((t0 - MP) >> 11) * 8 * 128 * 2048 + (t0 & 2047);
;             vbase = (u16*)(wsb + OFF_VTM) + sb + (size_t)(n0 - 1024) * S + 2 * tp;
;             dstr = S;
;           }
;           const float* Tc = T + (c * 64 + 2 * tp) * TS;
;           for (int d = 0; d < 16; ++d) {
;             const int dv = wid * 32 + d * 2 + dsub;
;             const float va = Tc[dv] * rsa, vb = Tc[TS + dv] * rsb;
;             *(unsigned*)(vbase + (size_t)dv * dstr) = pack2(va, vb);
;           }
.LBB0_1314:
	s_and_b64 vcc, exec, s[0:1]
	s_cbranch_vccz .LBB0_1111
	s_movk_i32 s5, 0x404
	v_readlane_b32 s0, v254, 13
	v_mul_lo_u32 v128, v138, s5
	v_readlane_b32 s1, v254, 14
	v_add3_u32 v135, s19, v128, v139
	ds_write2_b32 v135, v88, v96 offset1:16
	ds_write2_b32 v135, v120, v124 offset0:128 offset1:144
	v_add_u32_e32 v120, 0x400, v135
	ds_write2_b32 v120, v89, v97 offset0:1 offset1:17
	ds_write2_b32 v120, v121, v125 offset0:129 offset1:145
	v_add_u32_e32 v121, 0x800, v135
	ds_write2_b32 v121, v90, v98 offset0:2 offset1:18
	ds_write2_b32 v121, v122, v126 offset0:130 offset1:146
	v_add_u32_e32 v122, 0xc00, v135
	ds_write2_b32 v122, v91, v99 offset0:3 offset1:19
	ds_write2_b32 v122, v123, v127 offset0:131 offset1:147
	v_add_u32_e32 v123, 0x4000, v135
	ds_write2_b32 v123, v80, v84 offset0:16 offset1:32
	ds_write2_b32 v123, v112, v116 offset0:144 offset1:160
	v_add_u32_e32 v112, 0x4400, v135
	ds_write2_b32 v112, v81, v85 offset0:17 offset1:33
	ds_write2_b32 v112, v113, v117 offset0:145 offset1:161
	v_add_u32_e32 v113, 0x4800, v135
	ds_write2_b32 v113, v82, v86 offset0:18 offset1:34
	ds_write2_b32 v113, v114, v118 offset0:146 offset1:162
	v_add_u32_e32 v114, 0x4c00, v135
	ds_write2_b32 v114, v83, v87 offset0:19 offset1:35
	ds_write2_b32 v114, v115, v119 offset0:147 offset1:163
	v_add_u32_e32 v115, 0x8000, v135
	v_add_u32_e32 v116, 0x8400, v135
	ds_write2_b32 v115, v72, v76 offset0:32 offset1:48
	ds_write2_b32 v115, v104, v108 offset0:160 offset1:176
	ds_write2_b32 v116, v73, v77 offset0:33 offset1:49
	ds_write2_b32 v116, v105, v109 offset0:161 offset1:177
	v_add_u32_e32 v109, 0x8800, v135
	v_lshlrev_b32_e32 v133, 1, v137
	ds_write2_b32 v109, v74, v78 offset0:34 offset1:50
	ds_write2_b32 v109, v106, v110 offset0:162 offset1:178
	v_add_u32_e32 v110, 0x8c00, v135
	v_and_b32_e32 v134, 62, v133
	ds_write2_b32 v110, v75, v79 offset0:35 offset1:51
	ds_write2_b32 v110, v107, v111 offset0:163 offset1:179
	v_add_u32_e32 v111, 0xc000, v135
	ds_write2_b32 v111, v64, v68 offset0:48 offset1:64
	ds_write2_b32 v111, v92, v100 offset0:176 offset1:192
	v_add_u32_e32 v117, 0xc400, v135
	v_or_b32_e32 v64, s14, v134
	ds_write2_b32 v117, v65, v69 offset0:49 offset1:65
	ds_write2_b32 v117, v93, v101 offset0:177 offset1:193
	v_ashrrev_i32_e32 v65, 31, v64
	v_add_u32_e32 v118, 0xc800, v135
	v_add_u32_e32 v119, 0xcc00, v135
	v_lshl_add_u64 v[64:65], v[64:65], 2, s[16:17]
	ds_write2_b32 v118, v66, v70 offset0:50 offset1:66
	ds_write2_b32 v118, v94, v102 offset0:178 offset1:194
	ds_write2_b32 v119, v67, v71 offset0:51 offset1:67
	ds_write2_b32 v119, v95, v103 offset0:179 offset1:195
	s_waitcnt vmcnt(0) lgkmcnt(0)
	s_barrier
	global_load_dwordx2 v[64:65], v[64:65], off
	v_lshlrev_b32_e32 v148, 1, v134
	s_add_i32 s4, s20, 0xfffffc00
	v_lshl_add_u64 v[128:129], s[0:1], 0, v[148:149]
	s_mov_b64 s[0:1], 0x1e95ee00
	s_lshr_b32 s4, s4, 8
	v_lshl_add_u64 v[128:129], v[128:129], 0, s[0:1]
	s_lshl_b32 s0, s65, 4
	s_or_b32 s0, s4, s0
	s_ashr_i32 s1, s0, 31
	s_lshl_b64 s[0:1], s[0:1], 15
	v_lshl_add_u64 v[98:99], v[128:129], 0, s[0:1]
	s_mov_b32 s0, 0x358637bd
	v_mov_b64_e32 v[96:97], s[0:1]
	s_mov_b32 s6, 0x3a800000
	v_lshrrev_b32_e32 v130, 5, v137
	v_lshl_or_b32 v130, s15, 5, v130
	v_lshlrev_b32_e32 v136, 2, v130
	v_mad_u32_u24 v108, v134, s5, v136
	v_add_u32_e32 v107, 0x400, v108
	ds_read2_b32 v[66:67], v107 offset0:1 offset1:3
	s_mov_b32 s8, 0x45800000
	v_or_b32_e32 v131, 64, v133
	v_mad_u32_u24 v132, v131, s5, v136
	v_ashrrev_i32_e32 v131, 31, v130
	s_waitcnt lgkmcnt(0)
	v_mov_b32_e32 v73, v66
	v_lshlrev_b64 v[92:93], 7, v[130:131]
	v_add_u32_e32 v106, 0x400, v132
	s_waitcnt vmcnt(0)
	v_pk_fma_f32 v[64:65], v[64:65], s[6:7], v[96:97] op_sel_hi:[1,0,0]
	s_nop 0
	v_mul_f32_e32 v68, 0x4b800000, v64
	v_cmp_gt_f32_e64 s[0:1], s29, v64
	v_cmp_gt_f32_e32 vcc, s29, v65
	s_nop 0
	v_cndmask_b32_e64 v64, v64, v68, s[0:1]
	v_mul_f32_e32 v68, 0x4b800000, v65
	v_cndmask_b32_e32 v65, v65, v68, vcc
	v_rsq_f32_e32 v64, v64
	v_rsq_f32_e32 v65, v65
	s_nop 0
	v_pk_mul_f32 v[68:69], v[64:65], s[8:9] op_sel_hi:[1,0]
	s_nop 0
	v_cndmask_b32_e32 v101, v65, v69, vcc
	v_cndmask_b32_e64 v100, v64, v68, s[0:1]
	ds_read2_b32 v[64:65], v108 offset1:2
	ds_read2_b32 v[68:69], v108 offset0:4 offset1:6
	ds_read2_b32 v[70:71], v108 offset0:8 offset1:10
	s_or_b32 s0, s14, 64
	s_waitcnt lgkmcnt(2)
	v_mov_b32_e32 v72, v64
	v_pk_mul_f32 v[72:73], v[72:73], v[100:101]
	v_mov_b32_e32 v66, v65
	v_cvt_pk_bf16_f32 v64, v72, v73
	v_lshl_add_u64 v[72:73], v[98:99], 0, v[92:93]
	global_store_dword v[72:73], v64, off
	v_or_b32_e32 v72, 2, v130
	v_ashrrev_i32_e32 v73, 31, v72
	v_pk_mul_f32 v[64:65], v[66:67], v[100:101]
	v_lshlrev_b64 v[94:95], 7, v[72:73]
	v_cvt_pk_bf16_f32 v66, v64, v65
	v_lshl_add_u64 v[64:65], v[98:99], 0, v[94:95]
	global_store_dword v[64:65], v66, off
	ds_read2_b32 v[66:67], v107 offset0:5 offset1:7
	v_or_b32_e32 v64, 4, v130
	v_ashrrev_i32_e32 v65, 31, v64
	s_waitcnt lgkmcnt(0)
	v_mov_b32_e32 v72, v68
	v_lshlrev_b64 v[88:89], 7, v[64:65]
	v_mov_b32_e32 v73, v66
	v_pk_mul_f32 v[72:73], v[100:101], v[72:73]
	v_lshl_add_u64 v[64:65], v[98:99], 0, v[88:89]
	v_cvt_pk_bf16_f32 v66, v72, v73
	global_store_dword v[64:65], v66, off
	v_or_b32_e32 v64, 6, v130
	v_ashrrev_i32_e32 v65, 31, v64
	v_mov_b32_e32 v66, v69
	v_pk_mul_f32 v[66:67], v[100:101], v[66:67]
	v_lshlrev_b64 v[90:91], 7, v[64:65]
	v_cvt_pk_bf16_f32 v66, v66, v67
	v_lshl_add_u64 v[64:65], v[98:99], 0, v[90:91]
	global_store_dword v[64:65], v66, off
	ds_read2_b32 v[66:67], v107 offset0:9 offset1:11
	v_or_b32_e32 v64, 8, v130
	v_ashrrev_i32_e32 v65, 31, v64
	v_mov_b32_e32 v68, v70
	v_lshlrev_b64 v[84:85], 7, v[64:65]
	s_waitcnt lgkmcnt(0)
; template <int EPI, int TS, bool VT>
; DEVI void gemm_epilogue(const Params& p, char* smem, f32x4 (&acc)[2][2][4][2], int m0, int n0, float scale, const float* ssin,
;                         float* ssout, u16* xbout, int wid, int lane, int wr, int wc, int fr, int fq) {
;     ...
;           float rsa = 1.f, rsb = 1.f;
;           u16* vbase;
;           size_t dstr;
;           if constexpr (EPI == E_GLAIN) {
;             rsa = rsqrtf(ssin[t0 + 2 * tp] * (1.f / 1024.f) + EPS);
;             rsb = rsqrtf(ssin[t0 + 2 * tp + 1] * (1.f / 1024.f) + EPS);
;             const int h = (n0 - 1024) >> 8;
;             vbase = (u16*)(wsb + OFF_VTG) + ((size_t)((t0 >> 6) * 4 + h) * 256) * 64 + 2 * tp;
;             dstr = 64;
;           } else {
;             rsa = rsqrtf(ssin[t0 + 2 * tp] * (1.f / 256.f) + EPS);
;             rsb = rsqrtf(ssin[t0 + 2 * tp + 1] * (1.f / 256.f) + EPS);
;             const size_t S = t0 < MP ? 4096 : 2048;
;             const size_t sb = t0 < MP ? (size_t)(t0 >> 12) * 8 * 128 * 4096 + (t0 & 4095)
;                                       : (size_t)MP * 1024 + (size_t)((t0 - MP) >> 11) * 8 * 128 * 2048 + (t0 & 2047);
;             vbase = (u16*)(wsb + OFF_VTM) + sb + (size_t)(n0 - 1024) * S + 2 * tp;
;             dstr = S;
;           }
;           const float* Tc = T + (c * 64 + 2 * tp) * TS;
;           for (int d = 0; d < 16; ++d) {
;             const int dv = wid * 32 + d * 2 + dsub;
;             const float va = Tc[dv] * rsa, vb = Tc[TS + dv] * rsb;
;             *(unsigned*)(vbase + (size_t)dv * dstr) = pack2(va, vb);
;           }
	v_mov_b32_e32 v69, v66
	v_pk_mul_f32 v[68:69], v[100:101], v[68:69]
	v_lshl_add_u64 v[64:65], v[98:99], 0, v[84:85]
	v_cvt_pk_bf16_f32 v66, v68, v69
	global_store_dword v[64:65], v66, off
	v_or_b32_e32 v64, 10, v130
	v_ashrrev_i32_e32 v65, 31, v64
	v_mov_b32_e32 v66, v71
	v_pk_mul_f32 v[66:67], v[100:101], v[66:67]
	v_lshlrev_b64 v[86:87], 7, v[64:65]
	v_cvt_pk_bf16_f32 v66, v66, v67
	v_lshl_add_u64 v[64:65], v[98:99], 0, v[86:87]
	global_store_dword v[64:65], v66, off
	ds_read2_b32 v[66:67], v107 offset0:13 offset1:15
	ds_read2_b32 v[68:69], v108 offset0:12 offset1:14
	ds_read2_b32 v[70:71], v108 offset0:16 offset1:18
	ds_read2_b32 v[74:75], v108 offset0:20 offset1:22
	v_or_b32_e32 v64, 12, v130
	v_ashrrev_i32_e32 v65, 31, v64
	s_waitcnt lgkmcnt(0)
	v_mov_b32_e32 v72, v68
	v_mov_b32_e32 v73, v66
	v_pk_mul_f32 v[72:73], v[100:101], v[72:73]
	v_lshlrev_b64 v[80:81], 7, v[64:65]
	v_cvt_pk_bf16_f32 v66, v72, v73
	v_lshl_add_u64 v[64:65], v[98:99], 0, v[80:81]
	global_store_dword v[64:65], v66, off
	v_or_b32_e32 v64, 14, v130
	v_ashrrev_i32_e32 v65, 31, v64
	v_mov_b32_e32 v66, v69
	v_pk_mul_f32 v[66:67], v[100:101], v[66:67]
	v_lshlrev_b64 v[82:83], 7, v[64:65]
	v_cvt_pk_bf16_f32 v66, v66, v67
	v_lshl_add_u64 v[64:65], v[98:99], 0, v[82:83]
	global_store_dword v[64:65], v66, off
	ds_read2_b32 v[66:67], v107 offset0:17 offset1:19
	v_or_b32_e32 v64, 16, v130
	v_ashrrev_i32_e32 v65, 31, v64
	v_mov_b32_e32 v68, v70
	v_lshlrev_b64 v[76:77], 7, v[64:65]
	s_waitcnt lgkmcnt(0)
	v_mov_b32_e32 v69, v66
	v_pk_mul_f32 v[68:69], v[100:101], v[68:69]
	v_lshl_add_u64 v[64:65], v[98:99], 0, v[76:77]
	v_cvt_pk_bf16_f32 v66, v68, v69
	global_store_dword v[64:65], v66, off
	v_or_b32_e32 v64, 18, v130
	v_ashrrev_i32_e32 v65, 31, v64
	v_mov_b32_e32 v66, v71
	v_pk_mul_f32 v[66:67], v[100:101], v[66:67]
	v_lshlrev_b64 v[78:79], 7, v[64:65]
	v_cvt_pk_bf16_f32 v66, v66, v67
	v_lshl_add_u64 v[64:65], v[98:99], 0, v[78:79]
	global_store_dword v[64:65], v66, off
	ds_read2_b32 v[66:67], v107 offset0:21 offset1:23
	v_or_b32_e32 v64, 20, v130
	v_ashrrev_i32_e32 v65, 31, v64
	v_mov_b32_e32 v68, v74
	v_lshlrev_b64 v[72:73], 7, v[64:65]
	s_waitcnt lgkmcnt(0)
	v_mov_b32_e32 v69, v66
	v_pk_mul_f32 v[68:69], v[100:101], v[68:69]
	v_lshl_add_u64 v[64:65], v[98:99], 0, v[72:73]
	v_cvt_pk_bf16_f32 v66, v68, v69
	global_store_dword v[64:65], v66, off
	v_or_b32_e32 v64, 22, v130
	v_ashrrev_i32_e32 v65, 31, v64
	v_mov_b32_e32 v66, v75
	v_pk_mul_f32 v[66:67], v[100:101], v[66:67]
	v_lshlrev_b64 v[74:75], 7, v[64:65]
	v_cvt_pk_bf16_f32 v66, v66, v67
	v_lshl_add_u64 v[64:65], v[98:99], 0, v[74:75]
	global_store_dword v[64:65], v66, off
	ds_read2_b32 v[66:67], v107 offset0:25 offset1:27
	ds_read2_b32 v[70:71], v108 offset0:24 offset1:26
	ds_read2_b32 v[102:103], v108 offset0:28 offset1:30
	v_or_b32_e32 v64, 24, v130
	v_ashrrev_i32_e32 v65, 31, v64
	s_waitcnt lgkmcnt(0)
	v_mov_b32_e32 v69, v66
	v_mov_b32_e32 v68, v70
	v_pk_mul_f32 v[68:69], v[100:101], v[68:69]
	v_mov_b32_e32 v104, v102
	v_cvt_pk_bf16_f32 v66, v68, v69
	v_lshlrev_b64 v[68:69], 7, v[64:65]
	v_lshl_add_u64 v[64:65], v[98:99], 0, v[68:69]
	global_store_dword v[64:65], v66, off
	v_or_b32_e32 v64, 26, v130
	v_ashrrev_i32_e32 v65, 31, v64
	v_mov_b32_e32 v66, v71
	v_pk_mul_f32 v[66:67], v[100:101], v[66:67]
	v_lshlrev_b64 v[70:71], 7, v[64:65]
	v_cvt_pk_bf16_f32 v66, v66, v67
	v_lshl_add_u64 v[64:65], v[98:99], 0, v[70:71]
	global_store_dword v[64:65], v66, off
	ds_read2_b32 v[66:67], v107 offset0:29 offset1:31
	v_or_b32_e32 v64, 28, v130
	v_ashrrev_i32_e32 v65, 31, v64
	v_lshlrev_b64 v[64:65], 7, v[64:65]
	s_waitcnt lgkmcnt(0)
	v_mov_b32_e32 v105, v66
	v_pk_mul_f32 v[104:105], v[100:101], v[104:105]
	s_nop 0
	v_cvt_pk_bf16_f32 v66, v104, v105
	v_lshl_add_u64 v[104:105], v[98:99], 0, v[64:65]
	global_store_dword v[104:105], v66, off
	v_or_b32_e32 v104, 30, v130
	v_mov_b32_e32 v66, v103
	v_ashrrev_i32_e32 v105, 31, v104
	v_pk_mul_f32 v[66:67], v[100:101], v[66:67]
	ds_read2_b32 v[102:103], v132 offset1:2
	v_cvt_pk_bf16_f32 v100, v66, v67
	v_lshlrev_b64 v[66:67], 7, v[104:105]
	v_lshl_add_u64 v[98:99], v[98:99], 0, v[66:67]
	global_store_dword v[98:99], v100, off
	v_or_b32_e32 v98, s0, v133
	v_ashrrev_i32_e32 v99, 31, v98
	v_lshl_add_u64 v[104:105], v[98:99], 2, s[16:17]
	global_load_dwordx2 v[104:105], v[104:105], off
	s_ashr_i32 s0, s0, 4
	s_or_b32 s0, s4, s0
	s_ashr_i32 s1, s0, 31
	s_lshl_b64 s[0:1], s[0:1], 15
	v_lshl_add_u64 v[98:99], v[128:129], 0, s[0:1]
	ds_read2_b32 v[100:101], v106 offset0:1 offset1:3
	s_waitcnt vmcnt(0) lgkmcnt(0)
	v_pk_fma_f32 v[104:105], v[104:105], s[6:7], v[96:97] op_sel_hi:[1,0,0]
	s_nop 0
	v_mul_f32_e32 v124, 0x4b800000, v104
	v_cmp_gt_f32_e64 s[0:1], s29, v104
	v_cmp_gt_f32_e32 vcc, s29, v105
	s_nop 0
	v_cndmask_b32_e64 v104, v104, v124, s[0:1]
	v_mul_f32_e32 v124, 0x4b800000, v105
	v_cndmask_b32_e32 v105, v105, v124, vcc
	v_rsq_f32_e32 v104, v104
	v_rsq_f32_e32 v105, v105
	s_nop 0
	v_pk_mul_f32 v[124:125], v[104:105], s[8:9] op_sel_hi:[1,0]
	s_nop 0
	v_cndmask_b32_e32 v105, v105, v125, vcc
	v_cndmask_b32_e64 v104, v104, v124, s[0:1]
	v_mov_b32_e32 v124, v102
	v_mov_b32_e32 v125, v100
	v_pk_mul_f32 v[124:125], v[124:125], v[104:105]
	s_ashr_i32 s0, s18, 4
	v_cvt_pk_bf16_f32 v100, v124, v125
	v_lshl_add_u64 v[124:125], v[98:99], 0, v[92:93]
	global_store_dword v[124:125], v100, off
	v_mov_b32_e32 v100, v103
	v_pk_mul_f32 v[100:101], v[100:101], v[104:105]
	s_or_b32 s0, s4, s0
	v_cvt_pk_bf16_f32 v102, v100, v101
	v_lshl_add_u64 v[100:101], v[98:99], 0, v[94:95]
	global_store_dword v[100:101], v102, off
	ds_read2_b32 v[100:101], v132 offset0:4 offset1:6
	ds_read2_b32 v[102:103], v106 offset0:5 offset1:7
	s_ashr_i32 s1, s0, 31
	s_lshl_b64 s[0:1], s[0:1], 15
	s_waitcnt lgkmcnt(0)
; template <int EPI, int TS, bool VT>
; DEVI void gemm_epilogue(const Params& p, char* smem, f32x4 (&acc)[2][2][4][2], int m0, int n0, float scale, const float* ssin,
;                         float* ssout, u16* xbout, int wid, int lane, int wr, int wc, int fr, int fq) {
;     ...
;     {
;       float* tw = T + (wr * 64 + fq * 4) * TS + wc * 32 + fr;
; #pragma unroll
;       for (int m = 0; m < 4; ++m)
; #pragma unroll
;         for (int j = 0; j < 4; ++j)
; #pragma unroll
;           for (int v = 0; v < 4; ++v) tw[(m * 16 + j) * TS + (v >> 1) * 128 + (v & 1) * 16] = acc[ai][v >> 1][m][v & 1][j];
;     }
;     __syncthreads();
;     ...
;           for (int d = 0; d < 16; ++d) {
;             const int dv = wid * 32 + d * 2 + dsub;
;             const float va = Tc[dv] * rsa, vb = Tc[TS + dv] * rsb;
;             *(unsigned*)(vbase + (size_t)dv * dstr) = pack2(va, vb);
;           }
	v_mov_b32_e32 v124, v100
	v_mov_b32_e32 v125, v102
	v_pk_mul_f32 v[124:125], v[104:105], v[124:125]
	v_mov_b32_e32 v102, v101
	v_cvt_pk_bf16_f32 v100, v124, v125
	v_lshl_add_u64 v[124:125], v[98:99], 0, v[88:89]
	global_store_dword v[124:125], v100, off
	v_pk_mul_f32 v[100:101], v[104:105], v[102:103]
	s_nop 0
	v_cvt_pk_bf16_f32 v102, v100, v101
	v_lshl_add_u64 v[100:101], v[98:99], 0, v[90:91]
	global_store_dword v[100:101], v102, off
	ds_read2_b32 v[100:101], v132 offset0:8 offset1:10
	ds_read2_b32 v[102:103], v106 offset0:9 offset1:11
	s_waitcnt lgkmcnt(0)
	v_mov_b32_e32 v124, v100
	v_mov_b32_e32 v125, v102
	v_pk_mul_f32 v[124:125], v[104:105], v[124:125]
	v_mov_b32_e32 v102, v101
	v_cvt_pk_bf16_f32 v100, v124, v125
	v_lshl_add_u64 v[124:125], v[98:99], 0, v[84:85]
	global_store_dword v[124:125], v100, off
	v_pk_mul_f32 v[100:101], v[104:105], v[102:103]
	s_nop 0
	v_cvt_pk_bf16_f32 v102, v100, v101
	v_lshl_add_u64 v[100:101], v[98:99], 0, v[86:87]
	global_store_dword v[100:101], v102, off
	ds_read2_b32 v[100:101], v132 offset0:12 offset1:14
	ds_read2_b32 v[102:103], v106 offset0:13 offset1:15
	s_waitcnt lgkmcnt(0)
	v_mov_b32_e32 v124, v100
	v_mov_b32_e32 v125, v102
	v_pk_mul_f32 v[124:125], v[104:105], v[124:125]
	v_mov_b32_e32 v102, v101
	v_cvt_pk_bf16_f32 v100, v124, v125
	v_lshl_add_u64 v[124:125], v[98:99], 0, v[80:81]
	global_store_dword v[124:125], v100, off
	v_pk_mul_f32 v[100:101], v[104:105], v[102:103]
	s_nop 0
	v_cvt_pk_bf16_f32 v102, v100, v101
	v_lshl_add_u64 v[100:101], v[98:99], 0, v[82:83]
	global_store_dword v[100:101], v102, off
	ds_read2_b32 v[100:101], v132 offset0:16 offset1:18
	ds_read2_b32 v[102:103], v106 offset0:17 offset1:19
	s_waitcnt lgkmcnt(0)
	v_mov_b32_e32 v124, v100
	v_mov_b32_e32 v125, v102
	v_pk_mul_f32 v[124:125], v[104:105], v[124:125]
	v_mov_b32_e32 v102, v101
	v_cvt_pk_bf16_f32 v100, v124, v125
	v_lshl_add_u64 v[124:125], v[98:99], 0, v[76:77]
	global_store_dword v[124:125], v100, off
	v_pk_mul_f32 v[100:101], v[104:105], v[102:103]
	s_nop 0
	v_cvt_pk_bf16_f32 v102, v100, v101
	v_lshl_add_u64 v[100:101], v[98:99], 0, v[78:79]
	global_store_dword v[100:101], v102, off
	ds_read2_b32 v[100:101], v132 offset0:20 offset1:22
	ds_read2_b32 v[102:103], v106 offset0:21 offset1:23
	s_waitcnt lgkmcnt(0)
	v_mov_b32_e32 v124, v100
	v_mov_b32_e32 v125, v102
	v_pk_mul_f32 v[124:125], v[104:105], v[124:125]
	v_mov_b32_e32 v102, v101
	v_cvt_pk_bf16_f32 v100, v124, v125
	v_lshl_add_u64 v[124:125], v[98:99], 0, v[72:73]
	global_store_dword v[124:125], v100, off
	v_pk_mul_f32 v[100:101], v[104:105], v[102:103]
	s_nop 0
	v_cvt_pk_bf16_f32 v102, v100, v101
	v_lshl_add_u64 v[100:101], v[98:99], 0, v[74:75]
	global_store_dword v[100:101], v102, off
	ds_read2_b32 v[100:101], v132 offset0:24 offset1:26
	ds_read2_b32 v[102:103], v106 offset0:25 offset1:27
	s_waitcnt lgkmcnt(0)
	v_mov_b32_e32 v124, v100
	v_mov_b32_e32 v125, v102
	v_pk_mul_f32 v[124:125], v[104:105], v[124:125]
	v_mov_b32_e32 v102, v101
	v_cvt_pk_bf16_f32 v100, v124, v125
	v_lshl_add_u64 v[124:125], v[98:99], 0, v[68:69]
	global_store_dword v[124:125], v100, off
	v_pk_mul_f32 v[100:101], v[104:105], v[102:103]
	s_nop 0
	v_cvt_pk_bf16_f32 v102, v100, v101
	v_lshl_add_u64 v[100:101], v[98:99], 0, v[70:71]
	global_store_dword v[100:101], v102, off
	ds_read2_b32 v[100:101], v132 offset0:28 offset1:30
	ds_read2_b32 v[102:103], v106 offset0:29 offset1:31
	s_waitcnt lgkmcnt(0)
	v_mov_b32_e32 v124, v100
	v_mov_b32_e32 v125, v102
	v_pk_mul_f32 v[124:125], v[104:105], v[124:125]
	v_mov_b32_e32 v102, v101
	v_cvt_pk_bf16_f32 v100, v124, v125
	v_lshl_add_u64 v[124:125], v[98:99], 0, v[64:65]
	global_store_dword v[124:125], v100, off
	v_pk_mul_f32 v[100:101], v[104:105], v[102:103]
	v_lshl_add_u64 v[98:99], v[98:99], 0, v[66:67]
	v_cvt_pk_bf16_f32 v100, v100, v101
	global_store_dword v[98:99], v100, off
	s_waitcnt lgkmcnt(0)
	s_barrier
	ds_write2_b32 v135, v24, v28 offset1:16
	ds_write2_b32 v135, v56, v60 offset0:128 offset1:144
	ds_write2_b32 v120, v25, v29 offset0:1 offset1:17
	ds_write2_b32 v120, v57, v61 offset0:129 offset1:145
	ds_write2_b32 v121, v26, v30 offset0:2 offset1:18
	ds_write2_b32 v121, v58, v62 offset0:130 offset1:146
	ds_write2_b32 v122, v27, v31 offset0:3 offset1:19
	ds_write2_b32 v122, v59, v63 offset0:131 offset1:147
	ds_write2_b32 v123, v16, v20 offset0:16 offset1:32
	ds_write2_b32 v123, v48, v52 offset0:144 offset1:160
	ds_write2_b32 v112, v17, v21 offset0:17 offset1:33
	ds_write2_b32 v112, v49, v53 offset0:145 offset1:161
	ds_write2_b32 v113, v18, v22 offset0:18 offset1:34
	ds_write2_b32 v113, v50, v54 offset0:146 offset1:162
	ds_write2_b32 v114, v19, v23 offset0:19 offset1:35
	ds_write2_b32 v114, v51, v55 offset0:147 offset1:163
	ds_write2_b32 v115, v8, v12 offset0:32 offset1:48
	ds_write2_b32 v115, v40, v44 offset0:160 offset1:176
	ds_write2_b32 v116, v9, v13 offset0:33 offset1:49
	ds_write2_b32 v116, v41, v45 offset0:161 offset1:177
	ds_write2_b32 v109, v10, v14 offset0:34 offset1:50
	ds_write2_b32 v109, v42, v46 offset0:162 offset1:178
	ds_write2_b32 v110, v11, v15 offset0:35 offset1:51
	ds_write2_b32 v110, v43, v47 offset0:163 offset1:179
	ds_write2_b32 v111, v0, v4 offset0:48 offset1:64
	ds_write2_b32 v111, v32, v36 offset0:176 offset1:192
	ds_write2_b32 v117, v1, v5 offset0:49 offset1:65
	ds_write2_b32 v117, v33, v37 offset0:177 offset1:193
	ds_write2_b32 v118, v2, v6 offset0:50 offset1:66
	ds_write2_b32 v118, v34, v38 offset0:178 offset1:194
	ds_write2_b32 v119, v3, v7 offset0:51 offset1:67
	ds_write2_b32 v119, v35, v39 offset0:179 offset1:195
	v_or_b32_e32 v0, s18, v134
	v_ashrrev_i32_e32 v1, 31, v0
	v_lshl_add_u64 v[0:1], v[0:1], 2, s[16:17]
	s_waitcnt lgkmcnt(0)
	s_barrier
; template <int EPI, int TS, bool VT>
; DEVI void gemm_epilogue(const Params& p, char* smem, f32x4 (&acc)[2][2][4][2], int m0, int n0, float scale, const float* ssin,
;                         float* ssout, u16* xbout, int wid, int lane, int wr, int wc, int fr, int fq) {
;     ...
;           float rsa = 1.f, rsb = 1.f;
;           u16* vbase;
;           size_t dstr;
;           if constexpr (EPI == E_GLAIN) {
;             rsa = rsqrtf(ssin[t0 + 2 * tp] * (1.f / 1024.f) + EPS);
;             rsb = rsqrtf(ssin[t0 + 2 * tp + 1] * (1.f / 1024.f) + EPS);
;             const int h = (n0 - 1024) >> 8;
;             vbase = (u16*)(wsb + OFF_VTG) + ((size_t)((t0 >> 6) * 4 + h) * 256) * 64 + 2 * tp;
;             dstr = 64;
;           } else {
;             rsa = rsqrtf(ssin[t0 + 2 * tp] * (1.f / 256.f) + EPS);
;             rsb = rsqrtf(ssin[t0 + 2 * tp + 1] * (1.f / 256.f) + EPS);
;             const size_t S = t0 < MP ? 4096 : 2048;
;             const size_t sb = t0 < MP ? (size_t)(t0 >> 12) * 8 * 128 * 4096 + (t0 & 4095)
;                                       : (size_t)MP * 1024 + (size_t)((t0 - MP) >> 11) * 8 * 128 * 2048 + (t0 & 2047);
;             vbase = (u16*)(wsb + OFF_VTM) + sb + (size_t)(n0 - 1024) * S + 2 * tp;
;             dstr = S;
;           }
;           const float* Tc = T + (c * 64 + 2 * tp) * TS;
;           for (int d = 0; d < 16; ++d) {
;             const int dv = wid * 32 + d * 2 + dsub;
;             const float va = Tc[dv] * rsa, vb = Tc[TS + dv] * rsb;
;             *(unsigned*)(vbase + (size_t)dv * dstr) = pack2(va, vb);
;           }
	global_load_dwordx2 v[0:1], v[0:1], off
	v_lshl_add_u64 v[2:3], v[128:129], 0, s[0:1]
	ds_read2_b32 v[4:5], v107 offset0:1 offset1:3
	s_waitcnt lgkmcnt(0)
	v_mov_b32_e32 v13, v4
	s_waitcnt vmcnt(0)
	v_pk_fma_f32 v[0:1], v[0:1], s[6:7], v[96:97] op_sel_hi:[1,0,0]
	s_nop 0
	v_mul_f32_e32 v6, 0x4b800000, v0
	v_cmp_gt_f32_e64 s[0:1], s29, v0
	v_cmp_gt_f32_e32 vcc, s29, v1
	s_nop 0
	v_cndmask_b32_e64 v0, v0, v6, s[0:1]
	v_mul_f32_e32 v6, 0x4b800000, v1
	v_cndmask_b32_e32 v1, v1, v6, vcc
	v_rsq_f32_e32 v0, v0
	v_rsq_f32_e32 v1, v1
	s_nop 0
	v_pk_mul_f32 v[6:7], v[0:1], s[8:9] op_sel_hi:[1,0]
	s_nop 0
	v_cndmask_b32_e32 v1, v1, v7, vcc
	v_cndmask_b32_e64 v0, v0, v6, s[0:1]
	ds_read2_b32 v[6:7], v108 offset1:2
	ds_read2_b32 v[8:9], v108 offset0:4 offset1:6
	ds_read2_b32 v[10:11], v108 offset0:8 offset1:10
	s_or_b32 s0, s14, 0xc0
	s_waitcnt lgkmcnt(2)
	v_mov_b32_e32 v12, v6
	v_pk_mul_f32 v[12:13], v[12:13], v[0:1]
	s_nop 0
	v_cvt_pk_bf16_f32 v4, v12, v13
	v_lshl_add_u64 v[12:13], v[2:3], 0, v[92:93]
	global_store_dword v[12:13], v4, off
	v_mov_b32_e32 v4, v7
	v_pk_mul_f32 v[4:5], v[4:5], v[0:1]
	s_nop 0
	v_cvt_pk_bf16_f32 v6, v4, v5
	v_lshl_add_u64 v[4:5], v[2:3], 0, v[94:95]
	global_store_dword v[4:5], v6, off
	ds_read2_b32 v[4:5], v107 offset0:5 offset1:7
	s_waitcnt lgkmcnt(0)
	v_mov_b32_e32 v6, v8
	v_mov_b32_e32 v7, v4
	v_pk_mul_f32 v[6:7], v[0:1], v[6:7]
	s_nop 0
	v_cvt_pk_bf16_f32 v4, v6, v7
	v_lshl_add_u64 v[6:7], v[2:3], 0, v[88:89]
	global_store_dword v[6:7], v4, off
	v_mov_b32_e32 v4, v9
	v_pk_mul_f32 v[4:5], v[0:1], v[4:5]
	s_nop 0
	v_cvt_pk_bf16_f32 v6, v4, v5
	v_lshl_add_u64 v[4:5], v[2:3], 0, v[90:91]
	global_store_dword v[4:5], v6, off
	ds_read2_b32 v[4:5], v107 offset0:9 offset1:11
	v_mov_b32_e32 v6, v10
	s_waitcnt lgkmcnt(0)
	v_mov_b32_e32 v7, v4
	v_pk_mul_f32 v[6:7], v[0:1], v[6:7]
	s_nop 0
	v_cvt_pk_bf16_f32 v4, v6, v7
	v_lshl_add_u64 v[6:7], v[2:3], 0, v[84:85]
	global_store_dword v[6:7], v4, off
	v_mov_b32_e32 v4, v11
	v_pk_mul_f32 v[4:5], v[0:1], v[4:5]
	s_nop 0
	v_cvt_pk_bf16_f32 v6, v4, v5
	v_lshl_add_u64 v[4:5], v[2:3], 0, v[86:87]
	global_store_dword v[4:5], v6, off
	ds_read2_b32 v[4:5], v107 offset0:13 offset1:15
	ds_read2_b32 v[6:7], v108 offset0:12 offset1:14
	ds_read2_b32 v[8:9], v108 offset0:16 offset1:18
	ds_read2_b32 v[10:11], v108 offset0:20 offset1:22
	s_waitcnt lgkmcnt(0)
	v_mov_b32_e32 v13, v4
	v_mov_b32_e32 v12, v6
	v_pk_mul_f32 v[12:13], v[0:1], v[12:13]
	s_nop 0
	v_cvt_pk_bf16_f32 v4, v12, v13
	v_lshl_add_u64 v[12:13], v[2:3], 0, v[80:81]
	global_store_dword v[12:13], v4, off
	v_mov_b32_e32 v4, v7
	v_pk_mul_f32 v[4:5], v[0:1], v[4:5]
	s_nop 0
	v_cvt_pk_bf16_f32 v6, v4, v5
	v_lshl_add_u64 v[4:5], v[2:3], 0, v[82:83]
	global_store_dword v[4:5], v6, off
	ds_read2_b32 v[4:5], v107 offset0:17 offset1:19
	v_mov_b32_e32 v6, v8
	s_waitcnt lgkmcnt(0)
	v_mov_b32_e32 v7, v4
	v_pk_mul_f32 v[6:7], v[0:1], v[6:7]
	s_nop 0
	v_cvt_pk_bf16_f32 v4, v6, v7
	v_lshl_add_u64 v[6:7], v[2:3], 0, v[76:77]
	global_store_dword v[6:7], v4, off
	v_mov_b32_e32 v4, v9
	v_pk_mul_f32 v[4:5], v[0:1], v[4:5]
	s_nop 0
	v_cvt_pk_bf16_f32 v6, v4, v5
	v_lshl_add_u64 v[4:5], v[2:3], 0, v[78:79]
	global_store_dword v[4:5], v6, off
	ds_read2_b32 v[4:5], v107 offset0:21 offset1:23
	v_mov_b32_e32 v6, v10
	s_waitcnt lgkmcnt(0)
	v_mov_b32_e32 v7, v4
	v_pk_mul_f32 v[6:7], v[0:1], v[6:7]
	s_nop 0
	v_cvt_pk_bf16_f32 v4, v6, v7
	v_lshl_add_u64 v[6:7], v[2:3], 0, v[72:73]
	global_store_dword v[6:7], v4, off
	v_mov_b32_e32 v4, v11
	v_pk_mul_f32 v[4:5], v[0:1], v[4:5]
	s_nop 0
	v_cvt_pk_bf16_f32 v6, v4, v5
	v_lshl_add_u64 v[4:5], v[2:3], 0, v[74:75]
	global_store_dword v[4:5], v6, off
	ds_read2_b32 v[4:5], v107 offset0:25 offset1:27
	ds_read2_b32 v[6:7], v108 offset0:24 offset1:26
	ds_read2_b32 v[8:9], v108 offset0:28 offset1:30
	s_waitcnt lgkmcnt(0)
	v_mov_b32_e32 v11, v4
	v_mov_b32_e32 v10, v6
	v_pk_mul_f32 v[10:11], v[0:1], v[10:11]
	s_nop 0
	v_cvt_pk_bf16_f32 v4, v10, v11
	v_lshl_add_u64 v[10:11], v[2:3], 0, v[68:69]
	global_store_dword v[10:11], v4, off
	v_mov_b32_e32 v4, v7
	v_pk_mul_f32 v[4:5], v[0:1], v[4:5]
	s_nop 0
	v_cvt_pk_bf16_f32 v6, v4, v5
	v_lshl_add_u64 v[4:5], v[2:3], 0, v[70:71]
	global_store_dword v[4:5], v6, off
	ds_read2_b32 v[4:5], v107 offset0:29 offset1:31
	v_mov_b32_e32 v6, v8
	s_waitcnt lgkmcnt(0)
	v_mov_b32_e32 v7, v4
	v_pk_mul_f32 v[6:7], v[0:1], v[6:7]
	s_nop 0
	v_cvt_pk_bf16_f32 v4, v6, v7
	v_lshl_add_u64 v[6:7], v[2:3], 0, v[64:65]
	global_store_dword v[6:7], v4, off
	v_mov_b32_e32 v4, v9
	v_pk_mul_f32 v[0:1], v[0:1], v[4:5]
	s_nop 0
	v_cvt_pk_bf16_f32 v4, v0, v1
	v_lshl_add_u64 v[0:1], v[2:3], 0, v[66:67]
	global_store_dword v[0:1], v4, off
	v_or_b32_e32 v0, s0, v133
	v_ashrrev_i32_e32 v1, 31, v0
	v_lshl_add_u64 v[6:7], v[0:1], 2, s[16:17]
	ds_read2_b32 v[4:5], v132 offset1:2
	ds_read2_b32 v[2:3], v106 offset0:1 offset1:3
	global_load_dwordx2 v[6:7], v[6:7], off
	s_ashr_i32 s0, s0, 4
	s_or_b32 s0, s4, s0
	s_ashr_i32 s1, s0, 31
	s_lshl_b64 s[0:1], s[0:1], 15
	v_lshl_add_u64 v[0:1], v[128:129], 0, s[0:1]
	s_waitcnt vmcnt(0) lgkmcnt(0)
; template <int EPI, int TS, bool VT>
; DEVI void gemm_epilogue(const Params& p, char* smem, f32x4 (&acc)[2][2][4][2], int m0, int n0, float scale, const float* ssin,
;                         float* ssout, u16* xbout, int wid, int lane, int wr, int wc, int fr, int fq) {
;     ...
;         const int tp = lane & 31, dsub = lane >> 5;
; #pragma unroll
;         for (int c = 0; c < 2; ++c) {
;           const int t0 = m0 + ai * 128 + c * 64;
;           float rsa = 1.f, rsb = 1.f;
;           u16* vbase;
;           size_t dstr;
;           if constexpr (EPI == E_GLAIN) {
;             rsa = rsqrtf(ssin[t0 + 2 * tp] * (1.f / 1024.f) + EPS);
;             rsb = rsqrtf(ssin[t0 + 2 * tp + 1] * (1.f / 1024.f) + EPS);
;             const int h = (n0 - 1024) >> 8;
;             vbase = (u16*)(wsb + OFF_VTG) + ((size_t)((t0 >> 6) * 4 + h) * 256) * 64 + 2 * tp;
;             dstr = 64;
;           } else {
;             rsa = rsqrtf(ssin[t0 + 2 * tp] * (1.f / 256.f) + EPS);
;             rsb = rsqrtf(ssin[t0 + 2 * tp + 1] * (1.f / 256.f) + EPS);
;             const size_t S = t0 < MP ? 4096 : 2048;
;             const size_t sb = t0 < MP ? (size_t)(t0 >> 12) * 8 * 128 * 4096 + (t0 & 4095)
;                                       : (size_t)MP * 1024 + (size_t)((t0 - MP) >> 11) * 8 * 128 * 2048 + (t0 & 2047);
;             vbase = (u16*)(wsb + OFF_VTM) + sb + (size_t)(n0 - 1024) * S + 2 * tp;
;             dstr = S;
;           }
;           const float* Tc = T + (c * 64 + 2 * tp) * TS;
;           for (int d = 0; d < 16; ++d) {
;             const int dv = wid * 32 + d * 2 + dsub;
;             const float va = Tc[dv] * rsa, vb = Tc[TS + dv] * rsb;
;             *(unsigned*)(vbase + (size_t)dv * dstr) = pack2(va, vb);
;           }
	v_pk_fma_f32 v[6:7], v[6:7], s[6:7], v[96:97] op_sel_hi:[1,0,0]
	s_nop 0
	v_mul_f32_e32 v8, 0x4b800000, v6
	v_cmp_gt_f32_e64 s[0:1], s29, v6
	v_cmp_gt_f32_e32 vcc, s29, v7
	s_nop 0
	v_cndmask_b32_e64 v6, v6, v8, s[0:1]
	v_mul_f32_e32 v8, 0x4b800000, v7
	v_cndmask_b32_e32 v7, v7, v8, vcc
	v_rsq_f32_e32 v6, v6
	v_rsq_f32_e32 v7, v7
	s_nop 0
	v_pk_mul_f32 v[8:9], v[6:7], s[8:9] op_sel_hi:[1,0]
	s_nop 0
	v_cndmask_b32_e32 v7, v7, v9, vcc
	v_cndmask_b32_e64 v6, v6, v8, s[0:1]
	v_mov_b32_e32 v8, v4
	v_mov_b32_e32 v9, v2
	v_pk_mul_f32 v[8:9], v[8:9], v[6:7]
	s_nop 0
	v_cvt_pk_bf16_f32 v2, v8, v9
	v_lshl_add_u64 v[8:9], v[0:1], 0, v[92:93]
	global_store_dword v[8:9], v2, off
	v_mov_b32_e32 v2, v5
	v_pk_mul_f32 v[2:3], v[2:3], v[6:7]
	s_nop 0
	v_cvt_pk_bf16_f32 v4, v2, v3
	v_lshl_add_u64 v[2:3], v[0:1], 0, v[94:95]
	global_store_dword v[2:3], v4, off
	ds_read2_b32 v[2:3], v132 offset0:4 offset1:6
	ds_read2_b32 v[4:5], v106 offset0:5 offset1:7
	s_waitcnt lgkmcnt(0)
	v_mov_b32_e32 v8, v2
	v_mov_b32_e32 v9, v4
	v_pk_mul_f32 v[8:9], v[6:7], v[8:9]
	v_mov_b32_e32 v4, v3
	v_cvt_pk_bf16_f32 v2, v8, v9
	v_lshl_add_u64 v[8:9], v[0:1], 0, v[88:89]
	global_store_dword v[8:9], v2, off
	v_pk_mul_f32 v[2:3], v[6:7], v[4:5]
	s_nop 0
	v_cvt_pk_bf16_f32 v4, v2, v3
	v_lshl_add_u64 v[2:3], v[0:1], 0, v[90:91]
	global_store_dword v[2:3], v4, off
	ds_read2_b32 v[2:3], v132 offset0:8 offset1:10
	ds_read2_b32 v[4:5], v106 offset0:9 offset1:11
	s_waitcnt lgkmcnt(0)
	v_mov_b32_e32 v8, v2
	v_mov_b32_e32 v9, v4
	v_pk_mul_f32 v[8:9], v[6:7], v[8:9]
	v_mov_b32_e32 v4, v3
	v_cvt_pk_bf16_f32 v2, v8, v9
	v_lshl_add_u64 v[8:9], v[0:1], 0, v[84:85]
	global_store_dword v[8:9], v2, off
	v_pk_mul_f32 v[2:3], v[6:7], v[4:5]
	s_nop 0
	v_cvt_pk_bf16_f32 v4, v2, v3
	v_lshl_add_u64 v[2:3], v[0:1], 0, v[86:87]
	global_store_dword v[2:3], v4, off
	ds_read2_b32 v[2:3], v132 offset0:12 offset1:14
	ds_read2_b32 v[4:5], v106 offset0:13 offset1:15
	s_waitcnt lgkmcnt(0)
	v_mov_b32_e32 v8, v2
	v_mov_b32_e32 v9, v4
	v_pk_mul_f32 v[8:9], v[6:7], v[8:9]
	v_mov_b32_e32 v4, v3
	v_cvt_pk_bf16_f32 v2, v8, v9
	v_lshl_add_u64 v[8:9], v[0:1], 0, v[80:81]
	global_store_dword v[8:9], v2, off
	v_pk_mul_f32 v[2:3], v[6:7], v[4:5]
	s_nop 0
	v_cvt_pk_bf16_f32 v4, v2, v3
	v_lshl_add_u64 v[2:3], v[0:1], 0, v[82:83]
	global_store_dword v[2:3], v4, off
	ds_read2_b32 v[2:3], v132 offset0:16 offset1:18
	ds_read2_b32 v[4:5], v106 offset0:17 offset1:19
	s_waitcnt lgkmcnt(0)
	v_mov_b32_e32 v8, v2
	v_mov_b32_e32 v9, v4
	v_pk_mul_f32 v[8:9], v[6:7], v[8:9]
	v_mov_b32_e32 v4, v3
	v_cvt_pk_bf16_f32 v2, v8, v9
	v_lshl_add_u64 v[8:9], v[0:1], 0, v[76:77]
	global_store_dword v[8:9], v2, off
	v_pk_mul_f32 v[2:3], v[6:7], v[4:5]
	s_nop 0
	v_cvt_pk_bf16_f32 v4, v2, v3
	v_lshl_add_u64 v[2:3], v[0:1], 0, v[78:79]
	global_store_dword v[2:3], v4, off
	ds_read2_b32 v[2:3], v132 offset0:20 offset1:22
	ds_read2_b32 v[4:5], v106 offset0:21 offset1:23
	s_waitcnt lgkmcnt(0)
	v_mov_b32_e32 v8, v2
	v_mov_b32_e32 v9, v4
	v_pk_mul_f32 v[8:9], v[6:7], v[8:9]
	v_mov_b32_e32 v4, v3
	v_cvt_pk_bf16_f32 v2, v8, v9
	v_lshl_add_u64 v[8:9], v[0:1], 0, v[72:73]
	global_store_dword v[8:9], v2, off
	v_pk_mul_f32 v[2:3], v[6:7], v[4:5]
	s_nop 0
	v_cvt_pk_bf16_f32 v4, v2, v3
	v_lshl_add_u64 v[2:3], v[0:1], 0, v[74:75]
	global_store_dword v[2:3], v4, off
	ds_read2_b32 v[2:3], v132 offset0:24 offset1:26
	ds_read2_b32 v[4:5], v106 offset0:25 offset1:27
	s_waitcnt lgkmcnt(0)
	v_mov_b32_e32 v8, v2
	v_mov_b32_e32 v9, v4
	v_pk_mul_f32 v[8:9], v[6:7], v[8:9]
	v_mov_b32_e32 v4, v3
	v_cvt_pk_bf16_f32 v2, v8, v9
	v_lshl_add_u64 v[8:9], v[0:1], 0, v[68:69]
	global_store_dword v[8:9], v2, off
	v_pk_mul_f32 v[2:3], v[6:7], v[4:5]
	s_nop 0
	v_cvt_pk_bf16_f32 v4, v2, v3
	v_lshl_add_u64 v[2:3], v[0:1], 0, v[70:71]
	global_store_dword v[2:3], v4, off
	ds_read2_b32 v[2:3], v132 offset0:28 offset1:30
	ds_read2_b32 v[4:5], v106 offset0:29 offset1:31
	s_waitcnt lgkmcnt(0)
	v_mov_b32_e32 v8, v2
	v_mov_b32_e32 v9, v4
	v_pk_mul_f32 v[8:9], v[6:7], v[8:9]
	v_mov_b32_e32 v4, v3
	v_cvt_pk_bf16_f32 v2, v8, v9
	v_lshl_add_u64 v[8:9], v[0:1], 0, v[64:65]
	global_store_dword v[8:9], v2, off
	v_pk_mul_f32 v[2:3], v[6:7], v[4:5]
	v_lshl_add_u64 v[0:1], v[0:1], 0, v[66:67]
	v_cvt_pk_bf16_f32 v2, v2, v3
	global_store_dword v[0:1], v2, off
	s_waitcnt lgkmcnt(0)
	s_barrier
	s_branch .LBB0_1111

; DEVI void gla_phase(int wv, const Params& p, char* smem) {
;     ...
;     for (int i = tid; i < 17 * 128; i += NTHR) {
;       const int k = i >> 7, d = i & 127;
;       sW[i] = k < 16 ? wup[k * 512 + h * 128 + d] : bup[h * 128 + d];
;     }
.LBB0_1324:
	v_ashrrev_i32_e32 v10, 7, v7
	v_ashrrev_i32_e32 v11, 7, v6
	v_cmp_gt_i32_e32 vcc, 16, v11
	v_cmp_gt_i32_e64 s[64:65], 16, v10
	v_lshlrev_b32_e32 v10, 9, v10
	v_lshlrev_b32_e32 v11, 9, v11
	v_or_b32_e32 v10, v1, v10
	v_or_b32_e32 v12, v0, v11
	v_ashrrev_i32_e32 v11, 31, v10
	v_ashrrev_i32_e32 v13, 31, v12
	v_lshl_add_u64 v[12:13], v[12:13], 2, s[68:69]
	v_lshl_add_u64 v[10:11], v[10:11], 2, s[68:69]
	v_cndmask_b32_e64 v10, v2, v10, s[64:65]
	v_cndmask_b32_e32 v13, v5, v13, vcc
	v_cndmask_b32_e32 v12, v4, v12, vcc
	v_cndmask_b32_e64 v11, v3, v11, s[64:65]
	global_load_dword v12, v[12:13], off
	s_nop 0
	global_load_dword v10, v[10:11], off
	v_add_u32_e32 v8, -2, v8
	v_add_u32_e32 v11, 0xfffff800, v9
	v_cmp_eq_u32_e32 vcc, 0, v8
	v_add_u32_e32 v7, 0x400, v7
	v_add_u32_e32 v6, 0x400, v6
	s_or_b64 s[72:73], vcc, s[72:73]
	s_waitcnt vmcnt(0) lgkmcnt(0)
	ds_write_b32 v11, v12
	ds_write_b32 v9, v10
	v_add_u32_e32 v9, 0x1000, v9
	s_andn2_b64 exec, exec, s[72:73]
	s_cbranch_execnz .LBB0_1324
	s_or_b64 exec, exec, s[72:73]
	s_mov_b64 s[64:65], 0
	s_mov_b64 s[72:73], exec
	v_readlane_b32 s74, v255, 9
	v_readlane_b32 s75, v255, 10
	s_and_b64 s[74:75], s[72:73], s[74:75]
	s_mov_b64 exec, s[74:75]
	s_mov_b64 s[64:65], exec
	v_lshlrev_b32_e32 v2, 2, v197
	s_or_b64 exec, exec, s[72:73]
	s_orn2_b64 s[64:65], s[64:65], exec
	v_mov_b32_e32 v1, v197

; DEVI void gla_phase(int wv, const Params& p, char* smem) {
;     ...
;     for (int i = tid; i < 17 * 128; i += NTHR) {
;       const int k = i >> 7, d = i & 127;
;       sW[i] = k < 16 ? wup[k * 512 + h * 128 + d] : bup[h * 128 + d];
;     }
.LBB0_1330:
	v_ashrrev_i32_e32 v3, 7, v1
	v_lshl_or_b32 v6, v3, 9, v0
	v_ashrrev_i32_e32 v7, 31, v6
	v_cmp_gt_i32_e32 vcc, 16, v3
	v_lshl_add_u64 v[6:7], v[6:7], 2, s[68:69]
	s_movk_i32 s16, 0x67f
	v_cndmask_b32_e32 v7, v5, v7, vcc
	v_cndmask_b32_e32 v6, v4, v6, vcc
	global_load_dword v3, v[6:7], off
	v_cmp_lt_i32_e32 vcc, s16, v1
	s_or_b64 s[64:65], vcc, s[64:65]
	s_waitcnt vmcnt(0) lgkmcnt(0)
	ds_write_b32 v2, v3
	v_add_u32_e32 v3, 0x200, v1
	v_add_u32_e32 v2, 0x800, v2
	v_mov_b32_e32 v1, v3
	s_andn2_b64 exec, exec, s[64:65]
	s_cbranch_execnz .LBB0_1330

; DEVI f32x4 ozero() { float z = 0.f; asm volatile("" : "+v"(z)); return f32x4{z, z, z, z}; }
; DEVI void gla_phase(int wv, const Params& p, char* smem) {
;     ...
;     u16* O = (u16*)(wsb + (dir ? OFF_OB : OFF_OF));
;     __syncthreads();
;     const f32x4 zq = ozero();
;     for (int i = tid; i < 256 * 136 * 2 / 16; i += NTHR) ((f32x4*)sST)[i] = zq;
;     f32x4 sacc[8][2];
; #pragma unroll
;     for (int i = 0; i < 8; ++i) { sacc[i][0] = zq; sacc[i][1] = zq; }
;     __syncthreads();
;     unsigned qn[8], kn[8];
;     bf16x8 vn[2][2];
;     float4 lon = make_float4(0.f, 0.f, 0.f, 0.f);
;     ...
;     GLA_FETCH(0);
;     ...
;       for (int i2 = 0; i2 < 8; ++i2) {
;         const float2 tt = *(const float2*)(sTOT + i2 * 128 + 2 * dp);
;         bt0 += tt.x; bt1 += tt.y;
;         const bool inc = dir == 0 ? (i2 < ig) : (i2 > ig);
;         if (inc) { off0 += tt.x; off1 += tt.y; }
;       }
.LBB0_1334:
	s_or_b64 exec, exec, s[62:63]
	s_add_i32 s16, s14, -1
	s_lshl_b32 s44, s16, 6
	s_and_b64 s[62:63], s[66:67], exec
	s_cselect_b32 s64, 0, s44
	s_waitcnt lgkmcnt(0)
	s_barrier
	s_mov_b64 s[62:63], exec
	v_readlane_b32 s68, v254, 33
	v_readlane_b32 s69, v254, 34
	s_and_b64 s[68:69], s[62:63], s[68:69]
	s_xor_b64 s[62:63], s[68:69], s[62:63]
	s_mov_b64 exec, s[68:69]
	s_lshl_b32 s44, s17, 4
	s_or_saveexec_b64 s[62:63], s[62:63]
	v_mov_b32_e32 v148, v149
	s_add_i32 s64, s64, s9
	v_mov_b64_e32 v[24:25], s[44:45]
	v_mov_b64_e32 v[4:5], v[148:149]
	v_mov_b64_e32 v[6:7], v[148:149]
	s_xor_b64 exec, exec, s[62:63]
	s_cbranch_execz .LBB0_1338
	v_add_u32_e32 v4, s64, v177
	v_ashrrev_i32_e32 v5, 31, v4
	v_readlane_b32 s68, v254, 35
	v_lshlrev_b64 v[4:5], 7, v[4:5]
	v_readlane_b32 s69, v254, 36
	v_mov_b32_e32 v155, v149
	s_lshl_b32 s44, s17, 4
	v_lshl_add_u64 v[4:5], s[68:69], 0, v[4:5]
	s_lshl_b32 s68, s17, 6
	s_mov_b32 s69, s45
	v_lshl_add_u64 v[4:5], v[4:5], 0, s[68:69]
	v_lshl_add_u64 v[4:5], v[4:5], 0, v[154:155]
	global_load_dwordx4 v[4:7], v[4:5], off
	v_mov_b64_e32 v[24:25], s[44:45]
.LBB0_1338:
	s_or_b64 exec, exec, s[62:63]
	s_and_b64 s[62:63], s[66:67], exec
	s_mov_b32 s17, 0x5620000
	v_add_u32_e32 v8, s64, v179
	s_cselect_b32 s17, s17, 0x3335ee00
	v_ashrrev_i32_e32 v9, 31, v8
	s_add_u32 s17, s34, s17
	v_lshlrev_b64 v[8:9], 10, v[8:9]
	s_mov_b64 s[62:63], 0x400
	s_addc_u32 s65, s35, 0
	s_lshl_b32 s44, s15, 8
	v_lshl_add_u64 v[14:15], v[8:9], 0, s[62:63]
	s_mov_b64 s[62:63], 0x800
	v_lshl_add_u64 v[158:159], v[138:139], 0, s[44:45]
	v_lshl_add_u64 v[18:19], v[8:9], 0, s[62:63]
	s_mov_b64 s[62:63], 0xc00
	v_lshl_add_u64 v[160:161], v[140:141], 0, s[44:45]
	v_lshl_add_u64 v[10:11], v[158:159], 0, v[8:9]
	v_lshl_add_u64 v[22:23], v[8:9], 0, s[62:63]
	s_mov_b64 s[62:63], 0x1000
	v_lshl_add_u64 v[12:13], v[160:161], 0, v[8:9]
	v_lshl_add_u64 v[16:17], v[158:159], 0, v[14:15]
	v_lshl_add_u64 v[14:15], v[160:161], 0, v[14:15]
	v_lshl_add_u64 v[20:21], v[158:159], 0, v[18:19]
	v_lshl_add_u64 v[18:19], v[160:161], 0, v[18:19]
	v_lshl_add_u64 v[26:27], v[158:159], 0, v[22:23]
	v_lshl_add_u64 v[22:23], v[160:161], 0, v[22:23]
	global_load_dword v230, v[10:11], off
	global_load_dword v221, v[12:13], off
	global_load_dword v229, v[16:17], off
	global_load_dword v167, v[14:15], off
	global_load_dword v228, v[20:21], off
	global_load_dword v222, v[18:19], off
	global_load_dword v227, v[26:27], off
	global_load_dword v220, v[22:23], off
	v_lshl_add_u64 v[10:11], v[8:9], 0, s[62:63]
	s_mov_b64 s[62:63], 0x1400
	v_lshl_add_u64 v[14:15], v[8:9], 0, s[62:63]
	s_mov_b64 s[62:63], 0x1800
	v_lshl_add_u64 v[18:19], v[8:9], 0, s[62:63]
	s_mov_b64 s[62:63], 0x1c00
	s_ashr_i32 s44, s64, 4
	v_lshl_add_u64 v[12:13], v[158:159], 0, v[10:11]
	v_lshl_add_u64 v[8:9], v[8:9], 0, s[62:63]
	s_and_b32 s44, s44, -4
	v_lshl_add_u64 v[10:11], v[160:161], 0, v[10:11]
	v_lshl_add_u64 v[16:17], v[158:159], 0, v[14:15]
	v_lshl_add_u64 v[14:15], v[160:161], 0, v[14:15]
	v_lshl_add_u64 v[20:21], v[158:159], 0, v[18:19]
	v_lshl_add_u64 v[18:19], v[160:161], 0, v[18:19]
	v_lshl_add_u64 v[22:23], v[158:159], 0, v[8:9]
	v_lshl_add_u64 v[8:9], v[160:161], 0, v[8:9]
	global_load_dword v226, v[12:13], off
	global_load_dword v166, v[10:11], off
	global_load_dword v225, v[16:17], off
	global_load_dword v134, v[14:15], off
	global_load_dword v224, v[20:21], off
	global_load_dword v219, v[18:19], off
	global_load_dword v223, v[22:23], off
	global_load_dword v135, v[8:9], off
	s_or_b32 s62, s44, s15
	s_ashr_i32 s63, s62, 31
	s_lshl_b64 s[62:63], s[62:63], 15
	v_lshl_add_u64 v[8:9], v[152:153], 0, s[62:63]
	global_load_dwordx4 v[20:23], v[8:9], off
	global_load_dwordx4 v[12:15], v[8:9], off offset:64
	global_load_dwordx4 v[16:19], v[8:9], off offset:2048
	s_nop 0
	global_load_dwordx4 v[8:11], v[8:9], off offset:2112
	s_lshl_b32 s44, s15, 9
	s_add_u32 s62, s17, s44
	s_addc_u32 s63, s65, 0
	v_lshl_add_u64 v[26:27], v[142:143], 1, s[62:63]
	v_readlane_b32 s62, v254, 37
	v_readlane_b32 s63, v254, 38
	v_lshl_add_u64 v[164:165], v[24:25], 2, v[146:147]
	v_mov_b32_e32 v157, v149
	v_cndmask_b32_e64 v24, 0, 1, s[62:63]
	v_readlane_b32 s62, v254, 39
	v_readlane_b32 s63, v254, 40
	v_add_u32_e32 v148, s9, v187
	s_mov_b32 s17, 1
	v_cndmask_b32_e64 v25, 0, 1, s[62:63]
	v_cndmask_b32_e64 v24, v25, v24, s[66:67]
	v_readlane_b32 s62, v254, 41
	v_and_b32_e32 v24, 1, v24
	v_readlane_b32 s63, v254, 42
	v_cmp_eq_u32_e64 s[68:69], 1, v24
	v_lshl_add_u64 v[162:163], v[26:27], 0, v[156:157]
	v_cndmask_b32_e64 v24, 0, 1, s[62:63]
	v_readlane_b32 s62, v254, 43
	v_readlane_b32 s63, v254, 44
	s_xor_b64 s[86:87], s[18:19], s[66:67]
	s_xor_b64 s[88:89], s[20:21], s[66:67]
	v_cndmask_b32_e64 v25, 0, 1, s[62:63]
	v_cndmask_b32_e64 v24, v25, v24, s[66:67]
	v_readlane_b32 s62, v254, 45
	v_and_b32_e32 v24, 1, v24
	v_readlane_b32 s63, v254, 46
	v_cmp_eq_u32_e64 s[70:71], 1, v24
	v_mov_b32_e32 v26, v0
	v_cndmask_b32_e64 v24, 0, 1, s[62:63]
	v_readlane_b32 s62, v254, 47
	v_readlane_b32 s63, v254, 48
	v_mov_b32_e32 v27, v0
	v_mov_b32_e32 v28, v0
	v_cndmask_b32_e64 v25, 0, 1, s[62:63]
	v_cndmask_b32_e64 v24, v25, v24, s[66:67]
	v_readlane_b32 s62, v254, 49
	v_and_b32_e32 v24, 1, v24
	v_readlane_b32 s63, v254, 50
	v_cmp_eq_u32_e64 s[72:73], 1, v24
	v_mov_b32_e32 v29, v0
	v_cndmask_b32_e64 v24, 0, 1, s[62:63]
	v_readlane_b32 s62, v254, 51
	v_readlane_b32 s63, v254, 52
	v_mov_b32_e32 v30, v0
	v_mov_b32_e32 v31, v0
	v_cndmask_b32_e64 v25, 0, 1, s[62:63]
	v_cndmask_b32_e64 v24, v25, v24, s[66:67]
	v_readlane_b32 s62, v254, 53
	v_and_b32_e32 v24, 1, v24
	v_readlane_b32 s63, v254, 54
	v_cmp_eq_u32_e64 s[74:75], 1, v24
; DEVI u16 f2bf(float f) { return (u16)(pack2(f, 0.f) & 0xffffu); }
; DEVI float bflo(unsigned u) { return __uint_as_float(u << 16); }
; DEVI float bfhi(unsigned u) { return __uint_as_float(u & 0xffff0000u); }
; DEVI void gla_phase(int wv, const Params& p, char* smem) {
;     ...
;     f32x4 sacc[8][2];
; #pragma unroll
;     for (int i = 0; i < 8; ++i) { sacc[i][0] = zq; sacc[i][1] = zq; }
;     ...
;       float off0 = 0.f, off1 = 0.f, bt0 = 0.f, bt1 = 0.f;
; #pragma unroll
;       for (int i2 = 0; i2 < 8; ++i2) {
;         const float2 tt = *(const float2*)(sTOT + i2 * 128 + 2 * dp);
;         bt0 += tt.x; bt1 += tt.y;
;         const bool inc = dir == 0 ? (i2 < ig) : (i2 > ig);
;         if (inc) { off0 += tt.x; off1 += tt.y; }
;       }
;       if (ig == 0) *(float2*)(sDEC + 2 * dp) = make_float2(__expf(bt0), __expf(bt1));
;       unsigned ke0[4], ke1[4];
; #pragma unroll
;       for (int r = 0; r < 8; ++r) {
;         const float ea = e0[r] + off0, eb = e1[r] + off1;
;         const float q0 = bflo(qreg[r]), q1 = bfhi(qreg[r]), k0 = bflo(kreg[r]), k1 = bfhi(kreg[r]);
;         *(unsigned*)(sQD + (ig * 8 + r) * 136 + 2 * dp) = pack2(q0 * __expf(ea), q1 * __expf(eb));
;         *(unsigned*)(sKI + (ig * 8 + r) * 136 + 2 * dp) = pack2(k0 * __expf(-ea), k1 * __expf(-eb));
;         const unsigned a0 = f2bf(k0 * __expf(bt0 - ea)), a1 = f2bf(k1 * __expf(bt1 - eb));
	v_mov_b32_e32 v32, v0
	v_cndmask_b32_e64 v24, 0, 1, s[62:63]
	v_readlane_b32 s62, v254, 55
	v_readlane_b32 s63, v254, 56
	v_mov_b32_e32 v33, v0
	v_mov_b32_e32 v34, v0
	v_cndmask_b32_e64 v25, 0, 1, s[62:63]
	v_cndmask_b32_e64 v24, v25, v24, s[66:67]
	v_readlane_b32 s62, v254, 57
	v_and_b32_e32 v24, 1, v24
	v_readlane_b32 s63, v254, 58
	v_cmp_eq_u32_e64 s[76:77], 1, v24
	v_mov_b32_e32 v35, v0
	v_cndmask_b32_e64 v24, 0, 1, s[62:63]
	v_readlane_b32 s62, v254, 59
	v_readlane_b32 s63, v254, 60
	v_mov_b32_e32 v36, v0
	v_mov_b32_e32 v37, v0
	v_cndmask_b32_e64 v25, 0, 1, s[62:63]
	v_cndmask_b32_e64 v24, v25, v24, s[66:67]
	v_readlane_b32 s62, v254, 61
	v_and_b32_e32 v24, 1, v24
	v_readlane_b32 s63, v254, 62
	v_cmp_eq_u32_e64 s[78:79], 1, v24
	v_mov_b32_e32 v38, v0
	v_cndmask_b32_e64 v24, 0, 1, s[62:63]
	v_readlane_b32 s62, v254, 63
	v_readlane_b32 s63, v255, 0
	v_mov_b32_e32 v39, v0
	v_mov_b32_e32 v40, v0
	v_cndmask_b32_e64 v25, 0, 1, s[62:63]
	v_cndmask_b32_e64 v24, v25, v24, s[66:67]
	v_readlane_b32 s62, v255, 1
	v_and_b32_e32 v24, 1, v24
	v_readlane_b32 s63, v255, 2
	v_cmp_eq_u32_e64 s[80:81], 1, v24
	v_mov_b32_e32 v41, v0
	v_cndmask_b32_e64 v24, 0, 1, s[62:63]
	v_readlane_b32 s62, v255, 3
	v_readlane_b32 s63, v255, 4
	v_mov_b32_e32 v42, v0
	v_mov_b32_e32 v43, v0
	v_cndmask_b32_e64 v25, 0, 1, s[62:63]
	v_cndmask_b32_e64 v24, v25, v24, s[66:67]
	v_readlane_b32 s62, v255, 5
	v_and_b32_e32 v24, 1, v24
	v_readlane_b32 s63, v255, 6
	v_cmp_eq_u32_e64 s[82:83], 1, v24
	s_xor_b64 s[84:85], s[62:63], s[66:67]
	v_mov_b32_e32 v24, v0
	v_mov_b32_e32 v25, v0
	v_mov_b32_e32 v44, v0
	v_mov_b32_e32 v45, v0
	v_mov_b32_e32 v46, v0
	v_mov_b32_e32 v47, v0
	v_mov_b32_e32 v48, v0
	v_mov_b32_e32 v49, v0
	v_mov_b32_e32 v50, v0
	v_mov_b32_e32 v51, v0
	v_mov_b32_e32 v52, v0
	v_mov_b32_e32 v53, v0
	v_mov_b32_e32 v54, v0
	v_mov_b32_e32 v55, v0
	v_mov_b32_e32 v56, v0
	v_mov_b32_e32 v57, v0
	v_mov_b32_e32 v58, v0
	v_mov_b32_e32 v59, v0
	v_mov_b32_e32 v60, v0
	v_mov_b32_e32 v61, v0
	v_mov_b32_e32 v62, v0
	v_mov_b32_e32 v63, v0
	v_mov_b32_e32 v64, v0
	v_mov_b32_e32 v65, v0
	v_mov_b32_e32 v66, v0
	v_mov_b32_e32 v67, v0
	v_mov_b32_e32 v68, v0
	v_mov_b32_e32 v69, v0
	v_mov_b32_e32 v70, v0
	v_mov_b32_e32 v71, v0
	v_mov_b32_e32 v72, v0
	v_mov_b32_e32 v73, v0
	v_mov_b32_e32 v74, v0
	v_mov_b32_e32 v75, v0
	v_mov_b32_e32 v76, v0
	v_mov_b32_e32 v77, v0
	v_mov_b32_e32 v78, v0
	v_mov_b32_e32 v79, v0
	v_mov_b32_e32 v80, v0
	v_mov_b32_e32 v81, v0
	v_mov_b32_e32 v82, v0
	v_mov_b32_e32 v83, v0
	v_mov_b32_e32 v84, v0
	v_mov_b32_e32 v85, v0
	v_mov_b32_e32 v86, v0
	v_mov_b32_e32 v87, v0
	s_xor_b64 s[90:91], s[22:23], s[66:67]
	s_xor_b64 s[92:93], s[12:13], s[66:67]
	s_xor_b64 s[94:95], s[2:3], s[66:67]
	s_xor_b64 s[96:97], s[0:1], s[66:67]
	s_xor_b64 s[64:65], s[30:31], s[66:67]
	s_branch .LBB0_1340
.LBB0_1339:
	s_or_b64 exec, exec, s[62:63]
	v_cndmask_b32_e64 v109, 0, v109, s[68:69]
	v_cndmask_b32_e64 v108, 0, v108, s[68:69]
	v_add_f32_e32 v110, v108, v110
	v_add_f32_e32 v111, v109, v111
	v_cndmask_b32_e64 v109, v109, v111, s[70:71]
	v_cndmask_b32_e64 v108, v108, v110, s[70:71]
	v_add_f32_e32 v104, v108, v104
	v_add_f32_e32 v105, v109, v105
	v_cndmask_b32_e64 v105, v109, v105, s[72:73]
	v_cndmask_b32_e64 v104, v108, v104, s[72:73]
	v_add_f32_e32 v106, v104, v106
	v_add_f32_e32 v107, v105, v107
	v_cndmask_b32_e64 v105, v105, v107, s[74:75]
	v_cndmask_b32_e64 v104, v104, v106, s[74:75]
	v_add_f32_e32 v106, v104, v112
	v_add_f32_e32 v107, v105, v113
	v_cndmask_b32_e64 v105, v105, v107, s[76:77]
	v_cndmask_b32_e64 v104, v104, v106, s[76:77]
	v_add_f32_e32 v106, v104, v114
	v_add_f32_e32 v107, v105, v115
	v_cndmask_b32_e64 v105, v105, v107, s[78:79]
	v_cndmask_b32_e64 v104, v104, v106, s[78:79]
	v_add_f32_e32 v106, v104, v116
	v_add_f32_e32 v107, v105, v117
	v_cndmask_b32_e64 v105, v105, v107, s[80:81]
	v_cndmask_b32_e64 v104, v104, v106, s[80:81]
	v_add_f32_e32 v106, v104, v118
	v_add_f32_e32 v107, v105, v119
	v_cndmask_b32_e64 v176, v105, v107, s[82:83]
	v_cndmask_b32_e64 v236, v104, v106, s[82:83]
	v_add_f32_e32 v112, v234, v236
	v_add_f32_e32 v113, v233, v176
	v_mul_f32_e32 v108, 0x3fb8aa3b, v112
	v_mul_f32_e32 v109, 0x3fb8aa3b, v113
	v_exp_f32_e32 v108, v108
	v_exp_f32_e32 v109, v109
	s_waitcnt vmcnt(0)
	v_lshlrev_b32_e32 v106, 16, v230
	v_and_b32_e32 v107, 0xffff0000, v230
	v_add_f32_e32 v115, v132, v236
	v_pk_mul_f32 v[106:107], v[108:109], v[106:107]
	v_add_f32_e32 v118, v133, v176
	v_cvt_pk_bf16_f32 v107, v106, v107
	v_mul_f32_e32 v106, 0xbfb8aa3b, v112
	v_mul_f32_e32 v116, 0x3fb8aa3b, v115
	v_mul_f32_e32 v117, 0x3fb8aa3b, v118
	v_exp_f32_e32 v110, v106
	v_mul_f32_e32 v106, 0xbfb8aa3b, v113
	v_exp_f32_e32 v116, v116
	v_exp_f32_e32 v117, v117
	v_exp_f32_e32 v111, v106
	v_sub_f32_e32 v106, v231, v112
	v_mul_f32_e32 v106, 0x3fb8aa3b, v106
	v_exp_f32_e32 v114, v106
	v_sub_f32_e32 v106, v232, v113
	v_lshlrev_b32_e32 v112, 16, v229
	v_and_b32_e32 v113, 0xffff0000, v229
	v_pk_mul_f32 v[112:113], v[116:117], v[112:113]
	v_and_b32_e32 v119, 0xffff0000, v228
	v_cvt_pk_bf16_f32 v112, v112, v113
	ds_write2_b32 v193, v107, v112 offset1:68
	v_mul_f32_e32 v107, 0xbfb8aa3b, v115
	v_exp_f32_e32 v116, v107
	v_mul_f32_e32 v107, 0xbfb8aa3b, v118
	v_exp_f32_e32 v117, v107
	v_sub_f32_e32 v107, v232, v118
	v_mul_f32_e32 v107, 0x3fb8aa3b, v107
	v_exp_f32_e32 v112, v107
	v_sub_f32_e32 v107, v231, v115
	v_mul_f32_e32 v107, 0x3fb8aa3b, v107
	v_exp_f32_e32 v132, v107
	v_add_f32_e32 v107, v130, v236
	v_add_f32_e32 v113, v131, v176
	v_mul_f32_e32 v115, 0x3fb8aa3b, v107
	v_exp_f32_e32 v130, v115
	v_mul_f32_e32 v115, 0x3fb8aa3b, v113
	v_exp_f32_e32 v131, v115
	v_lshlrev_b32_e32 v118, 16, v228
	v_mul_f32_e32 v115, 0xbfb8aa3b, v107
; DEVI u16 f2bf(float f) { return (u16)(pack2(f, 0.f) & 0xffffu); }
; DEVI float bflo(unsigned u) { return __uint_as_float(u << 16); }
; DEVI float bfhi(unsigned u) { return __uint_as_float(u & 0xffff0000u); }
; DEVI void gla_phase(int wv, const Params& p, char* smem) {
;     ...
;       unsigned ke0[4], ke1[4];
; #pragma unroll
;       for (int r = 0; r < 8; ++r) {
;         const float ea = e0[r] + off0, eb = e1[r] + off1;
;         const float q0 = bflo(qreg[r]), q1 = bfhi(qreg[r]), k0 = bflo(kreg[r]), k1 = bfhi(kreg[r]);
;         *(unsigned*)(sQD + (ig * 8 + r) * 136 + 2 * dp) = pack2(q0 * __expf(ea), q1 * __expf(eb));
;         *(unsigned*)(sKI + (ig * 8 + r) * 136 + 2 * dp) = pack2(k0 * __expf(-ea), k1 * __expf(-eb));
;         const unsigned a0 = f2bf(k0 * __expf(bt0 - ea)), a1 = f2bf(k1 * __expf(bt1 - eb));
;         if (r & 1) { ke0[r >> 1] |= a0 << 16; ke1[r >> 1] |= a1 << 16; }
;         else { ke0[r >> 1] = a0; ke1[r >> 1] = a1; }
;       }
	v_sub_f32_e32 v107, v231, v107
	v_pk_mul_f32 v[118:119], v[130:131], v[118:119]
	v_mul_f32_e32 v107, 0x3fb8aa3b, v107
	v_cvt_pk_bf16_f32 v133, v118, v119
	v_exp_f32_e32 v118, v115
	v_mul_f32_e32 v115, 0xbfb8aa3b, v113
	v_exp_f32_e32 v119, v115
	v_exp_f32_e32 v115, v107
	v_sub_f32_e32 v107, v232, v113
	v_add_f32_e32 v174, v128, v236
	v_add_f32_e32 v113, v129, v176
	v_mul_f32_e32 v130, 0x3fb8aa3b, v174
	v_mul_f32_e32 v131, 0x3fb8aa3b, v113
	v_exp_f32_e32 v130, v130
	v_exp_f32_e32 v131, v131
	v_lshlrev_b32_e32 v128, 16, v227
	v_and_b32_e32 v129, 0xffff0000, v227
	v_add_f32_e32 v227, v126, v236
	v_pk_mul_f32 v[128:129], v[130:131], v[128:129]
	v_add_f32_e32 v228, v127, v176
	v_cvt_pk_bf16_f32 v128, v128, v129
	ds_write2_b32 v193, v133, v128 offset0:136 offset1:204
	v_mul_f32_e32 v128, 0xbfb8aa3b, v174
	v_sub_f32_e32 v130, v231, v174
	v_mul_f32_e32 v174, 0x3fb8aa3b, v227
	v_mul_f32_e32 v175, 0x3fb8aa3b, v228
	v_exp_f32_e32 v174, v174
	v_exp_f32_e32 v175, v175
	v_mul_f32_e32 v130, 0x3fb8aa3b, v130
	v_exp_f32_e32 v133, v130
	v_lshlrev_b32_e32 v130, 16, v226
	v_and_b32_e32 v131, 0xffff0000, v226
	v_pk_mul_f32 v[130:131], v[174:175], v[130:131]
	v_sub_f32_e32 v174, v231, v227
	v_cvt_pk_bf16_f32 v175, v130, v131
	v_mul_f32_e32 v130, 0xbfb8aa3b, v227
	v_add_f32_e32 v227, v124, v236
	v_add_f32_e32 v230, v125, v176
	v_lshlrev_b32_e32 v124, 16, v225
	v_and_b32_e32 v125, 0xffff0000, v225
	v_mul_f32_e32 v225, 0x3fb8aa3b, v227
	v_exp_f32_e32 v234, v225
	v_mul_f32_e32 v225, 0x3fb8aa3b, v230
	v_exp_f32_e32 v235, v225
	v_add_u32_e32 v233, 0x400, v193
	v_add_f32_e32 v238, v120, v236
	v_lshlrev_b32_e32 v120, 16, v223
	v_pk_mul_f32 v[124:125], v[234:235], v[124:125]
	v_lshlrev_b32_e32 v105, 16, v222
	v_cvt_pk_bf16_f32 v124, v124, v125
	ds_write2_b32 v233, v175, v124 offset0:16 offset1:84
	v_sub_f32_e32 v175, v232, v230
	v_mul_f32_e32 v175, 0x3fb8aa3b, v175
	v_exp_f32_e32 v234, v175
	v_sub_f32_e32 v175, v231, v227
	v_mul_f32_e32 v175, 0x3fb8aa3b, v175
	v_mul_f32_e32 v124, 0xbfb8aa3b, v227
	v_mul_f32_e32 v125, 0xbfb8aa3b, v230
	v_exp_f32_e32 v230, v175
	v_add_f32_e32 v175, v122, v236
	v_add_f32_e32 v227, v123, v176
	v_lshlrev_b32_e32 v122, 16, v224
	v_and_b32_e32 v123, 0xffff0000, v224
	v_mul_f32_e32 v224, 0x3fb8aa3b, v175
	v_mul_f32_e32 v225, 0x3fb8aa3b, v227
	v_exp_f32_e32 v224, v224
	v_exp_f32_e32 v225, v225
	v_add_f32_e32 v176, v121, v176
	v_and_b32_e32 v121, 0xffff0000, v223
	v_lshlrev_b32_e32 v104, 16, v221
	v_pk_mul_f32 v[122:123], v[224:225], v[122:123]
	v_mul_f32_e32 v174, 0x3fb8aa3b, v174
	v_cvt_pk_bf16_f32 v235, v122, v123
	v_mul_f32_e32 v122, 0xbfb8aa3b, v175
	v_exp_f32_e32 v224, v122
	v_mul_f32_e32 v122, 0xbfb8aa3b, v227
	v_exp_f32_e32 v225, v122
	v_sub_f32_e32 v122, v231, v175
	v_mul_f32_e32 v122, 0x3fb8aa3b, v122
	v_exp_f32_e32 v175, v122
	v_sub_f32_e32 v122, v232, v227
	v_mul_f32_e32 v122, 0x3fb8aa3b, v122
	v_exp_f32_e32 v227, v122
	v_mul_f32_e32 v122, 0x3fb8aa3b, v238
	v_mul_f32_e32 v123, 0x3fb8aa3b, v176
	v_exp_f32_e32 v122, v122
	v_exp_f32_e32 v123, v123
	v_lshlrev_b32_e32 v109, 16, v220
	v_lshlrev_b32_e32 v108, 16, v167
	v_exp_f32_e32 v174, v174
	v_pk_mul_f32 v[120:121], v[122:123], v[120:121]
	v_pk_mul_f32 v[114:115], v[114:115], v[104:105]
	v_cvt_pk_bf16_f32 v120, v120, v121
	ds_write2_b32 v233, v235, v120 offset0:152 offset1:220
	v_mul_f32_e32 v120, 0xbfb8aa3b, v238
	v_exp_f32_e32 v236, v120
	v_mul_f32_e32 v120, 0xbfb8aa3b, v176
	v_exp_f32_e32 v237, v120
	v_sub_f32_e32 v120, v232, v176
	v_mul_f32_e32 v120, 0x3fb8aa3b, v120
	v_exp_f32_e32 v235, v120
	v_sub_f32_e32 v120, v231, v238
	v_mul_f32_e32 v120, 0x3fb8aa3b, v120
	v_exp_f32_e32 v231, v120
	v_cvt_pk_bf16_f32 v120, v114, v115
	v_pk_mul_f32 v[114:115], v[132:133], v[108:109]
	v_lshlrev_b32_e32 v127, 16, v219
	v_cvt_pk_bf16_f32 v114, v114, v115
	v_lshlrev_b32_e32 v126, 16, v166
	v_and_b32_e32 v115, 0xffff0000, v114
	v_lshlrev_b32_e32 v114, 16, v114
	v_mul_f32_e32 v131, 0xbfb8aa3b, v228
	v_sub_f32_e32 v226, v232, v228
	v_lshlrev_b32_e32 v229, 16, v135
	v_lshlrev_b32_e32 v228, 16, v134
	v_or_b32_sdwa v121, v115, v120 dst_sel:DWORD dst_unused:UNUSED_PAD src0_sel:DWORD src1_sel:WORD_1
	v_or_b32_sdwa v120, v114, v120 dst_sel:DWORD dst_unused:UNUSED_PAD src0_sel:DWORD src1_sel:WORD_0
	v_pk_mul_f32 v[114:115], v[174:175], v[126:127]
	v_mul_f32_e32 v106, 0x3fb8aa3b, v106
	v_mul_f32_e32 v107, 0x3fb8aa3b, v107
	v_cvt_pk_bf16_f32 v122, v114, v115
	v_pk_mul_f32 v[114:115], v[230:231], v[228:229]
	v_exp_f32_e32 v106, v106
	v_exp_f32_e32 v107, v107
	v_mul_f32_e32 v129, 0xbfb8aa3b, v113
	v_sub_f32_e32 v113, v232, v113
	v_cvt_pk_bf16_f32 v114, v114, v115
	v_mul_f32_e32 v113, 0x3fb8aa3b, v113
	v_and_b32_e32 v115, 0xffff0000, v114
	v_lshlrev_b32_e32 v114, 16, v114
	v_exp_f32_e32 v128, v128
	v_exp_f32_e32 v129, v129
	v_exp_f32_e32 v113, v113
	v_or_b32_sdwa v123, v115, v122 dst_sel:DWORD dst_unused:UNUSED_PAD src0_sel:DWORD src1_sel:WORD_1
	v_or_b32_sdwa v122, v114, v122 dst_sel:DWORD dst_unused:UNUSED_PAD src0_sel:DWORD src1_sel:WORD_0
	v_and_b32_e32 v115, 0xffff0000, v222
	v_and_b32_e32 v114, 0xffff0000, v221
	v_mov_b32_e32 v132, v104
	v_mov_b32_e32 v133, v114
	v_mov_b32_e32 v104, v105
	v_mov_b32_e32 v105, v115
	v_pk_mul_f32 v[110:111], v[110:111], v[132:133]
	v_and_b32_e32 v133, 0xffff0000, v220
	v_pk_mul_f32 v[118:119], v[118:119], v[104:105]
	v_pk_mul_f32 v[104:105], v[106:107], v[114:115]
	v_and_b32_e32 v132, 0xffff0000, v167
	v_mov_b32_e32 v174, v108
	v_cvt_pk_bf16_f32 v108, v104, v105
	v_mov_b32_e32 v104, v109
	v_mov_b32_e32 v105, v133
	v_pk_mul_f32 v[106:107], v[128:129], v[104:105]
	v_pk_mul_f32 v[104:105], v[112:113], v[132:133]
	v_mul_f32_e32 v226, 0x3fb8aa3b, v226
	v_mov_b32_e32 v175, v132
; DEVI f32x4 mfma16(bf16x8 a, bf16x8 b, f32x4 c) { return __builtin_amdgcn_mfma_f32_16x16x32_bf16(a, b, c, 0, 0, 0); }
; DEVI void gla_phase(int wv, const Params& p, char* smem) {
;     ...
;         if (r & 1) { ke0[r >> 1] |= a0 << 16; ke1[r >> 1] |= a1 << 16; }
;         else { ke0[r >> 1] = a0; ke1[r >> 1] = a1; }
;       }
;       *(uint4*)(sKET + (2 * dp) * 72 + ig * 8) = make_uint4(ke0[0], ke0[1], ke0[2], ke0[3]);
;       *(uint4*)(sKET + (2 * dp + 1) * 72 + ig * 8) = make_uint4(ke1[0], ke1[1], ke1[2], ke1[3]);
;       __syncthreads();
;       {
;         const int jt = wave >> 1, it0 = (wave & 1) * 2;
;         f32x4 at[2] = {zq, zq};
; #pragma unroll
;         for (int ks = 0; ks < 4; ++ks) {
;           const bf16x8 kf = *(const bf16x8*)(sKI + (jt * 16 + fr) * 136 + ks * 32 + g * 8);
; #pragma unroll
;           for (int ii = 0; ii < 2; ++ii) {
;             const bf16x8 qq = *(const bf16x8*)(sQD + ((it0 + ii) * 16 + fr) * 136 + ks * 32 + g * 8);
;             at[ii] = mfma16(kf, qq, at[ii]);
;           }
;         }
; #pragma unroll
;         for (int ii = 0; ii < 2; ++ii) {
;           const int i = (it0 + ii) * 16 + fr;
;           float m[4];
; #pragma unroll
;           for (int jj = 0; jj < 4; ++jj) {
;             const int j = jt * 16 + g * 4 + jj;
;             const bool keep = dir == 0 ? (j <= i) : (j > i);
;             m[jj] = keep ? at[ii][jj] : 0.f;
;           }
;           uint2 v;
;           v.x = pack2(m[0], m[1]);
;           v.y = pack2(m[2], m[3]);
;           *(uint2*)(sAM + i * 72 + jt * 16 + g * 4) = v;
;         }
;       }
;       __syncthreads();
	v_cvt_pk_bf16_f32 v104, v104, v105
	v_exp_f32_e32 v226, v226
	v_pk_mul_f32 v[116:117], v[116:117], v[174:175]
	v_and_b32_e32 v105, 0xffff0000, v104
	v_lshlrev_b32_e32 v104, 16, v104
	v_or_b32_sdwa v105, v105, v108 dst_sel:DWORD dst_unused:UNUSED_PAD src0_sel:DWORD src1_sel:WORD_1
	v_or_b32_sdwa v104, v104, v108 dst_sel:DWORD dst_unused:UNUSED_PAD src0_sel:DWORD src1_sel:WORD_0
	v_cvt_pk_bf16_f32 v108, v110, v111
	v_cvt_pk_bf16_f32 v109, v116, v117
	ds_write2_b32 v194, v108, v109 offset1:68
	v_cvt_pk_bf16_f32 v108, v118, v119
	v_cvt_pk_bf16_f32 v106, v106, v107
	v_exp_f32_e32 v130, v130
	v_exp_f32_e32 v131, v131
	v_exp_f32_e32 v124, v124
	v_exp_f32_e32 v125, v125
	ds_write2_b32 v194, v108, v106 offset0:136 offset1:204
	v_and_b32_e32 v107, 0xffff0000, v219
	v_and_b32_e32 v106, 0xffff0000, v166
	v_mov_b32_e32 v109, v106
	v_and_b32_e32 v111, 0xffff0000, v135
	v_mov_b32_e32 v115, v107
	v_pk_mul_f32 v[106:107], v[226:227], v[106:107]
	v_and_b32_e32 v110, 0xffff0000, v134
	v_cvt_pk_bf16_f32 v118, v106, v107
	v_mov_b32_e32 v106, v229
	v_mov_b32_e32 v107, v111
	v_mov_b32_e32 v108, v126
	v_mov_b32_e32 v112, v228
	v_mov_b32_e32 v113, v110
	v_pk_mul_f32 v[116:117], v[236:237], v[106:107]
	v_pk_mul_f32 v[106:107], v[234:235], v[110:111]
	v_pk_mul_f32 v[108:109], v[130:131], v[108:109]
	v_pk_mul_f32 v[112:113], v[124:125], v[112:113]
	v_mov_b32_e32 v114, v127
	v_cvt_pk_bf16_f32 v106, v106, v107
	v_pk_mul_f32 v[114:115], v[224:225], v[114:115]
	v_and_b32_e32 v107, 0xffff0000, v106
	v_lshlrev_b32_e32 v106, 16, v106
	v_cvt_pk_bf16_f32 v108, v108, v109
	v_cvt_pk_bf16_f32 v109, v112, v113
	v_add_u32_e32 v110, 0x400, v194
	v_or_b32_sdwa v107, v107, v118 dst_sel:DWORD dst_unused:UNUSED_PAD src0_sel:DWORD src1_sel:WORD_1
	v_or_b32_sdwa v106, v106, v118 dst_sel:DWORD dst_unused:UNUSED_PAD src0_sel:DWORD src1_sel:WORD_0
	ds_write2_b32 v110, v108, v109 offset0:16 offset1:84
	v_cvt_pk_bf16_f32 v108, v114, v115
	v_cvt_pk_bf16_f32 v109, v116, v117
	ds_write2_b32 v110, v108, v109 offset0:152 offset1:220
	ds_write_b128 v185, v[120:123]
	ds_write_b128 v185, v[104:107] offset:144
	s_waitcnt lgkmcnt(0)
	s_barrier
	ds_read_b128 v[104:107], v186
	ds_read_b128 v[108:111], v200
	ds_read_b128 v[112:115], v200 offset:4352
	s_waitcnt lgkmcnt(1)
	v_mfma_f32_16x16x32_bf16 v[108:111], v[104:107], v[108:111], v[0:3]
	s_add_i32 s44, s17, -1
	s_and_b64 s[62:63], s[66:67], exec
	s_cselect_b32 s44, s44, s16
	s_waitcnt lgkmcnt(0)
	v_mfma_f32_16x16x32_bf16 v[104:107], v[104:107], v[112:115], v[0:3]
	ds_read_b128 v[112:115], v186 offset:64
	ds_read_b128 v[116:119], v200 offset:64
	v_lshl_add_u32 v166, s44, 6, v148
	v_ashrrev_i32_e32 v167, 31, v166
	s_waitcnt lgkmcnt(0)
	v_mfma_f32_16x16x32_bf16 v[108:111], v[112:115], v[116:119], v[108:111]
	ds_read_b128 v[116:119], v200 offset:4416
	v_lshlrev_b64 v[174:175], 11, v[166:167]
	v_lshl_add_u64 v[174:175], v[162:163], 0, v[174:175]
	s_waitcnt lgkmcnt(0)
	v_mfma_f32_16x16x32_bf16 v[104:107], v[112:115], v[116:119], v[104:107]
	ds_read_b128 v[112:115], v186 offset:128
	ds_read_b128 v[116:119], v200 offset:128
	s_movk_i32 s44, 0x1000
	s_mov_b64 s[62:63], 0x1000
	s_waitcnt lgkmcnt(0)
	v_mfma_f32_16x16x32_bf16 v[108:111], v[112:115], v[116:119], v[108:111]
	ds_read_b128 v[116:119], v200 offset:4480
	s_add_i32 s16, s16, -1
	s_add_i32 s17, s17, 1
	s_waitcnt lgkmcnt(0)
	v_mfma_f32_16x16x32_bf16 v[104:107], v[112:115], v[116:119], v[104:107]
	ds_read_b128 v[112:115], v186 offset:192
	ds_read_b128 v[116:119], v200 offset:192
	s_cmp_eq_u32 s16, -1
	v_mov_b32_e32 v219, v209
	s_waitcnt lgkmcnt(0)
	v_mfma_f32_16x16x32_bf16 v[108:111], v[112:115], v[116:119], v[108:111]
	ds_read_b128 v[116:119], v200 offset:4544
	s_waitcnt lgkmcnt(0)
	v_mfma_f32_16x16x32_bf16 v[104:107], v[112:115], v[116:119], v[104:107]
	s_nop 4
	v_cndmask_b32_e64 v108, 0, v108, s[84:85]
	v_cndmask_b32_e64 v109, 0, v109, s[86:87]
	v_cndmask_b32_e64 v110, 0, v110, s[88:89]
	v_cndmask_b32_e64 v111, 0, v111, s[90:91]
	v_cvt_pk_bf16_f32 v108, v108, v109
	v_cvt_pk_bf16_f32 v109, v110, v111
	v_cndmask_b32_e64 v104, 0, v104, s[92:93]
	v_cndmask_b32_e64 v105, 0, v105, s[94:95]
	v_cndmask_b32_e64 v106, 0, v106, s[96:97]
	v_cndmask_b32_e64 v107, 0, v107, s[64:65]
	ds_write_b64 v201, v[108:109]
	v_cvt_pk_bf16_f32 v104, v104, v105
	v_cvt_pk_bf16_f32 v105, v106, v107
	v_add_u32_e32 v108, v144, v195
	ds_write_b64 v201, v[104:105] offset:2304
	s_waitcnt lgkmcnt(0)
	s_barrier
; DEVI u16 f2bf(float f) { return (u16)(pack2(f, 0.f) & 0xffffu); }
; DEVI f32x4 mfma16(bf16x8 a, bf16x8 b, f32x4 c) { return __builtin_amdgcn_mfma_f32_16x16x32_bf16(a, b, c, 0, 0, 0); }
; DEVI void gla_phase(int wv, const Params& p, char* smem) {
;     ...
;       {
;         bf16x8 sf[2][4];
; #pragma unroll
;         for (int nt = 0; nt < 2; ++nt)
; #pragma unroll
;           for (int ks = 0; ks < 4; ++ks)
;             sf[nt][ks] = *(const bf16x8*)(sST + (wave * 32 + nt * 16 + fr) * 136 + ks * 32 + g * 8);
; #pragma unroll
;         for (int mt = 0; mt < 4; ++mt) {
;           f32x4 oa[2] = {zq, zq};
; #pragma unroll
;           for (int kk = 0; kk < 2; ++kk) {
;             const bf16x8 af = *(const bf16x8*)(sAM + (mt * 16 + fr) * 72 + kk * 32 + g * 8);
;             oa[0] = mfma16(af, vf[0][kk], oa[0]);
;             oa[1] = mfma16(af, vf[1][kk], oa[1]);
;           }
; #pragma unroll
;           for (int ks = 0; ks < 4; ++ks) {
;             const bf16x8 qq = *(const bf16x8*)(sQD + (mt * 16 + fr) * 136 + ks * 32 + g * 8);
;             oa[0] = mfma16(qq, sf[0][ks], oa[0]);
;             oa[1] = mfma16(qq, sf[1][ks], oa[1]);
;           }
; #pragma unroll
;           for (int nt = 0; nt < 2; ++nt)
; #pragma unroll
;             for (int jj = 0; jj < 4; ++jj)
;               O[(size_t)(tbase + mt * 16 + g * 4 + jj) * 1024 + h * 256 + wave * 32 + nt * 16 + fr] = f2bf(oa[nt][jj]);
	ds_read_b128 v[128:131], v108
	ds_read_b128 v[116:119], v108 offset:64
	ds_read_b128 v[112:115], v108 offset:128
	ds_read_b128 v[104:107], v108 offset:192
	ds_read_b128 v[132:135], v108 offset:4352
	ds_read_b128 v[124:127], v108 offset:4416
	ds_read_b128 v[120:123], v108 offset:4480
	ds_read_b128 v[108:111], v108 offset:4544
	ds_read_b128 v[220:223], v202
	ds_read_b128 v[228:231], v202 offset:64
	s_waitcnt lgkmcnt(1)
	v_mfma_f32_16x16x32_bf16 v[224:227], v[220:223], v[20:23], v[0:3]
	v_mfma_f32_16x16x32_bf16 v[220:223], v[220:223], v[16:19], v[0:3]
	s_waitcnt lgkmcnt(0)
	v_mfma_f32_16x16x32_bf16 v[224:227], v[228:231], v[12:15], v[224:227]
	v_mfma_f32_16x16x32_bf16 v[220:223], v[228:231], v[8:11], v[220:223]
	ds_read_b128 v[228:231], v203
	s_waitcnt lgkmcnt(0)
	v_mfma_f32_16x16x32_bf16 v[224:227], v[228:231], v[128:131], v[224:227]
	v_mfma_f32_16x16x32_bf16 v[220:223], v[228:231], v[132:135], v[220:223]
	ds_read_b128 v[228:231], v203 offset:64
	s_waitcnt lgkmcnt(0)
	v_mfma_f32_16x16x32_bf16 v[224:227], v[228:231], v[116:119], v[224:227]
	v_mfma_f32_16x16x32_bf16 v[220:223], v[228:231], v[124:127], v[220:223]
	ds_read_b128 v[228:231], v203 offset:128
	s_waitcnt lgkmcnt(0)
	v_mfma_f32_16x16x32_bf16 v[224:227], v[228:231], v[112:115], v[224:227]
	v_mfma_f32_16x16x32_bf16 v[220:223], v[228:231], v[120:123], v[220:223]
	ds_read_b128 v[228:231], v203 offset:192
	s_waitcnt lgkmcnt(0)
	v_mfma_f32_16x16x32_bf16 v[224:227], v[228:231], v[104:107], v[224:227]
	s_nop 7
	v_cvt_pk_bf16_f32 v167, v225, s0
	v_mfma_f32_16x16x32_bf16 v[220:223], v[228:231], v[108:111], v[220:223]
	v_add_co_u32_e32 v228, vcc, s44, v174
	global_store_short v[174:175], v167, off offset:2048
	v_cvt_pk_bf16_f32 v167, v226, s0
	v_addc_co_u32_e32 v229, vcc, 0, v175, vcc
	global_store_short v[228:229], v167, off
	v_cvt_pk_bf16_f32 v167, v227, s0
	global_store_short v[228:229], v167, off offset:2048
	s_nop 0
	v_cvt_pk_bf16_f32 v167, v220, s0
	global_store_short v[174:175], v167, off offset:32
	v_cvt_pk_bf16_f32 v167, v221, s0
	v_cvt_pk_bf16_f32 v176, v224, s0
	v_lshl_add_u64 v[224:225], v[174:175], 0, s[62:63]
	s_mov_b64 s[62:63], 0x1800
	global_store_short v[174:175], v167, off offset:2080
	v_cvt_pk_bf16_f32 v167, v222, s0
	v_lshl_add_u64 v[226:227], v[174:175], 0, s[62:63]
	global_store_short v[224:225], v167, off offset:32
	v_cvt_pk_bf16_f32 v167, v223, s0
	global_store_short v[174:175], v176, off
	global_store_short v[226:227], v167, off offset:32
	ds_read_b128 v[220:223], v202 offset:2304
	ds_read_b128 v[228:231], v202 offset:2368
	s_waitcnt lgkmcnt(0)
	v_mfma_f32_16x16x32_bf16 v[224:227], v[220:223], v[20:23], v[0:3]
	v_add_u32_e32 v174, 16, v166
	v_ashrrev_i32_e32 v175, 31, v174
	v_lshlrev_b64 v[174:175], 11, v[174:175]
	v_mfma_f32_16x16x32_bf16 v[220:223], v[220:223], v[16:19], v[0:3]
	v_lshl_add_u64 v[174:175], v[162:163], 0, v[174:175]
	v_mfma_f32_16x16x32_bf16 v[224:227], v[228:231], v[12:15], v[224:227]
	v_mfma_f32_16x16x32_bf16 v[220:223], v[228:231], v[8:11], v[220:223]
	ds_read_b128 v[228:231], v203 offset:4352
	s_waitcnt lgkmcnt(0)
	v_mfma_f32_16x16x32_bf16 v[224:227], v[228:231], v[128:131], v[224:227]
	v_mfma_f32_16x16x32_bf16 v[220:223], v[228:231], v[132:135], v[220:223]
	ds_read_b128 v[228:231], v203 offset:4416
	s_waitcnt lgkmcnt(0)
	v_mfma_f32_16x16x32_bf16 v[224:227], v[228:231], v[116:119], v[224:227]
	v_mfma_f32_16x16x32_bf16 v[220:223], v[228:231], v[124:127], v[220:223]
	ds_read_b128 v[228:231], v203 offset:4480
	s_waitcnt lgkmcnt(0)
	v_mfma_f32_16x16x32_bf16 v[224:227], v[228:231], v[112:115], v[224:227]
	v_mfma_f32_16x16x32_bf16 v[220:223], v[228:231], v[120:123], v[220:223]
	ds_read_b128 v[228:231], v203 offset:4544
	s_waitcnt lgkmcnt(0)
	v_mfma_f32_16x16x32_bf16 v[224:227], v[228:231], v[104:107], v[224:227]
	s_nop 7
	v_cvt_pk_bf16_f32 v167, v224, s0
	v_add_u32_e32 v224, 17, v166
	v_mfma_f32_16x16x32_bf16 v[220:223], v[228:231], v[108:111], v[220:223]
	global_store_short v[174:175], v167, off
	v_cvt_pk_bf16_f32 v167, v225, s0
	v_ashrrev_i32_e32 v225, 31, v224
	v_add_u32_e32 v228, 18, v166
	v_lshlrev_b64 v[224:225], 11, v[224:225]
	v_ashrrev_i32_e32 v229, 31, v228
	v_lshl_add_u64 v[224:225], v[162:163], 0, v[224:225]
	v_lshlrev_b64 v[228:229], 11, v[228:229]
	global_store_short v[224:225], v167, off
	v_cvt_pk_bf16_f32 v167, v226, s0
	v_lshl_add_u64 v[228:229], v[162:163], 0, v[228:229]
	v_add_u32_e32 v226, 19, v166
	global_store_short v[228:229], v167, off
	v_cvt_pk_bf16_f32 v167, v227, s0
	v_ashrrev_i32_e32 v227, 31, v226
	v_lshlrev_b64 v[226:227], 11, v[226:227]
	v_lshl_add_u64 v[226:227], v[162:163], 0, v[226:227]
	global_store_short v[226:227], v167, off
	v_cvt_pk_bf16_f32 v167, v220, s0
	global_store_short v[174:175], v167, off offset:32
	v_cvt_pk_bf16_f32 v167, v221, s0
	global_store_short v[224:225], v167, off offset:32
	v_cvt_pk_bf16_f32 v167, v222, s0
	global_store_short v[228:229], v167, off offset:32
	v_cvt_pk_bf16_f32 v167, v223, s0
	global_store_short v[226:227], v167, off offset:32
	ds_read_b128 v[220:223], v202 offset:4608
	ds_read_b128 v[228:231], v202 offset:4672
	s_waitcnt lgkmcnt(0)
	v_mfma_f32_16x16x32_bf16 v[224:227], v[220:223], v[20:23], v[0:3]
	v_add_u32_e32 v174, 32, v166
	v_ashrrev_i32_e32 v175, 31, v174
	v_lshlrev_b64 v[174:175], 11, v[174:175]
	v_mfma_f32_16x16x32_bf16 v[220:223], v[220:223], v[16:19], v[0:3]
	v_lshl_add_u64 v[174:175], v[162:163], 0, v[174:175]
	v_mfma_f32_16x16x32_bf16 v[224:227], v[228:231], v[12:15], v[224:227]
	v_mfma_f32_16x16x32_bf16 v[220:223], v[228:231], v[8:11], v[220:223]
	ds_read_b128 v[228:231], v203 offset:8704
	s_waitcnt lgkmcnt(0)
; DEVI u16 f2bf(float f) { return (u16)(pack2(f, 0.f) & 0xffffu); }
; DEVI f32x4 mfma16(bf16x8 a, bf16x8 b, f32x4 c) { return __builtin_amdgcn_mfma_f32_16x16x32_bf16(a, b, c, 0, 0, 0); }
; DEVI void gla_phase(int wv, const Params& p, char* smem) {
;     ...
;         for (int mt = 0; mt < 4; ++mt) {
;           f32x4 oa[2] = {zq, zq};
; #pragma unroll
;           for (int kk = 0; kk < 2; ++kk) {
;             const bf16x8 af = *(const bf16x8*)(sAM + (mt * 16 + fr) * 72 + kk * 32 + g * 8);
;             oa[0] = mfma16(af, vf[0][kk], oa[0]);
;             oa[1] = mfma16(af, vf[1][kk], oa[1]);
;           }
; #pragma unroll
;           for (int ks = 0; ks < 4; ++ks) {
;             const bf16x8 qq = *(const bf16x8*)(sQD + (mt * 16 + fr) * 136 + ks * 32 + g * 8);
;             oa[0] = mfma16(qq, sf[0][ks], oa[0]);
;             oa[1] = mfma16(qq, sf[1][ks], oa[1]);
;           }
; #pragma unroll
;           for (int nt = 0; nt < 2; ++nt)
; #pragma unroll
;             for (int jj = 0; jj < 4; ++jj)
;               O[(size_t)(tbase + mt * 16 + g * 4 + jj) * 1024 + h * 256 + wave * 32 + nt * 16 + fr] = f2bf(oa[nt][jj]);
;         }
; #pragma unroll
;         for (int mt = 0; mt < 8; ++mt) {
;           const float4 d4 = *(const float4*)(sDEC + mt * 16 + g * 4);
; #pragma unroll
;           for (int nt = 0; nt < 2; ++nt) {
;             sacc[mt][nt][0] *= d4.x;
;             sacc[mt][nt][1] *= d4.y;
;             sacc[mt][nt][2] *= d4.z;
;             sacc[mt][nt][3] *= d4.w;
;           }
; #pragma unroll
;           for (int kk = 0; kk < 2; ++kk) {
;             const bf16x8 kef = *(const bf16x8*)(sKET + (mt * 16 + fr) * 72 + kk * 32 + g * 8);
;             sacc[mt][0] = mfma16(kef, vf[0][kk], sacc[mt][0]);
;             sacc[mt][1] = mfma16(kef, vf[1][kk], sacc[mt][1]);
;           }
; #pragma unroll
;           for (int nt = 0; nt < 2; ++nt) {
;             uint2 v;
;             v.x = pack2(sacc[mt][nt][0], sacc[mt][nt][1]);
;             v.y = pack2(sacc[mt][nt][2], sacc[mt][nt][3]);
;             *(uint2*)(sST + (wave * 32 + nt * 16 + fr) * 136 + mt * 16 + g * 4) = v;
;           }
	v_mfma_f32_16x16x32_bf16 v[224:227], v[228:231], v[128:131], v[224:227]
	v_mfma_f32_16x16x32_bf16 v[220:223], v[228:231], v[132:135], v[220:223]
	ds_read_b128 v[228:231], v203 offset:8768
	s_waitcnt lgkmcnt(0)
	v_mfma_f32_16x16x32_bf16 v[224:227], v[228:231], v[116:119], v[224:227]
	v_mfma_f32_16x16x32_bf16 v[220:223], v[228:231], v[124:127], v[220:223]
	ds_read_b128 v[228:231], v203 offset:8832
	s_waitcnt lgkmcnt(0)
	v_mfma_f32_16x16x32_bf16 v[224:227], v[228:231], v[112:115], v[224:227]
	v_mfma_f32_16x16x32_bf16 v[220:223], v[228:231], v[120:123], v[220:223]
	ds_read_b128 v[228:231], v203 offset:8896
	s_waitcnt lgkmcnt(0)
	v_mfma_f32_16x16x32_bf16 v[224:227], v[228:231], v[104:107], v[224:227]
	s_nop 7
	v_cvt_pk_bf16_f32 v167, v224, s0
	v_add_u32_e32 v224, 33, v166
	v_mfma_f32_16x16x32_bf16 v[220:223], v[228:231], v[108:111], v[220:223]
	global_store_short v[174:175], v167, off
	v_cvt_pk_bf16_f32 v167, v225, s0
	v_ashrrev_i32_e32 v225, 31, v224
	v_add_u32_e32 v228, 34, v166
	v_lshlrev_b64 v[224:225], 11, v[224:225]
	v_ashrrev_i32_e32 v229, 31, v228
	v_lshl_add_u64 v[224:225], v[162:163], 0, v[224:225]
	v_lshlrev_b64 v[228:229], 11, v[228:229]
	global_store_short v[224:225], v167, off
	v_cvt_pk_bf16_f32 v167, v226, s0
	v_lshl_add_u64 v[228:229], v[162:163], 0, v[228:229]
	v_add_u32_e32 v226, 35, v166
	global_store_short v[228:229], v167, off
	v_cvt_pk_bf16_f32 v167, v227, s0
	v_ashrrev_i32_e32 v227, 31, v226
	v_lshlrev_b64 v[226:227], 11, v[226:227]
	v_lshl_add_u64 v[226:227], v[162:163], 0, v[226:227]
	global_store_short v[226:227], v167, off
	v_cvt_pk_bf16_f32 v167, v220, s0
	global_store_short v[174:175], v167, off offset:32
	v_cvt_pk_bf16_f32 v167, v221, s0
	global_store_short v[224:225], v167, off offset:32
	v_cvt_pk_bf16_f32 v167, v222, s0
	global_store_short v[228:229], v167, off offset:32
	v_cvt_pk_bf16_f32 v167, v223, s0
	global_store_short v[226:227], v167, off offset:32
	ds_read_b128 v[220:223], v202 offset:6912
	ds_read_b128 v[228:231], v202 offset:6976
	s_waitcnt lgkmcnt(0)
	v_mfma_f32_16x16x32_bf16 v[224:227], v[220:223], v[20:23], v[0:3]
	v_mov_b32_e32 v167, v157
	v_mfma_f32_16x16x32_bf16 v[220:223], v[220:223], v[16:19], v[0:3]
	v_mfma_f32_16x16x32_bf16 v[224:227], v[228:231], v[12:15], v[224:227]
	v_mfma_f32_16x16x32_bf16 v[220:223], v[228:231], v[8:11], v[220:223]
	ds_read_b128 v[228:231], v203 offset:13056
	s_waitcnt lgkmcnt(0)
	v_mfma_f32_16x16x32_bf16 v[132:135], v[228:231], v[132:135], v[220:223]
	s_nop 4
	ds_read_b128 v[220:223], v203 offset:13120
	v_mfma_f32_16x16x32_bf16 v[128:131], v[228:231], v[128:131], v[224:227]
	v_mov_b32_e32 v230, v210
	v_mov_b32_e32 v229, v212
	v_mov_b32_e32 v228, v213
	s_waitcnt lgkmcnt(0)
	v_mfma_f32_16x16x32_bf16 v[116:119], v[220:223], v[116:119], v[128:131]
	v_mov_b32_e32 v227, v214
	s_nop 1
	ds_read_b128 v[128:131], v203 offset:13184
	v_mov_b32_e32 v226, v215
	v_mfma_f32_16x16x32_bf16 v[124:127], v[220:223], v[124:127], v[132:135]
	v_mov_b32_e32 v225, v216
	v_mov_b32_e32 v224, v217
	v_mov_b32_e32 v223, v218
	s_waitcnt lgkmcnt(0)
	v_mfma_f32_16x16x32_bf16 v[112:115], v[128:131], v[112:115], v[116:119]
	v_mov_b32_e32 v220, v207
	v_mov_b32_e32 v221, v155
	v_mov_b32_e32 v222, v205
	v_mfma_f32_16x16x32_bf16 v[116:119], v[128:131], v[120:123], v[124:127]
	ds_read_b128 v[120:123], v203 offset:13248
	v_mov_b32_e32 v134, v208
	v_mov_b32_e32 v135, v211
	s_waitcnt lgkmcnt(0)
	v_mfma_f32_16x16x32_bf16 v[104:107], v[120:123], v[104:107], v[112:115]
	s_nop 2
	v_add_u32_e32 v112, 48, v166
	v_ashrrev_i32_e32 v113, 31, v112
	v_lshlrev_b64 v[112:113], 11, v[112:113]
	s_nop 1
	v_cvt_pk_bf16_f32 v104, v104, s0
	v_lshl_add_u64 v[112:113], v[162:163], 0, v[112:113]
	global_store_short v[112:113], v104, off
	v_add_u32_e32 v104, 49, v166
	v_cvt_pk_bf16_f32 v114, v105, s0
	v_ashrrev_i32_e32 v105, 31, v104
	v_lshlrev_b64 v[104:105], 11, v[104:105]
	v_lshl_add_u64 v[104:105], v[162:163], 0, v[104:105]
	v_mfma_f32_16x16x32_bf16 v[108:111], v[120:123], v[108:111], v[116:119]
	global_store_short v[104:105], v114, off
	v_add_u32_e32 v114, 50, v166
	v_ashrrev_i32_e32 v115, 31, v114
	v_lshlrev_b64 v[114:115], 11, v[114:115]
	v_cvt_pk_bf16_f32 v106, v106, s0
	v_lshl_add_u64 v[114:115], v[162:163], 0, v[114:115]
	global_store_short v[114:115], v106, off
	v_add_u32_e32 v106, 51, v166
	v_cvt_pk_bf16_f32 v108, v108, s0
	v_cvt_pk_bf16_f32 v116, v107, s0
	v_ashrrev_i32_e32 v107, 31, v106
	global_store_short v[112:113], v108, off offset:32
	v_cvt_pk_bf16_f32 v108, v109, s0
	v_lshlrev_b64 v[106:107], 11, v[106:107]
	global_store_short v[104:105], v108, off offset:32
	v_cvt_pk_bf16_f32 v104, v110, s0
	v_lshl_add_u64 v[106:107], v[162:163], 0, v[106:107]
	global_store_short v[114:115], v104, off offset:32
	v_cvt_pk_bf16_f32 v104, v111, s0
	global_store_short v[106:107], v116, off
	global_store_short v[106:107], v104, off offset:32
	ds_read_b128 v[104:107], v188
	v_mov_b32_e32 v166, v206
	s_waitcnt lgkmcnt(0)
	v_pk_mul_f32 v[26:27], v[26:27], v[106:107]
	v_pk_mul_f32 v[24:25], v[24:25], v[104:105]
	v_pk_mul_f32 v[30:31], v[30:31], v[106:107]
	v_pk_mul_f32 v[28:29], v[28:29], v[104:105]
	ds_read_b128 v[104:107], v204
	s_waitcnt lgkmcnt(0)
	v_mfma_f32_16x16x32_bf16 v[24:27], v[104:107], v[20:23], v[24:27]
	v_mfma_f32_16x16x32_bf16 v[28:31], v[104:107], v[16:19], v[28:31]
	ds_read_b128 v[104:107], v204 offset:64
	s_waitcnt lgkmcnt(0)
	v_mfma_f32_16x16x32_bf16 v[24:27], v[104:107], v[12:15], v[24:27]
	v_mfma_f32_16x16x32_bf16 v[28:31], v[104:107], v[8:11], v[28:31]
	s_nop 6
	v_cvt_pk_bf16_f32 v106, v24, v25
	v_cvt_pk_bf16_f32 v107, v26, v27
	v_add_u32_e32 v104, v180, v195
	ds_write_b64 v104, v[106:107]
	v_cvt_pk_bf16_f32 v106, v28, v29
	v_cvt_pk_bf16_f32 v107, v30, v31
	ds_write_b64 v104, v[106:107] offset:4352
	ds_read_b128 v[106:109], v188 offset:64
	s_waitcnt lgkmcnt(0)
; DEVI f32x4 mfma16(bf16x8 a, bf16x8 b, f32x4 c) { return __builtin_amdgcn_mfma_f32_16x16x32_bf16(a, b, c, 0, 0, 0); }
; DEVI void gla_phase(int wv, const Params& p, char* smem) {
;     ...
; #pragma unroll
;         for (int mt = 0; mt < 8; ++mt) {
;           const float4 d4 = *(const float4*)(sDEC + mt * 16 + g * 4);
; #pragma unroll
;           for (int nt = 0; nt < 2; ++nt) {
;             sacc[mt][nt][0] *= d4.x;
;             sacc[mt][nt][1] *= d4.y;
;             sacc[mt][nt][2] *= d4.z;
;             sacc[mt][nt][3] *= d4.w;
;           }
; #pragma unroll
;           for (int kk = 0; kk < 2; ++kk) {
;             const bf16x8 kef = *(const bf16x8*)(sKET + (mt * 16 + fr) * 72 + kk * 32 + g * 8);
;             sacc[mt][0] = mfma16(kef, vf[0][kk], sacc[mt][0]);
;             sacc[mt][1] = mfma16(kef, vf[1][kk], sacc[mt][1]);
;           }
; #pragma unroll
;           for (int nt = 0; nt < 2; ++nt) {
;             uint2 v;
;             v.x = pack2(sacc[mt][nt][0], sacc[mt][nt][1]);
;             v.y = pack2(sacc[mt][nt][2], sacc[mt][nt][3]);
;             *(uint2*)(sST + (wave * 32 + nt * 16 + fr) * 136 + mt * 16 + g * 4) = v;
;           }
;         }
;       }
;       __syncthreads();
	v_pk_mul_f32 v[34:35], v[34:35], v[108:109]
	v_pk_mul_f32 v[32:33], v[32:33], v[106:107]
	v_pk_mul_f32 v[38:39], v[38:39], v[108:109]
	v_pk_mul_f32 v[36:37], v[36:37], v[106:107]
	ds_read_b128 v[106:109], v204 offset:2304
	s_waitcnt lgkmcnt(0)
	v_mfma_f32_16x16x32_bf16 v[32:35], v[106:109], v[20:23], v[32:35]
	v_mfma_f32_16x16x32_bf16 v[36:39], v[106:109], v[16:19], v[36:39]
	ds_read_b128 v[106:109], v204 offset:2368
	s_waitcnt lgkmcnt(0)
	v_mfma_f32_16x16x32_bf16 v[32:35], v[106:109], v[12:15], v[32:35]
	v_mfma_f32_16x16x32_bf16 v[36:39], v[106:109], v[8:11], v[36:39]
	s_nop 6
	v_cvt_pk_bf16_f32 v106, v32, v33
	v_cvt_pk_bf16_f32 v107, v34, v35
	ds_write_b64 v104, v[106:107] offset:32
	v_cvt_pk_bf16_f32 v106, v36, v37
	v_cvt_pk_bf16_f32 v107, v38, v39
	ds_write_b64 v104, v[106:107] offset:4384
	ds_read_b128 v[106:109], v188 offset:128
	s_waitcnt lgkmcnt(0)
	v_pk_mul_f32 v[42:43], v[42:43], v[108:109]
	v_pk_mul_f32 v[40:41], v[40:41], v[106:107]
	v_pk_mul_f32 v[46:47], v[46:47], v[108:109]
	v_pk_mul_f32 v[44:45], v[44:45], v[106:107]
	ds_read_b128 v[106:109], v204 offset:4608
	s_waitcnt lgkmcnt(0)
	v_mfma_f32_16x16x32_bf16 v[40:43], v[106:109], v[20:23], v[40:43]
	v_mfma_f32_16x16x32_bf16 v[44:47], v[106:109], v[16:19], v[44:47]
	ds_read_b128 v[106:109], v204 offset:4672
	s_waitcnt lgkmcnt(0)
	v_mfma_f32_16x16x32_bf16 v[40:43], v[106:109], v[12:15], v[40:43]
	v_mfma_f32_16x16x32_bf16 v[44:47], v[106:109], v[8:11], v[44:47]
	s_nop 6
	v_cvt_pk_bf16_f32 v106, v40, v41
	v_cvt_pk_bf16_f32 v107, v42, v43
	ds_write_b64 v104, v[106:107] offset:64
	v_cvt_pk_bf16_f32 v106, v44, v45
	v_cvt_pk_bf16_f32 v107, v46, v47
	ds_write_b64 v104, v[106:107] offset:4416
	ds_read_b128 v[106:109], v188 offset:192
	s_waitcnt lgkmcnt(0)
	v_pk_mul_f32 v[50:51], v[50:51], v[108:109]
	v_pk_mul_f32 v[48:49], v[48:49], v[106:107]
	v_pk_mul_f32 v[54:55], v[54:55], v[108:109]
	v_pk_mul_f32 v[52:53], v[52:53], v[106:107]
	ds_read_b128 v[106:109], v204 offset:6912
	s_waitcnt lgkmcnt(0)
	v_mfma_f32_16x16x32_bf16 v[48:51], v[106:109], v[20:23], v[48:51]
	v_mfma_f32_16x16x32_bf16 v[52:55], v[106:109], v[16:19], v[52:55]
	ds_read_b128 v[106:109], v204 offset:6976
	s_waitcnt lgkmcnt(0)
	v_mfma_f32_16x16x32_bf16 v[48:51], v[106:109], v[12:15], v[48:51]
	v_mfma_f32_16x16x32_bf16 v[52:55], v[106:109], v[8:11], v[52:55]
	s_nop 6
	v_cvt_pk_bf16_f32 v106, v48, v49
	v_cvt_pk_bf16_f32 v107, v50, v51
	ds_write_b64 v104, v[106:107] offset:96
	v_cvt_pk_bf16_f32 v106, v52, v53
	v_cvt_pk_bf16_f32 v107, v54, v55
	ds_write_b64 v104, v[106:107] offset:4448
	ds_read_b128 v[106:109], v188 offset:256
	s_waitcnt lgkmcnt(0)
	v_pk_mul_f32 v[58:59], v[58:59], v[108:109]
	v_pk_mul_f32 v[56:57], v[56:57], v[106:107]
	v_pk_mul_f32 v[62:63], v[62:63], v[108:109]
	v_pk_mul_f32 v[60:61], v[60:61], v[106:107]
	ds_read_b128 v[106:109], v204 offset:9216
	s_waitcnt lgkmcnt(0)
	v_mfma_f32_16x16x32_bf16 v[56:59], v[106:109], v[20:23], v[56:59]
	v_mfma_f32_16x16x32_bf16 v[60:63], v[106:109], v[16:19], v[60:63]
	ds_read_b128 v[106:109], v204 offset:9280
	s_waitcnt lgkmcnt(0)
	v_mfma_f32_16x16x32_bf16 v[56:59], v[106:109], v[12:15], v[56:59]
	v_mfma_f32_16x16x32_bf16 v[60:63], v[106:109], v[8:11], v[60:63]
	s_nop 6
	v_cvt_pk_bf16_f32 v106, v56, v57
	v_cvt_pk_bf16_f32 v107, v58, v59
	ds_write_b64 v104, v[106:107] offset:128
	v_cvt_pk_bf16_f32 v106, v60, v61
	v_cvt_pk_bf16_f32 v107, v62, v63
	ds_write_b64 v104, v[106:107] offset:4480
	ds_read_b128 v[106:109], v188 offset:320
	s_waitcnt lgkmcnt(0)
	v_pk_mul_f32 v[66:67], v[66:67], v[108:109]
	v_pk_mul_f32 v[64:65], v[64:65], v[106:107]
	v_pk_mul_f32 v[70:71], v[70:71], v[108:109]
	v_pk_mul_f32 v[68:69], v[68:69], v[106:107]
	ds_read_b128 v[106:109], v204 offset:11520
	s_waitcnt lgkmcnt(0)
	v_mfma_f32_16x16x32_bf16 v[64:67], v[106:109], v[20:23], v[64:67]
	v_mfma_f32_16x16x32_bf16 v[68:71], v[106:109], v[16:19], v[68:71]
	ds_read_b128 v[106:109], v204 offset:11584
	s_waitcnt lgkmcnt(0)
	v_mfma_f32_16x16x32_bf16 v[64:67], v[106:109], v[12:15], v[64:67]
	v_mfma_f32_16x16x32_bf16 v[68:71], v[106:109], v[8:11], v[68:71]
	s_nop 6
	v_cvt_pk_bf16_f32 v106, v64, v65
	v_cvt_pk_bf16_f32 v107, v66, v67
	ds_write_b64 v104, v[106:107] offset:160
	v_cvt_pk_bf16_f32 v106, v68, v69
	v_cvt_pk_bf16_f32 v107, v70, v71
	ds_write_b64 v104, v[106:107] offset:4512
	ds_read_b128 v[106:109], v188 offset:384
	s_waitcnt lgkmcnt(0)
	v_pk_mul_f32 v[74:75], v[74:75], v[108:109]
	v_pk_mul_f32 v[72:73], v[72:73], v[106:107]
	v_pk_mul_f32 v[78:79], v[78:79], v[108:109]
	v_pk_mul_f32 v[76:77], v[76:77], v[106:107]
	ds_read_b128 v[106:109], v204 offset:13824
	s_waitcnt lgkmcnt(0)
	v_mfma_f32_16x16x32_bf16 v[72:75], v[106:109], v[20:23], v[72:75]
	v_mfma_f32_16x16x32_bf16 v[76:79], v[106:109], v[16:19], v[76:79]
	ds_read_b128 v[106:109], v204 offset:13888
	s_waitcnt lgkmcnt(0)
	v_mfma_f32_16x16x32_bf16 v[72:75], v[106:109], v[12:15], v[72:75]
	v_mfma_f32_16x16x32_bf16 v[76:79], v[106:109], v[8:11], v[76:79]
	s_nop 6
	v_cvt_pk_bf16_f32 v106, v72, v73
	v_cvt_pk_bf16_f32 v107, v74, v75
	ds_write_b64 v104, v[106:107] offset:192
	v_cvt_pk_bf16_f32 v106, v76, v77
	v_cvt_pk_bf16_f32 v107, v78, v79
	ds_write_b64 v104, v[106:107] offset:4544
	ds_read_b128 v[106:109], v188 offset:448
	s_waitcnt lgkmcnt(0)
	v_pk_mul_f32 v[82:83], v[82:83], v[108:109]
	v_pk_mul_f32 v[80:81], v[80:81], v[106:107]
	v_pk_mul_f32 v[86:87], v[86:87], v[108:109]
	v_pk_mul_f32 v[84:85], v[84:85], v[106:107]
	ds_read_b128 v[106:109], v204 offset:16128
	s_waitcnt lgkmcnt(0)
	v_mfma_f32_16x16x32_bf16 v[20:23], v[106:109], v[20:23], v[80:83]
	v_mfma_f32_16x16x32_bf16 v[16:19], v[106:109], v[16:19], v[84:87]
	s_nop 2
	ds_read_b128 v[84:87], v204 offset:16192
	s_waitcnt lgkmcnt(0)
	v_mfma_f32_16x16x32_bf16 v[80:83], v[84:87], v[12:15], v[20:23]
	v_mov_b64_e32 v[12:13], v[92:93]
	s_nop 1
	v_mov_b64_e32 v[20:21], v[88:89]
	v_mov_b64_e32 v[14:15], v[94:95]
	v_mfma_f32_16x16x32_bf16 v[84:87], v[84:87], v[8:11], v[16:19]
	s_nop 1
	v_cvt_pk_bf16_f32 v8, v80, v81
	v_cvt_pk_bf16_f32 v9, v82, v83
	ds_write_b64 v104, v[8:9] offset:224
	v_mov_b64_e32 v[16:17], v[96:97]
	v_mov_b64_e32 v[18:19], v[98:99]
	s_nop 0
	v_cvt_pk_bf16_f32 v8, v84, v85
	v_cvt_pk_bf16_f32 v9, v86, v87
	ds_write_b64 v104, v[8:9] offset:4576
	v_mov_b64_e32 v[8:9], v[100:101]
	v_mov_b64_e32 v[10:11], v[102:103]
	v_mov_b64_e32 v[22:23], v[90:91]
	s_waitcnt lgkmcnt(0)
	s_barrier
	s_cbranch_scc1 .LBB0_1316

.LBB0_1342:
	s_or_b64 exec, exec, s[62:63]
	s_cmp_ge_u32 s17, s14
	s_cbranch_scc1 .LBB0_1346
	s_add_i32 s44, s16, -1
	s_and_b64 s[62:63], s[66:67], exec
	s_cselect_b32 s44, s17, s44
	s_lshl_b32 s44, s44, 6
	s_add_i32 s44, s44, s9
	s_and_saveexec_b64 s[62:63], s[6:7]
	s_cbranch_execz .LBB0_1345
	s_waitcnt vmcnt(0) lgkmcnt(0)
	v_add_u32_e32 v4, s44, v177
	v_ashrrev_i32_e32 v5, 31, v4
	v_lshlrev_b64 v[4:5], 7, v[4:5]
	v_lshl_add_u64 v[4:5], v[164:165], 0, v[4:5]
	global_load_dwordx4 v[4:7], v[4:5], off
.LBB0_1345:
	s_or_b64 exec, exec, s[62:63]
	v_add_u32_e32 v88, s44, v179
	v_ashrrev_i32_e32 v89, 31, v88
	v_lshlrev_b64 v[88:89], 10, v[88:89]
	v_lshl_add_u64 v[90:91], v[158:159], 0, v[88:89]
	global_load_dword v210, v[90:91], off
	v_lshl_add_u64 v[90:91], v[160:161], 0, v[88:89]
	s_mov_b64 s[62:63], 0x400
	global_load_dword v155, v[90:91], off
	v_lshl_add_u64 v[90:91], v[88:89], 0, s[62:63]
	v_lshl_add_u64 v[92:93], v[158:159], 0, v[90:91]
	v_lshl_add_u64 v[90:91], v[160:161], 0, v[90:91]
	s_mov_b64 s[62:63], 0x800
	global_load_dword v212, v[92:93], off
	global_load_dword v157, v[90:91], off
	v_lshl_add_u64 v[90:91], v[88:89], 0, s[62:63]
	v_lshl_add_u64 v[92:93], v[158:159], 0, v[90:91]
	v_lshl_add_u64 v[90:91], v[160:161], 0, v[90:91]
	s_mov_b64 s[62:63], 0xc00
	global_load_dword v213, v[92:93], off
	global_load_dword v205, v[90:91], off
	v_lshl_add_u64 v[90:91], v[88:89], 0, s[62:63]
	v_lshl_add_u64 v[92:93], v[158:159], 0, v[90:91]
	v_lshl_add_u64 v[90:91], v[160:161], 0, v[90:91]
	s_mov_b64 s[62:63], 0x1000
	global_load_dword v214, v[92:93], off
	global_load_dword v207, v[90:91], off
	v_lshl_add_u64 v[90:91], v[88:89], 0, s[62:63]
	v_lshl_add_u64 v[92:93], v[158:159], 0, v[90:91]
	v_lshl_add_u64 v[90:91], v[160:161], 0, v[90:91]
	s_mov_b64 s[62:63], 0x1400
	global_load_dword v215, v[92:93], off
	global_load_dword v206, v[90:91], off
	v_lshl_add_u64 v[90:91], v[88:89], 0, s[62:63]
	v_lshl_add_u64 v[92:93], v[158:159], 0, v[90:91]
	v_lshl_add_u64 v[90:91], v[160:161], 0, v[90:91]
	s_mov_b64 s[62:63], 0x1800
	s_ashr_i32 s44, s44, 4
	global_load_dword v216, v[92:93], off
	global_load_dword v208, v[90:91], off
	v_lshl_add_u64 v[90:91], v[88:89], 0, s[62:63]
	s_mov_b64 s[62:63], 0x1c00
	s_and_b32 s44, s44, -4
	v_lshl_add_u64 v[88:89], v[88:89], 0, s[62:63]
	s_or_b32 s62, s44, s15
	s_ashr_i32 s63, s62, 31
	v_lshl_add_u64 v[92:93], v[158:159], 0, v[90:91]
	v_lshl_add_u64 v[90:91], v[160:161], 0, v[90:91]
	s_lshl_b64 s[62:63], s[62:63], 15
	global_load_dword v217, v[92:93], off
	global_load_dword v209, v[90:91], off
	v_lshl_add_u64 v[90:91], v[158:159], 0, v[88:89]
	v_lshl_add_u64 v[88:89], v[160:161], 0, v[88:89]
	v_lshl_add_u64 v[100:101], v[152:153], 0, s[62:63]
	global_load_dword v218, v[90:91], off
	global_load_dword v211, v[88:89], off
	s_nop 0
	global_load_dwordx4 v[88:91], v[100:101], off
	global_load_dwordx4 v[92:95], v[100:101], off offset:64
	global_load_dwordx4 v[96:99], v[100:101], off offset:2048
	s_nop 0
	global_load_dwordx4 v[100:103], v[100:101], off offset:2112
	s_branch .LBB0_1347

; DEVI u16 f2bf(float f) { return (u16)(pack2(f, 0.f) & 0xffffu); }
;     ...
;   for (int t = bid_; t < tk * tn; t += nb_) {
;     const int k0 = (t % tk) * 64, n0 = (t / tk) * 64;
;     {
;       const int nn = tid & 63;
;       const int src = mapcol(map, n0 + nn);
;       const bool valid = src < Nsrc;
; #pragma unroll
;       for (int i = 0; i < 8; ++i) {
;         const int kk = (tid >> 6) + 8 * i;
;         tile[kk * 65 + nn] = valid ? W[(size_t)(k0 + kk) * Nsrc + src] * (gain ? gain[k0 + kk] : 1.f) : 0.f;
;       }
;     }
;     __syncthreads();
;     {
;       const int kk = tid & 63;
; #pragma unroll
;       for (int i = 0; i < 8; ++i) {
;         const int nn = (tid >> 6) + 8 * i;
;         dst[(size_t)(n0 + nn) * K + k0 + kk] = f2bf(tile[kk * 65 + nn]);
;       }
;     }
;     __syncthreads();
;   }
.LBB0_1363:
	s_or_b64 exec, exec, s[82:83]
	ds_write_b32 v20, v6 offset:12480
	ds_write_b32 v20, v7 offset:14560
	s_waitcnt lgkmcnt(0)
	s_barrier
	ds_read2_b32 v[6:7], v19 offset1:8
	v_lshl_add_u64 v[4:5], v[8:9], 1, v[2:3]
	v_add_u32_e32 v8, s90, v0
	v_ashrrev_i32_e32 v9, 31, v8
	v_lshlrev_b64 v[8:9], 11, v[8:9]
	s_waitcnt lgkmcnt(0)
	v_cvt_pk_bf16_f32 v6, v6, s0
	v_lshl_add_u64 v[8:9], v[4:5], 0, v[8:9]
	global_store_short v[8:9], v6, off
	v_add_u32_e32 v6, s90, v12
	v_cvt_pk_bf16_f32 v8, v7, s0
	v_ashrrev_i32_e32 v7, 31, v6
	v_lshlrev_b64 v[6:7], 11, v[6:7]
	v_lshl_add_u64 v[6:7], v[4:5], 0, v[6:7]
	global_store_short v[6:7], v8, off
	ds_read2_b32 v[6:7], v19 offset0:16 offset1:24
	v_add_u32_e32 v8, s90, v13
	v_ashrrev_i32_e32 v9, 31, v8
	v_lshlrev_b64 v[8:9], 11, v[8:9]
	v_lshl_add_u64 v[8:9], v[4:5], 0, v[8:9]
	s_waitcnt lgkmcnt(0)
	v_cvt_pk_bf16_f32 v6, v6, s0
	global_store_short v[8:9], v6, off
	v_add_u32_e32 v6, s90, v14
	v_cvt_pk_bf16_f32 v8, v7, s0
	v_ashrrev_i32_e32 v7, 31, v6
	v_lshlrev_b64 v[6:7], 11, v[6:7]
	v_lshl_add_u64 v[6:7], v[4:5], 0, v[6:7]
	global_store_short v[6:7], v8, off
	ds_read2_b32 v[6:7], v19 offset0:32 offset1:40
	v_add_u32_e32 v8, s90, v15
	v_ashrrev_i32_e32 v9, 31, v8
	v_lshlrev_b64 v[8:9], 11, v[8:9]
	v_lshl_add_u64 v[8:9], v[4:5], 0, v[8:9]
	s_waitcnt lgkmcnt(0)
	v_cvt_pk_bf16_f32 v6, v6, s0
	global_store_short v[8:9], v6, off
	v_add_u32_e32 v6, s90, v16
	v_cvt_pk_bf16_f32 v8, v7, s0
	v_ashrrev_i32_e32 v7, 31, v6
	v_lshlrev_b64 v[6:7], 11, v[6:7]
	v_lshl_add_u64 v[6:7], v[4:5], 0, v[6:7]
	global_store_short v[6:7], v8, off
	ds_read2_b32 v[6:7], v19 offset0:48 offset1:56
	v_add_u32_e32 v8, s90, v17
	v_ashrrev_i32_e32 v9, 31, v8
	v_lshlrev_b64 v[8:9], 11, v[8:9]
	v_lshl_add_u64 v[8:9], v[4:5], 0, v[8:9]
	s_waitcnt lgkmcnt(0)
	v_cvt_pk_bf16_f32 v6, v6, s0
	global_store_short v[8:9], v6, off
	v_add_u32_e32 v6, s90, v18
	v_cvt_pk_bf16_f32 v8, v7, s0
	v_ashrrev_i32_e32 v7, 31, v6
	v_lshlrev_b64 v[6:7], 11, v[6:7]
	s_add_i32 s87, s87, s88
	s_add_i32 s44, s44, s89
	v_lshl_add_u64 v[4:5], v[4:5], 0, v[6:7]
	s_cmpk_lt_i32 s87, 0x580
	global_store_short v[4:5], v8, off
	s_waitcnt lgkmcnt(0)
	s_barrier
	s_cbranch_scc0 .LBB0_1372

; DEVI u16 f2bf(float f) { return (u16)(pack2(f, 0.f) & 0xffffu); }
;     ...
;   for (int t = bid_; t < tk * tn; t += nb_) {
;     const int k0 = (t % tk) * 64, n0 = (t / tk) * 64;
;     {
;       const int nn = tid & 63;
;       const int src = mapcol(map, n0 + nn);
;       const bool valid = src < Nsrc;
; #pragma unroll
;       for (int i = 0; i < 8; ++i) {
;         const int kk = (tid >> 6) + 8 * i;
;         tile[kk * 65 + nn] = valid ? W[(size_t)(k0 + kk) * Nsrc + src] * (gain ? gain[k0 + kk] : 1.f) : 0.f;
;       }
;     }
;     __syncthreads();
;     {
;       const int kk = tid & 63;
; #pragma unroll
;       for (int i = 0; i < 8; ++i) {
;         const int nn = (tid >> 6) + 8 * i;
;         dst[(size_t)(n0 + nn) * K + k0 + kk] = f2bf(tile[kk * 65 + nn]);
;       }
;     }
;     __syncthreads();
;   }
.LBB0_1378:
	s_or_b64 exec, exec, s[4:5]
	s_waitcnt vmcnt(1)
	ds_write_b32 v14, v15 offset:12480
	s_waitcnt vmcnt(0)
	ds_write_b32 v14, v16 offset:14560
	s_waitcnt lgkmcnt(0)
	s_barrier
	ds_read2_b32 v[16:17], v13 offset1:8
	s_add_i32 s4, s81, s85
	s_ashr_i32 s5, s4, 31
	v_lshl_add_u64 v[2:3], s[4:5], 1, v[0:1]
	s_movk_i32 s85, 0x1600
	s_waitcnt lgkmcnt(0)
	v_cvt_pk_bf16_f32 v15, v16, s0
	v_add_u32_e32 v16, s83, v5
	v_mad_i64_i32 v[18:19], s[4:5], v16, s85, v[2:3]
	v_add_u32_e32 v16, s83, v6
	global_store_short v[18:19], v15, off
	v_cvt_pk_bf16_f32 v15, v17, s0
	v_mad_i64_i32 v[16:17], s[4:5], v16, s85, v[2:3]
	global_store_short v[16:17], v15, off
	ds_read2_b32 v[16:17], v13 offset0:16 offset1:24
	s_add_i32 s44, s44, s80
	s_add_i32 s81, s81, s82
	s_cmpk_lt_i32 s44, 0x2c0
	s_waitcnt lgkmcnt(0)
	v_cvt_pk_bf16_f32 v15, v16, s0
	v_add_u32_e32 v16, s83, v7
	v_mad_i64_i32 v[18:19], s[4:5], v16, s85, v[2:3]
	v_add_u32_e32 v16, s83, v8
	global_store_short v[18:19], v15, off
	v_cvt_pk_bf16_f32 v15, v17, s0
	v_mad_i64_i32 v[16:17], s[4:5], v16, s85, v[2:3]
	global_store_short v[16:17], v15, off
	ds_read2_b32 v[16:17], v13 offset0:32 offset1:40
	s_waitcnt lgkmcnt(0)
	v_cvt_pk_bf16_f32 v15, v16, s0
	v_add_u32_e32 v16, s83, v9
	v_mad_i64_i32 v[18:19], s[4:5], v16, s85, v[2:3]
	v_add_u32_e32 v16, s83, v10
	global_store_short v[18:19], v15, off
	v_cvt_pk_bf16_f32 v15, v17, s0
	v_mad_i64_i32 v[16:17], s[4:5], v16, s85, v[2:3]
	global_store_short v[16:17], v15, off
	ds_read2_b32 v[16:17], v13 offset0:48 offset1:56
	s_waitcnt lgkmcnt(0)
	v_cvt_pk_bf16_f32 v15, v16, s0
	v_add_u32_e32 v16, s83, v11
	v_mad_i64_i32 v[18:19], s[4:5], v16, s85, v[2:3]
	v_add_u32_e32 v16, s83, v12
	global_store_short v[18:19], v15, off
	v_cvt_pk_bf16_f32 v15, v17, s0
	v_mad_i64_i32 v[2:3], s[4:5], v16, s85, v[2:3]
	global_store_short v[2:3], v15, off
	s_waitcnt lgkmcnt(0)
	s_barrier
	s_cbranch_scc0 .LBB0_1356

; DEVI u16 f2bf(float f) { return (u16)(pack2(f, 0.f) & 0xffffu); }
;     ...
;   for (int t = bid_; t < tk * tn; t += nb_) {
;     const int k0 = (t % tk) * 64, n0 = (t / tk) * 64;
;     {
;       const int nn = tid & 63;
;       const int src = mapcol(map, n0 + nn);
;       const bool valid = src < Nsrc;
; #pragma unroll
;       for (int i = 0; i < 8; ++i) {
;         const int kk = (tid >> 6) + 8 * i;
;         tile[kk * 65 + nn] = valid ? W[(size_t)(k0 + kk) * Nsrc + src] * (gain ? gain[k0 + kk] : 1.f) : 0.f;
;       }
;     }
;     __syncthreads();
;     {
;       const int kk = tid & 63;
; #pragma unroll
;       for (int i = 0; i < 8; ++i) {
;         const int nn = (tid >> 6) + 8 * i;
;         dst[(size_t)(n0 + nn) * K + k0 + kk] = f2bf(tile[kk * 65 + nn]);
;       }
;     }
;     __syncthreads();
;   }
.LBB0_1402:
	s_or_b64 exec, exec, s[4:5]
	ds_write_b32 v19, v7 offset:14560
	s_waitcnt lgkmcnt(0)
	s_barrier
	ds_read2_b32 v[6:7], v18 offset1:8
	v_add_u32_e32 v8, s81, v0
	s_ashr_i32 s15, s14, 31
	v_ashrrev_i32_e32 v9, 31, v8
	v_lshl_add_u64 v[4:5], s[14:15], 1, v[2:3]
	v_lshlrev_b64 v[8:9], 11, v[8:9]
	s_waitcnt lgkmcnt(0)
	v_cvt_pk_bf16_f32 v6, v6, s0
	v_lshl_add_u64 v[8:9], v[4:5], 0, v[8:9]
	global_store_short v[8:9], v6, off
	v_add_u32_e32 v6, s81, v11
	v_cvt_pk_bf16_f32 v8, v7, s0
	v_ashrrev_i32_e32 v7, 31, v6
	v_lshlrev_b64 v[6:7], 11, v[6:7]
	v_lshl_add_u64 v[6:7], v[4:5], 0, v[6:7]
	global_store_short v[6:7], v8, off
	ds_read2_b32 v[6:7], v18 offset0:16 offset1:24
	v_add_u32_e32 v8, s81, v12
	v_ashrrev_i32_e32 v9, 31, v8
	v_lshlrev_b64 v[8:9], 11, v[8:9]
	v_lshl_add_u64 v[8:9], v[4:5], 0, v[8:9]
	s_waitcnt lgkmcnt(0)
	v_cvt_pk_bf16_f32 v6, v6, s0
	global_store_short v[8:9], v6, off
	v_add_u32_e32 v6, s81, v13
	v_cvt_pk_bf16_f32 v8, v7, s0
	v_ashrrev_i32_e32 v7, 31, v6
	v_lshlrev_b64 v[6:7], 11, v[6:7]
	v_lshl_add_u64 v[6:7], v[4:5], 0, v[6:7]
	global_store_short v[6:7], v8, off
	ds_read2_b32 v[6:7], v18 offset0:32 offset1:40
	v_add_u32_e32 v8, s81, v14
	v_ashrrev_i32_e32 v9, 31, v8
	v_lshlrev_b64 v[8:9], 11, v[8:9]
	v_lshl_add_u64 v[8:9], v[4:5], 0, v[8:9]
	s_waitcnt lgkmcnt(0)
	v_cvt_pk_bf16_f32 v6, v6, s0
	global_store_short v[8:9], v6, off
	v_add_u32_e32 v6, s81, v15
	v_cvt_pk_bf16_f32 v8, v7, s0
	v_ashrrev_i32_e32 v7, 31, v6
	v_lshlrev_b64 v[6:7], 11, v[6:7]
	v_lshl_add_u64 v[6:7], v[4:5], 0, v[6:7]
	global_store_short v[6:7], v8, off
	ds_read2_b32 v[6:7], v18 offset0:48 offset1:56
	v_add_u32_e32 v8, s81, v16
	v_ashrrev_i32_e32 v9, 31, v8
	v_lshlrev_b64 v[8:9], 11, v[8:9]
	v_lshl_add_u64 v[8:9], v[4:5], 0, v[8:9]
	s_waitcnt lgkmcnt(0)
	v_cvt_pk_bf16_f32 v6, v6, s0
	global_store_short v[8:9], v6, off
	v_add_u32_e32 v6, s81, v17
	v_cvt_pk_bf16_f32 v8, v7, s0
	v_ashrrev_i32_e32 v7, 31, v6
	v_lshlrev_b64 v[6:7], 11, v[6:7]
	s_add_i32 s3, s3, s31
	s_add_i32 s44, s44, s80
	v_lshl_add_u64 v[4:5], v[4:5], 0, v[6:7]
	s_cmpk_lt_i32 s3, 0x100
	global_store_short v[4:5], v8, off
	s_waitcnt lgkmcnt(0)
	s_barrier
	s_cbranch_scc0 .LBB0_1434

; DEVI u16 f2bf(float f) { return (u16)(pack2(f, 0.f) & 0xffffu); }
;     ...
;   for (int t = bid_; t < tk * tn; t += nb_) {
;     const int k0 = (t % tk) * 64, n0 = (t / tk) * 64;
;     {
;       const int nn = tid & 63;
;       const int src = mapcol(map, n0 + nn);
;       const bool valid = src < Nsrc;
; #pragma unroll
;       for (int i = 0; i < 8; ++i) {
;         const int kk = (tid >> 6) + 8 * i;
;         tile[kk * 65 + nn] = valid ? W[(size_t)(k0 + kk) * Nsrc + src] * (gain ? gain[k0 + kk] : 1.f) : 0.f;
;       }
;     }
;     __syncthreads();
;     {
;       const int kk = tid & 63;
; #pragma unroll
;       for (int i = 0; i < 8; ++i) {
;         const int nn = (tid >> 6) + 8 * i;
;         dst[(size_t)(n0 + nn) * K + k0 + kk] = f2bf(tile[kk * 65 + nn]);
;       }
;     }
;     __syncthreads();
;   }
.LBB0_1440:
	s_or_b64 exec, exec, s[0:1]
	s_waitcnt vmcnt(1)
	ds_write_b32 v14, v15 offset:12480
	s_waitcnt vmcnt(0)
	ds_write_b32 v14, v16 offset:14560
	s_waitcnt lgkmcnt(0)
	s_barrier
	ds_read2_b32 v[16:17], v13 offset1:8
	s_add_i32 s0, s5, s16
	v_add_u32_e32 v18, s15, v5
	s_ashr_i32 s1, s0, 31
	v_ashrrev_i32_e32 v19, 31, v18
	v_lshl_add_u64 v[2:3], s[0:1], 1, v[0:1]
	v_lshlrev_b64 v[18:19], 9, v[18:19]
	s_waitcnt lgkmcnt(0)
	v_cvt_pk_bf16_f32 v15, v16, s0
	v_lshl_add_u64 v[18:19], v[2:3], 0, v[18:19]
	v_add_u32_e32 v16, s15, v6
	global_store_short v[18:19], v15, off
	v_cvt_pk_bf16_f32 v15, v17, s0
	v_ashrrev_i32_e32 v17, 31, v16
	v_lshlrev_b64 v[16:17], 9, v[16:17]
	v_lshl_add_u64 v[16:17], v[2:3], 0, v[16:17]
	global_store_short v[16:17], v15, off
	ds_read2_b32 v[16:17], v13 offset0:16 offset1:24
	v_add_u32_e32 v18, s15, v7
	v_ashrrev_i32_e32 v19, 31, v18
	v_lshlrev_b64 v[18:19], 9, v[18:19]
	v_lshl_add_u64 v[18:19], v[2:3], 0, v[18:19]
	s_waitcnt lgkmcnt(0)
	v_cvt_pk_bf16_f32 v15, v16, s0
	v_add_u32_e32 v16, s15, v8
	global_store_short v[18:19], v15, off
	v_cvt_pk_bf16_f32 v15, v17, s0
	v_ashrrev_i32_e32 v17, 31, v16
	v_lshlrev_b64 v[16:17], 9, v[16:17]
	v_lshl_add_u64 v[16:17], v[2:3], 0, v[16:17]
	global_store_short v[16:17], v15, off
	ds_read2_b32 v[16:17], v13 offset0:32 offset1:40
	v_add_u32_e32 v18, s15, v9
	v_ashrrev_i32_e32 v19, 31, v18
	v_lshlrev_b64 v[18:19], 9, v[18:19]
	v_lshl_add_u64 v[18:19], v[2:3], 0, v[18:19]
	s_waitcnt lgkmcnt(0)
	v_cvt_pk_bf16_f32 v15, v16, s0
	v_add_u32_e32 v16, s15, v10
	global_store_short v[18:19], v15, off
	v_cvt_pk_bf16_f32 v15, v17, s0
	v_ashrrev_i32_e32 v17, 31, v16
	v_lshlrev_b64 v[16:17], 9, v[16:17]
	v_lshl_add_u64 v[16:17], v[2:3], 0, v[16:17]
	global_store_short v[16:17], v15, off
	ds_read2_b32 v[16:17], v13 offset0:48 offset1:56
	v_add_u32_e32 v18, s15, v11
	v_ashrrev_i32_e32 v19, 31, v18
	v_lshlrev_b64 v[18:19], 9, v[18:19]
	v_lshl_add_u64 v[18:19], v[2:3], 0, v[18:19]
	s_waitcnt lgkmcnt(0)
	v_cvt_pk_bf16_f32 v15, v16, s0
	v_add_u32_e32 v16, s15, v12
	global_store_short v[18:19], v15, off
	v_cvt_pk_bf16_f32 v15, v17, s0
	v_ashrrev_i32_e32 v17, 31, v16
	v_lshlrev_b64 v[16:17], 9, v[16:17]
	s_add_i32 s3, s3, s4
	s_add_i32 s5, s5, s14
	v_lshl_add_u64 v[2:3], v[2:3], 0, v[16:17]
	s_cmp_lt_i32 s3, 64
	global_store_short v[2:3], v15, off
	s_waitcnt lgkmcnt(0)
	s_barrier
	s_cbranch_scc0 .LBB0_1449

; DEVI u16 f2bf(float f) { return (u16)(pack2(f, 0.f) & 0xffffu); }
;     ...
;   for (int t = bid_; t < tk * tn; t += nb_) {
;     const int k0 = (t % tk) * 64, n0 = (t / tk) * 64;
;     {
;       const int nn = tid & 63;
;       const int src = mapcol(map, n0 + nn);
;       const bool valid = src < Nsrc;
; #pragma unroll
;       for (int i = 0; i < 8; ++i) {
;         const int kk = (tid >> 6) + 8 * i;
;         tile[kk * 65 + nn] = valid ? W[(size_t)(k0 + kk) * Nsrc + src] * (gain ? gain[k0 + kk] : 1.f) : 0.f;
;       }
;     }
;     __syncthreads();
;     {
;       const int kk = tid & 63;
; #pragma unroll
;       for (int i = 0; i < 8; ++i) {
;         const int nn = (tid >> 6) + 8 * i;
;         dst[(size_t)(n0 + nn) * K + k0 + kk] = f2bf(tile[kk * 65 + nn]);
;       }
;     }
;     __syncthreads();
;   }
.LBB0_1456:
	s_or_b64 exec, exec, s[4:5]
	ds_write_b32 v16, v4 offset:14560
	s_waitcnt lgkmcnt(0)
	s_barrier
	ds_read2_b32 v[4:5], v15 offset1:8
	s_add_i32 s0, s22, s80
	v_add_u32_e32 v18, s44, v7
	s_ashr_i32 s1, s0, 31
	v_ashrrev_i32_e32 v19, 31, v18
	v_lshl_add_u64 v[2:3], s[0:1], 1, v[0:1]
	v_lshlrev_b64 v[18:19], 11, v[18:19]
	s_waitcnt lgkmcnt(0)
	v_cvt_pk_bf16_f32 v4, v4, s0
	v_lshl_add_u64 v[18:19], v[2:3], 0, v[18:19]
	global_store_short v[18:19], v4, off
	v_add_u32_e32 v4, s44, v8
	v_cvt_pk_bf16_f32 v17, v5, s0
	v_ashrrev_i32_e32 v5, 31, v4
	v_lshlrev_b64 v[4:5], 11, v[4:5]
	v_lshl_add_u64 v[4:5], v[2:3], 0, v[4:5]
	global_store_short v[4:5], v17, off
	ds_read2_b32 v[4:5], v15 offset0:16 offset1:24
	v_add_u32_e32 v18, s44, v9
	v_ashrrev_i32_e32 v19, 31, v18
	v_lshlrev_b64 v[18:19], 11, v[18:19]
	v_lshl_add_u64 v[18:19], v[2:3], 0, v[18:19]
	s_waitcnt lgkmcnt(0)
	v_cvt_pk_bf16_f32 v4, v4, s0
	global_store_short v[18:19], v4, off
	v_add_u32_e32 v4, s44, v10
	v_cvt_pk_bf16_f32 v17, v5, s0
	v_ashrrev_i32_e32 v5, 31, v4
	v_lshlrev_b64 v[4:5], 11, v[4:5]
	v_lshl_add_u64 v[4:5], v[2:3], 0, v[4:5]
	global_store_short v[4:5], v17, off
	ds_read2_b32 v[4:5], v15 offset0:32 offset1:40
	v_add_u32_e32 v18, s44, v11
	v_ashrrev_i32_e32 v19, 31, v18
	v_lshlrev_b64 v[18:19], 11, v[18:19]
	v_lshl_add_u64 v[18:19], v[2:3], 0, v[18:19]
	s_waitcnt lgkmcnt(0)
	v_cvt_pk_bf16_f32 v4, v4, s0
	global_store_short v[18:19], v4, off
	v_add_u32_e32 v4, s44, v12
	v_cvt_pk_bf16_f32 v17, v5, s0
	v_ashrrev_i32_e32 v5, 31, v4
	v_lshlrev_b64 v[4:5], 11, v[4:5]
	v_lshl_add_u64 v[4:5], v[2:3], 0, v[4:5]
	global_store_short v[4:5], v17, off
	ds_read2_b32 v[4:5], v15 offset0:48 offset1:56
	v_add_u32_e32 v18, s44, v13
	v_ashrrev_i32_e32 v19, 31, v18
	v_lshlrev_b64 v[18:19], 11, v[18:19]
	v_lshl_add_u64 v[18:19], v[2:3], 0, v[18:19]
	s_waitcnt lgkmcnt(0)
	v_cvt_pk_bf16_f32 v4, v4, s0
	global_store_short v[18:19], v4, off
	v_add_u32_e32 v4, s44, v14
	v_cvt_pk_bf16_f32 v17, v5, s0
	v_ashrrev_i32_e32 v5, 31, v4
	v_lshlrev_b64 v[4:5], 11, v[4:5]
	s_add_i32 s3, s3, s31
	s_add_i32 s22, s22, s23
	v_lshl_add_u64 v[2:3], v[2:3], 0, v[4:5]
	s_cmpk_lt_i32 s3, 0x100
	global_store_short v[2:3], v17, off
	s_waitcnt lgkmcnt(0)
	s_barrier
	s_cbranch_scc0 .LBB0_1488

; DEVI u16 f2bf(float f) { return (u16)(pack2(f, 0.f) & 0xffffu); }
;     ...
;   for (int t = bid_; t < tk * tn; t += nb_) {
;     const int k0 = (t % tk) * 64, n0 = (t / tk) * 64;
;     {
;       const int nn = tid & 63;
;       const int src = mapcol(map, n0 + nn);
;       const bool valid = src < Nsrc;
; #pragma unroll
;       for (int i = 0; i < 8; ++i) {
;         const int kk = (tid >> 6) + 8 * i;
;         tile[kk * 65 + nn] = valid ? W[(size_t)(k0 + kk) * Nsrc + src] * (gain ? gain[k0 + kk] : 1.f) : 0.f;
;       }
;     }
;     __syncthreads();
;     {
;       const int kk = tid & 63;
; #pragma unroll
;       for (int i = 0; i < 8; ++i) {
;         const int nn = (tid >> 6) + 8 * i;
;         dst[(size_t)(n0 + nn) * K + k0 + kk] = f2bf(tile[kk * 65 + nn]);
;       }
;     }
;     __syncthreads();
;   }
.LBB0_1494:
	s_or_b64 exec, exec, s[4:5]
	s_waitcnt vmcnt(1)
	ds_write_b32 v14, v15 offset:12480
	s_waitcnt vmcnt(0)
	ds_write_b32 v14, v16 offset:14560
	s_waitcnt lgkmcnt(0)
	s_barrier
	ds_read2_b32 v[16:17], v13 offset1:8
	s_add_i32 s4, s13, s16
	v_add_u32_e32 v18, s15, v5
	s_ashr_i32 s5, s4, 31
	v_ashrrev_i32_e32 v19, 31, v18
	v_lshl_add_u64 v[2:3], s[4:5], 1, v[0:1]
	v_lshlrev_b64 v[18:19], 9, v[18:19]
	s_waitcnt lgkmcnt(0)
	v_cvt_pk_bf16_f32 v15, v16, s0
	v_lshl_add_u64 v[18:19], v[2:3], 0, v[18:19]
	v_add_u32_e32 v16, s15, v6
	global_store_short v[18:19], v15, off
	v_cvt_pk_bf16_f32 v15, v17, s0
	v_ashrrev_i32_e32 v17, 31, v16
	v_lshlrev_b64 v[16:17], 9, v[16:17]
	v_lshl_add_u64 v[16:17], v[2:3], 0, v[16:17]
	global_store_short v[16:17], v15, off
	ds_read2_b32 v[16:17], v13 offset0:16 offset1:24
	v_add_u32_e32 v18, s15, v7
	v_ashrrev_i32_e32 v19, 31, v18
	v_lshlrev_b64 v[18:19], 9, v[18:19]
	v_lshl_add_u64 v[18:19], v[2:3], 0, v[18:19]
	s_waitcnt lgkmcnt(0)
	v_cvt_pk_bf16_f32 v15, v16, s0
	v_add_u32_e32 v16, s15, v8
	global_store_short v[18:19], v15, off
	v_cvt_pk_bf16_f32 v15, v17, s0
	v_ashrrev_i32_e32 v17, 31, v16
	v_lshlrev_b64 v[16:17], 9, v[16:17]
	v_lshl_add_u64 v[16:17], v[2:3], 0, v[16:17]
	global_store_short v[16:17], v15, off
	ds_read2_b32 v[16:17], v13 offset0:32 offset1:40
	v_add_u32_e32 v18, s15, v9
	v_ashrrev_i32_e32 v19, 31, v18
	v_lshlrev_b64 v[18:19], 9, v[18:19]
	v_lshl_add_u64 v[18:19], v[2:3], 0, v[18:19]
	s_waitcnt lgkmcnt(0)
	v_cvt_pk_bf16_f32 v15, v16, s0
	v_add_u32_e32 v16, s15, v10
	global_store_short v[18:19], v15, off
	v_cvt_pk_bf16_f32 v15, v17, s0
	v_ashrrev_i32_e32 v17, 31, v16
	v_lshlrev_b64 v[16:17], 9, v[16:17]
	v_lshl_add_u64 v[16:17], v[2:3], 0, v[16:17]
	global_store_short v[16:17], v15, off
	ds_read2_b32 v[16:17], v13 offset0:48 offset1:56
	v_add_u32_e32 v18, s15, v11
	v_ashrrev_i32_e32 v19, 31, v18
	v_lshlrev_b64 v[18:19], 9, v[18:19]
	v_lshl_add_u64 v[18:19], v[2:3], 0, v[18:19]
	s_waitcnt lgkmcnt(0)
	v_cvt_pk_bf16_f32 v15, v16, s0
	v_add_u32_e32 v16, s15, v12
	global_store_short v[18:19], v15, off
	v_cvt_pk_bf16_f32 v15, v17, s0
	v_ashrrev_i32_e32 v17, 31, v16
	v_lshlrev_b64 v[16:17], 9, v[16:17]
	s_add_i32 s3, s3, s12
	s_add_i32 s13, s13, s14
	v_lshl_add_u64 v[2:3], v[2:3], 0, v[16:17]
	s_cmp_lt_i32 s3, 64
	global_store_short v[2:3], v15, off
	s_waitcnt lgkmcnt(0)
	s_barrier
	s_cbranch_scc0 .LBB0_1503

; DEVI u16 f2bf(float f) { return (u16)(pack2(f, 0.f) & 0xffffu); }
;     ...
;   for (int t = bid_; t < tk * tn; t += nb_) {
;     const int k0 = (t % tk) * 64, n0 = (t / tk) * 64;
;     {
;       const int nn = tid & 63;
;       const int src = mapcol(map, n0 + nn);
;       const bool valid = src < Nsrc;
; #pragma unroll
;       for (int i = 0; i < 8; ++i) {
;         const int kk = (tid >> 6) + 8 * i;
;         tile[kk * 65 + nn] = valid ? W[(size_t)(k0 + kk) * Nsrc + src] * (gain ? gain[k0 + kk] : 1.f) : 0.f;
;       }
;     }
;     __syncthreads();
;     {
;       const int kk = tid & 63;
; #pragma unroll
;       for (int i = 0; i < 8; ++i) {
;         const int nn = (tid >> 6) + 8 * i;
;         dst[(size_t)(n0 + nn) * K + k0 + kk] = f2bf(tile[kk * 65 + nn]);
;       }
;     }
;     __syncthreads();
;   }
.LBB0_1509:
	s_or_b64 exec, exec, s[0:1]
	s_waitcnt vmcnt(1)
	ds_write_b32 v14, v15 offset:12480
	s_waitcnt vmcnt(0)
	ds_write_b32 v14, v16 offset:14560
	s_waitcnt lgkmcnt(0)
	s_barrier
	ds_read2_b32 v[16:17], v13 offset1:8
	s_add_i32 s0, s5, s14
	v_add_u32_e32 v18, s13, v5
	s_ashr_i32 s1, s0, 31
	v_ashrrev_i32_e32 v19, 31, v18
	v_lshl_add_u64 v[2:3], s[0:1], 1, v[0:1]
	v_lshlrev_b64 v[18:19], 11, v[18:19]
	s_waitcnt lgkmcnt(0)
	v_cvt_pk_bf16_f32 v15, v16, s0
	v_lshl_add_u64 v[18:19], v[2:3], 0, v[18:19]
	v_add_u32_e32 v16, s13, v6
	global_store_short v[18:19], v15, off
	v_cvt_pk_bf16_f32 v15, v17, s0
	v_ashrrev_i32_e32 v17, 31, v16
	v_lshlrev_b64 v[16:17], 11, v[16:17]
	v_lshl_add_u64 v[16:17], v[2:3], 0, v[16:17]
	global_store_short v[16:17], v15, off
	ds_read2_b32 v[16:17], v13 offset0:16 offset1:24
	v_add_u32_e32 v18, s13, v7
	v_ashrrev_i32_e32 v19, 31, v18
	v_lshlrev_b64 v[18:19], 11, v[18:19]
	v_lshl_add_u64 v[18:19], v[2:3], 0, v[18:19]
	s_waitcnt lgkmcnt(0)
	v_cvt_pk_bf16_f32 v15, v16, s0
	v_add_u32_e32 v16, s13, v8
	global_store_short v[18:19], v15, off
	v_cvt_pk_bf16_f32 v15, v17, s0
	v_ashrrev_i32_e32 v17, 31, v16
	v_lshlrev_b64 v[16:17], 11, v[16:17]
	v_lshl_add_u64 v[16:17], v[2:3], 0, v[16:17]
	global_store_short v[16:17], v15, off
	ds_read2_b32 v[16:17], v13 offset0:32 offset1:40
	v_add_u32_e32 v18, s13, v9
	v_ashrrev_i32_e32 v19, 31, v18
	v_lshlrev_b64 v[18:19], 11, v[18:19]
	v_lshl_add_u64 v[18:19], v[2:3], 0, v[18:19]
	s_waitcnt lgkmcnt(0)
	v_cvt_pk_bf16_f32 v15, v16, s0
	v_add_u32_e32 v16, s13, v10
	global_store_short v[18:19], v15, off
	v_cvt_pk_bf16_f32 v15, v17, s0
	v_ashrrev_i32_e32 v17, 31, v16
	v_lshlrev_b64 v[16:17], 11, v[16:17]
	v_lshl_add_u64 v[16:17], v[2:3], 0, v[16:17]
	global_store_short v[16:17], v15, off
	ds_read2_b32 v[16:17], v13 offset0:48 offset1:56
	v_add_u32_e32 v18, s13, v11
	v_ashrrev_i32_e32 v19, 31, v18
	v_lshlrev_b64 v[18:19], 11, v[18:19]
	v_lshl_add_u64 v[18:19], v[2:3], 0, v[18:19]
	s_waitcnt lgkmcnt(0)
	v_cvt_pk_bf16_f32 v15, v16, s0
	v_add_u32_e32 v16, s13, v12
	global_store_short v[18:19], v15, off
	v_cvt_pk_bf16_f32 v15, v17, s0
	v_ashrrev_i32_e32 v17, 31, v16
	v_lshlrev_b64 v[16:17], 11, v[16:17]
	s_add_i32 s3, s3, s4
	s_add_i32 s5, s5, s12
	v_lshl_add_u64 v[2:3], v[2:3], 0, v[16:17]
	s_cmpk_lt_i32 s3, 0x100
	global_store_short v[2:3], v15, off
	s_waitcnt lgkmcnt(0)
	s_barrier
	s_cbranch_scc0 .LBB0_1518

; DEVI u16 f2bf(float f) { return (u16)(pack2(f, 0.f) & 0xffffu); }
;     ...
;   for (int t = bid_; t < tk * tn; t += nb_) {
;     const int k0 = (t % tk) * 64, n0 = (t / tk) * 64;
;     {
;       const int nn = tid & 63;
;       const int src = mapcol(map, n0 + nn);
;       const bool valid = src < Nsrc;
; #pragma unroll
;       for (int i = 0; i < 8; ++i) {
;         const int kk = (tid >> 6) + 8 * i;
;         tile[kk * 65 + nn] = valid ? W[(size_t)(k0 + kk) * Nsrc + src] * (gain ? gain[k0 + kk] : 1.f) : 0.f;
;       }
;     }
;     __syncthreads();
;     {
;       const int kk = tid & 63;
; #pragma unroll
;       for (int i = 0; i < 8; ++i) {
;         const int nn = (tid >> 6) + 8 * i;
;         dst[(size_t)(n0 + nn) * K + k0 + kk] = f2bf(tile[kk * 65 + nn]);
;       }
;     }
;     __syncthreads();
;   }
.LBB0_1524:
	s_or_b64 exec, exec, s[4:5]
	ds_write_b32 v16, v4 offset:12480
	ds_write_b32 v16, v5 offset:14560
	s_waitcnt lgkmcnt(0)
	s_barrier
	ds_read2_b32 v[4:5], v15 offset1:8
	s_add_i32 s4, s13, s16
	v_add_u32_e32 v18, s15, v7
	s_ashr_i32 s5, s4, 31
	v_ashrrev_i32_e32 v19, 31, v18
	v_lshl_add_u64 v[2:3], s[4:5], 1, v[0:1]
	v_lshlrev_b64 v[18:19], 11, v[18:19]
	s_waitcnt lgkmcnt(0)
	v_cvt_pk_bf16_f32 v4, v4, s0
	v_lshl_add_u64 v[18:19], v[2:3], 0, v[18:19]
	global_store_short v[18:19], v4, off
	v_add_u32_e32 v4, s15, v8
	v_cvt_pk_bf16_f32 v17, v5, s0
	v_ashrrev_i32_e32 v5, 31, v4
	v_lshlrev_b64 v[4:5], 11, v[4:5]
	v_lshl_add_u64 v[4:5], v[2:3], 0, v[4:5]
	global_store_short v[4:5], v17, off
	ds_read2_b32 v[4:5], v15 offset0:16 offset1:24
	v_add_u32_e32 v18, s15, v9
	v_ashrrev_i32_e32 v19, 31, v18
	v_lshlrev_b64 v[18:19], 11, v[18:19]
	v_lshl_add_u64 v[18:19], v[2:3], 0, v[18:19]
	s_waitcnt lgkmcnt(0)
	v_cvt_pk_bf16_f32 v4, v4, s0
	global_store_short v[18:19], v4, off
	v_add_u32_e32 v4, s15, v10
	v_cvt_pk_bf16_f32 v17, v5, s0
	v_ashrrev_i32_e32 v5, 31, v4
	v_lshlrev_b64 v[4:5], 11, v[4:5]
	v_lshl_add_u64 v[4:5], v[2:3], 0, v[4:5]
	global_store_short v[4:5], v17, off
	ds_read2_b32 v[4:5], v15 offset0:32 offset1:40
	v_add_u32_e32 v18, s15, v11
	v_ashrrev_i32_e32 v19, 31, v18
	v_lshlrev_b64 v[18:19], 11, v[18:19]
	v_lshl_add_u64 v[18:19], v[2:3], 0, v[18:19]
	s_waitcnt lgkmcnt(0)
	v_cvt_pk_bf16_f32 v4, v4, s0
	global_store_short v[18:19], v4, off
	v_add_u32_e32 v4, s15, v12
	v_cvt_pk_bf16_f32 v17, v5, s0
	v_ashrrev_i32_e32 v5, 31, v4
	v_lshlrev_b64 v[4:5], 11, v[4:5]
	v_lshl_add_u64 v[4:5], v[2:3], 0, v[4:5]
	global_store_short v[4:5], v17, off
	ds_read2_b32 v[4:5], v15 offset0:48 offset1:56
	v_add_u32_e32 v18, s15, v13
	v_ashrrev_i32_e32 v19, 31, v18
	v_lshlrev_b64 v[18:19], 11, v[18:19]
	v_lshl_add_u64 v[18:19], v[2:3], 0, v[18:19]
	s_waitcnt lgkmcnt(0)
	v_cvt_pk_bf16_f32 v4, v4, s0
	global_store_short v[18:19], v4, off
	v_add_u32_e32 v4, s15, v14
	v_cvt_pk_bf16_f32 v17, v5, s0
	v_ashrrev_i32_e32 v5, 31, v4
	v_lshlrev_b64 v[4:5], 11, v[4:5]
	s_add_i32 s3, s3, s12
	s_add_i32 s13, s13, s14
	v_lshl_add_u64 v[2:3], v[2:3], 0, v[4:5]
	s_cmpk_lt_i32 s3, 0xc0
	global_store_short v[2:3], v17, off
	s_waitcnt lgkmcnt(0)
	s_barrier
	s_cbranch_scc0 .LBB0_1533

; DEVI u16 f2bf(float f) { return (u16)(pack2(f, 0.f) & 0xffffu); }
;     ...
;   for (int t = bid_; t < tk * tn; t += nb_) {
;     const int k0 = (t % tk) * 64, n0 = (t / tk) * 64;
;     {
;       const int nn = tid & 63;
;       const int src = mapcol(map, n0 + nn);
;       const bool valid = src < Nsrc;
; #pragma unroll
;       for (int i = 0; i < 8; ++i) {
;         const int kk = (tid >> 6) + 8 * i;
;         tile[kk * 65 + nn] = valid ? W[(size_t)(k0 + kk) * Nsrc + src] * (gain ? gain[k0 + kk] : 1.f) : 0.f;
;       }
;     }
;     __syncthreads();
;     {
;       const int kk = tid & 63;
; #pragma unroll
;       for (int i = 0; i < 8; ++i) {
;         const int nn = (tid >> 6) + 8 * i;
;         dst[(size_t)(n0 + nn) * K + k0 + kk] = f2bf(tile[kk * 65 + nn]);
;       }
;     }
;     __syncthreads();
;   }
.LBB0_1540:
	s_or_b64 exec, exec, s[4:5]
	ds_write_b32 v19, v7 offset:14560
	s_waitcnt lgkmcnt(0)
	s_barrier
	ds_read2_b32 v[6:7], v18 offset1:8
	s_ashr_i32 s15, s14, 31
	v_lshl_add_u64 v[4:5], s[14:15], 1, v[2:3]
	v_add_u32_e32 v8, s21, v0
	s_movk_i32 s4, 0x300
	s_waitcnt lgkmcnt(0)
	v_cvt_pk_bf16_f32 v6, v6, s0
	v_mad_i64_i32 v[8:9], s[0:1], v8, s4, v[4:5]
	global_store_short v[8:9], v6, off
	v_add_u32_e32 v6, s21, v11
	v_cvt_pk_bf16_f32 v8, v7, s0
	v_mad_i64_i32 v[6:7], s[0:1], v6, s4, v[4:5]
	global_store_short v[6:7], v8, off
	ds_read2_b32 v[6:7], v18 offset0:16 offset1:24
	v_add_u32_e32 v8, s21, v12
	s_add_i32 s3, s3, s18
	s_add_i32 s19, s19, s20
	s_cmpk_lt_i32 s3, 0x90
	s_waitcnt lgkmcnt(0)
	v_cvt_pk_bf16_f32 v6, v6, s0
	v_mad_i64_i32 v[8:9], s[0:1], v8, s4, v[4:5]
	global_store_short v[8:9], v6, off
	v_add_u32_e32 v6, s21, v13
	v_cvt_pk_bf16_f32 v8, v7, s0
	v_mad_i64_i32 v[6:7], s[0:1], v6, s4, v[4:5]
	global_store_short v[6:7], v8, off
	ds_read2_b32 v[6:7], v18 offset0:32 offset1:40
	v_add_u32_e32 v8, s21, v14
	s_waitcnt lgkmcnt(0)
	v_cvt_pk_bf16_f32 v6, v6, s0
	v_mad_i64_i32 v[8:9], s[0:1], v8, s4, v[4:5]
	global_store_short v[8:9], v6, off
	v_add_u32_e32 v6, s21, v15
	v_cvt_pk_bf16_f32 v8, v7, s0
	v_mad_i64_i32 v[6:7], s[0:1], v6, s4, v[4:5]
	global_store_short v[6:7], v8, off
	ds_read2_b32 v[6:7], v18 offset0:48 offset1:56
	v_add_u32_e32 v8, s21, v16
	s_waitcnt lgkmcnt(0)
	v_cvt_pk_bf16_f32 v6, v6, s0
	v_mad_i64_i32 v[8:9], s[0:1], v8, s4, v[4:5]
	global_store_short v[8:9], v6, off
	s_nop 0
	v_cvt_pk_bf16_f32 v6, v7, s0
	v_add_u32_e32 v7, s21, v17
	v_mad_i64_i32 v[4:5], s[0:1], v7, s4, v[4:5]
	global_store_short v[4:5], v6, off
	s_waitcnt lgkmcnt(0)
	s_barrier
	s_cbranch_scc0 .LBB0_1580

; DEVI u16 f2bf(float f) { return (u16)(pack2(f, 0.f) & 0xffffu); }
;     ...
;   for (int t = bid_; t < tk * tn; t += nb_) {
;     const int k0 = (t % tk) * 64, n0 = (t / tk) * 64;
;     {
;       const int nn = tid & 63;
;       const int src = mapcol(map, n0 + nn);
;       const bool valid = src < Nsrc;
; #pragma unroll
;       for (int i = 0; i < 8; ++i) {
;         const int kk = (tid >> 6) + 8 * i;
;         tile[kk * 65 + nn] = valid ? W[(size_t)(k0 + kk) * Nsrc + src] * (gain ? gain[k0 + kk] : 1.f) : 0.f;
;       }
;     }
;     __syncthreads();
;     {
;       const int kk = tid & 63;
; #pragma unroll
;       for (int i = 0; i < 8; ++i) {
;         const int nn = (tid >> 6) + 8 * i;
;         dst[(size_t)(n0 + nn) * K + k0 + kk] = f2bf(tile[kk * 65 + nn]);
;       }
;     }
;     __syncthreads();
;   }
.LBB0_1586:
	s_waitcnt vmcnt(0)
	v_mul_f32_e32 v2, v2, v7
	ds_write_b32 v18, v2 offset:14560
	s_waitcnt lgkmcnt(0)
	s_barrier
	ds_read2_b32 v[4:5], v17 offset1:8
	s_sub_i32 s0, 0, s16
	s_add_i32 s0, s13, s0
	v_add_u32_e32 v6, s15, v9
	s_ashr_i32 s1, s0, 31
	v_ashrrev_i32_e32 v7, 31, v6
	v_lshl_add_u64 v[2:3], s[0:1], 1, v[0:1]
	v_lshlrev_b64 v[6:7], 9, v[6:7]
	s_waitcnt lgkmcnt(0)
	v_cvt_pk_bf16_f32 v4, v4, s0
	v_lshl_add_u64 v[6:7], v[2:3], 0, v[6:7]
	global_store_short v[6:7], v4, off
	v_add_u32_e32 v4, s15, v10
	v_cvt_pk_bf16_f32 v6, v5, s0
	v_ashrrev_i32_e32 v5, 31, v4
	v_lshlrev_b64 v[4:5], 9, v[4:5]
	v_lshl_add_u64 v[4:5], v[2:3], 0, v[4:5]
	global_store_short v[4:5], v6, off
	ds_read2_b32 v[4:5], v17 offset0:16 offset1:24
	v_add_u32_e32 v6, s15, v11
	v_ashrrev_i32_e32 v7, 31, v6
	v_lshlrev_b64 v[6:7], 9, v[6:7]
	v_lshl_add_u64 v[6:7], v[2:3], 0, v[6:7]
	s_waitcnt lgkmcnt(0)
	v_cvt_pk_bf16_f32 v4, v4, s0
	global_store_short v[6:7], v4, off
	v_add_u32_e32 v4, s15, v12
	v_cvt_pk_bf16_f32 v6, v5, s0
	v_ashrrev_i32_e32 v5, 31, v4
	v_lshlrev_b64 v[4:5], 9, v[4:5]
	v_lshl_add_u64 v[4:5], v[2:3], 0, v[4:5]
	global_store_short v[4:5], v6, off
	ds_read2_b32 v[4:5], v17 offset0:32 offset1:40
	v_add_u32_e32 v6, s15, v13
	v_ashrrev_i32_e32 v7, 31, v6
	v_lshlrev_b64 v[6:7], 9, v[6:7]
	v_lshl_add_u64 v[6:7], v[2:3], 0, v[6:7]
	s_waitcnt lgkmcnt(0)
	v_cvt_pk_bf16_f32 v4, v4, s0
	global_store_short v[6:7], v4, off
	v_add_u32_e32 v4, s15, v14
	v_cvt_pk_bf16_f32 v6, v5, s0
	v_ashrrev_i32_e32 v5, 31, v4
	v_lshlrev_b64 v[4:5], 9, v[4:5]
	v_lshl_add_u64 v[4:5], v[2:3], 0, v[4:5]
	global_store_short v[4:5], v6, off
	ds_read2_b32 v[4:5], v17 offset0:48 offset1:56
	v_add_u32_e32 v6, s15, v15
	v_ashrrev_i32_e32 v7, 31, v6
	v_lshlrev_b64 v[6:7], 9, v[6:7]
	v_lshl_add_u64 v[6:7], v[2:3], 0, v[6:7]
	s_waitcnt lgkmcnt(0)
	v_cvt_pk_bf16_f32 v4, v4, s0
	global_store_short v[6:7], v4, off
	v_add_u32_e32 v4, s15, v16
	v_cvt_pk_bf16_f32 v6, v5, s0
	v_ashrrev_i32_e32 v5, 31, v4
	v_lshlrev_b64 v[4:5], 9, v[4:5]
	s_add_i32 s3, s3, s12
	s_add_i32 s13, s13, s14
	v_lshl_add_u64 v[2:3], v[2:3], 0, v[4:5]
	s_cmpk_lt_i32 s3, 0x80
	global_store_short v[2:3], v6, off
	s_waitcnt lgkmcnt(0)
	s_barrier
	s_cbranch_scc0 .LBB0_1603

;     ...
;   for (int e = gt; e < 4096 * 32; e += nb_ * NTHR) {
;     const int pos = e >> 5, i = e & 31;
;     const float invf = __builtin_amdgcn_exp2f(-(float)i * 0.41524101186092029f);
;     float rev = ((float)pos * invf) * 0.15915494309189535f;
;     rev -= rintf(rev);
;     const float s = __builtin_amdgcn_sinf(rev), c = __builtin_amdgcn_cosf(rev);
;     ct[e] = c;
;     sn[e] = s;
;   }
.LBB0_1624:
	v_ashrrev_i32_e32 v1, 5, v0
	v_cvt_f32_i32_e32 v1, v1
	v_add_co_u32_e32 v6, vcc, 0xfff80000, v2
	v_add_u32_e32 v0, s4, v0
	v_mul_f32_e32 v1, v4, v1
	v_mul_f32_e32 v5, 0.15915494, v1
	v_rndne_f32_e32 v5, v5
	v_fma_f32 v1, v1, 0.15915494, -v5
	v_sin_f32_e32 v5, v1
	v_cos_f32_e32 v1, v1
	v_addc_co_u32_e32 v7, vcc, -1, v3, vcc
	s_mov_b32 s3, 0x1ffff
	v_cmp_lt_i32_e32 vcc, s3, v0
	global_store_dword v[6:7], v1, off
	global_store_dword v[2:3], v5, off
	v_lshl_add_u64 v[2:3], v[2:3], 0, s[6:7]
	s_or_b64 s[12:13], vcc, s[12:13]
	s_andn2_b64 exec, exec, s[12:13]
	s_cbranch_execnz .LBB0_1624

; DEVI void pconv_phase(int wv, const Params& p, const float* p_prompt, const float* p_sample, int layer, int b0, int bn) {
;     ...
;   for (size_t e = (size_t)b0 * NTHR + otid(wv); e < n4; e += (size_t)bn * NTHR) {
;     const float4 v = e < np4 ? ((const float4*)pp)[e] : ((const float4*)ps)[e - np4];
;     uint2 o;
;     o.x = pack2(v.x, v.y);
;     o.y = pack2(v.z, v.w);
;     ((uint2*)PB)[e] = o;
;   }
.LBB0_1627:
	v_cmp_gt_u64_e32 vcc, s[20:21], v[0:1]
	v_lshl_add_u64 v[6:7], s[8:9], 0, v[2:3]
	v_lshl_add_u64 v[8:9], s[12:13], 0, v[2:3]
	v_cndmask_b32_e32 v7, v9, v7, vcc
	v_cndmask_b32_e32 v6, v8, v6, vcc
	global_load_dwordx4 v[6:9], v[6:7], off
	v_lshl_add_u64 v[0:1], v[0:1], 0, s[6:7]
	v_lshl_add_u64 v[2:3], v[2:3], 0, s[14:15]
	s_waitcnt vmcnt(0)
	v_cvt_pk_bf16_f32 v6, v6, v7
	v_cvt_pk_bf16_f32 v7, v8, v9
	v_add_co_u32_e32 v8, vcc, -4, v4
	s_nop 1
	v_addc_co_u32_e32 v9, vcc, -1, v5, vcc
	v_cmp_lt_u64_e32 vcc, s[22:23], v[0:1]
	v_lshl_add_u64 v[4:5], v[4:5], 0, s[16:17]
	s_or_b64 s[18:19], vcc, s[18:19]
	global_store_dwordx2 v[8:9], v[6:7], off
	s_andn2_b64 exec, exec, s[18:19]
	s_cbranch_execnz .LBB0_1627

; DEVI void pconv_phase(int wv, const Params& p, const float* p_prompt, const float* p_sample, int layer, int b0, int bn) {
;     ...
;   for (size_t e = (size_t)b0 * NTHR + otid(wv); e < n4; e += (size_t)bn * NTHR) {
;     const float4 v = e < np4 ? ((const float4*)pp)[e] : ((const float4*)ps)[e - np4];
;     uint2 o;
;     o.x = pack2(v.x, v.y);
;     o.y = pack2(v.z, v.w);
;     ((uint2*)PB)[e] = o;
;   }
.LBB0_1630:
	v_cmp_gt_u64_e32 vcc, s[16:17], v[0:1]
	v_lshl_add_u64 v[6:7], s[4:5], 0, v[2:3]
	v_lshl_add_u64 v[8:9], s[8:9], 0, v[2:3]
	v_cndmask_b32_e32 v7, v9, v7, vcc
	v_cndmask_b32_e32 v6, v8, v6, vcc
	global_load_dwordx4 v[6:9], v[6:7], off
	v_lshl_add_u64 v[0:1], v[0:1], 0, s[6:7]
	v_lshl_add_u64 v[2:3], v[2:3], 0, s[10:11]
	s_waitcnt vmcnt(0)
	v_cvt_pk_bf16_f32 v6, v6, v7
	v_cvt_pk_bf16_f32 v7, v8, v9
	v_add_co_u32_e32 v8, vcc, -4, v4
	s_nop 1
	v_addc_co_u32_e32 v9, vcc, -1, v5, vcc
	v_cmp_lt_u64_e32 vcc, s[18:19], v[0:1]
	v_lshl_add_u64 v[4:5], v[4:5], 0, s[2:3]
	s_or_b64 s[12:13], vcc, s[12:13]
	global_store_dwordx2 v[8:9], v[6:7], off
	s_andn2_b64 exec, exec, s[12:13]
	s_cbranch_execnz .LBB0_1630

; DEVI float bflo(unsigned u) { return __uint_as_float(u << 16); }
; DEVI float bfhi(unsigned u) { return __uint_as_float(u & 0xffff0000u); }
; DEVI float sxor(float v, int mask, int lane) { return __int_as_float(__builtin_amdgcn_ds_bpermute((lane ^ mask) << 2, __float_as_int(v))); }
; DEVI int onb() { int t = gridDim.x; asm volatile("" : "+s"(t)); return t; }
; DEVI int obid() { int t = blockIdx.x; asm volatile("" : "+s"(t)); return t; }
; DEVI void gla_out_phase(int wv, const Params& p) {
;     ...
;   for (int row = obid() * 8 + wave; row < MTOK; row += onb() * 8) {
;     const size_t base = (size_t)row * 1024 + (lane >> 4) * 256 + d0;
;     float o[16];
;     float ss = 0.f;
; #pragma unroll
;     for (int h2 = 0; h2 < 2; ++h2) {
;       const uint4 a = *(const uint4*)(OF + base + h2 * 8);
;       const uint4 b = *(const uint4*)(OB + base + h2 * 8);
;       const unsigned aa[4] = {a.x, a.y, a.z, a.w}, bb[4] = {b.x, b.y, b.z, b.w};
; #pragma unroll
;       for (int q = 0; q < 4; ++q) {
;         o[h2 * 8 + 2 * q] = bflo(aa[q]) + bflo(bb[q]);
;         o[h2 * 8 + 2 * q + 1] = bfhi(aa[q]) + bfhi(bb[q]);
;       }
;     }
; #pragma unroll
;     for (int i = 0; i < 16; ++i) ss += o[i] * o[i];
;     ss += sxor(ss, 1, lane);
;     ss += sxor(ss, 2, lane);
;     ss += sxor(ss, 4, lane);
;     ss += sxor(ss, 8, lane);
.LBB0_1643:
	v_ashrrev_i32_e32 v13, 31, v12
	v_lshlrev_b64 v[8:9], 11, v[12:13]
	v_lshl_or_b32 v8, v14, 1, v8
	v_lshl_add_u64 v[0:1], s[2:3], 0, v[8:9]
	v_lshl_add_u64 v[2:3], s[4:5], 0, v[8:9]
	global_load_dwordx4 v[26:29], v[0:1], off
	global_load_dwordx4 v[30:33], v[2:3], off
	global_load_dwordx4 v[34:37], v[0:1], off offset:16
	global_load_dwordx4 v[38:41], v[2:3], off offset:16
	v_lshl_add_u64 v[10:11], s[6:7], 0, v[8:9]
	global_load_dwordx4 v[42:45], v[10:11], off
	global_load_dwordx4 v[0:3], v[16:17], off offset:16
	global_load_dwordx4 v[4:7], v[16:17], off
	v_lshl_add_u64 v[18:19], s[8:9], 0, v[8:9]
	global_load_dwordx4 v[8:11], v[10:11], off offset:16
	s_waitcnt lgkmcnt(0)
	s_mov_b32 s12, s13
	s_waitcnt vmcnt(0)
	v_lshlrev_b32_e32 v46, 16, v26
	v_lshlrev_b32_e32 v48, 16, v30
	v_and_b32_e32 v47, 0xffff0000, v26
	v_and_b32_e32 v49, 0xffff0000, v30
	v_lshlrev_b32_e32 v26, 16, v27
	v_lshlrev_b32_e32 v30, 16, v31
	v_and_b32_e32 v27, 0xffff0000, v27
	v_and_b32_e32 v31, 0xffff0000, v31
	v_lshlrev_b32_e32 v50, 16, v28
	v_lshlrev_b32_e32 v52, 16, v32
	v_and_b32_e32 v51, 0xffff0000, v28
	v_and_b32_e32 v53, 0xffff0000, v32
	v_lshlrev_b32_e32 v58, 16, v36
	v_lshlrev_b32_e32 v60, 16, v40
	v_and_b32_e32 v59, 0xffff0000, v36
	v_and_b32_e32 v61, 0xffff0000, v40
	v_lshlrev_b32_e32 v21, 16, v37
	v_lshlrev_b32_e32 v63, 16, v41
	v_and_b32_e32 v20, 0xffff0000, v37
	v_and_b32_e32 v62, 0xffff0000, v41
	v_lshlrev_b32_e32 v36, 16, v42
	v_and_b32_e32 v37, 0xffff0000, v42
	v_lshlrev_b32_e32 v40, 16, v43
	v_and_b32_e32 v41, 0xffff0000, v43
	v_lshlrev_b32_e32 v42, 16, v44
	v_and_b32_e32 v43, 0xffff0000, v44
	v_lshlrev_b32_e32 v28, 16, v29
	v_lshlrev_b32_e32 v32, 16, v33
	v_and_b32_e32 v29, 0xffff0000, v29
	v_and_b32_e32 v33, 0xffff0000, v33
	v_pk_add_f32 v[50:51], v[50:51], v[52:53]
	v_mul_f32_e32 v13, 0xbfb8aa3b, v42
	v_mul_f32_e32 v25, 0xbfb8aa3b, v43
	v_pk_add_f32 v[52:53], v[26:27], v[30:31]
	v_mul_f32_e32 v26, 0xbfb8aa3b, v40
	v_mul_f32_e32 v27, 0xbfb8aa3b, v41
	v_pk_add_f32 v[20:21], v[20:21], v[62:63]
	v_pk_add_f32 v[62:63], v[28:29], v[32:33]
	v_mul_f32_e32 v28, 0xbfb8aa3b, v36
	v_mul_f32_e32 v29, 0xbfb8aa3b, v37
	v_exp_f32_e32 v13, v13
	v_exp_f32_e32 v25, v25
	v_exp_f32_e32 v26, v26
	v_exp_f32_e32 v27, v27
	v_exp_f32_e32 v28, v28
	v_exp_f32_e32 v29, v29
	v_add_f32_e32 v13, 1.0, v13
	v_add_f32_e32 v25, 1.0, v25
	v_add_f32_e32 v70, 1.0, v26
	v_add_f32_e32 v71, 1.0, v27
	v_add_f32_e32 v72, 1.0, v28
	v_add_f32_e32 v73, 1.0, v29
	v_rcp_f32_e32 v26, v13
	v_rcp_f32_e32 v27, v25
	v_rcp_f32_e32 v28, v70
	v_rcp_f32_e32 v29, v71
	v_lshlrev_b32_e32 v44, 16, v45
	v_pk_mul_f32 v[42:43], v[26:27], v[42:43]
	v_and_b32_e32 v45, 0xffff0000, v45
	v_pk_mul_f32 v[40:41], v[28:29], v[40:41]
	global_load_dwordx4 v[26:29], v[16:17], off offset:32
	v_mul_f32_e32 v32, 0xbfb8aa3b, v44
	v_mul_f32_e32 v33, 0xbfb8aa3b, v45
	v_exp_f32_e32 v32, v32
	v_exp_f32_e32 v33, v33
	v_pk_add_f32 v[46:47], v[46:47], v[48:49]
	v_pk_mul_f32 v[30:31], v[52:53], v[52:53]
	v_add_f32_e32 v74, 1.0, v32
	v_add_f32_e32 v75, 1.0, v33
	v_rcp_f32_e32 v32, v72
	v_rcp_f32_e32 v33, v73
	v_pk_mul_f32 v[48:49], v[46:47], v[46:47]
	v_pk_mul_f32 v[68:69], v[50:51], v[50:51]
	v_add_f32_e32 v13, v48, v49
	v_add_f32_e32 v13, v13, v30
	v_pk_mul_f32 v[36:37], v[32:33], v[36:37]
	v_add_f32_e32 v13, v31, v13
	global_load_dwordx4 v[30:33], v[16:17], off offset:48
	v_add_f32_e32 v13, v68, v13
	v_lshlrev_b32_e32 v54, 16, v34
	v_lshlrev_b32_e32 v56, 16, v38
	v_and_b32_e32 v55, 0xffff0000, v34
	v_and_b32_e32 v57, 0xffff0000, v38
	v_pk_mul_f32 v[66:67], v[62:63], v[62:63]
	v_add_f32_e32 v13, v69, v13
	v_pk_add_f32 v[54:55], v[54:55], v[56:57]
	v_add_f32_e32 v13, v66, v13
	v_lshlrev_b32_e32 v34, 16, v35
	v_lshlrev_b32_e32 v38, 16, v39
	v_and_b32_e32 v35, 0xffff0000, v35
	v_and_b32_e32 v39, 0xffff0000, v39
	v_pk_mul_f32 v[56:57], v[54:55], v[54:55]
	v_add_f32_e32 v13, v67, v13
	v_pk_add_f32 v[34:35], v[34:35], v[38:39]
	v_add_f32_e32 v13, v13, v56
	v_pk_mul_f32 v[38:39], v[34:35], v[34:35]
	v_add_f32_e32 v13, v57, v13
	v_pk_add_f32 v[58:59], v[58:59], v[60:61]
	v_add_f32_e32 v13, v38, v13
	v_pk_mul_f32 v[60:61], v[58:59], v[58:59]
	v_add_f32_e32 v13, v39, v13
	v_add_f32_e32 v13, v60, v13
	v_pk_mul_f32 v[64:65], v[20:21], v[20:21]
	v_add_f32_e32 v13, v61, v13
	v_add_f32_e32 v13, v65, v13
	v_add_f32_e32 v13, v64, v13
	ds_bpermute_b32 v25, v15, v13
	v_rcp_f32_e32 v70, v74
	v_rcp_f32_e32 v71, v75
	v_lshlrev_b32_e32 v72, 16, v10
	v_and_b32_e32 v73, 0xffff0000, v10
	s_waitcnt lgkmcnt(0)
; DEVI float fsig(float x) { return __builtin_amdgcn_rcpf(1.f + __expf(-x)); }
; DEVI float bflo(unsigned u) { return __uint_as_float(u << 16); }
; DEVI float bfhi(unsigned u) { return __uint_as_float(u & 0xffff0000u); }
; DEVI float sxor(float v, int mask, int lane) { return __int_as_float(__builtin_amdgcn_ds_bpermute((lane ^ mask) << 2, __float_as_int(v))); }
; DEVI void gla_out_phase(int wv, const Params& p) {
;     ...
;     ss += sxor(ss, 1, lane);
;     ss += sxor(ss, 2, lane);
;     ss += sxor(ss, 4, lane);
;     ss += sxor(ss, 8, lane);
;     const float rs = rsqrtf(ss * (1.f / 256.f) + EPS);
; #pragma unroll
;     for (int h2 = 0; h2 < 2; ++h2) {
;       const uint4 rr = *(const uint4*)(R + base + h2 * 8);
;       const unsigned r4[4] = {rr.x, rr.y, rr.z, rr.w};
;       unsigned ov[4];
; #pragma unroll
;       for (int q = 0; q < 4; ++q) {
;         const float r0 = bflo(r4[q]), r1 = bfhi(r4[q]);
;         const float g0 = GN[d0 + h2 * 8 + 2 * q], g1 = GN[d0 + h2 * 8 + 2 * q + 1];
;         const float y0 = o[h2 * 8 + 2 * q] * rs * g0 * (r0 * fsig(r0));
;         const float y1 = o[h2 * 8 + 2 * q + 1] * rs * g1 * (r1 * fsig(r1));
;         ov[q] = pack2(y0, y1);
;       }
;       *(uint4*)(ON + base + h2 * 8) = make_uint4(ov[0], ov[1], ov[2], ov[3]);
;     }
	v_add_f32_e32 v13, v13, v25
	ds_bpermute_b32 v25, v22, v13
	v_pk_mul_f32 v[44:45], v[70:71], v[44:45]
	v_lshlrev_b32_e32 v70, 16, v8
	v_and_b32_e32 v71, 0xffff0000, v8
	v_lshlrev_b32_e32 v8, 16, v9
	s_waitcnt lgkmcnt(0)
	v_add_f32_e32 v13, v13, v25
	ds_bpermute_b32 v25, v23, v13
	v_and_b32_e32 v9, 0xffff0000, v9
	v_mul_f32_e32 v38, 0xbfb8aa3b, v8
	v_mul_f32_e32 v39, 0xbfb8aa3b, v9
	v_mul_f32_e32 v48, 0xbfb8aa3b, v70
	s_waitcnt lgkmcnt(0)
	v_add_f32_e32 v13, v13, v25
	ds_bpermute_b32 v25, v24, v13
	v_mul_f32_e32 v49, 0xbfb8aa3b, v71
	v_exp_f32_e32 v38, v38
	v_exp_f32_e32 v39, v39
	v_exp_f32_e32 v48, v48
	s_waitcnt lgkmcnt(0)
	v_add_f32_e32 v13, v13, v25
	v_fmamk_f32 v13, v13, 0x3b800000, v150
	v_mul_f32_e32 v25, 0x4b800000, v13
	v_cmp_gt_f32_e32 vcc, s29, v13
	v_exp_f32_e32 v49, v49
	v_add_f32_e32 v38, 1.0, v38
	v_cndmask_b32_e32 v13, v13, v25, vcc
	v_rsq_f32_e32 v13, v13
	v_add_f32_e32 v39, 1.0, v39
	v_add_f32_e32 v48, 1.0, v48
	v_add_f32_e32 v49, 1.0, v49
	v_mul_f32_e32 v10, 0x45800000, v13
	v_cndmask_b32_e32 v10, v13, v10, vcc
	v_pk_mul_f32 v[46:47], v[46:47], v[10:11] op_sel_hi:[1,0]
	v_rcp_f32_e32 v38, v38
	v_pk_mul_f32 v[4:5], v[4:5], v[46:47]
	v_rcp_f32_e32 v39, v39
	v_pk_mul_f32 v[4:5], v[36:37], v[4:5]
	v_pk_mul_f32 v[36:37], v[52:53], v[10:11] op_sel_hi:[1,0]
	v_cvt_pk_bf16_f32 v4, v4, v5
	v_pk_mul_f32 v[6:7], v[6:7], v[36:37]
	v_rcp_f32_e32 v48, v48
	v_pk_mul_f32 v[6:7], v[40:41], v[6:7]
	v_rcp_f32_e32 v49, v49
	v_cvt_pk_bf16_f32 v5, v6, v7
	v_pk_mul_f32 v[6:7], v[50:51], v[10:11] op_sel_hi:[1,0]
	v_pk_mul_f32 v[8:9], v[38:39], v[8:9]
	v_pk_mul_f32 v[0:1], v[0:1], v[6:7]
	v_pk_mul_f32 v[38:39], v[48:49], v[70:71]
	v_pk_mul_f32 v[0:1], v[42:43], v[0:1]
	s_nop 0
	v_cvt_pk_bf16_f32 v6, v0, v1
	v_pk_mul_f32 v[0:1], v[62:63], v[10:11] op_sel_hi:[1,0]
	s_nop 0
	v_pk_mul_f32 v[0:1], v[2:3], v[0:1]
	v_pk_mul_f32 v[2:3], v[34:35], v[10:11] op_sel_hi:[1,0]
	v_pk_mul_f32 v[0:1], v[44:45], v[0:1]
	s_waitcnt vmcnt(0)
	v_pk_mul_f32 v[2:3], v[2:3], v[28:29]
	v_cvt_pk_bf16_f32 v7, v0, v1
	v_pk_mul_f32 v[0:1], v[54:55], v[10:11] op_sel_hi:[1,0]
	global_store_dwordx4 v[18:19], v[4:7], off
	v_pk_mul_f32 v[0:1], v[0:1], v[26:27]
	v_pk_mul_f32 v[2:3], v[8:9], v[2:3]
	v_pk_mul_f32 v[0:1], v[0:1], v[38:39]
	v_mul_f32_e32 v4, 0xbfb8aa3b, v73
	v_cvt_pk_bf16_f32 v0, v0, v1
	v_mul_f32_e32 v1, 0xbfb8aa3b, v72
	v_exp_f32_e32 v1, v1
	v_exp_f32_e32 v5, v4
	v_lshlrev_b32_e32 v6, 16, v11
	v_and_b32_e32 v7, 0xffff0000, v11
	v_add_f32_e32 v1, 1.0, v1
	v_rcp_f32_e32 v4, v1
	v_add_f32_e32 v1, 1.0, v5
	v_rcp_f32_e32 v5, v1
	v_mul_f32_e32 v8, 0xbfb8aa3b, v6
	v_mul_f32_e32 v9, 0xbfb8aa3b, v7
	v_exp_f32_e32 v8, v8
	v_exp_f32_e32 v9, v9
	v_cvt_pk_bf16_f32 v1, v2, v3
	v_pk_mul_f32 v[2:3], v[58:59], v[10:11] op_sel_hi:[1,0]
	v_pk_mul_f32 v[4:5], v[4:5], v[72:73]
	v_pk_mul_f32 v[2:3], v[2:3], v[30:31]
	s_nop 0
	v_pk_mul_f32 v[2:3], v[4:5], v[2:3]
	v_add_f32_e32 v4, 1.0, v8
	v_add_f32_e32 v5, 1.0, v9
	v_rcp_f32_e32 v4, v4
	v_rcp_f32_e32 v5, v5
	v_pk_mul_f32 v[8:9], v[20:21], v[10:11] op_sel_hi:[1,0]
	v_cvt_pk_bf16_f32 v2, v2, v3
	v_pk_mul_f32 v[8:9], v[8:9], v[32:33] op_sel:[1,0] op_sel_hi:[0,1]
	v_pk_mul_f32 v[4:5], v[4:5], v[6:7]
	s_nop 0
	v_pk_mul_f32 v[4:5], v[4:5], v[8:9]
	s_nop 0
	v_cvt_pk_bf16_f32 v3, v4, v5
	global_store_dwordx4 v[18:19], v[0:3], off offset:16
	s_nop 0
	v_lshl_add_u32 v12, s12, 3, v12
	s_mov_b32 s12, 0x13fff
	v_cmp_lt_i32_e32 vcc, s12, v12
	s_or_b64 s[10:11], vcc, s[10:11]
	s_andn2_b64 exec, exec, s[10:11]
	s_cbranch_execnz .LBB0_1643

; template <int EPI, int TS, bool VT>
; DEVI void gemm_epilogue(const Params& p, char* smem, f32x4 (&acc)[2][2][4][2], int m0, int n0, float scale, const float* ssin,
;                         float* ssout, u16* xbout, int wid, int lane, int wr, int wc, int fr, int fq) {
;     ...
;   for (int ai = 0; ai < 2; ++ai) {
;     {
;       float* tw = T + (wr * 64 + fq * 4) * TS + wc * 32 + fr;
; #pragma unroll
;       for (int m = 0; m < 4; ++m)
; #pragma unroll
;         for (int j = 0; j < 4; ++j)
; #pragma unroll
;           for (int v = 0; v < 4; ++v) tw[(m * 16 + j) * TS + (v >> 1) * 128 + (v & 1) * 16] = acc[ai][v >> 1][m][v & 1][j];
;     }
;     __syncthreads();
;     const int r0 = wid * 16;
;     const int g0 = m0 + ai * 128 + r0;
;     if constexpr (!VT) {
;       float rsv = 1.f;
;       if constexpr (EPI == E_PLEGATE || EPI == E_F32 || EPI == E_SWIGLU || EPI == E_GLAIN)
;         rsv = rsqrtf(ssin[g0 + (lane & 15)] * (1.f / 1024.f) + EPS);
;       if constexpr (EPI == E_QROPE) rsv = rsqrtf(ssin[g0 + (lane & 15)] * (1.f / 384.f) + EPS);
;       if constexpr (EPI == E_KV) rsv = rsqrtf(ssin[g0 + (lane & 15)] * (1.f / 256.f) + EPS);
;       for (int i0 = 0; i0 < 16; i0 += 8) {
;         float4 xo[8];
;         uint2 pv[8];
;         if constexpr (EPI == E_RESID || EPI == E_PLEGATE) {
; #pragma unroll
;           for (int u = 0; u < 8; ++u) {
;             const size_t ro = (size_t)(g0 + i0 + u) * 1024 + n0 + 4 * lane;
;             const int gr = g0 + i0 + u;
;             const float* xs = p.x + ro;
;             if (scale < 0.f)
;               xs = (gr < MP ? p.x_prompt + ro : p.x_sample + (ro - (size_t)MP * 1024));
;             { const f32x4 t_ = __builtin_nontemporal_load((const f32x4*)xs); xo[u] = make_float4(t_[0], t_[1], t_[2], t_[3]); }
;             if constexpr (EPI == E_PLEGATE) {
;               const unsigned long long t2_ = __builtin_nontemporal_load((const unsigned long long*)((const u16*)(wsb + OFF_PP) + ro));
;               pv[u] = make_uint2((unsigned)t2_, (unsigned)(t2_ >> 32));
;             }
;           }
;         }
; #pragma unroll
;         for (int u = 0; u < 8; ++u) {
;           const int i = i0 + u;
;           const int grow = g0 + i;
;           const float* Tr = T + (r0 + i) * TS;
;           const float rs = __int_as_float(__builtin_amdgcn_readlane(__float_as_int(rsv), i));
.LBB0_1669:
	v_readlane_b32 s12, v254, 13
	v_readlane_b32 s13, v254, 14
	v_lshrrev_b32_e32 v128, 2, v132
	v_and_or_b32 v128, v128, 12, s34
	s_movk_i32 s12, 0x410
	v_mul_lo_u32 v128, v128, s12
	s_lshl_b32 s9, s9, 7
	v_lshlrev_b32_e32 v129, 2, v133
	v_add3_u32 v130, s9, v128, v129
	s_lshl_b32 s9, s31, 4
	s_add_i32 s8, s9, s8
	v_and_b32_e32 v141, 63, v132
	ds_write2_b32 v130, v92, v100 offset1:16
	ds_write2_b32 v130, v120, v124 offset0:128 offset1:144
	v_add_u32_e32 v124, 0x400, v130
	s_ashr_i32 s9, s8, 31
	v_lshl_or_b32 v128, v141, 2, s10
	v_mov_b32_e32 v129, s11
	ds_write2_b32 v124, v93, v101 offset0:4 offset1:20
	ds_write2_b32 v124, v121, v125 offset0:132 offset1:148
	v_add_u32_e32 v121, 0x800, v130
	s_lshl_b64 s[10:11], s[8:9], 10
	s_or_b32 s22, s8, 1
	ds_write2_b32 v121, v94, v102 offset0:8 offset1:24
	ds_write2_b32 v121, v122, v126 offset0:136 offset1:152
	v_add_u32_e32 v122, 0xc00, v130
	v_lshl_add_u64 v[146:147], s[10:11], 0, v[128:129]
	s_ashr_i32 s23, s22, 31
	s_or_b32 s20, s8, 2
	ds_write2_b32 v122, v95, v103 offset0:12 offset1:28
	ds_write2_b32 v122, v123, v127 offset0:140 offset1:156
	v_add_u32_e32 v123, 0x4000, v130
	v_add_u32_e32 v125, 0x4400, v130
	v_add_u32_e32 v126, 0x4800, v130
	v_add_u32_e32 v127, 0x4c00, v130
	v_add_u32_e32 v131, 0x8000, v130
	v_add_u32_e32 v132, 0x8400, v130
	v_add_u32_e32 v133, 0x8800, v130
	v_add_u32_e32 v134, 0x8c00, v130
	v_add_u32_e32 v135, 0x9000, v130
	v_add_u32_e32 v136, 0xc000, v130
	v_add_u32_e32 v137, 0xc400, v130
	v_add_u32_e32 v138, 0xc800, v130
	v_add_u32_e32 v139, 0xcc00, v130
	v_add_u32_e32 v140, 0xd000, v130
	v_lshl_add_u64 v[156:157], v[146:147], 2, s[38:39]
	s_lshl_b64 s[10:11], s[22:23], 10
	s_ashr_i32 s21, s20, 31
	s_or_b32 s18, s8, 3
	ds_write2_b32 v123, v80, v84 offset0:64 offset1:80
	ds_write2_b32 v123, v112, v116 offset0:192 offset1:208
	ds_write2_b32 v125, v81, v85 offset0:68 offset1:84
	ds_write2_b32 v125, v113, v117 offset0:196 offset1:212
	ds_write2_b32 v126, v82, v86 offset0:72 offset1:88
	ds_write2_b32 v126, v114, v118 offset0:200 offset1:216
	ds_write2_b32 v127, v83, v87 offset0:76 offset1:92
	ds_write2_b32 v127, v115, v119 offset0:204 offset1:220
	ds_write2_b32 v131, v72, v76 offset0:128 offset1:144
	ds_write2_b32 v132, v104, v108 offset1:16
	ds_write2_b32 v132, v73, v77 offset0:132 offset1:148
	ds_write2_b32 v133, v105, v109 offset0:4 offset1:20
	ds_write2_b32 v133, v74, v78 offset0:136 offset1:152
	ds_write2_b32 v134, v106, v110 offset0:8 offset1:24
	ds_write2_b32 v134, v75, v79 offset0:140 offset1:156
	ds_write2_b32 v135, v107, v111 offset0:12 offset1:28
	ds_write2_b32 v136, v64, v68 offset0:192 offset1:208
	ds_write2_b32 v137, v88, v96 offset0:64 offset1:80
	ds_write2_b32 v137, v65, v69 offset0:196 offset1:212
	ds_write2_b32 v138, v89, v97 offset0:68 offset1:84
	ds_write2_b32 v138, v66, v70 offset0:200 offset1:216
	ds_write2_b32 v139, v90, v98 offset0:72 offset1:88
	ds_write2_b32 v139, v67, v71 offset0:204 offset1:220
	ds_write2_b32 v140, v91, v99 offset0:76 offset1:92
	s_waitcnt vmcnt(0) lgkmcnt(0)
	s_barrier
	global_load_dwordx4 v[142:145], v[156:157], off
	v_lshl_add_u64 v[118:119], s[10:11], 0, v[128:129]
	s_lshl_b64 s[10:11], s[20:21], 10
	s_ashr_i32 s19, s18, 31
	s_or_b32 s16, s8, 4
	v_lshl_add_u64 v[114:115], s[10:11], 0, v[128:129]
	s_lshl_b64 s[10:11], s[18:19], 10
	s_ashr_i32 s17, s16, 31
	s_or_b32 s14, s8, 5
	v_lshl_add_u64 v[110:111], s[10:11], 0, v[128:129]
	s_lshl_b64 s[10:11], s[16:17], 10
	s_ashr_i32 s15, s14, 31
	s_or_b32 s12, s8, 6
	v_lshl_add_u64 v[106:107], s[10:11], 0, v[128:129]
	s_lshl_b64 s[10:11], s[14:15], 10
	s_ashr_i32 s13, s12, 31
	v_lshl_add_u64 v[102:103], s[10:11], 0, v[128:129]
	s_lshl_b64 s[10:11], s[12:13], 10
	v_lshl_add_u64 v[98:99], s[10:11], 0, v[128:129]
	s_or_b32 s10, s8, 7
	s_ashr_i32 s11, s10, 31
	s_lshl_b64 s[34:35], s[10:11], 10
	v_lshl_add_u64 v[94:95], s[34:35], 0, v[128:129]
	v_lshl_add_u64 v[116:117], v[118:119], 2, s[38:39]
	v_lshl_add_u64 v[108:109], v[110:111], 2, s[38:39]
	v_lshl_add_u64 v[100:101], v[102:103], 2, s[38:39]
	v_lshl_add_u64 v[92:93], v[94:95], 2, s[38:39]
	v_lshl_add_u64 v[112:113], v[114:115], 2, s[38:39]
	global_load_dwordx4 v[88:91], v[116:117], off
	global_load_dwordx4 v[84:87], v[112:113], off
	v_lshl_add_u64 v[104:105], v[106:107], 2, s[38:39]
	global_load_dwordx4 v[80:83], v[108:109], off
	global_load_dwordx4 v[76:79], v[104:105], off
	v_lshl_add_u64 v[96:97], v[98:99], 2, s[38:39]
	global_load_dwordx4 v[72:75], v[100:101], off
	global_load_dwordx4 v[68:71], v[96:97], off
	global_load_dwordx4 v[64:67], v[92:93], off
	v_lshlrev_b32_e32 v120, 4, v141
	s_mulk_i32 s31, 0x4100
	v_add_u32_e32 v120, s31, v120
	ds_read_b128 v[152:155], v120
	v_cmp_eq_u32_e32 vcc, 0, v141
	v_lshl_add_u64 v[146:147], v[146:147], 1, s[4:5]
	s_waitcnt vmcnt(7) lgkmcnt(0)
	v_pk_add_f32 v[142:143], v[142:143], v[152:153]
	v_pk_add_f32 v[144:145], v[144:145], v[154:155]
	global_store_dwordx4 v[156:157], v[142:145], off
	v_cvt_pk_bf16_f32 v152, v142, v143
	v_cvt_pk_bf16_f32 v153, v144, v145
	v_pk_mul_f32 v[142:143], v[142:143], v[142:143]
	v_pk_mul_f32 v[144:145], v[144:145], v[144:145]
	v_add_f32_e32 v141, v142, v143
	v_add_f32_e32 v141, v141, v144
	v_add_f32_e32 v141, v141, v145
	global_store_dwordx2 v[146:147], v[152:153], off
	s_nop 0
	v_add_f32_dpp v141, v141, v141 row_ror:8 row_mask:0xf bank_mask:0xf bound_ctrl:1
	s_nop 1
	v_add_f32_dpp v141, v141, v141 row_ror:4 row_mask:0xf bank_mask:0xf bound_ctrl:1
	s_nop 1
	v_add_f32_dpp v141, v141, v141 row_ror:2 row_mask:0xf bank_mask:0xf bound_ctrl:1
	s_nop 1
	v_add_f32_dpp v141, v141, v141 row_ror:1 row_mask:0xf bank_mask:0xf bound_ctrl:1
	s_nop 0
	v_readlane_b32 s34, v141, 0
	v_readlane_b32 s68, v141, 16
	v_readlane_b32 s35, v141, 32
	v_readlane_b32 s67, v141, 48
	s_and_saveexec_b64 s[30:31], vcc
	s_cbranch_execz .LBB0_1671
	s_lshl_b64 s[70:71], s[8:9], 2
	v_mov_b32_e32 v141, s68
	s_add_u32 s70, s63, s70
	v_add_f32_e32 v141, s34, v141
	s_addc_u32 s71, s64, s71
	v_add_f32_e32 v141, s35, v141
	v_add_f32_e32 v141, s67, v141
	v_mov_b64_e32 v[142:143], s[70:71]
	global_atomic_add_f32 v[142:143], v141, off
; DEVI float fsig(float x) { return __builtin_amdgcn_rcpf(1.f + __expf(-x)); }
; DEVI float bflo(unsigned u) { return __uint_as_float(u << 16); }
; DEVI float bfhi(unsigned u) { return __uint_as_float(u & 0xffff0000u); }
; template <int EPI, int TS, bool VT>
; DEVI void gemm_epilogue(const Params& p, char* smem, f32x4 (&acc)[2][2][4][2], int m0, int n0, float scale, const float* ssin,
;                         float* ssout, u16* xbout, int wid, int lane, int wr, int wc, int fr, int fq) {
;     ...
; #pragma unroll
;         for (int u = 0; u < 8; ++u) {
;           const int i = i0 + u;
;           const int grow = g0 + i;
;           const float* Tr = T + (r0 + i) * TS;
;           const float rs = __int_as_float(__builtin_amdgcn_readlane(__float_as_int(rsv), i));
;           if constexpr (EPI == E_RESID || EPI == E_PLEGATE) {
;             const float4 a = *(const float4*)(Tr + 4 * lane);
;             const size_t ro = (size_t)grow * 1024 + n0 + 4 * lane;
;             float4 x4 = xo[u];
;             if constexpr (EPI == E_PLEGATE) {
;               x4.x += bflo(pv[u].x) * fsig(a.x * rs);
;               x4.y += bfhi(pv[u].x) * fsig(a.y * rs);
;               x4.z += bflo(pv[u].y) * fsig(a.z * rs);
;               x4.w += bfhi(pv[u].y) * fsig(a.w * rs);
;             } else {
;               const float sc = fabsf(scale);
;               x4.x += sc * a.x; x4.y += sc * a.y; x4.z += sc * a.z; x4.w += sc * a.w;
;             }
;             st_nt16(p.x + ro, x4);
;             if (xbout) {
;               uint2 o;
;               o.x = pack2(x4.x, x4.y);
;               o.y = pack2(x4.z, x4.w);
;               st_nt8(xbout + ro, o);
;             }
;             if (ssout) {
;               const float ssq = wsum(x4.x * x4.x + x4.y * x4.y + x4.z * x4.z + x4.w * x4.w, lane);
;               if (lane == 0) atomicAdd(ssout + grow, ssq);
.LBB0_1671:
	s_or_b64 exec, exec, s[30:31]
	ds_read_b128 v[142:145], v120 offset:1040
	v_lshl_add_u64 v[118:119], v[118:119], 1, s[4:5]
	s_waitcnt vmcnt(0) lgkmcnt(0)
	v_pk_add_f32 v[88:89], v[88:89], v[142:143]
	v_pk_add_f32 v[90:91], v[90:91], v[144:145]
	global_store_dwordx4 v[116:117], v[88:91], off
	v_cvt_pk_bf16_f32 v116, v88, v89
	v_cvt_pk_bf16_f32 v117, v90, v91
	v_pk_mul_f32 v[88:89], v[88:89], v[88:89]
	v_pk_mul_f32 v[90:91], v[90:91], v[90:91]
	v_add_f32_e32 v88, v88, v89
	v_add_f32_e32 v88, v88, v90
	v_add_f32_e32 v88, v88, v91
	global_store_dwordx2 v[118:119], v[116:117], off
	s_nop 0
	v_add_f32_dpp v88, v88, v88 row_ror:8 row_mask:0xf bank_mask:0xf bound_ctrl:1
	s_nop 1
	v_add_f32_dpp v88, v88, v88 row_ror:4 row_mask:0xf bank_mask:0xf bound_ctrl:1
	s_nop 1
	v_add_f32_dpp v88, v88, v88 row_ror:2 row_mask:0xf bank_mask:0xf bound_ctrl:1
	s_nop 1
	v_add_f32_dpp v88, v88, v88 row_ror:1 row_mask:0xf bank_mask:0xf bound_ctrl:1
	s_nop 0
	v_readlane_b32 s9, v88, 0
	v_readlane_b32 s67, v88, 16
	v_readlane_b32 s34, v88, 32
	v_readlane_b32 s35, v88, 48
	s_and_saveexec_b64 s[30:31], vcc
	s_cbranch_execz .LBB0_1673
	s_lshl_b64 s[22:23], s[22:23], 2
	v_mov_b32_e32 v88, s67
	s_add_u32 s22, s63, s22
	v_add_f32_e32 v88, s9, v88
	s_addc_u32 s23, s64, s23
	v_add_f32_e32 v88, s34, v88
	v_add_f32_e32 v90, s35, v88
	v_mov_b64_e32 v[88:89], s[22:23]
	global_atomic_add_f32 v[88:89], v90, off
.LBB0_1673:
	s_or_b64 exec, exec, s[30:31]
	ds_read_b128 v[88:91], v120 offset:2080
	v_lshl_add_u64 v[114:115], v[114:115], 1, s[4:5]
	s_waitcnt lgkmcnt(0)
	v_pk_add_f32 v[84:85], v[84:85], v[88:89]
	v_pk_add_f32 v[86:87], v[86:87], v[90:91]
	global_store_dwordx4 v[112:113], v[84:87], off
	v_cvt_pk_bf16_f32 v88, v84, v85
	v_cvt_pk_bf16_f32 v89, v86, v87
	v_pk_mul_f32 v[84:85], v[84:85], v[84:85]
	v_pk_mul_f32 v[86:87], v[86:87], v[86:87]
	v_add_f32_e32 v84, v84, v85
	v_add_f32_e32 v84, v84, v86
	v_add_f32_e32 v84, v84, v87
	global_store_dwordx2 v[114:115], v[88:89], off
	s_nop 0
	v_add_f32_dpp v84, v84, v84 row_ror:8 row_mask:0xf bank_mask:0xf bound_ctrl:1
	s_nop 1
	v_add_f32_dpp v84, v84, v84 row_ror:4 row_mask:0xf bank_mask:0xf bound_ctrl:1
	s_nop 1
	v_add_f32_dpp v84, v84, v84 row_ror:2 row_mask:0xf bank_mask:0xf bound_ctrl:1
	s_nop 1
	v_add_f32_dpp v84, v84, v84 row_ror:1 row_mask:0xf bank_mask:0xf bound_ctrl:1
	s_nop 0
	v_readlane_b32 s9, v84, 0
	v_readlane_b32 s34, v84, 16
	v_readlane_b32 s30, v84, 32
	v_readlane_b32 s31, v84, 48
	s_and_saveexec_b64 s[22:23], vcc
	s_cbranch_execz .LBB0_1675
	s_lshl_b64 s[20:21], s[20:21], 2
	v_mov_b32_e32 v84, s34
	s_add_u32 s20, s63, s20
	v_add_f32_e32 v84, s9, v84
	s_addc_u32 s21, s64, s21
	v_add_f32_e32 v84, s30, v84
	v_add_f32_e32 v86, s31, v84
	v_mov_b64_e32 v[84:85], s[20:21]
	global_atomic_add_f32 v[84:85], v86, off
.LBB0_1675:
	s_or_b64 exec, exec, s[22:23]
	ds_read_b128 v[84:87], v120 offset:3120
	v_lshl_add_u64 v[88:89], v[110:111], 1, s[4:5]
	s_waitcnt lgkmcnt(0)
	v_pk_add_f32 v[80:81], v[80:81], v[84:85]
	v_pk_add_f32 v[82:83], v[82:83], v[86:87]
	global_store_dwordx4 v[108:109], v[80:83], off
	v_cvt_pk_bf16_f32 v84, v80, v81
	v_cvt_pk_bf16_f32 v85, v82, v83
	v_pk_mul_f32 v[80:81], v[80:81], v[80:81]
	v_pk_mul_f32 v[82:83], v[82:83], v[82:83]
	v_add_f32_e32 v80, v80, v81
	v_add_f32_e32 v80, v80, v82
	v_add_f32_e32 v80, v80, v83
	global_store_dwordx2 v[88:89], v[84:85], off
	s_nop 0
	v_add_f32_dpp v80, v80, v80 row_ror:8 row_mask:0xf bank_mask:0xf bound_ctrl:1
	s_nop 1
	v_add_f32_dpp v80, v80, v80 row_ror:4 row_mask:0xf bank_mask:0xf bound_ctrl:1
	s_nop 1
	v_add_f32_dpp v80, v80, v80 row_ror:2 row_mask:0xf bank_mask:0xf bound_ctrl:1
	s_nop 1
	v_add_f32_dpp v80, v80, v80 row_ror:1 row_mask:0xf bank_mask:0xf bound_ctrl:1
	s_nop 0
	v_readlane_b32 s9, v80, 0
	v_readlane_b32 s30, v80, 16
	v_readlane_b32 s22, v80, 32
	v_readlane_b32 s23, v80, 48
	s_and_saveexec_b64 s[20:21], vcc
	s_cbranch_execz .LBB0_1677
	s_lshl_b64 s[18:19], s[18:19], 2
	v_mov_b32_e32 v80, s30
	s_add_u32 s18, s63, s18
	v_add_f32_e32 v80, s9, v80
	s_addc_u32 s19, s64, s19
	v_add_f32_e32 v80, s22, v80
	v_add_f32_e32 v82, s23, v80
	v_mov_b64_e32 v[80:81], s[18:19]
	global_atomic_add_f32 v[80:81], v82, off
.LBB0_1677:
	s_or_b64 exec, exec, s[20:21]
	ds_read_b128 v[80:83], v120 offset:4160
	v_lshl_add_u64 v[84:85], v[106:107], 1, s[4:5]
	s_waitcnt lgkmcnt(0)
	v_pk_add_f32 v[76:77], v[76:77], v[80:81]
	v_pk_add_f32 v[78:79], v[78:79], v[82:83]
	global_store_dwordx4 v[104:105], v[76:79], off
	v_cvt_pk_bf16_f32 v80, v76, v77
	v_cvt_pk_bf16_f32 v81, v78, v79
	v_pk_mul_f32 v[76:77], v[76:77], v[76:77]
	v_pk_mul_f32 v[78:79], v[78:79], v[78:79]
	v_add_f32_e32 v76, v76, v77
	v_add_f32_e32 v76, v76, v78
	v_add_f32_e32 v76, v76, v79
	global_store_dwordx2 v[84:85], v[80:81], off
	s_nop 0
	v_add_f32_dpp v76, v76, v76 row_ror:8 row_mask:0xf bank_mask:0xf bound_ctrl:1
	s_nop 1
	v_add_f32_dpp v76, v76, v76 row_ror:4 row_mask:0xf bank_mask:0xf bound_ctrl:1
	s_nop 1
	v_add_f32_dpp v76, v76, v76 row_ror:2 row_mask:0xf bank_mask:0xf bound_ctrl:1
	s_nop 1
	v_add_f32_dpp v76, v76, v76 row_ror:1 row_mask:0xf bank_mask:0xf bound_ctrl:1
	s_nop 0
	v_readlane_b32 s9, v76, 0
	v_readlane_b32 s22, v76, 16
	v_readlane_b32 s20, v76, 32
	v_readlane_b32 s21, v76, 48
	s_and_saveexec_b64 s[18:19], vcc
	s_cbranch_execz .LBB0_1679
	s_lshl_b64 s[16:17], s[16:17], 2
	v_mov_b32_e32 v76, s22
	s_add_u32 s16, s63, s16
	v_add_f32_e32 v76, s9, v76
	s_addc_u32 s17, s64, s17
	v_add_f32_e32 v76, s20, v76
	v_add_f32_e32 v78, s21, v76
	v_mov_b64_e32 v[76:77], s[16:17]
	global_atomic_add_f32 v[76:77], v78, off
; template <int EPI, int TS, bool VT>
; DEVI void gemm_epilogue(const Params& p, char* smem, f32x4 (&acc)[2][2][4][2], int m0, int n0, float scale, const float* ssin,
;                         float* ssout, u16* xbout, int wid, int lane, int wr, int wc, int fr, int fq) {
;     ...
;       for (int i0 = 0; i0 < 16; i0 += 8) {
;         float4 xo[8];
;         uint2 pv[8];
;         if constexpr (EPI == E_RESID || EPI == E_PLEGATE) {
; #pragma unroll
;           for (int u = 0; u < 8; ++u) {
;             const size_t ro = (size_t)(g0 + i0 + u) * 1024 + n0 + 4 * lane;
;             const int gr = g0 + i0 + u;
;             const float* xs = p.x + ro;
;             if (scale < 0.f)
;               xs = (gr < MP ? p.x_prompt + ro : p.x_sample + (ro - (size_t)MP * 1024));
;             { const f32x4 t_ = __builtin_nontemporal_load((const f32x4*)xs); xo[u] = make_float4(t_[0], t_[1], t_[2], t_[3]); }
;             if constexpr (EPI == E_PLEGATE) {
;               const unsigned long long t2_ = __builtin_nontemporal_load((const unsigned long long*)((const u16*)(wsb + OFF_PP) + ro));
;               pv[u] = make_uint2((unsigned)t2_, (unsigned)(t2_ >> 32));
;             }
;           }
;         }
; #pragma unroll
;         for (int u = 0; u < 8; ++u) {
;           const int i = i0 + u;
;           const int grow = g0 + i;
;           const float* Tr = T + (r0 + i) * TS;
;           const float rs = __int_as_float(__builtin_amdgcn_readlane(__float_as_int(rsv), i));
;           if constexpr (EPI == E_RESID || EPI == E_PLEGATE) {
;             const float4 a = *(const float4*)(Tr + 4 * lane);
;             const size_t ro = (size_t)grow * 1024 + n0 + 4 * lane;
;             float4 x4 = xo[u];
;             if constexpr (EPI == E_PLEGATE) {
;               x4.x += bflo(pv[u].x) * fsig(a.x * rs);
;               x4.y += bfhi(pv[u].x) * fsig(a.y * rs);
;               x4.z += bflo(pv[u].y) * fsig(a.z * rs);
;               x4.w += bfhi(pv[u].y) * fsig(a.w * rs);
;             } else {
;               const float sc = fabsf(scale);
;               x4.x += sc * a.x; x4.y += sc * a.y; x4.z += sc * a.z; x4.w += sc * a.w;
;             }
;             st_nt16(p.x + ro, x4);
;             if (xbout) {
;               uint2 o;
;               o.x = pack2(x4.x, x4.y);
;               o.y = pack2(x4.z, x4.w);
;               st_nt8(xbout + ro, o);
;             }
.LBB0_1679:
	s_or_b64 exec, exec, s[18:19]
	ds_read_b128 v[76:79], v120 offset:5200
	v_lshl_add_u64 v[80:81], v[102:103], 1, s[4:5]
	s_waitcnt lgkmcnt(0)
	v_pk_add_f32 v[72:73], v[72:73], v[76:77]
	v_pk_add_f32 v[74:75], v[74:75], v[78:79]
	global_store_dwordx4 v[100:101], v[72:75], off
	v_cvt_pk_bf16_f32 v76, v72, v73
	v_cvt_pk_bf16_f32 v77, v74, v75
	v_pk_mul_f32 v[72:73], v[72:73], v[72:73]
	v_pk_mul_f32 v[74:75], v[74:75], v[74:75]
	v_add_f32_e32 v72, v72, v73
	v_add_f32_e32 v72, v72, v74
	v_add_f32_e32 v72, v72, v75
	global_store_dwordx2 v[80:81], v[76:77], off
	s_nop 0
	v_add_f32_dpp v72, v72, v72 row_ror:8 row_mask:0xf bank_mask:0xf bound_ctrl:1
	s_nop 1
	v_add_f32_dpp v72, v72, v72 row_ror:4 row_mask:0xf bank_mask:0xf bound_ctrl:1
	s_nop 1
	v_add_f32_dpp v72, v72, v72 row_ror:2 row_mask:0xf bank_mask:0xf bound_ctrl:1
	s_nop 1
	v_add_f32_dpp v72, v72, v72 row_ror:1 row_mask:0xf bank_mask:0xf bound_ctrl:1
	s_nop 0
	v_readlane_b32 s9, v72, 0
	v_readlane_b32 s20, v72, 16
	v_readlane_b32 s18, v72, 32
	v_readlane_b32 s19, v72, 48
	s_and_saveexec_b64 s[16:17], vcc
	s_cbranch_execz .LBB0_1681
	s_lshl_b64 s[14:15], s[14:15], 2
	v_mov_b32_e32 v72, s20
	s_add_u32 s14, s63, s14
	v_add_f32_e32 v72, s9, v72
	s_addc_u32 s15, s64, s15
	v_add_f32_e32 v72, s18, v72
	v_add_f32_e32 v74, s19, v72
	v_mov_b64_e32 v[72:73], s[14:15]
	global_atomic_add_f32 v[72:73], v74, off
.LBB0_1681:
	s_or_b64 exec, exec, s[16:17]
	ds_read_b128 v[72:75], v120 offset:6240
	v_lshl_add_u64 v[76:77], v[98:99], 1, s[4:5]
	s_waitcnt lgkmcnt(0)
	v_pk_add_f32 v[68:69], v[68:69], v[72:73]
	v_pk_add_f32 v[70:71], v[70:71], v[74:75]
	global_store_dwordx4 v[96:97], v[68:71], off
	v_cvt_pk_bf16_f32 v72, v68, v69
	v_cvt_pk_bf16_f32 v73, v70, v71
	v_pk_mul_f32 v[68:69], v[68:69], v[68:69]
	v_pk_mul_f32 v[70:71], v[70:71], v[70:71]
	v_add_f32_e32 v68, v68, v69
	v_add_f32_e32 v68, v68, v70
	v_add_f32_e32 v68, v68, v71
	global_store_dwordx2 v[76:77], v[72:73], off
	s_nop 0
	v_add_f32_dpp v68, v68, v68 row_ror:8 row_mask:0xf bank_mask:0xf bound_ctrl:1
	s_nop 1
	v_add_f32_dpp v68, v68, v68 row_ror:4 row_mask:0xf bank_mask:0xf bound_ctrl:1
	s_nop 1
	v_add_f32_dpp v68, v68, v68 row_ror:2 row_mask:0xf bank_mask:0xf bound_ctrl:1
	s_nop 1
	v_add_f32_dpp v68, v68, v68 row_ror:1 row_mask:0xf bank_mask:0xf bound_ctrl:1
	s_nop 0
	v_readlane_b32 s9, v68, 0
	v_readlane_b32 s18, v68, 16
	v_readlane_b32 s16, v68, 32
	v_readlane_b32 s17, v68, 48
	s_and_saveexec_b64 s[14:15], vcc
	s_cbranch_execz .LBB0_1683
	s_lshl_b64 s[12:13], s[12:13], 2
	v_mov_b32_e32 v68, s18
	s_add_u32 s12, s63, s12
	v_add_f32_e32 v68, s9, v68
	s_addc_u32 s13, s64, s13
	v_add_f32_e32 v68, s16, v68
	v_add_f32_e32 v70, s17, v68
	v_mov_b64_e32 v[68:69], s[12:13]
	global_atomic_add_f32 v[68:69], v70, off
.LBB0_1683:
	s_or_b64 exec, exec, s[14:15]
	ds_read_b128 v[68:71], v120 offset:7280
	v_lshl_add_u64 v[72:73], v[94:95], 1, s[4:5]
	s_waitcnt lgkmcnt(0)
	v_pk_add_f32 v[64:65], v[64:65], v[68:69]
	v_pk_add_f32 v[66:67], v[66:67], v[70:71]
	global_store_dwordx4 v[92:93], v[64:67], off
	v_cvt_pk_bf16_f32 v68, v64, v65
	v_cvt_pk_bf16_f32 v69, v66, v67
	v_pk_mul_f32 v[64:65], v[64:65], v[64:65]
	v_pk_mul_f32 v[66:67], v[66:67], v[66:67]
	v_add_f32_e32 v64, v64, v65
	v_add_f32_e32 v64, v64, v66
	v_add_f32_e32 v64, v64, v67
	global_store_dwordx2 v[72:73], v[68:69], off
	s_nop 0
	v_add_f32_dpp v64, v64, v64 row_ror:8 row_mask:0xf bank_mask:0xf bound_ctrl:1
	s_nop 1
	v_add_f32_dpp v64, v64, v64 row_ror:4 row_mask:0xf bank_mask:0xf bound_ctrl:1
	s_nop 1
	v_add_f32_dpp v64, v64, v64 row_ror:2 row_mask:0xf bank_mask:0xf bound_ctrl:1
	s_nop 1
	v_add_f32_dpp v64, v64, v64 row_ror:1 row_mask:0xf bank_mask:0xf bound_ctrl:1
	s_nop 0
	v_readlane_b32 s9, v64, 0
	v_readlane_b32 s16, v64, 16
	v_readlane_b32 s14, v64, 32
	v_readlane_b32 s15, v64, 48
	s_and_saveexec_b64 s[12:13], vcc
	s_cbranch_execz .LBB0_1685
	s_lshl_b64 s[10:11], s[10:11], 2
	v_mov_b32_e32 v64, s16
	s_add_u32 s10, s63, s10
	v_add_f32_e32 v64, s9, v64
	s_addc_u32 s11, s64, s11
	v_add_f32_e32 v64, s14, v64
	v_add_f32_e32 v66, s15, v64
	v_mov_b64_e32 v[64:65], s[10:11]
	global_atomic_add_f32 v[64:65], v66, off
.LBB0_1685:
	s_or_b64 exec, exec, s[12:13]
	s_or_b32 s30, s8, 8
	s_ashr_i32 s31, s30, 31
	s_lshl_b64 s[10:11], s[30:31], 10
	s_or_b32 s22, s8, 9
	v_lshl_add_u64 v[146:147], s[10:11], 0, v[128:129]
	s_ashr_i32 s23, s22, 31
	s_or_b32 s20, s8, 10
	v_lshl_add_u64 v[156:157], v[146:147], 2, s[38:39]
	s_lshl_b64 s[10:11], s[22:23], 10
	s_ashr_i32 s21, s20, 31
	s_or_b32 s18, s8, 11
	global_load_dwordx4 v[142:145], v[156:157], off
	v_lshl_add_u64 v[118:119], s[10:11], 0, v[128:129]
	s_lshl_b64 s[10:11], s[20:21], 10
	s_ashr_i32 s19, s18, 31
	s_or_b32 s16, s8, 12
	v_lshl_add_u64 v[114:115], s[10:11], 0, v[128:129]
	s_lshl_b64 s[10:11], s[18:19], 10
	s_ashr_i32 s17, s16, 31
	s_or_b32 s14, s8, 13
	v_lshl_add_u64 v[110:111], s[10:11], 0, v[128:129]
	s_lshl_b64 s[10:11], s[16:17], 10
	s_ashr_i32 s15, s14, 31
	s_or_b32 s12, s8, 14
	v_lshl_add_u64 v[106:107], s[10:11], 0, v[128:129]
	s_lshl_b64 s[10:11], s[14:15], 10
	s_ashr_i32 s13, s12, 31
	v_lshl_add_u64 v[102:103], s[10:11], 0, v[128:129]
	s_lshl_b64 s[10:11], s[12:13], 10
	v_lshl_add_u64 v[98:99], s[10:11], 0, v[128:129]
	s_or_b32 s10, s8, 15
	s_ashr_i32 s11, s10, 31
	s_lshl_b64 s[34:35], s[10:11], 10
	v_lshl_add_u64 v[94:95], s[34:35], 0, v[128:129]
	v_lshl_add_u64 v[116:117], v[118:119], 2, s[38:39]
	v_lshl_add_u64 v[108:109], v[110:111], 2, s[38:39]
	v_lshl_add_u64 v[100:101], v[102:103], 2, s[38:39]
	v_lshl_add_u64 v[92:93], v[94:95], 2, s[38:39]
	v_lshl_add_u64 v[112:113], v[114:115], 2, s[38:39]
	global_load_dwordx4 v[88:91], v[116:117], off
	global_load_dwordx4 v[84:87], v[112:113], off
	v_lshl_add_u64 v[104:105], v[106:107], 2, s[38:39]
	global_load_dwordx4 v[80:83], v[108:109], off
	global_load_dwordx4 v[76:79], v[104:105], off
	v_lshl_add_u64 v[96:97], v[98:99], 2, s[38:39]
	global_load_dwordx4 v[72:75], v[100:101], off
	global_load_dwordx4 v[68:71], v[96:97], off
	global_load_dwordx4 v[64:67], v[92:93], off
	ds_read_b128 v[152:155], v120 offset:8320
	v_lshl_add_u64 v[146:147], v[146:147], 1, s[4:5]
	s_waitcnt vmcnt(0) lgkmcnt(0)
; DEVI float fsig(float x) { return __builtin_amdgcn_rcpf(1.f + __expf(-x)); }
; DEVI float bflo(unsigned u) { return __uint_as_float(u << 16); }
; DEVI float bfhi(unsigned u) { return __uint_as_float(u & 0xffff0000u); }
; template <int EPI, int TS, bool VT>
; DEVI void gemm_epilogue(const Params& p, char* smem, f32x4 (&acc)[2][2][4][2], int m0, int n0, float scale, const float* ssin,
;                         float* ssout, u16* xbout, int wid, int lane, int wr, int wc, int fr, int fq) {
;     ...
; #pragma unroll
;         for (int u = 0; u < 8; ++u) {
;           const int i = i0 + u;
;           const int grow = g0 + i;
;           const float* Tr = T + (r0 + i) * TS;
;           const float rs = __int_as_float(__builtin_amdgcn_readlane(__float_as_int(rsv), i));
;           if constexpr (EPI == E_RESID || EPI == E_PLEGATE) {
;             const float4 a = *(const float4*)(Tr + 4 * lane);
;             const size_t ro = (size_t)grow * 1024 + n0 + 4 * lane;
;             float4 x4 = xo[u];
;             if constexpr (EPI == E_PLEGATE) {
;               x4.x += bflo(pv[u].x) * fsig(a.x * rs);
;               x4.y += bfhi(pv[u].x) * fsig(a.y * rs);
;               x4.z += bflo(pv[u].y) * fsig(a.z * rs);
;               x4.w += bfhi(pv[u].y) * fsig(a.w * rs);
;             } else {
;               const float sc = fabsf(scale);
;               x4.x += sc * a.x; x4.y += sc * a.y; x4.z += sc * a.z; x4.w += sc * a.w;
;             }
;             st_nt16(p.x + ro, x4);
;             if (xbout) {
;               uint2 o;
;               o.x = pack2(x4.x, x4.y);
;               o.y = pack2(x4.z, x4.w);
;               st_nt8(xbout + ro, o);
;             }
;             if (ssout) {
;               const float ssq = wsum(x4.x * x4.x + x4.y * x4.y + x4.z * x4.z + x4.w * x4.w, lane);
;               if (lane == 0) atomicAdd(ssout + grow, ssq);
	v_pk_add_f32 v[142:143], v[142:143], v[152:153]
	v_pk_add_f32 v[144:145], v[144:145], v[154:155]
	global_store_dwordx4 v[156:157], v[142:145], off
	v_cvt_pk_bf16_f32 v152, v142, v143
	v_cvt_pk_bf16_f32 v153, v144, v145
	v_pk_mul_f32 v[142:143], v[142:143], v[142:143]
	v_pk_mul_f32 v[144:145], v[144:145], v[144:145]
	v_add_f32_e32 v141, v142, v143
	v_add_f32_e32 v141, v141, v144
	v_add_f32_e32 v141, v141, v145
	global_store_dwordx2 v[146:147], v[152:153], off
	s_nop 0
	v_add_f32_dpp v141, v141, v141 row_ror:8 row_mask:0xf bank_mask:0xf bound_ctrl:1
	s_nop 1
	v_add_f32_dpp v141, v141, v141 row_ror:4 row_mask:0xf bank_mask:0xf bound_ctrl:1
	s_nop 1
	v_add_f32_dpp v141, v141, v141 row_ror:2 row_mask:0xf bank_mask:0xf bound_ctrl:1
	s_nop 1
	v_add_f32_dpp v141, v141, v141 row_ror:1 row_mask:0xf bank_mask:0xf bound_ctrl:1
	s_nop 0
	v_readlane_b32 s9, v141, 0
	v_readlane_b32 s69, v141, 16
	v_readlane_b32 s67, v141, 32
	v_readlane_b32 s68, v141, 48
	s_and_saveexec_b64 s[34:35], vcc
	s_cbranch_execz .LBB0_1687
	s_lshl_b64 s[30:31], s[30:31], 2
	v_mov_b32_e32 v141, s69
	s_add_u32 s30, s63, s30
	v_add_f32_e32 v141, s9, v141
	s_addc_u32 s31, s64, s31
	v_add_f32_e32 v141, s67, v141
	v_add_f32_e32 v141, s68, v141
	v_mov_b64_e32 v[142:143], s[30:31]
	global_atomic_add_f32 v[142:143], v141, off
.LBB0_1687:
	s_or_b64 exec, exec, s[34:35]
	ds_read_b128 v[142:145], v120 offset:9360
	v_lshl_add_u64 v[118:119], v[118:119], 1, s[4:5]
	s_waitcnt lgkmcnt(0)
	v_pk_add_f32 v[88:89], v[88:89], v[142:143]
	v_pk_add_f32 v[90:91], v[90:91], v[144:145]
	global_store_dwordx4 v[116:117], v[88:91], off
	v_cvt_pk_bf16_f32 v116, v88, v89
	v_cvt_pk_bf16_f32 v117, v90, v91
	v_pk_mul_f32 v[88:89], v[88:89], v[88:89]
	v_pk_mul_f32 v[90:91], v[90:91], v[90:91]
	v_add_f32_e32 v88, v88, v89
	v_add_f32_e32 v88, v88, v90
	v_add_f32_e32 v88, v88, v91
	global_store_dwordx2 v[118:119], v[116:117], off
	s_nop 0
	v_add_f32_dpp v88, v88, v88 row_ror:8 row_mask:0xf bank_mask:0xf bound_ctrl:1
	s_nop 1
	v_add_f32_dpp v88, v88, v88 row_ror:4 row_mask:0xf bank_mask:0xf bound_ctrl:1
	s_nop 1
	v_add_f32_dpp v88, v88, v88 row_ror:2 row_mask:0xf bank_mask:0xf bound_ctrl:1
	s_nop 1
	v_add_f32_dpp v88, v88, v88 row_ror:1 row_mask:0xf bank_mask:0xf bound_ctrl:1
	s_nop 0
	v_readlane_b32 s9, v88, 0
	v_readlane_b32 s67, v88, 16
	v_readlane_b32 s34, v88, 32
	v_readlane_b32 s35, v88, 48
	s_and_saveexec_b64 s[30:31], vcc
	s_cbranch_execz .LBB0_1689
	s_lshl_b64 s[22:23], s[22:23], 2
	v_mov_b32_e32 v88, s67
	s_add_u32 s22, s63, s22
	v_add_f32_e32 v88, s9, v88
	s_addc_u32 s23, s64, s23
	v_add_f32_e32 v88, s34, v88
	v_add_f32_e32 v90, s35, v88
	v_mov_b64_e32 v[88:89], s[22:23]
	global_atomic_add_f32 v[88:89], v90, off
.LBB0_1689:
	s_or_b64 exec, exec, s[30:31]
	ds_read_b128 v[88:91], v120 offset:10400
	v_lshl_add_u64 v[114:115], v[114:115], 1, s[4:5]
	s_waitcnt lgkmcnt(0)
	v_pk_add_f32 v[84:85], v[84:85], v[88:89]
	v_pk_add_f32 v[86:87], v[86:87], v[90:91]
	global_store_dwordx4 v[112:113], v[84:87], off
	v_cvt_pk_bf16_f32 v88, v84, v85
	v_cvt_pk_bf16_f32 v89, v86, v87
	v_pk_mul_f32 v[84:85], v[84:85], v[84:85]
	v_pk_mul_f32 v[86:87], v[86:87], v[86:87]
	v_add_f32_e32 v84, v84, v85
	v_add_f32_e32 v84, v84, v86
	v_add_f32_e32 v84, v84, v87
	global_store_dwordx2 v[114:115], v[88:89], off
	s_nop 0
	v_add_f32_dpp v84, v84, v84 row_ror:8 row_mask:0xf bank_mask:0xf bound_ctrl:1
	s_nop 1
	v_add_f32_dpp v84, v84, v84 row_ror:4 row_mask:0xf bank_mask:0xf bound_ctrl:1
	s_nop 1
	v_add_f32_dpp v84, v84, v84 row_ror:2 row_mask:0xf bank_mask:0xf bound_ctrl:1
	s_nop 1
	v_add_f32_dpp v84, v84, v84 row_ror:1 row_mask:0xf bank_mask:0xf bound_ctrl:1
	s_nop 0
	v_readlane_b32 s9, v84, 0
	v_readlane_b32 s34, v84, 16
	v_readlane_b32 s30, v84, 32
	v_readlane_b32 s31, v84, 48
	s_and_saveexec_b64 s[22:23], vcc
	s_cbranch_execz .LBB0_1691
	s_lshl_b64 s[20:21], s[20:21], 2
	v_mov_b32_e32 v84, s34
	s_add_u32 s20, s63, s20
	v_add_f32_e32 v84, s9, v84
	s_addc_u32 s21, s64, s21
	v_add_f32_e32 v84, s30, v84
	v_add_f32_e32 v86, s31, v84
	v_mov_b64_e32 v[84:85], s[20:21]
	global_atomic_add_f32 v[84:85], v86, off
.LBB0_1691:
	s_or_b64 exec, exec, s[22:23]
	ds_read_b128 v[84:87], v120 offset:11440
	v_lshl_add_u64 v[88:89], v[110:111], 1, s[4:5]
	s_waitcnt lgkmcnt(0)
	v_pk_add_f32 v[80:81], v[80:81], v[84:85]
	v_pk_add_f32 v[82:83], v[82:83], v[86:87]
	global_store_dwordx4 v[108:109], v[80:83], off
	v_cvt_pk_bf16_f32 v84, v80, v81
	v_cvt_pk_bf16_f32 v85, v82, v83
	v_pk_mul_f32 v[80:81], v[80:81], v[80:81]
	v_pk_mul_f32 v[82:83], v[82:83], v[82:83]
	v_add_f32_e32 v80, v80, v81
	v_add_f32_e32 v80, v80, v82
	v_add_f32_e32 v80, v80, v83
	global_store_dwordx2 v[88:89], v[84:85], off
	s_nop 0
	v_add_f32_dpp v80, v80, v80 row_ror:8 row_mask:0xf bank_mask:0xf bound_ctrl:1
	s_nop 1
	v_add_f32_dpp v80, v80, v80 row_ror:4 row_mask:0xf bank_mask:0xf bound_ctrl:1
	s_nop 1
	v_add_f32_dpp v80, v80, v80 row_ror:2 row_mask:0xf bank_mask:0xf bound_ctrl:1
	s_nop 1
	v_add_f32_dpp v80, v80, v80 row_ror:1 row_mask:0xf bank_mask:0xf bound_ctrl:1
	s_nop 0
	v_readlane_b32 s9, v80, 0
	v_readlane_b32 s30, v80, 16
	v_readlane_b32 s22, v80, 32
	v_readlane_b32 s23, v80, 48
	s_and_saveexec_b64 s[20:21], vcc
	s_cbranch_execz .LBB0_1693
	s_lshl_b64 s[18:19], s[18:19], 2
	v_mov_b32_e32 v80, s30
	s_add_u32 s18, s63, s18
	v_add_f32_e32 v80, s9, v80
	s_addc_u32 s19, s64, s19
	v_add_f32_e32 v80, s22, v80
	v_add_f32_e32 v82, s23, v80
	v_mov_b64_e32 v[80:81], s[18:19]
	global_atomic_add_f32 v[80:81], v82, off
; DEVI float fsig(float x) { return __builtin_amdgcn_rcpf(1.f + __expf(-x)); }
; DEVI float bflo(unsigned u) { return __uint_as_float(u << 16); }
; DEVI float bfhi(unsigned u) { return __uint_as_float(u & 0xffff0000u); }
; template <int EPI, int TS, bool VT>
; DEVI void gemm_epilogue(const Params& p, char* smem, f32x4 (&acc)[2][2][4][2], int m0, int n0, float scale, const float* ssin,
;                         float* ssout, u16* xbout, int wid, int lane, int wr, int wc, int fr, int fq) {
;     ...
; #pragma unroll
;         for (int u = 0; u < 8; ++u) {
;           const int i = i0 + u;
;           const int grow = g0 + i;
;           const float* Tr = T + (r0 + i) * TS;
;           const float rs = __int_as_float(__builtin_amdgcn_readlane(__float_as_int(rsv), i));
;           if constexpr (EPI == E_RESID || EPI == E_PLEGATE) {
;             const float4 a = *(const float4*)(Tr + 4 * lane);
;             const size_t ro = (size_t)grow * 1024 + n0 + 4 * lane;
;             float4 x4 = xo[u];
;             if constexpr (EPI == E_PLEGATE) {
;               x4.x += bflo(pv[u].x) * fsig(a.x * rs);
;               x4.y += bfhi(pv[u].x) * fsig(a.y * rs);
;               x4.z += bflo(pv[u].y) * fsig(a.z * rs);
;               x4.w += bfhi(pv[u].y) * fsig(a.w * rs);
;             } else {
;               const float sc = fabsf(scale);
;               x4.x += sc * a.x; x4.y += sc * a.y; x4.z += sc * a.z; x4.w += sc * a.w;
;             }
;             st_nt16(p.x + ro, x4);
;             if (xbout) {
;               uint2 o;
;               o.x = pack2(x4.x, x4.y);
;               o.y = pack2(x4.z, x4.w);
;               st_nt8(xbout + ro, o);
;             }
;             if (ssout) {
;               const float ssq = wsum(x4.x * x4.x + x4.y * x4.y + x4.z * x4.z + x4.w * x4.w, lane);
;               if (lane == 0) atomicAdd(ssout + grow, ssq);
.LBB0_1693:
	s_or_b64 exec, exec, s[20:21]
	ds_read_b128 v[80:83], v120 offset:12480
	v_lshl_add_u64 v[84:85], v[106:107], 1, s[4:5]
	s_waitcnt lgkmcnt(0)
	v_pk_add_f32 v[76:77], v[76:77], v[80:81]
	v_pk_add_f32 v[78:79], v[78:79], v[82:83]
	global_store_dwordx4 v[104:105], v[76:79], off
	v_cvt_pk_bf16_f32 v80, v76, v77
	v_cvt_pk_bf16_f32 v81, v78, v79
	v_pk_mul_f32 v[76:77], v[76:77], v[76:77]
	v_pk_mul_f32 v[78:79], v[78:79], v[78:79]
	v_add_f32_e32 v76, v76, v77
	v_add_f32_e32 v76, v76, v78
	v_add_f32_e32 v76, v76, v79
	global_store_dwordx2 v[84:85], v[80:81], off
	s_nop 0
	v_add_f32_dpp v76, v76, v76 row_ror:8 row_mask:0xf bank_mask:0xf bound_ctrl:1
	s_nop 1
	v_add_f32_dpp v76, v76, v76 row_ror:4 row_mask:0xf bank_mask:0xf bound_ctrl:1
	s_nop 1
	v_add_f32_dpp v76, v76, v76 row_ror:2 row_mask:0xf bank_mask:0xf bound_ctrl:1
	s_nop 1
	v_add_f32_dpp v76, v76, v76 row_ror:1 row_mask:0xf bank_mask:0xf bound_ctrl:1
	s_nop 0
	v_readlane_b32 s9, v76, 0
	v_readlane_b32 s22, v76, 16
	v_readlane_b32 s20, v76, 32
	v_readlane_b32 s21, v76, 48
	s_and_saveexec_b64 s[18:19], vcc
	s_cbranch_execz .LBB0_1695
	s_lshl_b64 s[16:17], s[16:17], 2
	v_mov_b32_e32 v76, s22
	s_add_u32 s16, s63, s16
	v_add_f32_e32 v76, s9, v76
	s_addc_u32 s17, s64, s17
	v_add_f32_e32 v76, s20, v76
	v_add_f32_e32 v78, s21, v76
	v_mov_b64_e32 v[76:77], s[16:17]
	global_atomic_add_f32 v[76:77], v78, off
.LBB0_1695:
	s_or_b64 exec, exec, s[18:19]
	ds_read_b128 v[76:79], v120 offset:13520
	v_lshl_add_u64 v[80:81], v[102:103], 1, s[4:5]
	s_waitcnt lgkmcnt(0)
	v_pk_add_f32 v[72:73], v[72:73], v[76:77]
	v_pk_add_f32 v[74:75], v[74:75], v[78:79]
	global_store_dwordx4 v[100:101], v[72:75], off
	v_cvt_pk_bf16_f32 v76, v72, v73
	v_cvt_pk_bf16_f32 v77, v74, v75
	v_pk_mul_f32 v[72:73], v[72:73], v[72:73]
	v_pk_mul_f32 v[74:75], v[74:75], v[74:75]
	v_add_f32_e32 v72, v72, v73
	v_add_f32_e32 v72, v72, v74
	v_add_f32_e32 v72, v72, v75
	global_store_dwordx2 v[80:81], v[76:77], off
	s_nop 0
	v_add_f32_dpp v72, v72, v72 row_ror:8 row_mask:0xf bank_mask:0xf bound_ctrl:1
	s_nop 1
	v_add_f32_dpp v72, v72, v72 row_ror:4 row_mask:0xf bank_mask:0xf bound_ctrl:1
	s_nop 1
	v_add_f32_dpp v72, v72, v72 row_ror:2 row_mask:0xf bank_mask:0xf bound_ctrl:1
	s_nop 1
	v_add_f32_dpp v72, v72, v72 row_ror:1 row_mask:0xf bank_mask:0xf bound_ctrl:1
	s_nop 0
	v_readlane_b32 s9, v72, 0
	v_readlane_b32 s20, v72, 16
	v_readlane_b32 s18, v72, 32
	v_readlane_b32 s19, v72, 48
	s_and_saveexec_b64 s[16:17], vcc
	s_cbranch_execz .LBB0_1697
	s_lshl_b64 s[14:15], s[14:15], 2
	v_mov_b32_e32 v72, s20
	s_add_u32 s14, s63, s14
	v_add_f32_e32 v72, s9, v72
	s_addc_u32 s15, s64, s15
	v_add_f32_e32 v72, s18, v72
	v_add_f32_e32 v74, s19, v72
	v_mov_b64_e32 v[72:73], s[14:15]
	global_atomic_add_f32 v[72:73], v74, off
.LBB0_1697:
	s_or_b64 exec, exec, s[16:17]
	ds_read_b128 v[72:75], v120 offset:14560
	v_lshl_add_u64 v[76:77], v[98:99], 1, s[4:5]
	s_waitcnt lgkmcnt(0)
	v_pk_add_f32 v[68:69], v[68:69], v[72:73]
	v_pk_add_f32 v[70:71], v[70:71], v[74:75]
	global_store_dwordx4 v[96:97], v[68:71], off
	v_cvt_pk_bf16_f32 v72, v68, v69
	v_cvt_pk_bf16_f32 v73, v70, v71
	v_pk_mul_f32 v[68:69], v[68:69], v[68:69]
	v_pk_mul_f32 v[70:71], v[70:71], v[70:71]
	v_add_f32_e32 v68, v68, v69
	v_add_f32_e32 v68, v68, v70
	v_add_f32_e32 v68, v68, v71
	global_store_dwordx2 v[76:77], v[72:73], off
	s_nop 0
	v_add_f32_dpp v68, v68, v68 row_ror:8 row_mask:0xf bank_mask:0xf bound_ctrl:1
	s_nop 1
	v_add_f32_dpp v68, v68, v68 row_ror:4 row_mask:0xf bank_mask:0xf bound_ctrl:1
	s_nop 1
	v_add_f32_dpp v68, v68, v68 row_ror:2 row_mask:0xf bank_mask:0xf bound_ctrl:1
	s_nop 1
	v_add_f32_dpp v68, v68, v68 row_ror:1 row_mask:0xf bank_mask:0xf bound_ctrl:1
	s_nop 0
	v_readlane_b32 s9, v68, 0
	v_readlane_b32 s18, v68, 16
	v_readlane_b32 s16, v68, 32
	v_readlane_b32 s17, v68, 48
	s_and_saveexec_b64 s[14:15], vcc
	s_cbranch_execz .LBB0_1699
	s_lshl_b64 s[12:13], s[12:13], 2
	v_mov_b32_e32 v68, s18
	s_add_u32 s12, s63, s12
	v_add_f32_e32 v68, s9, v68
	s_addc_u32 s13, s64, s13
	v_add_f32_e32 v68, s16, v68
	v_add_f32_e32 v70, s17, v68
	v_mov_b64_e32 v[68:69], s[12:13]
	global_atomic_add_f32 v[68:69], v70, off
.LBB0_1699:
	s_or_b64 exec, exec, s[14:15]
	ds_read_b128 v[68:71], v120 offset:15600
	v_lshl_add_u64 v[72:73], v[94:95], 1, s[4:5]
	s_waitcnt lgkmcnt(0)
	v_pk_add_f32 v[64:65], v[64:65], v[68:69]
	v_pk_add_f32 v[66:67], v[66:67], v[70:71]
	global_store_dwordx4 v[92:93], v[64:67], off
	v_cvt_pk_bf16_f32 v68, v64, v65
	v_cvt_pk_bf16_f32 v69, v66, v67
	v_pk_mul_f32 v[64:65], v[64:65], v[64:65]
	v_pk_mul_f32 v[66:67], v[66:67], v[66:67]
	v_add_f32_e32 v64, v64, v65
	v_add_f32_e32 v64, v64, v66
	v_add_f32_e32 v64, v64, v67
	global_store_dwordx2 v[72:73], v[68:69], off
	s_nop 0
	v_add_f32_dpp v64, v64, v64 row_ror:8 row_mask:0xf bank_mask:0xf bound_ctrl:1
	s_nop 1
	v_add_f32_dpp v64, v64, v64 row_ror:4 row_mask:0xf bank_mask:0xf bound_ctrl:1
	s_nop 1
	v_add_f32_dpp v64, v64, v64 row_ror:2 row_mask:0xf bank_mask:0xf bound_ctrl:1
	s_nop 1
	v_add_f32_dpp v64, v64, v64 row_ror:1 row_mask:0xf bank_mask:0xf bound_ctrl:1
	s_nop 0
	v_readlane_b32 s9, v64, 0
	v_readlane_b32 s16, v64, 16
	v_readlane_b32 s14, v64, 32
	v_readlane_b32 s15, v64, 48
	s_and_saveexec_b64 s[12:13], vcc
	s_cbranch_execz .LBB0_1701
	s_lshl_b64 s[10:11], s[10:11], 2
	v_mov_b32_e32 v64, s16
	s_add_u32 s10, s63, s10
	v_add_f32_e32 v64, s9, v64
	s_addc_u32 s11, s64, s11
	v_add_f32_e32 v64, s14, v64
	v_add_f32_e32 v66, s15, v64
	v_mov_b64_e32 v[64:65], s[10:11]
	global_atomic_add_f32 v[64:65], v66, off
; template <int EPI, int TS, bool VT>
; DEVI void gemm_epilogue(const Params& p, char* smem, f32x4 (&acc)[2][2][4][2], int m0, int n0, float scale, const float* ssin,
;                         float* ssout, u16* xbout, int wid, int lane, int wr, int wc, int fr, int fq) {
;     ...
;   for (int ai = 0; ai < 2; ++ai) {
;     {
;       float* tw = T + (wr * 64 + fq * 4) * TS + wc * 32 + fr;
; #pragma unroll
;       for (int m = 0; m < 4; ++m)
; #pragma unroll
;         for (int j = 0; j < 4; ++j)
; #pragma unroll
;           for (int v = 0; v < 4; ++v) tw[(m * 16 + j) * TS + (v >> 1) * 128 + (v & 1) * 16] = acc[ai][v >> 1][m][v & 1][j];
;     }
;     __syncthreads();
;     const int r0 = wid * 16;
;     const int g0 = m0 + ai * 128 + r0;
;     if constexpr (!VT) {
;       float rsv = 1.f;
;       if constexpr (EPI == E_PLEGATE || EPI == E_F32 || EPI == E_SWIGLU || EPI == E_GLAIN)
;         rsv = rsqrtf(ssin[g0 + (lane & 15)] * (1.f / 1024.f) + EPS);
;       if constexpr (EPI == E_QROPE) rsv = rsqrtf(ssin[g0 + (lane & 15)] * (1.f / 384.f) + EPS);
;       if constexpr (EPI == E_KV) rsv = rsqrtf(ssin[g0 + (lane & 15)] * (1.f / 256.f) + EPS);
;       for (int i0 = 0; i0 < 16; i0 += 8) {
;         float4 xo[8];
;         uint2 pv[8];
;         if constexpr (EPI == E_RESID || EPI == E_PLEGATE) {
; #pragma unroll
;           for (int u = 0; u < 8; ++u) {
;             const size_t ro = (size_t)(g0 + i0 + u) * 1024 + n0 + 4 * lane;
;             const int gr = g0 + i0 + u;
;             const float* xs = p.x + ro;
;             if (scale < 0.f)
;               xs = (gr < MP ? p.x_prompt + ro : p.x_sample + (ro - (size_t)MP * 1024));
;             { const f32x4 t_ = __builtin_nontemporal_load((const f32x4*)xs); xo[u] = make_float4(t_[0], t_[1], t_[2], t_[3]); }
;             if constexpr (EPI == E_PLEGATE) {
;               const unsigned long long t2_ = __builtin_nontemporal_load((const unsigned long long*)((const u16*)(wsb + OFF_PP) + ro));
;               pv[u] = make_uint2((unsigned)t2_, (unsigned)(t2_ >> 32));
;             }
;           }
;         }
; #pragma unroll
;         for (int u = 0; u < 8; ++u) {
;           const int i = i0 + u;
;           const int grow = g0 + i;
;           const float* Tr = T + (r0 + i) * TS;
;           const float rs = __int_as_float(__builtin_amdgcn_readlane(__float_as_int(rsv), i));
.LBB0_1701:
	s_or_b64 exec, exec, s[12:13]
	s_add_i32 s30, s8, 0x80
	s_ashr_i32 s31, s30, 31
	s_lshl_b64 s[10:11], s[30:31], 10
	s_add_i32 s22, s8, 0x81
	v_lshl_add_u64 v[64:65], s[10:11], 0, v[128:129]
	s_ashr_i32 s23, s22, 31
	s_add_i32 s20, s8, 0x82
	v_lshl_add_u64 v[66:67], v[64:65], 2, s[38:39]
	s_lshl_b64 s[10:11], s[22:23], 10
	s_ashr_i32 s21, s20, 31
	s_add_i32 s18, s8, 0x83
	s_waitcnt lgkmcnt(0)
	s_barrier
	ds_write2_b32 v130, v24, v28 offset1:16
	ds_write2_b32 v130, v56, v60 offset0:128 offset1:144
	ds_write2_b32 v124, v25, v29 offset0:4 offset1:20
	ds_write2_b32 v124, v57, v61 offset0:132 offset1:148
	ds_write2_b32 v121, v26, v30 offset0:8 offset1:24
	ds_write2_b32 v121, v58, v62 offset0:136 offset1:152
	ds_write2_b32 v122, v27, v31 offset0:12 offset1:28
	ds_write2_b32 v122, v59, v63 offset0:140 offset1:156
	ds_write2_b32 v123, v16, v20 offset0:64 offset1:80
	ds_write2_b32 v123, v48, v52 offset0:192 offset1:208
	ds_write2_b32 v125, v17, v21 offset0:68 offset1:84
	ds_write2_b32 v125, v49, v53 offset0:196 offset1:212
	ds_write2_b32 v126, v18, v22 offset0:72 offset1:88
	ds_write2_b32 v126, v50, v54 offset0:200 offset1:216
	ds_write2_b32 v127, v19, v23 offset0:76 offset1:92
	ds_write2_b32 v127, v51, v55 offset0:204 offset1:220
	ds_write2_b32 v131, v8, v12 offset0:128 offset1:144
	ds_write2_b32 v132, v40, v44 offset1:16
	ds_write2_b32 v132, v9, v13 offset0:132 offset1:148
	ds_write2_b32 v133, v41, v45 offset0:4 offset1:20
	ds_write2_b32 v133, v10, v14 offset0:136 offset1:152
	ds_write2_b32 v134, v42, v46 offset0:8 offset1:24
	ds_write2_b32 v134, v11, v15 offset0:140 offset1:156
	ds_write2_b32 v135, v43, v47 offset0:12 offset1:28
	ds_write2_b32 v136, v0, v4 offset0:192 offset1:208
	ds_write2_b32 v137, v32, v36 offset0:64 offset1:80
	ds_write2_b32 v137, v1, v5 offset0:196 offset1:212
	ds_write2_b32 v138, v33, v37 offset0:68 offset1:84
	ds_write2_b32 v138, v2, v6 offset0:200 offset1:216
	ds_write2_b32 v139, v34, v38 offset0:72 offset1:88
	ds_write2_b32 v139, v3, v7 offset0:204 offset1:220
	ds_write2_b32 v140, v35, v39 offset0:76 offset1:92
	s_waitcnt lgkmcnt(0)
	s_barrier
	global_load_dwordx4 v[56:59], v[66:67], off
	v_lshl_add_u64 v[54:55], s[10:11], 0, v[128:129]
	s_lshl_b64 s[10:11], s[20:21], 10
	s_ashr_i32 s19, s18, 31
	s_add_i32 s16, s8, 0x84
	v_lshl_add_u64 v[50:51], s[10:11], 0, v[128:129]
	s_lshl_b64 s[10:11], s[18:19], 10
	s_ashr_i32 s17, s16, 31
	s_add_i32 s14, s8, 0x85
	v_lshl_add_u64 v[46:47], s[10:11], 0, v[128:129]
	s_lshl_b64 s[10:11], s[16:17], 10
	s_ashr_i32 s15, s14, 31
	s_add_i32 s12, s8, 0x86
	v_lshl_add_u64 v[42:43], s[10:11], 0, v[128:129]
	s_lshl_b64 s[10:11], s[14:15], 10
	s_ashr_i32 s13, s12, 31
	v_lshl_add_u64 v[38:39], s[10:11], 0, v[128:129]
	s_lshl_b64 s[10:11], s[12:13], 10
	v_lshl_add_u64 v[34:35], s[10:11], 0, v[128:129]
	s_add_i32 s10, s8, 0x87
	s_ashr_i32 s11, s10, 31
	s_lshl_b64 s[34:35], s[10:11], 10
	v_lshl_add_u64 v[30:31], s[34:35], 0, v[128:129]
	v_lshl_add_u64 v[52:53], v[54:55], 2, s[38:39]
	v_lshl_add_u64 v[44:45], v[46:47], 2, s[38:39]
	v_lshl_add_u64 v[36:37], v[38:39], 2, s[38:39]
	v_lshl_add_u64 v[28:29], v[30:31], 2, s[38:39]
	v_lshl_add_u64 v[48:49], v[50:51], 2, s[38:39]
	global_load_dwordx4 v[24:27], v[52:53], off
	global_load_dwordx4 v[20:23], v[48:49], off
	v_lshl_add_u64 v[40:41], v[42:43], 2, s[38:39]
	global_load_dwordx4 v[16:19], v[44:45], off
	global_load_dwordx4 v[12:15], v[40:41], off
	v_lshl_add_u64 v[32:33], v[34:35], 2, s[38:39]
	global_load_dwordx4 v[8:11], v[36:37], off
	global_load_dwordx4 v[4:7], v[32:33], off
	global_load_dwordx4 v[0:3], v[28:29], off
	ds_read_b128 v[60:63], v120
	s_waitcnt vmcnt(0) lgkmcnt(0)
	v_pk_add_f32 v[56:57], v[56:57], v[60:61]
	v_pk_add_f32 v[58:59], v[58:59], v[62:63]
	global_store_dwordx4 v[66:67], v[56:59], off
	v_cvt_pk_bf16_f32 v60, v56, v57
	v_cvt_pk_bf16_f32 v61, v58, v59
	v_pk_mul_f32 v[56:57], v[56:57], v[56:57]
	v_pk_mul_f32 v[58:59], v[58:59], v[58:59]
	v_add_f32_e32 v56, v56, v57
	v_add_f32_e32 v56, v56, v58
	v_add_f32_e32 v56, v56, v59
	v_lshl_add_u64 v[62:63], v[64:65], 1, s[4:5]
	global_store_dwordx2 v[62:63], v[60:61], off
	v_add_f32_dpp v56, v56, v56 row_ror:8 row_mask:0xf bank_mask:0xf bound_ctrl:1
	s_nop 1
	v_add_f32_dpp v56, v56, v56 row_ror:4 row_mask:0xf bank_mask:0xf bound_ctrl:1
	s_nop 1
	v_add_f32_dpp v56, v56, v56 row_ror:2 row_mask:0xf bank_mask:0xf bound_ctrl:1
	s_nop 1
	v_add_f32_dpp v56, v56, v56 row_ror:1 row_mask:0xf bank_mask:0xf bound_ctrl:1
	s_nop 0
	v_readlane_b32 s9, v56, 0
	v_readlane_b32 s69, v56, 16
	v_readlane_b32 s67, v56, 32
	v_readlane_b32 s68, v56, 48
	s_and_saveexec_b64 s[34:35], vcc
	s_cbranch_execz .LBB0_1703
	s_lshl_b64 s[30:31], s[30:31], 2
	v_mov_b32_e32 v56, s69
	s_add_u32 s30, s63, s30
	v_add_f32_e32 v56, s9, v56
	s_addc_u32 s31, s64, s31
	v_add_f32_e32 v56, s67, v56
	v_add_f32_e32 v58, s68, v56
	v_mov_b64_e32 v[56:57], s[30:31]
	global_atomic_add_f32 v[56:57], v58, off
.LBB0_1703:
	s_or_b64 exec, exec, s[34:35]
	ds_read_b128 v[56:59], v120 offset:1040
	v_lshl_add_u64 v[54:55], v[54:55], 1, s[4:5]
	s_waitcnt lgkmcnt(0)
	v_pk_add_f32 v[24:25], v[24:25], v[56:57]
	v_pk_add_f32 v[26:27], v[26:27], v[58:59]
	global_store_dwordx4 v[52:53], v[24:27], off
	v_cvt_pk_bf16_f32 v52, v24, v25
	v_cvt_pk_bf16_f32 v53, v26, v27
	v_pk_mul_f32 v[24:25], v[24:25], v[24:25]
	v_pk_mul_f32 v[26:27], v[26:27], v[26:27]
	v_add_f32_e32 v24, v24, v25
	v_add_f32_e32 v24, v24, v26
	v_add_f32_e32 v24, v24, v27
	global_store_dwordx2 v[54:55], v[52:53], off
	s_nop 0
	v_add_f32_dpp v24, v24, v24 row_ror:8 row_mask:0xf bank_mask:0xf bound_ctrl:1
	s_nop 1
	v_add_f32_dpp v24, v24, v24 row_ror:4 row_mask:0xf bank_mask:0xf bound_ctrl:1
	s_nop 1
	v_add_f32_dpp v24, v24, v24 row_ror:2 row_mask:0xf bank_mask:0xf bound_ctrl:1
	s_nop 1
	v_add_f32_dpp v24, v24, v24 row_ror:1 row_mask:0xf bank_mask:0xf bound_ctrl:1
	s_nop 0
	v_readlane_b32 s9, v24, 0
	v_readlane_b32 s67, v24, 16
	v_readlane_b32 s34, v24, 32
	v_readlane_b32 s35, v24, 48
	s_and_saveexec_b64 s[30:31], vcc
	s_cbranch_execz .LBB0_1705
	s_lshl_b64 s[22:23], s[22:23], 2
	v_mov_b32_e32 v24, s67
	s_add_u32 s22, s63, s22
	v_add_f32_e32 v24, s9, v24
	s_addc_u32 s23, s64, s23
	v_add_f32_e32 v24, s34, v24
	v_add_f32_e32 v26, s35, v24
	v_mov_b64_e32 v[24:25], s[22:23]
	global_atomic_add_f32 v[24:25], v26, off
; DEVI float fsig(float x) { return __builtin_amdgcn_rcpf(1.f + __expf(-x)); }
; DEVI float bflo(unsigned u) { return __uint_as_float(u << 16); }
; DEVI float bfhi(unsigned u) { return __uint_as_float(u & 0xffff0000u); }
; template <int EPI, int TS, bool VT>
; DEVI void gemm_epilogue(const Params& p, char* smem, f32x4 (&acc)[2][2][4][2], int m0, int n0, float scale, const float* ssin,
;                         float* ssout, u16* xbout, int wid, int lane, int wr, int wc, int fr, int fq) {
;     ...
;           if constexpr (EPI == E_RESID || EPI == E_PLEGATE) {
;             const float4 a = *(const float4*)(Tr + 4 * lane);
;             const size_t ro = (size_t)grow * 1024 + n0 + 4 * lane;
;             float4 x4 = xo[u];
;             if constexpr (EPI == E_PLEGATE) {
;               x4.x += bflo(pv[u].x) * fsig(a.x * rs);
;               x4.y += bfhi(pv[u].x) * fsig(a.y * rs);
;               x4.z += bflo(pv[u].y) * fsig(a.z * rs);
;               x4.w += bfhi(pv[u].y) * fsig(a.w * rs);
;             } else {
;               const float sc = fabsf(scale);
;               x4.x += sc * a.x; x4.y += sc * a.y; x4.z += sc * a.z; x4.w += sc * a.w;
;             }
;             st_nt16(p.x + ro, x4);
;             if (xbout) {
;               uint2 o;
;               o.x = pack2(x4.x, x4.y);
;               o.y = pack2(x4.z, x4.w);
;               st_nt8(xbout + ro, o);
;             }
;             if (ssout) {
;               const float ssq = wsum(x4.x * x4.x + x4.y * x4.y + x4.z * x4.z + x4.w * x4.w, lane);
;               if (lane == 0) atomicAdd(ssout + grow, ssq);
;             }
.LBB0_1705:
	s_or_b64 exec, exec, s[30:31]
	ds_read_b128 v[24:27], v120 offset:2080
	v_lshl_add_u64 v[50:51], v[50:51], 1, s[4:5]
	s_waitcnt lgkmcnt(0)
	v_pk_add_f32 v[20:21], v[20:21], v[24:25]
	v_pk_add_f32 v[22:23], v[22:23], v[26:27]
	global_store_dwordx4 v[48:49], v[20:23], off
	v_cvt_pk_bf16_f32 v24, v20, v21
	v_cvt_pk_bf16_f32 v25, v22, v23
	v_pk_mul_f32 v[20:21], v[20:21], v[20:21]
	v_pk_mul_f32 v[22:23], v[22:23], v[22:23]
	v_add_f32_e32 v20, v20, v21
	v_add_f32_e32 v20, v20, v22
	v_add_f32_e32 v20, v20, v23
	global_store_dwordx2 v[50:51], v[24:25], off
	s_nop 0
	v_add_f32_dpp v20, v20, v20 row_ror:8 row_mask:0xf bank_mask:0xf bound_ctrl:1
	s_nop 1
	v_add_f32_dpp v20, v20, v20 row_ror:4 row_mask:0xf bank_mask:0xf bound_ctrl:1
	s_nop 1
	v_add_f32_dpp v20, v20, v20 row_ror:2 row_mask:0xf bank_mask:0xf bound_ctrl:1
	s_nop 1
	v_add_f32_dpp v20, v20, v20 row_ror:1 row_mask:0xf bank_mask:0xf bound_ctrl:1
	s_nop 0
	v_readlane_b32 s9, v20, 0
	v_readlane_b32 s34, v20, 16
	v_readlane_b32 s30, v20, 32
	v_readlane_b32 s31, v20, 48
	s_and_saveexec_b64 s[22:23], vcc
	s_cbranch_execz .LBB0_1707
	s_lshl_b64 s[20:21], s[20:21], 2
	v_mov_b32_e32 v20, s34
	s_add_u32 s20, s63, s20
	v_add_f32_e32 v20, s9, v20
	s_addc_u32 s21, s64, s21
	v_add_f32_e32 v20, s30, v20
	v_add_f32_e32 v22, s31, v20
	v_mov_b64_e32 v[20:21], s[20:21]
	global_atomic_add_f32 v[20:21], v22, off
.LBB0_1707:
	s_or_b64 exec, exec, s[22:23]
	ds_read_b128 v[20:23], v120 offset:3120
	v_lshl_add_u64 v[24:25], v[46:47], 1, s[4:5]
	s_waitcnt lgkmcnt(0)
	v_pk_add_f32 v[16:17], v[16:17], v[20:21]
	v_pk_add_f32 v[18:19], v[18:19], v[22:23]
	global_store_dwordx4 v[44:45], v[16:19], off
	v_cvt_pk_bf16_f32 v20, v16, v17
	v_cvt_pk_bf16_f32 v21, v18, v19
	v_pk_mul_f32 v[16:17], v[16:17], v[16:17]
	v_pk_mul_f32 v[18:19], v[18:19], v[18:19]
	v_add_f32_e32 v16, v16, v17
	v_add_f32_e32 v16, v16, v18
	v_add_f32_e32 v16, v16, v19
	global_store_dwordx2 v[24:25], v[20:21], off
	s_nop 0
	v_add_f32_dpp v16, v16, v16 row_ror:8 row_mask:0xf bank_mask:0xf bound_ctrl:1
	s_nop 1
	v_add_f32_dpp v16, v16, v16 row_ror:4 row_mask:0xf bank_mask:0xf bound_ctrl:1
	s_nop 1
	v_add_f32_dpp v16, v16, v16 row_ror:2 row_mask:0xf bank_mask:0xf bound_ctrl:1
	s_nop 1
	v_add_f32_dpp v16, v16, v16 row_ror:1 row_mask:0xf bank_mask:0xf bound_ctrl:1
	s_nop 0
	v_readlane_b32 s9, v16, 0
	v_readlane_b32 s30, v16, 16
	v_readlane_b32 s22, v16, 32
	v_readlane_b32 s23, v16, 48
	s_and_saveexec_b64 s[20:21], vcc
	s_cbranch_execz .LBB0_1709
	s_lshl_b64 s[18:19], s[18:19], 2
	v_mov_b32_e32 v16, s30
	s_add_u32 s18, s63, s18
	v_add_f32_e32 v16, s9, v16
	s_addc_u32 s19, s64, s19
	v_add_f32_e32 v16, s22, v16
	v_add_f32_e32 v18, s23, v16
	v_mov_b64_e32 v[16:17], s[18:19]
	global_atomic_add_f32 v[16:17], v18, off
.LBB0_1709:
	s_or_b64 exec, exec, s[20:21]
	ds_read_b128 v[16:19], v120 offset:4160
	v_lshl_add_u64 v[20:21], v[42:43], 1, s[4:5]
	s_waitcnt lgkmcnt(0)
	v_pk_add_f32 v[12:13], v[12:13], v[16:17]
	v_pk_add_f32 v[14:15], v[14:15], v[18:19]
	global_store_dwordx4 v[40:41], v[12:15], off
	v_cvt_pk_bf16_f32 v16, v12, v13
	v_cvt_pk_bf16_f32 v17, v14, v15
	v_pk_mul_f32 v[12:13], v[12:13], v[12:13]
	v_pk_mul_f32 v[14:15], v[14:15], v[14:15]
	v_add_f32_e32 v12, v12, v13
	v_add_f32_e32 v12, v12, v14
	v_add_f32_e32 v12, v12, v15
	global_store_dwordx2 v[20:21], v[16:17], off
	s_nop 0
	v_add_f32_dpp v12, v12, v12 row_ror:8 row_mask:0xf bank_mask:0xf bound_ctrl:1
	s_nop 1
	v_add_f32_dpp v12, v12, v12 row_ror:4 row_mask:0xf bank_mask:0xf bound_ctrl:1
	s_nop 1
	v_add_f32_dpp v12, v12, v12 row_ror:2 row_mask:0xf bank_mask:0xf bound_ctrl:1
	s_nop 1
	v_add_f32_dpp v12, v12, v12 row_ror:1 row_mask:0xf bank_mask:0xf bound_ctrl:1
	s_nop 0
	v_readlane_b32 s9, v12, 0
	v_readlane_b32 s22, v12, 16
	v_readlane_b32 s20, v12, 32
	v_readlane_b32 s21, v12, 48
	s_and_saveexec_b64 s[18:19], vcc
	s_cbranch_execz .LBB0_1711
	s_lshl_b64 s[16:17], s[16:17], 2
	v_mov_b32_e32 v12, s22
	s_add_u32 s16, s63, s16
	v_add_f32_e32 v12, s9, v12
	s_addc_u32 s17, s64, s17
	v_add_f32_e32 v12, s20, v12
	v_add_f32_e32 v14, s21, v12
	v_mov_b64_e32 v[12:13], s[16:17]
	global_atomic_add_f32 v[12:13], v14, off
.LBB0_1711:
	s_or_b64 exec, exec, s[18:19]
	ds_read_b128 v[12:15], v120 offset:5200
	v_lshl_add_u64 v[16:17], v[38:39], 1, s[4:5]
	s_waitcnt lgkmcnt(0)
	v_pk_add_f32 v[8:9], v[8:9], v[12:13]
	v_pk_add_f32 v[10:11], v[10:11], v[14:15]
	global_store_dwordx4 v[36:37], v[8:11], off
	v_cvt_pk_bf16_f32 v12, v8, v9
	v_cvt_pk_bf16_f32 v13, v10, v11
	v_pk_mul_f32 v[8:9], v[8:9], v[8:9]
	v_pk_mul_f32 v[10:11], v[10:11], v[10:11]
	v_add_f32_e32 v8, v8, v9
	v_add_f32_e32 v8, v8, v10
	v_add_f32_e32 v8, v8, v11
	global_store_dwordx2 v[16:17], v[12:13], off
	s_nop 0
	v_add_f32_dpp v8, v8, v8 row_ror:8 row_mask:0xf bank_mask:0xf bound_ctrl:1
	s_nop 1
	v_add_f32_dpp v8, v8, v8 row_ror:4 row_mask:0xf bank_mask:0xf bound_ctrl:1
	s_nop 1
	v_add_f32_dpp v8, v8, v8 row_ror:2 row_mask:0xf bank_mask:0xf bound_ctrl:1
	s_nop 1
	v_add_f32_dpp v8, v8, v8 row_ror:1 row_mask:0xf bank_mask:0xf bound_ctrl:1
	s_nop 0
	v_readlane_b32 s9, v8, 0
	v_readlane_b32 s20, v8, 16
	v_readlane_b32 s18, v8, 32
	v_readlane_b32 s19, v8, 48
	s_and_saveexec_b64 s[16:17], vcc
	s_cbranch_execz .LBB0_1713
	s_lshl_b64 s[14:15], s[14:15], 2
	v_mov_b32_e32 v8, s20
	s_add_u32 s14, s63, s14
	v_add_f32_e32 v8, s9, v8
	s_addc_u32 s15, s64, s15
	v_add_f32_e32 v8, s18, v8
	v_add_f32_e32 v10, s19, v8
	v_mov_b64_e32 v[8:9], s[14:15]
	global_atomic_add_f32 v[8:9], v10, off
; DEVI float fsig(float x) { return __builtin_amdgcn_rcpf(1.f + __expf(-x)); }
; template <int EPI, int TS, bool VT>
; DEVI void gemm_epilogue(const Params& p, char* smem, f32x4 (&acc)[2][2][4][2], int m0, int n0, float scale, const float* ssin,
;                         float* ssout, u16* xbout, int wid, int lane, int wr, int wc, int fr, int fq) {
;     ...
;         if constexpr (EPI == E_RESID || EPI == E_PLEGATE) {
; #pragma unroll
;           for (int u = 0; u < 8; ++u) {
;             const size_t ro = (size_t)(g0 + i0 + u) * 1024 + n0 + 4 * lane;
;             const int gr = g0 + i0 + u;
;             const float* xs = p.x + ro;
;             if (scale < 0.f)
;               xs = (gr < MP ? p.x_prompt + ro : p.x_sample + (ro - (size_t)MP * 1024));
;             { const f32x4 t_ = __builtin_nontemporal_load((const f32x4*)xs); xo[u] = make_float4(t_[0], t_[1], t_[2], t_[3]); }
;             if constexpr (EPI == E_PLEGATE) {
;               const unsigned long long t2_ = __builtin_nontemporal_load((const unsigned long long*)((const u16*)(wsb + OFF_PP) + ro));
;               pv[u] = make_uint2((unsigned)t2_, (unsigned)(t2_ >> 32));
;             }
;           }
;         }
; #pragma unroll
;         for (int u = 0; u < 8; ++u) {
;           const int i = i0 + u;
;           const int grow = g0 + i;
;           const float* Tr = T + (r0 + i) * TS;
;           const float rs = __int_as_float(__builtin_amdgcn_readlane(__float_as_int(rsv), i));
;           if constexpr (EPI == E_RESID || EPI == E_PLEGATE) {
;             const float4 a = *(const float4*)(Tr + 4 * lane);
;             const size_t ro = (size_t)grow * 1024 + n0 + 4 * lane;
;             float4 x4 = xo[u];
;             if constexpr (EPI == E_PLEGATE) {
;               x4.x += bflo(pv[u].x) * fsig(a.x * rs);
;               x4.y += bfhi(pv[u].x) * fsig(a.y * rs);
;               x4.z += bflo(pv[u].y) * fsig(a.z * rs);
;               x4.w += bfhi(pv[u].y) * fsig(a.w * rs);
;             } else {
;               const float sc = fabsf(scale);
;               x4.x += sc * a.x; x4.y += sc * a.y; x4.z += sc * a.z; x4.w += sc * a.w;
;             }
;             st_nt16(p.x + ro, x4);
;             if (xbout) {
;               uint2 o;
;               o.x = pack2(x4.x, x4.y);
;               o.y = pack2(x4.z, x4.w);
;               st_nt8(xbout + ro, o);
;             }
;             if (ssout) {
.LBB0_1713:
	s_or_b64 exec, exec, s[16:17]
	ds_read_b128 v[8:11], v120 offset:6240
	v_lshl_add_u64 v[12:13], v[34:35], 1, s[4:5]
	s_waitcnt lgkmcnt(0)
	v_pk_add_f32 v[4:5], v[4:5], v[8:9]
	v_pk_add_f32 v[6:7], v[6:7], v[10:11]
	global_store_dwordx4 v[32:33], v[4:7], off
	v_cvt_pk_bf16_f32 v8, v4, v5
	v_cvt_pk_bf16_f32 v9, v6, v7
	v_pk_mul_f32 v[4:5], v[4:5], v[4:5]
	v_pk_mul_f32 v[6:7], v[6:7], v[6:7]
	v_add_f32_e32 v4, v4, v5
	v_add_f32_e32 v4, v4, v6
	v_add_f32_e32 v4, v4, v7
	global_store_dwordx2 v[12:13], v[8:9], off
	s_nop 0
	v_add_f32_dpp v4, v4, v4 row_ror:8 row_mask:0xf bank_mask:0xf bound_ctrl:1
	s_nop 1
	v_add_f32_dpp v4, v4, v4 row_ror:4 row_mask:0xf bank_mask:0xf bound_ctrl:1
	s_nop 1
	v_add_f32_dpp v4, v4, v4 row_ror:2 row_mask:0xf bank_mask:0xf bound_ctrl:1
	s_nop 1
	v_add_f32_dpp v4, v4, v4 row_ror:1 row_mask:0xf bank_mask:0xf bound_ctrl:1
	s_nop 0
	v_readlane_b32 s9, v4, 0
	v_readlane_b32 s18, v4, 16
	v_readlane_b32 s16, v4, 32
	v_readlane_b32 s17, v4, 48
	s_and_saveexec_b64 s[14:15], vcc
	s_cbranch_execz .LBB0_1715
	s_lshl_b64 s[12:13], s[12:13], 2
	v_mov_b32_e32 v4, s18
	s_add_u32 s12, s63, s12
	v_add_f32_e32 v4, s9, v4
	s_addc_u32 s13, s64, s13
	v_add_f32_e32 v4, s16, v4
	v_add_f32_e32 v6, s17, v4
	v_mov_b64_e32 v[4:5], s[12:13]
	global_atomic_add_f32 v[4:5], v6, off
.LBB0_1715:
	s_or_b64 exec, exec, s[14:15]
	ds_read_b128 v[4:7], v120 offset:7280
	v_lshl_add_u64 v[8:9], v[30:31], 1, s[4:5]
	s_waitcnt lgkmcnt(0)
	v_pk_add_f32 v[0:1], v[0:1], v[4:5]
	v_pk_add_f32 v[2:3], v[2:3], v[6:7]
	global_store_dwordx4 v[28:29], v[0:3], off
	v_cvt_pk_bf16_f32 v4, v0, v1
	v_cvt_pk_bf16_f32 v5, v2, v3
	v_pk_mul_f32 v[0:1], v[0:1], v[0:1]
	v_pk_mul_f32 v[2:3], v[2:3], v[2:3]
	v_add_f32_e32 v0, v0, v1
	v_add_f32_e32 v0, v0, v2
	v_add_f32_e32 v0, v0, v3
	global_store_dwordx2 v[8:9], v[4:5], off
	s_nop 0
	v_add_f32_dpp v0, v0, v0 row_ror:8 row_mask:0xf bank_mask:0xf bound_ctrl:1
	s_nop 1
	v_add_f32_dpp v0, v0, v0 row_ror:4 row_mask:0xf bank_mask:0xf bound_ctrl:1
	s_nop 1
	v_add_f32_dpp v0, v0, v0 row_ror:2 row_mask:0xf bank_mask:0xf bound_ctrl:1
	s_nop 1
	v_add_f32_dpp v0, v0, v0 row_ror:1 row_mask:0xf bank_mask:0xf bound_ctrl:1
	s_nop 0
	v_readlane_b32 s9, v0, 0
	v_readlane_b32 s16, v0, 16
	v_readlane_b32 s14, v0, 32
	v_readlane_b32 s15, v0, 48
	s_and_saveexec_b64 s[12:13], vcc
	s_cbranch_execz .LBB0_1717
	s_lshl_b64 s[10:11], s[10:11], 2
	v_mov_b32_e32 v0, s16
	s_add_u32 s10, s63, s10
	v_add_f32_e32 v0, s9, v0
	s_addc_u32 s11, s64, s11
	v_add_f32_e32 v0, s14, v0
	v_add_f32_e32 v2, s15, v0
	v_mov_b64_e32 v[0:1], s[10:11]
	global_atomic_add_f32 v[0:1], v2, off
.LBB0_1717:
	s_or_b64 exec, exec, s[12:13]
	s_add_i32 s22, s8, 0x88
	s_ashr_i32 s23, s22, 31
	s_lshl_b64 s[10:11], s[22:23], 10
	s_add_i32 s20, s8, 0x89
	v_lshl_add_u64 v[64:65], s[10:11], 0, v[128:129]
	s_ashr_i32 s21, s20, 31
	s_add_i32 s18, s8, 0x8a
	v_lshl_add_u64 v[66:67], v[64:65], 2, s[38:39]
	s_lshl_b64 s[10:11], s[20:21], 10
	s_ashr_i32 s19, s18, 31
	s_add_i32 s16, s8, 0x8b
	global_load_dwordx4 v[56:59], v[66:67], off
	v_lshl_add_u64 v[54:55], s[10:11], 0, v[128:129]
	s_lshl_b64 s[10:11], s[18:19], 10
	s_ashr_i32 s17, s16, 31
	s_add_i32 s14, s8, 0x8c
	v_lshl_add_u64 v[50:51], s[10:11], 0, v[128:129]
	s_lshl_b64 s[10:11], s[16:17], 10
	s_ashr_i32 s15, s14, 31
	s_add_i32 s12, s8, 0x8d
	v_lshl_add_u64 v[46:47], s[10:11], 0, v[128:129]
	s_lshl_b64 s[10:11], s[14:15], 10
	s_ashr_i32 s13, s12, 31
	v_lshl_add_u64 v[42:43], s[10:11], 0, v[128:129]
	s_lshl_b64 s[10:11], s[12:13], 10
	v_lshl_add_u64 v[38:39], s[10:11], 0, v[128:129]
	s_add_i32 s10, s8, 0x8e
	s_ashr_i32 s11, s10, 31
	s_addk_i32 s8, 0x8f
	s_lshl_b64 s[30:31], s[10:11], 10
	s_ashr_i32 s9, s8, 31
	v_lshl_add_u64 v[34:35], s[30:31], 0, v[128:129]
	s_lshl_b64 s[30:31], s[8:9], 10
	v_lshl_add_u64 v[30:31], s[30:31], 0, v[128:129]
	v_lshl_add_u64 v[52:53], v[54:55], 2, s[38:39]
	v_lshl_add_u64 v[44:45], v[46:47], 2, s[38:39]
	v_lshl_add_u64 v[36:37], v[38:39], 2, s[38:39]
	v_lshl_add_u64 v[28:29], v[30:31], 2, s[38:39]
	v_lshl_add_u64 v[48:49], v[50:51], 2, s[38:39]
	global_load_dwordx4 v[24:27], v[52:53], off
	global_load_dwordx4 v[20:23], v[48:49], off
	v_lshl_add_u64 v[40:41], v[42:43], 2, s[38:39]
	global_load_dwordx4 v[16:19], v[44:45], off
	global_load_dwordx4 v[12:15], v[40:41], off
	v_lshl_add_u64 v[32:33], v[34:35], 2, s[38:39]
	global_load_dwordx4 v[8:11], v[36:37], off
	global_load_dwordx4 v[4:7], v[32:33], off
	global_load_dwordx4 v[0:3], v[28:29], off
	ds_read_b128 v[60:63], v120 offset:8320
	v_lshl_add_u64 v[64:65], v[64:65], 1, s[4:5]
	s_waitcnt vmcnt(0) lgkmcnt(0)
	v_pk_add_f32 v[56:57], v[56:57], v[60:61]
	v_pk_add_f32 v[58:59], v[58:59], v[62:63]
	global_store_dwordx4 v[66:67], v[56:59], off
	v_cvt_pk_bf16_f32 v60, v56, v57
	v_cvt_pk_bf16_f32 v61, v58, v59
	v_pk_mul_f32 v[56:57], v[56:57], v[56:57]
	v_pk_mul_f32 v[58:59], v[58:59], v[58:59]
	v_add_f32_e32 v56, v56, v57
	v_add_f32_e32 v56, v56, v58
	v_add_f32_e32 v56, v56, v59
	global_store_dwordx2 v[64:65], v[60:61], off
	s_nop 0
	v_add_f32_dpp v56, v56, v56 row_ror:8 row_mask:0xf bank_mask:0xf bound_ctrl:1
	s_nop 1
	v_add_f32_dpp v56, v56, v56 row_ror:4 row_mask:0xf bank_mask:0xf bound_ctrl:1
	s_nop 1
	v_add_f32_dpp v56, v56, v56 row_ror:2 row_mask:0xf bank_mask:0xf bound_ctrl:1
	s_nop 1
	v_add_f32_dpp v56, v56, v56 row_ror:1 row_mask:0xf bank_mask:0xf bound_ctrl:1
	s_nop 0
	v_readlane_b32 s34, v56, 0
	v_readlane_b32 s68, v56, 16
	v_readlane_b32 s35, v56, 32
	v_readlane_b32 s67, v56, 48
	s_and_saveexec_b64 s[30:31], vcc
	s_cbranch_execz .LBB0_1719
	s_lshl_b64 s[22:23], s[22:23], 2
	v_mov_b32_e32 v56, s68
	s_add_u32 s22, s63, s22
	v_add_f32_e32 v56, s34, v56
	s_addc_u32 s23, s64, s23
	v_add_f32_e32 v56, s35, v56
	v_add_f32_e32 v58, s67, v56
	v_mov_b64_e32 v[56:57], s[22:23]
	global_atomic_add_f32 v[56:57], v58, off
; DEVI float fsig(float x) { return __builtin_amdgcn_rcpf(1.f + __expf(-x)); }
; DEVI float bflo(unsigned u) { return __uint_as_float(u << 16); }
; DEVI float bfhi(unsigned u) { return __uint_as_float(u & 0xffff0000u); }
; template <int EPI, int TS, bool VT>
; DEVI void gemm_epilogue(const Params& p, char* smem, f32x4 (&acc)[2][2][4][2], int m0, int n0, float scale, const float* ssin,
;                         float* ssout, u16* xbout, int wid, int lane, int wr, int wc, int fr, int fq) {
;     ...
;           if constexpr (EPI == E_RESID || EPI == E_PLEGATE) {
;             const float4 a = *(const float4*)(Tr + 4 * lane);
;             const size_t ro = (size_t)grow * 1024 + n0 + 4 * lane;
;             float4 x4 = xo[u];
;             if constexpr (EPI == E_PLEGATE) {
;               x4.x += bflo(pv[u].x) * fsig(a.x * rs);
;               x4.y += bfhi(pv[u].x) * fsig(a.y * rs);
;               x4.z += bflo(pv[u].y) * fsig(a.z * rs);
;               x4.w += bfhi(pv[u].y) * fsig(a.w * rs);
;             } else {
;               const float sc = fabsf(scale);
;               x4.x += sc * a.x; x4.y += sc * a.y; x4.z += sc * a.z; x4.w += sc * a.w;
;             }
;             st_nt16(p.x + ro, x4);
;             if (xbout) {
;               uint2 o;
;               o.x = pack2(x4.x, x4.y);
;               o.y = pack2(x4.z, x4.w);
;               st_nt8(xbout + ro, o);
;             }
;             if (ssout) {
;               const float ssq = wsum(x4.x * x4.x + x4.y * x4.y + x4.z * x4.z + x4.w * x4.w, lane);
;               if (lane == 0) atomicAdd(ssout + grow, ssq);
;             }
.LBB0_1719:
	s_or_b64 exec, exec, s[30:31]
	ds_read_b128 v[56:59], v120 offset:9360
	v_lshl_add_u64 v[54:55], v[54:55], 1, s[4:5]
	s_waitcnt lgkmcnt(0)
	v_pk_add_f32 v[24:25], v[24:25], v[56:57]
	v_pk_add_f32 v[26:27], v[26:27], v[58:59]
	global_store_dwordx4 v[52:53], v[24:27], off
	v_cvt_pk_bf16_f32 v52, v24, v25
	v_cvt_pk_bf16_f32 v53, v26, v27
	v_pk_mul_f32 v[24:25], v[24:25], v[24:25]
	v_pk_mul_f32 v[26:27], v[26:27], v[26:27]
	v_add_f32_e32 v24, v24, v25
	v_add_f32_e32 v24, v24, v26
	v_add_f32_e32 v24, v24, v27
	global_store_dwordx2 v[54:55], v[52:53], off
	s_nop 0
	v_add_f32_dpp v24, v24, v24 row_ror:8 row_mask:0xf bank_mask:0xf bound_ctrl:1
	s_nop 1
	v_add_f32_dpp v24, v24, v24 row_ror:4 row_mask:0xf bank_mask:0xf bound_ctrl:1
	s_nop 1
	v_add_f32_dpp v24, v24, v24 row_ror:2 row_mask:0xf bank_mask:0xf bound_ctrl:1
	s_nop 1
	v_add_f32_dpp v24, v24, v24 row_ror:1 row_mask:0xf bank_mask:0xf bound_ctrl:1
	s_nop 0
	v_readlane_b32 s30, v24, 0
	v_readlane_b32 s35, v24, 16
	v_readlane_b32 s31, v24, 32
	v_readlane_b32 s34, v24, 48
	s_and_saveexec_b64 s[22:23], vcc
	s_cbranch_execz .LBB0_1721
	s_lshl_b64 s[20:21], s[20:21], 2
	v_mov_b32_e32 v24, s35
	s_add_u32 s20, s63, s20
	v_add_f32_e32 v24, s30, v24
	s_addc_u32 s21, s64, s21
	v_add_f32_e32 v24, s31, v24
	v_add_f32_e32 v26, s34, v24
	v_mov_b64_e32 v[24:25], s[20:21]
	global_atomic_add_f32 v[24:25], v26, off
.LBB0_1721:
	s_or_b64 exec, exec, s[22:23]
	ds_read_b128 v[24:27], v120 offset:10400
	v_lshl_add_u64 v[50:51], v[50:51], 1, s[4:5]
	s_waitcnt lgkmcnt(0)
	v_pk_add_f32 v[20:21], v[20:21], v[24:25]
	v_pk_add_f32 v[22:23], v[22:23], v[26:27]
	global_store_dwordx4 v[48:49], v[20:23], off
	v_cvt_pk_bf16_f32 v24, v20, v21
	v_cvt_pk_bf16_f32 v25, v22, v23
	v_pk_mul_f32 v[20:21], v[20:21], v[20:21]
	v_pk_mul_f32 v[22:23], v[22:23], v[22:23]
	v_add_f32_e32 v20, v20, v21
	v_add_f32_e32 v20, v20, v22
	v_add_f32_e32 v20, v20, v23
	global_store_dwordx2 v[50:51], v[24:25], off
	s_nop 0
	v_add_f32_dpp v20, v20, v20 row_ror:8 row_mask:0xf bank_mask:0xf bound_ctrl:1
	s_nop 1
	v_add_f32_dpp v20, v20, v20 row_ror:4 row_mask:0xf bank_mask:0xf bound_ctrl:1
	s_nop 1
	v_add_f32_dpp v20, v20, v20 row_ror:2 row_mask:0xf bank_mask:0xf bound_ctrl:1
	s_nop 1
	v_add_f32_dpp v20, v20, v20 row_ror:1 row_mask:0xf bank_mask:0xf bound_ctrl:1
	s_nop 0
	v_readlane_b32 s22, v20, 0
	v_readlane_b32 s31, v20, 16
	v_readlane_b32 s23, v20, 32
	v_readlane_b32 s30, v20, 48
	s_and_saveexec_b64 s[20:21], vcc
	s_cbranch_execz .LBB0_1723
	s_lshl_b64 s[18:19], s[18:19], 2
	v_mov_b32_e32 v20, s31
	s_add_u32 s18, s63, s18
	v_add_f32_e32 v20, s22, v20
	s_addc_u32 s19, s64, s19
	v_add_f32_e32 v20, s23, v20
	v_add_f32_e32 v22, s30, v20
	v_mov_b64_e32 v[20:21], s[18:19]
	global_atomic_add_f32 v[20:21], v22, off
.LBB0_1723:
	s_or_b64 exec, exec, s[20:21]
	ds_read_b128 v[20:23], v120 offset:11440
	v_lshl_add_u64 v[24:25], v[46:47], 1, s[4:5]
	s_waitcnt lgkmcnt(0)
	v_pk_add_f32 v[16:17], v[16:17], v[20:21]
	v_pk_add_f32 v[18:19], v[18:19], v[22:23]
	global_store_dwordx4 v[44:45], v[16:19], off
	v_cvt_pk_bf16_f32 v20, v16, v17
	v_cvt_pk_bf16_f32 v21, v18, v19
	v_pk_mul_f32 v[16:17], v[16:17], v[16:17]
	v_pk_mul_f32 v[18:19], v[18:19], v[18:19]
	v_add_f32_e32 v16, v16, v17
	v_add_f32_e32 v16, v16, v18
	v_add_f32_e32 v16, v16, v19
	global_store_dwordx2 v[24:25], v[20:21], off
	s_nop 0
	v_add_f32_dpp v16, v16, v16 row_ror:8 row_mask:0xf bank_mask:0xf bound_ctrl:1
	s_nop 1
	v_add_f32_dpp v16, v16, v16 row_ror:4 row_mask:0xf bank_mask:0xf bound_ctrl:1
	s_nop 1
	v_add_f32_dpp v16, v16, v16 row_ror:2 row_mask:0xf bank_mask:0xf bound_ctrl:1
	s_nop 1
	v_add_f32_dpp v16, v16, v16 row_ror:1 row_mask:0xf bank_mask:0xf bound_ctrl:1
	s_nop 0
	v_readlane_b32 s20, v16, 0
	v_readlane_b32 s23, v16, 16
	v_readlane_b32 s21, v16, 32
	v_readlane_b32 s22, v16, 48
	s_and_saveexec_b64 s[18:19], vcc
	s_cbranch_execz .LBB0_1725
	s_lshl_b64 s[16:17], s[16:17], 2
	v_mov_b32_e32 v16, s23
	s_add_u32 s16, s63, s16
	v_add_f32_e32 v16, s20, v16
	s_addc_u32 s17, s64, s17
	v_add_f32_e32 v16, s21, v16
	v_add_f32_e32 v18, s22, v16
	v_mov_b64_e32 v[16:17], s[16:17]
	global_atomic_add_f32 v[16:17], v18, off
; DEVI float fsig(float x) { return __builtin_amdgcn_rcpf(1.f + __expf(-x)); }
; DEVI float bflo(unsigned u) { return __uint_as_float(u << 16); }
; DEVI float bfhi(unsigned u) { return __uint_as_float(u & 0xffff0000u); }
; template <int EPI, int TS, bool VT>
; DEVI void gemm_epilogue(const Params& p, char* smem, f32x4 (&acc)[2][2][4][2], int m0, int n0, float scale, const float* ssin,
;                         float* ssout, u16* xbout, int wid, int lane, int wr, int wc, int fr, int fq) {
;     ...
;           if constexpr (EPI == E_RESID || EPI == E_PLEGATE) {
;             const float4 a = *(const float4*)(Tr + 4 * lane);
;             const size_t ro = (size_t)grow * 1024 + n0 + 4 * lane;
;             float4 x4 = xo[u];
;             if constexpr (EPI == E_PLEGATE) {
;               x4.x += bflo(pv[u].x) * fsig(a.x * rs);
;               x4.y += bfhi(pv[u].x) * fsig(a.y * rs);
;               x4.z += bflo(pv[u].y) * fsig(a.z * rs);
;               x4.w += bfhi(pv[u].y) * fsig(a.w * rs);
;             } else {
;               const float sc = fabsf(scale);
;               x4.x += sc * a.x; x4.y += sc * a.y; x4.z += sc * a.z; x4.w += sc * a.w;
;             }
;             st_nt16(p.x + ro, x4);
;             if (xbout) {
;               uint2 o;
;               o.x = pack2(x4.x, x4.y);
;               o.y = pack2(x4.z, x4.w);
;               st_nt8(xbout + ro, o);
;             }
;             if (ssout) {
;               const float ssq = wsum(x4.x * x4.x + x4.y * x4.y + x4.z * x4.z + x4.w * x4.w, lane);
;               if (lane == 0) atomicAdd(ssout + grow, ssq);
;             }
.LBB0_1725:
	s_or_b64 exec, exec, s[18:19]
	ds_read_b128 v[16:19], v120 offset:12480
	v_lshl_add_u64 v[20:21], v[42:43], 1, s[4:5]
	s_waitcnt lgkmcnt(0)
	v_pk_add_f32 v[12:13], v[12:13], v[16:17]
	v_pk_add_f32 v[14:15], v[14:15], v[18:19]
	global_store_dwordx4 v[40:41], v[12:15], off
	v_cvt_pk_bf16_f32 v16, v12, v13
	v_cvt_pk_bf16_f32 v17, v14, v15
	v_pk_mul_f32 v[12:13], v[12:13], v[12:13]
	v_pk_mul_f32 v[14:15], v[14:15], v[14:15]
	v_add_f32_e32 v12, v12, v13
	v_add_f32_e32 v12, v12, v14
	v_add_f32_e32 v12, v12, v15
	global_store_dwordx2 v[20:21], v[16:17], off
	s_nop 0
	v_add_f32_dpp v12, v12, v12 row_ror:8 row_mask:0xf bank_mask:0xf bound_ctrl:1
	s_nop 1
	v_add_f32_dpp v12, v12, v12 row_ror:4 row_mask:0xf bank_mask:0xf bound_ctrl:1
	s_nop 1
	v_add_f32_dpp v12, v12, v12 row_ror:2 row_mask:0xf bank_mask:0xf bound_ctrl:1
	s_nop 1
	v_add_f32_dpp v12, v12, v12 row_ror:1 row_mask:0xf bank_mask:0xf bound_ctrl:1
	s_nop 0
	v_readlane_b32 s18, v12, 0
	v_readlane_b32 s21, v12, 16
	v_readlane_b32 s19, v12, 32
	v_readlane_b32 s20, v12, 48
	s_and_saveexec_b64 s[16:17], vcc
	s_cbranch_execz .LBB0_1727
	s_lshl_b64 s[14:15], s[14:15], 2
	v_mov_b32_e32 v12, s21
	s_add_u32 s14, s63, s14
	v_add_f32_e32 v12, s18, v12
	s_addc_u32 s15, s64, s15
	v_add_f32_e32 v12, s19, v12
	v_add_f32_e32 v14, s20, v12
	v_mov_b64_e32 v[12:13], s[14:15]
	global_atomic_add_f32 v[12:13], v14, off
.LBB0_1727:
	s_or_b64 exec, exec, s[16:17]
	ds_read_b128 v[12:15], v120 offset:13520
	v_lshl_add_u64 v[16:17], v[38:39], 1, s[4:5]
	s_waitcnt lgkmcnt(0)
	v_pk_add_f32 v[8:9], v[8:9], v[12:13]
	v_pk_add_f32 v[10:11], v[10:11], v[14:15]
	global_store_dwordx4 v[36:37], v[8:11], off
	v_cvt_pk_bf16_f32 v12, v8, v9
	v_cvt_pk_bf16_f32 v13, v10, v11
	v_pk_mul_f32 v[8:9], v[8:9], v[8:9]
	v_pk_mul_f32 v[10:11], v[10:11], v[10:11]
	v_add_f32_e32 v8, v8, v9
	v_add_f32_e32 v8, v8, v10
	v_add_f32_e32 v8, v8, v11
	global_store_dwordx2 v[16:17], v[12:13], off
	s_nop 0
	v_add_f32_dpp v8, v8, v8 row_ror:8 row_mask:0xf bank_mask:0xf bound_ctrl:1
	s_nop 1
	v_add_f32_dpp v8, v8, v8 row_ror:4 row_mask:0xf bank_mask:0xf bound_ctrl:1
	s_nop 1
	v_add_f32_dpp v8, v8, v8 row_ror:2 row_mask:0xf bank_mask:0xf bound_ctrl:1
	s_nop 1
	v_add_f32_dpp v8, v8, v8 row_ror:1 row_mask:0xf bank_mask:0xf bound_ctrl:1
	s_nop 0
	v_readlane_b32 s16, v8, 0
	v_readlane_b32 s19, v8, 16
	v_readlane_b32 s17, v8, 32
	v_readlane_b32 s18, v8, 48
	s_and_saveexec_b64 s[14:15], vcc
	s_cbranch_execz .LBB0_1729
	s_lshl_b64 s[12:13], s[12:13], 2
	v_mov_b32_e32 v8, s19
	s_add_u32 s12, s63, s12
	v_add_f32_e32 v8, s16, v8
	s_addc_u32 s13, s64, s13
	v_add_f32_e32 v8, s17, v8
	v_add_f32_e32 v10, s18, v8
	v_mov_b64_e32 v[8:9], s[12:13]
	global_atomic_add_f32 v[8:9], v10, off
.LBB0_1729:
	s_or_b64 exec, exec, s[14:15]
	ds_read_b128 v[8:11], v120 offset:14560
	v_lshl_add_u64 v[12:13], v[34:35], 1, s[4:5]
	s_waitcnt lgkmcnt(0)
	v_pk_add_f32 v[4:5], v[4:5], v[8:9]
	v_pk_add_f32 v[6:7], v[6:7], v[10:11]
	global_store_dwordx4 v[32:33], v[4:7], off
	v_cvt_pk_bf16_f32 v8, v4, v5
	v_cvt_pk_bf16_f32 v9, v6, v7
	v_pk_mul_f32 v[4:5], v[4:5], v[4:5]
	v_pk_mul_f32 v[6:7], v[6:7], v[6:7]
	v_add_f32_e32 v4, v4, v5
	v_add_f32_e32 v4, v4, v6
	v_add_f32_e32 v4, v4, v7
	global_store_dwordx2 v[12:13], v[8:9], off
	s_nop 0
	v_add_f32_dpp v4, v4, v4 row_ror:8 row_mask:0xf bank_mask:0xf bound_ctrl:1
	s_nop 1
	v_add_f32_dpp v4, v4, v4 row_ror:4 row_mask:0xf bank_mask:0xf bound_ctrl:1
	s_nop 1
	v_add_f32_dpp v4, v4, v4 row_ror:2 row_mask:0xf bank_mask:0xf bound_ctrl:1
	s_nop 1
	v_add_f32_dpp v4, v4, v4 row_ror:1 row_mask:0xf bank_mask:0xf bound_ctrl:1
	s_nop 0
	v_readlane_b32 s14, v4, 0
	v_readlane_b32 s17, v4, 16
	v_readlane_b32 s15, v4, 32
	v_readlane_b32 s16, v4, 48
	s_and_saveexec_b64 s[12:13], vcc
	s_cbranch_execz .LBB0_1731
	s_lshl_b64 s[10:11], s[10:11], 2
	v_mov_b32_e32 v4, s17
	s_add_u32 s10, s63, s10
	v_add_f32_e32 v4, s14, v4
	s_addc_u32 s11, s64, s11
	v_add_f32_e32 v4, s15, v4
	v_add_f32_e32 v6, s16, v4
	v_mov_b64_e32 v[4:5], s[10:11]
	global_atomic_add_f32 v[4:5], v6, off
.LBB0_1731:
	s_or_b64 exec, exec, s[12:13]
	ds_read_b128 v[4:7], v120 offset:15600
	v_lshl_add_u64 v[8:9], v[30:31], 1, s[4:5]
	s_waitcnt lgkmcnt(0)
	v_pk_add_f32 v[0:1], v[0:1], v[4:5]
	v_pk_add_f32 v[2:3], v[2:3], v[6:7]
	global_store_dwordx4 v[28:29], v[0:3], off
	v_cvt_pk_bf16_f32 v4, v0, v1
	v_cvt_pk_bf16_f32 v5, v2, v3
	v_pk_mul_f32 v[0:1], v[0:1], v[0:1]
	v_pk_mul_f32 v[2:3], v[2:3], v[2:3]
	v_add_f32_e32 v0, v0, v1
	v_add_f32_e32 v0, v0, v2
	v_add_f32_e32 v0, v0, v3
	global_store_dwordx2 v[8:9], v[4:5], off
	s_nop 0
	v_add_f32_dpp v0, v0, v0 row_ror:8 row_mask:0xf bank_mask:0xf bound_ctrl:1
	s_nop 1
	v_add_f32_dpp v0, v0, v0 row_ror:4 row_mask:0xf bank_mask:0xf bound_ctrl:1
	s_nop 1
	v_add_f32_dpp v0, v0, v0 row_ror:2 row_mask:0xf bank_mask:0xf bound_ctrl:1
	s_nop 1
	v_add_f32_dpp v0, v0, v0 row_ror:1 row_mask:0xf bank_mask:0xf bound_ctrl:1
	s_nop 0
	v_readlane_b32 s12, v0, 0
	v_readlane_b32 s15, v0, 16
	v_readlane_b32 s13, v0, 32
	v_readlane_b32 s14, v0, 48
	s_and_saveexec_b64 s[10:11], vcc
	s_cbranch_execz .LBB0_1660
	s_lshl_b64 s[8:9], s[8:9], 2
	v_mov_b32_e32 v0, s15
	s_add_u32 s8, s63, s8
	v_add_f32_e32 v0, s12, v0
	s_addc_u32 s9, s64, s9
	v_add_f32_e32 v0, s13, v0
	v_add_f32_e32 v2, s14, v0
	v_mov_b64_e32 v[0:1], s[8:9]
	global_atomic_add_f32 v[0:1], v2, off
	s_branch .LBB0_1660

; template <int EPI, int TS, bool VT>
; DEVI void gemm_epilogue(const Params& p, char* smem, f32x4 (&acc)[2][2][4][2], int m0, int n0, float scale, const float* ssin,
;                         float* ssout, u16* xbout, int wid, int lane, int wr, int wc, int fr, int fq) {
;     ...
;       float* tw = T + (wr * 64 + fq * 4) * TS + wc * 32 + fr;
; #pragma unroll
;       for (int m = 0; m < 4; ++m)
; #pragma unroll
;         for (int j = 0; j < 4; ++j)
; #pragma unroll
;           for (int v = 0; v < 4; ++v) tw[(m * 16 + j) * TS + (v >> 1) * 128 + (v & 1) * 16] = acc[ai][v >> 1][m][v & 1][j];
;     }
;     __syncthreads();
;     ...
;         if constexpr (EPI == E_RESID || EPI == E_PLEGATE) {
; #pragma unroll
;           for (int u = 0; u < 8; ++u) {
;             const size_t ro = (size_t)(g0 + i0 + u) * 1024 + n0 + 4 * lane;
;             const int gr = g0 + i0 + u;
;             const float* xs = p.x + ro;
;             if (scale < 0.f)
;               xs = (gr < MP ? p.x_prompt + ro : p.x_sample + (ro - (size_t)MP * 1024));
;             { const f32x4 t_ = __builtin_nontemporal_load((const f32x4*)xs); xo[u] = make_float4(t_[0], t_[1], t_[2], t_[3]); }
;             if constexpr (EPI == E_PLEGATE) {
;               const unsigned long long t2_ = __builtin_nontemporal_load((const unsigned long long*)((const u16*)(wsb + OFF_PP) + ro));
;               pv[u] = make_uint2((unsigned)t2_, (unsigned)(t2_ >> 32));
;             }
;           }
;         }
; #pragma unroll
;         for (int u = 0; u < 8; ++u) {
;           const int i = i0 + u;
;           const int grow = g0 + i;
;           const float* Tr = T + (r0 + i) * TS;
;           const float rs = __int_as_float(__builtin_amdgcn_readlane(__float_as_int(rsv), i));
;           if constexpr (EPI == E_RESID || EPI == E_PLEGATE) {
;             const float4 a = *(const float4*)(Tr + 4 * lane);
;             const size_t ro = (size_t)grow * 1024 + n0 + 4 * lane;
;             float4 x4 = xo[u];
;             if constexpr (EPI == E_PLEGATE) {
;               x4.x += bflo(pv[u].x) * fsig(a.x * rs);
;               x4.y += bfhi(pv[u].x) * fsig(a.y * rs);
;               x4.z += bflo(pv[u].y) * fsig(a.z * rs);
;               x4.w += bfhi(pv[u].y) * fsig(a.w * rs);
;             } else {
;               const float sc = fabsf(scale);
;               x4.x += sc * a.x; x4.y += sc * a.y; x4.z += sc * a.z; x4.w += sc * a.w;
.LBB0_1782:
	v_readlane_b32 s10, v254, 13
	v_readlane_b32 s11, v254, 14
	v_lshrrev_b32_e32 v128, 2, v132
	v_and_or_b32 v128, v128, 12, s62
	s_movk_i32 s10, 0x410
	v_mul_lo_u32 v128, v128, s10
	s_lshl_b32 s10, s35, 7
	v_lshlrev_b32_e32 v129, 2, v133
	v_add3_u32 v130, s10, v128, v129
	s_lshl_b32 s10, s34, 4
	s_add_i32 s10, s10, s22
	v_and_b32_e32 v141, 63, v132
	ds_write2_b32 v130, v92, v100 offset1:16
	ds_write2_b32 v130, v120, v124 offset0:128 offset1:144
	v_add_u32_e32 v124, 0x400, v130
	s_ashr_i32 s11, s10, 31
	v_lshl_or_b32 v128, v141, 2, s23
	v_mov_b32_e32 v129, s31
	ds_write2_b32 v124, v93, v101 offset0:4 offset1:20
	ds_write2_b32 v124, v121, v125 offset0:132 offset1:148
	v_add_u32_e32 v121, 0x800, v130
	s_lshl_b64 s[12:13], s[10:11], 10
	s_or_b32 s30, s10, 1
	ds_write2_b32 v121, v94, v102 offset0:8 offset1:24
	ds_write2_b32 v121, v122, v126 offset0:136 offset1:152
	v_add_u32_e32 v122, 0xc00, v130
	v_lshl_add_u64 v[146:147], s[12:13], 0, v[128:129]
	s_ashr_i32 s31, s30, 31
	s_or_b32 s22, s10, 2
	ds_write2_b32 v122, v95, v103 offset0:12 offset1:28
	ds_write2_b32 v122, v123, v127 offset0:140 offset1:156
	v_add_u32_e32 v123, 0x4000, v130
	v_add_u32_e32 v125, 0x4400, v130
	v_add_u32_e32 v126, 0x4800, v130
	v_add_u32_e32 v127, 0x4c00, v130
	v_add_u32_e32 v131, 0x8000, v130
	v_add_u32_e32 v132, 0x8400, v130
	v_add_u32_e32 v133, 0x8800, v130
	v_add_u32_e32 v134, 0x8c00, v130
	v_add_u32_e32 v135, 0x9000, v130
	v_add_u32_e32 v136, 0xc000, v130
	v_add_u32_e32 v137, 0xc400, v130
	v_add_u32_e32 v138, 0xc800, v130
	v_add_u32_e32 v139, 0xcc00, v130
	v_add_u32_e32 v140, 0xd000, v130
	v_lshl_add_u64 v[156:157], v[146:147], 2, s[38:39]
	s_lshl_b64 s[12:13], s[30:31], 10
	s_ashr_i32 s23, s22, 31
	s_or_b32 s20, s10, 3
	ds_write2_b32 v123, v80, v84 offset0:64 offset1:80
	ds_write2_b32 v123, v112, v116 offset0:192 offset1:208
	ds_write2_b32 v125, v81, v85 offset0:68 offset1:84
	ds_write2_b32 v125, v113, v117 offset0:196 offset1:212
	ds_write2_b32 v126, v82, v86 offset0:72 offset1:88
	ds_write2_b32 v126, v114, v118 offset0:200 offset1:216
	ds_write2_b32 v127, v83, v87 offset0:76 offset1:92
	ds_write2_b32 v127, v115, v119 offset0:204 offset1:220
	ds_write2_b32 v131, v72, v76 offset0:128 offset1:144
	ds_write2_b32 v132, v104, v108 offset1:16
	ds_write2_b32 v132, v73, v77 offset0:132 offset1:148
	ds_write2_b32 v133, v105, v109 offset0:4 offset1:20
	ds_write2_b32 v133, v74, v78 offset0:136 offset1:152
	ds_write2_b32 v134, v106, v110 offset0:8 offset1:24
	ds_write2_b32 v134, v75, v79 offset0:140 offset1:156
	ds_write2_b32 v135, v107, v111 offset0:12 offset1:28
	ds_write2_b32 v136, v64, v68 offset0:192 offset1:208
	ds_write2_b32 v137, v88, v96 offset0:64 offset1:80
	ds_write2_b32 v137, v65, v69 offset0:196 offset1:212
	ds_write2_b32 v138, v89, v97 offset0:68 offset1:84
	ds_write2_b32 v138, v66, v70 offset0:200 offset1:216
	ds_write2_b32 v139, v90, v98 offset0:72 offset1:88
	ds_write2_b32 v139, v67, v71 offset0:204 offset1:220
	ds_write2_b32 v140, v91, v99 offset0:76 offset1:92
	s_waitcnt vmcnt(0) lgkmcnt(0)
	s_barrier
	global_load_dwordx4 v[142:145], v[156:157], off
	v_lshl_add_u64 v[118:119], s[12:13], 0, v[128:129]
	s_lshl_b64 s[12:13], s[22:23], 10
	s_ashr_i32 s21, s20, 31
	s_or_b32 s18, s10, 4
	v_lshl_add_u64 v[114:115], s[12:13], 0, v[128:129]
	s_lshl_b64 s[12:13], s[20:21], 10
	s_ashr_i32 s19, s18, 31
	s_or_b32 s16, s10, 5
	v_lshl_add_u64 v[110:111], s[12:13], 0, v[128:129]
	s_lshl_b64 s[12:13], s[18:19], 10
	s_ashr_i32 s17, s16, 31
	s_or_b32 s14, s10, 6
	v_lshl_add_u64 v[106:107], s[12:13], 0, v[128:129]
	s_lshl_b64 s[12:13], s[16:17], 10
	s_ashr_i32 s15, s14, 31
	v_lshl_add_u64 v[102:103], s[12:13], 0, v[128:129]
	s_lshl_b64 s[12:13], s[14:15], 10
	v_lshl_add_u64 v[98:99], s[12:13], 0, v[128:129]
	s_or_b32 s12, s10, 7
	s_ashr_i32 s13, s12, 31
	s_lshl_b64 s[62:63], s[12:13], 10
	v_lshl_add_u64 v[94:95], s[62:63], 0, v[128:129]
	v_lshl_add_u64 v[116:117], v[118:119], 2, s[38:39]
	v_lshl_add_u64 v[108:109], v[110:111], 2, s[38:39]
	v_lshl_add_u64 v[100:101], v[102:103], 2, s[38:39]
	v_lshl_add_u64 v[92:93], v[94:95], 2, s[38:39]
	v_lshl_add_u64 v[112:113], v[114:115], 2, s[38:39]
	global_load_dwordx4 v[88:91], v[116:117], off
	global_load_dwordx4 v[84:87], v[112:113], off
	v_lshl_add_u64 v[104:105], v[106:107], 2, s[38:39]
	global_load_dwordx4 v[80:83], v[108:109], off
	global_load_dwordx4 v[76:79], v[104:105], off
	v_lshl_add_u64 v[96:97], v[98:99], 2, s[38:39]
	global_load_dwordx4 v[72:75], v[100:101], off
	global_load_dwordx4 v[68:71], v[96:97], off
	global_load_dwordx4 v[64:67], v[92:93], off
	v_lshlrev_b32_e32 v120, 4, v141
	s_mulk_i32 s34, 0x4100
	v_add_u32_e32 v120, s34, v120
	ds_read_b128 v[152:155], v120
	v_cmp_eq_u32_e32 vcc, 0, v141
	v_lshl_add_u64 v[146:147], v[146:147], 1, s[6:7]
	s_waitcnt vmcnt(7) lgkmcnt(0)
	v_pk_fma_f32 v[142:143], v[152:153], 0.5, v[142:143] op_sel_hi:[1,0,1]
	v_pk_fma_f32 v[144:145], v[154:155], 0.5, v[144:145] op_sel_hi:[1,0,1]
	global_store_dwordx4 v[156:157], v[142:145], off
	v_cvt_pk_bf16_f32 v152, v142, v143
	v_cvt_pk_bf16_f32 v153, v144, v145
	v_pk_mul_f32 v[142:143], v[142:143], v[142:143]
	v_pk_mul_f32 v[144:145], v[144:145], v[144:145]
	v_add_f32_e32 v141, v142, v143
	v_add_f32_e32 v141, v141, v144
	v_add_f32_e32 v141, v141, v145
	global_store_dwordx2 v[146:147], v[152:153], off
	s_nop 0
	v_add_f32_dpp v141, v141, v141 row_ror:8 row_mask:0xf bank_mask:0xf bound_ctrl:1
	s_nop 1
	v_add_f32_dpp v141, v141, v141 row_ror:4 row_mask:0xf bank_mask:0xf bound_ctrl:1
	s_nop 1
	v_add_f32_dpp v141, v141, v141 row_ror:2 row_mask:0xf bank_mask:0xf bound_ctrl:1
	s_nop 1
	v_add_f32_dpp v141, v141, v141 row_ror:1 row_mask:0xf bank_mask:0xf bound_ctrl:1
	s_nop 0
	v_readlane_b32 s62, v141, 0
	v_readlane_b32 s69, v141, 16
	v_readlane_b32 s63, v141, 32
	v_readlane_b32 s68, v141, 48
	s_and_saveexec_b64 s[34:35], vcc
	s_cbranch_execz .LBB0_1784
	s_lshl_b64 s[70:71], s[10:11], 2
	v_mov_b32_e32 v141, s69
	s_add_u32 s70, s2, s70
	v_add_f32_e32 v141, s62, v141
	s_addc_u32 s71, s3, s71
	v_add_f32_e32 v141, s63, v141
	v_add_f32_e32 v141, s68, v141
	v_mov_b64_e32 v[142:143], s[70:71]
	global_atomic_add_f32 v[142:143], v141, off
; DEVI float fsig(float x) { return __builtin_amdgcn_rcpf(1.f + __expf(-x)); }
; DEVI float bflo(unsigned u) { return __uint_as_float(u << 16); }
; DEVI float bfhi(unsigned u) { return __uint_as_float(u & 0xffff0000u); }
; template <int EPI, int TS, bool VT>
; DEVI void gemm_epilogue(const Params& p, char* smem, f32x4 (&acc)[2][2][4][2], int m0, int n0, float scale, const float* ssin,
;                         float* ssout, u16* xbout, int wid, int lane, int wr, int wc, int fr, int fq) {
;     ...
;           if constexpr (EPI == E_RESID || EPI == E_PLEGATE) {
;             const float4 a = *(const float4*)(Tr + 4 * lane);
;             const size_t ro = (size_t)grow * 1024 + n0 + 4 * lane;
;             float4 x4 = xo[u];
;             if constexpr (EPI == E_PLEGATE) {
;               x4.x += bflo(pv[u].x) * fsig(a.x * rs);
;               x4.y += bfhi(pv[u].x) * fsig(a.y * rs);
;               x4.z += bflo(pv[u].y) * fsig(a.z * rs);
;               x4.w += bfhi(pv[u].y) * fsig(a.w * rs);
;             } else {
;               const float sc = fabsf(scale);
;               x4.x += sc * a.x; x4.y += sc * a.y; x4.z += sc * a.z; x4.w += sc * a.w;
;             }
;             st_nt16(p.x + ro, x4);
;             if (xbout) {
;               uint2 o;
;               o.x = pack2(x4.x, x4.y);
;               o.y = pack2(x4.z, x4.w);
;               st_nt8(xbout + ro, o);
;             }
;             if (ssout) {
;               const float ssq = wsum(x4.x * x4.x + x4.y * x4.y + x4.z * x4.z + x4.w * x4.w, lane);
;               if (lane == 0) atomicAdd(ssout + grow, ssq);
;             }
.LBB0_1784:
	s_or_b64 exec, exec, s[34:35]
	ds_read_b128 v[142:145], v120 offset:1040
	v_lshl_add_u64 v[118:119], v[118:119], 1, s[6:7]
	s_waitcnt vmcnt(0) lgkmcnt(0)
	v_pk_fma_f32 v[88:89], v[142:143], 0.5, v[88:89] op_sel_hi:[1,0,1]
	v_pk_fma_f32 v[90:91], v[144:145], 0.5, v[90:91] op_sel_hi:[1,0,1]
	global_store_dwordx4 v[116:117], v[88:91], off
	v_cvt_pk_bf16_f32 v116, v88, v89
	v_cvt_pk_bf16_f32 v117, v90, v91
	v_pk_mul_f32 v[88:89], v[88:89], v[88:89]
	v_pk_mul_f32 v[90:91], v[90:91], v[90:91]
	v_add_f32_e32 v88, v88, v89
	v_add_f32_e32 v88, v88, v90
	v_add_f32_e32 v88, v88, v91
	global_store_dwordx2 v[118:119], v[116:117], off
	s_nop 0
	v_add_f32_dpp v88, v88, v88 row_ror:8 row_mask:0xf bank_mask:0xf bound_ctrl:1
	s_nop 1
	v_add_f32_dpp v88, v88, v88 row_ror:4 row_mask:0xf bank_mask:0xf bound_ctrl:1
	s_nop 1
	v_add_f32_dpp v88, v88, v88 row_ror:2 row_mask:0xf bank_mask:0xf bound_ctrl:1
	s_nop 1
	v_add_f32_dpp v88, v88, v88 row_ror:1 row_mask:0xf bank_mask:0xf bound_ctrl:1
	s_nop 0
	v_readlane_b32 s11, v88, 0
	v_readlane_b32 s68, v88, 16
	v_readlane_b32 s62, v88, 32
	v_readlane_b32 s63, v88, 48
	s_and_saveexec_b64 s[34:35], vcc
	s_cbranch_execz .LBB0_1786
	s_lshl_b64 s[30:31], s[30:31], 2
	v_mov_b32_e32 v88, s68
	s_add_u32 s30, s2, s30
	v_add_f32_e32 v88, s11, v88
	s_addc_u32 s31, s3, s31
	v_add_f32_e32 v88, s62, v88
	v_add_f32_e32 v90, s63, v88
	v_mov_b64_e32 v[88:89], s[30:31]
	global_atomic_add_f32 v[88:89], v90, off
.LBB0_1786:
	s_or_b64 exec, exec, s[34:35]
	ds_read_b128 v[88:91], v120 offset:2080
	v_lshl_add_u64 v[114:115], v[114:115], 1, s[6:7]
	s_waitcnt lgkmcnt(0)
	v_pk_fma_f32 v[84:85], v[88:89], 0.5, v[84:85] op_sel_hi:[1,0,1]
	v_pk_fma_f32 v[86:87], v[90:91], 0.5, v[86:87] op_sel_hi:[1,0,1]
	global_store_dwordx4 v[112:113], v[84:87], off
	v_cvt_pk_bf16_f32 v88, v84, v85
	v_cvt_pk_bf16_f32 v89, v86, v87
	v_pk_mul_f32 v[84:85], v[84:85], v[84:85]
	v_pk_mul_f32 v[86:87], v[86:87], v[86:87]
	v_add_f32_e32 v84, v84, v85
	v_add_f32_e32 v84, v84, v86
	v_add_f32_e32 v84, v84, v87
	global_store_dwordx2 v[114:115], v[88:89], off
	s_nop 0
	v_add_f32_dpp v84, v84, v84 row_ror:8 row_mask:0xf bank_mask:0xf bound_ctrl:1
	s_nop 1
	v_add_f32_dpp v84, v84, v84 row_ror:4 row_mask:0xf bank_mask:0xf bound_ctrl:1
	s_nop 1
	v_add_f32_dpp v84, v84, v84 row_ror:2 row_mask:0xf bank_mask:0xf bound_ctrl:1
	s_nop 1
	v_add_f32_dpp v84, v84, v84 row_ror:1 row_mask:0xf bank_mask:0xf bound_ctrl:1
	s_nop 0
	v_readlane_b32 s11, v84, 0
	v_readlane_b32 s62, v84, 16
	v_readlane_b32 s34, v84, 32
	v_readlane_b32 s35, v84, 48
	s_and_saveexec_b64 s[30:31], vcc
	s_cbranch_execz .LBB0_1788
	s_lshl_b64 s[22:23], s[22:23], 2
	v_mov_b32_e32 v84, s62
	s_add_u32 s22, s2, s22
	v_add_f32_e32 v84, s11, v84
	s_addc_u32 s23, s3, s23
	v_add_f32_e32 v84, s34, v84
	v_add_f32_e32 v86, s35, v84
	v_mov_b64_e32 v[84:85], s[22:23]
	global_atomic_add_f32 v[84:85], v86, off
.LBB0_1788:
	s_or_b64 exec, exec, s[30:31]
	ds_read_b128 v[84:87], v120 offset:3120
	v_lshl_add_u64 v[88:89], v[110:111], 1, s[6:7]
	s_waitcnt lgkmcnt(0)
	v_pk_fma_f32 v[80:81], v[84:85], 0.5, v[80:81] op_sel_hi:[1,0,1]
	v_pk_fma_f32 v[82:83], v[86:87], 0.5, v[82:83] op_sel_hi:[1,0,1]
	global_store_dwordx4 v[108:109], v[80:83], off
	v_cvt_pk_bf16_f32 v84, v80, v81
	v_cvt_pk_bf16_f32 v85, v82, v83
	v_pk_mul_f32 v[80:81], v[80:81], v[80:81]
	v_pk_mul_f32 v[82:83], v[82:83], v[82:83]
	v_add_f32_e32 v80, v80, v81
	v_add_f32_e32 v80, v80, v82
	v_add_f32_e32 v80, v80, v83
	global_store_dwordx2 v[88:89], v[84:85], off
	s_nop 0
	v_add_f32_dpp v80, v80, v80 row_ror:8 row_mask:0xf bank_mask:0xf bound_ctrl:1
	s_nop 1
	v_add_f32_dpp v80, v80, v80 row_ror:4 row_mask:0xf bank_mask:0xf bound_ctrl:1
	s_nop 1
	v_add_f32_dpp v80, v80, v80 row_ror:2 row_mask:0xf bank_mask:0xf bound_ctrl:1
	s_nop 1
	v_add_f32_dpp v80, v80, v80 row_ror:1 row_mask:0xf bank_mask:0xf bound_ctrl:1
	s_nop 0
	v_readlane_b32 s11, v80, 0
	v_readlane_b32 s34, v80, 16
	v_readlane_b32 s30, v80, 32
	v_readlane_b32 s31, v80, 48
	s_and_saveexec_b64 s[22:23], vcc
	s_cbranch_execz .LBB0_1790
	s_lshl_b64 s[20:21], s[20:21], 2
	v_mov_b32_e32 v80, s34
	s_add_u32 s20, s2, s20
	v_add_f32_e32 v80, s11, v80
	s_addc_u32 s21, s3, s21
	v_add_f32_e32 v80, s30, v80
	v_add_f32_e32 v82, s31, v80
	v_mov_b64_e32 v[80:81], s[20:21]
	global_atomic_add_f32 v[80:81], v82, off
.LBB0_1790:
	s_or_b64 exec, exec, s[22:23]
	ds_read_b128 v[80:83], v120 offset:4160
	v_lshl_add_u64 v[84:85], v[106:107], 1, s[6:7]
	s_waitcnt lgkmcnt(0)
	v_pk_fma_f32 v[76:77], v[80:81], 0.5, v[76:77] op_sel_hi:[1,0,1]
	v_pk_fma_f32 v[78:79], v[82:83], 0.5, v[78:79] op_sel_hi:[1,0,1]
	global_store_dwordx4 v[104:105], v[76:79], off
	v_cvt_pk_bf16_f32 v80, v76, v77
	v_cvt_pk_bf16_f32 v81, v78, v79
	v_pk_mul_f32 v[76:77], v[76:77], v[76:77]
	v_pk_mul_f32 v[78:79], v[78:79], v[78:79]
	v_add_f32_e32 v76, v76, v77
	v_add_f32_e32 v76, v76, v78
	v_add_f32_e32 v76, v76, v79
	global_store_dwordx2 v[84:85], v[80:81], off
	s_nop 0
	v_add_f32_dpp v76, v76, v76 row_ror:8 row_mask:0xf bank_mask:0xf bound_ctrl:1
	s_nop 1
	v_add_f32_dpp v76, v76, v76 row_ror:4 row_mask:0xf bank_mask:0xf bound_ctrl:1
	s_nop 1
	v_add_f32_dpp v76, v76, v76 row_ror:2 row_mask:0xf bank_mask:0xf bound_ctrl:1
	s_nop 1
	v_add_f32_dpp v76, v76, v76 row_ror:1 row_mask:0xf bank_mask:0xf bound_ctrl:1
	s_nop 0
	v_readlane_b32 s11, v76, 0
	v_readlane_b32 s30, v76, 16
	v_readlane_b32 s22, v76, 32
	v_readlane_b32 s23, v76, 48
	s_and_saveexec_b64 s[20:21], vcc
	s_cbranch_execz .LBB0_1792
	s_lshl_b64 s[18:19], s[18:19], 2
	v_mov_b32_e32 v76, s30
	s_add_u32 s18, s2, s18
	v_add_f32_e32 v76, s11, v76
	s_addc_u32 s19, s3, s19
	v_add_f32_e32 v76, s22, v76
	v_add_f32_e32 v78, s23, v76
	v_mov_b64_e32 v[76:77], s[18:19]
	global_atomic_add_f32 v[76:77], v78, off
; DEVI float fsig(float x) { return __builtin_amdgcn_rcpf(1.f + __expf(-x)); }
; DEVI float bflo(unsigned u) { return __uint_as_float(u << 16); }
; DEVI float bfhi(unsigned u) { return __uint_as_float(u & 0xffff0000u); }
; template <int EPI, int TS, bool VT>
; DEVI void gemm_epilogue(const Params& p, char* smem, f32x4 (&acc)[2][2][4][2], int m0, int n0, float scale, const float* ssin,
;                         float* ssout, u16* xbout, int wid, int lane, int wr, int wc, int fr, int fq) {
;     ...
;           if constexpr (EPI == E_RESID || EPI == E_PLEGATE) {
;             const float4 a = *(const float4*)(Tr + 4 * lane);
;             const size_t ro = (size_t)grow * 1024 + n0 + 4 * lane;
;             float4 x4 = xo[u];
;             if constexpr (EPI == E_PLEGATE) {
;               x4.x += bflo(pv[u].x) * fsig(a.x * rs);
;               x4.y += bfhi(pv[u].x) * fsig(a.y * rs);
;               x4.z += bflo(pv[u].y) * fsig(a.z * rs);
;               x4.w += bfhi(pv[u].y) * fsig(a.w * rs);
;             } else {
;               const float sc = fabsf(scale);
;               x4.x += sc * a.x; x4.y += sc * a.y; x4.z += sc * a.z; x4.w += sc * a.w;
;             }
;             st_nt16(p.x + ro, x4);
;             if (xbout) {
;               uint2 o;
;               o.x = pack2(x4.x, x4.y);
;               o.y = pack2(x4.z, x4.w);
;               st_nt8(xbout + ro, o);
;             }
;             if (ssout) {
;               const float ssq = wsum(x4.x * x4.x + x4.y * x4.y + x4.z * x4.z + x4.w * x4.w, lane);
;               if (lane == 0) atomicAdd(ssout + grow, ssq);
;             }
.LBB0_1792:
	s_or_b64 exec, exec, s[20:21]
	ds_read_b128 v[76:79], v120 offset:5200
	v_lshl_add_u64 v[80:81], v[102:103], 1, s[6:7]
	s_waitcnt lgkmcnt(0)
	v_pk_fma_f32 v[72:73], v[76:77], 0.5, v[72:73] op_sel_hi:[1,0,1]
	v_pk_fma_f32 v[74:75], v[78:79], 0.5, v[74:75] op_sel_hi:[1,0,1]
	global_store_dwordx4 v[100:101], v[72:75], off
	v_cvt_pk_bf16_f32 v76, v72, v73
	v_cvt_pk_bf16_f32 v77, v74, v75
	v_pk_mul_f32 v[72:73], v[72:73], v[72:73]
	v_pk_mul_f32 v[74:75], v[74:75], v[74:75]
	v_add_f32_e32 v72, v72, v73
	v_add_f32_e32 v72, v72, v74
	v_add_f32_e32 v72, v72, v75
	global_store_dwordx2 v[80:81], v[76:77], off
	s_nop 0
	v_add_f32_dpp v72, v72, v72 row_ror:8 row_mask:0xf bank_mask:0xf bound_ctrl:1
	s_nop 1
	v_add_f32_dpp v72, v72, v72 row_ror:4 row_mask:0xf bank_mask:0xf bound_ctrl:1
	s_nop 1
	v_add_f32_dpp v72, v72, v72 row_ror:2 row_mask:0xf bank_mask:0xf bound_ctrl:1
	s_nop 1
	v_add_f32_dpp v72, v72, v72 row_ror:1 row_mask:0xf bank_mask:0xf bound_ctrl:1
	s_nop 0
	v_readlane_b32 s11, v72, 0
	v_readlane_b32 s22, v72, 16
	v_readlane_b32 s20, v72, 32
	v_readlane_b32 s21, v72, 48
	s_and_saveexec_b64 s[18:19], vcc
	s_cbranch_execz .LBB0_1794
	s_lshl_b64 s[16:17], s[16:17], 2
	v_mov_b32_e32 v72, s22
	s_add_u32 s16, s2, s16
	v_add_f32_e32 v72, s11, v72
	s_addc_u32 s17, s3, s17
	v_add_f32_e32 v72, s20, v72
	v_add_f32_e32 v74, s21, v72
	v_mov_b64_e32 v[72:73], s[16:17]
	global_atomic_add_f32 v[72:73], v74, off
.LBB0_1794:
	s_or_b64 exec, exec, s[18:19]
	ds_read_b128 v[72:75], v120 offset:6240
	v_lshl_add_u64 v[76:77], v[98:99], 1, s[6:7]
	s_waitcnt lgkmcnt(0)
	v_pk_fma_f32 v[68:69], v[72:73], 0.5, v[68:69] op_sel_hi:[1,0,1]
	v_pk_fma_f32 v[70:71], v[74:75], 0.5, v[70:71] op_sel_hi:[1,0,1]
	global_store_dwordx4 v[96:97], v[68:71], off
	v_cvt_pk_bf16_f32 v72, v68, v69
	v_cvt_pk_bf16_f32 v73, v70, v71
	v_pk_mul_f32 v[68:69], v[68:69], v[68:69]
	v_pk_mul_f32 v[70:71], v[70:71], v[70:71]
	v_add_f32_e32 v68, v68, v69
	v_add_f32_e32 v68, v68, v70
	v_add_f32_e32 v68, v68, v71
	global_store_dwordx2 v[76:77], v[72:73], off
	s_nop 0
	v_add_f32_dpp v68, v68, v68 row_ror:8 row_mask:0xf bank_mask:0xf bound_ctrl:1
	s_nop 1
	v_add_f32_dpp v68, v68, v68 row_ror:4 row_mask:0xf bank_mask:0xf bound_ctrl:1
	s_nop 1
	v_add_f32_dpp v68, v68, v68 row_ror:2 row_mask:0xf bank_mask:0xf bound_ctrl:1
	s_nop 1
	v_add_f32_dpp v68, v68, v68 row_ror:1 row_mask:0xf bank_mask:0xf bound_ctrl:1
	s_nop 0
	v_readlane_b32 s11, v68, 0
	v_readlane_b32 s20, v68, 16
	v_readlane_b32 s18, v68, 32
	v_readlane_b32 s19, v68, 48
	s_and_saveexec_b64 s[16:17], vcc
	s_cbranch_execz .LBB0_1796
	s_lshl_b64 s[14:15], s[14:15], 2
	v_mov_b32_e32 v68, s20
	s_add_u32 s14, s2, s14
	v_add_f32_e32 v68, s11, v68
	s_addc_u32 s15, s3, s15
	v_add_f32_e32 v68, s18, v68
	v_add_f32_e32 v70, s19, v68
	v_mov_b64_e32 v[68:69], s[14:15]
	global_atomic_add_f32 v[68:69], v70, off
.LBB0_1796:
	s_or_b64 exec, exec, s[16:17]
	ds_read_b128 v[68:71], v120 offset:7280
	v_lshl_add_u64 v[72:73], v[94:95], 1, s[6:7]
	s_waitcnt lgkmcnt(0)
	v_pk_fma_f32 v[64:65], v[68:69], 0.5, v[64:65] op_sel_hi:[1,0,1]
	v_pk_fma_f32 v[66:67], v[70:71], 0.5, v[66:67] op_sel_hi:[1,0,1]
	global_store_dwordx4 v[92:93], v[64:67], off
	v_cvt_pk_bf16_f32 v68, v64, v65
	v_cvt_pk_bf16_f32 v69, v66, v67
	v_pk_mul_f32 v[64:65], v[64:65], v[64:65]
	v_pk_mul_f32 v[66:67], v[66:67], v[66:67]
	v_add_f32_e32 v64, v64, v65
	v_add_f32_e32 v64, v64, v66
	v_add_f32_e32 v64, v64, v67
	global_store_dwordx2 v[72:73], v[68:69], off
	s_nop 0
	v_add_f32_dpp v64, v64, v64 row_ror:8 row_mask:0xf bank_mask:0xf bound_ctrl:1
	s_nop 1
	v_add_f32_dpp v64, v64, v64 row_ror:4 row_mask:0xf bank_mask:0xf bound_ctrl:1
	s_nop 1
	v_add_f32_dpp v64, v64, v64 row_ror:2 row_mask:0xf bank_mask:0xf bound_ctrl:1
	s_nop 1
	v_add_f32_dpp v64, v64, v64 row_ror:1 row_mask:0xf bank_mask:0xf bound_ctrl:1
	s_nop 0
	v_readlane_b32 s11, v64, 0
	v_readlane_b32 s18, v64, 16
	v_readlane_b32 s16, v64, 32
	v_readlane_b32 s17, v64, 48
	s_and_saveexec_b64 s[14:15], vcc
	s_cbranch_execz .LBB0_1798
	s_lshl_b64 s[12:13], s[12:13], 2
	v_mov_b32_e32 v64, s18
	s_add_u32 s12, s2, s12
	v_add_f32_e32 v64, s11, v64
	s_addc_u32 s13, s3, s13
	v_add_f32_e32 v64, s16, v64
	v_add_f32_e32 v66, s17, v64
	v_mov_b64_e32 v[64:65], s[12:13]
	global_atomic_add_f32 v[64:65], v66, off
; DEVI float fsig(float x) { return __builtin_amdgcn_rcpf(1.f + __expf(-x)); }
; template <int EPI, int TS, bool VT>
; DEVI void gemm_epilogue(const Params& p, char* smem, f32x4 (&acc)[2][2][4][2], int m0, int n0, float scale, const float* ssin,
;                         float* ssout, u16* xbout, int wid, int lane, int wr, int wc, int fr, int fq) {
;     ...
;         if constexpr (EPI == E_RESID || EPI == E_PLEGATE) {
; #pragma unroll
;           for (int u = 0; u < 8; ++u) {
;             const size_t ro = (size_t)(g0 + i0 + u) * 1024 + n0 + 4 * lane;
;             const int gr = g0 + i0 + u;
;             const float* xs = p.x + ro;
;             if (scale < 0.f)
;               xs = (gr < MP ? p.x_prompt + ro : p.x_sample + (ro - (size_t)MP * 1024));
;             { const f32x4 t_ = __builtin_nontemporal_load((const f32x4*)xs); xo[u] = make_float4(t_[0], t_[1], t_[2], t_[3]); }
;             if constexpr (EPI == E_PLEGATE) {
;               const unsigned long long t2_ = __builtin_nontemporal_load((const unsigned long long*)((const u16*)(wsb + OFF_PP) + ro));
;               pv[u] = make_uint2((unsigned)t2_, (unsigned)(t2_ >> 32));
;             }
;           }
;         }
; #pragma unroll
;         for (int u = 0; u < 8; ++u) {
;           const int i = i0 + u;
;           const int grow = g0 + i;
;           const float* Tr = T + (r0 + i) * TS;
;           const float rs = __int_as_float(__builtin_amdgcn_readlane(__float_as_int(rsv), i));
;           if constexpr (EPI == E_RESID || EPI == E_PLEGATE) {
;             const float4 a = *(const float4*)(Tr + 4 * lane);
;             const size_t ro = (size_t)grow * 1024 + n0 + 4 * lane;
;             float4 x4 = xo[u];
;             if constexpr (EPI == E_PLEGATE) {
;               x4.x += bflo(pv[u].x) * fsig(a.x * rs);
;               x4.y += bfhi(pv[u].x) * fsig(a.y * rs);
;               x4.z += bflo(pv[u].y) * fsig(a.z * rs);
;               x4.w += bfhi(pv[u].y) * fsig(a.w * rs);
;             } else {
;               const float sc = fabsf(scale);
;               x4.x += sc * a.x; x4.y += sc * a.y; x4.z += sc * a.z; x4.w += sc * a.w;
;             }
;             st_nt16(p.x + ro, x4);
;             if (xbout) {
;               uint2 o;
;               o.x = pack2(x4.x, x4.y);
;               o.y = pack2(x4.z, x4.w);
;               st_nt8(xbout + ro, o);
;             }
;             if (ssout) {
.LBB0_1798:
	s_or_b64 exec, exec, s[14:15]
	s_or_b32 s34, s10, 8
	s_ashr_i32 s35, s34, 31
	s_lshl_b64 s[12:13], s[34:35], 10
	s_or_b32 s30, s10, 9
	v_lshl_add_u64 v[146:147], s[12:13], 0, v[128:129]
	s_ashr_i32 s31, s30, 31
	s_or_b32 s22, s10, 10
	v_lshl_add_u64 v[156:157], v[146:147], 2, s[38:39]
	s_lshl_b64 s[12:13], s[30:31], 10
	s_ashr_i32 s23, s22, 31
	s_or_b32 s20, s10, 11
	global_load_dwordx4 v[142:145], v[156:157], off
	v_lshl_add_u64 v[118:119], s[12:13], 0, v[128:129]
	s_lshl_b64 s[12:13], s[22:23], 10
	s_ashr_i32 s21, s20, 31
	s_or_b32 s18, s10, 12
	v_lshl_add_u64 v[114:115], s[12:13], 0, v[128:129]
	s_lshl_b64 s[12:13], s[20:21], 10
	s_ashr_i32 s19, s18, 31
	s_or_b32 s16, s10, 13
	v_lshl_add_u64 v[110:111], s[12:13], 0, v[128:129]
	s_lshl_b64 s[12:13], s[18:19], 10
	s_ashr_i32 s17, s16, 31
	s_or_b32 s14, s10, 14
	v_lshl_add_u64 v[106:107], s[12:13], 0, v[128:129]
	s_lshl_b64 s[12:13], s[16:17], 10
	s_ashr_i32 s15, s14, 31
	v_lshl_add_u64 v[102:103], s[12:13], 0, v[128:129]
	s_lshl_b64 s[12:13], s[14:15], 10
	v_lshl_add_u64 v[98:99], s[12:13], 0, v[128:129]
	s_or_b32 s12, s10, 15
	s_ashr_i32 s13, s12, 31
	s_lshl_b64 s[62:63], s[12:13], 10
	v_lshl_add_u64 v[94:95], s[62:63], 0, v[128:129]
	v_lshl_add_u64 v[116:117], v[118:119], 2, s[38:39]
	v_lshl_add_u64 v[108:109], v[110:111], 2, s[38:39]
	v_lshl_add_u64 v[100:101], v[102:103], 2, s[38:39]
	v_lshl_add_u64 v[92:93], v[94:95], 2, s[38:39]
	v_lshl_add_u64 v[112:113], v[114:115], 2, s[38:39]
	global_load_dwordx4 v[88:91], v[116:117], off
	global_load_dwordx4 v[84:87], v[112:113], off
	v_lshl_add_u64 v[104:105], v[106:107], 2, s[38:39]
	global_load_dwordx4 v[80:83], v[108:109], off
	global_load_dwordx4 v[76:79], v[104:105], off
	v_lshl_add_u64 v[96:97], v[98:99], 2, s[38:39]
	global_load_dwordx4 v[72:75], v[100:101], off
	global_load_dwordx4 v[68:71], v[96:97], off
	global_load_dwordx4 v[64:67], v[92:93], off
	ds_read_b128 v[152:155], v120 offset:8320
	v_lshl_add_u64 v[146:147], v[146:147], 1, s[6:7]
	s_waitcnt vmcnt(0) lgkmcnt(0)
	v_pk_fma_f32 v[142:143], v[152:153], 0.5, v[142:143] op_sel_hi:[1,0,1]
	v_pk_fma_f32 v[144:145], v[154:155], 0.5, v[144:145] op_sel_hi:[1,0,1]
	global_store_dwordx4 v[156:157], v[142:145], off
	v_cvt_pk_bf16_f32 v152, v142, v143
	v_cvt_pk_bf16_f32 v153, v144, v145
	v_pk_mul_f32 v[142:143], v[142:143], v[142:143]
	v_pk_mul_f32 v[144:145], v[144:145], v[144:145]
	v_add_f32_e32 v141, v142, v143
	v_add_f32_e32 v141, v141, v144
	v_add_f32_e32 v141, v141, v145
	global_store_dwordx2 v[146:147], v[152:153], off
	s_nop 0
	v_add_f32_dpp v141, v141, v141 row_ror:8 row_mask:0xf bank_mask:0xf bound_ctrl:1
	s_nop 1
	v_add_f32_dpp v141, v141, v141 row_ror:4 row_mask:0xf bank_mask:0xf bound_ctrl:1
	s_nop 1
	v_add_f32_dpp v141, v141, v141 row_ror:2 row_mask:0xf bank_mask:0xf bound_ctrl:1
	s_nop 1
	v_add_f32_dpp v141, v141, v141 row_ror:1 row_mask:0xf bank_mask:0xf bound_ctrl:1
	s_nop 0
	v_readlane_b32 s11, v141, 0
	v_readlane_b32 s70, v141, 16
	v_readlane_b32 s68, v141, 32
	v_readlane_b32 s69, v141, 48
	s_and_saveexec_b64 s[62:63], vcc
	s_cbranch_execz .LBB0_1800
	s_lshl_b64 s[34:35], s[34:35], 2
	v_mov_b32_e32 v141, s70
	s_add_u32 s34, s2, s34
	v_add_f32_e32 v141, s11, v141
	s_addc_u32 s35, s3, s35
	v_add_f32_e32 v141, s68, v141
	v_add_f32_e32 v141, s69, v141
	v_mov_b64_e32 v[142:143], s[34:35]
	global_atomic_add_f32 v[142:143], v141, off
.LBB0_1800:
	s_or_b64 exec, exec, s[62:63]
	ds_read_b128 v[142:145], v120 offset:9360
	v_lshl_add_u64 v[118:119], v[118:119], 1, s[6:7]
	s_waitcnt lgkmcnt(0)
	v_pk_fma_f32 v[88:89], v[142:143], 0.5, v[88:89] op_sel_hi:[1,0,1]
	v_pk_fma_f32 v[90:91], v[144:145], 0.5, v[90:91] op_sel_hi:[1,0,1]
	global_store_dwordx4 v[116:117], v[88:91], off
	v_cvt_pk_bf16_f32 v116, v88, v89
	v_cvt_pk_bf16_f32 v117, v90, v91
	v_pk_mul_f32 v[88:89], v[88:89], v[88:89]
	v_pk_mul_f32 v[90:91], v[90:91], v[90:91]
	v_add_f32_e32 v88, v88, v89
	v_add_f32_e32 v88, v88, v90
	v_add_f32_e32 v88, v88, v91
	global_store_dwordx2 v[118:119], v[116:117], off
	s_nop 0
	v_add_f32_dpp v88, v88, v88 row_ror:8 row_mask:0xf bank_mask:0xf bound_ctrl:1
	s_nop 1
	v_add_f32_dpp v88, v88, v88 row_ror:4 row_mask:0xf bank_mask:0xf bound_ctrl:1
	s_nop 1
	v_add_f32_dpp v88, v88, v88 row_ror:2 row_mask:0xf bank_mask:0xf bound_ctrl:1
	s_nop 1
	v_add_f32_dpp v88, v88, v88 row_ror:1 row_mask:0xf bank_mask:0xf bound_ctrl:1
	s_nop 0
	v_readlane_b32 s11, v88, 0
	v_readlane_b32 s68, v88, 16
	v_readlane_b32 s62, v88, 32
	v_readlane_b32 s63, v88, 48
	s_and_saveexec_b64 s[34:35], vcc
	s_cbranch_execz .LBB0_1802
	s_lshl_b64 s[30:31], s[30:31], 2
	v_mov_b32_e32 v88, s68
	s_add_u32 s30, s2, s30
	v_add_f32_e32 v88, s11, v88
	s_addc_u32 s31, s3, s31
	v_add_f32_e32 v88, s62, v88
	v_add_f32_e32 v90, s63, v88
	v_mov_b64_e32 v[88:89], s[30:31]
	global_atomic_add_f32 v[88:89], v90, off
.LBB0_1802:
	s_or_b64 exec, exec, s[34:35]
	ds_read_b128 v[88:91], v120 offset:10400
	v_lshl_add_u64 v[114:115], v[114:115], 1, s[6:7]
	s_waitcnt lgkmcnt(0)
	v_pk_fma_f32 v[84:85], v[88:89], 0.5, v[84:85] op_sel_hi:[1,0,1]
	v_pk_fma_f32 v[86:87], v[90:91], 0.5, v[86:87] op_sel_hi:[1,0,1]
	global_store_dwordx4 v[112:113], v[84:87], off
	v_cvt_pk_bf16_f32 v88, v84, v85
	v_cvt_pk_bf16_f32 v89, v86, v87
	v_pk_mul_f32 v[84:85], v[84:85], v[84:85]
	v_pk_mul_f32 v[86:87], v[86:87], v[86:87]
	v_add_f32_e32 v84, v84, v85
	v_add_f32_e32 v84, v84, v86
	v_add_f32_e32 v84, v84, v87
	global_store_dwordx2 v[114:115], v[88:89], off
	s_nop 0
	v_add_f32_dpp v84, v84, v84 row_ror:8 row_mask:0xf bank_mask:0xf bound_ctrl:1
	s_nop 1
	v_add_f32_dpp v84, v84, v84 row_ror:4 row_mask:0xf bank_mask:0xf bound_ctrl:1
	s_nop 1
	v_add_f32_dpp v84, v84, v84 row_ror:2 row_mask:0xf bank_mask:0xf bound_ctrl:1
	s_nop 1
	v_add_f32_dpp v84, v84, v84 row_ror:1 row_mask:0xf bank_mask:0xf bound_ctrl:1
	s_nop 0
	v_readlane_b32 s11, v84, 0
	v_readlane_b32 s62, v84, 16
	v_readlane_b32 s34, v84, 32
	v_readlane_b32 s35, v84, 48
	s_and_saveexec_b64 s[30:31], vcc
	s_cbranch_execz .LBB0_1804
	s_lshl_b64 s[22:23], s[22:23], 2
	v_mov_b32_e32 v84, s62
	s_add_u32 s22, s2, s22
	v_add_f32_e32 v84, s11, v84
	s_addc_u32 s23, s3, s23
	v_add_f32_e32 v84, s34, v84
	v_add_f32_e32 v86, s35, v84
	v_mov_b64_e32 v[84:85], s[22:23]
	global_atomic_add_f32 v[84:85], v86, off
; DEVI float fsig(float x) { return __builtin_amdgcn_rcpf(1.f + __expf(-x)); }
; DEVI float bflo(unsigned u) { return __uint_as_float(u << 16); }
; DEVI float bfhi(unsigned u) { return __uint_as_float(u & 0xffff0000u); }
; template <int EPI, int TS, bool VT>
; DEVI void gemm_epilogue(const Params& p, char* smem, f32x4 (&acc)[2][2][4][2], int m0, int n0, float scale, const float* ssin,
;                         float* ssout, u16* xbout, int wid, int lane, int wr, int wc, int fr, int fq) {
;     ...
;           if constexpr (EPI == E_RESID || EPI == E_PLEGATE) {
;             const float4 a = *(const float4*)(Tr + 4 * lane);
;             const size_t ro = (size_t)grow * 1024 + n0 + 4 * lane;
;             float4 x4 = xo[u];
;             if constexpr (EPI == E_PLEGATE) {
;               x4.x += bflo(pv[u].x) * fsig(a.x * rs);
;               x4.y += bfhi(pv[u].x) * fsig(a.y * rs);
;               x4.z += bflo(pv[u].y) * fsig(a.z * rs);
;               x4.w += bfhi(pv[u].y) * fsig(a.w * rs);
;             } else {
;               const float sc = fabsf(scale);
;               x4.x += sc * a.x; x4.y += sc * a.y; x4.z += sc * a.z; x4.w += sc * a.w;
;             }
;             st_nt16(p.x + ro, x4);
;             if (xbout) {
;               uint2 o;
;               o.x = pack2(x4.x, x4.y);
;               o.y = pack2(x4.z, x4.w);
;               st_nt8(xbout + ro, o);
;             }
;             if (ssout) {
;               const float ssq = wsum(x4.x * x4.x + x4.y * x4.y + x4.z * x4.z + x4.w * x4.w, lane);
;               if (lane == 0) atomicAdd(ssout + grow, ssq);
;             }
.LBB0_1804:
	s_or_b64 exec, exec, s[30:31]
	ds_read_b128 v[84:87], v120 offset:11440
	v_lshl_add_u64 v[88:89], v[110:111], 1, s[6:7]
	s_waitcnt lgkmcnt(0)
	v_pk_fma_f32 v[80:81], v[84:85], 0.5, v[80:81] op_sel_hi:[1,0,1]
	v_pk_fma_f32 v[82:83], v[86:87], 0.5, v[82:83] op_sel_hi:[1,0,1]
	global_store_dwordx4 v[108:109], v[80:83], off
	v_cvt_pk_bf16_f32 v84, v80, v81
	v_cvt_pk_bf16_f32 v85, v82, v83
	v_pk_mul_f32 v[80:81], v[80:81], v[80:81]
	v_pk_mul_f32 v[82:83], v[82:83], v[82:83]
	v_add_f32_e32 v80, v80, v81
	v_add_f32_e32 v80, v80, v82
	v_add_f32_e32 v80, v80, v83
	global_store_dwordx2 v[88:89], v[84:85], off
	s_nop 0
	v_add_f32_dpp v80, v80, v80 row_ror:8 row_mask:0xf bank_mask:0xf bound_ctrl:1
	s_nop 1
	v_add_f32_dpp v80, v80, v80 row_ror:4 row_mask:0xf bank_mask:0xf bound_ctrl:1
	s_nop 1
	v_add_f32_dpp v80, v80, v80 row_ror:2 row_mask:0xf bank_mask:0xf bound_ctrl:1
	s_nop 1
	v_add_f32_dpp v80, v80, v80 row_ror:1 row_mask:0xf bank_mask:0xf bound_ctrl:1
	s_nop 0
	v_readlane_b32 s11, v80, 0
	v_readlane_b32 s34, v80, 16
	v_readlane_b32 s30, v80, 32
	v_readlane_b32 s31, v80, 48
	s_and_saveexec_b64 s[22:23], vcc
	s_cbranch_execz .LBB0_1806
	s_lshl_b64 s[20:21], s[20:21], 2
	v_mov_b32_e32 v80, s34
	s_add_u32 s20, s2, s20
	v_add_f32_e32 v80, s11, v80
	s_addc_u32 s21, s3, s21
	v_add_f32_e32 v80, s30, v80
	v_add_f32_e32 v82, s31, v80
	v_mov_b64_e32 v[80:81], s[20:21]
	global_atomic_add_f32 v[80:81], v82, off
.LBB0_1806:
	s_or_b64 exec, exec, s[22:23]
	ds_read_b128 v[80:83], v120 offset:12480
	v_lshl_add_u64 v[84:85], v[106:107], 1, s[6:7]
	s_waitcnt lgkmcnt(0)
	v_pk_fma_f32 v[76:77], v[80:81], 0.5, v[76:77] op_sel_hi:[1,0,1]
	v_pk_fma_f32 v[78:79], v[82:83], 0.5, v[78:79] op_sel_hi:[1,0,1]
	global_store_dwordx4 v[104:105], v[76:79], off
	v_cvt_pk_bf16_f32 v80, v76, v77
	v_cvt_pk_bf16_f32 v81, v78, v79
	v_pk_mul_f32 v[76:77], v[76:77], v[76:77]
	v_pk_mul_f32 v[78:79], v[78:79], v[78:79]
	v_add_f32_e32 v76, v76, v77
	v_add_f32_e32 v76, v76, v78
	v_add_f32_e32 v76, v76, v79
	global_store_dwordx2 v[84:85], v[80:81], off
	s_nop 0
	v_add_f32_dpp v76, v76, v76 row_ror:8 row_mask:0xf bank_mask:0xf bound_ctrl:1
	s_nop 1
	v_add_f32_dpp v76, v76, v76 row_ror:4 row_mask:0xf bank_mask:0xf bound_ctrl:1
	s_nop 1
	v_add_f32_dpp v76, v76, v76 row_ror:2 row_mask:0xf bank_mask:0xf bound_ctrl:1
	s_nop 1
	v_add_f32_dpp v76, v76, v76 row_ror:1 row_mask:0xf bank_mask:0xf bound_ctrl:1
	s_nop 0
	v_readlane_b32 s11, v76, 0
	v_readlane_b32 s30, v76, 16
	v_readlane_b32 s22, v76, 32
	v_readlane_b32 s23, v76, 48
	s_and_saveexec_b64 s[20:21], vcc
	s_cbranch_execz .LBB0_1808
	s_lshl_b64 s[18:19], s[18:19], 2
	v_mov_b32_e32 v76, s30
	s_add_u32 s18, s2, s18
	v_add_f32_e32 v76, s11, v76
	s_addc_u32 s19, s3, s19
	v_add_f32_e32 v76, s22, v76
	v_add_f32_e32 v78, s23, v76
	v_mov_b64_e32 v[76:77], s[18:19]
	global_atomic_add_f32 v[76:77], v78, off
.LBB0_1808:
	s_or_b64 exec, exec, s[20:21]
	ds_read_b128 v[76:79], v120 offset:13520
	v_lshl_add_u64 v[80:81], v[102:103], 1, s[6:7]
	s_waitcnt lgkmcnt(0)
	v_pk_fma_f32 v[72:73], v[76:77], 0.5, v[72:73] op_sel_hi:[1,0,1]
	v_pk_fma_f32 v[74:75], v[78:79], 0.5, v[74:75] op_sel_hi:[1,0,1]
	global_store_dwordx4 v[100:101], v[72:75], off
	v_cvt_pk_bf16_f32 v76, v72, v73
	v_cvt_pk_bf16_f32 v77, v74, v75
	v_pk_mul_f32 v[72:73], v[72:73], v[72:73]
	v_pk_mul_f32 v[74:75], v[74:75], v[74:75]
	v_add_f32_e32 v72, v72, v73
	v_add_f32_e32 v72, v72, v74
	v_add_f32_e32 v72, v72, v75
	global_store_dwordx2 v[80:81], v[76:77], off
	s_nop 0
	v_add_f32_dpp v72, v72, v72 row_ror:8 row_mask:0xf bank_mask:0xf bound_ctrl:1
	s_nop 1
	v_add_f32_dpp v72, v72, v72 row_ror:4 row_mask:0xf bank_mask:0xf bound_ctrl:1
	s_nop 1
	v_add_f32_dpp v72, v72, v72 row_ror:2 row_mask:0xf bank_mask:0xf bound_ctrl:1
	s_nop 1
	v_add_f32_dpp v72, v72, v72 row_ror:1 row_mask:0xf bank_mask:0xf bound_ctrl:1
	s_nop 0
	v_readlane_b32 s11, v72, 0
	v_readlane_b32 s22, v72, 16
	v_readlane_b32 s20, v72, 32
	v_readlane_b32 s21, v72, 48
	s_and_saveexec_b64 s[18:19], vcc
	s_cbranch_execz .LBB0_1810
	s_lshl_b64 s[16:17], s[16:17], 2
	v_mov_b32_e32 v72, s22
	s_add_u32 s16, s2, s16
	v_add_f32_e32 v72, s11, v72
	s_addc_u32 s17, s3, s17
	v_add_f32_e32 v72, s20, v72
	v_add_f32_e32 v74, s21, v72
	v_mov_b64_e32 v[72:73], s[16:17]
	global_atomic_add_f32 v[72:73], v74, off
.LBB0_1810:
	s_or_b64 exec, exec, s[18:19]
	ds_read_b128 v[72:75], v120 offset:14560
	v_lshl_add_u64 v[76:77], v[98:99], 1, s[6:7]
	s_waitcnt lgkmcnt(0)
	v_pk_fma_f32 v[68:69], v[72:73], 0.5, v[68:69] op_sel_hi:[1,0,1]
	v_pk_fma_f32 v[70:71], v[74:75], 0.5, v[70:71] op_sel_hi:[1,0,1]
	global_store_dwordx4 v[96:97], v[68:71], off
	v_cvt_pk_bf16_f32 v72, v68, v69
	v_cvt_pk_bf16_f32 v73, v70, v71
	v_pk_mul_f32 v[68:69], v[68:69], v[68:69]
	v_pk_mul_f32 v[70:71], v[70:71], v[70:71]
	v_add_f32_e32 v68, v68, v69
	v_add_f32_e32 v68, v68, v70
	v_add_f32_e32 v68, v68, v71
	global_store_dwordx2 v[76:77], v[72:73], off
	s_nop 0
	v_add_f32_dpp v68, v68, v68 row_ror:8 row_mask:0xf bank_mask:0xf bound_ctrl:1
	s_nop 1
	v_add_f32_dpp v68, v68, v68 row_ror:4 row_mask:0xf bank_mask:0xf bound_ctrl:1
	s_nop 1
	v_add_f32_dpp v68, v68, v68 row_ror:2 row_mask:0xf bank_mask:0xf bound_ctrl:1
	s_nop 1
	v_add_f32_dpp v68, v68, v68 row_ror:1 row_mask:0xf bank_mask:0xf bound_ctrl:1
	s_nop 0
	v_readlane_b32 s11, v68, 0
	v_readlane_b32 s20, v68, 16
	v_readlane_b32 s18, v68, 32
	v_readlane_b32 s19, v68, 48
	s_and_saveexec_b64 s[16:17], vcc
	s_cbranch_execz .LBB0_1812
	s_lshl_b64 s[14:15], s[14:15], 2
	v_mov_b32_e32 v68, s20
	s_add_u32 s14, s2, s14
	v_add_f32_e32 v68, s11, v68
	s_addc_u32 s15, s3, s15
	v_add_f32_e32 v68, s18, v68
	v_add_f32_e32 v70, s19, v68
	v_mov_b64_e32 v[68:69], s[14:15]
	global_atomic_add_f32 v[68:69], v70, off
; template <int EPI, int TS, bool VT>
; DEVI void gemm_epilogue(const Params& p, char* smem, f32x4 (&acc)[2][2][4][2], int m0, int n0, float scale, const float* ssin,
;                         float* ssout, u16* xbout, int wid, int lane, int wr, int wc, int fr, int fq) {
;     ...
;       float* tw = T + (wr * 64 + fq * 4) * TS + wc * 32 + fr;
; #pragma unroll
;       for (int m = 0; m < 4; ++m)
; #pragma unroll
;         for (int j = 0; j < 4; ++j)
; #pragma unroll
;           for (int v = 0; v < 4; ++v) tw[(m * 16 + j) * TS + (v >> 1) * 128 + (v & 1) * 16] = acc[ai][v >> 1][m][v & 1][j];
;     }
;     __syncthreads();
;     ...
;         if constexpr (EPI == E_RESID || EPI == E_PLEGATE) {
; #pragma unroll
;           for (int u = 0; u < 8; ++u) {
;             const size_t ro = (size_t)(g0 + i0 + u) * 1024 + n0 + 4 * lane;
;             const int gr = g0 + i0 + u;
;             const float* xs = p.x + ro;
;             if (scale < 0.f)
;               xs = (gr < MP ? p.x_prompt + ro : p.x_sample + (ro - (size_t)MP * 1024));
;             { const f32x4 t_ = __builtin_nontemporal_load((const f32x4*)xs); xo[u] = make_float4(t_[0], t_[1], t_[2], t_[3]); }
;             if constexpr (EPI == E_PLEGATE) {
;               const unsigned long long t2_ = __builtin_nontemporal_load((const unsigned long long*)((const u16*)(wsb + OFF_PP) + ro));
;               pv[u] = make_uint2((unsigned)t2_, (unsigned)(t2_ >> 32));
;             }
;           }
;         }
; #pragma unroll
;         for (int u = 0; u < 8; ++u) {
;           const int i = i0 + u;
;           const int grow = g0 + i;
;           const float* Tr = T + (r0 + i) * TS;
;           const float rs = __int_as_float(__builtin_amdgcn_readlane(__float_as_int(rsv), i));
;           if constexpr (EPI == E_RESID || EPI == E_PLEGATE) {
;             const float4 a = *(const float4*)(Tr + 4 * lane);
;             const size_t ro = (size_t)grow * 1024 + n0 + 4 * lane;
;             float4 x4 = xo[u];
;             if constexpr (EPI == E_PLEGATE) {
;               x4.x += bflo(pv[u].x) * fsig(a.x * rs);
;               x4.y += bfhi(pv[u].x) * fsig(a.y * rs);
;               x4.z += bflo(pv[u].y) * fsig(a.z * rs);
;               x4.w += bfhi(pv[u].y) * fsig(a.w * rs);
;             } else {
;               const float sc = fabsf(scale);
;               x4.x += sc * a.x; x4.y += sc * a.y; x4.z += sc * a.z; x4.w += sc * a.w;
.LBB0_1812:
	s_or_b64 exec, exec, s[16:17]
	ds_read_b128 v[68:71], v120 offset:15600
	v_lshl_add_u64 v[72:73], v[94:95], 1, s[6:7]
	s_waitcnt lgkmcnt(0)
	v_pk_fma_f32 v[64:65], v[68:69], 0.5, v[64:65] op_sel_hi:[1,0,1]
	v_pk_fma_f32 v[66:67], v[70:71], 0.5, v[66:67] op_sel_hi:[1,0,1]
	global_store_dwordx4 v[92:93], v[64:67], off
	v_cvt_pk_bf16_f32 v68, v64, v65
	v_cvt_pk_bf16_f32 v69, v66, v67
	v_pk_mul_f32 v[64:65], v[64:65], v[64:65]
	v_pk_mul_f32 v[66:67], v[66:67], v[66:67]
	v_add_f32_e32 v64, v64, v65
	v_add_f32_e32 v64, v64, v66
	v_add_f32_e32 v64, v64, v67
	global_store_dwordx2 v[72:73], v[68:69], off
	s_nop 0
	v_add_f32_dpp v64, v64, v64 row_ror:8 row_mask:0xf bank_mask:0xf bound_ctrl:1
	s_nop 1
	v_add_f32_dpp v64, v64, v64 row_ror:4 row_mask:0xf bank_mask:0xf bound_ctrl:1
	s_nop 1
	v_add_f32_dpp v64, v64, v64 row_ror:2 row_mask:0xf bank_mask:0xf bound_ctrl:1
	s_nop 1
	v_add_f32_dpp v64, v64, v64 row_ror:1 row_mask:0xf bank_mask:0xf bound_ctrl:1
	s_nop 0
	v_readlane_b32 s11, v64, 0
	v_readlane_b32 s18, v64, 16
	v_readlane_b32 s16, v64, 32
	v_readlane_b32 s17, v64, 48
	s_and_saveexec_b64 s[14:15], vcc
	s_cbranch_execz .LBB0_1814
	s_lshl_b64 s[12:13], s[12:13], 2
	v_mov_b32_e32 v64, s18
	s_add_u32 s12, s2, s12
	v_add_f32_e32 v64, s11, v64
	s_addc_u32 s13, s3, s13
	v_add_f32_e32 v64, s16, v64
	v_add_f32_e32 v66, s17, v64
	v_mov_b64_e32 v[64:65], s[12:13]
	global_atomic_add_f32 v[64:65], v66, off
.LBB0_1814:
	s_or_b64 exec, exec, s[14:15]
	s_add_i32 s34, s10, 0x80
	s_ashr_i32 s35, s34, 31
	s_lshl_b64 s[12:13], s[34:35], 10
	s_add_i32 s30, s10, 0x81
	v_lshl_add_u64 v[64:65], s[12:13], 0, v[128:129]
	s_ashr_i32 s31, s30, 31
	s_add_i32 s22, s10, 0x82
	v_lshl_add_u64 v[66:67], v[64:65], 2, s[38:39]
	s_lshl_b64 s[12:13], s[30:31], 10
	s_ashr_i32 s23, s22, 31
	s_add_i32 s20, s10, 0x83
	s_waitcnt lgkmcnt(0)
	s_barrier
	ds_write2_b32 v130, v24, v28 offset1:16
	ds_write2_b32 v130, v56, v60 offset0:128 offset1:144
	ds_write2_b32 v124, v25, v29 offset0:4 offset1:20
	ds_write2_b32 v124, v57, v61 offset0:132 offset1:148
	ds_write2_b32 v121, v26, v30 offset0:8 offset1:24
	ds_write2_b32 v121, v58, v62 offset0:136 offset1:152
	ds_write2_b32 v122, v27, v31 offset0:12 offset1:28
	ds_write2_b32 v122, v59, v63 offset0:140 offset1:156
	ds_write2_b32 v123, v16, v20 offset0:64 offset1:80
	ds_write2_b32 v123, v48, v52 offset0:192 offset1:208
	ds_write2_b32 v125, v17, v21 offset0:68 offset1:84
	ds_write2_b32 v125, v49, v53 offset0:196 offset1:212
	ds_write2_b32 v126, v18, v22 offset0:72 offset1:88
	ds_write2_b32 v126, v50, v54 offset0:200 offset1:216
	ds_write2_b32 v127, v19, v23 offset0:76 offset1:92
	ds_write2_b32 v127, v51, v55 offset0:204 offset1:220
	ds_write2_b32 v131, v8, v12 offset0:128 offset1:144
	ds_write2_b32 v132, v40, v44 offset1:16
	ds_write2_b32 v132, v9, v13 offset0:132 offset1:148
	ds_write2_b32 v133, v41, v45 offset0:4 offset1:20
	ds_write2_b32 v133, v10, v14 offset0:136 offset1:152
	ds_write2_b32 v134, v42, v46 offset0:8 offset1:24
	ds_write2_b32 v134, v11, v15 offset0:140 offset1:156
	ds_write2_b32 v135, v43, v47 offset0:12 offset1:28
	ds_write2_b32 v136, v0, v4 offset0:192 offset1:208
	ds_write2_b32 v137, v32, v36 offset0:64 offset1:80
	ds_write2_b32 v137, v1, v5 offset0:196 offset1:212
	ds_write2_b32 v138, v33, v37 offset0:68 offset1:84
	ds_write2_b32 v138, v2, v6 offset0:200 offset1:216
	ds_write2_b32 v139, v34, v38 offset0:72 offset1:88
	ds_write2_b32 v139, v3, v7 offset0:204 offset1:220
	ds_write2_b32 v140, v35, v39 offset0:76 offset1:92
	s_waitcnt lgkmcnt(0)
	s_barrier
	global_load_dwordx4 v[56:59], v[66:67], off
	v_lshl_add_u64 v[54:55], s[12:13], 0, v[128:129]
	s_lshl_b64 s[12:13], s[22:23], 10
	s_ashr_i32 s21, s20, 31
	s_add_i32 s18, s10, 0x84
	v_lshl_add_u64 v[50:51], s[12:13], 0, v[128:129]
	s_lshl_b64 s[12:13], s[20:21], 10
	s_ashr_i32 s19, s18, 31
	s_add_i32 s16, s10, 0x85
	v_lshl_add_u64 v[46:47], s[12:13], 0, v[128:129]
	s_lshl_b64 s[12:13], s[18:19], 10
	s_ashr_i32 s17, s16, 31
	s_add_i32 s14, s10, 0x86
	v_lshl_add_u64 v[42:43], s[12:13], 0, v[128:129]
	s_lshl_b64 s[12:13], s[16:17], 10
	s_ashr_i32 s15, s14, 31
	v_lshl_add_u64 v[38:39], s[12:13], 0, v[128:129]
	s_lshl_b64 s[12:13], s[14:15], 10
	v_lshl_add_u64 v[34:35], s[12:13], 0, v[128:129]
	s_add_i32 s12, s10, 0x87
	s_ashr_i32 s13, s12, 31
	s_lshl_b64 s[62:63], s[12:13], 10
	v_lshl_add_u64 v[30:31], s[62:63], 0, v[128:129]
	v_lshl_add_u64 v[52:53], v[54:55], 2, s[38:39]
	v_lshl_add_u64 v[44:45], v[46:47], 2, s[38:39]
	v_lshl_add_u64 v[36:37], v[38:39], 2, s[38:39]
	v_lshl_add_u64 v[28:29], v[30:31], 2, s[38:39]
	v_lshl_add_u64 v[48:49], v[50:51], 2, s[38:39]
	global_load_dwordx4 v[24:27], v[52:53], off
	global_load_dwordx4 v[20:23], v[48:49], off
	v_lshl_add_u64 v[40:41], v[42:43], 2, s[38:39]
	global_load_dwordx4 v[16:19], v[44:45], off
	global_load_dwordx4 v[12:15], v[40:41], off
	v_lshl_add_u64 v[32:33], v[34:35], 2, s[38:39]
	global_load_dwordx4 v[8:11], v[36:37], off
	global_load_dwordx4 v[4:7], v[32:33], off
	global_load_dwordx4 v[0:3], v[28:29], off
	ds_read_b128 v[60:63], v120
	s_waitcnt vmcnt(0) lgkmcnt(0)
	v_pk_fma_f32 v[56:57], v[60:61], 0.5, v[56:57] op_sel_hi:[1,0,1]
	v_pk_fma_f32 v[58:59], v[62:63], 0.5, v[58:59] op_sel_hi:[1,0,1]
	global_store_dwordx4 v[66:67], v[56:59], off
	v_cvt_pk_bf16_f32 v60, v56, v57
	v_cvt_pk_bf16_f32 v61, v58, v59
	v_pk_mul_f32 v[56:57], v[56:57], v[56:57]
	v_pk_mul_f32 v[58:59], v[58:59], v[58:59]
	v_add_f32_e32 v56, v56, v57
	v_add_f32_e32 v56, v56, v58
	v_add_f32_e32 v56, v56, v59
	v_lshl_add_u64 v[62:63], v[64:65], 1, s[6:7]
	global_store_dwordx2 v[62:63], v[60:61], off
	v_add_f32_dpp v56, v56, v56 row_ror:8 row_mask:0xf bank_mask:0xf bound_ctrl:1
	s_nop 1
	v_add_f32_dpp v56, v56, v56 row_ror:4 row_mask:0xf bank_mask:0xf bound_ctrl:1
	s_nop 1
	v_add_f32_dpp v56, v56, v56 row_ror:2 row_mask:0xf bank_mask:0xf bound_ctrl:1
	s_nop 1
	v_add_f32_dpp v56, v56, v56 row_ror:1 row_mask:0xf bank_mask:0xf bound_ctrl:1
	s_nop 0
	v_readlane_b32 s11, v56, 0
	v_readlane_b32 s70, v56, 16
	v_readlane_b32 s68, v56, 32
	v_readlane_b32 s69, v56, 48
	s_and_saveexec_b64 s[62:63], vcc
	s_cbranch_execz .LBB0_1816
	s_lshl_b64 s[34:35], s[34:35], 2
	v_mov_b32_e32 v56, s70
	s_add_u32 s34, s2, s34
	v_add_f32_e32 v56, s11, v56
	s_addc_u32 s35, s3, s35
	v_add_f32_e32 v56, s68, v56
	v_add_f32_e32 v58, s69, v56
	v_mov_b64_e32 v[56:57], s[34:35]
	global_atomic_add_f32 v[56:57], v58, off
; DEVI float fsig(float x) { return __builtin_amdgcn_rcpf(1.f + __expf(-x)); }
; DEVI float bflo(unsigned u) { return __uint_as_float(u << 16); }
; DEVI float bfhi(unsigned u) { return __uint_as_float(u & 0xffff0000u); }
; template <int EPI, int TS, bool VT>
; DEVI void gemm_epilogue(const Params& p, char* smem, f32x4 (&acc)[2][2][4][2], int m0, int n0, float scale, const float* ssin,
;                         float* ssout, u16* xbout, int wid, int lane, int wr, int wc, int fr, int fq) {
;     ...
;           if constexpr (EPI == E_RESID || EPI == E_PLEGATE) {
;             const float4 a = *(const float4*)(Tr + 4 * lane);
;             const size_t ro = (size_t)grow * 1024 + n0 + 4 * lane;
;             float4 x4 = xo[u];
;             if constexpr (EPI == E_PLEGATE) {
;               x4.x += bflo(pv[u].x) * fsig(a.x * rs);
;               x4.y += bfhi(pv[u].x) * fsig(a.y * rs);
;               x4.z += bflo(pv[u].y) * fsig(a.z * rs);
;               x4.w += bfhi(pv[u].y) * fsig(a.w * rs);
;             } else {
;               const float sc = fabsf(scale);
;               x4.x += sc * a.x; x4.y += sc * a.y; x4.z += sc * a.z; x4.w += sc * a.w;
;             }
;             st_nt16(p.x + ro, x4);
;             if (xbout) {
;               uint2 o;
;               o.x = pack2(x4.x, x4.y);
;               o.y = pack2(x4.z, x4.w);
;               st_nt8(xbout + ro, o);
;             }
;             if (ssout) {
;               const float ssq = wsum(x4.x * x4.x + x4.y * x4.y + x4.z * x4.z + x4.w * x4.w, lane);
;               if (lane == 0) atomicAdd(ssout + grow, ssq);
;             }
.LBB0_1816:
	s_or_b64 exec, exec, s[62:63]
	ds_read_b128 v[56:59], v120 offset:1040
	v_lshl_add_u64 v[54:55], v[54:55], 1, s[6:7]
	s_waitcnt lgkmcnt(0)
	v_pk_fma_f32 v[24:25], v[56:57], 0.5, v[24:25] op_sel_hi:[1,0,1]
	v_pk_fma_f32 v[26:27], v[58:59], 0.5, v[26:27] op_sel_hi:[1,0,1]
	global_store_dwordx4 v[52:53], v[24:27], off
	v_cvt_pk_bf16_f32 v52, v24, v25
	v_cvt_pk_bf16_f32 v53, v26, v27
	v_pk_mul_f32 v[24:25], v[24:25], v[24:25]
	v_pk_mul_f32 v[26:27], v[26:27], v[26:27]
	v_add_f32_e32 v24, v24, v25
	v_add_f32_e32 v24, v24, v26
	v_add_f32_e32 v24, v24, v27
	global_store_dwordx2 v[54:55], v[52:53], off
	s_nop 0
	v_add_f32_dpp v24, v24, v24 row_ror:8 row_mask:0xf bank_mask:0xf bound_ctrl:1
	s_nop 1
	v_add_f32_dpp v24, v24, v24 row_ror:4 row_mask:0xf bank_mask:0xf bound_ctrl:1
	s_nop 1
	v_add_f32_dpp v24, v24, v24 row_ror:2 row_mask:0xf bank_mask:0xf bound_ctrl:1
	s_nop 1
	v_add_f32_dpp v24, v24, v24 row_ror:1 row_mask:0xf bank_mask:0xf bound_ctrl:1
	s_nop 0
	v_readlane_b32 s11, v24, 0
	v_readlane_b32 s68, v24, 16
	v_readlane_b32 s62, v24, 32
	v_readlane_b32 s63, v24, 48
	s_and_saveexec_b64 s[34:35], vcc
	s_cbranch_execz .LBB0_1818
	s_lshl_b64 s[30:31], s[30:31], 2
	v_mov_b32_e32 v24, s68
	s_add_u32 s30, s2, s30
	v_add_f32_e32 v24, s11, v24
	s_addc_u32 s31, s3, s31
	v_add_f32_e32 v24, s62, v24
	v_add_f32_e32 v26, s63, v24
	v_mov_b64_e32 v[24:25], s[30:31]
	global_atomic_add_f32 v[24:25], v26, off
.LBB0_1818:
	s_or_b64 exec, exec, s[34:35]
	ds_read_b128 v[24:27], v120 offset:2080
	v_lshl_add_u64 v[50:51], v[50:51], 1, s[6:7]
	s_waitcnt lgkmcnt(0)
	v_pk_fma_f32 v[20:21], v[24:25], 0.5, v[20:21] op_sel_hi:[1,0,1]
	v_pk_fma_f32 v[22:23], v[26:27], 0.5, v[22:23] op_sel_hi:[1,0,1]
	global_store_dwordx4 v[48:49], v[20:23], off
	v_cvt_pk_bf16_f32 v24, v20, v21
	v_cvt_pk_bf16_f32 v25, v22, v23
	v_pk_mul_f32 v[20:21], v[20:21], v[20:21]
	v_pk_mul_f32 v[22:23], v[22:23], v[22:23]
	v_add_f32_e32 v20, v20, v21
	v_add_f32_e32 v20, v20, v22
	v_add_f32_e32 v20, v20, v23
	global_store_dwordx2 v[50:51], v[24:25], off
	s_nop 0
	v_add_f32_dpp v20, v20, v20 row_ror:8 row_mask:0xf bank_mask:0xf bound_ctrl:1
	s_nop 1
	v_add_f32_dpp v20, v20, v20 row_ror:4 row_mask:0xf bank_mask:0xf bound_ctrl:1
	s_nop 1
	v_add_f32_dpp v20, v20, v20 row_ror:2 row_mask:0xf bank_mask:0xf bound_ctrl:1
	s_nop 1
	v_add_f32_dpp v20, v20, v20 row_ror:1 row_mask:0xf bank_mask:0xf bound_ctrl:1
	s_nop 0
	v_readlane_b32 s11, v20, 0
	v_readlane_b32 s62, v20, 16
	v_readlane_b32 s34, v20, 32
	v_readlane_b32 s35, v20, 48
	s_and_saveexec_b64 s[30:31], vcc
	s_cbranch_execz .LBB0_1820
	s_lshl_b64 s[22:23], s[22:23], 2
	v_mov_b32_e32 v20, s62
	s_add_u32 s22, s2, s22
	v_add_f32_e32 v20, s11, v20
	s_addc_u32 s23, s3, s23
	v_add_f32_e32 v20, s34, v20
	v_add_f32_e32 v22, s35, v20
	v_mov_b64_e32 v[20:21], s[22:23]
	global_atomic_add_f32 v[20:21], v22, off
.LBB0_1820:
	s_or_b64 exec, exec, s[30:31]
	ds_read_b128 v[20:23], v120 offset:3120
	v_lshl_add_u64 v[24:25], v[46:47], 1, s[6:7]
	s_waitcnt lgkmcnt(0)
	v_pk_fma_f32 v[16:17], v[20:21], 0.5, v[16:17] op_sel_hi:[1,0,1]
	v_pk_fma_f32 v[18:19], v[22:23], 0.5, v[18:19] op_sel_hi:[1,0,1]
	global_store_dwordx4 v[44:45], v[16:19], off
	v_cvt_pk_bf16_f32 v20, v16, v17
	v_cvt_pk_bf16_f32 v21, v18, v19
	v_pk_mul_f32 v[16:17], v[16:17], v[16:17]
	v_pk_mul_f32 v[18:19], v[18:19], v[18:19]
	v_add_f32_e32 v16, v16, v17
	v_add_f32_e32 v16, v16, v18
	v_add_f32_e32 v16, v16, v19
	global_store_dwordx2 v[24:25], v[20:21], off
	s_nop 0
	v_add_f32_dpp v16, v16, v16 row_ror:8 row_mask:0xf bank_mask:0xf bound_ctrl:1
	s_nop 1
	v_add_f32_dpp v16, v16, v16 row_ror:4 row_mask:0xf bank_mask:0xf bound_ctrl:1
	s_nop 1
	v_add_f32_dpp v16, v16, v16 row_ror:2 row_mask:0xf bank_mask:0xf bound_ctrl:1
	s_nop 1
	v_add_f32_dpp v16, v16, v16 row_ror:1 row_mask:0xf bank_mask:0xf bound_ctrl:1
	s_nop 0
	v_readlane_b32 s11, v16, 0
	v_readlane_b32 s34, v16, 16
	v_readlane_b32 s30, v16, 32
	v_readlane_b32 s31, v16, 48
	s_and_saveexec_b64 s[22:23], vcc
	s_cbranch_execz .LBB0_1822
	s_lshl_b64 s[20:21], s[20:21], 2
	v_mov_b32_e32 v16, s34
	s_add_u32 s20, s2, s20
	v_add_f32_e32 v16, s11, v16
	s_addc_u32 s21, s3, s21
	v_add_f32_e32 v16, s30, v16
	v_add_f32_e32 v18, s31, v16
	v_mov_b64_e32 v[16:17], s[20:21]
	global_atomic_add_f32 v[16:17], v18, off
.LBB0_1822:
	s_or_b64 exec, exec, s[22:23]
	ds_read_b128 v[16:19], v120 offset:4160
	v_lshl_add_u64 v[20:21], v[42:43], 1, s[6:7]
	s_waitcnt lgkmcnt(0)
	v_pk_fma_f32 v[12:13], v[16:17], 0.5, v[12:13] op_sel_hi:[1,0,1]
	v_pk_fma_f32 v[14:15], v[18:19], 0.5, v[14:15] op_sel_hi:[1,0,1]
	global_store_dwordx4 v[40:41], v[12:15], off
	v_cvt_pk_bf16_f32 v16, v12, v13
	v_cvt_pk_bf16_f32 v17, v14, v15
	v_pk_mul_f32 v[12:13], v[12:13], v[12:13]
	v_pk_mul_f32 v[14:15], v[14:15], v[14:15]
	v_add_f32_e32 v12, v12, v13
	v_add_f32_e32 v12, v12, v14
	v_add_f32_e32 v12, v12, v15
	global_store_dwordx2 v[20:21], v[16:17], off
	s_nop 0
	v_add_f32_dpp v12, v12, v12 row_ror:8 row_mask:0xf bank_mask:0xf bound_ctrl:1
	s_nop 1
	v_add_f32_dpp v12, v12, v12 row_ror:4 row_mask:0xf bank_mask:0xf bound_ctrl:1
	s_nop 1
	v_add_f32_dpp v12, v12, v12 row_ror:2 row_mask:0xf bank_mask:0xf bound_ctrl:1
	s_nop 1
	v_add_f32_dpp v12, v12, v12 row_ror:1 row_mask:0xf bank_mask:0xf bound_ctrl:1
	s_nop 0
	v_readlane_b32 s11, v12, 0
	v_readlane_b32 s30, v12, 16
	v_readlane_b32 s22, v12, 32
	v_readlane_b32 s23, v12, 48
	s_and_saveexec_b64 s[20:21], vcc
	s_cbranch_execz .LBB0_1824
	s_lshl_b64 s[18:19], s[18:19], 2
	v_mov_b32_e32 v12, s30
	s_add_u32 s18, s2, s18
	v_add_f32_e32 v12, s11, v12
	s_addc_u32 s19, s3, s19
	v_add_f32_e32 v12, s22, v12
	v_add_f32_e32 v14, s23, v12
	v_mov_b64_e32 v[12:13], s[18:19]
	global_atomic_add_f32 v[12:13], v14, off
; DEVI float fsig(float x) { return __builtin_amdgcn_rcpf(1.f + __expf(-x)); }
; template <int EPI, int TS, bool VT>
; DEVI void gemm_epilogue(const Params& p, char* smem, f32x4 (&acc)[2][2][4][2], int m0, int n0, float scale, const float* ssin,
;                         float* ssout, u16* xbout, int wid, int lane, int wr, int wc, int fr, int fq) {
;     ...
;         if constexpr (EPI == E_RESID || EPI == E_PLEGATE) {
; #pragma unroll
;           for (int u = 0; u < 8; ++u) {
;             const size_t ro = (size_t)(g0 + i0 + u) * 1024 + n0 + 4 * lane;
;             const int gr = g0 + i0 + u;
;             const float* xs = p.x + ro;
;             if (scale < 0.f)
;               xs = (gr < MP ? p.x_prompt + ro : p.x_sample + (ro - (size_t)MP * 1024));
;             { const f32x4 t_ = __builtin_nontemporal_load((const f32x4*)xs); xo[u] = make_float4(t_[0], t_[1], t_[2], t_[3]); }
;             if constexpr (EPI == E_PLEGATE) {
;               const unsigned long long t2_ = __builtin_nontemporal_load((const unsigned long long*)((const u16*)(wsb + OFF_PP) + ro));
;               pv[u] = make_uint2((unsigned)t2_, (unsigned)(t2_ >> 32));
;             }
;           }
;         }
; #pragma unroll
;         for (int u = 0; u < 8; ++u) {
;           const int i = i0 + u;
;           const int grow = g0 + i;
;           const float* Tr = T + (r0 + i) * TS;
;           const float rs = __int_as_float(__builtin_amdgcn_readlane(__float_as_int(rsv), i));
;           if constexpr (EPI == E_RESID || EPI == E_PLEGATE) {
;             const float4 a = *(const float4*)(Tr + 4 * lane);
;             const size_t ro = (size_t)grow * 1024 + n0 + 4 * lane;
;             float4 x4 = xo[u];
;             if constexpr (EPI == E_PLEGATE) {
;               x4.x += bflo(pv[u].x) * fsig(a.x * rs);
;               x4.y += bfhi(pv[u].x) * fsig(a.y * rs);
;               x4.z += bflo(pv[u].y) * fsig(a.z * rs);
;               x4.w += bfhi(pv[u].y) * fsig(a.w * rs);
;             } else {
;               const float sc = fabsf(scale);
;               x4.x += sc * a.x; x4.y += sc * a.y; x4.z += sc * a.z; x4.w += sc * a.w;
;             }
;             st_nt16(p.x + ro, x4);
;             if (xbout) {
;               uint2 o;
;               o.x = pack2(x4.x, x4.y);
;               o.y = pack2(x4.z, x4.w);
;               st_nt8(xbout + ro, o);
;             }
;             if (ssout) {
.LBB0_1824:
	s_or_b64 exec, exec, s[20:21]
	ds_read_b128 v[12:15], v120 offset:5200
	v_lshl_add_u64 v[16:17], v[38:39], 1, s[6:7]
	s_waitcnt lgkmcnt(0)
	v_pk_fma_f32 v[8:9], v[12:13], 0.5, v[8:9] op_sel_hi:[1,0,1]
	v_pk_fma_f32 v[10:11], v[14:15], 0.5, v[10:11] op_sel_hi:[1,0,1]
	global_store_dwordx4 v[36:37], v[8:11], off
	v_cvt_pk_bf16_f32 v12, v8, v9
	v_cvt_pk_bf16_f32 v13, v10, v11
	v_pk_mul_f32 v[8:9], v[8:9], v[8:9]
	v_pk_mul_f32 v[10:11], v[10:11], v[10:11]
	v_add_f32_e32 v8, v8, v9
	v_add_f32_e32 v8, v8, v10
	v_add_f32_e32 v8, v8, v11
	global_store_dwordx2 v[16:17], v[12:13], off
	s_nop 0
	v_add_f32_dpp v8, v8, v8 row_ror:8 row_mask:0xf bank_mask:0xf bound_ctrl:1
	s_nop 1
	v_add_f32_dpp v8, v8, v8 row_ror:4 row_mask:0xf bank_mask:0xf bound_ctrl:1
	s_nop 1
	v_add_f32_dpp v8, v8, v8 row_ror:2 row_mask:0xf bank_mask:0xf bound_ctrl:1
	s_nop 1
	v_add_f32_dpp v8, v8, v8 row_ror:1 row_mask:0xf bank_mask:0xf bound_ctrl:1
	s_nop 0
	v_readlane_b32 s11, v8, 0
	v_readlane_b32 s22, v8, 16
	v_readlane_b32 s20, v8, 32
	v_readlane_b32 s21, v8, 48
	s_and_saveexec_b64 s[18:19], vcc
	s_cbranch_execz .LBB0_1826
	s_lshl_b64 s[16:17], s[16:17], 2
	v_mov_b32_e32 v8, s22
	s_add_u32 s16, s2, s16
	v_add_f32_e32 v8, s11, v8
	s_addc_u32 s17, s3, s17
	v_add_f32_e32 v8, s20, v8
	v_add_f32_e32 v10, s21, v8
	v_mov_b64_e32 v[8:9], s[16:17]
	global_atomic_add_f32 v[8:9], v10, off
.LBB0_1826:
	s_or_b64 exec, exec, s[18:19]
	ds_read_b128 v[8:11], v120 offset:6240
	v_lshl_add_u64 v[12:13], v[34:35], 1, s[6:7]
	s_waitcnt lgkmcnt(0)
	v_pk_fma_f32 v[4:5], v[8:9], 0.5, v[4:5] op_sel_hi:[1,0,1]
	v_pk_fma_f32 v[6:7], v[10:11], 0.5, v[6:7] op_sel_hi:[1,0,1]
	global_store_dwordx4 v[32:33], v[4:7], off
	v_cvt_pk_bf16_f32 v8, v4, v5
	v_cvt_pk_bf16_f32 v9, v6, v7
	v_pk_mul_f32 v[4:5], v[4:5], v[4:5]
	v_pk_mul_f32 v[6:7], v[6:7], v[6:7]
	v_add_f32_e32 v4, v4, v5
	v_add_f32_e32 v4, v4, v6
	v_add_f32_e32 v4, v4, v7
	global_store_dwordx2 v[12:13], v[8:9], off
	s_nop 0
	v_add_f32_dpp v4, v4, v4 row_ror:8 row_mask:0xf bank_mask:0xf bound_ctrl:1
	s_nop 1
	v_add_f32_dpp v4, v4, v4 row_ror:4 row_mask:0xf bank_mask:0xf bound_ctrl:1
	s_nop 1
	v_add_f32_dpp v4, v4, v4 row_ror:2 row_mask:0xf bank_mask:0xf bound_ctrl:1
	s_nop 1
	v_add_f32_dpp v4, v4, v4 row_ror:1 row_mask:0xf bank_mask:0xf bound_ctrl:1
	s_nop 0
	v_readlane_b32 s11, v4, 0
	v_readlane_b32 s20, v4, 16
	v_readlane_b32 s18, v4, 32
	v_readlane_b32 s19, v4, 48
	s_and_saveexec_b64 s[16:17], vcc
	s_cbranch_execz .LBB0_1828
	s_lshl_b64 s[14:15], s[14:15], 2
	v_mov_b32_e32 v4, s20
	s_add_u32 s14, s2, s14
	v_add_f32_e32 v4, s11, v4
	s_addc_u32 s15, s3, s15
	v_add_f32_e32 v4, s18, v4
	v_add_f32_e32 v6, s19, v4
	v_mov_b64_e32 v[4:5], s[14:15]
	global_atomic_add_f32 v[4:5], v6, off
.LBB0_1828:
	s_or_b64 exec, exec, s[16:17]
	ds_read_b128 v[4:7], v120 offset:7280
	v_lshl_add_u64 v[8:9], v[30:31], 1, s[6:7]
	s_waitcnt lgkmcnt(0)
	v_pk_fma_f32 v[0:1], v[4:5], 0.5, v[0:1] op_sel_hi:[1,0,1]
	v_pk_fma_f32 v[2:3], v[6:7], 0.5, v[2:3] op_sel_hi:[1,0,1]
	global_store_dwordx4 v[28:29], v[0:3], off
	v_cvt_pk_bf16_f32 v4, v0, v1
	v_cvt_pk_bf16_f32 v5, v2, v3
	v_pk_mul_f32 v[0:1], v[0:1], v[0:1]
	v_pk_mul_f32 v[2:3], v[2:3], v[2:3]
	v_add_f32_e32 v0, v0, v1
	v_add_f32_e32 v0, v0, v2
	v_add_f32_e32 v0, v0, v3
	global_store_dwordx2 v[8:9], v[4:5], off
	s_nop 0
	v_add_f32_dpp v0, v0, v0 row_ror:8 row_mask:0xf bank_mask:0xf bound_ctrl:1
	s_nop 1
	v_add_f32_dpp v0, v0, v0 row_ror:4 row_mask:0xf bank_mask:0xf bound_ctrl:1
	s_nop 1
	v_add_f32_dpp v0, v0, v0 row_ror:2 row_mask:0xf bank_mask:0xf bound_ctrl:1
	s_nop 1
	v_add_f32_dpp v0, v0, v0 row_ror:1 row_mask:0xf bank_mask:0xf bound_ctrl:1
	s_nop 0
	v_readlane_b32 s11, v0, 0
	v_readlane_b32 s18, v0, 16
	v_readlane_b32 s16, v0, 32
	v_readlane_b32 s17, v0, 48
	s_and_saveexec_b64 s[14:15], vcc
	s_cbranch_execz .LBB0_1830
	s_lshl_b64 s[12:13], s[12:13], 2
	v_mov_b32_e32 v0, s18
	s_add_u32 s12, s2, s12
	v_add_f32_e32 v0, s11, v0
	s_addc_u32 s13, s3, s13
	v_add_f32_e32 v0, s16, v0
	v_add_f32_e32 v2, s17, v0
	v_mov_b64_e32 v[0:1], s[12:13]
	global_atomic_add_f32 v[0:1], v2, off
.LBB0_1830:
	s_or_b64 exec, exec, s[14:15]
	s_add_i32 s30, s10, 0x88
	s_ashr_i32 s31, s30, 31
	s_lshl_b64 s[12:13], s[30:31], 10
	s_add_i32 s22, s10, 0x89
	v_lshl_add_u64 v[64:65], s[12:13], 0, v[128:129]
	s_ashr_i32 s23, s22, 31
	s_add_i32 s20, s10, 0x8a
	v_lshl_add_u64 v[66:67], v[64:65], 2, s[38:39]
	s_lshl_b64 s[12:13], s[22:23], 10
	s_ashr_i32 s21, s20, 31
	s_add_i32 s18, s10, 0x8b
	global_load_dwordx4 v[56:59], v[66:67], off
	v_lshl_add_u64 v[54:55], s[12:13], 0, v[128:129]
	s_lshl_b64 s[12:13], s[20:21], 10
	s_ashr_i32 s19, s18, 31
	s_add_i32 s16, s10, 0x8c
	v_lshl_add_u64 v[50:51], s[12:13], 0, v[128:129]
	s_lshl_b64 s[12:13], s[18:19], 10
	s_ashr_i32 s17, s16, 31
	s_add_i32 s14, s10, 0x8d
	v_lshl_add_u64 v[46:47], s[12:13], 0, v[128:129]
	s_lshl_b64 s[12:13], s[16:17], 10
	s_ashr_i32 s15, s14, 31
	v_lshl_add_u64 v[42:43], s[12:13], 0, v[128:129]
	s_lshl_b64 s[12:13], s[14:15], 10
	v_lshl_add_u64 v[38:39], s[12:13], 0, v[128:129]
	s_add_i32 s12, s10, 0x8e
	s_ashr_i32 s13, s12, 31
	s_addk_i32 s10, 0x8f
	s_lshl_b64 s[34:35], s[12:13], 10
	s_ashr_i32 s11, s10, 31
	v_lshl_add_u64 v[34:35], s[34:35], 0, v[128:129]
	s_lshl_b64 s[34:35], s[10:11], 10
	v_lshl_add_u64 v[30:31], s[34:35], 0, v[128:129]
	v_lshl_add_u64 v[52:53], v[54:55], 2, s[38:39]
	v_lshl_add_u64 v[44:45], v[46:47], 2, s[38:39]
	v_lshl_add_u64 v[36:37], v[38:39], 2, s[38:39]
	v_lshl_add_u64 v[28:29], v[30:31], 2, s[38:39]
	v_lshl_add_u64 v[48:49], v[50:51], 2, s[38:39]
	global_load_dwordx4 v[24:27], v[52:53], off
	global_load_dwordx4 v[20:23], v[48:49], off
	v_lshl_add_u64 v[40:41], v[42:43], 2, s[38:39]
	global_load_dwordx4 v[16:19], v[44:45], off
	global_load_dwordx4 v[12:15], v[40:41], off
	v_lshl_add_u64 v[32:33], v[34:35], 2, s[38:39]
	global_load_dwordx4 v[8:11], v[36:37], off
	global_load_dwordx4 v[4:7], v[32:33], off
	global_load_dwordx4 v[0:3], v[28:29], off
	ds_read_b128 v[60:63], v120 offset:8320
	v_lshl_add_u64 v[64:65], v[64:65], 1, s[6:7]
	s_waitcnt vmcnt(0) lgkmcnt(0)
; DEVI float fsig(float x) { return __builtin_amdgcn_rcpf(1.f + __expf(-x)); }
; DEVI float bflo(unsigned u) { return __uint_as_float(u << 16); }
; DEVI float bfhi(unsigned u) { return __uint_as_float(u & 0xffff0000u); }
; template <int EPI, int TS, bool VT>
; DEVI void gemm_epilogue(const Params& p, char* smem, f32x4 (&acc)[2][2][4][2], int m0, int n0, float scale, const float* ssin,
;                         float* ssout, u16* xbout, int wid, int lane, int wr, int wc, int fr, int fq) {
;     ...
;           if constexpr (EPI == E_RESID || EPI == E_PLEGATE) {
;             const float4 a = *(const float4*)(Tr + 4 * lane);
;             const size_t ro = (size_t)grow * 1024 + n0 + 4 * lane;
;             float4 x4 = xo[u];
;             if constexpr (EPI == E_PLEGATE) {
;               x4.x += bflo(pv[u].x) * fsig(a.x * rs);
;               x4.y += bfhi(pv[u].x) * fsig(a.y * rs);
;               x4.z += bflo(pv[u].y) * fsig(a.z * rs);
;               x4.w += bfhi(pv[u].y) * fsig(a.w * rs);
;             } else {
;               const float sc = fabsf(scale);
;               x4.x += sc * a.x; x4.y += sc * a.y; x4.z += sc * a.z; x4.w += sc * a.w;
;             }
;             st_nt16(p.x + ro, x4);
;             if (xbout) {
;               uint2 o;
;               o.x = pack2(x4.x, x4.y);
;               o.y = pack2(x4.z, x4.w);
;               st_nt8(xbout + ro, o);
;             }
;             if (ssout) {
;               const float ssq = wsum(x4.x * x4.x + x4.y * x4.y + x4.z * x4.z + x4.w * x4.w, lane);
;               if (lane == 0) atomicAdd(ssout + grow, ssq);
;             }
	v_pk_fma_f32 v[56:57], v[60:61], 0.5, v[56:57] op_sel_hi:[1,0,1]
	v_pk_fma_f32 v[58:59], v[62:63], 0.5, v[58:59] op_sel_hi:[1,0,1]
	global_store_dwordx4 v[66:67], v[56:59], off
	v_cvt_pk_bf16_f32 v60, v56, v57
	v_cvt_pk_bf16_f32 v61, v58, v59
	v_pk_mul_f32 v[56:57], v[56:57], v[56:57]
	v_pk_mul_f32 v[58:59], v[58:59], v[58:59]
	v_add_f32_e32 v56, v56, v57
	v_add_f32_e32 v56, v56, v58
	v_add_f32_e32 v56, v56, v59
	global_store_dwordx2 v[64:65], v[60:61], off
	s_nop 0
	v_add_f32_dpp v56, v56, v56 row_ror:8 row_mask:0xf bank_mask:0xf bound_ctrl:1
	s_nop 1
	v_add_f32_dpp v56, v56, v56 row_ror:4 row_mask:0xf bank_mask:0xf bound_ctrl:1
	s_nop 1
	v_add_f32_dpp v56, v56, v56 row_ror:2 row_mask:0xf bank_mask:0xf bound_ctrl:1
	s_nop 1
	v_add_f32_dpp v56, v56, v56 row_ror:1 row_mask:0xf bank_mask:0xf bound_ctrl:1
	s_nop 0
	v_readlane_b32 s62, v56, 0
	v_readlane_b32 s69, v56, 16
	v_readlane_b32 s63, v56, 32
	v_readlane_b32 s68, v56, 48
	s_and_saveexec_b64 s[34:35], vcc
	s_cbranch_execz .LBB0_1832
	s_lshl_b64 s[30:31], s[30:31], 2
	v_mov_b32_e32 v56, s69
	s_add_u32 s30, s2, s30
	v_add_f32_e32 v56, s62, v56
	s_addc_u32 s31, s3, s31
	v_add_f32_e32 v56, s63, v56
	v_add_f32_e32 v58, s68, v56
	v_mov_b64_e32 v[56:57], s[30:31]
	global_atomic_add_f32 v[56:57], v58, off
.LBB0_1832:
	s_or_b64 exec, exec, s[34:35]
	ds_read_b128 v[56:59], v120 offset:9360
	v_lshl_add_u64 v[54:55], v[54:55], 1, s[6:7]
	s_waitcnt lgkmcnt(0)
	v_pk_fma_f32 v[24:25], v[56:57], 0.5, v[24:25] op_sel_hi:[1,0,1]
	v_pk_fma_f32 v[26:27], v[58:59], 0.5, v[26:27] op_sel_hi:[1,0,1]
	global_store_dwordx4 v[52:53], v[24:27], off
	v_cvt_pk_bf16_f32 v52, v24, v25
	v_cvt_pk_bf16_f32 v53, v26, v27
	v_pk_mul_f32 v[24:25], v[24:25], v[24:25]
	v_pk_mul_f32 v[26:27], v[26:27], v[26:27]
	v_add_f32_e32 v24, v24, v25
	v_add_f32_e32 v24, v24, v26
	v_add_f32_e32 v24, v24, v27
	global_store_dwordx2 v[54:55], v[52:53], off
	s_nop 0
	v_add_f32_dpp v24, v24, v24 row_ror:8 row_mask:0xf bank_mask:0xf bound_ctrl:1
	s_nop 1
	v_add_f32_dpp v24, v24, v24 row_ror:4 row_mask:0xf bank_mask:0xf bound_ctrl:1
	s_nop 1
	v_add_f32_dpp v24, v24, v24 row_ror:2 row_mask:0xf bank_mask:0xf bound_ctrl:1
	s_nop 1
	v_add_f32_dpp v24, v24, v24 row_ror:1 row_mask:0xf bank_mask:0xf bound_ctrl:1
	s_nop 0
	v_readlane_b32 s34, v24, 0
	v_readlane_b32 s63, v24, 16
	v_readlane_b32 s35, v24, 32
	v_readlane_b32 s62, v24, 48
	s_and_saveexec_b64 s[30:31], vcc
	s_cbranch_execz .LBB0_1834
	s_lshl_b64 s[22:23], s[22:23], 2
	v_mov_b32_e32 v24, s63
	s_add_u32 s22, s2, s22
	v_add_f32_e32 v24, s34, v24
	s_addc_u32 s23, s3, s23
	v_add_f32_e32 v24, s35, v24
	v_add_f32_e32 v26, s62, v24
	v_mov_b64_e32 v[24:25], s[22:23]
	global_atomic_add_f32 v[24:25], v26, off
.LBB0_1834:
	s_or_b64 exec, exec, s[30:31]
	ds_read_b128 v[24:27], v120 offset:10400
	v_lshl_add_u64 v[50:51], v[50:51], 1, s[6:7]
	s_waitcnt lgkmcnt(0)
	v_pk_fma_f32 v[20:21], v[24:25], 0.5, v[20:21] op_sel_hi:[1,0,1]
	v_pk_fma_f32 v[22:23], v[26:27], 0.5, v[22:23] op_sel_hi:[1,0,1]
	global_store_dwordx4 v[48:49], v[20:23], off
	v_cvt_pk_bf16_f32 v24, v20, v21
	v_cvt_pk_bf16_f32 v25, v22, v23
	v_pk_mul_f32 v[20:21], v[20:21], v[20:21]
	v_pk_mul_f32 v[22:23], v[22:23], v[22:23]
	v_add_f32_e32 v20, v20, v21
	v_add_f32_e32 v20, v20, v22
	v_add_f32_e32 v20, v20, v23
	global_store_dwordx2 v[50:51], v[24:25], off
	s_nop 0
	v_add_f32_dpp v20, v20, v20 row_ror:8 row_mask:0xf bank_mask:0xf bound_ctrl:1
	s_nop 1
	v_add_f32_dpp v20, v20, v20 row_ror:4 row_mask:0xf bank_mask:0xf bound_ctrl:1
	s_nop 1
	v_add_f32_dpp v20, v20, v20 row_ror:2 row_mask:0xf bank_mask:0xf bound_ctrl:1
	s_nop 1
	v_add_f32_dpp v20, v20, v20 row_ror:1 row_mask:0xf bank_mask:0xf bound_ctrl:1
	s_nop 0
	v_readlane_b32 s30, v20, 0
	v_readlane_b32 s35, v20, 16
	v_readlane_b32 s31, v20, 32
	v_readlane_b32 s34, v20, 48
	s_and_saveexec_b64 s[22:23], vcc
	s_cbranch_execz .LBB0_1836
	s_lshl_b64 s[20:21], s[20:21], 2
	v_mov_b32_e32 v20, s35
	s_add_u32 s20, s2, s20
	v_add_f32_e32 v20, s30, v20
	s_addc_u32 s21, s3, s21
	v_add_f32_e32 v20, s31, v20
	v_add_f32_e32 v22, s34, v20
	v_mov_b64_e32 v[20:21], s[20:21]
	global_atomic_add_f32 v[20:21], v22, off
.LBB0_1836:
	s_or_b64 exec, exec, s[22:23]
	ds_read_b128 v[20:23], v120 offset:11440
	v_lshl_add_u64 v[24:25], v[46:47], 1, s[6:7]
	s_waitcnt lgkmcnt(0)
	v_pk_fma_f32 v[16:17], v[20:21], 0.5, v[16:17] op_sel_hi:[1,0,1]
	v_pk_fma_f32 v[18:19], v[22:23], 0.5, v[18:19] op_sel_hi:[1,0,1]
	global_store_dwordx4 v[44:45], v[16:19], off
	v_cvt_pk_bf16_f32 v20, v16, v17
	v_cvt_pk_bf16_f32 v21, v18, v19
	v_pk_mul_f32 v[16:17], v[16:17], v[16:17]
	v_pk_mul_f32 v[18:19], v[18:19], v[18:19]
	v_add_f32_e32 v16, v16, v17
	v_add_f32_e32 v16, v16, v18
	v_add_f32_e32 v16, v16, v19
	global_store_dwordx2 v[24:25], v[20:21], off
	s_nop 0
	v_add_f32_dpp v16, v16, v16 row_ror:8 row_mask:0xf bank_mask:0xf bound_ctrl:1
	s_nop 1
	v_add_f32_dpp v16, v16, v16 row_ror:4 row_mask:0xf bank_mask:0xf bound_ctrl:1
	s_nop 1
	v_add_f32_dpp v16, v16, v16 row_ror:2 row_mask:0xf bank_mask:0xf bound_ctrl:1
	s_nop 1
	v_add_f32_dpp v16, v16, v16 row_ror:1 row_mask:0xf bank_mask:0xf bound_ctrl:1
	s_nop 0
	v_readlane_b32 s22, v16, 0
	v_readlane_b32 s31, v16, 16
	v_readlane_b32 s23, v16, 32
	v_readlane_b32 s30, v16, 48
	s_and_saveexec_b64 s[20:21], vcc
	s_cbranch_execz .LBB0_1838
	s_lshl_b64 s[18:19], s[18:19], 2
	v_mov_b32_e32 v16, s31
	s_add_u32 s18, s2, s18
	v_add_f32_e32 v16, s22, v16
	s_addc_u32 s19, s3, s19
	v_add_f32_e32 v16, s23, v16
	v_add_f32_e32 v18, s30, v16
	v_mov_b64_e32 v[16:17], s[18:19]
	global_atomic_add_f32 v[16:17], v18, off
; DEVI float fsig(float x) { return __builtin_amdgcn_rcpf(1.f + __expf(-x)); }
; DEVI float bflo(unsigned u) { return __uint_as_float(u << 16); }
; DEVI float bfhi(unsigned u) { return __uint_as_float(u & 0xffff0000u); }
; template <int EPI, int TS, bool VT>
; DEVI void gemm_epilogue(const Params& p, char* smem, f32x4 (&acc)[2][2][4][2], int m0, int n0, float scale, const float* ssin,
;                         float* ssout, u16* xbout, int wid, int lane, int wr, int wc, int fr, int fq) {
;     ...
;           if constexpr (EPI == E_RESID || EPI == E_PLEGATE) {
;             const float4 a = *(const float4*)(Tr + 4 * lane);
;             const size_t ro = (size_t)grow * 1024 + n0 + 4 * lane;
;             float4 x4 = xo[u];
;             if constexpr (EPI == E_PLEGATE) {
;               x4.x += bflo(pv[u].x) * fsig(a.x * rs);
;               x4.y += bfhi(pv[u].x) * fsig(a.y * rs);
;               x4.z += bflo(pv[u].y) * fsig(a.z * rs);
;               x4.w += bfhi(pv[u].y) * fsig(a.w * rs);
;             } else {
;               const float sc = fabsf(scale);
;               x4.x += sc * a.x; x4.y += sc * a.y; x4.z += sc * a.z; x4.w += sc * a.w;
;             }
;             st_nt16(p.x + ro, x4);
;             if (xbout) {
;               uint2 o;
;               o.x = pack2(x4.x, x4.y);
;               o.y = pack2(x4.z, x4.w);
;               st_nt8(xbout + ro, o);
;             }
;             if (ssout) {
;               const float ssq = wsum(x4.x * x4.x + x4.y * x4.y + x4.z * x4.z + x4.w * x4.w, lane);
;               if (lane == 0) atomicAdd(ssout + grow, ssq);
;             }
.LBB0_1838:
	s_or_b64 exec, exec, s[20:21]
	ds_read_b128 v[16:19], v120 offset:12480
	v_lshl_add_u64 v[20:21], v[42:43], 1, s[6:7]
	s_waitcnt lgkmcnt(0)
	v_pk_fma_f32 v[12:13], v[16:17], 0.5, v[12:13] op_sel_hi:[1,0,1]
	v_pk_fma_f32 v[14:15], v[18:19], 0.5, v[14:15] op_sel_hi:[1,0,1]
	global_store_dwordx4 v[40:41], v[12:15], off
	v_cvt_pk_bf16_f32 v16, v12, v13
	v_cvt_pk_bf16_f32 v17, v14, v15
	v_pk_mul_f32 v[12:13], v[12:13], v[12:13]
	v_pk_mul_f32 v[14:15], v[14:15], v[14:15]
	v_add_f32_e32 v12, v12, v13
	v_add_f32_e32 v12, v12, v14
	v_add_f32_e32 v12, v12, v15
	global_store_dwordx2 v[20:21], v[16:17], off
	s_nop 0
	v_add_f32_dpp v12, v12, v12 row_ror:8 row_mask:0xf bank_mask:0xf bound_ctrl:1
	s_nop 1
	v_add_f32_dpp v12, v12, v12 row_ror:4 row_mask:0xf bank_mask:0xf bound_ctrl:1
	s_nop 1
	v_add_f32_dpp v12, v12, v12 row_ror:2 row_mask:0xf bank_mask:0xf bound_ctrl:1
	s_nop 1
	v_add_f32_dpp v12, v12, v12 row_ror:1 row_mask:0xf bank_mask:0xf bound_ctrl:1
	s_nop 0
	v_readlane_b32 s20, v12, 0
	v_readlane_b32 s23, v12, 16
	v_readlane_b32 s21, v12, 32
	v_readlane_b32 s22, v12, 48
	s_and_saveexec_b64 s[18:19], vcc
	s_cbranch_execz .LBB0_1840
	s_lshl_b64 s[16:17], s[16:17], 2
	v_mov_b32_e32 v12, s23
	s_add_u32 s16, s2, s16
	v_add_f32_e32 v12, s20, v12
	s_addc_u32 s17, s3, s17
	v_add_f32_e32 v12, s21, v12
	v_add_f32_e32 v14, s22, v12
	v_mov_b64_e32 v[12:13], s[16:17]
	global_atomic_add_f32 v[12:13], v14, off
.LBB0_1840:
	s_or_b64 exec, exec, s[18:19]
	ds_read_b128 v[12:15], v120 offset:13520
	v_lshl_add_u64 v[16:17], v[38:39], 1, s[6:7]
	s_waitcnt lgkmcnt(0)
	v_pk_fma_f32 v[8:9], v[12:13], 0.5, v[8:9] op_sel_hi:[1,0,1]
	v_pk_fma_f32 v[10:11], v[14:15], 0.5, v[10:11] op_sel_hi:[1,0,1]
	global_store_dwordx4 v[36:37], v[8:11], off
	v_cvt_pk_bf16_f32 v12, v8, v9
	v_cvt_pk_bf16_f32 v13, v10, v11
	v_pk_mul_f32 v[8:9], v[8:9], v[8:9]
	v_pk_mul_f32 v[10:11], v[10:11], v[10:11]
	v_add_f32_e32 v8, v8, v9
	v_add_f32_e32 v8, v8, v10
	v_add_f32_e32 v8, v8, v11
	global_store_dwordx2 v[16:17], v[12:13], off
	s_nop 0
	v_add_f32_dpp v8, v8, v8 row_ror:8 row_mask:0xf bank_mask:0xf bound_ctrl:1
	s_nop 1
	v_add_f32_dpp v8, v8, v8 row_ror:4 row_mask:0xf bank_mask:0xf bound_ctrl:1
	s_nop 1
	v_add_f32_dpp v8, v8, v8 row_ror:2 row_mask:0xf bank_mask:0xf bound_ctrl:1
	s_nop 1
	v_add_f32_dpp v8, v8, v8 row_ror:1 row_mask:0xf bank_mask:0xf bound_ctrl:1
	s_nop 0
	v_readlane_b32 s18, v8, 0
	v_readlane_b32 s21, v8, 16
	v_readlane_b32 s19, v8, 32
	v_readlane_b32 s20, v8, 48
	s_and_saveexec_b64 s[16:17], vcc
	s_cbranch_execz .LBB0_1842
	s_lshl_b64 s[14:15], s[14:15], 2
	v_mov_b32_e32 v8, s21
	s_add_u32 s14, s2, s14
	v_add_f32_e32 v8, s18, v8
	s_addc_u32 s15, s3, s15
	v_add_f32_e32 v8, s19, v8
	v_add_f32_e32 v10, s20, v8
	v_mov_b64_e32 v[8:9], s[14:15]
	global_atomic_add_f32 v[8:9], v10, off
.LBB0_1842:
	s_or_b64 exec, exec, s[16:17]
	ds_read_b128 v[8:11], v120 offset:14560
	v_lshl_add_u64 v[12:13], v[34:35], 1, s[6:7]
	s_waitcnt lgkmcnt(0)
	v_pk_fma_f32 v[4:5], v[8:9], 0.5, v[4:5] op_sel_hi:[1,0,1]
	v_pk_fma_f32 v[6:7], v[10:11], 0.5, v[6:7] op_sel_hi:[1,0,1]
	global_store_dwordx4 v[32:33], v[4:7], off
	v_cvt_pk_bf16_f32 v8, v4, v5
	v_cvt_pk_bf16_f32 v9, v6, v7
	v_pk_mul_f32 v[4:5], v[4:5], v[4:5]
	v_pk_mul_f32 v[6:7], v[6:7], v[6:7]
	v_add_f32_e32 v4, v4, v5
	v_add_f32_e32 v4, v4, v6
	v_add_f32_e32 v4, v4, v7
	global_store_dwordx2 v[12:13], v[8:9], off
	s_nop 0
	v_add_f32_dpp v4, v4, v4 row_ror:8 row_mask:0xf bank_mask:0xf bound_ctrl:1
	s_nop 1
	v_add_f32_dpp v4, v4, v4 row_ror:4 row_mask:0xf bank_mask:0xf bound_ctrl:1
	s_nop 1
	v_add_f32_dpp v4, v4, v4 row_ror:2 row_mask:0xf bank_mask:0xf bound_ctrl:1
	s_nop 1
	v_add_f32_dpp v4, v4, v4 row_ror:1 row_mask:0xf bank_mask:0xf bound_ctrl:1
	s_nop 0
	v_readlane_b32 s16, v4, 0
	v_readlane_b32 s19, v4, 16
	v_readlane_b32 s17, v4, 32
	v_readlane_b32 s18, v4, 48
	s_and_saveexec_b64 s[14:15], vcc
	s_cbranch_execz .LBB0_1844
	s_lshl_b64 s[12:13], s[12:13], 2
	v_mov_b32_e32 v4, s19
	s_add_u32 s12, s2, s12
	v_add_f32_e32 v4, s16, v4
	s_addc_u32 s13, s3, s13
	v_add_f32_e32 v4, s17, v4
	v_add_f32_e32 v6, s18, v4
	v_mov_b64_e32 v[4:5], s[12:13]
	global_atomic_add_f32 v[4:5], v6, off
.LBB0_1844:
	s_or_b64 exec, exec, s[14:15]
	ds_read_b128 v[4:7], v120 offset:15600
	v_lshl_add_u64 v[8:9], v[30:31], 1, s[6:7]
	s_waitcnt lgkmcnt(0)
	v_pk_fma_f32 v[0:1], v[4:5], 0.5, v[0:1] op_sel_hi:[1,0,1]
	v_pk_fma_f32 v[2:3], v[6:7], 0.5, v[2:3] op_sel_hi:[1,0,1]
	global_store_dwordx4 v[28:29], v[0:3], off
	v_cvt_pk_bf16_f32 v4, v0, v1
	v_cvt_pk_bf16_f32 v5, v2, v3
	v_pk_mul_f32 v[0:1], v[0:1], v[0:1]
	v_pk_mul_f32 v[2:3], v[2:3], v[2:3]
	v_add_f32_e32 v0, v0, v1
	v_add_f32_e32 v0, v0, v2
	v_add_f32_e32 v0, v0, v3
	global_store_dwordx2 v[8:9], v[4:5], off
	s_nop 0
	v_add_f32_dpp v0, v0, v0 row_ror:8 row_mask:0xf bank_mask:0xf bound_ctrl:1
	s_nop 1
	v_add_f32_dpp v0, v0, v0 row_ror:4 row_mask:0xf bank_mask:0xf bound_ctrl:1
	s_nop 1
	v_add_f32_dpp v0, v0, v0 row_ror:2 row_mask:0xf bank_mask:0xf bound_ctrl:1
	s_nop 1
	v_add_f32_dpp v0, v0, v0 row_ror:1 row_mask:0xf bank_mask:0xf bound_ctrl:1
	s_nop 0
	v_readlane_b32 s14, v0, 0
	v_readlane_b32 s17, v0, 16
	v_readlane_b32 s15, v0, 32
	v_readlane_b32 s16, v0, 48
	s_and_saveexec_b64 s[12:13], vcc
	s_cbranch_execz .LBB0_1773
	s_lshl_b64 s[10:11], s[10:11], 2
	v_mov_b32_e32 v0, s17
	s_add_u32 s10, s2, s10
	v_add_f32_e32 v0, s14, v0
	s_addc_u32 s11, s3, s11
	v_add_f32_e32 v0, s15, v0
	v_add_f32_e32 v2, s16, v0
	v_mov_b64_e32 v[0:1], s[10:11]
	global_atomic_add_f32 v[0:1], v2, off
	s_branch .LBB0_1773

; template <int EPI, int TS, bool VT>
; DEVI void gemm_epilogue(const Params& p, char* smem, f32x4 (&acc)[2][2][4][2], int m0, int n0, float scale, const float* ssin,
;                         float* ssout, u16* xbout, int wid, int lane, int wr, int wc, int fr, int fq) {
;     ...
;       float* tw = T + (wr * 64 + fq * 4) * TS + wc * 32 + fr;
; #pragma unroll
;       for (int m = 0; m < 4; ++m)
; #pragma unroll
;         for (int j = 0; j < 4; ++j)
; #pragma unroll
;           for (int v = 0; v < 4; ++v) tw[(m * 16 + j) * TS + (v >> 1) * 128 + (v & 1) * 16] = acc[ai][v >> 1][m][v & 1][j];
;     }
;     __syncthreads();
;     ...
;           } else if constexpr (EPI == E_BF16) {
;             const float4 a = *(const float4*)(Tr + 4 * lane);
;             uint2 o;
;             o.x = pack2(a.x, a.y);
;             o.y = pack2(a.z, a.w);
;             st_nt8((u16*)(wsb + OFF_PP) + (size_t)grow * 1024 + n0 + 4 * lane, o);
.LBB0_1851:
	s_lshl_b32 s14, s30, 6
	v_lshrrev_b32_e32 v128, 2, v128
	v_and_or_b32 v128, v128, 12, s14
	s_movk_i32 s14, 0x410
	v_readlane_b32 s12, v254, 13
	v_mul_lo_u32 v128, v128, s14
	s_lshl_b32 s14, s34, 7
	v_lshlrev_b32_e32 v129, 2, v129
	v_readlane_b32 s13, v254, 14
	v_add3_u32 v128, s14, v128, v129
	ds_write2_b32 v128, v92, v100 offset1:16
	ds_write2_b32 v128, v120, v124 offset0:128 offset1:144
	v_add_u32_e32 v92, 0x400, v128
	ds_write2_b32 v92, v93, v101 offset0:4 offset1:20
	ds_write2_b32 v92, v121, v125 offset0:132 offset1:148
	v_add_u32_e32 v93, 0x800, v128
	ds_write2_b32 v93, v94, v102 offset0:8 offset1:24
	ds_write2_b32 v93, v122, v126 offset0:136 offset1:152
	v_add_u32_e32 v94, 0xc00, v128
	ds_write2_b32 v94, v95, v103 offset0:12 offset1:28
	ds_write2_b32 v94, v123, v127 offset0:140 offset1:156
	v_add_u32_e32 v95, 0x4000, v128
	ds_write2_b32 v95, v80, v84 offset0:64 offset1:80
	ds_write2_b32 v95, v112, v116 offset0:192 offset1:208
	v_add_u32_e32 v80, 0x4400, v128
	ds_write2_b32 v80, v81, v85 offset0:68 offset1:84
	ds_write2_b32 v80, v113, v117 offset0:196 offset1:212
	v_add_u32_e32 v81, 0x4800, v128
	ds_write2_b32 v81, v82, v86 offset0:72 offset1:88
	ds_write2_b32 v81, v114, v118 offset0:200 offset1:216
	v_add_u32_e32 v82, 0x4c00, v128
	ds_write2_b32 v82, v83, v87 offset0:76 offset1:92
	ds_write2_b32 v82, v115, v119 offset0:204 offset1:220
	v_add_u32_e32 v83, 0x8000, v128
	ds_write2_b32 v83, v72, v76 offset0:128 offset1:144
	v_add_u32_e32 v72, 0x8400, v128
	ds_write2_b32 v72, v104, v108 offset1:16
	ds_write2_b32 v72, v73, v77 offset0:132 offset1:148
	v_add_u32_e32 v73, 0x8800, v128
	ds_write2_b32 v73, v105, v109 offset0:4 offset1:20
	ds_write2_b32 v73, v74, v78 offset0:136 offset1:152
	v_add_u32_e32 v74, 0x8c00, v128
	ds_write2_b32 v74, v106, v110 offset0:8 offset1:24
	ds_write2_b32 v74, v75, v79 offset0:140 offset1:156
	v_add_u32_e32 v75, 0x9000, v128
	v_add_u32_e32 v76, 0xc000, v128
	v_add_u32_e32 v77, 0xc400, v128
	v_add_u32_e32 v78, 0xc800, v128
	s_lshl_b32 s14, s11, 4
	v_and_b32_e32 v129, 0xfc, v130
	ds_write2_b32 v75, v107, v111 offset0:12 offset1:28
	ds_write2_b32 v76, v64, v68 offset0:192 offset1:208
	ds_write2_b32 v77, v88, v96 offset0:64 offset1:80
	ds_write2_b32 v77, v65, v69 offset0:196 offset1:212
	ds_write2_b32 v78, v89, v97 offset0:68 offset1:84
	ds_write2_b32 v78, v66, v70 offset0:200 offset1:216
	v_add_u32_e32 v70, 0xcc00, v128
	s_mulk_i32 s11, 0x4100
	ds_write2_b32 v70, v90, v98 offset0:72 offset1:88
	ds_write2_b32 v70, v67, v71 offset0:204 offset1:220
	v_add_u32_e32 v71, 0xd000, v128
	v_lshl_add_u32 v79, v129, 2, s11
	s_add_i32 s10, s14, s10
	s_lshl_b64 s[8:9], s[8:9], 1
	ds_write2_b32 v71, v91, v99 offset0:76 offset1:92
	s_waitcnt vmcnt(0) lgkmcnt(0)
	s_barrier
	ds_read_b128 v[66:69], v79
	s_add_u32 s8, s12, s8
	s_addc_u32 s9, s13, s9
	v_lshlrev_b32_e32 v148, 1, v129
	v_lshl_add_u64 v[64:65], s[8:9], 0, v[148:149]
	s_mov_b64 s[8:9], 0x1495ee00
	s_ashr_i32 s11, s10, 31
	v_lshl_add_u64 v[64:65], v[64:65], 0, s[8:9]
	s_lshl_b64 s[8:9], s[10:11], 11
	s_waitcnt lgkmcnt(0)
	v_cvt_pk_bf16_f32 v66, v66, v67
	v_cvt_pk_bf16_f32 v67, v68, v69
	v_lshl_add_u64 v[68:69], v[64:65], 0, s[8:9]
	global_store_dwordx2 v[68:69], v[66:67], off
	ds_read_b128 v[66:69], v79 offset:1040
	s_or_b32 s8, s10, 1
	s_ashr_i32 s9, s8, 31
	s_lshl_b64 s[8:9], s[8:9], 11
	s_andn2_b64 vcc, exec, s[6:7]
	s_waitcnt lgkmcnt(0)
	v_cvt_pk_bf16_f32 v66, v66, v67
	v_cvt_pk_bf16_f32 v67, v68, v69
	v_lshl_add_u64 v[68:69], v[64:65], 0, s[8:9]
	global_store_dwordx2 v[68:69], v[66:67], off
	ds_read_b128 v[66:69], v79 offset:2080
	s_or_b32 s8, s10, 2
	s_ashr_i32 s9, s8, 31
	s_lshl_b64 s[8:9], s[8:9], 11
	s_waitcnt lgkmcnt(0)
	v_cvt_pk_bf16_f32 v66, v66, v67
	v_cvt_pk_bf16_f32 v67, v68, v69
	v_lshl_add_u64 v[68:69], v[64:65], 0, s[8:9]
	global_store_dwordx2 v[68:69], v[66:67], off
	ds_read_b128 v[66:69], v79 offset:3120
	s_or_b32 s8, s10, 3
	s_ashr_i32 s9, s8, 31
	s_lshl_b64 s[8:9], s[8:9], 11
	s_waitcnt lgkmcnt(0)
	v_cvt_pk_bf16_f32 v66, v66, v67
	v_cvt_pk_bf16_f32 v67, v68, v69
	v_lshl_add_u64 v[68:69], v[64:65], 0, s[8:9]
	global_store_dwordx2 v[68:69], v[66:67], off
	ds_read_b128 v[66:69], v79 offset:4160
	s_or_b32 s8, s10, 4
	s_ashr_i32 s9, s8, 31
	s_lshl_b64 s[8:9], s[8:9], 11
	s_waitcnt lgkmcnt(0)
	v_cvt_pk_bf16_f32 v66, v66, v67
	v_cvt_pk_bf16_f32 v67, v68, v69
	v_lshl_add_u64 v[68:69], v[64:65], 0, s[8:9]
	global_store_dwordx2 v[68:69], v[66:67], off
	ds_read_b128 v[66:69], v79 offset:5200
	s_or_b32 s8, s10, 5
	s_ashr_i32 s9, s8, 31
	s_lshl_b64 s[8:9], s[8:9], 11
	s_waitcnt lgkmcnt(0)
	v_cvt_pk_bf16_f32 v66, v66, v67
	v_cvt_pk_bf16_f32 v67, v68, v69
	v_lshl_add_u64 v[68:69], v[64:65], 0, s[8:9]
	global_store_dwordx2 v[68:69], v[66:67], off
	ds_read_b128 v[66:69], v79 offset:6240
	s_or_b32 s8, s10, 6
	s_ashr_i32 s9, s8, 31
	s_lshl_b64 s[8:9], s[8:9], 11
	s_waitcnt lgkmcnt(0)
	v_cvt_pk_bf16_f32 v66, v66, v67
	v_cvt_pk_bf16_f32 v67, v68, v69
	v_lshl_add_u64 v[68:69], v[64:65], 0, s[8:9]
	global_store_dwordx2 v[68:69], v[66:67], off
	ds_read_b128 v[66:69], v79 offset:7280
	s_or_b32 s8, s10, 7
	s_ashr_i32 s9, s8, 31
	s_lshl_b64 s[8:9], s[8:9], 11
	s_waitcnt lgkmcnt(0)
	v_cvt_pk_bf16_f32 v66, v66, v67
	v_cvt_pk_bf16_f32 v67, v68, v69
	v_lshl_add_u64 v[68:69], v[64:65], 0, s[8:9]
	global_store_dwordx2 v[68:69], v[66:67], off
	ds_read_b128 v[66:69], v79 offset:8320
	s_or_b32 s8, s10, 8
	s_ashr_i32 s9, s8, 31
	s_lshl_b64 s[8:9], s[8:9], 11
	s_waitcnt lgkmcnt(0)
	v_cvt_pk_bf16_f32 v66, v66, v67
	v_cvt_pk_bf16_f32 v67, v68, v69
	v_lshl_add_u64 v[68:69], v[64:65], 0, s[8:9]
	global_store_dwordx2 v[68:69], v[66:67], off
	ds_read_b128 v[66:69], v79 offset:9360
	s_or_b32 s8, s10, 9
	s_ashr_i32 s9, s8, 31
	s_lshl_b64 s[8:9], s[8:9], 11
	s_waitcnt lgkmcnt(0)
; template <int EPI, int TS, bool VT>
; DEVI void gemm_epilogue(const Params& p, char* smem, f32x4 (&acc)[2][2][4][2], int m0, int n0, float scale, const float* ssin,
;                         float* ssout, u16* xbout, int wid, int lane, int wr, int wc, int fr, int fq) {
;     ...
;       float* tw = T + (wr * 64 + fq * 4) * TS + wc * 32 + fr;
; #pragma unroll
;       for (int m = 0; m < 4; ++m)
; #pragma unroll
;         for (int j = 0; j < 4; ++j)
; #pragma unroll
;           for (int v = 0; v < 4; ++v) tw[(m * 16 + j) * TS + (v >> 1) * 128 + (v & 1) * 16] = acc[ai][v >> 1][m][v & 1][j];
;     }
;     __syncthreads();
;     ...
;           } else if constexpr (EPI == E_BF16) {
;             const float4 a = *(const float4*)(Tr + 4 * lane);
;             uint2 o;
;             o.x = pack2(a.x, a.y);
;             o.y = pack2(a.z, a.w);
;             st_nt8((u16*)(wsb + OFF_PP) + (size_t)grow * 1024 + n0 + 4 * lane, o);
	v_cvt_pk_bf16_f32 v66, v66, v67
	v_cvt_pk_bf16_f32 v67, v68, v69
	v_lshl_add_u64 v[68:69], v[64:65], 0, s[8:9]
	global_store_dwordx2 v[68:69], v[66:67], off
	ds_read_b128 v[66:69], v79 offset:10400
	s_or_b32 s8, s10, 10
	s_ashr_i32 s9, s8, 31
	s_lshl_b64 s[8:9], s[8:9], 11
	s_waitcnt lgkmcnt(0)
	v_cvt_pk_bf16_f32 v66, v66, v67
	v_cvt_pk_bf16_f32 v67, v68, v69
	v_lshl_add_u64 v[68:69], v[64:65], 0, s[8:9]
	global_store_dwordx2 v[68:69], v[66:67], off
	ds_read_b128 v[66:69], v79 offset:11440
	s_or_b32 s8, s10, 11
	s_ashr_i32 s9, s8, 31
	s_lshl_b64 s[8:9], s[8:9], 11
	s_waitcnt lgkmcnt(0)
	v_cvt_pk_bf16_f32 v66, v66, v67
	v_cvt_pk_bf16_f32 v67, v68, v69
	v_lshl_add_u64 v[68:69], v[64:65], 0, s[8:9]
	global_store_dwordx2 v[68:69], v[66:67], off
	ds_read_b128 v[66:69], v79 offset:12480
	s_or_b32 s8, s10, 12
	s_ashr_i32 s9, s8, 31
	s_lshl_b64 s[8:9], s[8:9], 11
	s_waitcnt lgkmcnt(0)
	v_cvt_pk_bf16_f32 v66, v66, v67
	v_cvt_pk_bf16_f32 v67, v68, v69
	v_lshl_add_u64 v[68:69], v[64:65], 0, s[8:9]
	global_store_dwordx2 v[68:69], v[66:67], off
	ds_read_b128 v[66:69], v79 offset:13520
	s_or_b32 s8, s10, 13
	s_ashr_i32 s9, s8, 31
	s_lshl_b64 s[8:9], s[8:9], 11
	s_waitcnt lgkmcnt(0)
	v_cvt_pk_bf16_f32 v66, v66, v67
	v_cvt_pk_bf16_f32 v67, v68, v69
	v_lshl_add_u64 v[68:69], v[64:65], 0, s[8:9]
	global_store_dwordx2 v[68:69], v[66:67], off
	ds_read_b128 v[66:69], v79 offset:14560
	s_or_b32 s8, s10, 14
	s_ashr_i32 s9, s8, 31
	s_lshl_b64 s[8:9], s[8:9], 11
	s_waitcnt lgkmcnt(0)
	v_cvt_pk_bf16_f32 v66, v66, v67
	v_cvt_pk_bf16_f32 v67, v68, v69
	v_lshl_add_u64 v[68:69], v[64:65], 0, s[8:9]
	global_store_dwordx2 v[68:69], v[66:67], off
	ds_read_b128 v[66:69], v79 offset:15600
	s_or_b32 s8, s10, 15
	s_ashr_i32 s9, s8, 31
	s_lshl_b64 s[8:9], s[8:9], 11
	s_waitcnt lgkmcnt(0)
	v_cvt_pk_bf16_f32 v66, v66, v67
	v_cvt_pk_bf16_f32 v67, v68, v69
	v_lshl_add_u64 v[68:69], v[64:65], 0, s[8:9]
	global_store_dwordx2 v[68:69], v[66:67], off
	s_waitcnt lgkmcnt(0)
	s_barrier
	ds_write2_b32 v128, v24, v28 offset1:16
	ds_write2_b32 v128, v56, v60 offset0:128 offset1:144
	ds_write2_b32 v92, v25, v29 offset0:4 offset1:20
	ds_write2_b32 v92, v57, v61 offset0:132 offset1:148
	ds_write2_b32 v93, v26, v30 offset0:8 offset1:24
	ds_write2_b32 v93, v58, v62 offset0:136 offset1:152
	ds_write2_b32 v94, v27, v31 offset0:12 offset1:28
	ds_write2_b32 v94, v59, v63 offset0:140 offset1:156
	ds_write2_b32 v95, v16, v20 offset0:64 offset1:80
	ds_write2_b32 v95, v48, v52 offset0:192 offset1:208
	ds_write2_b32 v80, v17, v21 offset0:68 offset1:84
	ds_write2_b32 v80, v49, v53 offset0:196 offset1:212
	ds_write2_b32 v81, v18, v22 offset0:72 offset1:88
	ds_write2_b32 v81, v50, v54 offset0:200 offset1:216
	ds_write2_b32 v82, v19, v23 offset0:76 offset1:92
	ds_write2_b32 v82, v51, v55 offset0:204 offset1:220
	ds_write2_b32 v83, v8, v12 offset0:128 offset1:144
	ds_write2_b32 v72, v40, v44 offset1:16
	ds_write2_b32 v72, v9, v13 offset0:132 offset1:148
	ds_write2_b32 v73, v41, v45 offset0:4 offset1:20
	ds_write2_b32 v73, v10, v14 offset0:136 offset1:152
	ds_write2_b32 v74, v42, v46 offset0:8 offset1:24
	ds_write2_b32 v74, v11, v15 offset0:140 offset1:156
	ds_write2_b32 v75, v43, v47 offset0:12 offset1:28
	ds_write2_b32 v76, v0, v4 offset0:192 offset1:208
	ds_write2_b32 v77, v32, v36 offset0:64 offset1:80
	ds_write2_b32 v77, v1, v5 offset0:196 offset1:212
	ds_write2_b32 v78, v33, v37 offset0:68 offset1:84
	ds_write2_b32 v78, v2, v6 offset0:200 offset1:216
	ds_write2_b32 v70, v34, v38 offset0:72 offset1:88
	ds_write2_b32 v70, v3, v7 offset0:204 offset1:220
	ds_write2_b32 v71, v35, v39 offset0:76 offset1:92
	s_waitcnt lgkmcnt(0)
	s_barrier
; template <int EPI, int TS, bool VT>
; DEVI void gemm_epilogue(const Params& p, char* smem, f32x4 (&acc)[2][2][4][2], int m0, int n0, float scale, const float* ssin,
;                         float* ssout, u16* xbout, int wid, int lane, int wr, int wc, int fr, int fq) {
;     ...
;           } else if constexpr (EPI == E_BF16) {
;             const float4 a = *(const float4*)(Tr + 4 * lane);
;             uint2 o;
;             o.x = pack2(a.x, a.y);
;             o.y = pack2(a.z, a.w);
;             st_nt8((u16*)(wsb + OFF_PP) + (size_t)grow * 1024 + n0 + 4 * lane, o);
	ds_read_b128 v[0:3], v79
	s_add_i32 s8, s10, 0x80
	s_ashr_i32 s9, s8, 31
	s_lshl_b64 s[8:9], s[8:9], 11
	s_waitcnt lgkmcnt(0)
	v_cvt_pk_bf16_f32 v0, v0, v1
	v_cvt_pk_bf16_f32 v1, v2, v3
	v_lshl_add_u64 v[2:3], v[64:65], 0, s[8:9]
	global_store_dwordx2 v[2:3], v[0:1], off
	ds_read_b128 v[0:3], v79 offset:1040
	s_add_i32 s8, s10, 0x81
	s_ashr_i32 s9, s8, 31
	s_lshl_b64 s[8:9], s[8:9], 11
	s_waitcnt lgkmcnt(0)
	v_cvt_pk_bf16_f32 v0, v0, v1
	v_cvt_pk_bf16_f32 v1, v2, v3
	v_lshl_add_u64 v[2:3], v[64:65], 0, s[8:9]
	global_store_dwordx2 v[2:3], v[0:1], off
	ds_read_b128 v[0:3], v79 offset:2080
	s_add_i32 s8, s10, 0x82
	s_ashr_i32 s9, s8, 31
	s_lshl_b64 s[8:9], s[8:9], 11
	s_waitcnt lgkmcnt(0)
	v_cvt_pk_bf16_f32 v0, v0, v1
	v_cvt_pk_bf16_f32 v1, v2, v3
	v_lshl_add_u64 v[2:3], v[64:65], 0, s[8:9]
	global_store_dwordx2 v[2:3], v[0:1], off
	ds_read_b128 v[0:3], v79 offset:3120
	s_add_i32 s8, s10, 0x83
	s_ashr_i32 s9, s8, 31
	s_lshl_b64 s[8:9], s[8:9], 11
	s_waitcnt lgkmcnt(0)
	v_cvt_pk_bf16_f32 v0, v0, v1
	v_cvt_pk_bf16_f32 v1, v2, v3
	v_lshl_add_u64 v[2:3], v[64:65], 0, s[8:9]
	global_store_dwordx2 v[2:3], v[0:1], off
	ds_read_b128 v[0:3], v79 offset:4160
	s_add_i32 s8, s10, 0x84
	s_ashr_i32 s9, s8, 31
	s_lshl_b64 s[8:9], s[8:9], 11
	s_waitcnt lgkmcnt(0)
	v_cvt_pk_bf16_f32 v0, v0, v1
	v_cvt_pk_bf16_f32 v1, v2, v3
	v_lshl_add_u64 v[2:3], v[64:65], 0, s[8:9]
	global_store_dwordx2 v[2:3], v[0:1], off
	ds_read_b128 v[0:3], v79 offset:5200
	s_add_i32 s8, s10, 0x85
	s_ashr_i32 s9, s8, 31
	s_lshl_b64 s[8:9], s[8:9], 11
	s_waitcnt lgkmcnt(0)
	v_cvt_pk_bf16_f32 v0, v0, v1
	v_cvt_pk_bf16_f32 v1, v2, v3
	v_lshl_add_u64 v[2:3], v[64:65], 0, s[8:9]
	global_store_dwordx2 v[2:3], v[0:1], off
	ds_read_b128 v[0:3], v79 offset:6240
	s_add_i32 s8, s10, 0x86
	s_ashr_i32 s9, s8, 31
	s_lshl_b64 s[8:9], s[8:9], 11
	s_waitcnt lgkmcnt(0)
	v_cvt_pk_bf16_f32 v0, v0, v1
	v_cvt_pk_bf16_f32 v1, v2, v3
	v_lshl_add_u64 v[2:3], v[64:65], 0, s[8:9]
	global_store_dwordx2 v[2:3], v[0:1], off
	ds_read_b128 v[0:3], v79 offset:7280
	s_add_i32 s8, s10, 0x87
	s_ashr_i32 s9, s8, 31
	s_lshl_b64 s[8:9], s[8:9], 11
	s_waitcnt lgkmcnt(0)
	v_cvt_pk_bf16_f32 v0, v0, v1
	v_cvt_pk_bf16_f32 v1, v2, v3
	v_lshl_add_u64 v[2:3], v[64:65], 0, s[8:9]
	global_store_dwordx2 v[2:3], v[0:1], off
	ds_read_b128 v[0:3], v79 offset:8320
	s_add_i32 s8, s10, 0x88
	s_ashr_i32 s9, s8, 31
	s_lshl_b64 s[8:9], s[8:9], 11
	s_waitcnt lgkmcnt(0)
	v_cvt_pk_bf16_f32 v0, v0, v1
	v_cvt_pk_bf16_f32 v1, v2, v3
	v_lshl_add_u64 v[2:3], v[64:65], 0, s[8:9]
	global_store_dwordx2 v[2:3], v[0:1], off
	ds_read_b128 v[0:3], v79 offset:9360
	s_add_i32 s8, s10, 0x89
	s_ashr_i32 s9, s8, 31
	s_lshl_b64 s[8:9], s[8:9], 11
	s_waitcnt lgkmcnt(0)
	v_cvt_pk_bf16_f32 v0, v0, v1
	v_cvt_pk_bf16_f32 v1, v2, v3
	v_lshl_add_u64 v[2:3], v[64:65], 0, s[8:9]
	global_store_dwordx2 v[2:3], v[0:1], off
	ds_read_b128 v[0:3], v79 offset:10400
	s_add_i32 s8, s10, 0x8a
	s_ashr_i32 s9, s8, 31
	s_lshl_b64 s[8:9], s[8:9], 11
	s_waitcnt lgkmcnt(0)
	v_cvt_pk_bf16_f32 v0, v0, v1
	v_cvt_pk_bf16_f32 v1, v2, v3
	v_lshl_add_u64 v[2:3], v[64:65], 0, s[8:9]
	global_store_dwordx2 v[2:3], v[0:1], off
	ds_read_b128 v[0:3], v79 offset:11440
	s_add_i32 s8, s10, 0x8b
	s_ashr_i32 s9, s8, 31
	s_lshl_b64 s[8:9], s[8:9], 11
	s_waitcnt lgkmcnt(0)
	v_cvt_pk_bf16_f32 v0, v0, v1
	v_cvt_pk_bf16_f32 v1, v2, v3
	v_lshl_add_u64 v[2:3], v[64:65], 0, s[8:9]
	global_store_dwordx2 v[2:3], v[0:1], off
	ds_read_b128 v[0:3], v79 offset:12480
	s_add_i32 s8, s10, 0x8c
	s_ashr_i32 s9, s8, 31
	s_lshl_b64 s[8:9], s[8:9], 11
	s_waitcnt lgkmcnt(0)
	v_cvt_pk_bf16_f32 v0, v0, v1
	v_cvt_pk_bf16_f32 v1, v2, v3
	v_lshl_add_u64 v[2:3], v[64:65], 0, s[8:9]
	global_store_dwordx2 v[2:3], v[0:1], off
	ds_read_b128 v[0:3], v79 offset:13520
	s_add_i32 s8, s10, 0x8d
	s_ashr_i32 s9, s8, 31
	s_lshl_b64 s[8:9], s[8:9], 11
	s_waitcnt lgkmcnt(0)
	v_cvt_pk_bf16_f32 v0, v0, v1
	v_cvt_pk_bf16_f32 v1, v2, v3
	v_lshl_add_u64 v[2:3], v[64:65], 0, s[8:9]
	global_store_dwordx2 v[2:3], v[0:1], off
	ds_read_b128 v[0:3], v79 offset:14560
	s_add_i32 s8, s10, 0x8e
	s_ashr_i32 s9, s8, 31
	s_lshl_b64 s[8:9], s[8:9], 11
	s_waitcnt lgkmcnt(0)
	v_cvt_pk_bf16_f32 v0, v0, v1
	v_cvt_pk_bf16_f32 v1, v2, v3
	v_lshl_add_u64 v[2:3], v[64:65], 0, s[8:9]
	global_store_dwordx2 v[2:3], v[0:1], off
	ds_read_b128 v[0:3], v79 offset:15600
	s_add_i32 s8, s10, 0x8f
	s_ashr_i32 s9, s8, 31
	s_lshl_b64 s[8:9], s[8:9], 11
	s_waitcnt lgkmcnt(0)
	v_cvt_pk_bf16_f32 v0, v0, v1
	v_cvt_pk_bf16_f32 v1, v2, v3
	v_lshl_add_u64 v[2:3], v[64:65], 0, s[8:9]
	s_mov_b32 s9, s22
	s_mov_b32 s8, s23
	global_store_dwordx2 v[2:3], v[0:1], off
	s_waitcnt lgkmcnt(0)
	s_barrier
	s_cbranch_vccz .LBB0_1858

; template <int EPI, int TS, bool VT>
; DEVI void gemm_epilogue(const Params& p, char* smem, f32x4 (&acc)[2][2][4][2], int m0, int n0, float scale, const float* ssin,
;                         float* ssout, u16* xbout, int wid, int lane, int wr, int wc, int fr, int fq) {
;     ...
;       float* tw = T + (wr * 64 + fq * 4) * TS + wc * 32 + fr;
; #pragma unroll
;       for (int m = 0; m < 4; ++m)
; #pragma unroll
;         for (int j = 0; j < 4; ++j)
; #pragma unroll
;           for (int v = 0; v < 4; ++v) tw[(m * 16 + j) * TS + (v >> 1) * 128 + (v & 1) * 16] = acc[ai][v >> 1][m][v & 1][j];
;     }
;     __syncthreads();
.LBB0_1886:
	v_lshrrev_b32_e32 v128, 2, v132
	v_and_or_b32 v128, v128, 12, s66
	s_movk_i32 s20, 0x410
	v_mul_lo_u32 v128, v128, s20
	s_lshl_b32 s20, s65, 7
	v_lshlrev_b32_e32 v129, 2, v143
	v_readlane_b32 s18, v254, 13
	v_add3_u32 v144, s20, v128, v129
	s_lshl_b32 s20, s5, 4
	v_readlane_b32 s19, v254, 14
	s_add_i32 s20, s20, s4
	v_add_u32_e32 v145, 0x400, v144
	v_add_u32_e32 v146, 0x800, v144
	v_add_u32_e32 v147, 0xc00, v144
	v_add_u32_e32 v148, 0x4000, v144
	v_add_u32_e32 v152, 0x4400, v144
	v_add_u32_e32 v153, 0x4800, v144
	v_add_u32_e32 v154, 0x4c00, v144
	v_add_u32_e32 v155, 0x8000, v144
	v_add_u32_e32 v156, 0x8400, v144
	v_add_u32_e32 v157, 0x8800, v144
	v_add_u32_e32 v158, 0x8c00, v144
	v_add_u32_e32 v160, 0xc000, v144
	ds_write2_b32 v144, v92, v100 offset1:16
	ds_write2_b32 v144, v120, v124 offset0:128 offset1:144
	ds_write2_b32 v145, v93, v101 offset0:4 offset1:20
	ds_write2_b32 v145, v121, v125 offset0:132 offset1:148
	ds_write2_b32 v146, v94, v102 offset0:8 offset1:24
	ds_write2_b32 v146, v122, v126 offset0:136 offset1:152
	ds_write2_b32 v147, v95, v103 offset0:12 offset1:28
	ds_write2_b32 v147, v123, v127 offset0:140 offset1:156
	ds_write2_b32 v148, v80, v84 offset0:64 offset1:80
	ds_write2_b32 v148, v112, v116 offset0:192 offset1:208
	ds_write2_b32 v152, v81, v85 offset0:68 offset1:84
	ds_write2_b32 v152, v113, v117 offset0:196 offset1:212
	ds_write2_b32 v153, v82, v86 offset0:72 offset1:88
	ds_write2_b32 v153, v114, v118 offset0:200 offset1:216
	ds_write2_b32 v154, v83, v87 offset0:76 offset1:92
	ds_write2_b32 v154, v115, v119 offset0:204 offset1:220
	ds_write2_b32 v155, v72, v76 offset0:128 offset1:144
	ds_write2_b32 v156, v104, v108 offset1:16
	ds_write2_b32 v156, v73, v77 offset0:132 offset1:148
	ds_write2_b32 v157, v105, v109 offset0:4 offset1:20
	ds_write2_b32 v157, v74, v78 offset0:136 offset1:152
	ds_write2_b32 v158, v106, v110 offset0:8 offset1:24
	ds_write2_b32 v158, v75, v79 offset0:140 offset1:156
	v_add_u32_e32 v159, 0x9000, v144
	ds_write2_b32 v160, v64, v68 offset0:192 offset1:208
	v_add_u32_e32 v161, 0xc400, v144
	v_or_b32_e32 v64, s20, v143
	ds_write2_b32 v159, v107, v111 offset0:12 offset1:28
	ds_write2_b32 v161, v88, v96 offset0:64 offset1:80
	ds_write2_b32 v161, v65, v69 offset0:196 offset1:212
	v_ashrrev_i32_e32 v65, 31, v64
	v_add_u32_e32 v162, 0xc800, v144
	v_add_u32_e32 v163, 0xcc00, v144
	v_add_u32_e32 v164, 0xd000, v144
	v_lshl_add_u64 v[64:65], v[64:65], 2, s[2:3]
	ds_write2_b32 v162, v89, v97 offset0:68 offset1:84
	ds_write2_b32 v162, v66, v70 offset0:200 offset1:216
	ds_write2_b32 v163, v90, v98 offset0:72 offset1:88
	ds_write2_b32 v163, v67, v71 offset0:204 offset1:220
	ds_write2_b32 v164, v91, v99 offset0:76 offset1:92
	s_waitcnt vmcnt(0) lgkmcnt(0)
	s_barrier
; template <int EPI, int TS, bool VT>
; DEVI void gemm_epilogue(const Params& p, char* smem, f32x4 (&acc)[2][2][4][2], int m0, int n0, float scale, const float* ssin,
;                         float* ssout, u16* xbout, int wid, int lane, int wr, int wc, int fr, int fq) {
;     ...
;       float rsv = 1.f;
;       if constexpr (EPI == E_PLEGATE || EPI == E_F32 || EPI == E_SWIGLU || EPI == E_GLAIN)
;         rsv = rsqrtf(ssin[g0 + (lane & 15)] * (1.f / 1024.f) + EPS);
;       if constexpr (EPI == E_QROPE) rsv = rsqrtf(ssin[g0 + (lane & 15)] * (1.f / 384.f) + EPS);
;       if constexpr (EPI == E_KV) rsv = rsqrtf(ssin[g0 + (lane & 15)] * (1.f / 256.f) + EPS);
;       for (int i0 = 0; i0 < 16; i0 += 8) {
;         float4 xo[8];
;         uint2 pv[8];
;         if constexpr (EPI == E_RESID || EPI == E_PLEGATE) {
; #pragma unroll
;           for (int u = 0; u < 8; ++u) {
;             const size_t ro = (size_t)(g0 + i0 + u) * 1024 + n0 + 4 * lane;
;             const int gr = g0 + i0 + u;
;             const float* xs = p.x + ro;
;             if (scale < 0.f)
;               xs = (gr < MP ? p.x_prompt + ro : p.x_sample + (ro - (size_t)MP * 1024));
;             { const f32x4 t_ = __builtin_nontemporal_load((const f32x4*)xs); xo[u] = make_float4(t_[0], t_[1], t_[2], t_[3]); }
;             if constexpr (EPI == E_PLEGATE) {
;               const unsigned long long t2_ = __builtin_nontemporal_load((const unsigned long long*)((const u16*)(wsb + OFF_PP) + ro));
;               pv[u] = make_uint2((unsigned)t2_, (unsigned)(t2_ >> 32));
;             }
;           }
;         }
; #pragma unroll
;         for (int u = 0; u < 8; ++u) {
;           const int i = i0 + u;
;           const int grow = g0 + i;
;           const float* Tr = T + (r0 + i) * TS;
;           const float rs = __int_as_float(__builtin_amdgcn_readlane(__float_as_int(rsv), i));
;           if constexpr (EPI == E_RESID || EPI == E_PLEGATE) {
;             const float4 a = *(const float4*)(Tr + 4 * lane);
;             const size_t ro = (size_t)grow * 1024 + n0 + 4 * lane;
;             float4 x4 = xo[u];
;             if constexpr (EPI == E_PLEGATE) {
;               x4.x += bflo(pv[u].x) * fsig(a.x * rs);
;               x4.y += bfhi(pv[u].x) * fsig(a.y * rs);
;               x4.z += bflo(pv[u].y) * fsig(a.z * rs);
;               x4.w += bfhi(pv[u].y) * fsig(a.w * rs);
;             } else {
	global_load_dword v64, v[64:65], off
	s_add_u32 s18, s18, 0x1495ee00
	v_and_b32_e32 v166, 63, v132
	s_addc_u32 s19, s19, 0
	s_ashr_i32 s21, s20, 31
	v_lshl_or_b32 v128, v166, 2, s0
	v_mov_b32_e32 v129, s1
	s_lshl_b64 s[0:1], s[20:21], 10
	v_lshl_add_u64 v[140:141], s[0:1], 0, v[128:129]
	v_lshl_add_u64 v[178:179], v[140:141], 2, s[38:39]
	global_load_dwordx4 v[92:95], v[178:179], off
	s_or_b32 s68, s20, 1
	s_ashr_i32 s69, s68, 31
	s_or_b32 s66, s20, 2
	s_lshl_b64 s[0:1], s[68:69], 10
	s_ashr_i32 s67, s66, 31
	s_or_b32 s64, s20, 3
	v_lshl_add_u64 v[134:135], s[0:1], 0, v[128:129]
	s_lshl_b64 s[0:1], s[66:67], 10
	s_ashr_i32 s65, s64, 31
	s_or_b32 s62, s20, 4
	v_lshl_add_u64 v[126:127], s[0:1], 0, v[128:129]
	s_lshl_b64 s[0:1], s[64:65], 10
	s_ashr_i32 s63, s62, 31
	s_or_b32 s34, s20, 5
	v_lshl_add_u64 v[120:121], s[0:1], 0, v[128:129]
	s_lshl_b64 s[0:1], s[62:63], 10
	s_ashr_i32 s35, s34, 31
	s_or_b32 s30, s20, 6
	v_lshl_add_u64 v[114:115], s[0:1], 0, v[128:129]
	s_lshl_b64 s[0:1], s[34:35], 10
	s_ashr_i32 s31, s30, 31
	s_or_b32 s22, s20, 7
	v_lshl_add_u64 v[108:109], s[0:1], 0, v[128:129]
	s_lshl_b64 s[0:1], s[30:31], 10
	s_ashr_i32 s23, s22, 31
	v_lshl_add_u64 v[102:103], s[0:1], 0, v[128:129]
	s_lshl_b64 s[0:1], s[22:23], 10
	v_lshl_add_u64 v[96:97], s[0:1], 0, v[128:129]
	v_lshl_add_u64 v[100:101], v[96:97], 1, s[18:19]
	v_lshl_add_u64 v[136:137], v[134:135], 2, s[38:39]
	v_lshl_add_u64 v[130:131], v[126:127], 2, s[38:39]
	v_lshl_add_u64 v[122:123], v[120:121], 2, s[38:39]
	v_lshl_add_u64 v[116:117], v[114:115], 2, s[38:39]
	global_load_dwordx2 v[100:101], v[100:101], off
	v_lshl_add_u64 v[110:111], v[108:109], 2, s[38:39]
	v_lshl_add_u64 v[104:105], v[102:103], 2, s[38:39]
	v_lshl_add_u64 v[98:99], v[96:97], 2, s[38:39]
	global_load_dwordx4 v[88:91], v[136:137], off
	global_load_dwordx4 v[84:87], v[130:131], off
	global_load_dwordx4 v[80:83], v[122:123], off
	global_load_dwordx4 v[76:79], v[116:117], off
	global_load_dwordx4 v[72:75], v[110:111], off
	global_load_dwordx4 v[68:71], v[104:105], off
	s_mulk_i32 s5, 0x4100
	v_lshl_add_u32 v142, v166, 4, s5
	ds_read_b128 v[174:177], v142
	s_waitcnt vmcnt(0) lgkmcnt(0)
	v_fmamk_f32 v64, v64, 0x3a800000, v150
	v_cmp_gt_f32_e32 vcc, s29, v64
	v_mul_f32_e32 v65, 0x4b800000, v64
	s_nop 0
	v_cndmask_b32_e32 v64, v64, v65, vcc
	v_rsq_f32_e32 v64, v64
	s_nop 0
	v_mul_f32_e32 v65, 0x45800000, v64
	v_cndmask_b32_e32 v165, v64, v65, vcc
	v_lshl_add_u64 v[64:65], v[140:141], 1, s[18:19]
	global_load_dwordx2 v[180:181], v[64:65], off
	v_lshl_add_u64 v[64:65], v[134:135], 1, s[18:19]
	global_load_dwordx2 v[138:139], v[64:65], off
	v_lshl_add_u64 v[64:65], v[126:127], 1, s[18:19]
	global_load_dwordx2 v[132:133], v[64:65], off
	v_lshl_add_u64 v[64:65], v[120:121], 1, s[18:19]
	global_load_dwordx2 v[124:125], v[64:65], off
	v_lshl_add_u64 v[64:65], v[114:115], 1, s[18:19]
	global_load_dwordx2 v[118:119], v[64:65], off
	v_lshl_add_u64 v[64:65], v[108:109], 1, s[18:19]
	global_load_dwordx2 v[112:113], v[64:65], off
	v_lshl_add_u64 v[64:65], v[102:103], 1, s[18:19]
	global_load_dwordx2 v[106:107], v[64:65], off
	v_readlane_b32 s0, v165, 0
	global_load_dwordx4 v[64:67], v[98:99], off
	s_andn2_b64 vcc, exec, s[14:15]
	v_mul_f32_e32 v174, s0, v174
	v_mul_f32_e32 v174, 0xbfb8aa3b, v174
	v_exp_f32_e32 v174, v174
	s_waitcnt vmcnt(0) lgkmcnt(0)
	v_lshlrev_b32_e32 v167, 16, v180
	v_add_f32_e32 v174, 1.0, v174
	v_rcp_f32_e32 v174, v174
	s_nop 0
	v_fma_f32 v92, v174, v167, v92
	v_mul_f32_e32 v174, s0, v175
	v_mul_f32_e32 v174, 0xbfb8aa3b, v174
	v_exp_f32_e32 v174, v174
	v_and_b32_e32 v167, 0xffff0000, v180
	v_add_f32_e32 v174, 1.0, v174
	v_rcp_f32_e32 v174, v174
	s_nop 0
	v_fma_f32 v93, v174, v167, v93
	v_mul_f32_e32 v174, s0, v176
	v_mul_f32_e32 v174, 0xbfb8aa3b, v174
	v_exp_f32_e32 v174, v174
	v_lshlrev_b32_e32 v167, 16, v181
	v_add_f32_e32 v174, 1.0, v174
	v_rcp_f32_e32 v174, v174
	s_nop 0
	v_fma_f32 v94, v174, v167, v94
	v_mul_f32_e32 v174, s0, v177
	v_mul_f32_e32 v174, 0xbfb8aa3b, v174
	v_exp_f32_e32 v174, v174
	v_and_b32_e32 v167, 0xffff0000, v181
	v_add_f32_e32 v174, 1.0, v174
	v_rcp_f32_e32 v174, v174
	s_nop 0
	v_fmac_f32_e32 v95, v174, v167
	v_cndmask_b32_e64 v167, 0, 1, s[14:15]
	v_cmp_ne_u32_e64 s[4:5], 1, v167
	global_store_dwordx4 v[178:179], v[92:95], off
	s_cbranch_vccnz .LBB0_1888
	v_cvt_pk_bf16_f32 v174, v92, v93
	v_cvt_pk_bf16_f32 v175, v94, v95
	v_lshl_add_u64 v[140:141], v[140:141], 1, s[8:9]
	global_store_dwordx2 v[140:141], v[174:175], off
.LBB0_1888:
	s_and_b64 vcc, exec, s[6:7]
	v_cmp_eq_u32_e64 s[0:1], 0, v166
	s_cbranch_vccnz .LBB0_1892
	v_mul_f32_e32 v93, v93, v93
	v_fmac_f32_e32 v93, v92, v92
	v_fmac_f32_e32 v93, v94, v94
	v_fmac_f32_e32 v93, v95, v95
	s_nop 1
	v_add_f32_dpp v92, v93, v93 row_ror:8 row_mask:0xf bank_mask:0xf bound_ctrl:1
	s_nop 1
	v_add_f32_dpp v92, v92, v92 row_ror:4 row_mask:0xf bank_mask:0xf bound_ctrl:1
	s_nop 1
	v_add_f32_dpp v92, v92, v92 row_ror:2 row_mask:0xf bank_mask:0xf bound_ctrl:1
	s_nop 1
	v_add_f32_dpp v92, v92, v92 row_ror:1 row_mask:0xf bank_mask:0xf bound_ctrl:1
	s_nop 0
	v_readlane_b32 s72, v92, 0
	v_readlane_b32 s81, v92, 16
	v_readlane_b32 s73, v92, 32
	v_readlane_b32 s80, v92, 48
	s_and_saveexec_b64 s[70:71], s[0:1]
	s_cbranch_execz .LBB0_1891
	s_lshl_b64 s[82:83], s[20:21], 2
	v_mov_b32_e32 v92, s81
	s_add_u32 s82, s76, s82
	v_add_f32_e32 v92, s72, v92
	s_addc_u32 s83, s77, s83
	v_add_f32_e32 v92, s73, v92
	v_add_f32_e32 v94, s80, v92
	v_mov_b64_e32 v[92:93], s[82:83]
	global_atomic_add_f32 v[92:93], v94, off

; DEVI float fsig(float x) { return __builtin_amdgcn_rcpf(1.f + __expf(-x)); }
; DEVI float bflo(unsigned u) { return __uint_as_float(u << 16); }
; DEVI float bfhi(unsigned u) { return __uint_as_float(u & 0xffff0000u); }
; template <int EPI, int TS, bool VT>
; DEVI void gemm_epilogue(const Params& p, char* smem, f32x4 (&acc)[2][2][4][2], int m0, int n0, float scale, const float* ssin,
;                         float* ssout, u16* xbout, int wid, int lane, int wr, int wc, int fr, int fq) {
;     ...
;           const float rs = __int_as_float(__builtin_amdgcn_readlane(__float_as_int(rsv), i));
;           if constexpr (EPI == E_RESID || EPI == E_PLEGATE) {
;             const float4 a = *(const float4*)(Tr + 4 * lane);
;             const size_t ro = (size_t)grow * 1024 + n0 + 4 * lane;
;             float4 x4 = xo[u];
;             if constexpr (EPI == E_PLEGATE) {
;               x4.x += bflo(pv[u].x) * fsig(a.x * rs);
;               x4.y += bfhi(pv[u].x) * fsig(a.y * rs);
;               x4.z += bflo(pv[u].y) * fsig(a.z * rs);
;               x4.w += bfhi(pv[u].y) * fsig(a.w * rs);
;             } else {
;               const float sc = fabsf(scale);
;               x4.x += sc * a.x; x4.y += sc * a.y; x4.z += sc * a.z; x4.w += sc * a.w;
;             }
;             st_nt16(p.x + ro, x4);
;             if (xbout) {
;               uint2 o;
;               o.x = pack2(x4.x, x4.y);
;               o.y = pack2(x4.z, x4.w);
;               st_nt8(xbout + ro, o);
;             }
;             if (ssout) {
;               const float ssq = wsum(x4.x * x4.x + x4.y * x4.y + x4.z * x4.z + x4.w * x4.w, lane);
;               if (lane == 0) atomicAdd(ssout + grow, ssq);
;             }
.LBB0_1892:
	ds_read_b128 v[92:95], v142 offset:1040
	v_readlane_b32 s21, v165, 1
	s_and_b64 vcc, exec, s[4:5]
	s_waitcnt lgkmcnt(0)
	v_mul_f32_e32 v92, s21, v92
	v_mul_f32_e32 v93, s21, v93
	v_mul_f32_e32 v92, 0xbfb8aa3b, v92
	v_mul_f32_e32 v93, 0xbfb8aa3b, v93
	v_mul_f32_e32 v94, s21, v94
	v_mul_f32_e32 v95, s21, v95
	v_exp_f32_e32 v140, v92
	v_exp_f32_e32 v141, v93
	v_mul_f32_e32 v94, 0xbfb8aa3b, v94
	v_mul_f32_e32 v95, 0xbfb8aa3b, v95
	v_exp_f32_e32 v94, v94
	v_exp_f32_e32 v95, v95
	v_lshlrev_b32_e32 v92, 16, v138
	v_and_b32_e32 v93, 0xffff0000, v138
	v_add_f32_e32 v138, 1.0, v140
	v_add_f32_e32 v141, 1.0, v141
	v_rcp_f32_e32 v140, v138
	v_rcp_f32_e32 v141, v141
	v_add_f32_e32 v94, 1.0, v94
	v_add_f32_e32 v95, 1.0, v95
	v_rcp_f32_e32 v94, v94
	v_rcp_f32_e32 v95, v95
	v_pk_fma_f32 v[88:89], v[140:141], v[92:93], v[88:89]
	v_lshlrev_b32_e32 v92, 16, v139
	v_and_b32_e32 v93, 0xffff0000, v139
	v_pk_fma_f32 v[90:91], v[94:95], v[92:93], v[90:91]
	global_store_dwordx4 v[136:137], v[88:91], off
	s_cbranch_vccnz .LBB0_1894
	v_cvt_pk_bf16_f32 v92, v88, v89
	v_cvt_pk_bf16_f32 v93, v90, v91
	v_lshl_add_u64 v[94:95], v[134:135], 1, s[8:9]
	global_store_dwordx2 v[94:95], v[92:93], off
.LBB0_1894:
	s_and_b64 vcc, exec, s[6:7]
	s_cbranch_vccnz .LBB0_1898
	v_pk_mul_f32 v[88:89], v[88:89], v[88:89]
	v_pk_mul_f32 v[90:91], v[90:91], v[90:91]
	v_add_f32_e32 v88, v88, v89
	v_add_f32_e32 v88, v88, v90
	v_add_f32_e32 v88, v91, v88
	s_nop 1
	v_add_f32_dpp v88, v88, v88 row_ror:8 row_mask:0xf bank_mask:0xf bound_ctrl:1
	s_nop 1
	v_add_f32_dpp v88, v88, v88 row_ror:4 row_mask:0xf bank_mask:0xf bound_ctrl:1
	s_nop 1
	v_add_f32_dpp v88, v88, v88 row_ror:2 row_mask:0xf bank_mask:0xf bound_ctrl:1
	s_nop 1
	v_add_f32_dpp v88, v88, v88 row_ror:1 row_mask:0xf bank_mask:0xf bound_ctrl:1
	s_nop 0
	v_readlane_b32 s21, v88, 0
	v_readlane_b32 s80, v88, 16
	v_readlane_b32 s72, v88, 32
	v_readlane_b32 s73, v88, 48
	s_and_saveexec_b64 s[70:71], s[0:1]
	s_cbranch_execz .LBB0_1897
	s_lshl_b64 s[68:69], s[68:69], 2
	v_mov_b32_e32 v88, s80
	s_add_u32 s68, s76, s68
	v_add_f32_e32 v88, s21, v88
	s_addc_u32 s69, s77, s69
	v_add_f32_e32 v88, s72, v88
	v_add_f32_e32 v90, s73, v88
	v_mov_b64_e32 v[88:89], s[68:69]
	global_atomic_add_f32 v[88:89], v90, off

; DEVI float fsig(float x) { return __builtin_amdgcn_rcpf(1.f + __expf(-x)); }
; DEVI float bflo(unsigned u) { return __uint_as_float(u << 16); }
; DEVI float bfhi(unsigned u) { return __uint_as_float(u & 0xffff0000u); }
; template <int EPI, int TS, bool VT>
; DEVI void gemm_epilogue(const Params& p, char* smem, f32x4 (&acc)[2][2][4][2], int m0, int n0, float scale, const float* ssin,
;                         float* ssout, u16* xbout, int wid, int lane, int wr, int wc, int fr, int fq) {
;     ...
;           const float rs = __int_as_float(__builtin_amdgcn_readlane(__float_as_int(rsv), i));
;           if constexpr (EPI == E_RESID || EPI == E_PLEGATE) {
;             const float4 a = *(const float4*)(Tr + 4 * lane);
;             const size_t ro = (size_t)grow * 1024 + n0 + 4 * lane;
;             float4 x4 = xo[u];
;             if constexpr (EPI == E_PLEGATE) {
;               x4.x += bflo(pv[u].x) * fsig(a.x * rs);
;               x4.y += bfhi(pv[u].x) * fsig(a.y * rs);
;               x4.z += bflo(pv[u].y) * fsig(a.z * rs);
;               x4.w += bfhi(pv[u].y) * fsig(a.w * rs);
;             } else {
;               const float sc = fabsf(scale);
;               x4.x += sc * a.x; x4.y += sc * a.y; x4.z += sc * a.z; x4.w += sc * a.w;
;             }
;             st_nt16(p.x + ro, x4);
;             if (xbout) {
;               uint2 o;
;               o.x = pack2(x4.x, x4.y);
;               o.y = pack2(x4.z, x4.w);
;               st_nt8(xbout + ro, o);
;             }
;             if (ssout) {
;               const float ssq = wsum(x4.x * x4.x + x4.y * x4.y + x4.z * x4.z + x4.w * x4.w, lane);
;               if (lane == 0) atomicAdd(ssout + grow, ssq);
;             }
.LBB0_1898:
	ds_read_b128 v[88:91], v142 offset:2080
	v_readlane_b32 s21, v165, 2
	s_and_b64 vcc, exec, s[4:5]
	s_waitcnt lgkmcnt(0)
	v_mul_f32_e32 v88, s21, v88
	v_mul_f32_e32 v89, s21, v89
	v_mul_f32_e32 v88, 0xbfb8aa3b, v88
	v_mul_f32_e32 v89, 0xbfb8aa3b, v89
	v_mul_f32_e32 v90, s21, v90
	v_mul_f32_e32 v91, s21, v91
	v_exp_f32_e32 v92, v88
	v_exp_f32_e32 v93, v89
	v_mul_f32_e32 v90, 0xbfb8aa3b, v90
	v_mul_f32_e32 v91, 0xbfb8aa3b, v91
	v_exp_f32_e32 v90, v90
	v_exp_f32_e32 v91, v91
	v_add_f32_e32 v92, 1.0, v92
	v_add_f32_e32 v93, 1.0, v93
	v_rcp_f32_e32 v92, v92
	v_rcp_f32_e32 v93, v93
	v_add_f32_e32 v90, 1.0, v90
	v_add_f32_e32 v91, 1.0, v91
	v_rcp_f32_e32 v90, v90
	v_rcp_f32_e32 v91, v91
	v_lshlrev_b32_e32 v88, 16, v132
	v_and_b32_e32 v89, 0xffff0000, v132
	v_pk_fma_f32 v[84:85], v[92:93], v[88:89], v[84:85]
	v_lshlrev_b32_e32 v88, 16, v133
	v_and_b32_e32 v89, 0xffff0000, v133
	v_pk_fma_f32 v[86:87], v[90:91], v[88:89], v[86:87]
	global_store_dwordx4 v[130:131], v[84:87], off
	s_cbranch_vccnz .LBB0_1900
	v_cvt_pk_bf16_f32 v88, v84, v85
	v_cvt_pk_bf16_f32 v89, v86, v87
	v_lshl_add_u64 v[90:91], v[126:127], 1, s[8:9]
	global_store_dwordx2 v[90:91], v[88:89], off
.LBB0_1900:
	s_and_b64 vcc, exec, s[6:7]
	s_cbranch_vccnz .LBB0_1904
	v_pk_mul_f32 v[84:85], v[84:85], v[84:85]
	v_pk_mul_f32 v[86:87], v[86:87], v[86:87]
	v_add_f32_e32 v84, v84, v85
	v_add_f32_e32 v84, v84, v86
	v_add_f32_e32 v84, v87, v84
	s_nop 1
	v_add_f32_dpp v84, v84, v84 row_ror:8 row_mask:0xf bank_mask:0xf bound_ctrl:1
	s_nop 1
	v_add_f32_dpp v84, v84, v84 row_ror:4 row_mask:0xf bank_mask:0xf bound_ctrl:1
	s_nop 1
	v_add_f32_dpp v84, v84, v84 row_ror:2 row_mask:0xf bank_mask:0xf bound_ctrl:1
	s_nop 1
	v_add_f32_dpp v84, v84, v84 row_ror:1 row_mask:0xf bank_mask:0xf bound_ctrl:1
	s_nop 0
	v_readlane_b32 s21, v84, 0
	v_readlane_b32 s72, v84, 16
	v_readlane_b32 s70, v84, 32
	v_readlane_b32 s71, v84, 48
	s_and_saveexec_b64 s[68:69], s[0:1]
	s_cbranch_execz .LBB0_1903
	s_lshl_b64 s[66:67], s[66:67], 2
	v_mov_b32_e32 v84, s72
	s_add_u32 s66, s76, s66
	v_add_f32_e32 v84, s21, v84
	s_addc_u32 s67, s77, s67
	v_add_f32_e32 v84, s70, v84
	v_add_f32_e32 v86, s71, v84
	v_mov_b64_e32 v[84:85], s[66:67]
	global_atomic_add_f32 v[84:85], v86, off

; DEVI float fsig(float x) { return __builtin_amdgcn_rcpf(1.f + __expf(-x)); }
; DEVI float bflo(unsigned u) { return __uint_as_float(u << 16); }
; DEVI float bfhi(unsigned u) { return __uint_as_float(u & 0xffff0000u); }
; template <int EPI, int TS, bool VT>
; DEVI void gemm_epilogue(const Params& p, char* smem, f32x4 (&acc)[2][2][4][2], int m0, int n0, float scale, const float* ssin,
;                         float* ssout, u16* xbout, int wid, int lane, int wr, int wc, int fr, int fq) {
;     ...
;           const float rs = __int_as_float(__builtin_amdgcn_readlane(__float_as_int(rsv), i));
;           if constexpr (EPI == E_RESID || EPI == E_PLEGATE) {
;             const float4 a = *(const float4*)(Tr + 4 * lane);
;             const size_t ro = (size_t)grow * 1024 + n0 + 4 * lane;
;             float4 x4 = xo[u];
;             if constexpr (EPI == E_PLEGATE) {
;               x4.x += bflo(pv[u].x) * fsig(a.x * rs);
;               x4.y += bfhi(pv[u].x) * fsig(a.y * rs);
;               x4.z += bflo(pv[u].y) * fsig(a.z * rs);
;               x4.w += bfhi(pv[u].y) * fsig(a.w * rs);
;             } else {
;               const float sc = fabsf(scale);
;               x4.x += sc * a.x; x4.y += sc * a.y; x4.z += sc * a.z; x4.w += sc * a.w;
;             }
;             st_nt16(p.x + ro, x4);
;             if (xbout) {
;               uint2 o;
;               o.x = pack2(x4.x, x4.y);
;               o.y = pack2(x4.z, x4.w);
;               st_nt8(xbout + ro, o);
;             }
;             if (ssout) {
;               const float ssq = wsum(x4.x * x4.x + x4.y * x4.y + x4.z * x4.z + x4.w * x4.w, lane);
;               if (lane == 0) atomicAdd(ssout + grow, ssq);
;             }
.LBB0_1904:
	ds_read_b128 v[84:87], v142 offset:3120
	v_readlane_b32 s21, v165, 3
	s_and_b64 vcc, exec, s[4:5]
	s_waitcnt lgkmcnt(0)
	v_mul_f32_e32 v84, s21, v84
	v_mul_f32_e32 v85, s21, v85
	v_mul_f32_e32 v84, 0xbfb8aa3b, v84
	v_mul_f32_e32 v85, 0xbfb8aa3b, v85
	v_mul_f32_e32 v86, s21, v86
	v_mul_f32_e32 v87, s21, v87
	v_exp_f32_e32 v88, v84
	v_exp_f32_e32 v89, v85
	v_mul_f32_e32 v86, 0xbfb8aa3b, v86
	v_mul_f32_e32 v87, 0xbfb8aa3b, v87
	v_exp_f32_e32 v86, v86
	v_exp_f32_e32 v87, v87
	v_add_f32_e32 v88, 1.0, v88
	v_add_f32_e32 v89, 1.0, v89
	v_rcp_f32_e32 v88, v88
	v_rcp_f32_e32 v89, v89
	v_add_f32_e32 v86, 1.0, v86
	v_add_f32_e32 v87, 1.0, v87
	v_rcp_f32_e32 v86, v86
	v_rcp_f32_e32 v87, v87
	v_lshlrev_b32_e32 v84, 16, v124
	v_and_b32_e32 v85, 0xffff0000, v124
	v_pk_fma_f32 v[80:81], v[88:89], v[84:85], v[80:81]
	v_lshlrev_b32_e32 v84, 16, v125
	v_and_b32_e32 v85, 0xffff0000, v125
	v_pk_fma_f32 v[82:83], v[86:87], v[84:85], v[82:83]
	global_store_dwordx4 v[122:123], v[80:83], off
	s_cbranch_vccnz .LBB0_1906
	v_cvt_pk_bf16_f32 v84, v80, v81
	v_cvt_pk_bf16_f32 v85, v82, v83
	v_lshl_add_u64 v[86:87], v[120:121], 1, s[8:9]
	global_store_dwordx2 v[86:87], v[84:85], off
.LBB0_1906:
	s_and_b64 vcc, exec, s[6:7]
	s_cbranch_vccnz .LBB0_1910
	v_pk_mul_f32 v[80:81], v[80:81], v[80:81]
	v_pk_mul_f32 v[82:83], v[82:83], v[82:83]
	v_add_f32_e32 v80, v80, v81
	v_add_f32_e32 v80, v80, v82
	v_add_f32_e32 v80, v83, v80
	s_nop 1
	v_add_f32_dpp v80, v80, v80 row_ror:8 row_mask:0xf bank_mask:0xf bound_ctrl:1
	s_nop 1
	v_add_f32_dpp v80, v80, v80 row_ror:4 row_mask:0xf bank_mask:0xf bound_ctrl:1
	s_nop 1
	v_add_f32_dpp v80, v80, v80 row_ror:2 row_mask:0xf bank_mask:0xf bound_ctrl:1
	s_nop 1
	v_add_f32_dpp v80, v80, v80 row_ror:1 row_mask:0xf bank_mask:0xf bound_ctrl:1
	s_nop 0
	v_readlane_b32 s21, v80, 0
	v_readlane_b32 s70, v80, 16
	v_readlane_b32 s68, v80, 32
	v_readlane_b32 s69, v80, 48
	s_and_saveexec_b64 s[66:67], s[0:1]
	s_cbranch_execz .LBB0_1909
	s_lshl_b64 s[64:65], s[64:65], 2
	v_mov_b32_e32 v80, s70
	s_add_u32 s64, s76, s64
	v_add_f32_e32 v80, s21, v80
	s_addc_u32 s65, s77, s65
	v_add_f32_e32 v80, s68, v80
	v_add_f32_e32 v82, s69, v80
	v_mov_b64_e32 v[80:81], s[64:65]
	global_atomic_add_f32 v[80:81], v82, off

; DEVI float fsig(float x) { return __builtin_amdgcn_rcpf(1.f + __expf(-x)); }
; DEVI float bflo(unsigned u) { return __uint_as_float(u << 16); }
; DEVI float bfhi(unsigned u) { return __uint_as_float(u & 0xffff0000u); }
; template <int EPI, int TS, bool VT>
; DEVI void gemm_epilogue(const Params& p, char* smem, f32x4 (&acc)[2][2][4][2], int m0, int n0, float scale, const float* ssin,
;                         float* ssout, u16* xbout, int wid, int lane, int wr, int wc, int fr, int fq) {
;     ...
;           const float rs = __int_as_float(__builtin_amdgcn_readlane(__float_as_int(rsv), i));
;           if constexpr (EPI == E_RESID || EPI == E_PLEGATE) {
;             const float4 a = *(const float4*)(Tr + 4 * lane);
;             const size_t ro = (size_t)grow * 1024 + n0 + 4 * lane;
;             float4 x4 = xo[u];
;             if constexpr (EPI == E_PLEGATE) {
;               x4.x += bflo(pv[u].x) * fsig(a.x * rs);
;               x4.y += bfhi(pv[u].x) * fsig(a.y * rs);
;               x4.z += bflo(pv[u].y) * fsig(a.z * rs);
;               x4.w += bfhi(pv[u].y) * fsig(a.w * rs);
;             } else {
;               const float sc = fabsf(scale);
;               x4.x += sc * a.x; x4.y += sc * a.y; x4.z += sc * a.z; x4.w += sc * a.w;
;             }
;             st_nt16(p.x + ro, x4);
;             if (xbout) {
;               uint2 o;
;               o.x = pack2(x4.x, x4.y);
;               o.y = pack2(x4.z, x4.w);
;               st_nt8(xbout + ro, o);
;             }
;             if (ssout) {
;               const float ssq = wsum(x4.x * x4.x + x4.y * x4.y + x4.z * x4.z + x4.w * x4.w, lane);
;               if (lane == 0) atomicAdd(ssout + grow, ssq);
;             }
.LBB0_1910:
	ds_read_b128 v[80:83], v142 offset:4160
	v_readlane_b32 s21, v165, 4
	s_and_b64 vcc, exec, s[4:5]
	s_waitcnt lgkmcnt(0)
	v_mul_f32_e32 v80, s21, v80
	v_mul_f32_e32 v81, s21, v81
	v_mul_f32_e32 v80, 0xbfb8aa3b, v80
	v_mul_f32_e32 v81, 0xbfb8aa3b, v81
	v_mul_f32_e32 v82, s21, v82
	v_mul_f32_e32 v83, s21, v83
	v_exp_f32_e32 v84, v80
	v_exp_f32_e32 v85, v81
	v_mul_f32_e32 v82, 0xbfb8aa3b, v82
	v_mul_f32_e32 v83, 0xbfb8aa3b, v83
	v_exp_f32_e32 v82, v82
	v_exp_f32_e32 v83, v83
	v_add_f32_e32 v84, 1.0, v84
	v_add_f32_e32 v85, 1.0, v85
	v_rcp_f32_e32 v84, v84
	v_rcp_f32_e32 v85, v85
	v_add_f32_e32 v82, 1.0, v82
	v_add_f32_e32 v83, 1.0, v83
	v_rcp_f32_e32 v82, v82
	v_rcp_f32_e32 v83, v83
	v_lshlrev_b32_e32 v80, 16, v118
	v_and_b32_e32 v81, 0xffff0000, v118
	v_pk_fma_f32 v[76:77], v[84:85], v[80:81], v[76:77]
	v_lshlrev_b32_e32 v80, 16, v119
	v_and_b32_e32 v81, 0xffff0000, v119
	v_pk_fma_f32 v[78:79], v[82:83], v[80:81], v[78:79]
	global_store_dwordx4 v[116:117], v[76:79], off
	s_cbranch_vccnz .LBB0_1912
	v_cvt_pk_bf16_f32 v80, v76, v77
	v_cvt_pk_bf16_f32 v81, v78, v79
	v_lshl_add_u64 v[82:83], v[114:115], 1, s[8:9]
	global_store_dwordx2 v[82:83], v[80:81], off
.LBB0_1912:
	s_and_b64 vcc, exec, s[6:7]
	s_cbranch_vccnz .LBB0_1916
	v_pk_mul_f32 v[76:77], v[76:77], v[76:77]
	v_pk_mul_f32 v[78:79], v[78:79], v[78:79]
	v_add_f32_e32 v76, v76, v77
	v_add_f32_e32 v76, v76, v78
	v_add_f32_e32 v76, v79, v76
	s_nop 1
	v_add_f32_dpp v76, v76, v76 row_ror:8 row_mask:0xf bank_mask:0xf bound_ctrl:1
	s_nop 1
	v_add_f32_dpp v76, v76, v76 row_ror:4 row_mask:0xf bank_mask:0xf bound_ctrl:1
	s_nop 1
	v_add_f32_dpp v76, v76, v76 row_ror:2 row_mask:0xf bank_mask:0xf bound_ctrl:1
	s_nop 1
	v_add_f32_dpp v76, v76, v76 row_ror:1 row_mask:0xf bank_mask:0xf bound_ctrl:1
	s_nop 0
	v_readlane_b32 s21, v76, 0
	v_readlane_b32 s68, v76, 16
	v_readlane_b32 s66, v76, 32
	v_readlane_b32 s67, v76, 48
	s_and_saveexec_b64 s[64:65], s[0:1]
	s_cbranch_execz .LBB0_1915
	s_lshl_b64 s[62:63], s[62:63], 2
	v_mov_b32_e32 v76, s68
	s_add_u32 s62, s76, s62
	v_add_f32_e32 v76, s21, v76
	s_addc_u32 s63, s77, s63
	v_add_f32_e32 v76, s66, v76
	v_add_f32_e32 v78, s67, v76
	v_mov_b64_e32 v[76:77], s[62:63]
	global_atomic_add_f32 v[76:77], v78, off

; DEVI float fsig(float x) { return __builtin_amdgcn_rcpf(1.f + __expf(-x)); }
; DEVI float bflo(unsigned u) { return __uint_as_float(u << 16); }
; DEVI float bfhi(unsigned u) { return __uint_as_float(u & 0xffff0000u); }
; template <int EPI, int TS, bool VT>
; DEVI void gemm_epilogue(const Params& p, char* smem, f32x4 (&acc)[2][2][4][2], int m0, int n0, float scale, const float* ssin,
;                         float* ssout, u16* xbout, int wid, int lane, int wr, int wc, int fr, int fq) {
;     ...
;           const float rs = __int_as_float(__builtin_amdgcn_readlane(__float_as_int(rsv), i));
;           if constexpr (EPI == E_RESID || EPI == E_PLEGATE) {
;             const float4 a = *(const float4*)(Tr + 4 * lane);
;             const size_t ro = (size_t)grow * 1024 + n0 + 4 * lane;
;             float4 x4 = xo[u];
;             if constexpr (EPI == E_PLEGATE) {
;               x4.x += bflo(pv[u].x) * fsig(a.x * rs);
;               x4.y += bfhi(pv[u].x) * fsig(a.y * rs);
;               x4.z += bflo(pv[u].y) * fsig(a.z * rs);
;               x4.w += bfhi(pv[u].y) * fsig(a.w * rs);
;             } else {
;               const float sc = fabsf(scale);
;               x4.x += sc * a.x; x4.y += sc * a.y; x4.z += sc * a.z; x4.w += sc * a.w;
;             }
;             st_nt16(p.x + ro, x4);
;             if (xbout) {
;               uint2 o;
;               o.x = pack2(x4.x, x4.y);
;               o.y = pack2(x4.z, x4.w);
;               st_nt8(xbout + ro, o);
;             }
;             if (ssout) {
;               const float ssq = wsum(x4.x * x4.x + x4.y * x4.y + x4.z * x4.z + x4.w * x4.w, lane);
;               if (lane == 0) atomicAdd(ssout + grow, ssq);
;             }
.LBB0_1916:
	ds_read_b128 v[76:79], v142 offset:5200
	v_readlane_b32 s21, v165, 5
	s_and_b64 vcc, exec, s[4:5]
	s_waitcnt lgkmcnt(0)
	v_mul_f32_e32 v76, s21, v76
	v_mul_f32_e32 v77, s21, v77
	v_mul_f32_e32 v76, 0xbfb8aa3b, v76
	v_mul_f32_e32 v77, 0xbfb8aa3b, v77
	v_mul_f32_e32 v78, s21, v78
	v_mul_f32_e32 v79, s21, v79
	v_exp_f32_e32 v80, v76
	v_exp_f32_e32 v81, v77
	v_mul_f32_e32 v78, 0xbfb8aa3b, v78
	v_mul_f32_e32 v79, 0xbfb8aa3b, v79
	v_exp_f32_e32 v78, v78
	v_exp_f32_e32 v79, v79
	v_add_f32_e32 v80, 1.0, v80
	v_add_f32_e32 v81, 1.0, v81
	v_rcp_f32_e32 v80, v80
	v_rcp_f32_e32 v81, v81
	v_add_f32_e32 v78, 1.0, v78
	v_add_f32_e32 v79, 1.0, v79
	v_rcp_f32_e32 v78, v78
	v_rcp_f32_e32 v79, v79
	v_lshlrev_b32_e32 v76, 16, v112
	v_and_b32_e32 v77, 0xffff0000, v112
	v_pk_fma_f32 v[72:73], v[80:81], v[76:77], v[72:73]
	v_lshlrev_b32_e32 v76, 16, v113
	v_and_b32_e32 v77, 0xffff0000, v113
	v_pk_fma_f32 v[74:75], v[78:79], v[76:77], v[74:75]
	global_store_dwordx4 v[110:111], v[72:75], off
	s_cbranch_vccnz .LBB0_1918
	v_cvt_pk_bf16_f32 v76, v72, v73
	v_cvt_pk_bf16_f32 v77, v74, v75
	v_lshl_add_u64 v[78:79], v[108:109], 1, s[8:9]
	global_store_dwordx2 v[78:79], v[76:77], off
.LBB0_1918:
	s_and_b64 vcc, exec, s[6:7]
	s_cbranch_vccnz .LBB0_1922
	v_pk_mul_f32 v[72:73], v[72:73], v[72:73]
	v_pk_mul_f32 v[74:75], v[74:75], v[74:75]
	v_add_f32_e32 v72, v72, v73
	v_add_f32_e32 v72, v72, v74
	v_add_f32_e32 v72, v75, v72
	s_nop 1
	v_add_f32_dpp v72, v72, v72 row_ror:8 row_mask:0xf bank_mask:0xf bound_ctrl:1
	s_nop 1
	v_add_f32_dpp v72, v72, v72 row_ror:4 row_mask:0xf bank_mask:0xf bound_ctrl:1
	s_nop 1
	v_add_f32_dpp v72, v72, v72 row_ror:2 row_mask:0xf bank_mask:0xf bound_ctrl:1
	s_nop 1
	v_add_f32_dpp v72, v72, v72 row_ror:1 row_mask:0xf bank_mask:0xf bound_ctrl:1
	s_nop 0
	v_readlane_b32 s21, v72, 0
	v_readlane_b32 s66, v72, 16
	v_readlane_b32 s64, v72, 32
	v_readlane_b32 s65, v72, 48
	s_and_saveexec_b64 s[62:63], s[0:1]
	s_cbranch_execz .LBB0_1921
	s_lshl_b64 s[34:35], s[34:35], 2
	v_mov_b32_e32 v72, s66
	s_add_u32 s34, s76, s34
	v_add_f32_e32 v72, s21, v72
	s_addc_u32 s35, s77, s35
	v_add_f32_e32 v72, s64, v72
	v_add_f32_e32 v74, s65, v72
	v_mov_b64_e32 v[72:73], s[34:35]
	global_atomic_add_f32 v[72:73], v74, off

; DEVI float fsig(float x) { return __builtin_amdgcn_rcpf(1.f + __expf(-x)); }
; DEVI float bflo(unsigned u) { return __uint_as_float(u << 16); }
; DEVI float bfhi(unsigned u) { return __uint_as_float(u & 0xffff0000u); }
; template <int EPI, int TS, bool VT>
; DEVI void gemm_epilogue(const Params& p, char* smem, f32x4 (&acc)[2][2][4][2], int m0, int n0, float scale, const float* ssin,
;                         float* ssout, u16* xbout, int wid, int lane, int wr, int wc, int fr, int fq) {
;     ...
;           const float rs = __int_as_float(__builtin_amdgcn_readlane(__float_as_int(rsv), i));
;           if constexpr (EPI == E_RESID || EPI == E_PLEGATE) {
;             const float4 a = *(const float4*)(Tr + 4 * lane);
;             const size_t ro = (size_t)grow * 1024 + n0 + 4 * lane;
;             float4 x4 = xo[u];
;             if constexpr (EPI == E_PLEGATE) {
;               x4.x += bflo(pv[u].x) * fsig(a.x * rs);
;               x4.y += bfhi(pv[u].x) * fsig(a.y * rs);
;               x4.z += bflo(pv[u].y) * fsig(a.z * rs);
;               x4.w += bfhi(pv[u].y) * fsig(a.w * rs);
;             } else {
;               const float sc = fabsf(scale);
;               x4.x += sc * a.x; x4.y += sc * a.y; x4.z += sc * a.z; x4.w += sc * a.w;
;             }
;             st_nt16(p.x + ro, x4);
;             if (xbout) {
;               uint2 o;
;               o.x = pack2(x4.x, x4.y);
;               o.y = pack2(x4.z, x4.w);
;               st_nt8(xbout + ro, o);
;             }
;             if (ssout) {
;               const float ssq = wsum(x4.x * x4.x + x4.y * x4.y + x4.z * x4.z + x4.w * x4.w, lane);
;               if (lane == 0) atomicAdd(ssout + grow, ssq);
;             }
.LBB0_1922:
	ds_read_b128 v[72:75], v142 offset:6240
	v_readlane_b32 s21, v165, 6
	s_and_b64 vcc, exec, s[4:5]
	s_waitcnt lgkmcnt(0)
	v_mul_f32_e32 v72, s21, v72
	v_mul_f32_e32 v73, s21, v73
	v_mul_f32_e32 v72, 0xbfb8aa3b, v72
	v_mul_f32_e32 v73, 0xbfb8aa3b, v73
	v_mul_f32_e32 v74, s21, v74
	v_mul_f32_e32 v75, s21, v75
	v_exp_f32_e32 v76, v72
	v_exp_f32_e32 v77, v73
	v_mul_f32_e32 v74, 0xbfb8aa3b, v74
	v_mul_f32_e32 v75, 0xbfb8aa3b, v75
	v_exp_f32_e32 v74, v74
	v_exp_f32_e32 v75, v75
	v_add_f32_e32 v76, 1.0, v76
	v_add_f32_e32 v77, 1.0, v77
	v_rcp_f32_e32 v76, v76
	v_rcp_f32_e32 v77, v77
	v_add_f32_e32 v74, 1.0, v74
	v_add_f32_e32 v75, 1.0, v75
	v_rcp_f32_e32 v74, v74
	v_rcp_f32_e32 v75, v75
	v_lshlrev_b32_e32 v72, 16, v106
	v_and_b32_e32 v73, 0xffff0000, v106
	v_pk_fma_f32 v[68:69], v[76:77], v[72:73], v[68:69]
	v_lshlrev_b32_e32 v72, 16, v107
	v_and_b32_e32 v73, 0xffff0000, v107
	v_pk_fma_f32 v[70:71], v[74:75], v[72:73], v[70:71]
	global_store_dwordx4 v[104:105], v[68:71], off
	s_cbranch_vccnz .LBB0_1924
	v_cvt_pk_bf16_f32 v72, v68, v69
	v_cvt_pk_bf16_f32 v73, v70, v71
	v_lshl_add_u64 v[74:75], v[102:103], 1, s[8:9]
	global_store_dwordx2 v[74:75], v[72:73], off
.LBB0_1924:
	s_and_b64 vcc, exec, s[6:7]
	s_cbranch_vccnz .LBB0_1928
	v_pk_mul_f32 v[68:69], v[68:69], v[68:69]
	v_pk_mul_f32 v[70:71], v[70:71], v[70:71]
	v_add_f32_e32 v68, v68, v69
	v_add_f32_e32 v68, v68, v70
	v_add_f32_e32 v68, v71, v68
	s_nop 1
	v_add_f32_dpp v68, v68, v68 row_ror:8 row_mask:0xf bank_mask:0xf bound_ctrl:1
	s_nop 1
	v_add_f32_dpp v68, v68, v68 row_ror:4 row_mask:0xf bank_mask:0xf bound_ctrl:1
	s_nop 1
	v_add_f32_dpp v68, v68, v68 row_ror:2 row_mask:0xf bank_mask:0xf bound_ctrl:1
	s_nop 1
	v_add_f32_dpp v68, v68, v68 row_ror:1 row_mask:0xf bank_mask:0xf bound_ctrl:1
	s_nop 0
	v_readlane_b32 s21, v68, 0
	v_readlane_b32 s64, v68, 16
	v_readlane_b32 s62, v68, 32
	v_readlane_b32 s63, v68, 48
	s_and_saveexec_b64 s[34:35], s[0:1]
	s_cbranch_execz .LBB0_1927
	s_lshl_b64 s[30:31], s[30:31], 2
	v_mov_b32_e32 v68, s64
	s_add_u32 s30, s76, s30
	v_add_f32_e32 v68, s21, v68
	s_addc_u32 s31, s77, s31
	v_add_f32_e32 v68, s62, v68
	v_add_f32_e32 v70, s63, v68
	v_mov_b64_e32 v[68:69], s[30:31]
	global_atomic_add_f32 v[68:69], v70, off

; DEVI float fsig(float x) { return __builtin_amdgcn_rcpf(1.f + __expf(-x)); }
; DEVI float bflo(unsigned u) { return __uint_as_float(u << 16); }
; DEVI float bfhi(unsigned u) { return __uint_as_float(u & 0xffff0000u); }
; template <int EPI, int TS, bool VT>
; DEVI void gemm_epilogue(const Params& p, char* smem, f32x4 (&acc)[2][2][4][2], int m0, int n0, float scale, const float* ssin,
;                         float* ssout, u16* xbout, int wid, int lane, int wr, int wc, int fr, int fq) {
;     ...
;           const float rs = __int_as_float(__builtin_amdgcn_readlane(__float_as_int(rsv), i));
;           if constexpr (EPI == E_RESID || EPI == E_PLEGATE) {
;             const float4 a = *(const float4*)(Tr + 4 * lane);
;             const size_t ro = (size_t)grow * 1024 + n0 + 4 * lane;
;             float4 x4 = xo[u];
;             if constexpr (EPI == E_PLEGATE) {
;               x4.x += bflo(pv[u].x) * fsig(a.x * rs);
;               x4.y += bfhi(pv[u].x) * fsig(a.y * rs);
;               x4.z += bflo(pv[u].y) * fsig(a.z * rs);
;               x4.w += bfhi(pv[u].y) * fsig(a.w * rs);
;             } else {
;               const float sc = fabsf(scale);
;               x4.x += sc * a.x; x4.y += sc * a.y; x4.z += sc * a.z; x4.w += sc * a.w;
;             }
;             st_nt16(p.x + ro, x4);
;             if (xbout) {
;               uint2 o;
;               o.x = pack2(x4.x, x4.y);
;               o.y = pack2(x4.z, x4.w);
;               st_nt8(xbout + ro, o);
;             }
;             if (ssout) {
;               const float ssq = wsum(x4.x * x4.x + x4.y * x4.y + x4.z * x4.z + x4.w * x4.w, lane);
;               if (lane == 0) atomicAdd(ssout + grow, ssq);
;             }
.LBB0_1928:
	ds_read_b128 v[68:71], v142 offset:7280
	v_readlane_b32 s21, v165, 7
	s_and_b64 vcc, exec, s[4:5]
	s_waitcnt lgkmcnt(0)
	v_mul_f32_e32 v68, s21, v68
	v_mul_f32_e32 v69, s21, v69
	v_mul_f32_e32 v68, 0xbfb8aa3b, v68
	v_mul_f32_e32 v69, 0xbfb8aa3b, v69
	v_mul_f32_e32 v70, s21, v70
	v_mul_f32_e32 v71, s21, v71
	v_exp_f32_e32 v72, v68
	v_exp_f32_e32 v73, v69
	v_mul_f32_e32 v70, 0xbfb8aa3b, v70
	v_mul_f32_e32 v71, 0xbfb8aa3b, v71
	v_exp_f32_e32 v70, v70
	v_exp_f32_e32 v71, v71
	v_add_f32_e32 v72, 1.0, v72
	v_add_f32_e32 v73, 1.0, v73
	v_rcp_f32_e32 v72, v72
	v_rcp_f32_e32 v73, v73
	v_add_f32_e32 v70, 1.0, v70
	v_add_f32_e32 v71, 1.0, v71
	v_rcp_f32_e32 v70, v70
	v_rcp_f32_e32 v71, v71
	v_lshlrev_b32_e32 v68, 16, v100
	v_and_b32_e32 v69, 0xffff0000, v100
	v_pk_fma_f32 v[64:65], v[72:73], v[68:69], v[64:65]
	v_lshlrev_b32_e32 v68, 16, v101
	v_and_b32_e32 v69, 0xffff0000, v101
	v_pk_fma_f32 v[66:67], v[70:71], v[68:69], v[66:67]
	global_store_dwordx4 v[98:99], v[64:67], off
	s_cbranch_vccnz .LBB0_1930
	v_cvt_pk_bf16_f32 v68, v64, v65
	v_cvt_pk_bf16_f32 v69, v66, v67
	v_lshl_add_u64 v[70:71], v[96:97], 1, s[8:9]
	global_store_dwordx2 v[70:71], v[68:69], off
.LBB0_1930:
	s_and_b64 vcc, exec, s[6:7]
	s_cbranch_vccnz .LBB0_1934
	v_pk_mul_f32 v[64:65], v[64:65], v[64:65]
	v_pk_mul_f32 v[66:67], v[66:67], v[66:67]
	v_add_f32_e32 v64, v64, v65
	v_add_f32_e32 v64, v64, v66
	v_add_f32_e32 v64, v67, v64
	s_nop 1
	v_add_f32_dpp v64, v64, v64 row_ror:8 row_mask:0xf bank_mask:0xf bound_ctrl:1
	s_nop 1
	v_add_f32_dpp v64, v64, v64 row_ror:4 row_mask:0xf bank_mask:0xf bound_ctrl:1
	s_nop 1
	v_add_f32_dpp v64, v64, v64 row_ror:2 row_mask:0xf bank_mask:0xf bound_ctrl:1
	s_nop 1
	v_add_f32_dpp v64, v64, v64 row_ror:1 row_mask:0xf bank_mask:0xf bound_ctrl:1
	s_nop 0
	v_readlane_b32 s21, v64, 0
	v_readlane_b32 s62, v64, 16
	v_readlane_b32 s34, v64, 32
	v_readlane_b32 s35, v64, 48
	s_and_saveexec_b64 s[30:31], s[0:1]
	s_cbranch_execz .LBB0_1933
	s_lshl_b64 s[22:23], s[22:23], 2
	v_mov_b32_e32 v64, s62
	s_add_u32 s22, s76, s22
	v_add_f32_e32 v64, s21, v64
	s_addc_u32 s23, s77, s23
	v_add_f32_e32 v64, s34, v64
	v_add_f32_e32 v66, s35, v64
	v_mov_b64_e32 v[64:65], s[22:23]
	global_atomic_add_f32 v[64:65], v66, off

; DEVI float fsig(float x) { return __builtin_amdgcn_rcpf(1.f + __expf(-x)); }
; template <int EPI, int TS, bool VT>
; DEVI void gemm_epilogue(const Params& p, char* smem, f32x4 (&acc)[2][2][4][2], int m0, int n0, float scale, const float* ssin,
;                         float* ssout, u16* xbout, int wid, int lane, int wr, int wc, int fr, int fq) {
;     ...
;         if constexpr (EPI == E_RESID || EPI == E_PLEGATE) {
; #pragma unroll
;           for (int u = 0; u < 8; ++u) {
;             const size_t ro = (size_t)(g0 + i0 + u) * 1024 + n0 + 4 * lane;
;             const int gr = g0 + i0 + u;
;             const float* xs = p.x + ro;
;             if (scale < 0.f)
;               xs = (gr < MP ? p.x_prompt + ro : p.x_sample + (ro - (size_t)MP * 1024));
;             { const f32x4 t_ = __builtin_nontemporal_load((const f32x4*)xs); xo[u] = make_float4(t_[0], t_[1], t_[2], t_[3]); }
;             if constexpr (EPI == E_PLEGATE) {
;               const unsigned long long t2_ = __builtin_nontemporal_load((const unsigned long long*)((const u16*)(wsb + OFF_PP) + ro));
;               pv[u] = make_uint2((unsigned)t2_, (unsigned)(t2_ >> 32));
;             }
;           }
;         }
; #pragma unroll
;         for (int u = 0; u < 8; ++u) {
;           const int i = i0 + u;
;           const int grow = g0 + i;
;           const float* Tr = T + (r0 + i) * TS;
;           const float rs = __int_as_float(__builtin_amdgcn_readlane(__float_as_int(rsv), i));
;           if constexpr (EPI == E_RESID || EPI == E_PLEGATE) {
;             const float4 a = *(const float4*)(Tr + 4 * lane);
;             const size_t ro = (size_t)grow * 1024 + n0 + 4 * lane;
;             float4 x4 = xo[u];
;             if constexpr (EPI == E_PLEGATE) {
;               x4.x += bflo(pv[u].x) * fsig(a.x * rs);
;               x4.y += bfhi(pv[u].x) * fsig(a.y * rs);
;               x4.z += bflo(pv[u].y) * fsig(a.z * rs);
;               x4.w += bfhi(pv[u].y) * fsig(a.w * rs);
;             } else {
;               const float sc = fabsf(scale);
;               x4.x += sc * a.x; x4.y += sc * a.y; x4.z += sc * a.z; x4.w += sc * a.w;
;             }
;             st_nt16(p.x + ro, x4);
;             if (xbout) {
;               uint2 o;
;               o.x = pack2(x4.x, x4.y);
;               o.y = pack2(x4.z, x4.w);
;               st_nt8(xbout + ro, o);
;             }
;             if (ssout) {
.LBB0_1934:
	s_or_b32 s70, s20, 8
	s_ashr_i32 s71, s70, 31
	s_or_b32 s68, s20, 9
	s_lshl_b64 s[22:23], s[70:71], 10
	s_ashr_i32 s69, s68, 31
	s_or_b32 s66, s20, 10
	v_lshl_add_u64 v[140:141], s[22:23], 0, v[128:129]
	s_lshl_b64 s[22:23], s[68:69], 10
	s_ashr_i32 s67, s66, 31
	s_or_b32 s64, s20, 11
	v_lshl_add_u64 v[134:135], s[22:23], 0, v[128:129]
	s_lshl_b64 s[22:23], s[66:67], 10
	s_ashr_i32 s65, s64, 31
	s_or_b32 s62, s20, 12
	v_lshl_add_u64 v[126:127], s[22:23], 0, v[128:129]
	s_lshl_b64 s[22:23], s[64:65], 10
	s_ashr_i32 s63, s62, 31
	s_or_b32 s34, s20, 13
	v_lshl_add_u64 v[120:121], s[22:23], 0, v[128:129]
	s_lshl_b64 s[22:23], s[62:63], 10
	s_ashr_i32 s35, s34, 31
	s_or_b32 s30, s20, 14
	v_lshl_add_u64 v[114:115], s[22:23], 0, v[128:129]
	s_lshl_b64 s[22:23], s[34:35], 10
	s_ashr_i32 s31, s30, 31
	v_lshl_add_u64 v[108:109], s[22:23], 0, v[128:129]
	s_lshl_b64 s[22:23], s[30:31], 10
	v_lshl_add_u64 v[166:167], v[140:141], 2, s[38:39]
	v_lshl_add_u64 v[102:103], s[22:23], 0, v[128:129]
	s_or_b32 s22, s20, 15
	global_load_dwordx4 v[92:95], v[166:167], off
	s_ashr_i32 s23, s22, 31
	v_lshl_add_u64 v[64:65], v[140:141], 1, s[18:19]
	v_lshl_add_u64 v[136:137], v[134:135], 2, s[38:39]
	s_lshl_b64 s[72:73], s[22:23], 10
	v_lshl_add_u64 v[66:67], v[134:135], 1, s[18:19]
	v_lshl_add_u64 v[130:131], v[126:127], 2, s[38:39]
	global_load_dwordx4 v[88:91], v[136:137], off
	global_load_dwordx4 v[84:87], v[130:131], off
	v_lshl_add_u64 v[68:69], v[126:127], 1, s[18:19]
	v_lshl_add_u64 v[70:71], v[120:121], 1, s[18:19]
	global_load_dwordx2 v[178:179], v[64:65], off
	global_load_dwordx2 v[138:139], v[66:67], off
	global_load_dwordx2 v[132:133], v[68:69], off
	global_load_dwordx2 v[124:125], v[70:71], off
	v_lshl_add_u64 v[96:97], s[72:73], 0, v[128:129]
	v_lshl_add_u64 v[122:123], v[120:121], 2, s[38:39]
	v_lshl_add_u64 v[100:101], v[114:115], 1, s[18:19]
	v_lshl_add_u64 v[110:111], v[108:109], 2, s[38:39]
	v_lshl_add_u64 v[106:107], v[108:109], 1, s[18:19]
	v_lshl_add_u64 v[98:99], v[96:97], 2, s[38:39]
	v_lshl_add_u64 v[116:117], v[114:115], 2, s[38:39]
	global_load_dwordx4 v[80:83], v[122:123], off
	global_load_dwordx4 v[76:79], v[116:117], off
	v_lshl_add_u64 v[104:105], v[102:103], 2, s[38:39]
	global_load_dwordx4 v[72:75], v[110:111], off
	global_load_dwordx4 v[68:71], v[104:105], off
	v_lshl_add_u64 v[174:175], v[102:103], 1, s[18:19]
	global_load_dwordx4 v[64:67], v[98:99], off
	v_lshl_add_u64 v[176:177], v[96:97], 1, s[18:19]
	global_load_dwordx2 v[118:119], v[100:101], off
	global_load_dwordx2 v[112:113], v[106:107], off
	s_nop 0
	global_load_dwordx2 v[106:107], v[174:175], off
	global_load_dwordx2 v[100:101], v[176:177], off
	ds_read_b128 v[174:177], v142 offset:8320
	v_readlane_b32 s21, v165, 8
	s_and_b64 vcc, exec, s[4:5]
	s_waitcnt vmcnt(0) lgkmcnt(0)
	v_lshlrev_b32_e32 v180, 16, v178
	v_mul_f32_e32 v174, s21, v174
	v_mul_f32_e32 v175, s21, v175
	v_mul_f32_e32 v174, 0xbfb8aa3b, v174
	v_mul_f32_e32 v175, 0xbfb8aa3b, v175
	v_exp_f32_e32 v174, v174
	v_exp_f32_e32 v175, v175
	v_mul_f32_e32 v176, s21, v176
	v_mul_f32_e32 v177, s21, v177
	v_mul_f32_e32 v176, 0xbfb8aa3b, v176
	v_mul_f32_e32 v177, 0xbfb8aa3b, v177
	v_exp_f32_e32 v176, v176
	v_add_f32_e32 v174, 1.0, v174
	v_add_f32_e32 v175, 1.0, v175
	v_exp_f32_e32 v177, v177
	v_rcp_f32_e32 v174, v174
	v_rcp_f32_e32 v175, v175
	v_add_f32_e32 v176, 1.0, v176
	v_and_b32_e32 v178, 0xffff0000, v178
	v_fma_f32 v92, v174, v180, v92
	v_fma_f32 v93, v175, v178, v93
	v_rcp_f32_e32 v174, v176
	v_add_f32_e32 v175, 1.0, v177
	v_rcp_f32_e32 v175, v175
	v_lshlrev_b32_e32 v176, 16, v179
	v_fma_f32 v94, v174, v176, v94
	v_and_b32_e32 v174, 0xffff0000, v179
	v_fmac_f32_e32 v95, v175, v174
	global_store_dwordx4 v[166:167], v[92:95], off
	s_cbranch_vccnz .LBB0_1936
	v_cvt_pk_bf16_f32 v166, v92, v93
	v_cvt_pk_bf16_f32 v167, v94, v95
	v_lshl_add_u64 v[140:141], v[140:141], 1, s[8:9]
	global_store_dwordx2 v[140:141], v[166:167], off
.LBB0_1936:
	s_and_b64 vcc, exec, s[6:7]
	s_cbranch_vccnz .LBB0_1940
	v_mul_f32_e32 v93, v93, v93
	v_fmac_f32_e32 v93, v92, v92
	v_fmac_f32_e32 v93, v94, v94
	v_fmac_f32_e32 v93, v95, v95
	s_nop 1
	v_add_f32_dpp v92, v93, v93 row_ror:8 row_mask:0xf bank_mask:0xf bound_ctrl:1
	s_nop 1
	v_add_f32_dpp v92, v92, v92 row_ror:4 row_mask:0xf bank_mask:0xf bound_ctrl:1
	s_nop 1
	v_add_f32_dpp v92, v92, v92 row_ror:2 row_mask:0xf bank_mask:0xf bound_ctrl:1
	s_nop 1
	v_add_f32_dpp v92, v92, v92 row_ror:1 row_mask:0xf bank_mask:0xf bound_ctrl:1
	s_nop 0
	v_readlane_b32 s21, v92, 0
	v_readlane_b32 s82, v92, 16
	v_readlane_b32 s80, v92, 32
	v_readlane_b32 s81, v92, 48
	s_and_saveexec_b64 s[72:73], s[0:1]
	s_cbranch_execz .LBB0_1939
	s_lshl_b64 s[70:71], s[70:71], 2
	v_mov_b32_e32 v92, s82
	s_add_u32 s70, s76, s70
	v_add_f32_e32 v92, s21, v92
	s_addc_u32 s71, s77, s71
	v_add_f32_e32 v92, s80, v92
	v_add_f32_e32 v94, s81, v92
	v_mov_b64_e32 v[92:93], s[70:71]
	global_atomic_add_f32 v[92:93], v94, off

; DEVI float fsig(float x) { return __builtin_amdgcn_rcpf(1.f + __expf(-x)); }
; DEVI float bflo(unsigned u) { return __uint_as_float(u << 16); }
; DEVI float bfhi(unsigned u) { return __uint_as_float(u & 0xffff0000u); }
; template <int EPI, int TS, bool VT>
; DEVI void gemm_epilogue(const Params& p, char* smem, f32x4 (&acc)[2][2][4][2], int m0, int n0, float scale, const float* ssin,
;                         float* ssout, u16* xbout, int wid, int lane, int wr, int wc, int fr, int fq) {
;     ...
;           const float rs = __int_as_float(__builtin_amdgcn_readlane(__float_as_int(rsv), i));
;           if constexpr (EPI == E_RESID || EPI == E_PLEGATE) {
;             const float4 a = *(const float4*)(Tr + 4 * lane);
;             const size_t ro = (size_t)grow * 1024 + n0 + 4 * lane;
;             float4 x4 = xo[u];
;             if constexpr (EPI == E_PLEGATE) {
;               x4.x += bflo(pv[u].x) * fsig(a.x * rs);
;               x4.y += bfhi(pv[u].x) * fsig(a.y * rs);
;               x4.z += bflo(pv[u].y) * fsig(a.z * rs);
;               x4.w += bfhi(pv[u].y) * fsig(a.w * rs);
;             } else {
;               const float sc = fabsf(scale);
;               x4.x += sc * a.x; x4.y += sc * a.y; x4.z += sc * a.z; x4.w += sc * a.w;
;             }
;             st_nt16(p.x + ro, x4);
;             if (xbout) {
;               uint2 o;
;               o.x = pack2(x4.x, x4.y);
;               o.y = pack2(x4.z, x4.w);
;               st_nt8(xbout + ro, o);
;             }
.LBB0_1940:
	ds_read_b128 v[92:95], v142 offset:9360
	v_readlane_b32 s21, v165, 9
	s_and_b64 vcc, exec, s[4:5]
	s_waitcnt lgkmcnt(0)
	v_mul_f32_e32 v92, s21, v92
	v_mul_f32_e32 v93, s21, v93
	v_mul_f32_e32 v92, 0xbfb8aa3b, v92
	v_mul_f32_e32 v93, 0xbfb8aa3b, v93
	v_mul_f32_e32 v94, s21, v94
	v_mul_f32_e32 v95, s21, v95
	v_exp_f32_e32 v140, v92
	v_exp_f32_e32 v141, v93
	v_mul_f32_e32 v94, 0xbfb8aa3b, v94
	v_mul_f32_e32 v95, 0xbfb8aa3b, v95
	v_exp_f32_e32 v94, v94
	v_exp_f32_e32 v95, v95
	v_lshlrev_b32_e32 v92, 16, v138
	v_and_b32_e32 v93, 0xffff0000, v138
	v_add_f32_e32 v138, 1.0, v140
	v_add_f32_e32 v141, 1.0, v141
	v_rcp_f32_e32 v140, v138
	v_rcp_f32_e32 v141, v141
	v_add_f32_e32 v94, 1.0, v94
	v_add_f32_e32 v95, 1.0, v95
	v_rcp_f32_e32 v94, v94
	v_rcp_f32_e32 v95, v95
	v_pk_fma_f32 v[88:89], v[140:141], v[92:93], v[88:89]
	v_lshlrev_b32_e32 v92, 16, v139
	v_and_b32_e32 v93, 0xffff0000, v139
	v_pk_fma_f32 v[90:91], v[94:95], v[92:93], v[90:91]
	global_store_dwordx4 v[136:137], v[88:91], off
	s_cbranch_vccnz .LBB0_1942
	v_cvt_pk_bf16_f32 v92, v88, v89
	v_cvt_pk_bf16_f32 v93, v90, v91
	v_lshl_add_u64 v[94:95], v[134:135], 1, s[8:9]
	global_store_dwordx2 v[94:95], v[92:93], off

; DEVI float fsig(float x) { return __builtin_amdgcn_rcpf(1.f + __expf(-x)); }
; DEVI float bflo(unsigned u) { return __uint_as_float(u << 16); }
; DEVI float bfhi(unsigned u) { return __uint_as_float(u & 0xffff0000u); }
; template <int EPI, int TS, bool VT>
; DEVI void gemm_epilogue(const Params& p, char* smem, f32x4 (&acc)[2][2][4][2], int m0, int n0, float scale, const float* ssin,
;                         float* ssout, u16* xbout, int wid, int lane, int wr, int wc, int fr, int fq) {
;     ...
;           const float rs = __int_as_float(__builtin_amdgcn_readlane(__float_as_int(rsv), i));
;           if constexpr (EPI == E_RESID || EPI == E_PLEGATE) {
;             const float4 a = *(const float4*)(Tr + 4 * lane);
;             const size_t ro = (size_t)grow * 1024 + n0 + 4 * lane;
;             float4 x4 = xo[u];
;             if constexpr (EPI == E_PLEGATE) {
;               x4.x += bflo(pv[u].x) * fsig(a.x * rs);
;               x4.y += bfhi(pv[u].x) * fsig(a.y * rs);
;               x4.z += bflo(pv[u].y) * fsig(a.z * rs);
;               x4.w += bfhi(pv[u].y) * fsig(a.w * rs);
;             } else {
;               const float sc = fabsf(scale);
;               x4.x += sc * a.x; x4.y += sc * a.y; x4.z += sc * a.z; x4.w += sc * a.w;
;             }
;             st_nt16(p.x + ro, x4);
;             if (xbout) {
;               uint2 o;
;               o.x = pack2(x4.x, x4.y);
;               o.y = pack2(x4.z, x4.w);
;               st_nt8(xbout + ro, o);
;             }
.LBB0_1946:
	ds_read_b128 v[88:91], v142 offset:10400
	v_readlane_b32 s21, v165, 10
	s_and_b64 vcc, exec, s[4:5]
	s_waitcnt lgkmcnt(0)
	v_mul_f32_e32 v88, s21, v88
	v_mul_f32_e32 v89, s21, v89
	v_mul_f32_e32 v88, 0xbfb8aa3b, v88
	v_mul_f32_e32 v89, 0xbfb8aa3b, v89
	v_mul_f32_e32 v90, s21, v90
	v_mul_f32_e32 v91, s21, v91
	v_exp_f32_e32 v92, v88
	v_exp_f32_e32 v93, v89
	v_mul_f32_e32 v90, 0xbfb8aa3b, v90
	v_mul_f32_e32 v91, 0xbfb8aa3b, v91
	v_exp_f32_e32 v90, v90
	v_exp_f32_e32 v91, v91
	v_add_f32_e32 v92, 1.0, v92
	v_add_f32_e32 v93, 1.0, v93
	v_rcp_f32_e32 v92, v92
	v_rcp_f32_e32 v93, v93
	v_add_f32_e32 v90, 1.0, v90
	v_add_f32_e32 v91, 1.0, v91
	v_rcp_f32_e32 v90, v90
	v_rcp_f32_e32 v91, v91
	v_lshlrev_b32_e32 v88, 16, v132
	v_and_b32_e32 v89, 0xffff0000, v132
	v_pk_fma_f32 v[84:85], v[92:93], v[88:89], v[84:85]
	v_lshlrev_b32_e32 v88, 16, v133
	v_and_b32_e32 v89, 0xffff0000, v133
	v_pk_fma_f32 v[86:87], v[90:91], v[88:89], v[86:87]
	global_store_dwordx4 v[130:131], v[84:87], off
	s_cbranch_vccnz .LBB0_1948
	v_cvt_pk_bf16_f32 v88, v84, v85
	v_cvt_pk_bf16_f32 v89, v86, v87
	v_lshl_add_u64 v[90:91], v[126:127], 1, s[8:9]
	global_store_dwordx2 v[90:91], v[88:89], off

; DEVI float fsig(float x) { return __builtin_amdgcn_rcpf(1.f + __expf(-x)); }
; DEVI float bflo(unsigned u) { return __uint_as_float(u << 16); }
; DEVI float bfhi(unsigned u) { return __uint_as_float(u & 0xffff0000u); }
; template <int EPI, int TS, bool VT>
; DEVI void gemm_epilogue(const Params& p, char* smem, f32x4 (&acc)[2][2][4][2], int m0, int n0, float scale, const float* ssin,
;                         float* ssout, u16* xbout, int wid, int lane, int wr, int wc, int fr, int fq) {
;     ...
;           const float rs = __int_as_float(__builtin_amdgcn_readlane(__float_as_int(rsv), i));
;           if constexpr (EPI == E_RESID || EPI == E_PLEGATE) {
;             const float4 a = *(const float4*)(Tr + 4 * lane);
;             const size_t ro = (size_t)grow * 1024 + n0 + 4 * lane;
;             float4 x4 = xo[u];
;             if constexpr (EPI == E_PLEGATE) {
;               x4.x += bflo(pv[u].x) * fsig(a.x * rs);
;               x4.y += bfhi(pv[u].x) * fsig(a.y * rs);
;               x4.z += bflo(pv[u].y) * fsig(a.z * rs);
;               x4.w += bfhi(pv[u].y) * fsig(a.w * rs);
;             } else {
;               const float sc = fabsf(scale);
;               x4.x += sc * a.x; x4.y += sc * a.y; x4.z += sc * a.z; x4.w += sc * a.w;
;             }
;             st_nt16(p.x + ro, x4);
;             if (xbout) {
;               uint2 o;
;               o.x = pack2(x4.x, x4.y);
;               o.y = pack2(x4.z, x4.w);
;               st_nt8(xbout + ro, o);
;             }
.LBB0_1952:
	ds_read_b128 v[84:87], v142 offset:11440
	v_readlane_b32 s21, v165, 11
	s_and_b64 vcc, exec, s[4:5]
	s_waitcnt lgkmcnt(0)
	v_mul_f32_e32 v84, s21, v84
	v_mul_f32_e32 v85, s21, v85
	v_mul_f32_e32 v84, 0xbfb8aa3b, v84
	v_mul_f32_e32 v85, 0xbfb8aa3b, v85
	v_mul_f32_e32 v86, s21, v86
	v_mul_f32_e32 v87, s21, v87
	v_exp_f32_e32 v88, v84
	v_exp_f32_e32 v89, v85
	v_mul_f32_e32 v86, 0xbfb8aa3b, v86
	v_mul_f32_e32 v87, 0xbfb8aa3b, v87
	v_exp_f32_e32 v86, v86
	v_exp_f32_e32 v87, v87
	v_add_f32_e32 v88, 1.0, v88
	v_add_f32_e32 v89, 1.0, v89
	v_rcp_f32_e32 v88, v88
	v_rcp_f32_e32 v89, v89
	v_add_f32_e32 v86, 1.0, v86
	v_add_f32_e32 v87, 1.0, v87
	v_rcp_f32_e32 v86, v86
	v_rcp_f32_e32 v87, v87
	v_lshlrev_b32_e32 v84, 16, v124
	v_and_b32_e32 v85, 0xffff0000, v124
	v_pk_fma_f32 v[80:81], v[88:89], v[84:85], v[80:81]
	v_lshlrev_b32_e32 v84, 16, v125
	v_and_b32_e32 v85, 0xffff0000, v125
	v_pk_fma_f32 v[82:83], v[86:87], v[84:85], v[82:83]
	global_store_dwordx4 v[122:123], v[80:83], off
	s_cbranch_vccnz .LBB0_1954
	v_cvt_pk_bf16_f32 v84, v80, v81
	v_cvt_pk_bf16_f32 v85, v82, v83
	v_lshl_add_u64 v[86:87], v[120:121], 1, s[8:9]
	global_store_dwordx2 v[86:87], v[84:85], off

; DEVI float fsig(float x) { return __builtin_amdgcn_rcpf(1.f + __expf(-x)); }
; DEVI float bflo(unsigned u) { return __uint_as_float(u << 16); }
; DEVI float bfhi(unsigned u) { return __uint_as_float(u & 0xffff0000u); }
; template <int EPI, int TS, bool VT>
; DEVI void gemm_epilogue(const Params& p, char* smem, f32x4 (&acc)[2][2][4][2], int m0, int n0, float scale, const float* ssin,
;                         float* ssout, u16* xbout, int wid, int lane, int wr, int wc, int fr, int fq) {
;     ...
;           const float rs = __int_as_float(__builtin_amdgcn_readlane(__float_as_int(rsv), i));
;           if constexpr (EPI == E_RESID || EPI == E_PLEGATE) {
;             const float4 a = *(const float4*)(Tr + 4 * lane);
;             const size_t ro = (size_t)grow * 1024 + n0 + 4 * lane;
;             float4 x4 = xo[u];
;             if constexpr (EPI == E_PLEGATE) {
;               x4.x += bflo(pv[u].x) * fsig(a.x * rs);
;               x4.y += bfhi(pv[u].x) * fsig(a.y * rs);
;               x4.z += bflo(pv[u].y) * fsig(a.z * rs);
;               x4.w += bfhi(pv[u].y) * fsig(a.w * rs);
;             } else {
;               const float sc = fabsf(scale);
;               x4.x += sc * a.x; x4.y += sc * a.y; x4.z += sc * a.z; x4.w += sc * a.w;
;             }
;             st_nt16(p.x + ro, x4);
;             if (xbout) {
;               uint2 o;
;               o.x = pack2(x4.x, x4.y);
;               o.y = pack2(x4.z, x4.w);
;               st_nt8(xbout + ro, o);
;             }
.LBB0_1958:
	ds_read_b128 v[80:83], v142 offset:12480
	v_readlane_b32 s21, v165, 12
	s_and_b64 vcc, exec, s[4:5]
	s_waitcnt lgkmcnt(0)
	v_mul_f32_e32 v80, s21, v80
	v_mul_f32_e32 v81, s21, v81
	v_mul_f32_e32 v80, 0xbfb8aa3b, v80
	v_mul_f32_e32 v81, 0xbfb8aa3b, v81
	v_mul_f32_e32 v82, s21, v82
	v_mul_f32_e32 v83, s21, v83
	v_exp_f32_e32 v84, v80
	v_exp_f32_e32 v85, v81
	v_mul_f32_e32 v82, 0xbfb8aa3b, v82
	v_mul_f32_e32 v83, 0xbfb8aa3b, v83
	v_exp_f32_e32 v82, v82
	v_exp_f32_e32 v83, v83
	v_add_f32_e32 v84, 1.0, v84
	v_add_f32_e32 v85, 1.0, v85
	v_rcp_f32_e32 v84, v84
	v_rcp_f32_e32 v85, v85
	v_add_f32_e32 v82, 1.0, v82
	v_add_f32_e32 v83, 1.0, v83
	v_rcp_f32_e32 v82, v82
	v_rcp_f32_e32 v83, v83
	v_lshlrev_b32_e32 v80, 16, v118
	v_and_b32_e32 v81, 0xffff0000, v118
	v_pk_fma_f32 v[76:77], v[84:85], v[80:81], v[76:77]
	v_lshlrev_b32_e32 v80, 16, v119
	v_and_b32_e32 v81, 0xffff0000, v119
	v_pk_fma_f32 v[78:79], v[82:83], v[80:81], v[78:79]
	global_store_dwordx4 v[116:117], v[76:79], off
	s_cbranch_vccnz .LBB0_1960
	v_cvt_pk_bf16_f32 v80, v76, v77
	v_cvt_pk_bf16_f32 v81, v78, v79
	v_lshl_add_u64 v[82:83], v[114:115], 1, s[8:9]
	global_store_dwordx2 v[82:83], v[80:81], off

; DEVI float fsig(float x) { return __builtin_amdgcn_rcpf(1.f + __expf(-x)); }
; DEVI float bflo(unsigned u) { return __uint_as_float(u << 16); }
; DEVI float bfhi(unsigned u) { return __uint_as_float(u & 0xffff0000u); }
; template <int EPI, int TS, bool VT>
; DEVI void gemm_epilogue(const Params& p, char* smem, f32x4 (&acc)[2][2][4][2], int m0, int n0, float scale, const float* ssin,
;                         float* ssout, u16* xbout, int wid, int lane, int wr, int wc, int fr, int fq) {
;     ...
;           const float rs = __int_as_float(__builtin_amdgcn_readlane(__float_as_int(rsv), i));
;           if constexpr (EPI == E_RESID || EPI == E_PLEGATE) {
;             const float4 a = *(const float4*)(Tr + 4 * lane);
;             const size_t ro = (size_t)grow * 1024 + n0 + 4 * lane;
;             float4 x4 = xo[u];
;             if constexpr (EPI == E_PLEGATE) {
;               x4.x += bflo(pv[u].x) * fsig(a.x * rs);
;               x4.y += bfhi(pv[u].x) * fsig(a.y * rs);
;               x4.z += bflo(pv[u].y) * fsig(a.z * rs);
;               x4.w += bfhi(pv[u].y) * fsig(a.w * rs);
;             } else {
;               const float sc = fabsf(scale);
;               x4.x += sc * a.x; x4.y += sc * a.y; x4.z += sc * a.z; x4.w += sc * a.w;
;             }
;             st_nt16(p.x + ro, x4);
;             if (xbout) {
;               uint2 o;
;               o.x = pack2(x4.x, x4.y);
;               o.y = pack2(x4.z, x4.w);
;               st_nt8(xbout + ro, o);
;             }
.LBB0_1964:
	ds_read_b128 v[76:79], v142 offset:13520
	v_readlane_b32 s21, v165, 13
	s_and_b64 vcc, exec, s[4:5]
	s_waitcnt lgkmcnt(0)
	v_mul_f32_e32 v76, s21, v76
	v_mul_f32_e32 v77, s21, v77
	v_mul_f32_e32 v76, 0xbfb8aa3b, v76
	v_mul_f32_e32 v77, 0xbfb8aa3b, v77
	v_mul_f32_e32 v78, s21, v78
	v_mul_f32_e32 v79, s21, v79
	v_exp_f32_e32 v80, v76
	v_exp_f32_e32 v81, v77
	v_mul_f32_e32 v78, 0xbfb8aa3b, v78
	v_mul_f32_e32 v79, 0xbfb8aa3b, v79
	v_exp_f32_e32 v78, v78
	v_exp_f32_e32 v79, v79
	v_add_f32_e32 v80, 1.0, v80
	v_add_f32_e32 v81, 1.0, v81
	v_rcp_f32_e32 v80, v80
	v_rcp_f32_e32 v81, v81
	v_add_f32_e32 v78, 1.0, v78
	v_add_f32_e32 v79, 1.0, v79
	v_rcp_f32_e32 v78, v78
	v_rcp_f32_e32 v79, v79
	v_lshlrev_b32_e32 v76, 16, v112
	v_and_b32_e32 v77, 0xffff0000, v112
	v_pk_fma_f32 v[72:73], v[80:81], v[76:77], v[72:73]
	v_lshlrev_b32_e32 v76, 16, v113
	v_and_b32_e32 v77, 0xffff0000, v113
	v_pk_fma_f32 v[74:75], v[78:79], v[76:77], v[74:75]
	global_store_dwordx4 v[110:111], v[72:75], off
	s_cbranch_vccnz .LBB0_1966
	v_cvt_pk_bf16_f32 v76, v72, v73
	v_cvt_pk_bf16_f32 v77, v74, v75
	v_lshl_add_u64 v[78:79], v[108:109], 1, s[8:9]
	global_store_dwordx2 v[78:79], v[76:77], off

; DEVI float fsig(float x) { return __builtin_amdgcn_rcpf(1.f + __expf(-x)); }
; DEVI float bflo(unsigned u) { return __uint_as_float(u << 16); }
; DEVI float bfhi(unsigned u) { return __uint_as_float(u & 0xffff0000u); }
; template <int EPI, int TS, bool VT>
; DEVI void gemm_epilogue(const Params& p, char* smem, f32x4 (&acc)[2][2][4][2], int m0, int n0, float scale, const float* ssin,
;                         float* ssout, u16* xbout, int wid, int lane, int wr, int wc, int fr, int fq) {
;     ...
;           const float rs = __int_as_float(__builtin_amdgcn_readlane(__float_as_int(rsv), i));
;           if constexpr (EPI == E_RESID || EPI == E_PLEGATE) {
;             const float4 a = *(const float4*)(Tr + 4 * lane);
;             const size_t ro = (size_t)grow * 1024 + n0 + 4 * lane;
;             float4 x4 = xo[u];
;             if constexpr (EPI == E_PLEGATE) {
;               x4.x += bflo(pv[u].x) * fsig(a.x * rs);
;               x4.y += bfhi(pv[u].x) * fsig(a.y * rs);
;               x4.z += bflo(pv[u].y) * fsig(a.z * rs);
;               x4.w += bfhi(pv[u].y) * fsig(a.w * rs);
;             } else {
;               const float sc = fabsf(scale);
;               x4.x += sc * a.x; x4.y += sc * a.y; x4.z += sc * a.z; x4.w += sc * a.w;
;             }
;             st_nt16(p.x + ro, x4);
;             if (xbout) {
;               uint2 o;
;               o.x = pack2(x4.x, x4.y);
;               o.y = pack2(x4.z, x4.w);
;               st_nt8(xbout + ro, o);
;             }
.LBB0_1970:
	ds_read_b128 v[72:75], v142 offset:14560
	v_readlane_b32 s21, v165, 14
	s_and_b64 vcc, exec, s[4:5]
	s_waitcnt lgkmcnt(0)
	v_mul_f32_e32 v72, s21, v72
	v_mul_f32_e32 v73, s21, v73
	v_mul_f32_e32 v72, 0xbfb8aa3b, v72
	v_mul_f32_e32 v73, 0xbfb8aa3b, v73
	v_mul_f32_e32 v74, s21, v74
	v_mul_f32_e32 v75, s21, v75
	v_exp_f32_e32 v76, v72
	v_exp_f32_e32 v77, v73
	v_mul_f32_e32 v74, 0xbfb8aa3b, v74
	v_mul_f32_e32 v75, 0xbfb8aa3b, v75
	v_exp_f32_e32 v74, v74
	v_exp_f32_e32 v75, v75
	v_add_f32_e32 v76, 1.0, v76
	v_add_f32_e32 v77, 1.0, v77
	v_rcp_f32_e32 v76, v76
	v_rcp_f32_e32 v77, v77
	v_add_f32_e32 v74, 1.0, v74
	v_add_f32_e32 v75, 1.0, v75
	v_rcp_f32_e32 v74, v74
	v_rcp_f32_e32 v75, v75
	v_lshlrev_b32_e32 v72, 16, v106
	v_and_b32_e32 v73, 0xffff0000, v106
	v_pk_fma_f32 v[68:69], v[76:77], v[72:73], v[68:69]
	v_lshlrev_b32_e32 v72, 16, v107
	v_and_b32_e32 v73, 0xffff0000, v107
	v_pk_fma_f32 v[70:71], v[74:75], v[72:73], v[70:71]
	global_store_dwordx4 v[104:105], v[68:71], off
	s_cbranch_vccnz .LBB0_1972
	v_cvt_pk_bf16_f32 v72, v68, v69
	v_cvt_pk_bf16_f32 v73, v70, v71
	v_lshl_add_u64 v[74:75], v[102:103], 1, s[8:9]
	global_store_dwordx2 v[74:75], v[72:73], off

; DEVI float fsig(float x) { return __builtin_amdgcn_rcpf(1.f + __expf(-x)); }
; DEVI float bflo(unsigned u) { return __uint_as_float(u << 16); }
; DEVI float bfhi(unsigned u) { return __uint_as_float(u & 0xffff0000u); }
; template <int EPI, int TS, bool VT>
; DEVI void gemm_epilogue(const Params& p, char* smem, f32x4 (&acc)[2][2][4][2], int m0, int n0, float scale, const float* ssin,
;                         float* ssout, u16* xbout, int wid, int lane, int wr, int wc, int fr, int fq) {
;     ...
;           const float rs = __int_as_float(__builtin_amdgcn_readlane(__float_as_int(rsv), i));
;           if constexpr (EPI == E_RESID || EPI == E_PLEGATE) {
;             const float4 a = *(const float4*)(Tr + 4 * lane);
;             const size_t ro = (size_t)grow * 1024 + n0 + 4 * lane;
;             float4 x4 = xo[u];
;             if constexpr (EPI == E_PLEGATE) {
;               x4.x += bflo(pv[u].x) * fsig(a.x * rs);
;               x4.y += bfhi(pv[u].x) * fsig(a.y * rs);
;               x4.z += bflo(pv[u].y) * fsig(a.z * rs);
;               x4.w += bfhi(pv[u].y) * fsig(a.w * rs);
;             } else {
;               const float sc = fabsf(scale);
;               x4.x += sc * a.x; x4.y += sc * a.y; x4.z += sc * a.z; x4.w += sc * a.w;
;             }
;             st_nt16(p.x + ro, x4);
;             if (xbout) {
;               uint2 o;
;               o.x = pack2(x4.x, x4.y);
;               o.y = pack2(x4.z, x4.w);
;               st_nt8(xbout + ro, o);
;             }
.LBB0_1976:
	ds_read_b128 v[68:71], v142 offset:15600
	v_readlane_b32 s21, v165, 15
	s_and_b64 vcc, exec, s[4:5]
	s_waitcnt lgkmcnt(0)
	v_mul_f32_e32 v68, s21, v68
	v_mul_f32_e32 v69, s21, v69
	v_mul_f32_e32 v68, 0xbfb8aa3b, v68
	v_mul_f32_e32 v69, 0xbfb8aa3b, v69
	v_mul_f32_e32 v70, s21, v70
	v_mul_f32_e32 v71, s21, v71
	v_exp_f32_e32 v72, v68
	v_exp_f32_e32 v73, v69
	v_mul_f32_e32 v70, 0xbfb8aa3b, v70
	v_mul_f32_e32 v71, 0xbfb8aa3b, v71
	v_exp_f32_e32 v70, v70
	v_exp_f32_e32 v71, v71
	v_add_f32_e32 v72, 1.0, v72
	v_add_f32_e32 v73, 1.0, v73
	v_rcp_f32_e32 v72, v72
	v_rcp_f32_e32 v73, v73
	v_add_f32_e32 v70, 1.0, v70
	v_add_f32_e32 v71, 1.0, v71
	v_rcp_f32_e32 v70, v70
	v_rcp_f32_e32 v71, v71
	v_lshlrev_b32_e32 v68, 16, v100
	v_and_b32_e32 v69, 0xffff0000, v100
	v_pk_fma_f32 v[64:65], v[72:73], v[68:69], v[64:65]
	v_lshlrev_b32_e32 v68, 16, v101
	v_and_b32_e32 v69, 0xffff0000, v101
	v_pk_fma_f32 v[66:67], v[70:71], v[68:69], v[66:67]
	global_store_dwordx4 v[98:99], v[64:67], off
	s_cbranch_vccnz .LBB0_1978
	v_cvt_pk_bf16_f32 v68, v64, v65
	v_cvt_pk_bf16_f32 v69, v66, v67
	v_lshl_add_u64 v[70:71], v[96:97], 1, s[8:9]
	global_store_dwordx2 v[70:71], v[68:69], off

; template <int EPI, int TS, bool VT>
; DEVI void gemm_epilogue(const Params& p, char* smem, f32x4 (&acc)[2][2][4][2], int m0, int n0, float scale, const float* ssin,
;                         float* ssout, u16* xbout, int wid, int lane, int wr, int wc, int fr, int fq) {
;     ...
;       float* tw = T + (wr * 64 + fq * 4) * TS + wc * 32 + fr;
; #pragma unroll
;       for (int m = 0; m < 4; ++m)
; #pragma unroll
;         for (int j = 0; j < 4; ++j)
; #pragma unroll
;           for (int v = 0; v < 4; ++v) tw[(m * 16 + j) * TS + (v >> 1) * 128 + (v & 1) * 16] = acc[ai][v >> 1][m][v & 1][j];
;     }
;     __syncthreads();
;     const int r0 = wid * 16;
;     const int g0 = m0 + ai * 128 + r0;
;     if constexpr (!VT) {
;       float rsv = 1.f;
;       if constexpr (EPI == E_PLEGATE || EPI == E_F32 || EPI == E_SWIGLU || EPI == E_GLAIN)
;         rsv = rsqrtf(ssin[g0 + (lane & 15)] * (1.f / 1024.f) + EPS);
;     ...
;         if constexpr (EPI == E_RESID || EPI == E_PLEGATE) {
; #pragma unroll
;           for (int u = 0; u < 8; ++u) {
;             const size_t ro = (size_t)(g0 + i0 + u) * 1024 + n0 + 4 * lane;
;             const int gr = g0 + i0 + u;
;             const float* xs = p.x + ro;
;             if (scale < 0.f)
;               xs = (gr < MP ? p.x_prompt + ro : p.x_sample + (ro - (size_t)MP * 1024));
;             { const f32x4 t_ = __builtin_nontemporal_load((const f32x4*)xs); xo[u] = make_float4(t_[0], t_[1], t_[2], t_[3]); }
;             if constexpr (EPI == E_PLEGATE) {
;               const unsigned long long t2_ = __builtin_nontemporal_load((const unsigned long long*)((const u16*)(wsb + OFF_PP) + ro));
;               pv[u] = make_uint2((unsigned)t2_, (unsigned)(t2_ >> 32));
;             }
;           }
;         }
; #pragma unroll
;         for (int u = 0; u < 8; ++u) {
;           const int i = i0 + u;
;           const int grow = g0 + i;
;           const float* Tr = T + (r0 + i) * TS;
;           const float rs = __int_as_float(__builtin_amdgcn_readlane(__float_as_int(rsv), i));
;           if constexpr (EPI == E_RESID || EPI == E_PLEGATE) {
;             const float4 a = *(const float4*)(Tr + 4 * lane);
;             const size_t ro = (size_t)grow * 1024 + n0 + 4 * lane;
;             float4 x4 = xo[u];
;             if constexpr (EPI == E_PLEGATE) {
;               x4.x += bflo(pv[u].x) * fsig(a.x * rs);
.LBB0_1982:
	s_add_i32 s70, s20, 0x80
	s_waitcnt lgkmcnt(0)
	s_barrier
	ds_write2_b32 v144, v24, v28 offset1:16
	ds_write2_b32 v144, v56, v60 offset0:128 offset1:144
	ds_write2_b32 v145, v25, v29 offset0:4 offset1:20
	ds_write2_b32 v145, v57, v61 offset0:132 offset1:148
	ds_write2_b32 v146, v26, v30 offset0:8 offset1:24
	ds_write2_b32 v146, v58, v62 offset0:136 offset1:152
	ds_write2_b32 v147, v27, v31 offset0:12 offset1:28
	ds_write2_b32 v147, v59, v63 offset0:140 offset1:156
	ds_write2_b32 v148, v16, v20 offset0:64 offset1:80
	ds_write2_b32 v148, v48, v52 offset0:192 offset1:208
	ds_write2_b32 v152, v17, v21 offset0:68 offset1:84
	ds_write2_b32 v152, v49, v53 offset0:196 offset1:212
	ds_write2_b32 v153, v18, v22 offset0:72 offset1:88
	ds_write2_b32 v153, v50, v54 offset0:200 offset1:216
	ds_write2_b32 v154, v19, v23 offset0:76 offset1:92
	ds_write2_b32 v154, v51, v55 offset0:204 offset1:220
	ds_write2_b32 v155, v8, v12 offset0:128 offset1:144
	ds_write2_b32 v156, v40, v44 offset1:16
	ds_write2_b32 v156, v9, v13 offset0:132 offset1:148
	ds_write2_b32 v157, v41, v45 offset0:4 offset1:20
	ds_write2_b32 v157, v10, v14 offset0:136 offset1:152
	ds_write2_b32 v158, v42, v46 offset0:8 offset1:24
	ds_write2_b32 v158, v11, v15 offset0:140 offset1:156
	ds_write2_b32 v159, v43, v47 offset0:12 offset1:28
	ds_write2_b32 v160, v0, v4 offset0:192 offset1:208
	ds_write2_b32 v161, v32, v36 offset0:64 offset1:80
	ds_write2_b32 v161, v1, v5 offset0:196 offset1:212
	ds_write2_b32 v162, v33, v37 offset0:68 offset1:84
	ds_write2_b32 v162, v2, v6 offset0:200 offset1:216
	ds_write2_b32 v163, v34, v38 offset0:72 offset1:88
	ds_write2_b32 v163, v3, v7 offset0:204 offset1:220
	ds_write2_b32 v164, v35, v39 offset0:76 offset1:92
	v_or_b32_e32 v0, s70, v143
	v_ashrrev_i32_e32 v1, 31, v0
	v_lshl_add_u64 v[0:1], v[0:1], 2, s[2:3]
	s_waitcnt lgkmcnt(0)
	s_barrier
	global_load_dword v80, v[0:1], off
	s_ashr_i32 s71, s70, 31
	s_add_i32 s68, s20, 0x81
	s_lshl_b64 s[22:23], s[70:71], 10
	s_ashr_i32 s69, s68, 31
	s_add_i32 s66, s20, 0x82
	v_lshl_add_u64 v[74:75], s[22:23], 0, v[128:129]
	s_lshl_b64 s[22:23], s[68:69], 10
	s_ashr_i32 s67, s66, 31
	s_add_i32 s64, s20, 0x83
	v_lshl_add_u64 v[82:83], v[74:75], 2, s[38:39]
	v_lshl_add_u64 v[68:69], s[22:23], 0, v[128:129]
	s_lshl_b64 s[22:23], s[66:67], 10
	s_ashr_i32 s65, s64, 31
	global_load_dwordx4 v[28:31], v[82:83], off
	v_lshl_add_u64 v[62:63], s[22:23], 0, v[128:129]
	s_lshl_b64 s[22:23], s[64:65], 10
	v_lshl_add_u64 v[0:1], v[74:75], 1, s[18:19]
	v_lshl_add_u64 v[70:71], v[68:69], 2, s[38:39]
	v_lshl_add_u64 v[56:57], s[22:23], 0, v[128:129]
	s_add_i32 s62, s20, 0x84
	v_lshl_add_u64 v[2:3], v[68:69], 1, s[18:19]
	v_lshl_add_u64 v[64:65], v[62:63], 2, s[38:39]
	global_load_dwordx4 v[24:27], v[70:71], off
	global_load_dwordx4 v[20:23], v[64:65], off
	v_lshl_add_u64 v[4:5], v[62:63], 1, s[18:19]
	v_lshl_add_u64 v[6:7], v[56:57], 1, s[18:19]
	global_load_dwordx2 v[84:85], v[0:1], off
	global_load_dwordx2 v[72:73], v[2:3], off
	global_load_dwordx2 v[66:67], v[4:5], off
	global_load_dwordx2 v[60:61], v[6:7], off
	s_ashr_i32 s63, s62, 31
	s_add_i32 s34, s20, 0x85
	s_lshl_b64 s[22:23], s[62:63], 10
	s_ashr_i32 s35, s34, 31
	s_add_i32 s30, s20, 0x86
	v_lshl_add_u64 v[50:51], s[22:23], 0, v[128:129]
	s_lshl_b64 s[22:23], s[34:35], 10
	s_ashr_i32 s31, s30, 31
	v_lshl_add_u64 v[44:45], s[22:23], 0, v[128:129]
	s_lshl_b64 s[22:23], s[30:31], 10
	v_lshl_add_u64 v[38:39], s[22:23], 0, v[128:129]
	s_add_i32 s22, s20, 0x87
	s_ashr_i32 s23, s22, 31
	s_lshl_b64 s[72:73], s[22:23], 10
	v_lshl_add_u64 v[32:33], s[72:73], 0, v[128:129]
	v_lshl_add_u64 v[58:59], v[56:57], 2, s[38:39]
	v_lshl_add_u64 v[36:37], v[50:51], 1, s[18:19]
	v_lshl_add_u64 v[46:47], v[44:45], 2, s[38:39]
	v_lshl_add_u64 v[42:43], v[44:45], 1, s[18:19]
	v_lshl_add_u64 v[34:35], v[32:33], 2, s[38:39]
	v_lshl_add_u64 v[52:53], v[50:51], 2, s[38:39]
	global_load_dwordx4 v[16:19], v[58:59], off
	global_load_dwordx4 v[12:15], v[52:53], off
	v_lshl_add_u64 v[40:41], v[38:39], 2, s[38:39]
	global_load_dwordx4 v[8:11], v[46:47], off
	global_load_dwordx4 v[4:7], v[40:41], off
	v_lshl_add_u64 v[76:77], v[38:39], 1, s[18:19]
	global_load_dwordx4 v[0:3], v[34:35], off
	v_lshl_add_u64 v[78:79], v[32:33], 1, s[18:19]
	global_load_dwordx2 v[54:55], v[36:37], off
	global_load_dwordx2 v[48:49], v[42:43], off
	s_nop 0
	global_load_dwordx2 v[42:43], v[76:77], off
	global_load_dwordx2 v[36:37], v[78:79], off
	s_waitcnt vmcnt(0) lgkmcnt(0)
	v_fmamk_f32 v76, v80, 0x3a800000, v150
	v_mul_f32_e32 v77, 0x4b800000, v76
	v_cmp_gt_f32_e32 vcc, s29, v76
	ds_read_b128 v[78:81], v142
	s_nop 0
	v_cndmask_b32_e32 v76, v76, v77, vcc
	v_rsq_f32_e32 v76, v76
	s_nop 0
	v_mul_f32_e32 v77, 0x45800000, v76
	v_cndmask_b32_e32 v76, v76, v77, vcc
	s_and_b64 vcc, exec, s[4:5]
	v_readlane_b32 s21, v76, 0
	s_waitcnt lgkmcnt(0)
	s_nop 0
	v_mul_f32_e32 v77, s21, v78
	v_mul_f32_e32 v77, 0xbfb8aa3b, v77
	v_exp_f32_e32 v77, v77
	v_mul_f32_e32 v78, s21, v79
	v_mul_f32_e32 v78, 0xbfb8aa3b, v78
	v_exp_f32_e32 v78, v78
	v_add_f32_e32 v77, 1.0, v77
	v_rcp_f32_e32 v77, v77
	v_lshlrev_b32_e32 v79, 16, v84
	v_add_f32_e32 v78, 1.0, v78
	v_rcp_f32_e32 v78, v78
	v_fma_f32 v28, v77, v79, v28
	v_mul_f32_e32 v79, s21, v80
	v_mul_f32_e32 v79, 0xbfb8aa3b, v79
	v_mul_f32_e32 v80, s21, v81
	v_exp_f32_e32 v79, v79
	v_mul_f32_e32 v80, 0xbfb8aa3b, v80
	v_exp_f32_e32 v80, v80
	v_and_b32_e32 v77, 0xffff0000, v84
	v_fma_f32 v29, v78, v77, v29
	v_add_f32_e32 v77, 1.0, v79
	v_rcp_f32_e32 v77, v77
	v_add_f32_e32 v78, 1.0, v80
	v_rcp_f32_e32 v78, v78
	v_lshlrev_b32_e32 v79, 16, v85
	v_fma_f32 v30, v77, v79, v30
	v_and_b32_e32 v77, 0xffff0000, v85
	v_fmac_f32_e32 v31, v78, v77
	global_store_dwordx4 v[82:83], v[28:31], off
	s_cbranch_vccnz .LBB0_1984
	v_cvt_pk_bf16_f32 v78, v28, v29
	v_cvt_pk_bf16_f32 v79, v30, v31
	v_lshl_add_u64 v[74:75], v[74:75], 1, s[8:9]
	global_store_dwordx2 v[74:75], v[78:79], off
.LBB0_1984:
	s_and_b64 vcc, exec, s[6:7]
	s_cbranch_vccnz .LBB0_1988
	v_mul_f32_e32 v29, v29, v29
	v_fmac_f32_e32 v29, v28, v28
	v_fmac_f32_e32 v29, v30, v30
	v_fmac_f32_e32 v29, v31, v31
	s_nop 1
	v_add_f32_dpp v28, v29, v29 row_ror:8 row_mask:0xf bank_mask:0xf bound_ctrl:1
	s_nop 1
	v_add_f32_dpp v28, v28, v28 row_ror:4 row_mask:0xf bank_mask:0xf bound_ctrl:1
	s_nop 1
	v_add_f32_dpp v28, v28, v28 row_ror:2 row_mask:0xf bank_mask:0xf bound_ctrl:1
	s_nop 1
	v_add_f32_dpp v28, v28, v28 row_ror:1 row_mask:0xf bank_mask:0xf bound_ctrl:1
	s_nop 0
	v_readlane_b32 s21, v28, 0
	v_readlane_b32 s82, v28, 16
	v_readlane_b32 s80, v28, 32
	v_readlane_b32 s81, v28, 48
	s_and_saveexec_b64 s[72:73], s[0:1]
	s_cbranch_execz .LBB0_1987
	s_lshl_b64 s[70:71], s[70:71], 2
	v_mov_b32_e32 v28, s82
	s_add_u32 s70, s76, s70
	v_add_f32_e32 v28, s21, v28
	s_addc_u32 s71, s77, s71
	v_add_f32_e32 v28, s80, v28
	v_add_f32_e32 v30, s81, v28
	v_mov_b64_e32 v[28:29], s[70:71]
	global_atomic_add_f32 v[28:29], v30, off

; DEVI float fsig(float x) { return __builtin_amdgcn_rcpf(1.f + __expf(-x)); }
; DEVI float bflo(unsigned u) { return __uint_as_float(u << 16); }
; DEVI float bfhi(unsigned u) { return __uint_as_float(u & 0xffff0000u); }
; template <int EPI, int TS, bool VT>
; DEVI void gemm_epilogue(const Params& p, char* smem, f32x4 (&acc)[2][2][4][2], int m0, int n0, float scale, const float* ssin,
;                         float* ssout, u16* xbout, int wid, int lane, int wr, int wc, int fr, int fq) {
;     ...
;           const float rs = __int_as_float(__builtin_amdgcn_readlane(__float_as_int(rsv), i));
;           if constexpr (EPI == E_RESID || EPI == E_PLEGATE) {
;             const float4 a = *(const float4*)(Tr + 4 * lane);
;             const size_t ro = (size_t)grow * 1024 + n0 + 4 * lane;
;             float4 x4 = xo[u];
;             if constexpr (EPI == E_PLEGATE) {
;               x4.x += bflo(pv[u].x) * fsig(a.x * rs);
;               x4.y += bfhi(pv[u].x) * fsig(a.y * rs);
;               x4.z += bflo(pv[u].y) * fsig(a.z * rs);
;               x4.w += bfhi(pv[u].y) * fsig(a.w * rs);
;             } else {
;               const float sc = fabsf(scale);
;               x4.x += sc * a.x; x4.y += sc * a.y; x4.z += sc * a.z; x4.w += sc * a.w;
;             }
;             st_nt16(p.x + ro, x4);
;             if (xbout) {
;               uint2 o;
;               o.x = pack2(x4.x, x4.y);
;               o.y = pack2(x4.z, x4.w);
;               st_nt8(xbout + ro, o);
;             }
;             if (ssout) {
;               const float ssq = wsum(x4.x * x4.x + x4.y * x4.y + x4.z * x4.z + x4.w * x4.w, lane);
;               if (lane == 0) atomicAdd(ssout + grow, ssq);
;             }
.LBB0_1988:
	ds_read_b128 v[28:31], v142 offset:1040
	v_readlane_b32 s21, v76, 1
	s_and_b64 vcc, exec, s[4:5]
	s_waitcnt lgkmcnt(0)
	v_mul_f32_e32 v28, s21, v28
	v_mul_f32_e32 v29, s21, v29
	v_mul_f32_e32 v28, 0xbfb8aa3b, v28
	v_mul_f32_e32 v29, 0xbfb8aa3b, v29
	v_mul_f32_e32 v30, s21, v30
	v_mul_f32_e32 v31, s21, v31
	v_exp_f32_e32 v74, v28
	v_exp_f32_e32 v75, v29
	v_mul_f32_e32 v30, 0xbfb8aa3b, v30
	v_mul_f32_e32 v31, 0xbfb8aa3b, v31
	v_exp_f32_e32 v30, v30
	v_exp_f32_e32 v31, v31
	v_lshlrev_b32_e32 v28, 16, v72
	v_and_b32_e32 v29, 0xffff0000, v72
	v_add_f32_e32 v72, 1.0, v74
	v_add_f32_e32 v75, 1.0, v75
	v_rcp_f32_e32 v74, v72
	v_rcp_f32_e32 v75, v75
	v_add_f32_e32 v30, 1.0, v30
	v_add_f32_e32 v31, 1.0, v31
	v_rcp_f32_e32 v30, v30
	v_rcp_f32_e32 v31, v31
	v_pk_fma_f32 v[24:25], v[74:75], v[28:29], v[24:25]
	v_lshlrev_b32_e32 v28, 16, v73
	v_and_b32_e32 v29, 0xffff0000, v73
	v_pk_fma_f32 v[26:27], v[30:31], v[28:29], v[26:27]
	global_store_dwordx4 v[70:71], v[24:27], off
	s_cbranch_vccnz .LBB0_1990
	v_cvt_pk_bf16_f32 v28, v24, v25
	v_cvt_pk_bf16_f32 v29, v26, v27
	v_lshl_add_u64 v[30:31], v[68:69], 1, s[8:9]
	global_store_dwordx2 v[30:31], v[28:29], off
.LBB0_1990:
	s_and_b64 vcc, exec, s[6:7]
	s_cbranch_vccnz .LBB0_1994
	v_pk_mul_f32 v[24:25], v[24:25], v[24:25]
	v_pk_mul_f32 v[26:27], v[26:27], v[26:27]
	v_add_f32_e32 v24, v24, v25
	v_add_f32_e32 v24, v24, v26
	v_add_f32_e32 v24, v27, v24
	s_nop 1
	v_add_f32_dpp v24, v24, v24 row_ror:8 row_mask:0xf bank_mask:0xf bound_ctrl:1
	s_nop 1
	v_add_f32_dpp v24, v24, v24 row_ror:4 row_mask:0xf bank_mask:0xf bound_ctrl:1
	s_nop 1
	v_add_f32_dpp v24, v24, v24 row_ror:2 row_mask:0xf bank_mask:0xf bound_ctrl:1
	s_nop 1
	v_add_f32_dpp v24, v24, v24 row_ror:1 row_mask:0xf bank_mask:0xf bound_ctrl:1
	s_nop 0
	v_readlane_b32 s21, v24, 0
	v_readlane_b32 s80, v24, 16
	v_readlane_b32 s72, v24, 32
	v_readlane_b32 s73, v24, 48
	s_and_saveexec_b64 s[70:71], s[0:1]
	s_cbranch_execz .LBB0_1993
	s_lshl_b64 s[68:69], s[68:69], 2
	v_mov_b32_e32 v24, s80
	s_add_u32 s68, s76, s68
	v_add_f32_e32 v24, s21, v24
	s_addc_u32 s69, s77, s69
	v_add_f32_e32 v24, s72, v24
	v_add_f32_e32 v26, s73, v24
	v_mov_b64_e32 v[24:25], s[68:69]
	global_atomic_add_f32 v[24:25], v26, off

; DEVI float fsig(float x) { return __builtin_amdgcn_rcpf(1.f + __expf(-x)); }
; DEVI float bflo(unsigned u) { return __uint_as_float(u << 16); }
; DEVI float bfhi(unsigned u) { return __uint_as_float(u & 0xffff0000u); }
; template <int EPI, int TS, bool VT>
; DEVI void gemm_epilogue(const Params& p, char* smem, f32x4 (&acc)[2][2][4][2], int m0, int n0, float scale, const float* ssin,
;                         float* ssout, u16* xbout, int wid, int lane, int wr, int wc, int fr, int fq) {
;     ...
;           const float rs = __int_as_float(__builtin_amdgcn_readlane(__float_as_int(rsv), i));
;           if constexpr (EPI == E_RESID || EPI == E_PLEGATE) {
;             const float4 a = *(const float4*)(Tr + 4 * lane);
;             const size_t ro = (size_t)grow * 1024 + n0 + 4 * lane;
;             float4 x4 = xo[u];
;             if constexpr (EPI == E_PLEGATE) {
;               x4.x += bflo(pv[u].x) * fsig(a.x * rs);
;               x4.y += bfhi(pv[u].x) * fsig(a.y * rs);
;               x4.z += bflo(pv[u].y) * fsig(a.z * rs);
;               x4.w += bfhi(pv[u].y) * fsig(a.w * rs);
;             } else {
;               const float sc = fabsf(scale);
;               x4.x += sc * a.x; x4.y += sc * a.y; x4.z += sc * a.z; x4.w += sc * a.w;
;             }
;             st_nt16(p.x + ro, x4);
;             if (xbout) {
;               uint2 o;
;               o.x = pack2(x4.x, x4.y);
;               o.y = pack2(x4.z, x4.w);
;               st_nt8(xbout + ro, o);
;             }
;             if (ssout) {
;               const float ssq = wsum(x4.x * x4.x + x4.y * x4.y + x4.z * x4.z + x4.w * x4.w, lane);
;               if (lane == 0) atomicAdd(ssout + grow, ssq);
;             }
.LBB0_1994:
	ds_read_b128 v[24:27], v142 offset:2080
	v_readlane_b32 s21, v76, 2
	s_and_b64 vcc, exec, s[4:5]
	s_waitcnt lgkmcnt(0)
	v_mul_f32_e32 v24, s21, v24
	v_mul_f32_e32 v25, s21, v25
	v_mul_f32_e32 v24, 0xbfb8aa3b, v24
	v_mul_f32_e32 v25, 0xbfb8aa3b, v25
	v_mul_f32_e32 v26, s21, v26
	v_mul_f32_e32 v27, s21, v27
	v_exp_f32_e32 v28, v24
	v_exp_f32_e32 v29, v25
	v_mul_f32_e32 v26, 0xbfb8aa3b, v26
	v_mul_f32_e32 v27, 0xbfb8aa3b, v27
	v_exp_f32_e32 v26, v26
	v_exp_f32_e32 v27, v27
	v_add_f32_e32 v28, 1.0, v28
	v_add_f32_e32 v29, 1.0, v29
	v_rcp_f32_e32 v28, v28
	v_rcp_f32_e32 v29, v29
	v_add_f32_e32 v26, 1.0, v26
	v_add_f32_e32 v27, 1.0, v27
	v_rcp_f32_e32 v26, v26
	v_rcp_f32_e32 v27, v27
	v_lshlrev_b32_e32 v24, 16, v66
	v_and_b32_e32 v25, 0xffff0000, v66
	v_pk_fma_f32 v[20:21], v[28:29], v[24:25], v[20:21]
	v_lshlrev_b32_e32 v24, 16, v67
	v_and_b32_e32 v25, 0xffff0000, v67
	v_pk_fma_f32 v[22:23], v[26:27], v[24:25], v[22:23]
	global_store_dwordx4 v[64:65], v[20:23], off
	s_cbranch_vccnz .LBB0_1996
	v_cvt_pk_bf16_f32 v24, v20, v21
	v_cvt_pk_bf16_f32 v25, v22, v23
	v_lshl_add_u64 v[26:27], v[62:63], 1, s[8:9]
	global_store_dwordx2 v[26:27], v[24:25], off
.LBB0_1996:
	s_and_b64 vcc, exec, s[6:7]
	s_cbranch_vccnz .LBB0_2000
	v_pk_mul_f32 v[20:21], v[20:21], v[20:21]
	v_pk_mul_f32 v[22:23], v[22:23], v[22:23]
	v_add_f32_e32 v20, v20, v21
	v_add_f32_e32 v20, v20, v22
	v_add_f32_e32 v20, v23, v20
	s_nop 1
	v_add_f32_dpp v20, v20, v20 row_ror:8 row_mask:0xf bank_mask:0xf bound_ctrl:1
	s_nop 1
	v_add_f32_dpp v20, v20, v20 row_ror:4 row_mask:0xf bank_mask:0xf bound_ctrl:1
	s_nop 1
	v_add_f32_dpp v20, v20, v20 row_ror:2 row_mask:0xf bank_mask:0xf bound_ctrl:1
	s_nop 1
	v_add_f32_dpp v20, v20, v20 row_ror:1 row_mask:0xf bank_mask:0xf bound_ctrl:1
	s_nop 0
	v_readlane_b32 s21, v20, 0
	v_readlane_b32 s72, v20, 16
	v_readlane_b32 s70, v20, 32
	v_readlane_b32 s71, v20, 48
	s_and_saveexec_b64 s[68:69], s[0:1]
	s_cbranch_execz .LBB0_1999
	s_lshl_b64 s[66:67], s[66:67], 2
	v_mov_b32_e32 v20, s72
	s_add_u32 s66, s76, s66
	v_add_f32_e32 v20, s21, v20
	s_addc_u32 s67, s77, s67
	v_add_f32_e32 v20, s70, v20
	v_add_f32_e32 v22, s71, v20
	v_mov_b64_e32 v[20:21], s[66:67]
	global_atomic_add_f32 v[20:21], v22, off

; DEVI float fsig(float x) { return __builtin_amdgcn_rcpf(1.f + __expf(-x)); }
; DEVI float bflo(unsigned u) { return __uint_as_float(u << 16); }
; DEVI float bfhi(unsigned u) { return __uint_as_float(u & 0xffff0000u); }
; template <int EPI, int TS, bool VT>
; DEVI void gemm_epilogue(const Params& p, char* smem, f32x4 (&acc)[2][2][4][2], int m0, int n0, float scale, const float* ssin,
;                         float* ssout, u16* xbout, int wid, int lane, int wr, int wc, int fr, int fq) {
;     ...
;           const float rs = __int_as_float(__builtin_amdgcn_readlane(__float_as_int(rsv), i));
;           if constexpr (EPI == E_RESID || EPI == E_PLEGATE) {
;             const float4 a = *(const float4*)(Tr + 4 * lane);
;             const size_t ro = (size_t)grow * 1024 + n0 + 4 * lane;
;             float4 x4 = xo[u];
;             if constexpr (EPI == E_PLEGATE) {
;               x4.x += bflo(pv[u].x) * fsig(a.x * rs);
;               x4.y += bfhi(pv[u].x) * fsig(a.y * rs);
;               x4.z += bflo(pv[u].y) * fsig(a.z * rs);
;               x4.w += bfhi(pv[u].y) * fsig(a.w * rs);
;             } else {
;               const float sc = fabsf(scale);
;               x4.x += sc * a.x; x4.y += sc * a.y; x4.z += sc * a.z; x4.w += sc * a.w;
;             }
;             st_nt16(p.x + ro, x4);
;             if (xbout) {
;               uint2 o;
;               o.x = pack2(x4.x, x4.y);
;               o.y = pack2(x4.z, x4.w);
;               st_nt8(xbout + ro, o);
;             }
;             if (ssout) {
;               const float ssq = wsum(x4.x * x4.x + x4.y * x4.y + x4.z * x4.z + x4.w * x4.w, lane);
;               if (lane == 0) atomicAdd(ssout + grow, ssq);
;             }
.LBB0_2000:
	ds_read_b128 v[20:23], v142 offset:3120
	v_readlane_b32 s21, v76, 3
	s_and_b64 vcc, exec, s[4:5]
	s_waitcnt lgkmcnt(0)
	v_mul_f32_e32 v20, s21, v20
	v_mul_f32_e32 v21, s21, v21
	v_mul_f32_e32 v20, 0xbfb8aa3b, v20
	v_mul_f32_e32 v21, 0xbfb8aa3b, v21
	v_mul_f32_e32 v22, s21, v22
	v_mul_f32_e32 v23, s21, v23
	v_exp_f32_e32 v24, v20
	v_exp_f32_e32 v25, v21
	v_mul_f32_e32 v22, 0xbfb8aa3b, v22
	v_mul_f32_e32 v23, 0xbfb8aa3b, v23
	v_exp_f32_e32 v22, v22
	v_exp_f32_e32 v23, v23
	v_add_f32_e32 v24, 1.0, v24
	v_add_f32_e32 v25, 1.0, v25
	v_rcp_f32_e32 v24, v24
	v_rcp_f32_e32 v25, v25
	v_add_f32_e32 v22, 1.0, v22
	v_add_f32_e32 v23, 1.0, v23
	v_rcp_f32_e32 v22, v22
	v_rcp_f32_e32 v23, v23
	v_lshlrev_b32_e32 v20, 16, v60
	v_and_b32_e32 v21, 0xffff0000, v60
	v_pk_fma_f32 v[16:17], v[24:25], v[20:21], v[16:17]
	v_lshlrev_b32_e32 v20, 16, v61
	v_and_b32_e32 v21, 0xffff0000, v61
	v_pk_fma_f32 v[18:19], v[22:23], v[20:21], v[18:19]
	global_store_dwordx4 v[58:59], v[16:19], off
	s_cbranch_vccnz .LBB0_2002
	v_cvt_pk_bf16_f32 v20, v16, v17
	v_cvt_pk_bf16_f32 v21, v18, v19
	v_lshl_add_u64 v[22:23], v[56:57], 1, s[8:9]
	global_store_dwordx2 v[22:23], v[20:21], off
.LBB0_2002:
	s_and_b64 vcc, exec, s[6:7]
	s_cbranch_vccnz .LBB0_2006
	v_pk_mul_f32 v[16:17], v[16:17], v[16:17]
	v_pk_mul_f32 v[18:19], v[18:19], v[18:19]
	v_add_f32_e32 v16, v16, v17
	v_add_f32_e32 v16, v16, v18
	v_add_f32_e32 v16, v19, v16
	s_nop 1
	v_add_f32_dpp v16, v16, v16 row_ror:8 row_mask:0xf bank_mask:0xf bound_ctrl:1
	s_nop 1
	v_add_f32_dpp v16, v16, v16 row_ror:4 row_mask:0xf bank_mask:0xf bound_ctrl:1
	s_nop 1
	v_add_f32_dpp v16, v16, v16 row_ror:2 row_mask:0xf bank_mask:0xf bound_ctrl:1
	s_nop 1
	v_add_f32_dpp v16, v16, v16 row_ror:1 row_mask:0xf bank_mask:0xf bound_ctrl:1
	s_nop 0
	v_readlane_b32 s21, v16, 0
	v_readlane_b32 s70, v16, 16
	v_readlane_b32 s68, v16, 32
	v_readlane_b32 s69, v16, 48
	s_and_saveexec_b64 s[66:67], s[0:1]
	s_cbranch_execz .LBB0_2005
	s_lshl_b64 s[64:65], s[64:65], 2
	v_mov_b32_e32 v16, s70
	s_add_u32 s64, s76, s64
	v_add_f32_e32 v16, s21, v16
	s_addc_u32 s65, s77, s65
	v_add_f32_e32 v16, s68, v16
	v_add_f32_e32 v18, s69, v16
	v_mov_b64_e32 v[16:17], s[64:65]
	global_atomic_add_f32 v[16:17], v18, off

; DEVI float fsig(float x) { return __builtin_amdgcn_rcpf(1.f + __expf(-x)); }
; DEVI float bflo(unsigned u) { return __uint_as_float(u << 16); }
; DEVI float bfhi(unsigned u) { return __uint_as_float(u & 0xffff0000u); }
; template <int EPI, int TS, bool VT>
; DEVI void gemm_epilogue(const Params& p, char* smem, f32x4 (&acc)[2][2][4][2], int m0, int n0, float scale, const float* ssin,
;                         float* ssout, u16* xbout, int wid, int lane, int wr, int wc, int fr, int fq) {
;     ...
;           const float rs = __int_as_float(__builtin_amdgcn_readlane(__float_as_int(rsv), i));
;           if constexpr (EPI == E_RESID || EPI == E_PLEGATE) {
;             const float4 a = *(const float4*)(Tr + 4 * lane);
;             const size_t ro = (size_t)grow * 1024 + n0 + 4 * lane;
;             float4 x4 = xo[u];
;             if constexpr (EPI == E_PLEGATE) {
;               x4.x += bflo(pv[u].x) * fsig(a.x * rs);
;               x4.y += bfhi(pv[u].x) * fsig(a.y * rs);
;               x4.z += bflo(pv[u].y) * fsig(a.z * rs);
;               x4.w += bfhi(pv[u].y) * fsig(a.w * rs);
;             } else {
;               const float sc = fabsf(scale);
;               x4.x += sc * a.x; x4.y += sc * a.y; x4.z += sc * a.z; x4.w += sc * a.w;
;             }
;             st_nt16(p.x + ro, x4);
;             if (xbout) {
;               uint2 o;
;               o.x = pack2(x4.x, x4.y);
;               o.y = pack2(x4.z, x4.w);
;               st_nt8(xbout + ro, o);
;             }
;             if (ssout) {
;               const float ssq = wsum(x4.x * x4.x + x4.y * x4.y + x4.z * x4.z + x4.w * x4.w, lane);
;               if (lane == 0) atomicAdd(ssout + grow, ssq);
;             }
.LBB0_2006:
	ds_read_b128 v[16:19], v142 offset:4160
	v_readlane_b32 s21, v76, 4
	s_and_b64 vcc, exec, s[4:5]
	s_waitcnt lgkmcnt(0)
	v_mul_f32_e32 v16, s21, v16
	v_mul_f32_e32 v17, s21, v17
	v_mul_f32_e32 v16, 0xbfb8aa3b, v16
	v_mul_f32_e32 v17, 0xbfb8aa3b, v17
	v_mul_f32_e32 v18, s21, v18
	v_mul_f32_e32 v19, s21, v19
	v_exp_f32_e32 v20, v16
	v_exp_f32_e32 v21, v17
	v_mul_f32_e32 v18, 0xbfb8aa3b, v18
	v_mul_f32_e32 v19, 0xbfb8aa3b, v19
	v_exp_f32_e32 v18, v18
	v_exp_f32_e32 v19, v19
	v_add_f32_e32 v20, 1.0, v20
	v_add_f32_e32 v21, 1.0, v21
	v_rcp_f32_e32 v20, v20
	v_rcp_f32_e32 v21, v21
	v_add_f32_e32 v18, 1.0, v18
	v_add_f32_e32 v19, 1.0, v19
	v_rcp_f32_e32 v18, v18
	v_rcp_f32_e32 v19, v19
	v_lshlrev_b32_e32 v16, 16, v54
	v_and_b32_e32 v17, 0xffff0000, v54
	v_pk_fma_f32 v[12:13], v[20:21], v[16:17], v[12:13]
	v_lshlrev_b32_e32 v16, 16, v55
	v_and_b32_e32 v17, 0xffff0000, v55
	v_pk_fma_f32 v[14:15], v[18:19], v[16:17], v[14:15]
	global_store_dwordx4 v[52:53], v[12:15], off
	s_cbranch_vccnz .LBB0_2008
	v_cvt_pk_bf16_f32 v16, v12, v13
	v_cvt_pk_bf16_f32 v17, v14, v15
	v_lshl_add_u64 v[18:19], v[50:51], 1, s[8:9]
	global_store_dwordx2 v[18:19], v[16:17], off
.LBB0_2008:
	s_and_b64 vcc, exec, s[6:7]
	s_cbranch_vccnz .LBB0_2012
	v_pk_mul_f32 v[12:13], v[12:13], v[12:13]
	v_pk_mul_f32 v[14:15], v[14:15], v[14:15]
	v_add_f32_e32 v12, v12, v13
	v_add_f32_e32 v12, v12, v14
	v_add_f32_e32 v12, v15, v12
	s_nop 1
	v_add_f32_dpp v12, v12, v12 row_ror:8 row_mask:0xf bank_mask:0xf bound_ctrl:1
	s_nop 1
	v_add_f32_dpp v12, v12, v12 row_ror:4 row_mask:0xf bank_mask:0xf bound_ctrl:1
	s_nop 1
	v_add_f32_dpp v12, v12, v12 row_ror:2 row_mask:0xf bank_mask:0xf bound_ctrl:1
	s_nop 1
	v_add_f32_dpp v12, v12, v12 row_ror:1 row_mask:0xf bank_mask:0xf bound_ctrl:1
	s_nop 0
	v_readlane_b32 s21, v12, 0
	v_readlane_b32 s68, v12, 16
	v_readlane_b32 s66, v12, 32
	v_readlane_b32 s67, v12, 48
	s_and_saveexec_b64 s[64:65], s[0:1]
	s_cbranch_execz .LBB0_2011
	s_lshl_b64 s[62:63], s[62:63], 2
	v_mov_b32_e32 v12, s68
	s_add_u32 s62, s76, s62
	v_add_f32_e32 v12, s21, v12
	s_addc_u32 s63, s77, s63
	v_add_f32_e32 v12, s66, v12
	v_add_f32_e32 v14, s67, v12
	v_mov_b64_e32 v[12:13], s[62:63]
	global_atomic_add_f32 v[12:13], v14, off

; DEVI float fsig(float x) { return __builtin_amdgcn_rcpf(1.f + __expf(-x)); }
; DEVI float bflo(unsigned u) { return __uint_as_float(u << 16); }
; DEVI float bfhi(unsigned u) { return __uint_as_float(u & 0xffff0000u); }
; template <int EPI, int TS, bool VT>
; DEVI void gemm_epilogue(const Params& p, char* smem, f32x4 (&acc)[2][2][4][2], int m0, int n0, float scale, const float* ssin,
;                         float* ssout, u16* xbout, int wid, int lane, int wr, int wc, int fr, int fq) {
;     ...
;           const float rs = __int_as_float(__builtin_amdgcn_readlane(__float_as_int(rsv), i));
;           if constexpr (EPI == E_RESID || EPI == E_PLEGATE) {
;             const float4 a = *(const float4*)(Tr + 4 * lane);
;             const size_t ro = (size_t)grow * 1024 + n0 + 4 * lane;
;             float4 x4 = xo[u];
;             if constexpr (EPI == E_PLEGATE) {
;               x4.x += bflo(pv[u].x) * fsig(a.x * rs);
;               x4.y += bfhi(pv[u].x) * fsig(a.y * rs);
;               x4.z += bflo(pv[u].y) * fsig(a.z * rs);
;               x4.w += bfhi(pv[u].y) * fsig(a.w * rs);
;             } else {
;               const float sc = fabsf(scale);
;               x4.x += sc * a.x; x4.y += sc * a.y; x4.z += sc * a.z; x4.w += sc * a.w;
;             }
;             st_nt16(p.x + ro, x4);
;             if (xbout) {
;               uint2 o;
;               o.x = pack2(x4.x, x4.y);
;               o.y = pack2(x4.z, x4.w);
;               st_nt8(xbout + ro, o);
;             }
;             if (ssout) {
;               const float ssq = wsum(x4.x * x4.x + x4.y * x4.y + x4.z * x4.z + x4.w * x4.w, lane);
;               if (lane == 0) atomicAdd(ssout + grow, ssq);
;             }
.LBB0_2012:
	ds_read_b128 v[12:15], v142 offset:5200
	v_readlane_b32 s21, v76, 5
	s_and_b64 vcc, exec, s[4:5]
	s_waitcnt lgkmcnt(0)
	v_mul_f32_e32 v12, s21, v12
	v_mul_f32_e32 v13, s21, v13
	v_mul_f32_e32 v12, 0xbfb8aa3b, v12
	v_mul_f32_e32 v13, 0xbfb8aa3b, v13
	v_mul_f32_e32 v14, s21, v14
	v_mul_f32_e32 v15, s21, v15
	v_exp_f32_e32 v16, v12
	v_exp_f32_e32 v17, v13
	v_mul_f32_e32 v14, 0xbfb8aa3b, v14
	v_mul_f32_e32 v15, 0xbfb8aa3b, v15
	v_exp_f32_e32 v14, v14
	v_exp_f32_e32 v15, v15
	v_add_f32_e32 v16, 1.0, v16
	v_add_f32_e32 v17, 1.0, v17
	v_rcp_f32_e32 v16, v16
	v_rcp_f32_e32 v17, v17
	v_add_f32_e32 v14, 1.0, v14
	v_add_f32_e32 v15, 1.0, v15
	v_rcp_f32_e32 v14, v14
	v_rcp_f32_e32 v15, v15
	v_lshlrev_b32_e32 v12, 16, v48
	v_and_b32_e32 v13, 0xffff0000, v48
	v_pk_fma_f32 v[8:9], v[16:17], v[12:13], v[8:9]
	v_lshlrev_b32_e32 v12, 16, v49
	v_and_b32_e32 v13, 0xffff0000, v49
	v_pk_fma_f32 v[10:11], v[14:15], v[12:13], v[10:11]
	global_store_dwordx4 v[46:47], v[8:11], off
	s_cbranch_vccnz .LBB0_2014
	v_cvt_pk_bf16_f32 v12, v8, v9
	v_cvt_pk_bf16_f32 v13, v10, v11
	v_lshl_add_u64 v[14:15], v[44:45], 1, s[8:9]
	global_store_dwordx2 v[14:15], v[12:13], off
.LBB0_2014:
	s_and_b64 vcc, exec, s[6:7]
	s_cbranch_vccnz .LBB0_2018
	v_pk_mul_f32 v[8:9], v[8:9], v[8:9]
	v_pk_mul_f32 v[10:11], v[10:11], v[10:11]
	v_add_f32_e32 v8, v8, v9
	v_add_f32_e32 v8, v8, v10
	v_add_f32_e32 v8, v11, v8
	s_nop 1
	v_add_f32_dpp v8, v8, v8 row_ror:8 row_mask:0xf bank_mask:0xf bound_ctrl:1
	s_nop 1
	v_add_f32_dpp v8, v8, v8 row_ror:4 row_mask:0xf bank_mask:0xf bound_ctrl:1
	s_nop 1
	v_add_f32_dpp v8, v8, v8 row_ror:2 row_mask:0xf bank_mask:0xf bound_ctrl:1
	s_nop 1
	v_add_f32_dpp v8, v8, v8 row_ror:1 row_mask:0xf bank_mask:0xf bound_ctrl:1
	s_nop 0
	v_readlane_b32 s21, v8, 0
	v_readlane_b32 s66, v8, 16
	v_readlane_b32 s64, v8, 32
	v_readlane_b32 s65, v8, 48
	s_and_saveexec_b64 s[62:63], s[0:1]
	s_cbranch_execz .LBB0_2017
	s_lshl_b64 s[34:35], s[34:35], 2
	v_mov_b32_e32 v8, s66
	s_add_u32 s34, s76, s34
	v_add_f32_e32 v8, s21, v8
	s_addc_u32 s35, s77, s35
	v_add_f32_e32 v8, s64, v8
	v_add_f32_e32 v10, s65, v8
	v_mov_b64_e32 v[8:9], s[34:35]
	global_atomic_add_f32 v[8:9], v10, off

; DEVI float fsig(float x) { return __builtin_amdgcn_rcpf(1.f + __expf(-x)); }
; DEVI float bflo(unsigned u) { return __uint_as_float(u << 16); }
; DEVI float bfhi(unsigned u) { return __uint_as_float(u & 0xffff0000u); }
; template <int EPI, int TS, bool VT>
; DEVI void gemm_epilogue(const Params& p, char* smem, f32x4 (&acc)[2][2][4][2], int m0, int n0, float scale, const float* ssin,
;                         float* ssout, u16* xbout, int wid, int lane, int wr, int wc, int fr, int fq) {
;     ...
;           const float rs = __int_as_float(__builtin_amdgcn_readlane(__float_as_int(rsv), i));
;           if constexpr (EPI == E_RESID || EPI == E_PLEGATE) {
;             const float4 a = *(const float4*)(Tr + 4 * lane);
;             const size_t ro = (size_t)grow * 1024 + n0 + 4 * lane;
;             float4 x4 = xo[u];
;             if constexpr (EPI == E_PLEGATE) {
;               x4.x += bflo(pv[u].x) * fsig(a.x * rs);
;               x4.y += bfhi(pv[u].x) * fsig(a.y * rs);
;               x4.z += bflo(pv[u].y) * fsig(a.z * rs);
;               x4.w += bfhi(pv[u].y) * fsig(a.w * rs);
;             } else {
;               const float sc = fabsf(scale);
;               x4.x += sc * a.x; x4.y += sc * a.y; x4.z += sc * a.z; x4.w += sc * a.w;
;             }
;             st_nt16(p.x + ro, x4);
;             if (xbout) {
;               uint2 o;
;               o.x = pack2(x4.x, x4.y);
;               o.y = pack2(x4.z, x4.w);
;               st_nt8(xbout + ro, o);
;             }
;             if (ssout) {
;               const float ssq = wsum(x4.x * x4.x + x4.y * x4.y + x4.z * x4.z + x4.w * x4.w, lane);
;               if (lane == 0) atomicAdd(ssout + grow, ssq);
;             }
.LBB0_2018:
	ds_read_b128 v[8:11], v142 offset:6240
	v_readlane_b32 s21, v76, 6
	s_and_b64 vcc, exec, s[4:5]
	s_waitcnt lgkmcnt(0)
	v_mul_f32_e32 v8, s21, v8
	v_mul_f32_e32 v9, s21, v9
	v_mul_f32_e32 v8, 0xbfb8aa3b, v8
	v_mul_f32_e32 v9, 0xbfb8aa3b, v9
	v_mul_f32_e32 v10, s21, v10
	v_mul_f32_e32 v11, s21, v11
	v_exp_f32_e32 v12, v8
	v_exp_f32_e32 v13, v9
	v_mul_f32_e32 v10, 0xbfb8aa3b, v10
	v_mul_f32_e32 v11, 0xbfb8aa3b, v11
	v_exp_f32_e32 v10, v10
	v_exp_f32_e32 v11, v11
	v_add_f32_e32 v12, 1.0, v12
	v_add_f32_e32 v13, 1.0, v13
	v_rcp_f32_e32 v12, v12
	v_rcp_f32_e32 v13, v13
	v_add_f32_e32 v10, 1.0, v10
	v_add_f32_e32 v11, 1.0, v11
	v_rcp_f32_e32 v10, v10
	v_rcp_f32_e32 v11, v11
	v_lshlrev_b32_e32 v8, 16, v42
	v_and_b32_e32 v9, 0xffff0000, v42
	v_pk_fma_f32 v[4:5], v[12:13], v[8:9], v[4:5]
	v_lshlrev_b32_e32 v8, 16, v43
	v_and_b32_e32 v9, 0xffff0000, v43
	v_pk_fma_f32 v[6:7], v[10:11], v[8:9], v[6:7]
	global_store_dwordx4 v[40:41], v[4:7], off
	s_cbranch_vccnz .LBB0_2020
	v_cvt_pk_bf16_f32 v8, v4, v5
	v_cvt_pk_bf16_f32 v9, v6, v7
	v_lshl_add_u64 v[10:11], v[38:39], 1, s[8:9]
	global_store_dwordx2 v[10:11], v[8:9], off
.LBB0_2020:
	s_and_b64 vcc, exec, s[6:7]
	s_cbranch_vccnz .LBB0_2024
	v_pk_mul_f32 v[4:5], v[4:5], v[4:5]
	v_pk_mul_f32 v[6:7], v[6:7], v[6:7]
	v_add_f32_e32 v4, v4, v5
	v_add_f32_e32 v4, v4, v6
	v_add_f32_e32 v4, v7, v4
	s_nop 1
	v_add_f32_dpp v4, v4, v4 row_ror:8 row_mask:0xf bank_mask:0xf bound_ctrl:1
	s_nop 1
	v_add_f32_dpp v4, v4, v4 row_ror:4 row_mask:0xf bank_mask:0xf bound_ctrl:1
	s_nop 1
	v_add_f32_dpp v4, v4, v4 row_ror:2 row_mask:0xf bank_mask:0xf bound_ctrl:1
	s_nop 1
	v_add_f32_dpp v4, v4, v4 row_ror:1 row_mask:0xf bank_mask:0xf bound_ctrl:1
	s_nop 0
	v_readlane_b32 s21, v4, 0
	v_readlane_b32 s64, v4, 16
	v_readlane_b32 s62, v4, 32
	v_readlane_b32 s63, v4, 48
	s_and_saveexec_b64 s[34:35], s[0:1]
	s_cbranch_execz .LBB0_2023
	s_lshl_b64 s[30:31], s[30:31], 2
	v_mov_b32_e32 v4, s64
	s_add_u32 s30, s76, s30
	v_add_f32_e32 v4, s21, v4
	s_addc_u32 s31, s77, s31
	v_add_f32_e32 v4, s62, v4
	v_add_f32_e32 v6, s63, v4
	v_mov_b64_e32 v[4:5], s[30:31]
	global_atomic_add_f32 v[4:5], v6, off

; DEVI float fsig(float x) { return __builtin_amdgcn_rcpf(1.f + __expf(-x)); }
; DEVI float bflo(unsigned u) { return __uint_as_float(u << 16); }
; DEVI float bfhi(unsigned u) { return __uint_as_float(u & 0xffff0000u); }
; template <int EPI, int TS, bool VT>
; DEVI void gemm_epilogue(const Params& p, char* smem, f32x4 (&acc)[2][2][4][2], int m0, int n0, float scale, const float* ssin,
;                         float* ssout, u16* xbout, int wid, int lane, int wr, int wc, int fr, int fq) {
;     ...
;           const float rs = __int_as_float(__builtin_amdgcn_readlane(__float_as_int(rsv), i));
;           if constexpr (EPI == E_RESID || EPI == E_PLEGATE) {
;             const float4 a = *(const float4*)(Tr + 4 * lane);
;             const size_t ro = (size_t)grow * 1024 + n0 + 4 * lane;
;             float4 x4 = xo[u];
;             if constexpr (EPI == E_PLEGATE) {
;               x4.x += bflo(pv[u].x) * fsig(a.x * rs);
;               x4.y += bfhi(pv[u].x) * fsig(a.y * rs);
;               x4.z += bflo(pv[u].y) * fsig(a.z * rs);
;               x4.w += bfhi(pv[u].y) * fsig(a.w * rs);
;             } else {
;               const float sc = fabsf(scale);
;               x4.x += sc * a.x; x4.y += sc * a.y; x4.z += sc * a.z; x4.w += sc * a.w;
;             }
;             st_nt16(p.x + ro, x4);
;             if (xbout) {
;               uint2 o;
;               o.x = pack2(x4.x, x4.y);
;               o.y = pack2(x4.z, x4.w);
;               st_nt8(xbout + ro, o);
;             }
;             if (ssout) {
;               const float ssq = wsum(x4.x * x4.x + x4.y * x4.y + x4.z * x4.z + x4.w * x4.w, lane);
;               if (lane == 0) atomicAdd(ssout + grow, ssq);
;             }
.LBB0_2024:
	ds_read_b128 v[4:7], v142 offset:7280
	v_readlane_b32 s21, v76, 7
	s_and_b64 vcc, exec, s[4:5]
	s_waitcnt lgkmcnt(0)
	v_mul_f32_e32 v4, s21, v4
	v_mul_f32_e32 v5, s21, v5
	v_mul_f32_e32 v4, 0xbfb8aa3b, v4
	v_mul_f32_e32 v5, 0xbfb8aa3b, v5
	v_mul_f32_e32 v6, s21, v6
	v_mul_f32_e32 v7, s21, v7
	v_exp_f32_e32 v8, v4
	v_exp_f32_e32 v9, v5
	v_mul_f32_e32 v6, 0xbfb8aa3b, v6
	v_mul_f32_e32 v7, 0xbfb8aa3b, v7
	v_exp_f32_e32 v6, v6
	v_exp_f32_e32 v7, v7
	v_add_f32_e32 v8, 1.0, v8
	v_add_f32_e32 v9, 1.0, v9
	v_rcp_f32_e32 v8, v8
	v_rcp_f32_e32 v9, v9
	v_add_f32_e32 v6, 1.0, v6
	v_add_f32_e32 v7, 1.0, v7
	v_rcp_f32_e32 v6, v6
	v_rcp_f32_e32 v7, v7
	v_lshlrev_b32_e32 v4, 16, v36
	v_and_b32_e32 v5, 0xffff0000, v36
	v_pk_fma_f32 v[0:1], v[8:9], v[4:5], v[0:1]
	v_lshlrev_b32_e32 v4, 16, v37
	v_and_b32_e32 v5, 0xffff0000, v37
	v_pk_fma_f32 v[2:3], v[6:7], v[4:5], v[2:3]
	global_store_dwordx4 v[34:35], v[0:3], off
	s_cbranch_vccnz .LBB0_2026
	v_cvt_pk_bf16_f32 v4, v0, v1
	v_cvt_pk_bf16_f32 v5, v2, v3
	v_lshl_add_u64 v[6:7], v[32:33], 1, s[8:9]
	global_store_dwordx2 v[6:7], v[4:5], off
.LBB0_2026:
	s_and_b64 vcc, exec, s[6:7]
	s_cbranch_vccnz .LBB0_2030
	v_pk_mul_f32 v[0:1], v[0:1], v[0:1]
	v_pk_mul_f32 v[2:3], v[2:3], v[2:3]
	v_add_f32_e32 v0, v0, v1
	v_add_f32_e32 v0, v0, v2
	v_add_f32_e32 v0, v3, v0
	s_nop 1
	v_add_f32_dpp v0, v0, v0 row_ror:8 row_mask:0xf bank_mask:0xf bound_ctrl:1
	s_nop 1
	v_add_f32_dpp v0, v0, v0 row_ror:4 row_mask:0xf bank_mask:0xf bound_ctrl:1
	s_nop 1
	v_add_f32_dpp v0, v0, v0 row_ror:2 row_mask:0xf bank_mask:0xf bound_ctrl:1
	s_nop 1
	v_add_f32_dpp v0, v0, v0 row_ror:1 row_mask:0xf bank_mask:0xf bound_ctrl:1
	s_nop 0
	v_readlane_b32 s21, v0, 0
	v_readlane_b32 s62, v0, 16
	v_readlane_b32 s34, v0, 32
	v_readlane_b32 s35, v0, 48
	s_and_saveexec_b64 s[30:31], s[0:1]
	s_cbranch_execz .LBB0_2029
	s_lshl_b64 s[22:23], s[22:23], 2
	v_mov_b32_e32 v0, s62
	s_add_u32 s22, s76, s22
	v_add_f32_e32 v0, s21, v0
	s_addc_u32 s23, s77, s23
	v_add_f32_e32 v0, s34, v0
	v_add_f32_e32 v2, s35, v0
	v_mov_b64_e32 v[0:1], s[22:23]
	global_atomic_add_f32 v[0:1], v2, off

; DEVI float fsig(float x) { return __builtin_amdgcn_rcpf(1.f + __expf(-x)); }
; template <int EPI, int TS, bool VT>
; DEVI void gemm_epilogue(const Params& p, char* smem, f32x4 (&acc)[2][2][4][2], int m0, int n0, float scale, const float* ssin,
;                         float* ssout, u16* xbout, int wid, int lane, int wr, int wc, int fr, int fq) {
;     ...
;         if constexpr (EPI == E_RESID || EPI == E_PLEGATE) {
; #pragma unroll
;           for (int u = 0; u < 8; ++u) {
;             const size_t ro = (size_t)(g0 + i0 + u) * 1024 + n0 + 4 * lane;
;             const int gr = g0 + i0 + u;
;             const float* xs = p.x + ro;
;             if (scale < 0.f)
;               xs = (gr < MP ? p.x_prompt + ro : p.x_sample + (ro - (size_t)MP * 1024));
;             { const f32x4 t_ = __builtin_nontemporal_load((const f32x4*)xs); xo[u] = make_float4(t_[0], t_[1], t_[2], t_[3]); }
;             if constexpr (EPI == E_PLEGATE) {
;               const unsigned long long t2_ = __builtin_nontemporal_load((const unsigned long long*)((const u16*)(wsb + OFF_PP) + ro));
;               pv[u] = make_uint2((unsigned)t2_, (unsigned)(t2_ >> 32));
;             }
;           }
;         }
; #pragma unroll
;         for (int u = 0; u < 8; ++u) {
;           const int i = i0 + u;
;           const int grow = g0 + i;
;           const float* Tr = T + (r0 + i) * TS;
;           const float rs = __int_as_float(__builtin_amdgcn_readlane(__float_as_int(rsv), i));
;           if constexpr (EPI == E_RESID || EPI == E_PLEGATE) {
;             const float4 a = *(const float4*)(Tr + 4 * lane);
;             const size_t ro = (size_t)grow * 1024 + n0 + 4 * lane;
;             float4 x4 = xo[u];
;             if constexpr (EPI == E_PLEGATE) {
;               x4.x += bflo(pv[u].x) * fsig(a.x * rs);
;               x4.y += bfhi(pv[u].x) * fsig(a.y * rs);
;               x4.z += bflo(pv[u].y) * fsig(a.z * rs);
;               x4.w += bfhi(pv[u].y) * fsig(a.w * rs);
;             } else {
;               const float sc = fabsf(scale);
;               x4.x += sc * a.x; x4.y += sc * a.y; x4.z += sc * a.z; x4.w += sc * a.w;
;             }
;             st_nt16(p.x + ro, x4);
;             if (xbout) {
;               uint2 o;
;               o.x = pack2(x4.x, x4.y);
;               o.y = pack2(x4.z, x4.w);
;               st_nt8(xbout + ro, o);
;             }
;             if (ssout) {
.LBB0_2030:
	s_add_i32 s68, s20, 0x88
	s_ashr_i32 s69, s68, 31
	s_add_i32 s66, s20, 0x89
	s_lshl_b64 s[22:23], s[68:69], 10
	s_ashr_i32 s67, s66, 31
	s_add_i32 s64, s20, 0x8a
	v_lshl_add_u64 v[74:75], s[22:23], 0, v[128:129]
	s_lshl_b64 s[22:23], s[66:67], 10
	s_ashr_i32 s65, s64, 31
	s_add_i32 s62, s20, 0x8b
	v_lshl_add_u64 v[68:69], s[22:23], 0, v[128:129]
	s_lshl_b64 s[22:23], s[64:65], 10
	s_ashr_i32 s63, s62, 31
	s_add_i32 s34, s20, 0x8c
	v_lshl_add_u64 v[62:63], s[22:23], 0, v[128:129]
	s_lshl_b64 s[22:23], s[62:63], 10
	s_ashr_i32 s35, s34, 31
	s_add_i32 s30, s20, 0x8d
	v_lshl_add_u64 v[56:57], s[22:23], 0, v[128:129]
	s_lshl_b64 s[22:23], s[34:35], 10
	s_ashr_i32 s31, s30, 31
	v_lshl_add_u64 v[50:51], s[22:23], 0, v[128:129]
	s_lshl_b64 s[22:23], s[30:31], 10
	v_lshl_add_u64 v[44:45], s[22:23], 0, v[128:129]
	s_add_i32 s22, s20, 0x8e
	v_lshl_add_u64 v[82:83], v[74:75], 2, s[38:39]
	s_ashr_i32 s23, s22, 31
	s_addk_i32 s20, 0x8f
	global_load_dwordx4 v[28:31], v[82:83], off
	s_lshl_b64 s[70:71], s[22:23], 10
	s_ashr_i32 s21, s20, 31
	v_lshl_add_u64 v[0:1], v[74:75], 1, s[18:19]
	v_lshl_add_u64 v[70:71], v[68:69], 2, s[38:39]
	v_lshl_add_u64 v[38:39], s[70:71], 0, v[128:129]
	s_lshl_b64 s[70:71], s[20:21], 10
	v_lshl_add_u64 v[2:3], v[68:69], 1, s[18:19]
	v_lshl_add_u64 v[64:65], v[62:63], 2, s[38:39]
	global_load_dwordx4 v[24:27], v[70:71], off
	global_load_dwordx4 v[20:23], v[64:65], off
	v_lshl_add_u64 v[4:5], v[62:63], 1, s[18:19]
	v_lshl_add_u64 v[6:7], v[56:57], 1, s[18:19]
	global_load_dwordx2 v[84:85], v[0:1], off
	global_load_dwordx2 v[72:73], v[2:3], off
	global_load_dwordx2 v[66:67], v[4:5], off
	global_load_dwordx2 v[60:61], v[6:7], off
	v_lshl_add_u64 v[32:33], s[70:71], 0, v[128:129]
	v_lshl_add_u64 v[58:59], v[56:57], 2, s[38:39]
	v_lshl_add_u64 v[36:37], v[50:51], 1, s[18:19]
	v_lshl_add_u64 v[46:47], v[44:45], 2, s[38:39]
	v_lshl_add_u64 v[42:43], v[44:45], 1, s[18:19]
	v_lshl_add_u64 v[34:35], v[32:33], 2, s[38:39]
	v_lshl_add_u64 v[52:53], v[50:51], 2, s[38:39]
	global_load_dwordx4 v[16:19], v[58:59], off
	global_load_dwordx4 v[12:15], v[52:53], off
	v_lshl_add_u64 v[40:41], v[38:39], 2, s[38:39]
	global_load_dwordx4 v[8:11], v[46:47], off
	global_load_dwordx4 v[4:7], v[40:41], off
	v_lshl_add_u64 v[78:79], v[38:39], 1, s[18:19]
	global_load_dwordx4 v[0:3], v[34:35], off
	v_lshl_add_u64 v[80:81], v[32:33], 1, s[18:19]
	global_load_dwordx2 v[54:55], v[36:37], off
	global_load_dwordx2 v[48:49], v[42:43], off
	s_nop 0
	global_load_dwordx2 v[42:43], v[78:79], off
	global_load_dwordx2 v[36:37], v[80:81], off
	ds_read_b128 v[78:81], v142 offset:8320
	v_readlane_b32 s18, v76, 8
	s_and_b64 vcc, exec, s[4:5]
	s_waitcnt lgkmcnt(0)
	v_mul_f32_e32 v77, s18, v78
	v_mul_f32_e32 v78, s18, v79
	v_mul_f32_e32 v77, 0xbfb8aa3b, v77
	v_mul_f32_e32 v78, 0xbfb8aa3b, v78
	v_exp_f32_e32 v77, v77
	v_exp_f32_e32 v78, v78
	v_mul_f32_e32 v79, s18, v80
	v_mul_f32_e32 v80, s18, v81
	v_mul_f32_e32 v79, 0xbfb8aa3b, v79
	v_mul_f32_e32 v80, 0xbfb8aa3b, v80
	v_exp_f32_e32 v79, v79
	v_add_f32_e32 v77, 1.0, v77
	v_add_f32_e32 v78, 1.0, v78
	v_exp_f32_e32 v80, v80
	v_rcp_f32_e32 v77, v77
	v_rcp_f32_e32 v78, v78
	v_add_f32_e32 v79, 1.0, v79
	s_waitcnt vmcnt(0)
	v_lshlrev_b32_e32 v81, 16, v84
	v_and_b32_e32 v84, 0xffff0000, v84
	v_fma_f32 v28, v77, v81, v28
	v_fma_f32 v29, v78, v84, v29
	v_rcp_f32_e32 v77, v79
	v_add_f32_e32 v78, 1.0, v80
	v_rcp_f32_e32 v78, v78
	v_lshlrev_b32_e32 v79, 16, v85
	v_fma_f32 v30, v77, v79, v30
	v_and_b32_e32 v77, 0xffff0000, v85
	v_fmac_f32_e32 v31, v78, v77
	global_store_dwordx4 v[82:83], v[28:31], off
	s_cbranch_vccnz .LBB0_2032
	v_cvt_pk_bf16_f32 v78, v28, v29
	v_cvt_pk_bf16_f32 v79, v30, v31
	v_lshl_add_u64 v[74:75], v[74:75], 1, s[8:9]
	global_store_dwordx2 v[74:75], v[78:79], off
.LBB0_2032:
	s_and_b64 vcc, exec, s[6:7]
	s_cbranch_vccnz .LBB0_2036
	v_mul_f32_e32 v29, v29, v29
	v_fmac_f32_e32 v29, v28, v28
	v_fmac_f32_e32 v29, v30, v30
	v_fmac_f32_e32 v29, v31, v31
	s_nop 1
	v_add_f32_dpp v28, v29, v29 row_ror:8 row_mask:0xf bank_mask:0xf bound_ctrl:1
	s_nop 1
	v_add_f32_dpp v28, v28, v28 row_ror:4 row_mask:0xf bank_mask:0xf bound_ctrl:1
	s_nop 1
	v_add_f32_dpp v28, v28, v28 row_ror:2 row_mask:0xf bank_mask:0xf bound_ctrl:1
	s_nop 1
	v_add_f32_dpp v28, v28, v28 row_ror:1 row_mask:0xf bank_mask:0xf bound_ctrl:1
	s_nop 0
	v_readlane_b32 s70, v28, 0
	v_readlane_b32 s73, v28, 16
	v_readlane_b32 s71, v28, 32
	v_readlane_b32 s72, v28, 48
	s_and_saveexec_b64 s[18:19], s[0:1]
	s_cbranch_execz .LBB0_2035
	s_lshl_b64 s[68:69], s[68:69], 2
	v_mov_b32_e32 v28, s73
	s_add_u32 s68, s76, s68
	v_add_f32_e32 v28, s70, v28
	s_addc_u32 s69, s77, s69
	v_add_f32_e32 v28, s71, v28
	v_add_f32_e32 v30, s72, v28
	v_mov_b64_e32 v[28:29], s[68:69]
	global_atomic_add_f32 v[28:29], v30, off

; DEVI float fsig(float x) { return __builtin_amdgcn_rcpf(1.f + __expf(-x)); }
; DEVI float bflo(unsigned u) { return __uint_as_float(u << 16); }
; DEVI float bfhi(unsigned u) { return __uint_as_float(u & 0xffff0000u); }
; template <int EPI, int TS, bool VT>
; DEVI void gemm_epilogue(const Params& p, char* smem, f32x4 (&acc)[2][2][4][2], int m0, int n0, float scale, const float* ssin,
;                         float* ssout, u16* xbout, int wid, int lane, int wr, int wc, int fr, int fq) {
;     ...
;           const float rs = __int_as_float(__builtin_amdgcn_readlane(__float_as_int(rsv), i));
;           if constexpr (EPI == E_RESID || EPI == E_PLEGATE) {
;             const float4 a = *(const float4*)(Tr + 4 * lane);
;             const size_t ro = (size_t)grow * 1024 + n0 + 4 * lane;
;             float4 x4 = xo[u];
;             if constexpr (EPI == E_PLEGATE) {
;               x4.x += bflo(pv[u].x) * fsig(a.x * rs);
;               x4.y += bfhi(pv[u].x) * fsig(a.y * rs);
;               x4.z += bflo(pv[u].y) * fsig(a.z * rs);
;               x4.w += bfhi(pv[u].y) * fsig(a.w * rs);
;             } else {
;               const float sc = fabsf(scale);
;               x4.x += sc * a.x; x4.y += sc * a.y; x4.z += sc * a.z; x4.w += sc * a.w;
;             }
;             st_nt16(p.x + ro, x4);
;             if (xbout) {
;               uint2 o;
;               o.x = pack2(x4.x, x4.y);
;               o.y = pack2(x4.z, x4.w);
;               st_nt8(xbout + ro, o);
;             }
;             if (ssout) {
;               const float ssq = wsum(x4.x * x4.x + x4.y * x4.y + x4.z * x4.z + x4.w * x4.w, lane);
;               if (lane == 0) atomicAdd(ssout + grow, ssq);
;             }
.LBB0_2036:
	ds_read_b128 v[28:31], v142 offset:9360
	v_readlane_b32 s18, v76, 9
	s_and_b64 vcc, exec, s[4:5]
	s_waitcnt lgkmcnt(0)
	v_mul_f32_e32 v28, s18, v28
	v_mul_f32_e32 v29, s18, v29
	v_mul_f32_e32 v28, 0xbfb8aa3b, v28
	v_mul_f32_e32 v29, 0xbfb8aa3b, v29
	v_mul_f32_e32 v30, s18, v30
	v_mul_f32_e32 v31, s18, v31
	v_exp_f32_e32 v74, v28
	v_exp_f32_e32 v75, v29
	v_mul_f32_e32 v30, 0xbfb8aa3b, v30
	v_mul_f32_e32 v31, 0xbfb8aa3b, v31
	v_exp_f32_e32 v30, v30
	v_exp_f32_e32 v31, v31
	v_lshlrev_b32_e32 v28, 16, v72
	v_and_b32_e32 v29, 0xffff0000, v72
	v_add_f32_e32 v72, 1.0, v74
	v_add_f32_e32 v75, 1.0, v75
	v_rcp_f32_e32 v74, v72
	v_rcp_f32_e32 v75, v75
	v_add_f32_e32 v30, 1.0, v30
	v_add_f32_e32 v31, 1.0, v31
	v_rcp_f32_e32 v30, v30
	v_rcp_f32_e32 v31, v31
	v_pk_fma_f32 v[24:25], v[74:75], v[28:29], v[24:25]
	v_lshlrev_b32_e32 v28, 16, v73
	v_and_b32_e32 v29, 0xffff0000, v73
	v_pk_fma_f32 v[26:27], v[30:31], v[28:29], v[26:27]
	global_store_dwordx4 v[70:71], v[24:27], off
	s_cbranch_vccnz .LBB0_2038
	v_cvt_pk_bf16_f32 v28, v24, v25
	v_cvt_pk_bf16_f32 v29, v26, v27
	v_lshl_add_u64 v[30:31], v[68:69], 1, s[8:9]
	global_store_dwordx2 v[30:31], v[28:29], off
.LBB0_2038:
	s_and_b64 vcc, exec, s[6:7]
	s_cbranch_vccnz .LBB0_2042
	v_pk_mul_f32 v[24:25], v[24:25], v[24:25]
	v_pk_mul_f32 v[26:27], v[26:27], v[26:27]
	v_add_f32_e32 v24, v24, v25
	v_add_f32_e32 v24, v24, v26
	v_add_f32_e32 v24, v27, v24
	s_nop 1
	v_add_f32_dpp v24, v24, v24 row_ror:8 row_mask:0xf bank_mask:0xf bound_ctrl:1
	s_nop 1
	v_add_f32_dpp v24, v24, v24 row_ror:4 row_mask:0xf bank_mask:0xf bound_ctrl:1
	s_nop 1
	v_add_f32_dpp v24, v24, v24 row_ror:2 row_mask:0xf bank_mask:0xf bound_ctrl:1
	s_nop 1
	v_add_f32_dpp v24, v24, v24 row_ror:1 row_mask:0xf bank_mask:0xf bound_ctrl:1
	s_nop 0
	v_readlane_b32 s68, v24, 0
	v_readlane_b32 s71, v24, 16
	v_readlane_b32 s69, v24, 32
	v_readlane_b32 s70, v24, 48
	s_and_saveexec_b64 s[18:19], s[0:1]
	s_cbranch_execz .LBB0_2041
	s_lshl_b64 s[66:67], s[66:67], 2
	v_mov_b32_e32 v24, s71
	s_add_u32 s66, s76, s66
	v_add_f32_e32 v24, s68, v24
	s_addc_u32 s67, s77, s67
	v_add_f32_e32 v24, s69, v24
	v_add_f32_e32 v26, s70, v24
	v_mov_b64_e32 v[24:25], s[66:67]
	global_atomic_add_f32 v[24:25], v26, off

; DEVI float fsig(float x) { return __builtin_amdgcn_rcpf(1.f + __expf(-x)); }
; DEVI float bflo(unsigned u) { return __uint_as_float(u << 16); }
; DEVI float bfhi(unsigned u) { return __uint_as_float(u & 0xffff0000u); }
; template <int EPI, int TS, bool VT>
; DEVI void gemm_epilogue(const Params& p, char* smem, f32x4 (&acc)[2][2][4][2], int m0, int n0, float scale, const float* ssin,
;                         float* ssout, u16* xbout, int wid, int lane, int wr, int wc, int fr, int fq) {
;     ...
;           const float rs = __int_as_float(__builtin_amdgcn_readlane(__float_as_int(rsv), i));
;           if constexpr (EPI == E_RESID || EPI == E_PLEGATE) {
;             const float4 a = *(const float4*)(Tr + 4 * lane);
;             const size_t ro = (size_t)grow * 1024 + n0 + 4 * lane;
;             float4 x4 = xo[u];
;             if constexpr (EPI == E_PLEGATE) {
;               x4.x += bflo(pv[u].x) * fsig(a.x * rs);
;               x4.y += bfhi(pv[u].x) * fsig(a.y * rs);
;               x4.z += bflo(pv[u].y) * fsig(a.z * rs);
;               x4.w += bfhi(pv[u].y) * fsig(a.w * rs);
;             } else {
;               const float sc = fabsf(scale);
;               x4.x += sc * a.x; x4.y += sc * a.y; x4.z += sc * a.z; x4.w += sc * a.w;
;             }
;             st_nt16(p.x + ro, x4);
;             if (xbout) {
;               uint2 o;
;               o.x = pack2(x4.x, x4.y);
;               o.y = pack2(x4.z, x4.w);
;               st_nt8(xbout + ro, o);
;             }
;             if (ssout) {
;               const float ssq = wsum(x4.x * x4.x + x4.y * x4.y + x4.z * x4.z + x4.w * x4.w, lane);
;               if (lane == 0) atomicAdd(ssout + grow, ssq);
;             }
.LBB0_2042:
	ds_read_b128 v[24:27], v142 offset:10400
	v_readlane_b32 s18, v76, 10
	s_and_b64 vcc, exec, s[4:5]
	s_waitcnt lgkmcnt(0)
	v_mul_f32_e32 v24, s18, v24
	v_mul_f32_e32 v25, s18, v25
	v_mul_f32_e32 v24, 0xbfb8aa3b, v24
	v_mul_f32_e32 v25, 0xbfb8aa3b, v25
	v_mul_f32_e32 v26, s18, v26
	v_mul_f32_e32 v27, s18, v27
	v_exp_f32_e32 v28, v24
	v_exp_f32_e32 v29, v25
	v_mul_f32_e32 v26, 0xbfb8aa3b, v26
	v_mul_f32_e32 v27, 0xbfb8aa3b, v27
	v_exp_f32_e32 v26, v26
	v_exp_f32_e32 v27, v27
	v_add_f32_e32 v28, 1.0, v28
	v_add_f32_e32 v29, 1.0, v29
	v_rcp_f32_e32 v28, v28
	v_rcp_f32_e32 v29, v29
	v_add_f32_e32 v26, 1.0, v26
	v_add_f32_e32 v27, 1.0, v27
	v_rcp_f32_e32 v26, v26
	v_rcp_f32_e32 v27, v27
	v_lshlrev_b32_e32 v24, 16, v66
	v_and_b32_e32 v25, 0xffff0000, v66
	v_pk_fma_f32 v[20:21], v[28:29], v[24:25], v[20:21]
	v_lshlrev_b32_e32 v24, 16, v67
	v_and_b32_e32 v25, 0xffff0000, v67
	v_pk_fma_f32 v[22:23], v[26:27], v[24:25], v[22:23]
	global_store_dwordx4 v[64:65], v[20:23], off
	s_cbranch_vccnz .LBB0_2044
	v_cvt_pk_bf16_f32 v24, v20, v21
	v_cvt_pk_bf16_f32 v25, v22, v23
	v_lshl_add_u64 v[26:27], v[62:63], 1, s[8:9]
	global_store_dwordx2 v[26:27], v[24:25], off
.LBB0_2044:
	s_and_b64 vcc, exec, s[6:7]
	s_cbranch_vccnz .LBB0_2048
	v_pk_mul_f32 v[20:21], v[20:21], v[20:21]
	v_pk_mul_f32 v[22:23], v[22:23], v[22:23]
	v_add_f32_e32 v20, v20, v21
	v_add_f32_e32 v20, v20, v22
	v_add_f32_e32 v20, v23, v20
	s_nop 1
	v_add_f32_dpp v20, v20, v20 row_ror:8 row_mask:0xf bank_mask:0xf bound_ctrl:1
	s_nop 1
	v_add_f32_dpp v20, v20, v20 row_ror:4 row_mask:0xf bank_mask:0xf bound_ctrl:1
	s_nop 1
	v_add_f32_dpp v20, v20, v20 row_ror:2 row_mask:0xf bank_mask:0xf bound_ctrl:1
	s_nop 1
	v_add_f32_dpp v20, v20, v20 row_ror:1 row_mask:0xf bank_mask:0xf bound_ctrl:1
	s_nop 0
	v_readlane_b32 s66, v20, 0
	v_readlane_b32 s69, v20, 16
	v_readlane_b32 s67, v20, 32
	v_readlane_b32 s68, v20, 48
	s_and_saveexec_b64 s[18:19], s[0:1]
	s_cbranch_execz .LBB0_2047
	s_lshl_b64 s[64:65], s[64:65], 2
	v_mov_b32_e32 v20, s69
	s_add_u32 s64, s76, s64
	v_add_f32_e32 v20, s66, v20
	s_addc_u32 s65, s77, s65
	v_add_f32_e32 v20, s67, v20
	v_add_f32_e32 v22, s68, v20
	v_mov_b64_e32 v[20:21], s[64:65]
	global_atomic_add_f32 v[20:21], v22, off

; DEVI float fsig(float x) { return __builtin_amdgcn_rcpf(1.f + __expf(-x)); }
; DEVI float bflo(unsigned u) { return __uint_as_float(u << 16); }
; DEVI float bfhi(unsigned u) { return __uint_as_float(u & 0xffff0000u); }
; template <int EPI, int TS, bool VT>
; DEVI void gemm_epilogue(const Params& p, char* smem, f32x4 (&acc)[2][2][4][2], int m0, int n0, float scale, const float* ssin,
;                         float* ssout, u16* xbout, int wid, int lane, int wr, int wc, int fr, int fq) {
;     ...
;           const float rs = __int_as_float(__builtin_amdgcn_readlane(__float_as_int(rsv), i));
;           if constexpr (EPI == E_RESID || EPI == E_PLEGATE) {
;             const float4 a = *(const float4*)(Tr + 4 * lane);
;             const size_t ro = (size_t)grow * 1024 + n0 + 4 * lane;
;             float4 x4 = xo[u];
;             if constexpr (EPI == E_PLEGATE) {
;               x4.x += bflo(pv[u].x) * fsig(a.x * rs);
;               x4.y += bfhi(pv[u].x) * fsig(a.y * rs);
;               x4.z += bflo(pv[u].y) * fsig(a.z * rs);
;               x4.w += bfhi(pv[u].y) * fsig(a.w * rs);
;             } else {
;               const float sc = fabsf(scale);
;               x4.x += sc * a.x; x4.y += sc * a.y; x4.z += sc * a.z; x4.w += sc * a.w;
;             }
;             st_nt16(p.x + ro, x4);
;             if (xbout) {
;               uint2 o;
;               o.x = pack2(x4.x, x4.y);
;               o.y = pack2(x4.z, x4.w);
;               st_nt8(xbout + ro, o);
;             }
;             if (ssout) {
;               const float ssq = wsum(x4.x * x4.x + x4.y * x4.y + x4.z * x4.z + x4.w * x4.w, lane);
;               if (lane == 0) atomicAdd(ssout + grow, ssq);
;             }
.LBB0_2048:
	ds_read_b128 v[20:23], v142 offset:11440
	v_readlane_b32 s18, v76, 11
	s_and_b64 vcc, exec, s[4:5]
	s_waitcnt lgkmcnt(0)
	v_mul_f32_e32 v20, s18, v20
	v_mul_f32_e32 v21, s18, v21
	v_mul_f32_e32 v20, 0xbfb8aa3b, v20
	v_mul_f32_e32 v21, 0xbfb8aa3b, v21
	v_mul_f32_e32 v22, s18, v22
	v_mul_f32_e32 v23, s18, v23
	v_exp_f32_e32 v24, v20
	v_exp_f32_e32 v25, v21
	v_mul_f32_e32 v22, 0xbfb8aa3b, v22
	v_mul_f32_e32 v23, 0xbfb8aa3b, v23
	v_exp_f32_e32 v22, v22
	v_exp_f32_e32 v23, v23
	v_add_f32_e32 v24, 1.0, v24
	v_add_f32_e32 v25, 1.0, v25
	v_rcp_f32_e32 v24, v24
	v_rcp_f32_e32 v25, v25
	v_add_f32_e32 v22, 1.0, v22
	v_add_f32_e32 v23, 1.0, v23
	v_rcp_f32_e32 v22, v22
	v_rcp_f32_e32 v23, v23
	v_lshlrev_b32_e32 v20, 16, v60
	v_and_b32_e32 v21, 0xffff0000, v60
	v_pk_fma_f32 v[16:17], v[24:25], v[20:21], v[16:17]
	v_lshlrev_b32_e32 v20, 16, v61
	v_and_b32_e32 v21, 0xffff0000, v61
	v_pk_fma_f32 v[18:19], v[22:23], v[20:21], v[18:19]
	global_store_dwordx4 v[58:59], v[16:19], off
	s_cbranch_vccnz .LBB0_2050
	v_cvt_pk_bf16_f32 v20, v16, v17
	v_cvt_pk_bf16_f32 v21, v18, v19
	v_lshl_add_u64 v[22:23], v[56:57], 1, s[8:9]
	global_store_dwordx2 v[22:23], v[20:21], off
.LBB0_2050:
	s_and_b64 vcc, exec, s[6:7]
	s_cbranch_vccnz .LBB0_2054
	v_pk_mul_f32 v[16:17], v[16:17], v[16:17]
	v_pk_mul_f32 v[18:19], v[18:19], v[18:19]
	v_add_f32_e32 v16, v16, v17
	v_add_f32_e32 v16, v16, v18
	v_add_f32_e32 v16, v19, v16
	s_nop 1
	v_add_f32_dpp v16, v16, v16 row_ror:8 row_mask:0xf bank_mask:0xf bound_ctrl:1
	s_nop 1
	v_add_f32_dpp v16, v16, v16 row_ror:4 row_mask:0xf bank_mask:0xf bound_ctrl:1
	s_nop 1
	v_add_f32_dpp v16, v16, v16 row_ror:2 row_mask:0xf bank_mask:0xf bound_ctrl:1
	s_nop 1
	v_add_f32_dpp v16, v16, v16 row_ror:1 row_mask:0xf bank_mask:0xf bound_ctrl:1
	s_nop 0
	v_readlane_b32 s64, v16, 0
	v_readlane_b32 s67, v16, 16
	v_readlane_b32 s65, v16, 32
	v_readlane_b32 s66, v16, 48
	s_and_saveexec_b64 s[18:19], s[0:1]
	s_cbranch_execz .LBB0_2053
	s_lshl_b64 s[62:63], s[62:63], 2
	v_mov_b32_e32 v16, s67
	s_add_u32 s62, s76, s62
	v_add_f32_e32 v16, s64, v16
	s_addc_u32 s63, s77, s63
	v_add_f32_e32 v16, s65, v16
	v_add_f32_e32 v18, s66, v16
	v_mov_b64_e32 v[16:17], s[62:63]
	global_atomic_add_f32 v[16:17], v18, off

; DEVI float fsig(float x) { return __builtin_amdgcn_rcpf(1.f + __expf(-x)); }
; DEVI float bflo(unsigned u) { return __uint_as_float(u << 16); }
; DEVI float bfhi(unsigned u) { return __uint_as_float(u & 0xffff0000u); }
; template <int EPI, int TS, bool VT>
; DEVI void gemm_epilogue(const Params& p, char* smem, f32x4 (&acc)[2][2][4][2], int m0, int n0, float scale, const float* ssin,
;                         float* ssout, u16* xbout, int wid, int lane, int wr, int wc, int fr, int fq) {
;     ...
;           const float rs = __int_as_float(__builtin_amdgcn_readlane(__float_as_int(rsv), i));
;           if constexpr (EPI == E_RESID || EPI == E_PLEGATE) {
;             const float4 a = *(const float4*)(Tr + 4 * lane);
;             const size_t ro = (size_t)grow * 1024 + n0 + 4 * lane;
;             float4 x4 = xo[u];
;             if constexpr (EPI == E_PLEGATE) {
;               x4.x += bflo(pv[u].x) * fsig(a.x * rs);
;               x4.y += bfhi(pv[u].x) * fsig(a.y * rs);
;               x4.z += bflo(pv[u].y) * fsig(a.z * rs);
;               x4.w += bfhi(pv[u].y) * fsig(a.w * rs);
;             } else {
;               const float sc = fabsf(scale);
;               x4.x += sc * a.x; x4.y += sc * a.y; x4.z += sc * a.z; x4.w += sc * a.w;
;             }
;             st_nt16(p.x + ro, x4);
;             if (xbout) {
;               uint2 o;
;               o.x = pack2(x4.x, x4.y);
;               o.y = pack2(x4.z, x4.w);
;               st_nt8(xbout + ro, o);
;             }
;             if (ssout) {
;               const float ssq = wsum(x4.x * x4.x + x4.y * x4.y + x4.z * x4.z + x4.w * x4.w, lane);
;               if (lane == 0) atomicAdd(ssout + grow, ssq);
;             }
.LBB0_2054:
	ds_read_b128 v[16:19], v142 offset:12480
	v_readlane_b32 s18, v76, 12
	s_and_b64 vcc, exec, s[4:5]
	s_waitcnt lgkmcnt(0)
	v_mul_f32_e32 v16, s18, v16
	v_mul_f32_e32 v17, s18, v17
	v_mul_f32_e32 v16, 0xbfb8aa3b, v16
	v_mul_f32_e32 v17, 0xbfb8aa3b, v17
	v_mul_f32_e32 v18, s18, v18
	v_mul_f32_e32 v19, s18, v19
	v_exp_f32_e32 v20, v16
	v_exp_f32_e32 v21, v17
	v_mul_f32_e32 v18, 0xbfb8aa3b, v18
	v_mul_f32_e32 v19, 0xbfb8aa3b, v19
	v_exp_f32_e32 v18, v18
	v_exp_f32_e32 v19, v19
	v_add_f32_e32 v20, 1.0, v20
	v_add_f32_e32 v21, 1.0, v21
	v_rcp_f32_e32 v20, v20
	v_rcp_f32_e32 v21, v21
	v_add_f32_e32 v18, 1.0, v18
	v_add_f32_e32 v19, 1.0, v19
	v_rcp_f32_e32 v18, v18
	v_rcp_f32_e32 v19, v19
	v_lshlrev_b32_e32 v16, 16, v54
	v_and_b32_e32 v17, 0xffff0000, v54
	v_pk_fma_f32 v[12:13], v[20:21], v[16:17], v[12:13]
	v_lshlrev_b32_e32 v16, 16, v55
	v_and_b32_e32 v17, 0xffff0000, v55
	v_pk_fma_f32 v[14:15], v[18:19], v[16:17], v[14:15]
	global_store_dwordx4 v[52:53], v[12:15], off
	s_cbranch_vccnz .LBB0_2056
	v_cvt_pk_bf16_f32 v16, v12, v13
	v_cvt_pk_bf16_f32 v17, v14, v15
	v_lshl_add_u64 v[18:19], v[50:51], 1, s[8:9]
	global_store_dwordx2 v[18:19], v[16:17], off
.LBB0_2056:
	s_and_b64 vcc, exec, s[6:7]
	s_cbranch_vccnz .LBB0_2060
	v_pk_mul_f32 v[12:13], v[12:13], v[12:13]
	v_pk_mul_f32 v[14:15], v[14:15], v[14:15]
	v_add_f32_e32 v12, v12, v13
	v_add_f32_e32 v12, v12, v14
	v_add_f32_e32 v12, v15, v12
	s_nop 1
	v_add_f32_dpp v12, v12, v12 row_ror:8 row_mask:0xf bank_mask:0xf bound_ctrl:1
	s_nop 1
	v_add_f32_dpp v12, v12, v12 row_ror:4 row_mask:0xf bank_mask:0xf bound_ctrl:1
	s_nop 1
	v_add_f32_dpp v12, v12, v12 row_ror:2 row_mask:0xf bank_mask:0xf bound_ctrl:1
	s_nop 1
	v_add_f32_dpp v12, v12, v12 row_ror:1 row_mask:0xf bank_mask:0xf bound_ctrl:1
	s_nop 0
	v_readlane_b32 s62, v12, 0
	v_readlane_b32 s65, v12, 16
	v_readlane_b32 s63, v12, 32
	v_readlane_b32 s64, v12, 48
	s_and_saveexec_b64 s[18:19], s[0:1]
	s_cbranch_execz .LBB0_2059
	s_lshl_b64 s[34:35], s[34:35], 2
	v_mov_b32_e32 v12, s65
	s_add_u32 s34, s76, s34
	v_add_f32_e32 v12, s62, v12
	s_addc_u32 s35, s77, s35
	v_add_f32_e32 v12, s63, v12
	v_add_f32_e32 v14, s64, v12
	v_mov_b64_e32 v[12:13], s[34:35]
	global_atomic_add_f32 v[12:13], v14, off

; DEVI float fsig(float x) { return __builtin_amdgcn_rcpf(1.f + __expf(-x)); }
; DEVI float bflo(unsigned u) { return __uint_as_float(u << 16); }
; DEVI float bfhi(unsigned u) { return __uint_as_float(u & 0xffff0000u); }
; template <int EPI, int TS, bool VT>
; DEVI void gemm_epilogue(const Params& p, char* smem, f32x4 (&acc)[2][2][4][2], int m0, int n0, float scale, const float* ssin,
;                         float* ssout, u16* xbout, int wid, int lane, int wr, int wc, int fr, int fq) {
;     ...
;           const float rs = __int_as_float(__builtin_amdgcn_readlane(__float_as_int(rsv), i));
;           if constexpr (EPI == E_RESID || EPI == E_PLEGATE) {
;             const float4 a = *(const float4*)(Tr + 4 * lane);
;             const size_t ro = (size_t)grow * 1024 + n0 + 4 * lane;
;             float4 x4 = xo[u];
;             if constexpr (EPI == E_PLEGATE) {
;               x4.x += bflo(pv[u].x) * fsig(a.x * rs);
;               x4.y += bfhi(pv[u].x) * fsig(a.y * rs);
;               x4.z += bflo(pv[u].y) * fsig(a.z * rs);
;               x4.w += bfhi(pv[u].y) * fsig(a.w * rs);
;             } else {
;               const float sc = fabsf(scale);
;               x4.x += sc * a.x; x4.y += sc * a.y; x4.z += sc * a.z; x4.w += sc * a.w;
;             }
;             st_nt16(p.x + ro, x4);
;             if (xbout) {
;               uint2 o;
;               o.x = pack2(x4.x, x4.y);
;               o.y = pack2(x4.z, x4.w);
;               st_nt8(xbout + ro, o);
;             }
;             if (ssout) {
;               const float ssq = wsum(x4.x * x4.x + x4.y * x4.y + x4.z * x4.z + x4.w * x4.w, lane);
;               if (lane == 0) atomicAdd(ssout + grow, ssq);
;             }
.LBB0_2060:
	ds_read_b128 v[12:15], v142 offset:13520
	v_readlane_b32 s18, v76, 13
	s_and_b64 vcc, exec, s[4:5]
	s_waitcnt lgkmcnt(0)
	v_mul_f32_e32 v12, s18, v12
	v_mul_f32_e32 v13, s18, v13
	v_mul_f32_e32 v12, 0xbfb8aa3b, v12
	v_mul_f32_e32 v13, 0xbfb8aa3b, v13
	v_mul_f32_e32 v14, s18, v14
	v_mul_f32_e32 v15, s18, v15
	v_exp_f32_e32 v16, v12
	v_exp_f32_e32 v17, v13
	v_mul_f32_e32 v14, 0xbfb8aa3b, v14
	v_mul_f32_e32 v15, 0xbfb8aa3b, v15
	v_exp_f32_e32 v14, v14
	v_exp_f32_e32 v15, v15
	v_add_f32_e32 v16, 1.0, v16
	v_add_f32_e32 v17, 1.0, v17
	v_rcp_f32_e32 v16, v16
	v_rcp_f32_e32 v17, v17
	v_add_f32_e32 v14, 1.0, v14
	v_add_f32_e32 v15, 1.0, v15
	v_rcp_f32_e32 v14, v14
	v_rcp_f32_e32 v15, v15
	v_lshlrev_b32_e32 v12, 16, v48
	v_and_b32_e32 v13, 0xffff0000, v48
	v_pk_fma_f32 v[8:9], v[16:17], v[12:13], v[8:9]
	v_lshlrev_b32_e32 v12, 16, v49
	v_and_b32_e32 v13, 0xffff0000, v49
	v_pk_fma_f32 v[10:11], v[14:15], v[12:13], v[10:11]
	global_store_dwordx4 v[46:47], v[8:11], off
	s_cbranch_vccnz .LBB0_2062
	v_cvt_pk_bf16_f32 v12, v8, v9
	v_cvt_pk_bf16_f32 v13, v10, v11
	v_lshl_add_u64 v[14:15], v[44:45], 1, s[8:9]
	global_store_dwordx2 v[14:15], v[12:13], off
.LBB0_2062:
	s_and_b64 vcc, exec, s[6:7]
	s_cbranch_vccnz .LBB0_2066
	v_pk_mul_f32 v[8:9], v[8:9], v[8:9]
	v_pk_mul_f32 v[10:11], v[10:11], v[10:11]
	v_add_f32_e32 v8, v8, v9
	v_add_f32_e32 v8, v8, v10
	v_add_f32_e32 v8, v11, v8
	s_nop 1
	v_add_f32_dpp v8, v8, v8 row_ror:8 row_mask:0xf bank_mask:0xf bound_ctrl:1
	s_nop 1
	v_add_f32_dpp v8, v8, v8 row_ror:4 row_mask:0xf bank_mask:0xf bound_ctrl:1
	s_nop 1
	v_add_f32_dpp v8, v8, v8 row_ror:2 row_mask:0xf bank_mask:0xf bound_ctrl:1
	s_nop 1
	v_add_f32_dpp v8, v8, v8 row_ror:1 row_mask:0xf bank_mask:0xf bound_ctrl:1
	s_nop 0
	v_readlane_b32 s34, v8, 0
	v_readlane_b32 s63, v8, 16
	v_readlane_b32 s35, v8, 32
	v_readlane_b32 s62, v8, 48
	s_and_saveexec_b64 s[18:19], s[0:1]
	s_cbranch_execz .LBB0_2065
	s_lshl_b64 s[30:31], s[30:31], 2
	v_mov_b32_e32 v8, s63
	s_add_u32 s30, s76, s30
	v_add_f32_e32 v8, s34, v8
	s_addc_u32 s31, s77, s31
	v_add_f32_e32 v8, s35, v8
	v_add_f32_e32 v10, s62, v8
	v_mov_b64_e32 v[8:9], s[30:31]
	global_atomic_add_f32 v[8:9], v10, off

; DEVI float fsig(float x) { return __builtin_amdgcn_rcpf(1.f + __expf(-x)); }
; DEVI float bflo(unsigned u) { return __uint_as_float(u << 16); }
; DEVI float bfhi(unsigned u) { return __uint_as_float(u & 0xffff0000u); }
; template <int EPI, int TS, bool VT>
; DEVI void gemm_epilogue(const Params& p, char* smem, f32x4 (&acc)[2][2][4][2], int m0, int n0, float scale, const float* ssin,
;                         float* ssout, u16* xbout, int wid, int lane, int wr, int wc, int fr, int fq) {
;     ...
;           const float rs = __int_as_float(__builtin_amdgcn_readlane(__float_as_int(rsv), i));
;           if constexpr (EPI == E_RESID || EPI == E_PLEGATE) {
;             const float4 a = *(const float4*)(Tr + 4 * lane);
;             const size_t ro = (size_t)grow * 1024 + n0 + 4 * lane;
;             float4 x4 = xo[u];
;             if constexpr (EPI == E_PLEGATE) {
;               x4.x += bflo(pv[u].x) * fsig(a.x * rs);
;               x4.y += bfhi(pv[u].x) * fsig(a.y * rs);
;               x4.z += bflo(pv[u].y) * fsig(a.z * rs);
;               x4.w += bfhi(pv[u].y) * fsig(a.w * rs);
;             } else {
;               const float sc = fabsf(scale);
;               x4.x += sc * a.x; x4.y += sc * a.y; x4.z += sc * a.z; x4.w += sc * a.w;
;             }
;             st_nt16(p.x + ro, x4);
;             if (xbout) {
;               uint2 o;
;               o.x = pack2(x4.x, x4.y);
;               o.y = pack2(x4.z, x4.w);
;               st_nt8(xbout + ro, o);
;             }
;             if (ssout) {
;               const float ssq = wsum(x4.x * x4.x + x4.y * x4.y + x4.z * x4.z + x4.w * x4.w, lane);
;               if (lane == 0) atomicAdd(ssout + grow, ssq);
;             }
.LBB0_2066:
	ds_read_b128 v[8:11], v142 offset:14560
	v_readlane_b32 s18, v76, 14
	s_and_b64 vcc, exec, s[4:5]
	s_waitcnt lgkmcnt(0)
	v_mul_f32_e32 v8, s18, v8
	v_mul_f32_e32 v9, s18, v9
	v_mul_f32_e32 v8, 0xbfb8aa3b, v8
	v_mul_f32_e32 v9, 0xbfb8aa3b, v9
	v_mul_f32_e32 v10, s18, v10
	v_mul_f32_e32 v11, s18, v11
	v_exp_f32_e32 v12, v8
	v_exp_f32_e32 v13, v9
	v_mul_f32_e32 v10, 0xbfb8aa3b, v10
	v_mul_f32_e32 v11, 0xbfb8aa3b, v11
	v_exp_f32_e32 v10, v10
	v_exp_f32_e32 v11, v11
	v_add_f32_e32 v12, 1.0, v12
	v_add_f32_e32 v13, 1.0, v13
	v_rcp_f32_e32 v12, v12
	v_rcp_f32_e32 v13, v13
	v_add_f32_e32 v10, 1.0, v10
	v_add_f32_e32 v11, 1.0, v11
	v_rcp_f32_e32 v10, v10
	v_rcp_f32_e32 v11, v11
	v_lshlrev_b32_e32 v8, 16, v42
	v_and_b32_e32 v9, 0xffff0000, v42
	v_pk_fma_f32 v[4:5], v[12:13], v[8:9], v[4:5]
	v_lshlrev_b32_e32 v8, 16, v43
	v_and_b32_e32 v9, 0xffff0000, v43
	v_pk_fma_f32 v[6:7], v[10:11], v[8:9], v[6:7]
	global_store_dwordx4 v[40:41], v[4:7], off
	s_cbranch_vccnz .LBB0_2068
	v_cvt_pk_bf16_f32 v8, v4, v5
	v_cvt_pk_bf16_f32 v9, v6, v7
	v_lshl_add_u64 v[10:11], v[38:39], 1, s[8:9]
	global_store_dwordx2 v[10:11], v[8:9], off
.LBB0_2068:
	s_and_b64 vcc, exec, s[6:7]
	s_cbranch_vccnz .LBB0_2072
	v_pk_mul_f32 v[4:5], v[4:5], v[4:5]
	v_pk_mul_f32 v[6:7], v[6:7], v[6:7]
	v_add_f32_e32 v4, v4, v5
	v_add_f32_e32 v4, v4, v6
	v_add_f32_e32 v4, v7, v4
	s_nop 1
	v_add_f32_dpp v4, v4, v4 row_ror:8 row_mask:0xf bank_mask:0xf bound_ctrl:1
	s_nop 1
	v_add_f32_dpp v4, v4, v4 row_ror:4 row_mask:0xf bank_mask:0xf bound_ctrl:1
	s_nop 1
	v_add_f32_dpp v4, v4, v4 row_ror:2 row_mask:0xf bank_mask:0xf bound_ctrl:1
	s_nop 1
	v_add_f32_dpp v4, v4, v4 row_ror:1 row_mask:0xf bank_mask:0xf bound_ctrl:1
	s_nop 0
	v_readlane_b32 s30, v4, 0
	v_readlane_b32 s35, v4, 16
	v_readlane_b32 s31, v4, 32
	v_readlane_b32 s34, v4, 48
	s_and_saveexec_b64 s[18:19], s[0:1]
	s_cbranch_execz .LBB0_2071
	s_lshl_b64 s[22:23], s[22:23], 2
	v_mov_b32_e32 v4, s35
	s_add_u32 s22, s76, s22
	v_add_f32_e32 v4, s30, v4
	s_addc_u32 s23, s77, s23
	v_add_f32_e32 v4, s31, v4
	v_add_f32_e32 v6, s34, v4
	v_mov_b64_e32 v[4:5], s[22:23]
	global_atomic_add_f32 v[4:5], v6, off

; DEVI float fsig(float x) { return __builtin_amdgcn_rcpf(1.f + __expf(-x)); }
; DEVI float bflo(unsigned u) { return __uint_as_float(u << 16); }
; DEVI float bfhi(unsigned u) { return __uint_as_float(u & 0xffff0000u); }
; template <int EPI, int TS, bool VT>
; DEVI void gemm_epilogue(const Params& p, char* smem, f32x4 (&acc)[2][2][4][2], int m0, int n0, float scale, const float* ssin,
;                         float* ssout, u16* xbout, int wid, int lane, int wr, int wc, int fr, int fq) {
;     ...
;           const float rs = __int_as_float(__builtin_amdgcn_readlane(__float_as_int(rsv), i));
;           if constexpr (EPI == E_RESID || EPI == E_PLEGATE) {
;             const float4 a = *(const float4*)(Tr + 4 * lane);
;             const size_t ro = (size_t)grow * 1024 + n0 + 4 * lane;
;             float4 x4 = xo[u];
;             if constexpr (EPI == E_PLEGATE) {
;               x4.x += bflo(pv[u].x) * fsig(a.x * rs);
;               x4.y += bfhi(pv[u].x) * fsig(a.y * rs);
;               x4.z += bflo(pv[u].y) * fsig(a.z * rs);
;               x4.w += bfhi(pv[u].y) * fsig(a.w * rs);
;             } else {
;               const float sc = fabsf(scale);
;               x4.x += sc * a.x; x4.y += sc * a.y; x4.z += sc * a.z; x4.w += sc * a.w;
;             }
;             st_nt16(p.x + ro, x4);
;             if (xbout) {
;               uint2 o;
;               o.x = pack2(x4.x, x4.y);
;               o.y = pack2(x4.z, x4.w);
;               st_nt8(xbout + ro, o);
;             }
;             if (ssout) {
;               const float ssq = wsum(x4.x * x4.x + x4.y * x4.y + x4.z * x4.z + x4.w * x4.w, lane);
;               if (lane == 0) atomicAdd(ssout + grow, ssq);
;             }
.LBB0_2072:
	ds_read_b128 v[4:7], v142 offset:15600
	v_readlane_b32 s18, v76, 15
	s_and_b64 vcc, exec, s[4:5]
	s_waitcnt lgkmcnt(0)
	v_mul_f32_e32 v4, s18, v4
	v_mul_f32_e32 v5, s18, v5
	v_mul_f32_e32 v4, 0xbfb8aa3b, v4
	v_mul_f32_e32 v5, 0xbfb8aa3b, v5
	v_mul_f32_e32 v6, s18, v6
	v_mul_f32_e32 v7, s18, v7
	v_exp_f32_e32 v8, v4
	v_exp_f32_e32 v9, v5
	v_mul_f32_e32 v6, 0xbfb8aa3b, v6
	v_mul_f32_e32 v7, 0xbfb8aa3b, v7
	v_exp_f32_e32 v6, v6
	v_exp_f32_e32 v7, v7
	v_add_f32_e32 v8, 1.0, v8
	v_add_f32_e32 v9, 1.0, v9
	v_rcp_f32_e32 v8, v8
	v_rcp_f32_e32 v9, v9
	v_add_f32_e32 v6, 1.0, v6
	v_add_f32_e32 v7, 1.0, v7
	v_rcp_f32_e32 v6, v6
	v_rcp_f32_e32 v7, v7
	v_lshlrev_b32_e32 v4, 16, v36
	v_and_b32_e32 v5, 0xffff0000, v36
	v_pk_fma_f32 v[0:1], v[8:9], v[4:5], v[0:1]
	v_lshlrev_b32_e32 v4, 16, v37
	v_and_b32_e32 v5, 0xffff0000, v37
	v_pk_fma_f32 v[2:3], v[6:7], v[4:5], v[2:3]
	global_store_dwordx4 v[34:35], v[0:3], off
	s_cbranch_vccnz .LBB0_2074
	v_cvt_pk_bf16_f32 v4, v0, v1
	v_cvt_pk_bf16_f32 v5, v2, v3
	v_lshl_add_u64 v[6:7], v[32:33], 1, s[8:9]
	global_store_dwordx2 v[6:7], v[4:5], off
.LBB0_2074:
	s_and_b64 vcc, exec, s[6:7]
	s_cbranch_vccnz .LBB0_1877
	v_pk_mul_f32 v[0:1], v[0:1], v[0:1]
	v_pk_mul_f32 v[2:3], v[2:3], v[2:3]
	v_add_f32_e32 v0, v0, v1
	v_add_f32_e32 v0, v0, v2
	v_add_f32_e32 v0, v3, v0
	s_nop 1
	v_add_f32_dpp v0, v0, v0 row_ror:8 row_mask:0xf bank_mask:0xf bound_ctrl:1
	s_nop 1
	v_add_f32_dpp v0, v0, v0 row_ror:4 row_mask:0xf bank_mask:0xf bound_ctrl:1
	s_nop 1
	v_add_f32_dpp v0, v0, v0 row_ror:2 row_mask:0xf bank_mask:0xf bound_ctrl:1
	s_nop 1
	v_add_f32_dpp v0, v0, v0 row_ror:1 row_mask:0xf bank_mask:0xf bound_ctrl:1
	s_nop 0
	v_readlane_b32 s18, v0, 0
	v_readlane_b32 s23, v0, 16
	v_readlane_b32 s19, v0, 32
	v_readlane_b32 s22, v0, 48
	s_and_saveexec_b64 s[4:5], s[0:1]
	s_cbranch_execz .LBB0_1876
	s_lshl_b64 s[0:1], s[20:21], 2
	v_mov_b32_e32 v0, s23
	s_add_u32 s0, s76, s0
	v_add_f32_e32 v0, s18, v0
	s_addc_u32 s1, s77, s1
	v_add_f32_e32 v0, s19, v0
	v_add_f32_e32 v2, s22, v0
	v_mov_b64_e32 v[0:1], s[0:1]
	global_atomic_add_f32 v[0:1], v2, off
	s_branch .LBB0_1876
